# wprep rewritten as LDS-DMA ring with nt loads; attention softmax VALU spread into QK MFMA gaps; per-cluster s_setprio flips removed from GEMM loops, static prio 1 for waves 0-3
# speedup vs baseline: 1.0352x; 1.0180x over previous
_Z6mk_fwd6Params:
	s_load_dwordx2 s[92:93], s[0:1], 0xd0
	s_load_dwordx4 s[84:87], s[0:1], 0xc0
	v_and_b32_e32 v1, 0x3ff, v0
	s_mov_b32 s88, s2
	s_mov_b64 s[90:91], s[0:1]
	s_movk_i32 s1, 0x3ff
	s_waitcnt lgkmcnt(0)
	s_cmp_gt_i32 s93, -1
	v_readfirstlane_b32 s0, v1
	s_nop 0
	s_cmp_ge_u32 s0, 0x100
	s_cbranch_scc1 .Lprio_skip
	s_setprio 1
.Lprio_skip:
	s_cmp_gt_i32 s93, -1
	s_cbranch_scc1 .LBB0_12
	v_lshrrev_b32_e32 v2, 20, v0
	v_lshrrev_b32_e32 v0, 10, v0
	v_or_b32_e32 v0, v0, v2
	v_and_or_b32 v0, v0, s1, v1
	v_cmp_eq_u32_e32 vcc, 0, v0
	s_barrier
	s_and_saveexec_b64 s[2:3], vcc
	s_cbranch_execz .LBB0_11
	buffer_wbl2 sc1
	s_load_dwordx2 s[4:5], s[90:91], 0x130
	s_mov_b64 s[6:7], exec
	v_mbcnt_lo_u32_b32 v0, s6, 0
	v_mbcnt_hi_u32_b32 v0, s7, v0
	v_cmp_eq_u32_e32 vcc, 0, v0
	s_waitcnt lgkmcnt(0)
	s_load_dword s1, s[4:5], 0x28
	s_and_saveexec_b64 s[8:9], vcc
	s_cbranch_execz .LBB0_4
	s_bcnt1_i32_b64 s6, s[6:7]
	v_mov_b32_e32 v1, 0
	v_mov_b32_e32 v2, s6
	global_atomic_add v1, v1, v2, s[4:5] offset:32 sc0

.LBB0_115:
	s_or_b64 exec, exec, s[2:3]
	s_abs_i32 s15, s12
	v_cvt_f32_u32_e32 v2, s15
	v_lshlrev_b32_e32 v0, 2, v76
	v_and_b32_e32 v82, 60, v0
	s_sub_i32 s2, 0, s15
	v_rcp_iflag_f32_e32 v0, v2
	s_mov_b32 s13, s88
	s_add_i32 s14, s13, s12
	v_mul_f32_e32 v0, 0x4f7ffffe, v0
	v_cvt_u32_f32_e32 v0, v0
	s_abs_i32 s1, s14
	s_ashr_i32 s0, s14, 31
	v_ashrrev_i32_e32 v78, 3, v76
	v_readfirstlane_b32 s16, v0
	s_mul_i32 s2, s2, s16
	s_mul_hi_u32 s2, s16, s2
	s_add_i32 s16, s16, s2
	s_mul_hi_u32 s2, s1, s16
	s_mul_i32 s2, s2, s15
	s_sub_i32 s1, s1, s2
	s_sub_i32 s2, s1, s15
	s_cmp_ge_u32 s1, s15
	s_cselect_b32 s1, s2, s1
	s_sub_i32 s2, s1, s15
	s_cmp_ge_u32 s1, s15
	s_cselect_b32 s1, s2, s1
	s_xor_b32 s1, s1, s0
	v_lshlrev_b32_e32 v2, 3, v76
	s_sub_i32 s17, s1, s0
	v_ashrrev_i32_e32 v77, 4, v76
	v_mov_b32_e32 v1, 0
	v_lshl_add_u32 v79, v82, 2, 0
	v_and_b32_e32 v80, 56, v2
	s_cmpk_lt_i32 s17, 0x480
	v_lshl_add_u32 v81, v78, 2, 0
	s_load_dword s59, s[90:91], 0xd8
	v_mbcnt_lo_u32_b32 v100, -1, 0
	v_mbcnt_hi_u32_b32 v100, -1, v100
	s_lshr_b32 s69, s94, 6
	s_lshl_b32 s82, s69, 10
	s_lshl_b32 s83, s69, 1
	s_lshr_b32 s98, s69, 2
	v_lshrrev_b32_e32 v101, 5, v100
	v_and_b32_e32 v113, 31, v100
	s_add_i32 s70, s83, 0
	v_add_u32_e32 v102, s70, v101
	s_add_i32 s70, s98, 0
	v_xor_b32_e32 v106, s70, v113
	v_lshlrev_b32_e32 v106, 4, v106
	s_add_i32 s70, s83, 16
	v_add_u32_e32 v103, s70, v101
	s_add_i32 s70, s98, 2
	v_xor_b32_e32 v107, s70, v113
	v_lshlrev_b32_e32 v107, 4, v107
	s_add_i32 s70, s83, 32
	v_add_u32_e32 v104, s70, v101
	s_add_i32 s70, s98, 4
	v_xor_b32_e32 v108, s70, v113
	v_lshlrev_b32_e32 v108, 4, v108
	s_add_i32 s70, s83, 48
	v_add_u32_e32 v105, s70, v101
	s_add_i32 s70, s98, 6
	v_xor_b32_e32 v109, s70, v113
	v_lshlrev_b32_e32 v109, 4, v109
	s_lshr_b32 s70, s94, 3
	v_lshrrev_b32_e32 v112, 3, v100
	v_add_u32_e32 v112, s70, v112
	v_and_b32_e32 v101, 7, v100
	v_lshlrev_b32_e32 v111, 4, v101
	v_lshrrev_b32_e32 v113, 2, v112
	v_xor_b32_e32 v113, v113, v101
	v_lshlrev_b32_e32 v113, 4, v113
	v_lshl_add_u32 v110, v101, 12, v113
	v_and_b32_e32 v113, 3, v112
	v_lshl_add_u32 v110, v113, 2, v110
	s_waitcnt lgkmcnt(0)
	s_mov_b32 s61, s88
	s_mov_b32 s60, s88
	s_mov_b32 s58, -2
.Lwp0_loop:
	s_cmp_lt_i32 s58, 0
	s_cbranch_scc1 .Lwp0_doissue
	s_cmp_lt_u32 s61, 7520
	s_cbranch_scc0 .Lwp0_end
	s_cmp_lt_u32 s60, 7520
	s_cbranch_scc0 .Lwp0_w0
	s_cmp_eq_u32 s58, 0
	s_cbranch_scc1 .Lwp0_wt0
	s_waitcnt vmcnt(6)
	s_branch .Lwp0_wd
.Lwp0_wt0:
	s_waitcnt vmcnt(4)
	s_branch .Lwp0_wd

.Lwp0_wd:
	s_barrier
	s_cmp_lt_i32 s58, 0
	s_cbranch_scc1 .Lwp0_doissue
	s_cmp_lt_u32 s61, 2272
	s_cbranch_scc0 .Lwp0_psel_1
	s_sub_u32 s65, s61, 0
	s_mul_hi_u32 s66, s65, 0x39b0ad2
	s_mul_i32 s69, s66, 71
	s_sub_u32 s67, s65, s69
	s_mov_b32 s76, 0x1000
	s_mov_b32 s78, 0x4b600
	s_lshl_b32 s79, s67, 7
	s_cmp_eq_u32 s67, 70
	s_cselect_b32 s77, 1, 0
	s_branch .Lwp0_psel_done
.Lwp0_psel_1:
	s_cmp_lt_u32 s61, 2400
	s_cbranch_scc0 .Lwp0_psel_2
	s_sub_u32 s65, s61, 2272
	s_lshr_b32 s66, s65, 4
	s_mul_i32 s69, s66, 16
	s_sub_u32 s67, s65, s69
	s_mov_b32 s76, 0x1000
	s_mov_b32 s78, 0x26cb600
	s_lshl_b32 s79, s67, 7
	s_mov_b32 s77, 0
	s_branch .Lwp0_psel_done
.Lwp0_psel_2:
	s_cmp_lt_u32 s61, 2656
	s_cbranch_scc0 .Lwp0_psel_3
	s_sub_u32 s65, s61, 2400
	s_lshr_b32 s66, s65, 4
	s_mul_i32 s69, s66, 16
	s_sub_u32 s67, s65, s69
	s_mov_b32 s76, 0x1000
	s_mov_b32 s78, 0x26cba00
	s_lshl_b32 s79, s67, 7
	s_mov_b32 s77, 0
	s_branch .Lwp0_psel_done
.Lwp0_psel_3:
	s_cmp_lt_u32 s61, 2784
	s_cbranch_scc0 .Lwp0_psel_4
	s_sub_u32 s65, s61, 2656
	s_lshr_b32 s66, s65, 4
	s_mul_i32 s69, s66, 16
	s_sub_u32 s67, s65, s69
	s_mov_b32 s76, 0x1000
	s_mov_b32 s78, 0x26cc200
	s_lshl_b32 s79, s67, 7
	s_mov_b32 s77, 0
	s_branch .Lwp0_psel_done
.Lwp0_psel_4:
	s_cmp_lt_u32 s61, 3296
	s_cbranch_scc0 .Lwp0_psel_5
	s_sub_u32 s65, s61, 2784
	s_lshr_b32 s66, s65, 4
	s_mul_i32 s69, s66, 16
	s_sub_u32 s67, s65, s69
	s_mov_b32 s76, 0x1000
	s_mov_b32 s78, 0x2ecb600
	s_lshl_b32 s79, s67, 7
	s_mov_b32 s77, 0
	s_branch .Lwp0_psel_done
.Lwp0_psel_5:
	s_cmp_lt_u32 s61, 4704
	s_cbranch_scc0 .Lwp0_psel_6
	s_sub_u32 s65, s61, 3296
	s_mul_hi_u32 s66, s65, 0x5d1745e
	s_mul_i32 s69, s66, 44
	s_sub_u32 s67, s65, s69
	s_mov_b32 s76, 0x1000
	s_mov_b32 s78, 0x36cb600
	s_lshl_b32 s79, s67, 8
	s_mov_b32 s77, 0
	s_branch .Lwp0_psel_done
.Lwp0_psel_6:
	s_cmp_lt_u32 s61, 6112
	s_cbranch_scc0 .Lwp0_psel_7
	s_sub_u32 s65, s61, 4704
	s_mul_hi_u32 s66, s65, 0x5d1745e
	s_mul_i32 s69, s66, 44
	s_sub_u32 s67, s65, s69
	s_mov_b32 s76, 0x1000
	s_mov_b32 s78, 0x36cb600
	s_lshl_b32 s79, s67, 8
	s_add_u32 s79, s79, 128
	s_mov_b32 s77, 0
	s_branch .Lwp0_psel_done
.Lwp0_psel_7:
	s_sub_u32 s65, s61, 6112
	s_lshr_b32 s66, s65, 4
	s_mul_i32 s69, s66, 16
	s_sub_u32 s67, s65, s69
	s_mov_b32 s76, 0x2c00
	s_mov_b32 s78, 0x62cb600
	s_lshl_b32 s79, s67, 7
	s_mov_b32 s77, 0
.Lwp0_psel_done:
	s_lshl_b32 s69, s66, 7
	s_add_u32 s78, s78, s69
	s_mul_i32 s70, s79, s76
	s_add_u32 s78, s78, s70
	s_add_u32 s72, s86, s78
	s_addc_u32 s73, s87, 0
	s_lshl_b32 s70, s76, 6
	s_add_u32 s74, s72, s70
	s_addc_u32 s75, s73, 0
	s_and_b32 s69, s58, 3
	s_lshl_b32 s69, s69, 15
	v_add_u32_e32 v141, s69, v110
	ds_read_b32 v116, v141 offset:0
	ds_read_b32 v117, v141 offset:512
	ds_read_b32 v118, v141 offset:1024
	ds_read_b32 v119, v141 offset:1536
	ds_read_b32 v120, v141 offset:2048
	ds_read_b32 v121, v141 offset:2560
	ds_read_b32 v122, v141 offset:3072
	ds_read_b32 v123, v141 offset:3584
	ds_read_b32 v124, v141 offset:256
	ds_read_b32 v125, v141 offset:768
	ds_read_b32 v126, v141 offset:1280
	ds_read_b32 v127, v141 offset:1792
	ds_read_b32 v128, v141 offset:2304
	ds_read_b32 v129, v141 offset:2816
	ds_read_b32 v130, v141 offset:3328
	ds_read_b32 v131, v141 offset:3840
	v_mad_u32_u24 v140, v112, s76, v111
	s_waitcnt lgkmcnt(8)
	v_cvt_pk_bf16_f32 v132, v116, v117
	v_cvt_pk_bf16_f32 v133, v118, v119
	v_cvt_pk_bf16_f32 v134, v120, v121
	v_cvt_pk_bf16_f32 v135, v122, v123
	global_store_dwordx4 v140, v[132:135], s[72:73]
	s_waitcnt lgkmcnt(0)
	s_cmp_eq_u32 s77, 0
	s_cbranch_scc0 .Lwp0_dup
	v_cvt_pk_bf16_f32 v136, v124, v125
	v_cvt_pk_bf16_f32 v137, v126, v127
	v_cvt_pk_bf16_f32 v138, v128, v129
	v_cvt_pk_bf16_f32 v139, v130, v131
	global_store_dwordx4 v140, v[136:139], s[74:75]
	s_branch .Lwp0_next
.Lwp0_dup:
	global_store_dwordx4 v140, v[132:135], s[72:73]
.Lwp0_next:
	s_add_u32 s61, s61, s59
.Lwp0_doissue:
	s_cmp_lt_u32 s60, 7520
	s_cbranch_scc0 .Lwp0_noissue
	s_add_u32 s99, s58, 2
	s_and_b32 s99, s99, 3
	s_cmp_lt_u32 s60, 2272
	s_cbranch_scc0 .Lwp0_isel_m_1
	v_readlane_b32 s62, v245, 0
	v_readlane_b32 s63, v245, 1
	s_sub_u32 s65, s60, 0
	s_mov_b32 s64, 0x8d00
	s_mul_hi_u32 s66, s65, 0x39b0ad2
	s_mul_i32 s69, s66, 71
	s_sub_u32 s67, s65, s69
	s_cmp_eq_u32 s67, 70
	s_cselect_b32 s68, 1, 0
	s_branch .Lwp0_isel_done_m
.Lwp0_isel_m_1:
	s_cmp_lt_u32 s60, 2400
	s_cbranch_scc0 .Lwp0_isel_m_2
	v_readlane_b32 s62, v245, 16
	v_readlane_b32 s63, v245, 17
	s_sub_u32 s65, s60, 2272
	s_mov_b32 s64, 0x2000
	s_lshr_b32 s66, s65, 4
	s_mul_i32 s69, s66, 16
	s_sub_u32 s67, s65, s69
	s_mov_b32 s68, 0
	s_branch .Lwp0_isel_done_m
.Lwp0_isel_m_2:
	s_cmp_lt_u32 s60, 2656
	s_cbranch_scc0 .Lwp0_isel_m_3
	v_readlane_b32 s62, v245, 18
	v_readlane_b32 s63, v245, 19
	s_sub_u32 s65, s60, 2400
	s_mov_b32 s64, 0x2000
	s_lshr_b32 s66, s65, 4
	s_mul_i32 s69, s66, 16
	s_sub_u32 s67, s65, s69
	s_mov_b32 s68, 0
	s_branch .Lwp0_isel_done_m
.Lwp0_isel_m_3:
	s_cmp_lt_u32 s60, 2784
	s_cbranch_scc0 .Lwp0_isel_m_4
	v_readlane_b32 s62, v245, 22
	v_readlane_b32 s63, v245, 23
	s_sub_u32 s65, s60, 2656
	s_mov_b32 s64, 0x2000
	s_lshr_b32 s66, s65, 4
	s_mul_i32 s69, s66, 16
	s_sub_u32 s67, s65, s69
	s_mov_b32 s68, 0
	s_branch .Lwp0_isel_done_m
.Lwp0_isel_m_4:
	s_cmp_lt_u32 s60, 3296
	s_cbranch_scc0 .Lwp0_isel_m_5
	v_readlane_b32 s62, v245, 24
	v_readlane_b32 s63, v245, 25
	s_sub_u32 s65, s60, 2784
	s_mov_b32 s64, 0x2000
	s_lshr_b32 s66, s65, 4
	s_mul_i32 s69, s66, 16
	s_sub_u32 s67, s65, s69
	s_mov_b32 s68, 0
	s_branch .Lwp0_isel_done_m
.Lwp0_isel_m_5:
	s_cmp_lt_u32 s60, 4704
	s_cbranch_scc0 .Lwp0_isel_m_6
	v_readlane_b32 s62, v245, 26
	v_readlane_b32 s63, v245, 27
	s_sub_u32 s65, s60, 3296
	s_mov_b32 s64, 0x5800
	s_mul_hi_u32 s66, s65, 0x5d1745e
	s_mul_i32 s69, s66, 44
	s_sub_u32 s67, s65, s69
	s_mov_b32 s68, 0
	s_branch .Lwp0_isel_done_m
.Lwp0_isel_m_6:
	s_cmp_lt_u32 s60, 6112
	s_cbranch_scc0 .Lwp0_isel_m_7
	v_readlane_b32 s62, v245, 28
	v_readlane_b32 s63, v245, 29
	s_sub_u32 s65, s60, 4704
	s_mov_b32 s64, 0x5800
	s_mul_hi_u32 s66, s65, 0x5d1745e
	s_mul_i32 s69, s66, 44
	s_sub_u32 s67, s65, s69
	s_mov_b32 s68, 0
	s_branch .Lwp0_isel_done_m
.Lwp0_isel_m_7:
	v_readlane_b32 s62, v245, 30
	v_readlane_b32 s63, v245, 31
	s_sub_u32 s65, s60, 6112
	s_mov_b32 s64, 0x2000
	s_lshr_b32 s66, s65, 4
	s_mul_i32 s69, s66, 16
	s_sub_u32 s67, s65, s69
	s_mov_b32 s68, 0
.Lwp0_isel_done_m:
	s_lshl_b32 s69, s64, 6
	s_mul_i32 s69, s69, s66
	s_lshl_b32 s70, s67, 9
	s_add_u32 s69, s69, s70
	s_add_u32 s62, s62, s69
	s_addc_u32 s63, s63, 0
	s_lshl_b32 s100, s99, 15
	s_add_i32 s100, s100, s82
	s_cmp_eq_u32 s68, 0
	s_cbranch_scc1 .Lwp0_noedge_m
	s_mov_b32 exec_lo, 0xffff
	s_mov_b32 exec_hi, 0xffff
.Lwp0_noedge_m:
	v_mad_u32_u24 v114, v102, s64, v106
	s_mov_b32 m0, s100
	s_nop 0
	global_load_lds_dwordx4 v114, s[62:63] nt
	v_mad_u32_u24 v115, v103, s64, v107
	s_add_i32 m0, s100, 0x2000
	s_nop 0
	global_load_lds_dwordx4 v115, s[62:63] nt
	v_mad_u32_u24 v114, v104, s64, v108
	s_add_i32 m0, s100, 0x4000
	s_nop 0
	global_load_lds_dwordx4 v114, s[62:63] nt
	v_mad_u32_u24 v115, v105, s64, v109
	s_add_i32 m0, s100, 0x6000
	s_nop 0
	global_load_lds_dwordx4 v115, s[62:63] nt
	s_mov_b64 exec, -1
.Lwp0_noissue:
.Lwp0_next0:
	s_add_i32 s58, s58, 1
	s_add_u32 s60, s60, s59
	s_branch .Lwp0_loop
.Lwp0_end:
	s_waitcnt vmcnt(0) lgkmcnt(0)
	s_barrier

.LBB0_197:
.LBB0_236:
	v_lshl_add_u32 v4, s13, 9, v76
	s_movk_i32 s0, 0x2400
	v_cmp_gt_i32_e32 vcc, s0, v4
	s_waitcnt lgkmcnt(0)
	s_barrier
	s_and_saveexec_b64 s[2:3], vcc
	s_cbranch_execz .LBB0_241
	s_load_dwordx16 s[16:31], s[90:91], 0x40
	s_lshl_b64 s[0:1], s[54:55], 2
	v_ashrrev_i32_e32 v5, 31, v4
	s_mov_b64 s[10:11], 0
	v_mov_b32_e32 v3, 0
	s_waitcnt lgkmcnt(0)
	s_add_u32 s4, s18, s0
	s_addc_u32 s5, s19, s1
	s_lshl_b32 s6, s12, 9
	s_add_u32 s0, s86, s54
	s_addc_u32 s1, s87, s55
	v_lshl_add_u64 v[0:1], v[4:5], 2, s[0:1]
	s_mov_b64 s[0:1], 0x219b3600
	s_ashr_i32 s7, s6, 31
	v_lshl_add_u64 v[0:1], v[0:1], 0, s[0:1]
	s_lshl_b64 s[8:9], s[6:7], 2
	s_movk_i32 s0, 0x1800
	s_movk_i32 s1, 0x23ff
	v_mov_b32_e32 v2, v4
	s_branch .LBB0_239

.LBB0_285:
	ds_read_b128 v[128:131], v154
	ds_read_b128 v[132:135], v154 offset:1024
	ds_read_b128 v[136:139], v154 offset:2048
	ds_read_b128 v[140:143], v154 offset:3072
	s_add_u32 s45, s60, 0xfff80080
	s_addc_u32 s46, s61, -1
	s_cmp_eq_u32 s44, 28
	s_cselect_b32 s47, s53, s46
	s_cselect_b32 s46, s52, s45
	s_cselect_b32 s49, s55, s43
	s_cselect_b32 s48, s54, s42
	v_lshl_add_u64 v[150:151], s[60:61], 0, v[148:149]
	s_add_i32 m0, s21, 0xc000
	ds_read_b128 v[158:161], v155
	ds_read_b128 v[162:165], v155 offset:1024
	ds_read_b128 v[166:169], v155 offset:2048
	ds_read_b128 v[170:173], v155 offset:3072
	ds_read_b128 v[174:177], v155 offset:4096
	ds_read_b128 v[178:181], v155 offset:5120
	ds_read_b128 v[182:185], v155 offset:6144
	ds_read_b128 v[186:189], v155 offset:7168
	global_load_lds_dwordx4 v[150:151], off
	v_lshl_add_u64 v[150:151], v[150:151], 0, s[2:3]
	s_add_i32 m0, s21, 0xe000
	s_nop 0
	global_load_lds_dwordx4 v[150:151], off
	s_waitcnt lgkmcnt(8)
	s_barrier
	s_waitcnt lgkmcnt(0)
	s_waitcnt lgkmcnt(0)
	v_mfma_f32_16x16x32_bf16 v[124:127], v[128:131], v[158:161], v[124:127]
	v_mfma_f32_16x16x32_bf16 v[120:123], v[136:139], v[158:161], v[120:123]
	v_mfma_f32_16x16x32_bf16 v[116:119], v[128:131], v[166:169], v[116:119]
	v_mfma_f32_16x16x32_bf16 v[112:115], v[136:139], v[166:169], v[112:115]
	v_mfma_f32_16x16x32_bf16 v[108:111], v[128:131], v[174:177], v[108:111]
	v_mfma_f32_16x16x32_bf16 v[100:103], v[136:139], v[174:177], v[100:103]
	v_mfma_f32_16x16x32_bf16 v[92:95], v[128:131], v[182:185], v[92:95]
	v_mfma_f32_16x16x32_bf16 v[84:87], v[136:139], v[182:185], v[84:87]
	v_mfma_f32_16x16x32_bf16 v[124:127], v[132:135], v[162:165], v[124:127]
	v_mfma_f32_16x16x32_bf16 v[120:123], v[140:143], v[162:165], v[120:123]
	v_mfma_f32_16x16x32_bf16 v[116:119], v[132:135], v[170:173], v[116:119]
	v_mfma_f32_16x16x32_bf16 v[112:115], v[140:143], v[170:173], v[112:115]
	v_mfma_f32_16x16x32_bf16 v[108:111], v[132:135], v[178:181], v[108:111]
	v_mfma_f32_16x16x32_bf16 v[100:103], v[140:143], v[178:181], v[100:103]
	v_mfma_f32_16x16x32_bf16 v[92:95], v[132:135], v[186:189], v[92:95]
	v_mfma_f32_16x16x32_bf16 v[84:87], v[140:143], v[186:189], v[84:87]
	s_barrier
	s_add_i32 s45, s39, s20
	v_lshl_add_u64 v[150:151], s[48:49], 0, v[144:145]
	s_mov_b32 m0, s45
	ds_read_b128 v[190:193], v156
	ds_read_b128 v[194:197], v156 offset:1024
	ds_read_b128 v[198:201], v156 offset:2048
	ds_read_b128 v[202:205], v156 offset:3072
	global_load_lds_dwordx4 v[150:151], off
	v_lshl_add_u64 v[206:207], v[150:151], 0, s[2:3]
	s_add_i32 m0, s45, 0x2000
	s_nop 0
	global_load_lds_dwordx4 v[206:207], off
	s_barrier
	s_waitcnt lgkmcnt(0)
	s_waitcnt lgkmcnt(0)
	v_mfma_f32_16x16x32_bf16 v[104:107], v[190:193], v[158:161], v[104:107]
	v_mfma_f32_16x16x32_bf16 v[96:99], v[198:201], v[158:161], v[96:99]
	v_mfma_f32_16x16x32_bf16 v[88:91], v[190:193], v[166:169], v[88:91]
	v_mfma_f32_16x16x32_bf16 v[80:83], v[198:201], v[166:169], v[80:83]
	v_mfma_f32_16x16x32_bf16 v[76:79], v[190:193], v[174:177], v[76:79]
	v_mfma_f32_16x16x32_bf16 v[72:75], v[198:201], v[174:177], v[72:75]
	v_mfma_f32_16x16x32_bf16 v[68:71], v[190:193], v[182:185], v[68:71]
	v_mfma_f32_16x16x32_bf16 v[64:67], v[198:201], v[182:185], v[64:67]
	v_mfma_f32_16x16x32_bf16 v[104:107], v[194:197], v[162:165], v[104:107]
	v_mfma_f32_16x16x32_bf16 v[96:99], v[202:205], v[162:165], v[96:99]
	v_mfma_f32_16x16x32_bf16 v[88:91], v[194:197], v[170:173], v[88:91]
	v_mfma_f32_16x16x32_bf16 v[80:83], v[202:205], v[170:173], v[80:83]
	v_mfma_f32_16x16x32_bf16 v[76:79], v[194:197], v[178:181], v[76:79]
	v_mfma_f32_16x16x32_bf16 v[72:75], v[202:205], v[178:181], v[72:75]
	v_mfma_f32_16x16x32_bf16 v[68:71], v[194:197], v[186:189], v[68:71]
	v_mfma_f32_16x16x32_bf16 v[64:67], v[202:205], v[186:189], v[64:67]
	s_mov_b32 m0, s21
	v_lshl_add_u64 v[206:207], s[46:47], 0, v[146:147]
	s_barrier
	ds_read_b128 v[158:161], v155 offset:16384
	ds_read_b128 v[162:165], v155 offset:17408
	ds_read_b128 v[166:169], v155 offset:18432
	ds_read_b128 v[170:173], v155 offset:19456
	ds_read_b128 v[174:177], v155 offset:20480
	ds_read_b128 v[178:181], v155 offset:21504
	ds_read_b128 v[182:185], v155 offset:22528
	ds_read_b128 v[186:189], v155 offset:23552
	global_load_lds_dwordx4 v[206:207], off
	v_lshl_add_u64 v[208:209], v[206:207], 0, s[2:3]
	s_mov_b32 m0, s28
	s_nop 0
	global_load_lds_dwordx4 v[208:209], off
	s_barrier
	s_waitcnt lgkmcnt(0)
	s_waitcnt lgkmcnt(0)
	v_mfma_f32_16x16x32_bf16 v[60:63], v[128:131], v[158:161], v[60:63]
	v_mfma_f32_16x16x32_bf16 v[56:59], v[136:139], v[158:161], v[56:59]
	v_mfma_f32_16x16x32_bf16 v[48:51], v[128:131], v[166:169], v[48:51]
	v_mfma_f32_16x16x32_bf16 v[40:43], v[136:139], v[166:169], v[40:43]
	v_mfma_f32_16x16x32_bf16 v[32:35], v[128:131], v[174:177], v[32:35]
	v_mfma_f32_16x16x32_bf16 v[24:27], v[136:139], v[174:177], v[24:27]
	v_mfma_f32_16x16x32_bf16 v[16:19], v[128:131], v[182:185], v[16:19]
	v_mfma_f32_16x16x32_bf16 v[8:11], v[136:139], v[182:185], v[8:11]
	v_mfma_f32_16x16x32_bf16 v[60:63], v[132:135], v[162:165], v[60:63]
	v_mfma_f32_16x16x32_bf16 v[56:59], v[140:143], v[162:165], v[56:59]
	v_mfma_f32_16x16x32_bf16 v[48:51], v[132:135], v[170:173], v[48:51]
	v_mfma_f32_16x16x32_bf16 v[40:43], v[140:143], v[170:173], v[40:43]
	v_mfma_f32_16x16x32_bf16 v[32:35], v[132:135], v[178:181], v[32:35]
	v_mfma_f32_16x16x32_bf16 v[24:27], v[140:143], v[178:181], v[24:27]
	v_mfma_f32_16x16x32_bf16 v[16:19], v[132:135], v[186:189], v[16:19]
	v_mfma_f32_16x16x32_bf16 v[8:11], v[140:143], v[186:189], v[8:11]
	s_barrier
	s_add_i32 s45, s40, s20
	v_lshl_add_u64 v[128:129], v[150:151], 0, s[6:7]
	s_mov_b32 m0, s45
	s_nop 0
	global_load_lds_dwordx4 v[128:129], off
	v_lshl_add_u64 v[128:129], v[150:151], 0, s[8:9]
	s_add_i32 m0, s45, 0x2000
	s_nop 0
	global_load_lds_dwordx4 v[128:129], off
	s_waitcnt vmcnt(6)
	s_barrier
	v_mfma_f32_16x16x32_bf16 v[52:55], v[190:193], v[158:161], v[52:55]
	v_mfma_f32_16x16x32_bf16 v[44:47], v[198:201], v[158:161], v[44:47]
	v_mfma_f32_16x16x32_bf16 v[36:39], v[190:193], v[166:169], v[36:39]
	v_mfma_f32_16x16x32_bf16 v[28:31], v[198:201], v[166:169], v[28:31]
	v_mfma_f32_16x16x32_bf16 v[20:23], v[190:193], v[174:177], v[20:23]
	v_mfma_f32_16x16x32_bf16 v[12:15], v[198:201], v[174:177], v[12:15]
	v_mfma_f32_16x16x32_bf16 v[4:7], v[190:193], v[182:185], v[4:7]
	v_mfma_f32_16x16x32_bf16 v[0:3], v[198:201], v[182:185], v[0:3]
	v_mfma_f32_16x16x32_bf16 v[52:55], v[194:197], v[162:165], v[52:55]
	v_mfma_f32_16x16x32_bf16 v[44:47], v[202:205], v[162:165], v[44:47]
	v_mfma_f32_16x16x32_bf16 v[36:39], v[194:197], v[170:173], v[36:39]
	v_mfma_f32_16x16x32_bf16 v[28:31], v[202:205], v[170:173], v[28:31]
	v_mfma_f32_16x16x32_bf16 v[20:23], v[194:197], v[178:181], v[20:23]
	v_mfma_f32_16x16x32_bf16 v[12:15], v[202:205], v[178:181], v[12:15]
	v_mfma_f32_16x16x32_bf16 v[4:7], v[194:197], v[186:189], v[4:7]
	v_mfma_f32_16x16x32_bf16 v[0:3], v[202:205], v[186:189], v[0:3]
	s_add_i32 s45, 0, 0x18000
	v_add_u32_e32 v140, s45, v153
	s_barrier
	ds_read_b128 v[128:131], v140
	ds_read_b128 v[132:135], v140 offset:1024
	ds_read_b128 v[136:139], v140 offset:2048
	ds_read_b128 v[140:143], v140 offset:3072
	s_mov_b32 m0, s29
	v_lshl_add_u64 v[190:191], v[206:207], 0, s[6:7]
	ds_read_b128 v[158:161], v155 offset:32768
	ds_read_b128 v[162:165], v155 offset:33792
	ds_read_b128 v[166:169], v155 offset:34816
	ds_read_b128 v[170:173], v155 offset:35840
	ds_read_b128 v[174:177], v155 offset:36864
	ds_read_b128 v[178:181], v155 offset:37888
	ds_read_b128 v[182:185], v155 offset:38912
	ds_read_b128 v[186:189], v155 offset:39936
	global_load_lds_dwordx4 v[190:191], off
	v_lshl_add_u64 v[190:191], v[206:207], 0, s[8:9]
	s_mov_b32 m0, s30
	s_nop 0
	global_load_lds_dwordx4 v[190:191], off
	s_waitcnt lgkmcnt(8)
	s_barrier
	s_waitcnt lgkmcnt(0)
	s_waitcnt lgkmcnt(0)
	v_mfma_f32_16x16x32_bf16 v[124:127], v[128:131], v[158:161], v[124:127]
	v_mfma_f32_16x16x32_bf16 v[120:123], v[136:139], v[158:161], v[120:123]
	v_mfma_f32_16x16x32_bf16 v[116:119], v[128:131], v[166:169], v[116:119]
	v_mfma_f32_16x16x32_bf16 v[112:115], v[136:139], v[166:169], v[112:115]
	v_mfma_f32_16x16x32_bf16 v[108:111], v[128:131], v[174:177], v[108:111]
	v_mfma_f32_16x16x32_bf16 v[100:103], v[136:139], v[174:177], v[100:103]
	v_mfma_f32_16x16x32_bf16 v[92:95], v[128:131], v[182:185], v[92:95]
	v_mfma_f32_16x16x32_bf16 v[84:87], v[136:139], v[182:185], v[84:87]
	v_mfma_f32_16x16x32_bf16 v[124:127], v[132:135], v[162:165], v[124:127]
	v_mfma_f32_16x16x32_bf16 v[120:123], v[140:143], v[162:165], v[120:123]
	v_mfma_f32_16x16x32_bf16 v[116:119], v[132:135], v[170:173], v[116:119]
	v_mfma_f32_16x16x32_bf16 v[112:115], v[140:143], v[170:173], v[112:115]
	v_mfma_f32_16x16x32_bf16 v[108:111], v[132:135], v[178:181], v[108:111]
	v_mfma_f32_16x16x32_bf16 v[100:103], v[140:143], v[178:181], v[100:103]
	v_mfma_f32_16x16x32_bf16 v[92:95], v[132:135], v[186:189], v[92:95]
	v_mfma_f32_16x16x32_bf16 v[84:87], v[140:143], v[186:189], v[84:87]
	s_barrier
	s_add_i32 s46, 0, 0x1c000
	s_add_i32 s45, s45, s20
	v_add_u32_e32 v157, s46, v153
	v_lshl_add_u64 v[208:209], v[150:151], 0, s[22:23]
	s_mov_b32 m0, s45
	ds_read_b128 v[190:193], v157
	ds_read_b128 v[194:197], v157 offset:1024
	ds_read_b128 v[198:201], v157 offset:2048
	ds_read_b128 v[202:205], v157 offset:3072
	global_load_lds_dwordx4 v[208:209], off
	v_lshl_add_u64 v[208:209], v[150:151], 0, s[24:25]
	s_add_i32 m0, s45, 0x2000
	s_nop 0
	global_load_lds_dwordx4 v[208:209], off
	s_barrier
	s_waitcnt lgkmcnt(0)
	s_waitcnt lgkmcnt(0)
	v_mfma_f32_16x16x32_bf16 v[104:107], v[190:193], v[158:161], v[104:107]
	v_mfma_f32_16x16x32_bf16 v[96:99], v[198:201], v[158:161], v[96:99]
	v_mfma_f32_16x16x32_bf16 v[88:91], v[190:193], v[166:169], v[88:91]
	v_mfma_f32_16x16x32_bf16 v[80:83], v[198:201], v[166:169], v[80:83]
	v_mfma_f32_16x16x32_bf16 v[76:79], v[190:193], v[174:177], v[76:79]
	v_mfma_f32_16x16x32_bf16 v[72:75], v[198:201], v[174:177], v[72:75]
	v_mfma_f32_16x16x32_bf16 v[68:71], v[190:193], v[182:185], v[68:71]
	v_mfma_f32_16x16x32_bf16 v[64:67], v[198:201], v[182:185], v[64:67]
	v_mfma_f32_16x16x32_bf16 v[104:107], v[194:197], v[162:165], v[104:107]
	v_mfma_f32_16x16x32_bf16 v[96:99], v[202:205], v[162:165], v[96:99]
	v_mfma_f32_16x16x32_bf16 v[88:91], v[194:197], v[170:173], v[88:91]
	v_mfma_f32_16x16x32_bf16 v[80:83], v[202:205], v[170:173], v[80:83]
	v_mfma_f32_16x16x32_bf16 v[76:79], v[194:197], v[178:181], v[76:79]
	v_mfma_f32_16x16x32_bf16 v[72:75], v[202:205], v[178:181], v[72:75]
	v_mfma_f32_16x16x32_bf16 v[68:71], v[194:197], v[186:189], v[68:71]
	v_mfma_f32_16x16x32_bf16 v[64:67], v[202:205], v[186:189], v[64:67]
	s_mov_b32 m0, s31
	v_lshl_add_u64 v[208:209], v[206:207], 0, s[22:23]
	s_barrier
	ds_read_b128 v[158:161], v155 offset:49152
	ds_read_b128 v[162:165], v155 offset:50176
	ds_read_b128 v[166:169], v155 offset:51200
	ds_read_b128 v[170:173], v155 offset:52224
	ds_read_b128 v[174:177], v155 offset:53248
	ds_read_b128 v[178:181], v155 offset:54272
	ds_read_b128 v[182:185], v155 offset:55296
	ds_read_b128 v[186:189], v155 offset:56320
	global_load_lds_dwordx4 v[208:209], off
	v_lshl_add_u64 v[206:207], v[206:207], 0, s[24:25]
	s_mov_b32 m0, s33
	s_nop 0
	global_load_lds_dwordx4 v[206:207], off
	s_barrier
	s_waitcnt lgkmcnt(0)
	s_waitcnt lgkmcnt(0)
	v_mfma_f32_16x16x32_bf16 v[60:63], v[128:131], v[158:161], v[60:63]
	v_mfma_f32_16x16x32_bf16 v[56:59], v[136:139], v[158:161], v[56:59]
	v_mfma_f32_16x16x32_bf16 v[48:51], v[128:131], v[166:169], v[48:51]
	v_mfma_f32_16x16x32_bf16 v[40:43], v[136:139], v[166:169], v[40:43]
	v_mfma_f32_16x16x32_bf16 v[32:35], v[128:131], v[174:177], v[32:35]
	v_mfma_f32_16x16x32_bf16 v[24:27], v[136:139], v[174:177], v[24:27]
	v_mfma_f32_16x16x32_bf16 v[16:19], v[128:131], v[182:185], v[16:19]
	v_mfma_f32_16x16x32_bf16 v[8:11], v[136:139], v[182:185], v[8:11]
	v_mfma_f32_16x16x32_bf16 v[60:63], v[132:135], v[162:165], v[60:63]
	v_mfma_f32_16x16x32_bf16 v[56:59], v[140:143], v[162:165], v[56:59]
	v_mfma_f32_16x16x32_bf16 v[48:51], v[132:135], v[170:173], v[48:51]
	v_mfma_f32_16x16x32_bf16 v[40:43], v[140:143], v[170:173], v[40:43]
	v_mfma_f32_16x16x32_bf16 v[32:35], v[132:135], v[178:181], v[32:35]
	v_mfma_f32_16x16x32_bf16 v[24:27], v[140:143], v[178:181], v[24:27]
	v_mfma_f32_16x16x32_bf16 v[16:19], v[132:135], v[186:189], v[16:19]
	v_mfma_f32_16x16x32_bf16 v[8:11], v[140:143], v[186:189], v[8:11]
	s_barrier
	s_add_i32 s45, s46, s20
	v_lshl_add_u64 v[128:129], v[150:151], 0, s[26:27]
	s_mov_b32 m0, s45
	s_nop 0
	global_load_lds_dwordx4 v[128:129], off
	v_lshl_add_u64 v[128:129], v[150:151], 0, s[34:35]
	s_add_i32 m0, s45, 0x2000
	s_nop 0
	global_load_lds_dwordx4 v[128:129], off
	s_waitcnt vmcnt(6)
	s_barrier
	v_mfma_f32_16x16x32_bf16 v[52:55], v[190:193], v[158:161], v[52:55]
	v_mfma_f32_16x16x32_bf16 v[44:47], v[198:201], v[158:161], v[44:47]
	v_mfma_f32_16x16x32_bf16 v[36:39], v[190:193], v[166:169], v[36:39]
	v_mfma_f32_16x16x32_bf16 v[28:31], v[198:201], v[166:169], v[28:31]
	v_mfma_f32_16x16x32_bf16 v[20:23], v[190:193], v[174:177], v[20:23]
	v_mfma_f32_16x16x32_bf16 v[12:15], v[198:201], v[174:177], v[12:15]
	v_mfma_f32_16x16x32_bf16 v[4:7], v[190:193], v[182:185], v[4:7]
	v_mfma_f32_16x16x32_bf16 v[0:3], v[198:201], v[182:185], v[0:3]
	v_mfma_f32_16x16x32_bf16 v[52:55], v[194:197], v[162:165], v[52:55]
	v_mfma_f32_16x16x32_bf16 v[44:47], v[202:205], v[162:165], v[44:47]
	v_mfma_f32_16x16x32_bf16 v[36:39], v[194:197], v[170:173], v[36:39]
	v_mfma_f32_16x16x32_bf16 v[28:31], v[202:205], v[170:173], v[28:31]
	v_mfma_f32_16x16x32_bf16 v[20:23], v[194:197], v[178:181], v[20:23]
	v_mfma_f32_16x16x32_bf16 v[12:15], v[202:205], v[178:181], v[12:15]
	v_mfma_f32_16x16x32_bf16 v[4:7], v[194:197], v[186:189], v[4:7]
	v_mfma_f32_16x16x32_bf16 v[0:3], v[202:205], v[186:189], v[0:3]
	s_add_i32 s44, s44, 2
	s_add_u32 s60, s60, 0x100
	s_addc_u32 s61, s61, 0
	s_add_u32 s42, s42, 0x100
	s_addc_u32 s43, s43, 0
	s_cmp_gt_u32 s44, 29
	s_barrier
	s_cbranch_scc0 .LBB0_285
	v_mov_b32_e32 v157, v152
	s_mov_b32 s42, s36
	s_mov_b32 s43, s17
	s_lshl_b32 s44, s58, 8
	s_lshl_b32 s42, s42, 5
	s_add_i32 s42, s42, s44
	v_lshrrev_b32_e32 v128, 1, v157
	v_and_or_b32 v150, v128, 24, s42
	v_ashrrev_i32_e32 v151, 31, v150
	v_lshl_add_u64 v[128:129], v[150:151], 2, s[18:19]
	global_load_dwordx4 v[140:143], v[128:129], off
	global_load_dwordx4 v[136:139], v[128:129], off offset:16
	global_load_dwordx4 v[132:135], v[128:129], off offset:512
	s_nop 0
	global_load_dwordx4 v[128:131], v[128:129], off offset:528
	s_lshl_b32 s42, s56, 8
	v_and_or_b32 v157, v157, 15, s42
	v_lshl_add_u32 v157, s43, 6, v157
	v_lshl_add_u64 v[150:151], v[150:151], 1, s[10:11]
	v_mad_i64_i32 v[158:159], s[42:43], v157, s41, v[150:151]
	v_or_b32_e32 v160, 16, v157
	v_mad_i64_i32 v[160:161], s[42:43], v160, s41, v[150:151]
	v_or_b32_e32 v162, 32, v157
	v_mad_i64_i32 v[162:163], s[42:43], v162, s41, v[150:151]
	v_or_b32_e32 v168, 48, v157
	s_mov_b64 s[60:61], -1
	s_waitcnt vmcnt(0)
	v_pk_add_f32 v[126:127], v[126:127], v[142:143]
	v_pk_add_f32 v[124:125], v[124:125], v[140:141]
	v_pk_add_f32 v[166:167], v[68:69], v[132:133]
	v_cvt_pk_bf16_f32 v68, v124, v125
	v_cvt_pk_bf16_f32 v69, v126, v127
	v_pk_add_f32 v[122:123], v[122:123], v[138:139]
	v_pk_add_f32 v[120:121], v[120:121], v[136:137]
	v_pk_add_f32 v[106:107], v[106:107], v[134:135]
	v_pk_add_f32 v[104:105], v[104:105], v[132:133]
	v_pk_add_f32 v[164:165], v[70:71], v[134:135]
	v_cvt_pk_bf16_f32 v70, v120, v121
	v_cvt_pk_bf16_f32 v71, v122, v123
	global_store_dwordx4 v[158:159], v[68:71], off
	v_pk_add_f32 v[98:99], v[98:99], v[130:131]
	v_pk_add_f32 v[96:97], v[96:97], v[128:129]
	v_cvt_pk_bf16_f32 v68, v104, v105
	v_cvt_pk_bf16_f32 v69, v106, v107
	v_pk_add_f32 v[118:119], v[118:119], v[142:143]
	v_pk_add_f32 v[116:117], v[116:117], v[140:141]
	v_cvt_pk_bf16_f32 v70, v96, v97
	v_cvt_pk_bf16_f32 v71, v98, v99
	global_store_dwordx4 v[158:159], v[68:71], off offset:256
	v_pk_add_f32 v[114:115], v[114:115], v[138:139]
	v_pk_add_f32 v[112:113], v[112:113], v[136:137]
	v_cvt_pk_bf16_f32 v68, v116, v117
	v_cvt_pk_bf16_f32 v69, v118, v119
	v_pk_add_f32 v[90:91], v[90:91], v[134:135]
	v_pk_add_f32 v[88:89], v[88:89], v[132:133]
	v_cvt_pk_bf16_f32 v70, v112, v113
	v_cvt_pk_bf16_f32 v71, v114, v115
	global_store_dwordx4 v[160:161], v[68:71], off
	v_pk_add_f32 v[82:83], v[82:83], v[130:131]
	v_pk_add_f32 v[80:81], v[80:81], v[128:129]
	v_cvt_pk_bf16_f32 v68, v88, v89
	v_cvt_pk_bf16_f32 v69, v90, v91
	v_pk_add_f32 v[110:111], v[110:111], v[142:143]
	v_pk_add_f32 v[108:109], v[108:109], v[140:141]
	v_cvt_pk_bf16_f32 v70, v80, v81
	v_cvt_pk_bf16_f32 v71, v82, v83
	global_store_dwordx4 v[160:161], v[68:71], off offset:256
	v_pk_add_f32 v[102:103], v[102:103], v[138:139]
	v_pk_add_f32 v[100:101], v[100:101], v[136:137]
	v_cvt_pk_bf16_f32 v68, v108, v109
	v_cvt_pk_bf16_f32 v69, v110, v111
	v_pk_add_f32 v[78:79], v[78:79], v[134:135]
	v_pk_add_f32 v[76:77], v[76:77], v[132:133]
	v_cvt_pk_bf16_f32 v70, v100, v101
	v_cvt_pk_bf16_f32 v71, v102, v103
	global_store_dwordx4 v[162:163], v[68:71], off
	v_pk_add_f32 v[74:75], v[74:75], v[130:131]
	v_pk_add_f32 v[72:73], v[72:73], v[128:129]
	v_cvt_pk_bf16_f32 v68, v76, v77
	v_cvt_pk_bf16_f32 v69, v78, v79
	v_pk_add_f32 v[94:95], v[94:95], v[142:143]
	v_pk_add_f32 v[92:93], v[92:93], v[140:141]
	v_mad_i64_i32 v[124:125], s[42:43], v168, s41, v[150:151]
	v_cvt_pk_bf16_f32 v70, v72, v73
	v_cvt_pk_bf16_f32 v71, v74, v75
	global_store_dwordx4 v[162:163], v[68:71], off offset:256
	v_pk_add_f32 v[86:87], v[86:87], v[138:139]
	v_pk_add_f32 v[84:85], v[84:85], v[136:137]
	v_cvt_pk_bf16_f32 v68, v92, v93
	v_cvt_pk_bf16_f32 v69, v94, v95
	v_pk_add_f32 v[62:63], v[62:63], v[142:143]
	v_cvt_pk_bf16_f32 v70, v84, v85
	v_cvt_pk_bf16_f32 v71, v86, v87
	global_store_dwordx4 v[124:125], v[68:71], off
	v_pk_add_f32 v[60:61], v[60:61], v[140:141]
	v_pk_add_f32 v[52:53], v[52:53], v[132:133]
	v_pk_add_f32 v[68:69], v[66:67], v[130:131]
	v_pk_add_f32 v[66:67], v[64:65], v[128:129]
	v_cvt_pk_bf16_f32 v64, v166, v167
	v_cvt_pk_bf16_f32 v65, v164, v165
	v_pk_add_f32 v[54:55], v[54:55], v[134:135]
	v_cvt_pk_bf16_f32 v66, v66, v67
	v_cvt_pk_bf16_f32 v67, v68, v69
	global_store_dwordx4 v[124:125], v[64:67], off offset:256
	v_pk_add_f32 v[48:49], v[48:49], v[140:141]
	v_pk_add_f32 v[36:37], v[36:37], v[132:133]
	v_add_u32_e32 v64, 0x80, v157
	v_mad_i64_i32 v[64:65], s[42:43], v64, s41, v[150:151]
	v_pk_add_f32 v[66:67], v[58:59], v[138:139]
	v_pk_add_f32 v[58:59], v[56:57], v[136:137]
	v_cvt_pk_bf16_f32 v56, v60, v61
	v_cvt_pk_bf16_f32 v57, v62, v63
	v_pk_add_f32 v[38:39], v[38:39], v[134:135]
	v_cvt_pk_bf16_f32 v58, v58, v59
	v_cvt_pk_bf16_f32 v59, v66, v67
	global_store_dwordx4 v[64:65], v[56:59], off
	v_pk_add_f32 v[32:33], v[32:33], v[140:141]
	v_pk_add_f32 v[20:21], v[20:21], v[132:133]
	v_pk_add_f32 v[56:57], v[46:47], v[130:131]
	v_pk_add_f32 v[46:47], v[44:45], v[128:129]
	v_cvt_pk_bf16_f32 v44, v52, v53
	v_cvt_pk_bf16_f32 v45, v54, v55
	v_pk_add_f32 v[22:23], v[22:23], v[134:135]
	v_cvt_pk_bf16_f32 v46, v46, v47
	v_cvt_pk_bf16_f32 v47, v56, v57
	global_store_dwordx4 v[64:65], v[44:47], off offset:256
	v_pk_add_f32 v[16:17], v[16:17], v[140:141]
	v_pk_add_f32 v[6:7], v[6:7], v[134:135]
	v_add_u32_e32 v44, 0x90, v157
	v_mad_i64_i32 v[44:45], s[42:43], v44, s41, v[150:151]
	v_pk_add_f32 v[46:47], v[50:51], v[142:143]
	v_pk_add_f32 v[50:51], v[42:43], v[138:139]
	v_pk_add_f32 v[42:43], v[40:41], v[136:137]
	v_cvt_pk_bf16_f32 v40, v48, v49
	v_cvt_pk_bf16_f32 v41, v46, v47
	v_pk_add_f32 v[4:5], v[4:5], v[132:133]
	v_cvt_pk_bf16_f32 v42, v42, v43
	v_cvt_pk_bf16_f32 v43, v50, v51
	global_store_dwordx4 v[44:45], v[40:43], off
	s_nop 1
	v_pk_add_f32 v[40:41], v[30:31], v[130:131]
	v_pk_add_f32 v[30:31], v[28:29], v[128:129]
	v_cvt_pk_bf16_f32 v28, v36, v37
	v_cvt_pk_bf16_f32 v29, v38, v39
	s_nop 0
	v_cvt_pk_bf16_f32 v30, v30, v31
	v_cvt_pk_bf16_f32 v31, v40, v41
	global_store_dwordx4 v[44:45], v[28:31], off offset:256
	s_nop 1
	v_add_u32_e32 v28, 0xa0, v157
	v_mad_i64_i32 v[28:29], s[42:43], v28, s41, v[150:151]
	v_pk_add_f32 v[30:31], v[34:35], v[142:143]
	v_pk_add_f32 v[34:35], v[26:27], v[138:139]
	v_pk_add_f32 v[26:27], v[24:25], v[136:137]
	v_cvt_pk_bf16_f32 v24, v32, v33
	v_cvt_pk_bf16_f32 v25, v30, v31
	s_nop 0
	v_cvt_pk_bf16_f32 v26, v26, v27
	v_cvt_pk_bf16_f32 v27, v34, v35
	global_store_dwordx4 v[28:29], v[24:27], off
	s_nop 1
	v_pk_add_f32 v[24:25], v[14:15], v[130:131]
	v_pk_add_f32 v[14:15], v[12:13], v[128:129]
	v_cvt_pk_bf16_f32 v12, v20, v21
	v_cvt_pk_bf16_f32 v13, v22, v23
	s_nop 0
	v_cvt_pk_bf16_f32 v14, v14, v15
	v_cvt_pk_bf16_f32 v15, v24, v25
	global_store_dwordx4 v[28:29], v[12:15], off offset:256
	s_nop 1
	v_add_u32_e32 v12, 0xb0, v157
	v_mad_i64_i32 v[12:13], s[42:43], v12, s41, v[150:151]
	v_pk_add_f32 v[14:15], v[18:19], v[142:143]
	v_pk_add_f32 v[18:19], v[10:11], v[138:139]
	v_pk_add_f32 v[10:11], v[8:9], v[136:137]
	v_cvt_pk_bf16_f32 v8, v16, v17
	v_cvt_pk_bf16_f32 v9, v14, v15
	s_mov_b32 s42, s37
	v_cvt_pk_bf16_f32 v10, v10, v11
	v_cvt_pk_bf16_f32 v11, v18, v19
	global_store_dwordx4 v[12:13], v[8:11], off
	s_nop 1
	v_pk_add_f32 v[8:9], v[2:3], v[130:131]
	v_pk_add_f32 v[2:3], v[0:1], v[128:129]
	v_cvt_pk_bf16_f32 v0, v4, v5
	v_cvt_pk_bf16_f32 v1, v6, v7
	s_nop 0
	v_cvt_pk_bf16_f32 v2, v2, v3
	v_cvt_pk_bf16_f32 v3, v8, v9
	global_store_dwordx4 v[12:13], v[0:3], off offset:256
	s_mul_i32 s42, s42, s0
	s_add_i32 s42, s42, s1
	s_cmpk_gt_i32 s42, 0x4c7
	s_cbranch_scc1 .LBB0_281
	s_ashr_i32 s43, s42, 31
	s_lshr_b32 s43, s43, 29
	s_add_i32 s43, s42, s43
	s_ashr_i32 s44, s43, 3
	s_and_b32 s43, s43, -8
	s_sub_i32 s42, s42, s43
	s_cmp_lt_i32 s42, 0
	s_cselect_b32 s43, s38, 0x99
	s_mul_i32 s42, s43, s42
	s_add_i32 s42, s42, s44
	s_mul_hi_i32 s43, s42, 0x38e38e39
	s_lshr_b32 s44, s43, 31
	s_ashr_i32 s43, s43, 6
	s_add_i32 s43, s43, s44
	s_lshl_b32 s44, s43, 3
	s_sub_i32 s45, 34, s44
	s_min_u32 s45, s45, 8
	s_mulk_i32 s43, 0x120
	s_sub_i32 s46, s42, s43
	v_cvt_f32_ubyte0_e32 v1, s45
	v_cvt_f32_i32_e32 v0, s46
	v_rcp_iflag_f32_e32 v2, v1
	s_ashr_i32 s42, s46, 30
	s_or_b32 s47, s42, 1
	s_mov_b64 s[60:61], 0
	v_mul_f32_e32 v2, v0, v2
	v_trunc_f32_e32 v2, v2
	v_fma_f32 v0, -v2, v1, v0
	v_cvt_i32_f32_e32 v2, v2
	v_cmp_ge_f32_e64 s[42:43], |v0|, v1
	s_and_b64 s[42:43], s[42:43], exec
	s_cselect_b32 s42, s47, 0
	v_readfirstlane_b32 s43, v2
	s_add_i32 s42, s43, s42
	s_sext_i32_i16 s58, s42
	s_mul_i32 s42, s42, s45
	s_sub_i32 s42, s46, s42
	s_sext_i32_i16 s42, s42
	s_add_i32 s56, s44, s42
	s_branch .LBB0_281

.LBB0_320:
	ds_read_b128 v[142:145], v138
	ds_read_b128 v[146:149], v138 offset:1024
	ds_read_b128 v[150:153], v138 offset:2048
	ds_read_b128 v[154:157], v138 offset:3072
	s_add_u32 s47, s66, 0xffdc0080
	s_addc_u32 s48, s67, -1
	s_cmp_eq_u32 s46, 4
	s_cselect_b32 s49, s63, s48
	s_cselect_b32 s48, s62, s47
	s_cselect_b32 s51, s65, s45
	s_cselect_b32 s50, s64, s44
	v_lshl_add_u64 v[134:135], s[66:67], 0, v[132:133]
	s_add_i32 m0, s28, 0xc000
	ds_read_b128 v[158:161], v139
	ds_read_b128 v[162:165], v139 offset:1024
	ds_read_b128 v[166:169], v139 offset:2048
	ds_read_b128 v[170:173], v139 offset:3072
	ds_read_b128 v[174:177], v139 offset:4096
	ds_read_b128 v[178:181], v139 offset:5120
	ds_read_b128 v[182:185], v139 offset:6144
	ds_read_b128 v[186:189], v139 offset:7168
	global_load_lds_dwordx4 v[134:135], off
	v_lshl_add_u64 v[134:135], v[134:135], 0, s[10:11]
	s_add_i32 m0, s28, 0xe000
	s_nop 0
	global_load_lds_dwordx4 v[134:135], off
	s_waitcnt lgkmcnt(8)
	s_barrier
	s_waitcnt lgkmcnt(0)
	s_waitcnt lgkmcnt(0)
	v_mfma_f32_16x16x32_bf16 v[124:127], v[142:145], v[158:161], v[124:127]
	v_mfma_f32_16x16x32_bf16 v[120:123], v[150:153], v[158:161], v[120:123]
	v_mfma_f32_16x16x32_bf16 v[112:115], v[142:145], v[166:169], v[112:115]
	v_mfma_f32_16x16x32_bf16 v[104:107], v[150:153], v[166:169], v[104:107]
	v_mfma_f32_16x16x32_bf16 v[96:99], v[142:145], v[174:177], v[96:99]
	v_mfma_f32_16x16x32_bf16 v[88:91], v[150:153], v[174:177], v[88:91]
	v_mfma_f32_16x16x32_bf16 v[80:83], v[142:145], v[182:185], v[80:83]
	v_mfma_f32_16x16x32_bf16 v[72:75], v[150:153], v[182:185], v[72:75]
	v_mfma_f32_16x16x32_bf16 v[124:127], v[146:149], v[162:165], v[124:127]
	v_mfma_f32_16x16x32_bf16 v[120:123], v[154:157], v[162:165], v[120:123]
	v_mfma_f32_16x16x32_bf16 v[112:115], v[146:149], v[170:173], v[112:115]
	v_mfma_f32_16x16x32_bf16 v[104:107], v[154:157], v[170:173], v[104:107]
	v_mfma_f32_16x16x32_bf16 v[96:99], v[146:149], v[178:181], v[96:99]
	v_mfma_f32_16x16x32_bf16 v[88:91], v[154:157], v[178:181], v[88:91]
	v_mfma_f32_16x16x32_bf16 v[80:83], v[146:149], v[186:189], v[80:83]
	v_mfma_f32_16x16x32_bf16 v[72:75], v[154:157], v[186:189], v[72:75]
	s_barrier
	s_add_i32 s47, s39, s21
	v_lshl_add_u64 v[134:135], s[50:51], 0, v[130:131]
	s_mov_b32 m0, s47
	ds_read_b128 v[190:193], v140
	ds_read_b128 v[194:197], v140 offset:1024
	ds_read_b128 v[198:201], v140 offset:2048
	ds_read_b128 v[202:205], v140 offset:3072
	global_load_lds_dwordx4 v[134:135], off
	v_lshl_add_u64 v[206:207], v[134:135], 0, s[8:9]
	s_add_i32 m0, s47, 0x2000
	s_nop 0
	global_load_lds_dwordx4 v[206:207], off
	s_barrier
	s_waitcnt lgkmcnt(0)
	s_waitcnt lgkmcnt(0)
	v_mfma_f32_16x16x32_bf16 v[116:119], v[190:193], v[158:161], v[116:119]
	v_mfma_f32_16x16x32_bf16 v[108:111], v[198:201], v[158:161], v[108:111]
	v_mfma_f32_16x16x32_bf16 v[100:103], v[190:193], v[166:169], v[100:103]
	v_mfma_f32_16x16x32_bf16 v[92:95], v[198:201], v[166:169], v[92:95]
	v_mfma_f32_16x16x32_bf16 v[84:87], v[190:193], v[174:177], v[84:87]
	v_mfma_f32_16x16x32_bf16 v[76:79], v[198:201], v[174:177], v[76:79]
	v_mfma_f32_16x16x32_bf16 v[68:71], v[190:193], v[182:185], v[68:71]
	v_mfma_f32_16x16x32_bf16 v[64:67], v[198:201], v[182:185], v[64:67]
	v_mfma_f32_16x16x32_bf16 v[116:119], v[194:197], v[162:165], v[116:119]
	v_mfma_f32_16x16x32_bf16 v[108:111], v[202:205], v[162:165], v[108:111]
	v_mfma_f32_16x16x32_bf16 v[100:103], v[194:197], v[170:173], v[100:103]
	v_mfma_f32_16x16x32_bf16 v[92:95], v[202:205], v[170:173], v[92:95]
	v_mfma_f32_16x16x32_bf16 v[84:87], v[194:197], v[178:181], v[84:87]
	v_mfma_f32_16x16x32_bf16 v[76:79], v[202:205], v[178:181], v[76:79]
	v_mfma_f32_16x16x32_bf16 v[68:71], v[194:197], v[186:189], v[68:71]
	v_mfma_f32_16x16x32_bf16 v[64:67], v[202:205], v[186:189], v[64:67]
	s_mov_b32 m0, s28
	v_lshl_add_u64 v[206:207], s[48:49], 0, v[128:129]
	s_barrier
	ds_read_b128 v[158:161], v139 offset:16384
	ds_read_b128 v[162:165], v139 offset:17408
	ds_read_b128 v[166:169], v139 offset:18432
	ds_read_b128 v[170:173], v139 offset:19456
	ds_read_b128 v[174:177], v139 offset:20480
	ds_read_b128 v[178:181], v139 offset:21504
	ds_read_b128 v[182:185], v139 offset:22528
	ds_read_b128 v[186:189], v139 offset:23552
	global_load_lds_dwordx4 v[206:207], off
	v_lshl_add_u64 v[208:209], v[206:207], 0, s[10:11]
	s_mov_b32 m0, s29
	s_nop 0
	global_load_lds_dwordx4 v[208:209], off
	s_barrier
	s_waitcnt lgkmcnt(0)
	s_waitcnt lgkmcnt(0)
	v_mfma_f32_16x16x32_bf16 v[60:63], v[142:145], v[158:161], v[60:63]
	v_mfma_f32_16x16x32_bf16 v[56:59], v[150:153], v[158:161], v[56:59]
	v_mfma_f32_16x16x32_bf16 v[48:51], v[142:145], v[166:169], v[48:51]
	v_mfma_f32_16x16x32_bf16 v[40:43], v[150:153], v[166:169], v[40:43]
	v_mfma_f32_16x16x32_bf16 v[32:35], v[142:145], v[174:177], v[32:35]
	v_mfma_f32_16x16x32_bf16 v[24:27], v[150:153], v[174:177], v[24:27]
	v_mfma_f32_16x16x32_bf16 v[16:19], v[142:145], v[182:185], v[16:19]
	v_mfma_f32_16x16x32_bf16 v[8:11], v[150:153], v[182:185], v[8:11]
	v_mfma_f32_16x16x32_bf16 v[60:63], v[146:149], v[162:165], v[60:63]
	v_mfma_f32_16x16x32_bf16 v[56:59], v[154:157], v[162:165], v[56:59]
	v_mfma_f32_16x16x32_bf16 v[48:51], v[146:149], v[170:173], v[48:51]
	v_mfma_f32_16x16x32_bf16 v[40:43], v[154:157], v[170:173], v[40:43]
	v_mfma_f32_16x16x32_bf16 v[32:35], v[146:149], v[178:181], v[32:35]
	v_mfma_f32_16x16x32_bf16 v[24:27], v[154:157], v[178:181], v[24:27]
	v_mfma_f32_16x16x32_bf16 v[16:19], v[146:149], v[186:189], v[16:19]
	v_mfma_f32_16x16x32_bf16 v[8:11], v[154:157], v[186:189], v[8:11]
	s_barrier
	s_add_i32 s47, s40, s21
	v_lshl_add_u64 v[142:143], v[134:135], 0, s[18:19]
	s_mov_b32 m0, s47
	s_nop 0
	global_load_lds_dwordx4 v[142:143], off
	v_lshl_add_u64 v[142:143], v[134:135], 0, s[22:23]
	s_add_i32 m0, s47, 0x2000
	s_nop 0
	global_load_lds_dwordx4 v[142:143], off
	s_waitcnt vmcnt(6)
	s_barrier
	v_mfma_f32_16x16x32_bf16 v[52:55], v[190:193], v[158:161], v[52:55]
	v_mfma_f32_16x16x32_bf16 v[44:47], v[198:201], v[158:161], v[44:47]
	v_mfma_f32_16x16x32_bf16 v[36:39], v[190:193], v[166:169], v[36:39]
	v_mfma_f32_16x16x32_bf16 v[28:31], v[198:201], v[166:169], v[28:31]
	v_mfma_f32_16x16x32_bf16 v[20:23], v[190:193], v[174:177], v[20:23]
	v_mfma_f32_16x16x32_bf16 v[12:15], v[198:201], v[174:177], v[12:15]
	v_mfma_f32_16x16x32_bf16 v[4:7], v[190:193], v[182:185], v[4:7]
	v_mfma_f32_16x16x32_bf16 v[0:3], v[198:201], v[182:185], v[0:3]
	v_mfma_f32_16x16x32_bf16 v[52:55], v[194:197], v[162:165], v[52:55]
	v_mfma_f32_16x16x32_bf16 v[44:47], v[202:205], v[162:165], v[44:47]
	v_mfma_f32_16x16x32_bf16 v[36:39], v[194:197], v[170:173], v[36:39]
	v_mfma_f32_16x16x32_bf16 v[28:31], v[202:205], v[170:173], v[28:31]
	v_mfma_f32_16x16x32_bf16 v[20:23], v[194:197], v[178:181], v[20:23]
	v_mfma_f32_16x16x32_bf16 v[12:15], v[202:205], v[178:181], v[12:15]
	v_mfma_f32_16x16x32_bf16 v[4:7], v[194:197], v[186:189], v[4:7]
	v_mfma_f32_16x16x32_bf16 v[0:3], v[202:205], v[186:189], v[0:3]
	s_add_i32 s47, 0, 0x18000
	v_add_u32_e32 v141, s47, v137
	s_barrier
	ds_read_b128 v[142:145], v141
	ds_read_b128 v[146:149], v141 offset:1024
	ds_read_b128 v[150:153], v141 offset:2048
	ds_read_b128 v[154:157], v141 offset:3072
	s_mov_b32 m0, s30
	v_lshl_add_u64 v[190:191], v[206:207], 0, s[24:25]
	ds_read_b128 v[158:161], v139 offset:32768
	ds_read_b128 v[162:165], v139 offset:33792
	ds_read_b128 v[166:169], v139 offset:34816
	ds_read_b128 v[170:173], v139 offset:35840
	ds_read_b128 v[174:177], v139 offset:36864
	ds_read_b128 v[178:181], v139 offset:37888
	ds_read_b128 v[182:185], v139 offset:38912
	ds_read_b128 v[186:189], v139 offset:39936
	global_load_lds_dwordx4 v[190:191], off
	v_lshl_add_u64 v[190:191], v[206:207], 0, s[26:27]
	s_mov_b32 m0, s31
	s_nop 0
	global_load_lds_dwordx4 v[190:191], off
	s_waitcnt lgkmcnt(8)
	s_barrier
	s_waitcnt lgkmcnt(0)
	s_waitcnt lgkmcnt(0)
	v_mfma_f32_16x16x32_bf16 v[124:127], v[142:145], v[158:161], v[124:127]
	v_mfma_f32_16x16x32_bf16 v[120:123], v[150:153], v[158:161], v[120:123]
	v_mfma_f32_16x16x32_bf16 v[112:115], v[142:145], v[166:169], v[112:115]
	v_mfma_f32_16x16x32_bf16 v[104:107], v[150:153], v[166:169], v[104:107]
	v_mfma_f32_16x16x32_bf16 v[96:99], v[142:145], v[174:177], v[96:99]
	v_mfma_f32_16x16x32_bf16 v[88:91], v[150:153], v[174:177], v[88:91]
	v_mfma_f32_16x16x32_bf16 v[80:83], v[142:145], v[182:185], v[80:83]
	v_mfma_f32_16x16x32_bf16 v[72:75], v[150:153], v[182:185], v[72:75]
	v_mfma_f32_16x16x32_bf16 v[124:127], v[146:149], v[162:165], v[124:127]
	v_mfma_f32_16x16x32_bf16 v[120:123], v[154:157], v[162:165], v[120:123]
	v_mfma_f32_16x16x32_bf16 v[112:115], v[146:149], v[170:173], v[112:115]
	v_mfma_f32_16x16x32_bf16 v[104:107], v[154:157], v[170:173], v[104:107]
	v_mfma_f32_16x16x32_bf16 v[96:99], v[146:149], v[178:181], v[96:99]
	v_mfma_f32_16x16x32_bf16 v[88:91], v[154:157], v[178:181], v[88:91]
	v_mfma_f32_16x16x32_bf16 v[80:83], v[146:149], v[186:189], v[80:83]
	v_mfma_f32_16x16x32_bf16 v[72:75], v[154:157], v[186:189], v[72:75]
	s_barrier
	s_add_i32 s48, 0, 0x1c000
	s_add_i32 s47, s47, s21
	v_add_u32_e32 v141, s48, v137
	v_lshl_add_u64 v[208:209], v[134:135], 0, s[52:53]
	s_mov_b32 m0, s47
	ds_read_b128 v[190:193], v141
	ds_read_b128 v[194:197], v141 offset:1024
	ds_read_b128 v[198:201], v141 offset:2048
	ds_read_b128 v[202:205], v141 offset:3072
	global_load_lds_dwordx4 v[208:209], off
	v_lshl_add_u64 v[208:209], v[134:135], 0, s[54:55]
	s_add_i32 m0, s47, 0x2000
	s_nop 0
	global_load_lds_dwordx4 v[208:209], off
	s_barrier
	s_waitcnt lgkmcnt(0)
	s_waitcnt lgkmcnt(0)
	v_mfma_f32_16x16x32_bf16 v[116:119], v[190:193], v[158:161], v[116:119]
	v_mfma_f32_16x16x32_bf16 v[108:111], v[198:201], v[158:161], v[108:111]
	v_mfma_f32_16x16x32_bf16 v[100:103], v[190:193], v[166:169], v[100:103]
	v_mfma_f32_16x16x32_bf16 v[92:95], v[198:201], v[166:169], v[92:95]
	v_mfma_f32_16x16x32_bf16 v[84:87], v[190:193], v[174:177], v[84:87]
	v_mfma_f32_16x16x32_bf16 v[76:79], v[198:201], v[174:177], v[76:79]
	v_mfma_f32_16x16x32_bf16 v[68:71], v[190:193], v[182:185], v[68:71]
	v_mfma_f32_16x16x32_bf16 v[64:67], v[198:201], v[182:185], v[64:67]
	v_mfma_f32_16x16x32_bf16 v[116:119], v[194:197], v[162:165], v[116:119]
	v_mfma_f32_16x16x32_bf16 v[108:111], v[202:205], v[162:165], v[108:111]
	v_mfma_f32_16x16x32_bf16 v[100:103], v[194:197], v[170:173], v[100:103]
	v_mfma_f32_16x16x32_bf16 v[92:95], v[202:205], v[170:173], v[92:95]
	v_mfma_f32_16x16x32_bf16 v[84:87], v[194:197], v[178:181], v[84:87]
	v_mfma_f32_16x16x32_bf16 v[76:79], v[202:205], v[178:181], v[76:79]
	v_mfma_f32_16x16x32_bf16 v[68:71], v[194:197], v[186:189], v[68:71]
	v_mfma_f32_16x16x32_bf16 v[64:67], v[202:205], v[186:189], v[64:67]
	s_mov_b32 m0, s37
	v_lshl_add_u64 v[208:209], v[206:207], 0, s[52:53]
	s_barrier
	ds_read_b128 v[158:161], v139 offset:49152
	ds_read_b128 v[162:165], v139 offset:50176
	ds_read_b128 v[166:169], v139 offset:51200
	ds_read_b128 v[170:173], v139 offset:52224
	ds_read_b128 v[174:177], v139 offset:53248
	ds_read_b128 v[178:181], v139 offset:54272
	ds_read_b128 v[182:185], v139 offset:55296
	ds_read_b128 v[186:189], v139 offset:56320
	global_load_lds_dwordx4 v[208:209], off
	v_lshl_add_u64 v[206:207], v[206:207], 0, s[56:57]
	s_mov_b32 m0, s38
	s_nop 0
	global_load_lds_dwordx4 v[206:207], off
	s_barrier
	s_waitcnt lgkmcnt(0)
	s_waitcnt lgkmcnt(0)
	v_mfma_f32_16x16x32_bf16 v[60:63], v[142:145], v[158:161], v[60:63]
	v_mfma_f32_16x16x32_bf16 v[56:59], v[150:153], v[158:161], v[56:59]
	v_mfma_f32_16x16x32_bf16 v[48:51], v[142:145], v[166:169], v[48:51]
	v_mfma_f32_16x16x32_bf16 v[40:43], v[150:153], v[166:169], v[40:43]
	v_mfma_f32_16x16x32_bf16 v[32:35], v[142:145], v[174:177], v[32:35]
	v_mfma_f32_16x16x32_bf16 v[24:27], v[150:153], v[174:177], v[24:27]
	v_mfma_f32_16x16x32_bf16 v[16:19], v[142:145], v[182:185], v[16:19]
	v_mfma_f32_16x16x32_bf16 v[8:11], v[150:153], v[182:185], v[8:11]
	v_mfma_f32_16x16x32_bf16 v[60:63], v[146:149], v[162:165], v[60:63]
	v_mfma_f32_16x16x32_bf16 v[56:59], v[154:157], v[162:165], v[56:59]
	v_mfma_f32_16x16x32_bf16 v[48:51], v[146:149], v[170:173], v[48:51]
	v_mfma_f32_16x16x32_bf16 v[40:43], v[154:157], v[170:173], v[40:43]
	v_mfma_f32_16x16x32_bf16 v[32:35], v[146:149], v[178:181], v[32:35]
	v_mfma_f32_16x16x32_bf16 v[24:27], v[154:157], v[178:181], v[24:27]
	v_mfma_f32_16x16x32_bf16 v[16:19], v[146:149], v[186:189], v[16:19]
	v_mfma_f32_16x16x32_bf16 v[8:11], v[154:157], v[186:189], v[8:11]
	s_barrier
	s_add_i32 s47, s48, s21
	v_lshl_add_u64 v[142:143], v[134:135], 0, s[58:59]
	s_mov_b32 m0, s47
	v_lshl_add_u64 v[134:135], v[134:135], 0, s[60:61]
	global_load_lds_dwordx4 v[142:143], off
	s_add_i32 m0, s47, 0x2000
	s_nop 0
	global_load_lds_dwordx4 v[134:135], off
	s_waitcnt vmcnt(6)
	s_barrier
	v_mfma_f32_16x16x32_bf16 v[52:55], v[190:193], v[158:161], v[52:55]
	v_mfma_f32_16x16x32_bf16 v[44:47], v[198:201], v[158:161], v[44:47]
	v_mfma_f32_16x16x32_bf16 v[36:39], v[190:193], v[166:169], v[36:39]
	v_mfma_f32_16x16x32_bf16 v[28:31], v[198:201], v[166:169], v[28:31]
	v_mfma_f32_16x16x32_bf16 v[20:23], v[190:193], v[174:177], v[20:23]
	v_mfma_f32_16x16x32_bf16 v[12:15], v[198:201], v[174:177], v[12:15]
	v_mfma_f32_16x16x32_bf16 v[4:7], v[190:193], v[182:185], v[4:7]
	v_mfma_f32_16x16x32_bf16 v[0:3], v[198:201], v[182:185], v[0:3]
	v_mfma_f32_16x16x32_bf16 v[52:55], v[194:197], v[162:165], v[52:55]
	v_mfma_f32_16x16x32_bf16 v[44:47], v[202:205], v[162:165], v[44:47]
	v_mfma_f32_16x16x32_bf16 v[36:39], v[194:197], v[170:173], v[36:39]
	v_mfma_f32_16x16x32_bf16 v[28:31], v[202:205], v[170:173], v[28:31]
	v_mfma_f32_16x16x32_bf16 v[20:23], v[194:197], v[178:181], v[20:23]
	v_mfma_f32_16x16x32_bf16 v[12:15], v[202:205], v[178:181], v[12:15]
	v_mfma_f32_16x16x32_bf16 v[4:7], v[194:197], v[186:189], v[4:7]
	v_mfma_f32_16x16x32_bf16 v[0:3], v[202:205], v[186:189], v[0:3]
	s_add_i32 s46, s46, 2
	s_add_u32 s66, s66, 0x100
	s_addc_u32 s67, s67, 0
	s_add_u32 s44, s44, 0x100
	s_addc_u32 s45, s45, 0
	s_cmp_gt_u32 s46, 5
	s_barrier
	s_cbranch_scc0 .LBB0_320
	v_mov_b32_e32 v141, v136
	s_mov_b32 s44, s20
	s_mov_b32 s45, s36
	s_lshl_b32 s43, s43, 8
	s_lshl_b32 s45, s45, 5
	s_add_i32 s45, s45, s43
	v_lshrrev_b32_e32 v134, 1, v141
	v_and_or_b32 v134, v134, 24, s45
	s_lshl_b32 s42, s42, 8
	v_ashrrev_i32_e32 v135, 31, v134
	v_and_or_b32 v141, v141, 15, s42
	v_lshl_add_u32 v141, s44, 6, v141
	v_lshl_add_u64 v[134:135], v[134:135], 1, s[34:35]
	v_mad_i64_i32 v[142:143], s[42:43], v141, s41, v[134:135]
	v_pk_add_f32 v[126:127], v[126:127], 0 op_sel_hi:[1,0]
	v_pk_add_f32 v[124:125], v[124:125], 0 op_sel_hi:[1,0]
	v_pk_add_f32 v[144:145], v[122:123], 0 op_sel_hi:[1,0]
	v_pk_add_f32 v[122:123], v[120:121], 0 op_sel_hi:[1,0]
	v_cvt_pk_bf16_f32 v120, v124, v125
	v_cvt_pk_bf16_f32 v121, v126, v127
	v_pk_add_f32 v[116:117], v[116:117], 0 op_sel_hi:[1,0]
	v_cvt_pk_bf16_f32 v122, v122, v123
	v_cvt_pk_bf16_f32 v123, v144, v145
	global_store_dwordx4 v[142:143], v[120:123], off
	v_pk_add_f32 v[118:119], v[118:119], 0 op_sel_hi:[1,0]
	v_pk_add_f32 v[112:113], v[112:113], 0 op_sel_hi:[1,0]
	v_pk_add_f32 v[120:121], v[110:111], 0 op_sel_hi:[1,0]
	v_pk_add_f32 v[110:111], v[108:109], 0 op_sel_hi:[1,0]
	v_cvt_pk_bf16_f32 v108, v116, v117
	v_cvt_pk_bf16_f32 v109, v118, v119
	v_pk_add_f32 v[100:101], v[100:101], 0 op_sel_hi:[1,0]
	v_cvt_pk_bf16_f32 v110, v110, v111
	v_cvt_pk_bf16_f32 v111, v120, v121
	global_store_dwordx4 v[142:143], v[108:111], off offset:256
	v_pk_add_f32 v[102:103], v[102:103], 0 op_sel_hi:[1,0]
	v_pk_add_f32 v[96:97], v[96:97], 0 op_sel_hi:[1,0]
	v_or_b32_e32 v108, 16, v141
	v_mad_i64_i32 v[108:109], s[42:43], v108, s41, v[134:135]
	v_pk_add_f32 v[110:111], v[114:115], 0 op_sel_hi:[1,0]
	v_pk_add_f32 v[114:115], v[106:107], 0 op_sel_hi:[1,0]
	v_pk_add_f32 v[106:107], v[104:105], 0 op_sel_hi:[1,0]
	v_cvt_pk_bf16_f32 v104, v112, v113
	v_cvt_pk_bf16_f32 v105, v110, v111
	v_pk_add_f32 v[84:85], v[84:85], 0 op_sel_hi:[1,0]
	v_cvt_pk_bf16_f32 v106, v106, v107
	v_cvt_pk_bf16_f32 v107, v114, v115
	global_store_dwordx4 v[108:109], v[104:107], off
	v_pk_add_f32 v[86:87], v[86:87], 0 op_sel_hi:[1,0]
	v_pk_add_f32 v[80:81], v[80:81], 0 op_sel_hi:[1,0]
	v_pk_add_f32 v[104:105], v[94:95], 0 op_sel_hi:[1,0]
	v_pk_add_f32 v[94:95], v[92:93], 0 op_sel_hi:[1,0]
	v_cvt_pk_bf16_f32 v92, v100, v101
	v_cvt_pk_bf16_f32 v93, v102, v103
	v_pk_add_f32 v[68:69], v[68:69], 0 op_sel_hi:[1,0]
	v_cvt_pk_bf16_f32 v94, v94, v95
	v_cvt_pk_bf16_f32 v95, v104, v105
	global_store_dwordx4 v[108:109], v[92:95], off offset:256
	v_pk_add_f32 v[70:71], v[70:71], 0 op_sel_hi:[1,0]
	v_pk_add_f32 v[62:63], v[62:63], 0 op_sel_hi:[1,0]
	v_or_b32_e32 v92, 32, v141
	v_mad_i64_i32 v[92:93], s[42:43], v92, s41, v[134:135]
	v_pk_add_f32 v[94:95], v[98:99], 0 op_sel_hi:[1,0]
	v_pk_add_f32 v[98:99], v[90:91], 0 op_sel_hi:[1,0]
	v_pk_add_f32 v[90:91], v[88:89], 0 op_sel_hi:[1,0]
	v_cvt_pk_bf16_f32 v88, v96, v97
	v_cvt_pk_bf16_f32 v89, v94, v95
	v_pk_add_f32 v[60:61], v[60:61], 0 op_sel_hi:[1,0]
	v_cvt_pk_bf16_f32 v90, v90, v91
	v_cvt_pk_bf16_f32 v91, v98, v99
	global_store_dwordx4 v[92:93], v[88:91], off
	v_pk_add_f32 v[52:53], v[52:53], 0 op_sel_hi:[1,0]
	v_pk_add_f32 v[54:55], v[54:55], 0 op_sel_hi:[1,0]
	v_pk_add_f32 v[88:89], v[78:79], 0 op_sel_hi:[1,0]
	v_pk_add_f32 v[78:79], v[76:77], 0 op_sel_hi:[1,0]
	v_cvt_pk_bf16_f32 v76, v84, v85
	v_cvt_pk_bf16_f32 v77, v86, v87
	v_pk_add_f32 v[48:49], v[48:49], 0 op_sel_hi:[1,0]
	v_cvt_pk_bf16_f32 v78, v78, v79
	v_cvt_pk_bf16_f32 v79, v88, v89
	global_store_dwordx4 v[92:93], v[76:79], off offset:256
	v_pk_add_f32 v[36:37], v[36:37], 0 op_sel_hi:[1,0]
	v_pk_add_f32 v[38:39], v[38:39], 0 op_sel_hi:[1,0]
	v_or_b32_e32 v76, 48, v141
	v_mad_i64_i32 v[76:77], s[42:43], v76, s41, v[134:135]
	v_pk_add_f32 v[78:79], v[82:83], 0 op_sel_hi:[1,0]
	v_pk_add_f32 v[82:83], v[74:75], 0 op_sel_hi:[1,0]
	v_pk_add_f32 v[74:75], v[72:73], 0 op_sel_hi:[1,0]
	v_cvt_pk_bf16_f32 v72, v80, v81
	v_cvt_pk_bf16_f32 v73, v78, v79
	v_pk_add_f32 v[32:33], v[32:33], 0 op_sel_hi:[1,0]
	v_cvt_pk_bf16_f32 v74, v74, v75
	v_cvt_pk_bf16_f32 v75, v82, v83
	global_store_dwordx4 v[76:77], v[72:75], off
	v_pk_add_f32 v[20:21], v[20:21], 0 op_sel_hi:[1,0]
	v_pk_add_f32 v[22:23], v[22:23], 0 op_sel_hi:[1,0]
	v_pk_add_f32 v[72:73], v[66:67], 0 op_sel_hi:[1,0]
	v_pk_add_f32 v[66:67], v[64:65], 0 op_sel_hi:[1,0]
	v_cvt_pk_bf16_f32 v64, v68, v69
	v_cvt_pk_bf16_f32 v65, v70, v71
	v_pk_add_f32 v[16:17], v[16:17], 0 op_sel_hi:[1,0]
	v_cvt_pk_bf16_f32 v66, v66, v67
	v_cvt_pk_bf16_f32 v67, v72, v73
	global_store_dwordx4 v[76:77], v[64:67], off offset:256
	v_pk_add_f32 v[6:7], v[6:7], 0 op_sel_hi:[1,0]
	v_pk_add_f32 v[4:5], v[4:5], 0 op_sel_hi:[1,0]
	v_add_u32_e32 v64, 0x80, v141
	v_mad_i64_i32 v[64:65], s[42:43], v64, s41, v[134:135]
	v_pk_add_f32 v[66:67], v[58:59], 0 op_sel_hi:[1,0]
	v_pk_add_f32 v[58:59], v[56:57], 0 op_sel_hi:[1,0]
	v_cvt_pk_bf16_f32 v56, v60, v61
	v_cvt_pk_bf16_f32 v57, v62, v63
	s_mov_b64 s[66:67], -1
	v_cvt_pk_bf16_f32 v58, v58, v59
	v_cvt_pk_bf16_f32 v59, v66, v67
	global_store_dwordx4 v[64:65], v[56:59], off
	s_nop 1
	v_pk_add_f32 v[56:57], v[46:47], 0 op_sel_hi:[1,0]
	v_pk_add_f32 v[46:47], v[44:45], 0 op_sel_hi:[1,0]
	v_cvt_pk_bf16_f32 v44, v52, v53
	v_cvt_pk_bf16_f32 v45, v54, v55
	s_nop 0
	v_cvt_pk_bf16_f32 v46, v46, v47
	v_cvt_pk_bf16_f32 v47, v56, v57
	global_store_dwordx4 v[64:65], v[44:47], off offset:256
	s_nop 1
	v_add_u32_e32 v44, 0x90, v141
	v_mad_i64_i32 v[44:45], s[42:43], v44, s41, v[134:135]
	v_pk_add_f32 v[46:47], v[50:51], 0 op_sel_hi:[1,0]
	v_pk_add_f32 v[50:51], v[42:43], 0 op_sel_hi:[1,0]
	v_pk_add_f32 v[42:43], v[40:41], 0 op_sel_hi:[1,0]
	v_cvt_pk_bf16_f32 v40, v48, v49
	v_cvt_pk_bf16_f32 v41, v46, v47
	s_nop 0
	v_cvt_pk_bf16_f32 v42, v42, v43
	v_cvt_pk_bf16_f32 v43, v50, v51
	global_store_dwordx4 v[44:45], v[40:43], off
	s_nop 1
	v_pk_add_f32 v[40:41], v[30:31], 0 op_sel_hi:[1,0]
	v_pk_add_f32 v[30:31], v[28:29], 0 op_sel_hi:[1,0]
	v_cvt_pk_bf16_f32 v28, v36, v37
	v_cvt_pk_bf16_f32 v29, v38, v39
	s_nop 0
	v_cvt_pk_bf16_f32 v30, v30, v31
	v_cvt_pk_bf16_f32 v31, v40, v41
	global_store_dwordx4 v[44:45], v[28:31], off offset:256
	s_nop 1
	v_add_u32_e32 v28, 0xa0, v141
	v_mad_i64_i32 v[28:29], s[42:43], v28, s41, v[134:135]
	v_pk_add_f32 v[30:31], v[34:35], 0 op_sel_hi:[1,0]
	v_pk_add_f32 v[34:35], v[26:27], 0 op_sel_hi:[1,0]
	v_pk_add_f32 v[26:27], v[24:25], 0 op_sel_hi:[1,0]
	v_cvt_pk_bf16_f32 v24, v32, v33
	v_cvt_pk_bf16_f32 v25, v30, v31
	s_nop 0
	v_cvt_pk_bf16_f32 v26, v26, v27
	v_cvt_pk_bf16_f32 v27, v34, v35
	global_store_dwordx4 v[28:29], v[24:27], off
	s_nop 1
	v_pk_add_f32 v[24:25], v[14:15], 0 op_sel_hi:[1,0]
	v_pk_add_f32 v[14:15], v[12:13], 0 op_sel_hi:[1,0]
	v_cvt_pk_bf16_f32 v12, v20, v21
	v_cvt_pk_bf16_f32 v13, v22, v23
	s_nop 0
	v_cvt_pk_bf16_f32 v14, v14, v15
	v_cvt_pk_bf16_f32 v15, v24, v25
	global_store_dwordx4 v[28:29], v[12:15], off offset:256
	s_nop 1
	v_add_u32_e32 v12, 0xb0, v141
	v_mad_i64_i32 v[12:13], s[42:43], v12, s41, v[134:135]
	v_pk_add_f32 v[14:15], v[18:19], 0 op_sel_hi:[1,0]
	v_pk_add_f32 v[18:19], v[10:11], 0 op_sel_hi:[1,0]
	v_pk_add_f32 v[10:11], v[8:9], 0 op_sel_hi:[1,0]
	v_cvt_pk_bf16_f32 v8, v16, v17
	v_cvt_pk_bf16_f32 v9, v14, v15
	s_mov_b32 s42, s33
	v_cvt_pk_bf16_f32 v10, v10, v11
	v_cvt_pk_bf16_f32 v11, v18, v19
	global_store_dwordx4 v[12:13], v[8:11], off
	s_nop 1
	v_pk_add_f32 v[8:9], v[2:3], 0 op_sel_hi:[1,0]
	v_pk_add_f32 v[2:3], v[0:1], 0 op_sel_hi:[1,0]
	v_cvt_pk_bf16_f32 v0, v4, v5
	v_cvt_pk_bf16_f32 v1, v6, v7
	s_nop 0
	v_cvt_pk_bf16_f32 v2, v2, v3
	v_cvt_pk_bf16_f32 v3, v8, v9
	global_store_dwordx4 v[12:13], v[0:3], off offset:256
	s_mul_i32 s44, s42, s13
	s_add_i32 s44, s44, s14
	s_cmpk_gt_i32 s44, 0xcb
	s_cbranch_scc1 .LBB0_312
	s_ashr_i32 s42, s44, 31
	s_lshr_b32 s42, s42, 29
	s_add_i32 s42, s44, s42
	s_and_b32 s43, s42, -8
	s_sub_i32 s43, s44, s43
	s_cmp_gt_i32 s43, 3
	s_cbranch_scc0 .LBB0_324
	s_mul_i32 s44, s43, 25
	s_add_i32 s44, s44, 4
	s_mov_b64 s[66:67], 0

.LBB0_337:
	s_add_u32 s74, s66, s46
	s_addc_u32 s75, s67, 0
	s_add_u32 s47, s74, 0x100
	s_addc_u32 s50, s75, 0
	s_and_b64 s[48:49], s[70:71], exec
	v_cndmask_b32_e64 v132, 0, 1, s[72:73]
	s_cselect_b32 s72, s62, s47
	s_cselect_b32 s73, s63, s50
	s_add_u32 s46, s68, s46
	s_addc_u32 s47, s69, 0
	ds_read_b128 v[140:143], v135
	ds_read_b128 v[144:147], v135 offset:1024
	ds_read_b128 v[148:151], v135 offset:2048
	ds_read_b128 v[152:155], v135 offset:3072
	s_add_u32 s48, s46, 0x100
	s_addc_u32 s49, s47, 0
	s_and_b64 s[46:47], s[70:71], exec
	s_cselect_b32 s70, s64, s48
	s_cselect_b32 s71, s65, s49
	s_add_i32 s49, 0, 0x1c000
	s_add_i32 s51, 0, 0x18000
	s_add_i32 s47, s49, s30
	s_add_i32 s79, s42, s30
	s_add_i32 s77, s43, s30
	s_add_i32 s50, s51, s30
	s_add_i32 s46, s47, 0x2000
	s_add_i32 m0, s31, 0xc000
	s_add_i32 s80, s31, 0xe000
	s_add_i32 s78, s79, 0x2000
	s_add_i32 s76, s77, 0x2000
	s_add_i32 s48, s50, 0x2000
	v_cmp_ne_u32_e32 vcc, 1, v132
	v_lshl_add_u64 v[132:133], s[74:75], 0, v[130:131]
	s_mov_b64 s[74:75], 0x240080
	v_lshl_add_u64 v[188:189], v[132:133], 0, s[74:75]
	s_mov_b64 s[74:75], 0x360080
	ds_read_b128 v[156:159], v137
	ds_read_b128 v[160:163], v137 offset:1024
	ds_read_b128 v[164:167], v137 offset:2048
	ds_read_b128 v[168:171], v137 offset:3072
	ds_read_b128 v[172:175], v137 offset:4096
	ds_read_b128 v[176:179], v137 offset:5120
	ds_read_b128 v[180:183], v137 offset:6144
	ds_read_b128 v[184:187], v137 offset:7168
	global_load_lds_dwordx4 v[188:189], off
	v_lshl_add_u64 v[132:133], v[132:133], 0, s[74:75]
	s_mov_b32 m0, s80
	s_nop 0
	global_load_lds_dwordx4 v[132:133], off
	s_waitcnt lgkmcnt(8)
	s_barrier
	s_waitcnt lgkmcnt(0)
	s_waitcnt lgkmcnt(0)
	v_mfma_f32_16x16x32_bf16 v[124:127], v[140:143], v[156:159], v[124:127]
	v_mfma_f32_16x16x32_bf16 v[120:123], v[148:151], v[156:159], v[120:123]
	v_mfma_f32_16x16x32_bf16 v[112:115], v[140:143], v[164:167], v[112:115]
	v_mfma_f32_16x16x32_bf16 v[104:107], v[148:151], v[164:167], v[104:107]
	v_mfma_f32_16x16x32_bf16 v[96:99], v[140:143], v[172:175], v[96:99]
	v_mfma_f32_16x16x32_bf16 v[88:91], v[148:151], v[172:175], v[88:91]
	v_mfma_f32_16x16x32_bf16 v[80:83], v[140:143], v[180:183], v[80:83]
	v_mfma_f32_16x16x32_bf16 v[72:75], v[148:151], v[180:183], v[72:75]
	v_mfma_f32_16x16x32_bf16 v[124:127], v[144:147], v[160:163], v[124:127]
	v_mfma_f32_16x16x32_bf16 v[120:123], v[152:155], v[160:163], v[120:123]
	v_mfma_f32_16x16x32_bf16 v[112:115], v[144:147], v[168:171], v[112:115]
	v_mfma_f32_16x16x32_bf16 v[104:107], v[152:155], v[168:171], v[104:107]
	v_mfma_f32_16x16x32_bf16 v[96:99], v[144:147], v[176:179], v[96:99]
	v_mfma_f32_16x16x32_bf16 v[88:91], v[152:155], v[176:179], v[88:91]
	v_mfma_f32_16x16x32_bf16 v[80:83], v[144:147], v[184:187], v[80:83]
	v_mfma_f32_16x16x32_bf16 v[72:75], v[152:155], v[184:187], v[72:75]
	s_barrier
	s_mov_b32 m0, s79
	v_lshl_add_u64 v[132:133], s[70:71], 0, v[128:129]
	ds_read_b128 v[188:191], v138
	ds_read_b128 v[192:195], v138 offset:1024
	ds_read_b128 v[196:199], v138 offset:2048
	ds_read_b128 v[200:203], v138 offset:3072
	global_load_lds_dwordx4 v[132:133], off
	v_lshl_add_u64 v[204:205], v[132:133], 0, s[8:9]
	s_mov_b32 m0, s78
	s_nop 0
	global_load_lds_dwordx4 v[204:205], off
	s_barrier
	s_waitcnt lgkmcnt(0)
	s_waitcnt lgkmcnt(0)
	v_mfma_f32_16x16x32_bf16 v[116:119], v[188:191], v[156:159], v[116:119]
	v_mfma_f32_16x16x32_bf16 v[108:111], v[196:199], v[156:159], v[108:111]
	v_mfma_f32_16x16x32_bf16 v[100:103], v[188:191], v[164:167], v[100:103]
	v_mfma_f32_16x16x32_bf16 v[92:95], v[196:199], v[164:167], v[92:95]
	v_mfma_f32_16x16x32_bf16 v[84:87], v[188:191], v[172:175], v[84:87]
	v_mfma_f32_16x16x32_bf16 v[76:79], v[196:199], v[172:175], v[76:79]
	v_mfma_f32_16x16x32_bf16 v[68:71], v[188:191], v[180:183], v[68:71]
	v_mfma_f32_16x16x32_bf16 v[64:67], v[196:199], v[180:183], v[64:67]
	v_mfma_f32_16x16x32_bf16 v[116:119], v[192:195], v[160:163], v[116:119]
	v_mfma_f32_16x16x32_bf16 v[108:111], v[200:203], v[160:163], v[108:111]
	v_mfma_f32_16x16x32_bf16 v[100:103], v[192:195], v[168:171], v[100:103]
	v_mfma_f32_16x16x32_bf16 v[92:95], v[200:203], v[168:171], v[92:95]
	v_mfma_f32_16x16x32_bf16 v[84:87], v[192:195], v[176:179], v[84:87]
	v_mfma_f32_16x16x32_bf16 v[76:79], v[200:203], v[176:179], v[76:79]
	v_mfma_f32_16x16x32_bf16 v[68:71], v[192:195], v[184:187], v[68:71]
	v_mfma_f32_16x16x32_bf16 v[64:67], v[200:203], v[184:187], v[64:67]
	s_mov_b32 m0, s31
	v_lshl_add_u64 v[204:205], s[72:73], 0, v[130:131]
	s_barrier
	ds_read_b128 v[156:159], v137 offset:16384
	ds_read_b128 v[160:163], v137 offset:17408
	ds_read_b128 v[164:167], v137 offset:18432
	ds_read_b128 v[168:171], v137 offset:19456
	ds_read_b128 v[172:175], v137 offset:20480
	ds_read_b128 v[176:179], v137 offset:21504
	ds_read_b128 v[180:183], v137 offset:22528
	ds_read_b128 v[184:187], v137 offset:23552
	global_load_lds_dwordx4 v[204:205], off
	v_lshl_add_u64 v[206:207], v[204:205], 0, s[10:11]
	s_mov_b32 m0, s33
	s_nop 0
	global_load_lds_dwordx4 v[206:207], off
	s_barrier
	s_waitcnt lgkmcnt(0)
	s_waitcnt lgkmcnt(0)
	v_mfma_f32_16x16x32_bf16 v[60:63], v[140:143], v[156:159], v[60:63]
	v_mfma_f32_16x16x32_bf16 v[56:59], v[148:151], v[156:159], v[56:59]
	v_mfma_f32_16x16x32_bf16 v[48:51], v[140:143], v[164:167], v[48:51]
	v_mfma_f32_16x16x32_bf16 v[40:43], v[148:151], v[164:167], v[40:43]
	v_mfma_f32_16x16x32_bf16 v[32:35], v[140:143], v[172:175], v[32:35]
	v_mfma_f32_16x16x32_bf16 v[24:27], v[148:151], v[172:175], v[24:27]
	v_mfma_f32_16x16x32_bf16 v[16:19], v[140:143], v[180:183], v[16:19]
	v_mfma_f32_16x16x32_bf16 v[8:11], v[148:151], v[180:183], v[8:11]
	v_mfma_f32_16x16x32_bf16 v[60:63], v[144:147], v[160:163], v[60:63]
	v_mfma_f32_16x16x32_bf16 v[56:59], v[152:155], v[160:163], v[56:59]
	v_mfma_f32_16x16x32_bf16 v[48:51], v[144:147], v[168:171], v[48:51]
	v_mfma_f32_16x16x32_bf16 v[40:43], v[152:155], v[168:171], v[40:43]
	v_mfma_f32_16x16x32_bf16 v[32:35], v[144:147], v[176:179], v[32:35]
	v_mfma_f32_16x16x32_bf16 v[24:27], v[152:155], v[176:179], v[24:27]
	v_mfma_f32_16x16x32_bf16 v[16:19], v[144:147], v[184:187], v[16:19]
	v_mfma_f32_16x16x32_bf16 v[8:11], v[152:155], v[184:187], v[8:11]
	s_barrier
	s_mov_b32 m0, s77
	v_lshl_add_u64 v[140:141], v[132:133], 0, s[18:19]
	global_load_lds_dwordx4 v[140:141], off
	v_lshl_add_u64 v[140:141], v[132:133], 0, s[22:23]
	s_mov_b32 m0, s76
	s_nop 0
	global_load_lds_dwordx4 v[140:141], off
	s_waitcnt vmcnt(6)
	s_barrier
	v_mfma_f32_16x16x32_bf16 v[52:55], v[188:191], v[156:159], v[52:55]
	v_mfma_f32_16x16x32_bf16 v[44:47], v[196:199], v[156:159], v[44:47]
	v_mfma_f32_16x16x32_bf16 v[36:39], v[188:191], v[164:167], v[36:39]
	v_mfma_f32_16x16x32_bf16 v[28:31], v[196:199], v[164:167], v[28:31]
	v_mfma_f32_16x16x32_bf16 v[20:23], v[188:191], v[172:175], v[20:23]
	v_mfma_f32_16x16x32_bf16 v[12:15], v[196:199], v[172:175], v[12:15]
	v_mfma_f32_16x16x32_bf16 v[4:7], v[188:191], v[180:183], v[4:7]
	v_mfma_f32_16x16x32_bf16 v[0:3], v[196:199], v[180:183], v[0:3]
	v_mfma_f32_16x16x32_bf16 v[52:55], v[192:195], v[160:163], v[52:55]
	v_mfma_f32_16x16x32_bf16 v[44:47], v[200:203], v[160:163], v[44:47]
	v_mfma_f32_16x16x32_bf16 v[36:39], v[192:195], v[168:171], v[36:39]
	v_mfma_f32_16x16x32_bf16 v[28:31], v[200:203], v[168:171], v[28:31]
	v_mfma_f32_16x16x32_bf16 v[20:23], v[192:195], v[176:179], v[20:23]
	v_mfma_f32_16x16x32_bf16 v[12:15], v[200:203], v[176:179], v[12:15]
	v_mfma_f32_16x16x32_bf16 v[4:7], v[192:195], v[184:187], v[4:7]
	v_mfma_f32_16x16x32_bf16 v[0:3], v[200:203], v[184:187], v[0:3]
	v_add_u32_e32 v139, s51, v134
	s_barrier
	ds_read_b128 v[140:143], v139
	ds_read_b128 v[144:147], v139 offset:1024
	ds_read_b128 v[148:151], v139 offset:2048
	ds_read_b128 v[152:155], v139 offset:3072
	s_mov_b32 m0, s36
	v_lshl_add_u64 v[188:189], v[204:205], 0, s[24:25]
	ds_read_b128 v[156:159], v137 offset:32768
	ds_read_b128 v[160:163], v137 offset:33792
	ds_read_b128 v[164:167], v137 offset:34816
	ds_read_b128 v[168:171], v137 offset:35840
	ds_read_b128 v[172:175], v137 offset:36864
	ds_read_b128 v[176:179], v137 offset:37888
	ds_read_b128 v[180:183], v137 offset:38912
	ds_read_b128 v[184:187], v137 offset:39936
	global_load_lds_dwordx4 v[188:189], off
	v_lshl_add_u64 v[188:189], v[204:205], 0, s[26:27]
	s_mov_b32 m0, s37
	s_nop 0
	global_load_lds_dwordx4 v[188:189], off
	s_waitcnt lgkmcnt(8)
	s_barrier
	s_waitcnt lgkmcnt(0)
	s_waitcnt lgkmcnt(0)
	v_mfma_f32_16x16x32_bf16 v[124:127], v[140:143], v[156:159], v[124:127]
	v_mfma_f32_16x16x32_bf16 v[120:123], v[148:151], v[156:159], v[120:123]
	v_mfma_f32_16x16x32_bf16 v[112:115], v[140:143], v[164:167], v[112:115]
	v_mfma_f32_16x16x32_bf16 v[104:107], v[148:151], v[164:167], v[104:107]
	v_mfma_f32_16x16x32_bf16 v[96:99], v[140:143], v[172:175], v[96:99]
	v_mfma_f32_16x16x32_bf16 v[88:91], v[148:151], v[172:175], v[88:91]
	v_mfma_f32_16x16x32_bf16 v[80:83], v[140:143], v[180:183], v[80:83]
	v_mfma_f32_16x16x32_bf16 v[72:75], v[148:151], v[180:183], v[72:75]
	v_mfma_f32_16x16x32_bf16 v[124:127], v[144:147], v[160:163], v[124:127]
	v_mfma_f32_16x16x32_bf16 v[120:123], v[152:155], v[160:163], v[120:123]
	v_mfma_f32_16x16x32_bf16 v[112:115], v[144:147], v[168:171], v[112:115]
	v_mfma_f32_16x16x32_bf16 v[104:107], v[152:155], v[168:171], v[104:107]
	v_mfma_f32_16x16x32_bf16 v[96:99], v[144:147], v[176:179], v[96:99]
	v_mfma_f32_16x16x32_bf16 v[88:91], v[152:155], v[176:179], v[88:91]
	v_mfma_f32_16x16x32_bf16 v[80:83], v[144:147], v[184:187], v[80:83]
	v_mfma_f32_16x16x32_bf16 v[72:75], v[152:155], v[184:187], v[72:75]
	s_barrier
	s_mov_b32 m0, s50
	v_add_u32_e32 v139, s49, v134
	v_lshl_add_u64 v[206:207], v[132:133], 0, s[52:53]
	ds_read_b128 v[188:191], v139
	ds_read_b128 v[192:195], v139 offset:1024
	ds_read_b128 v[196:199], v139 offset:2048
	ds_read_b128 v[200:203], v139 offset:3072
	global_load_lds_dwordx4 v[206:207], off
	v_lshl_add_u64 v[206:207], v[132:133], 0, s[54:55]
	s_mov_b32 m0, s48
	s_nop 0
	global_load_lds_dwordx4 v[206:207], off
	s_barrier
	s_waitcnt lgkmcnt(0)
	s_waitcnt lgkmcnt(0)
	v_mfma_f32_16x16x32_bf16 v[116:119], v[188:191], v[156:159], v[116:119]
	v_mfma_f32_16x16x32_bf16 v[108:111], v[196:199], v[156:159], v[108:111]
	v_mfma_f32_16x16x32_bf16 v[100:103], v[188:191], v[164:167], v[100:103]
	v_mfma_f32_16x16x32_bf16 v[92:95], v[196:199], v[164:167], v[92:95]
	v_mfma_f32_16x16x32_bf16 v[84:87], v[188:191], v[172:175], v[84:87]
	v_mfma_f32_16x16x32_bf16 v[76:79], v[196:199], v[172:175], v[76:79]
	v_mfma_f32_16x16x32_bf16 v[68:71], v[188:191], v[180:183], v[68:71]
	v_mfma_f32_16x16x32_bf16 v[64:67], v[196:199], v[180:183], v[64:67]
	v_mfma_f32_16x16x32_bf16 v[116:119], v[192:195], v[160:163], v[116:119]
	v_mfma_f32_16x16x32_bf16 v[108:111], v[200:203], v[160:163], v[108:111]
	v_mfma_f32_16x16x32_bf16 v[100:103], v[192:195], v[168:171], v[100:103]
	v_mfma_f32_16x16x32_bf16 v[92:95], v[200:203], v[168:171], v[92:95]
	v_mfma_f32_16x16x32_bf16 v[84:87], v[192:195], v[176:179], v[84:87]
	v_mfma_f32_16x16x32_bf16 v[76:79], v[200:203], v[176:179], v[76:79]
	v_mfma_f32_16x16x32_bf16 v[68:71], v[192:195], v[184:187], v[68:71]
	v_mfma_f32_16x16x32_bf16 v[64:67], v[200:203], v[184:187], v[64:67]
	s_mov_b32 m0, s40
	v_lshl_add_u64 v[206:207], v[204:205], 0, s[52:53]
	s_barrier
	ds_read_b128 v[156:159], v137 offset:49152
	ds_read_b128 v[160:163], v137 offset:50176
	ds_read_b128 v[164:167], v137 offset:51200
	ds_read_b128 v[168:171], v137 offset:52224
	ds_read_b128 v[172:175], v137 offset:53248
	ds_read_b128 v[176:179], v137 offset:54272
	ds_read_b128 v[180:183], v137 offset:55296
	ds_read_b128 v[184:187], v137 offset:56320
	global_load_lds_dwordx4 v[206:207], off
	v_lshl_add_u64 v[204:205], v[204:205], 0, s[56:57]
	s_mov_b32 m0, s41
	s_nop 0
	global_load_lds_dwordx4 v[204:205], off
	s_barrier
	s_waitcnt lgkmcnt(0)
	s_waitcnt lgkmcnt(0)
	v_mfma_f32_16x16x32_bf16 v[60:63], v[140:143], v[156:159], v[60:63]
	v_mfma_f32_16x16x32_bf16 v[56:59], v[148:151], v[156:159], v[56:59]
	v_mfma_f32_16x16x32_bf16 v[48:51], v[140:143], v[164:167], v[48:51]
	v_mfma_f32_16x16x32_bf16 v[40:43], v[148:151], v[164:167], v[40:43]
	v_mfma_f32_16x16x32_bf16 v[32:35], v[140:143], v[172:175], v[32:35]
	v_mfma_f32_16x16x32_bf16 v[24:27], v[148:151], v[172:175], v[24:27]
	v_mfma_f32_16x16x32_bf16 v[16:19], v[140:143], v[180:183], v[16:19]
	v_mfma_f32_16x16x32_bf16 v[8:11], v[148:151], v[180:183], v[8:11]
	v_mfma_f32_16x16x32_bf16 v[60:63], v[144:147], v[160:163], v[60:63]
	v_mfma_f32_16x16x32_bf16 v[56:59], v[152:155], v[160:163], v[56:59]
	v_mfma_f32_16x16x32_bf16 v[48:51], v[144:147], v[168:171], v[48:51]
	v_mfma_f32_16x16x32_bf16 v[40:43], v[152:155], v[168:171], v[40:43]
	v_mfma_f32_16x16x32_bf16 v[32:35], v[144:147], v[176:179], v[32:35]
	v_mfma_f32_16x16x32_bf16 v[24:27], v[152:155], v[176:179], v[24:27]
	v_mfma_f32_16x16x32_bf16 v[16:19], v[144:147], v[184:187], v[16:19]
	v_mfma_f32_16x16x32_bf16 v[8:11], v[152:155], v[184:187], v[8:11]
	s_barrier
	s_mov_b32 m0, s47
	v_lshl_add_u64 v[140:141], v[132:133], 0, s[58:59]
	global_load_lds_dwordx4 v[140:141], off
	v_lshl_add_u64 v[132:133], v[132:133], 0, s[60:61]
	s_mov_b32 m0, s46
	s_nop 0
	global_load_lds_dwordx4 v[132:133], off
	s_waitcnt vmcnt(6)
	s_barrier
	v_mfma_f32_16x16x32_bf16 v[52:55], v[188:191], v[156:159], v[52:55]
	v_mfma_f32_16x16x32_bf16 v[44:47], v[196:199], v[156:159], v[44:47]
	v_mfma_f32_16x16x32_bf16 v[36:39], v[188:191], v[164:167], v[36:39]
	v_mfma_f32_16x16x32_bf16 v[28:31], v[196:199], v[164:167], v[28:31]
	v_mfma_f32_16x16x32_bf16 v[20:23], v[188:191], v[172:175], v[20:23]
	v_mfma_f32_16x16x32_bf16 v[12:15], v[196:199], v[172:175], v[12:15]
	v_mfma_f32_16x16x32_bf16 v[4:7], v[188:191], v[180:183], v[4:7]
	v_mfma_f32_16x16x32_bf16 v[0:3], v[196:199], v[180:183], v[0:3]
	v_mfma_f32_16x16x32_bf16 v[52:55], v[192:195], v[160:163], v[52:55]
	v_mfma_f32_16x16x32_bf16 v[44:47], v[200:203], v[160:163], v[44:47]
	v_mfma_f32_16x16x32_bf16 v[36:39], v[192:195], v[168:171], v[36:39]
	v_mfma_f32_16x16x32_bf16 v[28:31], v[200:203], v[168:171], v[28:31]
	v_mfma_f32_16x16x32_bf16 v[20:23], v[192:195], v[176:179], v[20:23]
	v_mfma_f32_16x16x32_bf16 v[12:15], v[200:203], v[176:179], v[12:15]
	v_mfma_f32_16x16x32_bf16 v[4:7], v[192:195], v[184:187], v[4:7]
	v_mfma_f32_16x16x32_bf16 v[0:3], v[200:203], v[184:187], v[0:3]
	s_movk_i32 s46, 0x100
	s_mov_b64 s[72:73], 0
	s_mov_b64 s[70:71], -1
	s_barrier
	s_cbranch_vccz .LBB0_337
	v_mov_b32_e32 v139, v136
	s_mov_b32 s46, s29
	s_mov_b32 s47, s39
	s_lshl_b32 s45, s45, 8
	s_lshl_b32 s47, s47, 5
	s_lshl_b32 s44, s44, 8
	s_add_i32 s47, s47, s45
	v_lshrrev_b32_e32 v132, 1, v139
	v_and_or_b32 v139, v139, 15, s44
	v_and_or_b32 v132, v132, 24, s47
	v_lshl_add_u32 v140, s46, 6, v139
	v_ashrrev_i32_e32 v133, 31, v132
	v_ashrrev_i32_e32 v141, 31, v140
	v_lshl_add_u64 v[142:143], v[132:133], 1, s[34:35]
	v_lshlrev_b64 v[132:133], 12, v[140:141]
	v_lshl_add_u64 v[132:133], v[142:143], 0, v[132:133]
	v_pk_add_f32 v[126:127], v[126:127], 0 op_sel_hi:[1,0]
	v_pk_add_f32 v[124:125], v[124:125], 0 op_sel_hi:[1,0]
	v_pk_add_f32 v[144:145], v[122:123], 0 op_sel_hi:[1,0]
	v_pk_add_f32 v[122:123], v[120:121], 0 op_sel_hi:[1,0]
	v_cvt_pk_bf16_f32 v120, v124, v125
	v_cvt_pk_bf16_f32 v121, v126, v127
	v_pk_add_f32 v[116:117], v[116:117], 0 op_sel_hi:[1,0]
	v_cvt_pk_bf16_f32 v122, v122, v123
	v_cvt_pk_bf16_f32 v123, v144, v145
	global_store_dwordx4 v[132:133], v[120:123], off
	v_pk_add_f32 v[118:119], v[118:119], 0 op_sel_hi:[1,0]
	v_pk_add_f32 v[112:113], v[112:113], 0 op_sel_hi:[1,0]
	v_pk_add_f32 v[120:121], v[110:111], 0 op_sel_hi:[1,0]
	v_pk_add_f32 v[110:111], v[108:109], 0 op_sel_hi:[1,0]
	v_cvt_pk_bf16_f32 v108, v116, v117
	v_cvt_pk_bf16_f32 v109, v118, v119
	v_pk_add_f32 v[100:101], v[100:101], 0 op_sel_hi:[1,0]
	v_cvt_pk_bf16_f32 v110, v110, v111
	v_cvt_pk_bf16_f32 v111, v120, v121
	global_store_dwordx4 v[132:133], v[108:111], off offset:256
	v_pk_add_f32 v[102:103], v[102:103], 0 op_sel_hi:[1,0]
	v_pk_add_f32 v[96:97], v[96:97], 0 op_sel_hi:[1,0]
	v_or_b32_e32 v108, 16, v140
	v_ashrrev_i32_e32 v109, 31, v108
	v_lshlrev_b64 v[108:109], 12, v[108:109]
	v_lshl_add_u64 v[108:109], v[142:143], 0, v[108:109]
	v_pk_add_f32 v[110:111], v[114:115], 0 op_sel_hi:[1,0]
	v_pk_add_f32 v[114:115], v[106:107], 0 op_sel_hi:[1,0]
	v_pk_add_f32 v[106:107], v[104:105], 0 op_sel_hi:[1,0]
	v_cvt_pk_bf16_f32 v104, v112, v113
	v_cvt_pk_bf16_f32 v105, v110, v111
	v_pk_add_f32 v[84:85], v[84:85], 0 op_sel_hi:[1,0]
	v_cvt_pk_bf16_f32 v106, v106, v107
	v_cvt_pk_bf16_f32 v107, v114, v115
	global_store_dwordx4 v[108:109], v[104:107], off
	v_pk_add_f32 v[86:87], v[86:87], 0 op_sel_hi:[1,0]
	v_pk_add_f32 v[80:81], v[80:81], 0 op_sel_hi:[1,0]
	v_pk_add_f32 v[104:105], v[94:95], 0 op_sel_hi:[1,0]
	v_pk_add_f32 v[94:95], v[92:93], 0 op_sel_hi:[1,0]
	v_cvt_pk_bf16_f32 v92, v100, v101
	v_cvt_pk_bf16_f32 v93, v102, v103
	v_pk_add_f32 v[70:71], v[70:71], 0 op_sel_hi:[1,0]
	v_cvt_pk_bf16_f32 v94, v94, v95
	v_cvt_pk_bf16_f32 v95, v104, v105
	global_store_dwordx4 v[108:109], v[92:95], off offset:256
	v_pk_add_f32 v[68:69], v[68:69], 0 op_sel_hi:[1,0]
	s_mov_b64 s[44:45], 0x80000
	v_or_b32_e32 v92, 32, v140
	v_ashrrev_i32_e32 v93, 31, v92
	v_lshlrev_b64 v[92:93], 12, v[92:93]
	v_lshl_add_u64 v[92:93], v[142:143], 0, v[92:93]
	v_pk_add_f32 v[94:95], v[98:99], 0 op_sel_hi:[1,0]
	v_pk_add_f32 v[98:99], v[90:91], 0 op_sel_hi:[1,0]
	v_pk_add_f32 v[90:91], v[88:89], 0 op_sel_hi:[1,0]
	v_cvt_pk_bf16_f32 v88, v96, v97
	v_cvt_pk_bf16_f32 v89, v94, v95
	v_pk_add_f32 v[60:61], v[60:61], 0 op_sel_hi:[1,0]
	v_cvt_pk_bf16_f32 v90, v90, v91
	v_cvt_pk_bf16_f32 v91, v98, v99
	global_store_dwordx4 v[92:93], v[88:91], off
	v_pk_add_f32 v[62:63], v[62:63], 0 op_sel_hi:[1,0]
	v_pk_add_f32 v[54:55], v[54:55], 0 op_sel_hi:[1,0]
	v_pk_add_f32 v[88:89], v[78:79], 0 op_sel_hi:[1,0]
	v_pk_add_f32 v[78:79], v[76:77], 0 op_sel_hi:[1,0]
	v_cvt_pk_bf16_f32 v76, v84, v85
	v_cvt_pk_bf16_f32 v77, v86, v87
	v_pk_add_f32 v[52:53], v[52:53], 0 op_sel_hi:[1,0]
	v_cvt_pk_bf16_f32 v78, v78, v79
	v_cvt_pk_bf16_f32 v79, v88, v89
	global_store_dwordx4 v[92:93], v[76:79], off offset:256
	v_pk_add_f32 v[48:49], v[48:49], 0 op_sel_hi:[1,0]
	v_pk_add_f32 v[38:39], v[38:39], 0 op_sel_hi:[1,0]
	v_or_b32_e32 v76, 48, v140
	v_ashrrev_i32_e32 v77, 31, v76
	v_lshlrev_b64 v[76:77], 12, v[76:77]
	v_lshl_add_u64 v[76:77], v[142:143], 0, v[76:77]
	v_pk_add_f32 v[78:79], v[82:83], 0 op_sel_hi:[1,0]
	v_pk_add_f32 v[82:83], v[74:75], 0 op_sel_hi:[1,0]
	v_pk_add_f32 v[74:75], v[72:73], 0 op_sel_hi:[1,0]
	v_cvt_pk_bf16_f32 v72, v80, v81
	v_cvt_pk_bf16_f32 v73, v78, v79
	v_pk_add_f32 v[36:37], v[36:37], 0 op_sel_hi:[1,0]
	v_cvt_pk_bf16_f32 v74, v74, v75
	v_cvt_pk_bf16_f32 v75, v82, v83
	global_store_dwordx4 v[76:77], v[72:75], off
	v_pk_add_f32 v[32:33], v[32:33], 0 op_sel_hi:[1,0]
	v_pk_add_f32 v[22:23], v[22:23], 0 op_sel_hi:[1,0]
	v_pk_add_f32 v[72:73], v[66:67], 0 op_sel_hi:[1,0]
	v_pk_add_f32 v[66:67], v[64:65], 0 op_sel_hi:[1,0]
	v_cvt_pk_bf16_f32 v64, v68, v69
	v_cvt_pk_bf16_f32 v65, v70, v71
	v_pk_add_f32 v[20:21], v[20:21], 0 op_sel_hi:[1,0]
	v_cvt_pk_bf16_f32 v66, v66, v67
	v_cvt_pk_bf16_f32 v67, v72, v73
	global_store_dwordx4 v[76:77], v[64:67], off offset:256
	v_pk_add_f32 v[16:17], v[16:17], 0 op_sel_hi:[1,0]
	v_pk_add_f32 v[6:7], v[6:7], 0 op_sel_hi:[1,0]
	v_lshl_add_u64 v[64:65], v[132:133], 0, s[44:45]
	s_mov_b32 s44, 0x80000
	v_pk_add_f32 v[66:67], v[58:59], 0 op_sel_hi:[1,0]
	v_pk_add_f32 v[58:59], v[56:57], 0 op_sel_hi:[1,0]
	v_cvt_pk_bf16_f32 v56, v60, v61
	v_add_co_u32_e32 v60, vcc, s44, v132
	v_cvt_pk_bf16_f32 v57, v62, v63
	v_cvt_pk_bf16_f32 v58, v58, v59
	v_cvt_pk_bf16_f32 v59, v66, v67
	s_mov_b64 s[44:45], 0x90000
	s_nop 0
	v_addc_co_u32_e32 v61, vcc, 0, v133, vcc
	global_store_dwordx4 v[60:61], v[56:59], off
	v_pk_add_f32 v[4:5], v[4:5], 0 op_sel_hi:[1,0]
	s_mov_b64 s[66:67], -1
	v_pk_add_f32 v[56:57], v[46:47], 0 op_sel_hi:[1,0]
	v_pk_add_f32 v[46:47], v[44:45], 0 op_sel_hi:[1,0]
	v_cvt_pk_bf16_f32 v44, v52, v53
	v_cvt_pk_bf16_f32 v45, v54, v55
	s_nop 0
	v_cvt_pk_bf16_f32 v46, v46, v47
	v_cvt_pk_bf16_f32 v47, v56, v57
	global_store_dwordx4 v[64:65], v[44:47], off offset:256
	s_nop 1
	v_lshl_add_u64 v[44:45], v[132:133], 0, s[44:45]
	v_pk_add_f32 v[46:47], v[50:51], 0 op_sel_hi:[1,0]
	s_mov_b32 s44, 0x90000
	v_pk_add_f32 v[50:51], v[42:43], 0 op_sel_hi:[1,0]
	v_pk_add_f32 v[42:43], v[40:41], 0 op_sel_hi:[1,0]
	v_cvt_pk_bf16_f32 v40, v48, v49
	v_cvt_pk_bf16_f32 v41, v46, v47
	v_add_co_u32_e32 v46, vcc, s44, v132
	v_cvt_pk_bf16_f32 v42, v42, v43
	v_cvt_pk_bf16_f32 v43, v50, v51
	s_mov_b64 s[44:45], 0xa0000
	s_nop 0
	v_addc_co_u32_e32 v47, vcc, 0, v133, vcc
	global_store_dwordx4 v[46:47], v[40:43], off
	s_nop 1
	v_pk_add_f32 v[40:41], v[30:31], 0 op_sel_hi:[1,0]
	v_pk_add_f32 v[30:31], v[28:29], 0 op_sel_hi:[1,0]
	v_cvt_pk_bf16_f32 v28, v36, v37
	v_cvt_pk_bf16_f32 v29, v38, v39
	s_nop 0
	v_cvt_pk_bf16_f32 v30, v30, v31
	v_cvt_pk_bf16_f32 v31, v40, v41
	global_store_dwordx4 v[44:45], v[28:31], off offset:256
	s_nop 1
	v_lshl_add_u64 v[28:29], v[132:133], 0, s[44:45]
	v_pk_add_f32 v[30:31], v[34:35], 0 op_sel_hi:[1,0]
	s_mov_b32 s44, 0xa0000
	v_pk_add_f32 v[34:35], v[26:27], 0 op_sel_hi:[1,0]
	v_pk_add_f32 v[26:27], v[24:25], 0 op_sel_hi:[1,0]
	v_cvt_pk_bf16_f32 v24, v32, v33
	v_cvt_pk_bf16_f32 v25, v30, v31
	v_add_co_u32_e32 v30, vcc, s44, v132
	v_cvt_pk_bf16_f32 v26, v26, v27
	v_cvt_pk_bf16_f32 v27, v34, v35
	s_mov_b64 s[44:45], 0xb0000
	s_nop 0
	v_addc_co_u32_e32 v31, vcc, 0, v133, vcc
	global_store_dwordx4 v[30:31], v[24:27], off
	s_nop 1
	v_pk_add_f32 v[24:25], v[14:15], 0 op_sel_hi:[1,0]
	v_pk_add_f32 v[14:15], v[12:13], 0 op_sel_hi:[1,0]
	v_cvt_pk_bf16_f32 v12, v20, v21
	v_cvt_pk_bf16_f32 v13, v22, v23
	s_nop 0
	v_cvt_pk_bf16_f32 v14, v14, v15
	v_cvt_pk_bf16_f32 v15, v24, v25
	global_store_dwordx4 v[28:29], v[12:15], off offset:256
	s_nop 1
	v_lshl_add_u64 v[12:13], v[132:133], 0, s[44:45]
	v_pk_add_f32 v[14:15], v[18:19], 0 op_sel_hi:[1,0]
	s_mov_b32 s44, 0xb0000
	v_pk_add_f32 v[18:19], v[10:11], 0 op_sel_hi:[1,0]
	v_pk_add_f32 v[10:11], v[8:9], 0 op_sel_hi:[1,0]
	v_cvt_pk_bf16_f32 v8, v16, v17
	v_cvt_pk_bf16_f32 v9, v14, v15
	v_add_co_u32_e32 v14, vcc, s44, v132
	v_cvt_pk_bf16_f32 v10, v10, v11
	v_cvt_pk_bf16_f32 v11, v18, v19
	s_mov_b32 s44, s38
	s_nop 0
	v_addc_co_u32_e32 v15, vcc, 0, v133, vcc
	global_store_dwordx4 v[14:15], v[8:11], off
	s_nop 1
	v_pk_add_f32 v[8:9], v[2:3], 0 op_sel_hi:[1,0]
	v_pk_add_f32 v[2:3], v[0:1], 0 op_sel_hi:[1,0]
	v_cvt_pk_bf16_f32 v0, v4, v5
	v_cvt_pk_bf16_f32 v1, v6, v7
	s_nop 0
	v_cvt_pk_bf16_f32 v2, v2, v3
	v_cvt_pk_bf16_f32 v3, v8, v9
	global_store_dwordx4 v[12:13], v[0:3], off offset:256
	s_mul_i32 s46, s44, s13
	s_add_i32 s46, s46, s0
	s_cmpk_gt_i32 s46, 0x10f
	s_cbranch_scc1 .LBB0_333
	s_ashr_i32 s44, s46, 31
	s_lshr_b32 s44, s44, 29
	s_add_i32 s44, s46, s44
	s_ashr_i32 s45, s44, 3
	s_and_b32 s44, s44, -8
	s_sub_i32 s44, s46, s44
	s_cmp_lt_i32 s44, 0
	s_cselect_b32 s46, 35, 34
	s_mul_i32 s44, s46, s44
	s_add_i32 s44, s44, s45
	s_ashr_i32 s45, s44, 31
	s_lshr_b32 s45, s45, 26
	s_add_i32 s45, s44, s45
	s_ashr_i32 s46, s45, 6
	s_lshl_b32 s46, s46, 3
	s_sub_i32 s47, 34, s46
	s_min_u32 s47, s47, 8
	s_andn2_b32 s45, s45, 63
	s_sub_i32 s48, s44, s45
	v_cvt_f32_ubyte0_e32 v1, s47
	v_cvt_f32_i32_e32 v0, s48
	v_rcp_iflag_f32_e32 v2, v1
	s_ashr_i32 s44, s48, 30
	s_or_b32 s49, s44, 1
	s_mov_b64 s[66:67], 0
	v_mul_f32_e32 v2, v0, v2
	v_trunc_f32_e32 v2, v2
	v_fma_f32 v0, -v2, v1, v0
	v_cvt_i32_f32_e32 v2, v2
	v_cmp_ge_f32_e64 s[44:45], |v0|, v1
	s_and_b64 s[44:45], s[44:45], exec
	s_cselect_b32 s44, s49, 0
	v_readfirstlane_b32 s45, v2
	s_add_i32 s44, s45, s44
	s_sext_i32_i8 s45, s44
	s_mul_i32 s44, s44, s47
	s_sub_i32 s44, s48, s44
	s_sext_i32_i8 s44, s44
	s_add_i32 s44, s46, s44
	s_branch .LBB0_333

.LBB0_358:
	ds_read_b128 v[142:145], v138
	ds_read_b128 v[146:149], v138 offset:1024
	ds_read_b128 v[150:153], v138 offset:2048
	ds_read_b128 v[154:157], v138 offset:3072
	s_add_u32 s49, s66, 0xfffe0080
	s_addc_u32 s50, s67, -1
	s_cmp_eq_u32 s48, 4
	s_cselect_b32 s51, s65, s50
	s_cselect_b32 s50, s64, s49
	s_cselect_b32 s69, s63, s47
	s_cselect_b32 s68, s62, s46
	v_lshl_add_u64 v[190:191], s[66:67], 0, v[134:135]
	s_add_i32 m0, s29, 0xc000
	ds_read_b128 v[158:161], v139
	ds_read_b128 v[162:165], v139 offset:1024
	ds_read_b128 v[166:169], v139 offset:2048
	ds_read_b128 v[170:173], v139 offset:3072
	ds_read_b128 v[174:177], v139 offset:4096
	ds_read_b128 v[178:181], v139 offset:5120
	ds_read_b128 v[182:185], v139 offset:6144
	ds_read_b128 v[186:189], v139 offset:7168
	global_load_lds_dwordx4 v[190:191], off
	v_lshl_add_u64 v[190:191], v[190:191], 0, s[18:19]
	s_add_i32 m0, s29, 0xe000
	s_nop 0
	global_load_lds_dwordx4 v[190:191], off
	s_waitcnt lgkmcnt(8)
	s_barrier
	s_waitcnt lgkmcnt(0)
	s_waitcnt lgkmcnt(0)
	v_mfma_f32_16x16x32_bf16 v[124:127], v[142:145], v[158:161], v[124:127]
	v_mfma_f32_16x16x32_bf16 v[120:123], v[150:153], v[158:161], v[120:123]
	v_mfma_f32_16x16x32_bf16 v[112:115], v[142:145], v[166:169], v[112:115]
	v_mfma_f32_16x16x32_bf16 v[104:107], v[150:153], v[166:169], v[104:107]
	v_mfma_f32_16x16x32_bf16 v[96:99], v[142:145], v[174:177], v[96:99]
	v_mfma_f32_16x16x32_bf16 v[88:91], v[150:153], v[174:177], v[88:91]
	v_mfma_f32_16x16x32_bf16 v[80:83], v[142:145], v[182:185], v[80:83]
	v_mfma_f32_16x16x32_bf16 v[72:75], v[150:153], v[182:185], v[72:75]
	v_mfma_f32_16x16x32_bf16 v[124:127], v[146:149], v[162:165], v[124:127]
	v_mfma_f32_16x16x32_bf16 v[120:123], v[154:157], v[162:165], v[120:123]
	v_mfma_f32_16x16x32_bf16 v[112:115], v[146:149], v[170:173], v[112:115]
	v_mfma_f32_16x16x32_bf16 v[104:107], v[154:157], v[170:173], v[104:107]
	v_mfma_f32_16x16x32_bf16 v[96:99], v[146:149], v[178:181], v[96:99]
	v_mfma_f32_16x16x32_bf16 v[88:91], v[154:157], v[178:181], v[88:91]
	v_mfma_f32_16x16x32_bf16 v[80:83], v[146:149], v[186:189], v[80:83]
	v_mfma_f32_16x16x32_bf16 v[72:75], v[154:157], v[186:189], v[72:75]
	s_barrier
	s_add_i32 s49, s42, s28
	v_lshl_add_u64 v[206:207], s[68:69], 0, v[128:129]
	s_mov_b32 m0, s49
	ds_read_b128 v[190:193], v140
	ds_read_b128 v[194:197], v140 offset:1024
	ds_read_b128 v[198:201], v140 offset:2048
	ds_read_b128 v[202:205], v140 offset:3072
	global_load_lds_dwordx4 v[206:207], off
	v_lshl_add_u64 v[208:209], v[206:207], 0, s[10:11]
	s_add_i32 m0, s49, 0x2000
	s_nop 0
	global_load_lds_dwordx4 v[208:209], off
	s_barrier
	s_waitcnt lgkmcnt(0)
	s_waitcnt lgkmcnt(0)
	v_mfma_f32_16x16x32_bf16 v[116:119], v[190:193], v[158:161], v[116:119]
	v_mfma_f32_16x16x32_bf16 v[108:111], v[198:201], v[158:161], v[108:111]
	v_mfma_f32_16x16x32_bf16 v[100:103], v[190:193], v[166:169], v[100:103]
	v_mfma_f32_16x16x32_bf16 v[92:95], v[198:201], v[166:169], v[92:95]
	v_mfma_f32_16x16x32_bf16 v[84:87], v[190:193], v[174:177], v[84:87]
	v_mfma_f32_16x16x32_bf16 v[76:79], v[198:201], v[174:177], v[76:79]
	v_mfma_f32_16x16x32_bf16 v[68:71], v[190:193], v[182:185], v[68:71]
	v_mfma_f32_16x16x32_bf16 v[64:67], v[198:201], v[182:185], v[64:67]
	v_mfma_f32_16x16x32_bf16 v[116:119], v[194:197], v[162:165], v[116:119]
	v_mfma_f32_16x16x32_bf16 v[108:111], v[202:205], v[162:165], v[108:111]
	v_mfma_f32_16x16x32_bf16 v[100:103], v[194:197], v[170:173], v[100:103]
	v_mfma_f32_16x16x32_bf16 v[92:95], v[202:205], v[170:173], v[92:95]
	v_mfma_f32_16x16x32_bf16 v[84:87], v[194:197], v[178:181], v[84:87]
	v_mfma_f32_16x16x32_bf16 v[76:79], v[202:205], v[178:181], v[76:79]
	v_mfma_f32_16x16x32_bf16 v[68:71], v[194:197], v[186:189], v[68:71]
	v_mfma_f32_16x16x32_bf16 v[64:67], v[202:205], v[186:189], v[64:67]
	s_mov_b32 m0, s29
	v_lshl_add_u64 v[208:209], s[50:51], 0, v[130:131]
	s_barrier
	ds_read_b128 v[158:161], v139 offset:16384
	ds_read_b128 v[162:165], v139 offset:17408
	ds_read_b128 v[166:169], v139 offset:18432
	ds_read_b128 v[170:173], v139 offset:19456
	ds_read_b128 v[174:177], v139 offset:20480
	ds_read_b128 v[178:181], v139 offset:21504
	ds_read_b128 v[182:185], v139 offset:22528
	ds_read_b128 v[186:189], v139 offset:23552
	global_load_lds_dwordx4 v[208:209], off
	v_lshl_add_u64 v[210:211], v[208:209], 0, s[18:19]
	s_mov_b32 m0, s30
	s_nop 0
	global_load_lds_dwordx4 v[210:211], off
	s_barrier
	s_waitcnt lgkmcnt(0)
	s_waitcnt lgkmcnt(0)
	v_mfma_f32_16x16x32_bf16 v[60:63], v[142:145], v[158:161], v[60:63]
	v_mfma_f32_16x16x32_bf16 v[56:59], v[150:153], v[158:161], v[56:59]
	v_mfma_f32_16x16x32_bf16 v[52:55], v[142:145], v[166:169], v[52:55]
	v_mfma_f32_16x16x32_bf16 v[44:47], v[150:153], v[166:169], v[44:47]
	v_mfma_f32_16x16x32_bf16 v[36:39], v[142:145], v[174:177], v[36:39]
	v_mfma_f32_16x16x32_bf16 v[28:31], v[150:153], v[174:177], v[28:31]
	v_mfma_f32_16x16x32_bf16 v[20:23], v[142:145], v[182:185], v[20:23]
	v_mfma_f32_16x16x32_bf16 v[12:15], v[150:153], v[182:185], v[12:15]
	v_mfma_f32_16x16x32_bf16 v[60:63], v[146:149], v[162:165], v[60:63]
	v_mfma_f32_16x16x32_bf16 v[56:59], v[154:157], v[162:165], v[56:59]
	v_mfma_f32_16x16x32_bf16 v[52:55], v[146:149], v[170:173], v[52:55]
	v_mfma_f32_16x16x32_bf16 v[44:47], v[154:157], v[170:173], v[44:47]
	v_mfma_f32_16x16x32_bf16 v[36:39], v[146:149], v[178:181], v[36:39]
	v_mfma_f32_16x16x32_bf16 v[28:31], v[154:157], v[178:181], v[28:31]
	v_mfma_f32_16x16x32_bf16 v[20:23], v[146:149], v[186:189], v[20:23]
	v_mfma_f32_16x16x32_bf16 v[12:15], v[154:157], v[186:189], v[12:15]
	s_barrier
	s_add_i32 s49, s43, s28
	v_lshl_add_u64 v[142:143], v[206:207], 0, s[22:23]
	s_mov_b32 m0, s49
	s_nop 0
	global_load_lds_dwordx4 v[142:143], off
	v_lshl_add_u64 v[142:143], v[206:207], 0, s[24:25]
	s_add_i32 m0, s49, 0x2000
	s_nop 0
	global_load_lds_dwordx4 v[142:143], off
	s_waitcnt vmcnt(6)
	s_barrier
	v_mfma_f32_16x16x32_bf16 v[48:51], v[190:193], v[158:161], v[48:51]
	v_mfma_f32_16x16x32_bf16 v[40:43], v[198:201], v[158:161], v[40:43]
	v_mfma_f32_16x16x32_bf16 v[32:35], v[190:193], v[166:169], v[32:35]
	v_mfma_f32_16x16x32_bf16 v[24:27], v[198:201], v[166:169], v[24:27]
	v_mfma_f32_16x16x32_bf16 v[16:19], v[190:193], v[174:177], v[16:19]
	v_mfma_f32_16x16x32_bf16 v[8:11], v[198:201], v[174:177], v[8:11]
	v_mfma_f32_16x16x32_bf16 v[4:7], v[190:193], v[182:185], v[4:7]
	v_mfma_f32_16x16x32_bf16 v[0:3], v[198:201], v[182:185], v[0:3]
	v_mfma_f32_16x16x32_bf16 v[48:51], v[194:197], v[162:165], v[48:51]
	v_mfma_f32_16x16x32_bf16 v[40:43], v[202:205], v[162:165], v[40:43]
	v_mfma_f32_16x16x32_bf16 v[32:35], v[194:197], v[170:173], v[32:35]
	v_mfma_f32_16x16x32_bf16 v[24:27], v[202:205], v[170:173], v[24:27]
	v_mfma_f32_16x16x32_bf16 v[16:19], v[194:197], v[178:181], v[16:19]
	v_mfma_f32_16x16x32_bf16 v[8:11], v[202:205], v[178:181], v[8:11]
	v_mfma_f32_16x16x32_bf16 v[4:7], v[194:197], v[186:189], v[4:7]
	v_mfma_f32_16x16x32_bf16 v[0:3], v[202:205], v[186:189], v[0:3]
	s_add_i32 s49, 0, 0x18000
	v_add_u32_e32 v132, s49, v137
	s_barrier
	ds_read_b128 v[142:145], v132
	ds_read_b128 v[146:149], v132 offset:1024
	ds_read_b128 v[150:153], v132 offset:2048
	ds_read_b128 v[154:157], v132 offset:3072
	s_mov_b32 m0, s31
	v_lshl_add_u64 v[190:191], v[208:209], 0, s[26:27]
	ds_read_b128 v[158:161], v139 offset:32768
	ds_read_b128 v[162:165], v139 offset:33792
	ds_read_b128 v[166:169], v139 offset:34816
	ds_read_b128 v[170:173], v139 offset:35840
	ds_read_b128 v[174:177], v139 offset:36864
	ds_read_b128 v[178:181], v139 offset:37888
	ds_read_b128 v[182:185], v139 offset:38912
	ds_read_b128 v[186:189], v139 offset:39936
	global_load_lds_dwordx4 v[190:191], off
	v_lshl_add_u64 v[190:191], v[208:209], 0, s[34:35]
	s_mov_b32 m0, s33
	s_nop 0
	global_load_lds_dwordx4 v[190:191], off
	s_waitcnt lgkmcnt(8)
	s_barrier
	s_waitcnt lgkmcnt(0)
	s_waitcnt lgkmcnt(0)
	v_mfma_f32_16x16x32_bf16 v[124:127], v[142:145], v[158:161], v[124:127]
	v_mfma_f32_16x16x32_bf16 v[120:123], v[150:153], v[158:161], v[120:123]
	v_mfma_f32_16x16x32_bf16 v[112:115], v[142:145], v[166:169], v[112:115]
	v_mfma_f32_16x16x32_bf16 v[104:107], v[150:153], v[166:169], v[104:107]
	v_mfma_f32_16x16x32_bf16 v[96:99], v[142:145], v[174:177], v[96:99]
	v_mfma_f32_16x16x32_bf16 v[88:91], v[150:153], v[174:177], v[88:91]
	v_mfma_f32_16x16x32_bf16 v[80:83], v[142:145], v[182:185], v[80:83]
	v_mfma_f32_16x16x32_bf16 v[72:75], v[150:153], v[182:185], v[72:75]
	v_mfma_f32_16x16x32_bf16 v[124:127], v[146:149], v[162:165], v[124:127]
	v_mfma_f32_16x16x32_bf16 v[120:123], v[154:157], v[162:165], v[120:123]
	v_mfma_f32_16x16x32_bf16 v[112:115], v[146:149], v[170:173], v[112:115]
	v_mfma_f32_16x16x32_bf16 v[104:107], v[154:157], v[170:173], v[104:107]
	v_mfma_f32_16x16x32_bf16 v[96:99], v[146:149], v[178:181], v[96:99]
	v_mfma_f32_16x16x32_bf16 v[88:91], v[154:157], v[178:181], v[88:91]
	v_mfma_f32_16x16x32_bf16 v[80:83], v[146:149], v[186:189], v[80:83]
	v_mfma_f32_16x16x32_bf16 v[72:75], v[154:157], v[186:189], v[72:75]
	s_barrier
	s_add_i32 s50, 0, 0x1c000
	s_add_i32 s49, s49, s28
	v_add_u32_e32 v132, s50, v137
	v_lshl_add_u64 v[210:211], v[206:207], 0, s[52:53]
	s_mov_b32 m0, s49
	ds_read_b128 v[190:193], v132
	ds_read_b128 v[194:197], v132 offset:1024
	ds_read_b128 v[198:201], v132 offset:2048
	ds_read_b128 v[202:205], v132 offset:3072
	global_load_lds_dwordx4 v[210:211], off
	v_lshl_add_u64 v[210:211], v[206:207], 0, s[54:55]
	s_add_i32 m0, s49, 0x2000
	s_nop 0
	global_load_lds_dwordx4 v[210:211], off
	s_barrier
	s_waitcnt lgkmcnt(0)
	s_waitcnt lgkmcnt(0)
	v_mfma_f32_16x16x32_bf16 v[116:119], v[190:193], v[158:161], v[116:119]
	v_mfma_f32_16x16x32_bf16 v[108:111], v[198:201], v[158:161], v[108:111]
	v_mfma_f32_16x16x32_bf16 v[100:103], v[190:193], v[166:169], v[100:103]
	v_mfma_f32_16x16x32_bf16 v[92:95], v[198:201], v[166:169], v[92:95]
	v_mfma_f32_16x16x32_bf16 v[84:87], v[190:193], v[174:177], v[84:87]
	v_mfma_f32_16x16x32_bf16 v[76:79], v[198:201], v[174:177], v[76:79]
	v_mfma_f32_16x16x32_bf16 v[68:71], v[190:193], v[182:185], v[68:71]
	v_mfma_f32_16x16x32_bf16 v[64:67], v[198:201], v[182:185], v[64:67]
	v_mfma_f32_16x16x32_bf16 v[116:119], v[194:197], v[162:165], v[116:119]
	v_mfma_f32_16x16x32_bf16 v[108:111], v[202:205], v[162:165], v[108:111]
	v_mfma_f32_16x16x32_bf16 v[100:103], v[194:197], v[170:173], v[100:103]
	v_mfma_f32_16x16x32_bf16 v[92:95], v[202:205], v[170:173], v[92:95]
	v_mfma_f32_16x16x32_bf16 v[84:87], v[194:197], v[178:181], v[84:87]
	v_mfma_f32_16x16x32_bf16 v[76:79], v[202:205], v[178:181], v[76:79]
	v_mfma_f32_16x16x32_bf16 v[68:71], v[194:197], v[186:189], v[68:71]
	v_mfma_f32_16x16x32_bf16 v[64:67], v[202:205], v[186:189], v[64:67]
	s_mov_b32 m0, s38
	v_lshl_add_u64 v[210:211], v[208:209], 0, s[52:53]
	s_barrier
	ds_read_b128 v[158:161], v139 offset:49152
	ds_read_b128 v[162:165], v139 offset:50176
	ds_read_b128 v[166:169], v139 offset:51200
	ds_read_b128 v[170:173], v139 offset:52224
	ds_read_b128 v[174:177], v139 offset:53248
	ds_read_b128 v[178:181], v139 offset:54272
	ds_read_b128 v[182:185], v139 offset:55296
	ds_read_b128 v[186:189], v139 offset:56320
	global_load_lds_dwordx4 v[210:211], off
	v_lshl_add_u64 v[208:209], v[208:209], 0, s[56:57]
	s_mov_b32 m0, s39
	s_nop 0
	global_load_lds_dwordx4 v[208:209], off
	s_barrier
	s_waitcnt lgkmcnt(0)
	s_waitcnt lgkmcnt(0)
	v_mfma_f32_16x16x32_bf16 v[60:63], v[142:145], v[158:161], v[60:63]
	v_mfma_f32_16x16x32_bf16 v[56:59], v[150:153], v[158:161], v[56:59]
	v_mfma_f32_16x16x32_bf16 v[52:55], v[142:145], v[166:169], v[52:55]
	v_mfma_f32_16x16x32_bf16 v[44:47], v[150:153], v[166:169], v[44:47]
	v_mfma_f32_16x16x32_bf16 v[36:39], v[142:145], v[174:177], v[36:39]
	v_mfma_f32_16x16x32_bf16 v[28:31], v[150:153], v[174:177], v[28:31]
	v_mfma_f32_16x16x32_bf16 v[20:23], v[142:145], v[182:185], v[20:23]
	v_mfma_f32_16x16x32_bf16 v[12:15], v[150:153], v[182:185], v[12:15]
	v_mfma_f32_16x16x32_bf16 v[60:63], v[146:149], v[162:165], v[60:63]
	v_mfma_f32_16x16x32_bf16 v[56:59], v[154:157], v[162:165], v[56:59]
	v_mfma_f32_16x16x32_bf16 v[52:55], v[146:149], v[170:173], v[52:55]
	v_mfma_f32_16x16x32_bf16 v[44:47], v[154:157], v[170:173], v[44:47]
	v_mfma_f32_16x16x32_bf16 v[36:39], v[146:149], v[178:181], v[36:39]
	v_mfma_f32_16x16x32_bf16 v[28:31], v[154:157], v[178:181], v[28:31]
	v_mfma_f32_16x16x32_bf16 v[20:23], v[146:149], v[186:189], v[20:23]
	v_mfma_f32_16x16x32_bf16 v[12:15], v[154:157], v[186:189], v[12:15]
	s_barrier
	s_add_i32 s49, s50, s28
	v_lshl_add_u64 v[142:143], v[206:207], 0, s[58:59]
	s_mov_b32 m0, s49
	s_nop 0
	global_load_lds_dwordx4 v[142:143], off
	v_lshl_add_u64 v[142:143], v[206:207], 0, s[60:61]
	s_add_i32 m0, s49, 0x2000
	s_nop 0
	global_load_lds_dwordx4 v[142:143], off
	s_waitcnt vmcnt(6)
	s_barrier
	v_mfma_f32_16x16x32_bf16 v[48:51], v[190:193], v[158:161], v[48:51]
	v_mfma_f32_16x16x32_bf16 v[40:43], v[198:201], v[158:161], v[40:43]
	v_mfma_f32_16x16x32_bf16 v[32:35], v[190:193], v[166:169], v[32:35]
	v_mfma_f32_16x16x32_bf16 v[24:27], v[198:201], v[166:169], v[24:27]
	v_mfma_f32_16x16x32_bf16 v[16:19], v[190:193], v[174:177], v[16:19]
	v_mfma_f32_16x16x32_bf16 v[8:11], v[198:201], v[174:177], v[8:11]
	v_mfma_f32_16x16x32_bf16 v[4:7], v[190:193], v[182:185], v[4:7]
	v_mfma_f32_16x16x32_bf16 v[0:3], v[198:201], v[182:185], v[0:3]
	v_mfma_f32_16x16x32_bf16 v[48:51], v[194:197], v[162:165], v[48:51]
	v_mfma_f32_16x16x32_bf16 v[40:43], v[202:205], v[162:165], v[40:43]
	v_mfma_f32_16x16x32_bf16 v[32:35], v[194:197], v[170:173], v[32:35]
	v_mfma_f32_16x16x32_bf16 v[24:27], v[202:205], v[170:173], v[24:27]
	v_mfma_f32_16x16x32_bf16 v[16:19], v[194:197], v[178:181], v[16:19]
	v_mfma_f32_16x16x32_bf16 v[8:11], v[202:205], v[178:181], v[8:11]
	v_mfma_f32_16x16x32_bf16 v[4:7], v[194:197], v[186:189], v[4:7]
	v_mfma_f32_16x16x32_bf16 v[0:3], v[202:205], v[186:189], v[0:3]
	s_add_i32 s48, s48, 2
	s_add_u32 s66, s66, 0x100
	s_addc_u32 s67, s67, 0
	s_add_u32 s46, s46, 0x100
	s_addc_u32 s47, s47, 0
	s_cmp_gt_u32 s48, 5
	s_barrier
	s_cbranch_scc0 .LBB0_358
	s_lshl_b32 s48, s45, 5
	s_and_b32 s48, s48, 0xfffffe00
	s_lshl_b32 s44, s44, 7
	v_mov_b32_e32 v132, v136
	s_mov_b32 s46, s37
	s_mov_b32 s47, s21
	s_add_i32 s48, s48, s44
	s_lshl_b32 s44, s45, 9
	s_and_b32 s44, s44, 0x1e00
	v_and_or_b32 v141, v132, 15, s48
	v_lshl_add_u32 v142, s47, 6, v141
	s_add_u32 s47, s40, s44
	s_addc_u32 s48, s41, 0
	s_lshl_b32 s44, s46, 5
	s_ashr_i32 s45, s44, 31
	s_lshl_b64 s[44:45], s[44:45], 1
	s_add_u32 s44, s47, s44
	s_addc_u32 s45, s48, s45
	v_and_b32_e32 v132, 48, v132
	v_ashrrev_i32_e32 v143, 31, v142
	v_lshl_add_u64 v[144:145], s[44:45], 0, v[132:133]
	v_lshlrev_b64 v[146:147], 14, v[142:143]
	v_lshl_add_u64 v[148:149], v[144:145], 0, v[146:147]
	v_cvt_pk_bf16_f32 v124, v124, v125
	v_cvt_pk_bf16_f32 v125, v126, v127
	v_cvt_pk_bf16_f32 v126, v120, v121
	v_cvt_pk_bf16_f32 v127, v122, v123
	global_store_dwordx4 v[148:149], v[124:127], off
	v_cvt_pk_bf16_f32 v116, v116, v117
	v_cvt_pk_bf16_f32 v117, v118, v119
	v_cvt_pk_bf16_f32 v118, v108, v109
	v_or_b32_e32 v108, 16, v142
	v_ashrrev_i32_e32 v109, 31, v108
	v_cvt_pk_bf16_f32 v119, v110, v111
	global_store_dwordx4 v[148:149], v[116:119], off offset:256
	s_mov_b64 s[44:45], 0x2000
	s_mov_b64 s[66:67], -1
	v_lshlrev_b64 v[116:117], 14, v[108:109]
	v_lshl_add_u64 v[118:119], v[144:145], 0, v[116:117]
	v_cvt_pk_bf16_f32 v108, v112, v113
	v_cvt_pk_bf16_f32 v109, v114, v115
	v_cvt_pk_bf16_f32 v110, v104, v105
	v_cvt_pk_bf16_f32 v111, v106, v107
	global_store_dwordx4 v[118:119], v[108:111], off
	v_cvt_pk_bf16_f32 v100, v100, v101
	v_cvt_pk_bf16_f32 v101, v102, v103
	v_cvt_pk_bf16_f32 v102, v92, v93
	v_or_b32_e32 v92, 32, v142
	v_ashrrev_i32_e32 v93, 31, v92
	v_cvt_pk_bf16_f32 v103, v94, v95
	global_store_dwordx4 v[118:119], v[100:103], off offset:256
	s_nop 1
	v_lshlrev_b64 v[100:101], 14, v[92:93]
	v_lshl_add_u64 v[102:103], v[144:145], 0, v[100:101]
	v_cvt_pk_bf16_f32 v92, v96, v97
	v_cvt_pk_bf16_f32 v93, v98, v99
	v_cvt_pk_bf16_f32 v94, v88, v89
	v_cvt_pk_bf16_f32 v95, v90, v91
	global_store_dwordx4 v[102:103], v[92:95], off
	v_cvt_pk_bf16_f32 v84, v84, v85
	v_cvt_pk_bf16_f32 v85, v86, v87
	v_cvt_pk_bf16_f32 v86, v76, v77
	v_or_b32_e32 v76, 48, v142
	v_ashrrev_i32_e32 v77, 31, v76
	v_cvt_pk_bf16_f32 v87, v78, v79
	global_store_dwordx4 v[102:103], v[84:87], off offset:256
	s_nop 1
	v_lshlrev_b64 v[84:85], 14, v[76:77]
	v_lshl_add_u64 v[86:87], v[144:145], 0, v[84:85]
	v_cvt_pk_bf16_f32 v76, v80, v81
	v_cvt_pk_bf16_f32 v77, v82, v83
	v_cvt_pk_bf16_f32 v78, v72, v73
	v_cvt_pk_bf16_f32 v79, v74, v75
	global_store_dwordx4 v[86:87], v[76:79], off
	v_cvt_pk_bf16_f32 v68, v68, v69
	v_cvt_pk_bf16_f32 v69, v70, v71
	v_cvt_pk_bf16_f32 v70, v64, v65
	v_lshl_add_u64 v[64:65], v[144:145], 0, s[44:45]
	v_cvt_pk_bf16_f32 v71, v66, v67
	v_lshl_add_u64 v[66:67], v[64:65], 0, v[146:147]
	global_store_dwordx4 v[86:87], v[68:71], off offset:256
	v_cvt_pk_bf16_f32 v60, v60, v61
	v_cvt_pk_bf16_f32 v61, v62, v63
	v_cvt_pk_bf16_f32 v62, v56, v57
	v_cvt_pk_bf16_f32 v63, v58, v59
	global_store_dwordx4 v[66:67], v[60:63], off
	v_cvt_pk_bf16_f32 v48, v48, v49
	v_cvt_pk_bf16_f32 v49, v50, v51
	v_cvt_pk_bf16_f32 v50, v40, v41
	v_cvt_pk_bf16_f32 v51, v42, v43
	global_store_dwordx4 v[66:67], v[48:51], off offset:256
	v_cvt_pk_bf16_f32 v40, v52, v53
	v_cvt_pk_bf16_f32 v41, v54, v55
	v_cvt_pk_bf16_f32 v42, v44, v45
	v_cvt_pk_bf16_f32 v43, v46, v47
	s_mov_b32 s44, s36
	s_nop 0
	v_lshl_add_u64 v[48:49], v[64:65], 0, v[116:117]
	global_store_dwordx4 v[48:49], v[40:43], off
	v_cvt_pk_bf16_f32 v32, v32, v33
	v_cvt_pk_bf16_f32 v33, v34, v35
	v_cvt_pk_bf16_f32 v34, v24, v25
	v_cvt_pk_bf16_f32 v35, v26, v27
	global_store_dwordx4 v[48:49], v[32:35], off offset:256
	v_cvt_pk_bf16_f32 v24, v36, v37
	v_cvt_pk_bf16_f32 v25, v38, v39
	v_cvt_pk_bf16_f32 v26, v28, v29
	v_cvt_pk_bf16_f32 v27, v30, v31
	s_nop 1
	v_lshl_add_u64 v[32:33], v[64:65], 0, v[100:101]
	global_store_dwordx4 v[32:33], v[24:27], off
	v_cvt_pk_bf16_f32 v16, v16, v17
	v_cvt_pk_bf16_f32 v17, v18, v19
	v_cvt_pk_bf16_f32 v18, v8, v9
	v_cvt_pk_bf16_f32 v19, v10, v11
	global_store_dwordx4 v[32:33], v[16:19], off offset:256
	v_cvt_pk_bf16_f32 v8, v20, v21
	v_cvt_pk_bf16_f32 v9, v22, v23
	v_cvt_pk_bf16_f32 v10, v12, v13
	v_cvt_pk_bf16_f32 v11, v14, v15
	s_nop 1
	v_lshl_add_u64 v[16:17], v[64:65], 0, v[84:85]
	global_store_dwordx4 v[16:17], v[8:11], off
	v_cvt_pk_bf16_f32 v4, v4, v5
	v_cvt_pk_bf16_f32 v5, v6, v7
	v_cvt_pk_bf16_f32 v6, v0, v1
	v_cvt_pk_bf16_f32 v7, v2, v3
	global_store_dwordx4 v[16:17], v[4:7], off offset:256
	s_mul_i32 s46, s44, s13
	s_add_i32 s46, s46, s1
	s_cmpk_gt_i32 s46, 0x7f
	s_cbranch_scc1 .LBB0_348
	s_ashr_i32 s44, s46, 31
	s_lshr_b32 s44, s44, 29
	s_add_i32 s44, s46, s44
	s_and_b32 s45, s44, -8
	s_sub_i32 s45, s46, s45
	s_cmp_gt_i32 s45, -1
	s_cbranch_scc0 .LBB0_362
	s_lshl_b32 s46, s45, 4
	s_mov_b64 s[66:67], 0

.LBB0_375:
	ds_read_b128 v[142:145], v138
	ds_read_b128 v[146:149], v138 offset:1024
	ds_read_b128 v[150:153], v138 offset:2048
	ds_read_b128 v[154:157], v138 offset:3072
	s_add_u32 s48, s68, 0xfffe0080
	s_addc_u32 s49, s69, -1
	s_cmp_eq_u32 s47, 4
	s_cselect_b32 s49, s65, s49
	s_cselect_b32 s48, s64, s48
	s_cselect_b32 s51, s67, s46
	s_cselect_b32 s50, s66, s45
	s_mov_b32 m0, s39
	v_lshl_add_u64 v[190:191], s[68:69], 0, v[134:135]
	ds_read_b128 v[158:161], v139
	ds_read_b128 v[162:165], v139 offset:1024
	ds_read_b128 v[166:169], v139 offset:2048
	ds_read_b128 v[170:173], v139 offset:3072
	ds_read_b128 v[174:177], v139 offset:4096
	ds_read_b128 v[178:181], v139 offset:5120
	ds_read_b128 v[182:185], v139 offset:6144
	ds_read_b128 v[186:189], v139 offset:7168
	global_load_lds_dwordx4 v[190:191], off
	v_lshl_add_u64 v[190:191], v[190:191], 0, s[18:19]
	s_mov_b32 m0, s40
	s_nop 0
	global_load_lds_dwordx4 v[190:191], off
	s_waitcnt lgkmcnt(8)
	s_barrier
	s_waitcnt lgkmcnt(0)
	s_waitcnt lgkmcnt(0)
	v_mfma_f32_16x16x32_bf16 v[124:127], v[142:145], v[158:161], v[124:127]
	v_mfma_f32_16x16x32_bf16 v[120:123], v[150:153], v[158:161], v[120:123]
	v_mfma_f32_16x16x32_bf16 v[112:115], v[142:145], v[166:169], v[112:115]
	v_mfma_f32_16x16x32_bf16 v[104:107], v[150:153], v[166:169], v[104:107]
	v_mfma_f32_16x16x32_bf16 v[96:99], v[142:145], v[174:177], v[96:99]
	v_mfma_f32_16x16x32_bf16 v[88:91], v[150:153], v[174:177], v[88:91]
	v_mfma_f32_16x16x32_bf16 v[80:83], v[142:145], v[182:185], v[80:83]
	v_mfma_f32_16x16x32_bf16 v[72:75], v[150:153], v[182:185], v[72:75]
	v_mfma_f32_16x16x32_bf16 v[124:127], v[146:149], v[162:165], v[124:127]
	v_mfma_f32_16x16x32_bf16 v[120:123], v[154:157], v[162:165], v[120:123]
	v_mfma_f32_16x16x32_bf16 v[112:115], v[146:149], v[170:173], v[112:115]
	v_mfma_f32_16x16x32_bf16 v[104:107], v[154:157], v[170:173], v[104:107]
	v_mfma_f32_16x16x32_bf16 v[96:99], v[146:149], v[178:181], v[96:99]
	v_mfma_f32_16x16x32_bf16 v[88:91], v[154:157], v[178:181], v[88:91]
	v_mfma_f32_16x16x32_bf16 v[80:83], v[146:149], v[186:189], v[80:83]
	v_mfma_f32_16x16x32_bf16 v[72:75], v[154:157], v[186:189], v[72:75]
	s_barrier
	s_mov_b32 m0, s41
	v_lshl_add_u64 v[206:207], s[50:51], 0, v[128:129]
	ds_read_b128 v[190:193], v140
	ds_read_b128 v[194:197], v140 offset:1024
	ds_read_b128 v[198:201], v140 offset:2048
	ds_read_b128 v[202:205], v140 offset:3072
	global_load_lds_dwordx4 v[206:207], off
	v_lshl_add_u64 v[208:209], v[206:207], 0, s[10:11]
	s_add_i32 m0, s41, 0x2000
	s_nop 0
	global_load_lds_dwordx4 v[208:209], off
	s_barrier
	s_waitcnt lgkmcnt(0)
	s_waitcnt lgkmcnt(0)
	v_mfma_f32_16x16x32_bf16 v[116:119], v[190:193], v[158:161], v[116:119]
	v_mfma_f32_16x16x32_bf16 v[108:111], v[198:201], v[158:161], v[108:111]
	v_mfma_f32_16x16x32_bf16 v[100:103], v[190:193], v[166:169], v[100:103]
	v_mfma_f32_16x16x32_bf16 v[92:95], v[198:201], v[166:169], v[92:95]
	v_mfma_f32_16x16x32_bf16 v[84:87], v[190:193], v[174:177], v[84:87]
	v_mfma_f32_16x16x32_bf16 v[76:79], v[198:201], v[174:177], v[76:79]
	v_mfma_f32_16x16x32_bf16 v[68:71], v[190:193], v[182:185], v[68:71]
	v_mfma_f32_16x16x32_bf16 v[64:67], v[198:201], v[182:185], v[64:67]
	v_mfma_f32_16x16x32_bf16 v[116:119], v[194:197], v[162:165], v[116:119]
	v_mfma_f32_16x16x32_bf16 v[108:111], v[202:205], v[162:165], v[108:111]
	v_mfma_f32_16x16x32_bf16 v[100:103], v[194:197], v[170:173], v[100:103]
	v_mfma_f32_16x16x32_bf16 v[92:95], v[202:205], v[170:173], v[92:95]
	v_mfma_f32_16x16x32_bf16 v[84:87], v[194:197], v[178:181], v[84:87]
	v_mfma_f32_16x16x32_bf16 v[76:79], v[202:205], v[178:181], v[76:79]
	v_mfma_f32_16x16x32_bf16 v[68:71], v[194:197], v[186:189], v[68:71]
	v_mfma_f32_16x16x32_bf16 v[64:67], v[202:205], v[186:189], v[64:67]
	s_mov_b32 m0, s28
	v_lshl_add_u64 v[208:209], s[48:49], 0, v[130:131]
	s_barrier
	ds_read_b128 v[158:161], v139 offset:16384
	ds_read_b128 v[162:165], v139 offset:17408
	ds_read_b128 v[166:169], v139 offset:18432
	ds_read_b128 v[170:173], v139 offset:19456
	ds_read_b128 v[174:177], v139 offset:20480
	ds_read_b128 v[178:181], v139 offset:21504
	ds_read_b128 v[182:185], v139 offset:22528
	ds_read_b128 v[186:189], v139 offset:23552
	global_load_lds_dwordx4 v[208:209], off
	v_lshl_add_u64 v[210:211], v[208:209], 0, s[18:19]
	s_mov_b32 m0, s29
	s_nop 0
	global_load_lds_dwordx4 v[210:211], off
	s_barrier
	s_waitcnt lgkmcnt(0)
	s_waitcnt lgkmcnt(0)
	v_mfma_f32_16x16x32_bf16 v[60:63], v[142:145], v[158:161], v[60:63]
	v_mfma_f32_16x16x32_bf16 v[56:59], v[150:153], v[158:161], v[56:59]
	v_mfma_f32_16x16x32_bf16 v[52:55], v[142:145], v[166:169], v[52:55]
	v_mfma_f32_16x16x32_bf16 v[44:47], v[150:153], v[166:169], v[44:47]
	v_mfma_f32_16x16x32_bf16 v[36:39], v[142:145], v[174:177], v[36:39]
	v_mfma_f32_16x16x32_bf16 v[28:31], v[150:153], v[174:177], v[28:31]
	v_mfma_f32_16x16x32_bf16 v[20:23], v[142:145], v[182:185], v[20:23]
	v_mfma_f32_16x16x32_bf16 v[12:15], v[150:153], v[182:185], v[12:15]
	v_mfma_f32_16x16x32_bf16 v[60:63], v[146:149], v[162:165], v[60:63]
	v_mfma_f32_16x16x32_bf16 v[56:59], v[154:157], v[162:165], v[56:59]
	v_mfma_f32_16x16x32_bf16 v[52:55], v[146:149], v[170:173], v[52:55]
	v_mfma_f32_16x16x32_bf16 v[44:47], v[154:157], v[170:173], v[44:47]
	v_mfma_f32_16x16x32_bf16 v[36:39], v[146:149], v[178:181], v[36:39]
	v_mfma_f32_16x16x32_bf16 v[28:31], v[154:157], v[178:181], v[28:31]
	v_mfma_f32_16x16x32_bf16 v[20:23], v[146:149], v[186:189], v[20:23]
	v_mfma_f32_16x16x32_bf16 v[12:15], v[154:157], v[186:189], v[12:15]
	s_barrier
	s_add_i32 s48, s38, s21
	v_lshl_add_u64 v[142:143], v[206:207], 0, s[22:23]
	s_mov_b32 m0, s48
	s_nop 0
	global_load_lds_dwordx4 v[142:143], off
	v_lshl_add_u64 v[142:143], v[206:207], 0, s[24:25]
	s_add_i32 m0, s48, 0x2000
	s_nop 0
	global_load_lds_dwordx4 v[142:143], off
	s_waitcnt vmcnt(6)
	s_barrier
	v_mfma_f32_16x16x32_bf16 v[48:51], v[190:193], v[158:161], v[48:51]
	v_mfma_f32_16x16x32_bf16 v[40:43], v[198:201], v[158:161], v[40:43]
	v_mfma_f32_16x16x32_bf16 v[32:35], v[190:193], v[166:169], v[32:35]
	v_mfma_f32_16x16x32_bf16 v[24:27], v[198:201], v[166:169], v[24:27]
	v_mfma_f32_16x16x32_bf16 v[16:19], v[190:193], v[174:177], v[16:19]
	v_mfma_f32_16x16x32_bf16 v[8:11], v[198:201], v[174:177], v[8:11]
	v_mfma_f32_16x16x32_bf16 v[4:7], v[190:193], v[182:185], v[4:7]
	v_mfma_f32_16x16x32_bf16 v[0:3], v[198:201], v[182:185], v[0:3]
	v_mfma_f32_16x16x32_bf16 v[48:51], v[194:197], v[162:165], v[48:51]
	v_mfma_f32_16x16x32_bf16 v[40:43], v[202:205], v[162:165], v[40:43]
	v_mfma_f32_16x16x32_bf16 v[32:35], v[194:197], v[170:173], v[32:35]
	v_mfma_f32_16x16x32_bf16 v[24:27], v[202:205], v[170:173], v[24:27]
	v_mfma_f32_16x16x32_bf16 v[16:19], v[194:197], v[178:181], v[16:19]
	v_mfma_f32_16x16x32_bf16 v[8:11], v[202:205], v[178:181], v[8:11]
	v_mfma_f32_16x16x32_bf16 v[4:7], v[194:197], v[186:189], v[4:7]
	v_mfma_f32_16x16x32_bf16 v[0:3], v[202:205], v[186:189], v[0:3]
	s_add_i32 s48, 0, 0x18000
	v_add_u32_e32 v132, s48, v137
	s_barrier
	ds_read_b128 v[142:145], v132
	ds_read_b128 v[146:149], v132 offset:1024
	ds_read_b128 v[150:153], v132 offset:2048
	ds_read_b128 v[154:157], v132 offset:3072
	s_mov_b32 m0, s30
	v_lshl_add_u64 v[190:191], v[208:209], 0, s[26:27]
	ds_read_b128 v[158:161], v139 offset:32768
	ds_read_b128 v[162:165], v139 offset:33792
	ds_read_b128 v[166:169], v139 offset:34816
	ds_read_b128 v[170:173], v139 offset:35840
	ds_read_b128 v[174:177], v139 offset:36864
	ds_read_b128 v[178:181], v139 offset:37888
	ds_read_b128 v[182:185], v139 offset:38912
	ds_read_b128 v[186:189], v139 offset:39936
	global_load_lds_dwordx4 v[190:191], off
	v_lshl_add_u64 v[190:191], v[208:209], 0, s[34:35]
	s_mov_b32 m0, s31
	s_nop 0
	global_load_lds_dwordx4 v[190:191], off
	s_waitcnt lgkmcnt(8)
	s_barrier
	s_waitcnt lgkmcnt(0)
	s_waitcnt lgkmcnt(0)
	v_mfma_f32_16x16x32_bf16 v[124:127], v[142:145], v[158:161], v[124:127]
	v_mfma_f32_16x16x32_bf16 v[120:123], v[150:153], v[158:161], v[120:123]
	v_mfma_f32_16x16x32_bf16 v[112:115], v[142:145], v[166:169], v[112:115]
	v_mfma_f32_16x16x32_bf16 v[104:107], v[150:153], v[166:169], v[104:107]
	v_mfma_f32_16x16x32_bf16 v[96:99], v[142:145], v[174:177], v[96:99]
	v_mfma_f32_16x16x32_bf16 v[88:91], v[150:153], v[174:177], v[88:91]
	v_mfma_f32_16x16x32_bf16 v[80:83], v[142:145], v[182:185], v[80:83]
	v_mfma_f32_16x16x32_bf16 v[72:75], v[150:153], v[182:185], v[72:75]
	v_mfma_f32_16x16x32_bf16 v[124:127], v[146:149], v[162:165], v[124:127]
	v_mfma_f32_16x16x32_bf16 v[120:123], v[154:157], v[162:165], v[120:123]
	v_mfma_f32_16x16x32_bf16 v[112:115], v[146:149], v[170:173], v[112:115]
	v_mfma_f32_16x16x32_bf16 v[104:107], v[154:157], v[170:173], v[104:107]
	v_mfma_f32_16x16x32_bf16 v[96:99], v[146:149], v[178:181], v[96:99]
	v_mfma_f32_16x16x32_bf16 v[88:91], v[154:157], v[178:181], v[88:91]
	v_mfma_f32_16x16x32_bf16 v[80:83], v[146:149], v[186:189], v[80:83]
	v_mfma_f32_16x16x32_bf16 v[72:75], v[154:157], v[186:189], v[72:75]
	s_barrier
	s_add_i32 s49, 0, 0x1c000
	s_add_i32 s48, s48, s21
	v_add_u32_e32 v132, s49, v137
	v_lshl_add_u64 v[210:211], v[206:207], 0, s[54:55]
	s_mov_b32 m0, s48
	ds_read_b128 v[190:193], v132
	ds_read_b128 v[194:197], v132 offset:1024
	ds_read_b128 v[198:201], v132 offset:2048
	ds_read_b128 v[202:205], v132 offset:3072
	global_load_lds_dwordx4 v[210:211], off
	v_lshl_add_u64 v[210:211], v[206:207], 0, s[56:57]
	s_add_i32 m0, s48, 0x2000
	s_nop 0
	global_load_lds_dwordx4 v[210:211], off
	s_barrier
	s_waitcnt lgkmcnt(0)
	s_waitcnt lgkmcnt(0)
	v_mfma_f32_16x16x32_bf16 v[116:119], v[190:193], v[158:161], v[116:119]
	v_mfma_f32_16x16x32_bf16 v[108:111], v[198:201], v[158:161], v[108:111]
	v_mfma_f32_16x16x32_bf16 v[100:103], v[190:193], v[166:169], v[100:103]
	v_mfma_f32_16x16x32_bf16 v[92:95], v[198:201], v[166:169], v[92:95]
	v_mfma_f32_16x16x32_bf16 v[84:87], v[190:193], v[174:177], v[84:87]
	v_mfma_f32_16x16x32_bf16 v[76:79], v[198:201], v[174:177], v[76:79]
	v_mfma_f32_16x16x32_bf16 v[68:71], v[190:193], v[182:185], v[68:71]
	v_mfma_f32_16x16x32_bf16 v[64:67], v[198:201], v[182:185], v[64:67]
	v_mfma_f32_16x16x32_bf16 v[116:119], v[194:197], v[162:165], v[116:119]
	v_mfma_f32_16x16x32_bf16 v[108:111], v[202:205], v[162:165], v[108:111]
	v_mfma_f32_16x16x32_bf16 v[100:103], v[194:197], v[170:173], v[100:103]
	v_mfma_f32_16x16x32_bf16 v[92:95], v[202:205], v[170:173], v[92:95]
	v_mfma_f32_16x16x32_bf16 v[84:87], v[194:197], v[178:181], v[84:87]
	v_mfma_f32_16x16x32_bf16 v[76:79], v[202:205], v[178:181], v[76:79]
	v_mfma_f32_16x16x32_bf16 v[68:71], v[194:197], v[186:189], v[68:71]
	v_mfma_f32_16x16x32_bf16 v[64:67], v[202:205], v[186:189], v[64:67]
	s_mov_b32 m0, s36
	v_lshl_add_u64 v[210:211], v[208:209], 0, s[54:55]
	s_barrier
	ds_read_b128 v[158:161], v139 offset:49152
	ds_read_b128 v[162:165], v139 offset:50176
	ds_read_b128 v[166:169], v139 offset:51200
	ds_read_b128 v[170:173], v139 offset:52224
	ds_read_b128 v[174:177], v139 offset:53248
	ds_read_b128 v[178:181], v139 offset:54272
	ds_read_b128 v[182:185], v139 offset:55296
	ds_read_b128 v[186:189], v139 offset:56320
	global_load_lds_dwordx4 v[210:211], off
	v_lshl_add_u64 v[208:209], v[208:209], 0, s[58:59]
	s_mov_b32 m0, s37
	s_nop 0
	global_load_lds_dwordx4 v[208:209], off
	s_barrier
	s_waitcnt lgkmcnt(0)
	s_waitcnt lgkmcnt(0)
	v_mfma_f32_16x16x32_bf16 v[60:63], v[142:145], v[158:161], v[60:63]
	v_mfma_f32_16x16x32_bf16 v[56:59], v[150:153], v[158:161], v[56:59]
	v_mfma_f32_16x16x32_bf16 v[52:55], v[142:145], v[166:169], v[52:55]
	v_mfma_f32_16x16x32_bf16 v[44:47], v[150:153], v[166:169], v[44:47]
	v_mfma_f32_16x16x32_bf16 v[36:39], v[142:145], v[174:177], v[36:39]
	v_mfma_f32_16x16x32_bf16 v[28:31], v[150:153], v[174:177], v[28:31]
	v_mfma_f32_16x16x32_bf16 v[20:23], v[142:145], v[182:185], v[20:23]
	v_mfma_f32_16x16x32_bf16 v[12:15], v[150:153], v[182:185], v[12:15]
	v_mfma_f32_16x16x32_bf16 v[60:63], v[146:149], v[162:165], v[60:63]
	v_mfma_f32_16x16x32_bf16 v[56:59], v[154:157], v[162:165], v[56:59]
	v_mfma_f32_16x16x32_bf16 v[52:55], v[146:149], v[170:173], v[52:55]
	v_mfma_f32_16x16x32_bf16 v[44:47], v[154:157], v[170:173], v[44:47]
	v_mfma_f32_16x16x32_bf16 v[36:39], v[146:149], v[178:181], v[36:39]
	v_mfma_f32_16x16x32_bf16 v[28:31], v[154:157], v[178:181], v[28:31]
	v_mfma_f32_16x16x32_bf16 v[20:23], v[146:149], v[186:189], v[20:23]
	v_mfma_f32_16x16x32_bf16 v[12:15], v[154:157], v[186:189], v[12:15]
	s_barrier
	s_add_i32 s48, s49, s21
	v_lshl_add_u64 v[142:143], v[206:207], 0, s[60:61]
	s_mov_b32 m0, s48
	s_nop 0
	global_load_lds_dwordx4 v[142:143], off
	v_lshl_add_u64 v[142:143], v[206:207], 0, s[62:63]
	s_add_i32 m0, s48, 0x2000
	s_nop 0
	global_load_lds_dwordx4 v[142:143], off
	s_waitcnt vmcnt(6)
	s_barrier
	v_mfma_f32_16x16x32_bf16 v[48:51], v[190:193], v[158:161], v[48:51]
	v_mfma_f32_16x16x32_bf16 v[40:43], v[198:201], v[158:161], v[40:43]
	v_mfma_f32_16x16x32_bf16 v[32:35], v[190:193], v[166:169], v[32:35]
	v_mfma_f32_16x16x32_bf16 v[24:27], v[198:201], v[166:169], v[24:27]
	v_mfma_f32_16x16x32_bf16 v[16:19], v[190:193], v[174:177], v[16:19]
	v_mfma_f32_16x16x32_bf16 v[8:11], v[198:201], v[174:177], v[8:11]
	v_mfma_f32_16x16x32_bf16 v[4:7], v[190:193], v[182:185], v[4:7]
	v_mfma_f32_16x16x32_bf16 v[0:3], v[198:201], v[182:185], v[0:3]
	v_mfma_f32_16x16x32_bf16 v[48:51], v[194:197], v[162:165], v[48:51]
	v_mfma_f32_16x16x32_bf16 v[40:43], v[202:205], v[162:165], v[40:43]
	v_mfma_f32_16x16x32_bf16 v[32:35], v[194:197], v[170:173], v[32:35]
	v_mfma_f32_16x16x32_bf16 v[24:27], v[202:205], v[170:173], v[24:27]
	v_mfma_f32_16x16x32_bf16 v[16:19], v[194:197], v[178:181], v[16:19]
	v_mfma_f32_16x16x32_bf16 v[8:11], v[202:205], v[178:181], v[8:11]
	v_mfma_f32_16x16x32_bf16 v[4:7], v[194:197], v[186:189], v[4:7]
	v_mfma_f32_16x16x32_bf16 v[0:3], v[202:205], v[186:189], v[0:3]
	s_add_i32 s47, s47, 2
	s_add_u32 s68, s68, 0x100
	s_addc_u32 s69, s69, 0
	s_add_u32 s45, s45, 0x100
	s_addc_u32 s46, s46, 0
	s_cmp_gt_u32 s47, 5
	s_barrier
	s_cbranch_scc0 .LBB0_375
	s_lshl_b32 s48, s44, 8
	s_ashr_i32 s49, s44, 31
	s_add_i32 s47, s44, 32
	s_and_b32 s48, s48, s49
	s_lshr_b32 s47, s47, 4
	s_and_b32 s48, s48, 0xf00
	s_cmp_lt_i32 s44, 0
	s_cselect_b32 s44, s47, s44
	s_movk_i32 s47, 0x200
	s_cselect_b32 s52, 0x2000, s47
	s_mov_b32 s47, 0x15eb3600
	s_cselect_b32 s47, s47, 0x16eb3600
	s_cselect_b32 s49, 13, 9
	s_add_u32 s47, s4, s47
	s_addc_u32 s50, s5, 0
	s_lshl_b32 s44, s44, 9
	s_lshl_b32 s43, s43, 7
	s_add_i32 s44, s44, s43
	s_lshl_b32 s43, s48, 1
	v_mov_b32_e32 v132, v136
	s_mov_b32 s45, s16
	s_mov_b32 s46, s33
	s_add_u32 s43, s47, s43
	s_addc_u32 s47, s50, 0
	v_and_or_b32 v141, v132, 15, s44
	s_lshl_b32 s44, s46, 5
	v_lshl_add_u32 v142, s45, 6, v141
	s_ashr_i32 s45, s44, 31
	s_lshl_b64 s[44:45], s[44:45], 1
	s_add_u32 s44, s43, s44
	v_ashrrev_i32_e32 v143, 31, v142
	s_addc_u32 s45, s47, s45
	v_and_b32_e32 v132, 48, v132
	v_lshlrev_b64 v[146:147], s49, v[142:143]
	v_lshl_add_u64 v[144:145], s[44:45], 0, v[132:133]
	v_lshlrev_b64 v[146:147], 1, v[146:147]
	v_lshl_add_u64 v[148:149], v[144:145], 0, v[146:147]
	v_cvt_pk_bf16_f32 v124, v124, v125
	v_cvt_pk_bf16_f32 v125, v126, v127
	v_cvt_pk_bf16_f32 v126, v120, v121
	v_cvt_pk_bf16_f32 v127, v122, v123
	global_store_dwordx4 v[148:149], v[124:127], off
	v_cvt_pk_bf16_f32 v116, v116, v117
	v_cvt_pk_bf16_f32 v117, v118, v119
	v_cvt_pk_bf16_f32 v118, v108, v109
	v_or_b32_e32 v108, 16, v142
	v_ashrrev_i32_e32 v109, 31, v108
	v_lshlrev_b64 v[108:109], s49, v[108:109]
	v_cvt_pk_bf16_f32 v119, v110, v111
	global_store_dwordx4 v[148:149], v[116:119], off offset:256
	s_mov_b32 s43, s42
	s_mov_b64 s[68:69], -1
	v_lshlrev_b64 v[116:117], 1, v[108:109]
	v_lshl_add_u64 v[118:119], v[144:145], 0, v[116:117]
	v_cvt_pk_bf16_f32 v108, v112, v113
	v_cvt_pk_bf16_f32 v109, v114, v115
	v_cvt_pk_bf16_f32 v110, v104, v105
	v_cvt_pk_bf16_f32 v111, v106, v107
	global_store_dwordx4 v[118:119], v[108:111], off
	v_cvt_pk_bf16_f32 v100, v100, v101
	v_cvt_pk_bf16_f32 v101, v102, v103
	v_cvt_pk_bf16_f32 v102, v92, v93
	v_or_b32_e32 v92, 32, v142
	v_ashrrev_i32_e32 v93, 31, v92
	v_lshlrev_b64 v[92:93], s49, v[92:93]
	v_cvt_pk_bf16_f32 v103, v94, v95
	global_store_dwordx4 v[118:119], v[100:103], off offset:256
	s_nop 1
	v_lshlrev_b64 v[100:101], 1, v[92:93]
	v_lshl_add_u64 v[102:103], v[144:145], 0, v[100:101]
	v_cvt_pk_bf16_f32 v92, v96, v97
	v_cvt_pk_bf16_f32 v93, v98, v99
	v_cvt_pk_bf16_f32 v94, v88, v89
	v_cvt_pk_bf16_f32 v95, v90, v91
	global_store_dwordx4 v[102:103], v[92:95], off
	v_cvt_pk_bf16_f32 v84, v84, v85
	v_cvt_pk_bf16_f32 v85, v86, v87
	v_cvt_pk_bf16_f32 v86, v76, v77
	v_or_b32_e32 v76, 48, v142
	v_ashrrev_i32_e32 v77, 31, v76
	v_lshlrev_b64 v[76:77], s49, v[76:77]
	v_cvt_pk_bf16_f32 v87, v78, v79
	global_store_dwordx4 v[102:103], v[84:87], off offset:256
	s_nop 1
	v_lshlrev_b64 v[84:85], 1, v[76:77]
	v_lshl_add_u64 v[86:87], v[144:145], 0, v[84:85]
	v_cvt_pk_bf16_f32 v76, v80, v81
	v_cvt_pk_bf16_f32 v77, v82, v83
	v_cvt_pk_bf16_f32 v78, v72, v73
	v_cvt_pk_bf16_f32 v79, v74, v75
	global_store_dwordx4 v[86:87], v[76:79], off
	v_cvt_pk_bf16_f32 v68, v68, v69
	v_cvt_pk_bf16_f32 v69, v70, v71
	v_cvt_pk_bf16_f32 v70, v64, v65
	v_lshl_add_u64 v[64:65], v[144:145], 0, s[52:53]
	v_cvt_pk_bf16_f32 v71, v66, v67
	v_lshl_add_u64 v[66:67], v[64:65], 0, v[146:147]
	global_store_dwordx4 v[86:87], v[68:71], off offset:256
	v_cvt_pk_bf16_f32 v60, v60, v61
	v_cvt_pk_bf16_f32 v61, v62, v63
	v_cvt_pk_bf16_f32 v62, v56, v57
	v_cvt_pk_bf16_f32 v63, v58, v59
	global_store_dwordx4 v[66:67], v[60:63], off
	v_cvt_pk_bf16_f32 v48, v48, v49
	v_cvt_pk_bf16_f32 v49, v50, v51
	v_cvt_pk_bf16_f32 v50, v40, v41
	v_cvt_pk_bf16_f32 v51, v42, v43
	global_store_dwordx4 v[66:67], v[48:51], off offset:256
	v_cvt_pk_bf16_f32 v40, v52, v53
	v_cvt_pk_bf16_f32 v41, v54, v55
	v_cvt_pk_bf16_f32 v42, v44, v45
	v_cvt_pk_bf16_f32 v43, v46, v47
	s_nop 1
	v_lshl_add_u64 v[48:49], v[64:65], 0, v[116:117]
	global_store_dwordx4 v[48:49], v[40:43], off
	v_cvt_pk_bf16_f32 v32, v32, v33
	v_cvt_pk_bf16_f32 v33, v34, v35
	v_cvt_pk_bf16_f32 v34, v24, v25
	v_cvt_pk_bf16_f32 v35, v26, v27
	global_store_dwordx4 v[48:49], v[32:35], off offset:256
	v_cvt_pk_bf16_f32 v24, v36, v37
	v_cvt_pk_bf16_f32 v25, v38, v39
	v_cvt_pk_bf16_f32 v26, v28, v29
	v_cvt_pk_bf16_f32 v27, v30, v31
	s_nop 1
	v_lshl_add_u64 v[32:33], v[64:65], 0, v[100:101]
	global_store_dwordx4 v[32:33], v[24:27], off
	v_cvt_pk_bf16_f32 v16, v16, v17
	v_cvt_pk_bf16_f32 v17, v18, v19
	v_cvt_pk_bf16_f32 v18, v8, v9
	v_cvt_pk_bf16_f32 v19, v10, v11
	global_store_dwordx4 v[32:33], v[16:19], off offset:256
	v_cvt_pk_bf16_f32 v8, v20, v21
	v_cvt_pk_bf16_f32 v9, v22, v23
	v_cvt_pk_bf16_f32 v10, v12, v13
	v_cvt_pk_bf16_f32 v11, v14, v15
	s_nop 1
	v_lshl_add_u64 v[16:17], v[64:65], 0, v[84:85]
	global_store_dwordx4 v[16:17], v[8:11], off
	v_cvt_pk_bf16_f32 v4, v4, v5
	v_cvt_pk_bf16_f32 v5, v6, v7
	v_cvt_pk_bf16_f32 v6, v0, v1
	v_cvt_pk_bf16_f32 v7, v2, v3
	global_store_dwordx4 v[16:17], v[4:7], off offset:256
	s_mul_i32 s45, s43, s13
	s_add_i32 s45, s45, s0
	s_cmp_gt_i32 s45, 7
	s_cbranch_scc1 .LBB0_371
	s_ashr_i32 s43, s45, 31
	s_lshr_b32 s43, s43, 29
	s_add_i32 s43, s45, s43
	s_ashr_i32 s44, s43, 3
	s_and_b32 s43, s43, -8
	s_sub_i32 s43, s45, s43
	s_lshr_b32 s45, s43, 31
	s_lshl_b32 s43, s43, s45
	s_add_i32 s43, s43, s44
	s_ashr_i32 s44, s43, 31
	s_lshr_b32 s44, s44, 28
	s_add_i32 s44, s43, s44
	s_ashr_i32 s45, s44, 4
	s_lshl_b32 s46, s45, 3
	s_sub_i32 s45, 4, s46
	s_min_u32 s47, s45, 8
	s_and_b32 s44, s44, -16
	s_sub_i32 s43, s43, s44
	v_cvt_f32_ubyte0_e32 v1, s47
	v_cvt_f32_i32_e32 v0, s43
	v_rcp_iflag_f32_e32 v2, v1
	s_ashr_i32 s44, s43, 30
	s_or_b32 s48, s44, 1
	s_mov_b64 s[68:69], 0
	v_mul_f32_e32 v2, v0, v2
	v_trunc_f32_e32 v2, v2
	v_fma_f32 v0, -v2, v1, v0
	v_cvt_i32_f32_e32 v2, v2
	v_cmp_ge_f32_e64 s[44:45], |v0|, v1
	s_and_b64 s[44:45], s[44:45], exec
	s_cselect_b32 s44, s48, 0
	v_readfirstlane_b32 s45, v2
	s_add_i32 s45, s45, s44
	s_sext_i32_i8 s44, s45
	s_mul_i32 s45, s45, s47
	s_sub_i32 s43, s43, s45
	s_sext_i32_i8 s43, s43
	s_add_i32 s43, s46, s43
	s_branch .LBB0_371

.LBB0_424:
	s_add_u32 s44, s2, s56
	ds_read_b128 v[0:3], v175
	ds_read_b128 v[4:7], v175 offset:1024
	ds_read_b128 v[8:11], v175 offset:2048
	ds_read_b128 v[12:15], v175 offset:3072
	s_addc_u32 s45, s3, s57
	s_and_b64 s[42:43], s[60:61], exec
	s_cselect_b32 s57, s45, s59
	s_cselect_b32 s56, s44, s58
	s_add_u32 s44, s1, s62
	s_addc_u32 s45, s14, s63
	s_and_b64 s[42:43], s[60:61], exec
	s_cselect_b32 s5, s45, s5
	s_cselect_b32 s4, s44, s4
	v_lshl_add_u64 v[48:49], s[58:59], 0, v[166:167]
	s_mov_b64 s[42:43], 0x8080
	s_mov_b32 m0, s37
	v_lshl_add_u64 v[50:51], v[48:49], 0, s[42:43]
	s_mov_b64 s[42:43], 0xc080
	ds_read_b128 v[16:19], v177
	ds_read_b128 v[20:23], v177 offset:1024
	ds_read_b128 v[24:27], v177 offset:2048
	ds_read_b128 v[28:31], v177 offset:3072
	ds_read_b128 v[32:35], v177 offset:4096
	ds_read_b128 v[36:39], v177 offset:5120
	ds_read_b128 v[40:43], v177 offset:6144
	ds_read_b128 v[44:47], v177 offset:7168
	global_load_lds_dwordx4 v[50:51], off
	v_lshl_add_u64 v[48:49], v[48:49], 0, s[42:43]
	s_mov_b32 m0, s38
	s_nop 0
	global_load_lds_dwordx4 v[48:49], off
	s_waitcnt lgkmcnt(8)
	s_barrier
	s_waitcnt lgkmcnt(0)
	s_waitcnt lgkmcnt(0)
	v_mfma_f32_16x16x32_bf16 v[72:75], v[0:3], v[40:43], 0
	v_mfma_f32_16x16x32_bf16 v[48:51], v[0:3], v[16:19], 0
	v_mfma_f32_16x16x32_bf16 v[52:55], v[8:11], v[16:19], 0
	v_mfma_f32_16x16x32_bf16 v[56:59], v[0:3], v[24:27], 0
	v_mfma_f32_16x16x32_bf16 v[60:63], v[8:11], v[24:27], 0
	v_mfma_f32_16x16x32_bf16 v[64:67], v[0:3], v[32:35], 0
	v_mfma_f32_16x16x32_bf16 v[68:71], v[8:11], v[32:35], 0
	v_mfma_f32_16x16x32_bf16 v[76:79], v[4:7], v[44:47], v[72:75]
	v_mfma_f32_16x16x32_bf16 v[72:75], v[8:11], v[40:43], 0
	v_mfma_f32_16x16x32_bf16 v[48:51], v[4:7], v[20:23], v[48:51]
	v_mfma_f32_16x16x32_bf16 v[52:55], v[12:15], v[20:23], v[52:55]
	v_mfma_f32_16x16x32_bf16 v[56:59], v[4:7], v[28:31], v[56:59]
	v_mfma_f32_16x16x32_bf16 v[60:63], v[12:15], v[28:31], v[60:63]
	v_mfma_f32_16x16x32_bf16 v[64:67], v[4:7], v[36:39], v[64:67]
	v_mfma_f32_16x16x32_bf16 v[68:71], v[12:15], v[36:39], v[68:71]
	v_mfma_f32_16x16x32_bf16 v[84:87], v[12:15], v[44:47], v[72:75]
	s_barrier
	s_mov_b32 m0, s40
	v_lshl_add_u64 v[240:241], s[4:5], 0, v[164:165]
	ds_read_b128 v[72:75], v178
	ds_read_b128 v[80:83], v178 offset:1024
	ds_read_b128 v[88:91], v178 offset:2048
	ds_read_b128 v[92:95], v178 offset:3072
	global_load_lds_dwordx4 v[240:241], off
	v_lshl_add_u64 v[96:97], v[240:241], 0, s[6:7]
	s_add_i32 m0, s40, 0x2000
	s_nop 0
	global_load_lds_dwordx4 v[96:97], off
	s_barrier
	s_waitcnt lgkmcnt(0)
	s_waitcnt lgkmcnt(0)
	v_mfma_f32_16x16x32_bf16 v[96:99], v[72:75], v[16:19], 0
	v_mfma_f32_16x16x32_bf16 v[16:19], v[88:91], v[16:19], 0
	v_mfma_f32_16x16x32_bf16 v[96:99], v[80:83], v[20:23], v[96:99]
	v_mfma_f32_16x16x32_bf16 v[20:23], v[92:95], v[20:23], v[16:19]
	v_mfma_f32_16x16x32_bf16 v[16:19], v[72:75], v[24:27], 0
	v_mfma_f32_16x16x32_bf16 v[100:103], v[80:83], v[28:31], v[16:19]
	v_mfma_f32_16x16x32_bf16 v[16:19], v[88:91], v[24:27], 0
	v_mfma_f32_16x16x32_bf16 v[24:27], v[92:95], v[28:31], v[16:19]
	v_mfma_f32_16x16x32_bf16 v[16:19], v[72:75], v[32:35], 0
	v_mfma_f32_16x16x32_bf16 v[28:31], v[80:83], v[36:39], v[16:19]
	v_mfma_f32_16x16x32_bf16 v[16:19], v[88:91], v[32:35], 0
	v_mfma_f32_16x16x32_bf16 v[32:35], v[92:95], v[36:39], v[16:19]
	v_mfma_f32_16x16x32_bf16 v[16:19], v[72:75], v[40:43], 0
	v_mfma_f32_16x16x32_bf16 v[104:107], v[80:83], v[44:47], v[16:19]
	v_mfma_f32_16x16x32_bf16 v[16:19], v[88:91], v[40:43], 0
	v_mfma_f32_16x16x32_bf16 v[44:47], v[92:95], v[44:47], v[16:19]
	s_mov_b32 m0, s17
	v_lshl_add_u64 v[242:243], s[56:57], 0, v[166:167]
	s_barrier
	s_nop 2
	ds_read_b128 v[16:19], v177 offset:16384
	ds_read_b128 v[36:39], v177 offset:17408
	ds_read_b128 v[40:43], v177 offset:18432
	ds_read_b128 v[108:111], v177 offset:19456
	ds_read_b128 v[112:115], v177 offset:20480
	ds_read_b128 v[116:119], v177 offset:21504
	ds_read_b128 v[120:123], v177 offset:22528
	ds_read_b128 v[124:127], v177 offset:23552
	global_load_lds_dwordx4 v[242:243], off
	v_lshl_add_u64 v[128:129], v[242:243], 0, s[6:7]
	s_mov_b32 m0, s20
	s_nop 0
	global_load_lds_dwordx4 v[128:129], off
	s_barrier
	s_waitcnt lgkmcnt(0)
	s_waitcnt lgkmcnt(0)
	v_mfma_f32_16x16x32_bf16 v[128:131], v[0:3], v[16:19], 0
	v_mfma_f32_16x16x32_bf16 v[136:139], v[0:3], v[40:43], 0
	v_mfma_f32_16x16x32_bf16 v[144:147], v[0:3], v[112:115], 0
	v_mfma_f32_16x16x32_bf16 v[0:3], v[0:3], v[120:123], 0
	v_mfma_f32_16x16x32_bf16 v[132:135], v[8:11], v[16:19], 0
	v_mfma_f32_16x16x32_bf16 v[140:143], v[8:11], v[40:43], 0
	v_mfma_f32_16x16x32_bf16 v[148:151], v[4:7], v[116:119], v[144:147]
	v_mfma_f32_16x16x32_bf16 v[144:147], v[8:11], v[112:115], 0
	v_mfma_f32_16x16x32_bf16 v[170:173], v[4:7], v[124:127], v[0:3]
	v_mfma_f32_16x16x32_bf16 v[0:3], v[8:11], v[120:123], 0
	v_mfma_f32_16x16x32_bf16 v[128:131], v[4:7], v[36:39], v[128:131]
	v_mfma_f32_16x16x32_bf16 v[132:135], v[12:15], v[36:39], v[132:135]
	v_mfma_f32_16x16x32_bf16 v[140:143], v[12:15], v[108:111], v[140:143]
	v_mfma_f32_16x16x32_bf16 v[156:159], v[12:15], v[116:119], v[144:147]
	v_mfma_f32_16x16x32_bf16 v[12:15], v[12:15], v[124:127], v[0:3]
	v_mfma_f32_16x16x32_bf16 v[136:139], v[4:7], v[108:111], v[136:139]
	s_barrier
	s_add_i32 s42, s39, s16
	v_lshl_add_u64 v[0:1], v[240:241], 0, s[8:9]
	s_mov_b32 m0, s42
	s_nop 0
	global_load_lds_dwordx4 v[0:1], off
	v_lshl_add_u64 v[0:1], v[240:241], 0, s[18:19]
	s_add_i32 m0, s42, 0x2000
	s_nop 0
	global_load_lds_dwordx4 v[0:1], off
	s_waitcnt vmcnt(6)
	s_barrier
	v_mfma_f32_16x16x32_bf16 v[0:3], v[72:75], v[16:19], 0
	v_mfma_f32_16x16x32_bf16 v[180:183], v[80:83], v[36:39], v[0:3]
	v_mfma_f32_16x16x32_bf16 v[0:3], v[88:91], v[16:19], 0
	v_mfma_f32_16x16x32_bf16 v[184:187], v[92:95], v[36:39], v[0:3]
	v_mfma_f32_16x16x32_bf16 v[0:3], v[72:75], v[40:43], 0
	v_mfma_f32_16x16x32_bf16 v[188:191], v[80:83], v[108:111], v[0:3]
	v_mfma_f32_16x16x32_bf16 v[0:3], v[88:91], v[40:43], 0
	v_mfma_f32_16x16x32_bf16 v[108:111], v[92:95], v[108:111], v[0:3]
	v_mfma_f32_16x16x32_bf16 v[0:3], v[72:75], v[112:115], 0
	v_mfma_f32_16x16x32_bf16 v[192:195], v[80:83], v[116:119], v[0:3]
	v_mfma_f32_16x16x32_bf16 v[0:3], v[88:91], v[112:115], 0
	v_mfma_f32_16x16x32_bf16 v[196:199], v[92:95], v[116:119], v[0:3]
	v_mfma_f32_16x16x32_bf16 v[0:3], v[72:75], v[120:123], 0
	v_mfma_f32_16x16x32_bf16 v[200:203], v[80:83], v[124:127], v[0:3]
	v_mfma_f32_16x16x32_bf16 v[0:3], v[88:91], v[120:123], 0
	v_mfma_f32_16x16x32_bf16 v[92:95], v[92:95], v[124:127], v[0:3]
	s_add_i32 s42, 0, 0x18000
	s_nop 4
	v_add_u32_e32 v0, s42, v174
	s_barrier
	ds_read_b128 v[120:123], v0
	ds_read_b128 v[204:207], v0 offset:1024
	ds_read_b128 v[208:211], v0 offset:2048
	ds_read_b128 v[212:215], v0 offset:3072
	s_mov_b32 m0, s21
	v_lshl_add_u64 v[8:9], v[242:243], 0, s[8:9]
	ds_read_b128 v[0:3], v177 offset:32768
	ds_read_b128 v[4:7], v177 offset:33792
	ds_read_b128 v[36:39], v177 offset:34816
	ds_read_b128 v[88:91], v177 offset:35840
	ds_read_b128 v[144:147], v177 offset:36864
	ds_read_b128 v[160:163], v177 offset:37888
	ds_read_b128 v[216:219], v177 offset:38912
	ds_read_b128 v[220:223], v177 offset:39936
	global_load_lds_dwordx4 v[8:9], off
	v_lshl_add_u64 v[8:9], v[242:243], 0, s[18:19]
	s_mov_b32 m0, s28
	s_nop 0
	global_load_lds_dwordx4 v[8:9], off
	s_waitcnt lgkmcnt(8)
	s_barrier
	s_waitcnt lgkmcnt(0)
	s_waitcnt lgkmcnt(0)
	v_mfma_f32_16x16x32_bf16 v[8:11], v[120:123], v[0:3], v[48:51]
	v_mfma_f32_16x16x32_bf16 v[152:155], v[204:207], v[4:7], v[8:11]
	v_mfma_f32_16x16x32_bf16 v[8:11], v[208:211], v[0:3], v[52:55]
	v_mfma_f32_16x16x32_bf16 v[124:127], v[212:215], v[4:7], v[8:11]
	v_mfma_f32_16x16x32_bf16 v[8:11], v[120:123], v[36:39], v[56:59]
	v_mfma_f32_16x16x32_bf16 v[80:83], v[204:207], v[88:91], v[8:11]
	v_mfma_f32_16x16x32_bf16 v[8:11], v[208:211], v[36:39], v[60:63]
	v_mfma_f32_16x16x32_bf16 v[72:75], v[212:215], v[88:91], v[8:11]
	v_mfma_f32_16x16x32_bf16 v[8:11], v[120:123], v[144:147], v[64:67]
	v_mfma_f32_16x16x32_bf16 v[48:51], v[204:207], v[160:163], v[8:11]
	v_mfma_f32_16x16x32_bf16 v[8:11], v[208:211], v[144:147], v[68:71]
	v_mfma_f32_16x16x32_bf16 v[40:43], v[212:215], v[160:163], v[8:11]
	v_mfma_f32_16x16x32_bf16 v[8:11], v[120:123], v[216:219], v[76:79]
	v_mfma_f32_16x16x32_bf16 v[16:19], v[204:207], v[220:223], v[8:11]
	v_mfma_f32_16x16x32_bf16 v[8:11], v[208:211], v[216:219], v[84:87]
	v_mfma_f32_16x16x32_bf16 v[8:11], v[212:215], v[220:223], v[8:11]
	s_barrier
	s_add_i32 s44, 0, 0x1c000
	v_add_u32_e32 v52, s44, v174
	s_add_i32 s42, s42, s16
	ds_read_b128 v[224:227], v52
	ds_read_b128 v[228:231], v52 offset:1024
	ds_read_b128 v[232:235], v52 offset:2048
	ds_read_b128 v[236:239], v52 offset:3072
	v_lshl_add_u64 v[52:53], v[240:241], 0, s[26:27]
	s_mov_b32 m0, s42
	s_nop 0
	global_load_lds_dwordx4 v[52:53], off
	v_lshl_add_u64 v[52:53], v[240:241], 0, s[34:35]
	s_add_i32 m0, s42, 0x2000
	s_nop 0
	global_load_lds_dwordx4 v[52:53], off
	s_barrier
	s_waitcnt lgkmcnt(0)
	s_waitcnt lgkmcnt(0)
	v_mfma_f32_16x16x32_bf16 v[52:55], v[224:227], v[0:3], v[96:99]
	v_mfma_f32_16x16x32_bf16 v[0:3], v[232:235], v[0:3], v[20:23]
	v_mfma_f32_16x16x32_bf16 v[112:115], v[236:239], v[4:7], v[0:3]
	v_mfma_f32_16x16x32_bf16 v[0:3], v[224:227], v[36:39], v[100:103]
	v_mfma_f32_16x16x32_bf16 v[68:71], v[228:231], v[88:91], v[0:3]
	v_mfma_f32_16x16x32_bf16 v[0:3], v[232:235], v[36:39], v[24:27]
	v_mfma_f32_16x16x32_bf16 v[64:67], v[236:239], v[88:91], v[0:3]
	v_mfma_f32_16x16x32_bf16 v[0:3], v[224:227], v[144:147], v[28:31]
	v_mfma_f32_16x16x32_bf16 v[36:39], v[228:231], v[160:163], v[0:3]
	v_mfma_f32_16x16x32_bf16 v[0:3], v[232:235], v[144:147], v[32:35]
	v_mfma_f32_16x16x32_bf16 v[32:35], v[236:239], v[160:163], v[0:3]
	v_mfma_f32_16x16x32_bf16 v[0:3], v[224:227], v[216:219], v[104:107]
	v_mfma_f32_16x16x32_bf16 v[116:119], v[228:231], v[4:7], v[52:55]
	v_mfma_f32_16x16x32_bf16 v[4:7], v[228:231], v[220:223], v[0:3]
	v_mfma_f32_16x16x32_bf16 v[0:3], v[232:235], v[216:219], v[44:47]
	v_mfma_f32_16x16x32_bf16 v[0:3], v[236:239], v[220:223], v[0:3]
	s_mov_b64 s[42:43], 0x80
	s_mov_b32 m0, s31
	v_lshl_add_u64 v[24:25], v[242:243], 0, s[42:43]
	s_mov_b64 s[42:43], 0x4080
	s_barrier
	ds_read_b128 v[20:23], v177 offset:49152
	ds_read_b128 v[44:47], v177 offset:50176
	ds_read_b128 v[52:55], v177 offset:51200
	ds_read_b128 v[76:79], v177 offset:52224
	ds_read_b128 v[96:99], v177 offset:53248
	ds_read_b128 v[104:107], v177 offset:54272
	ds_read_b128 v[216:219], v177 offset:55296
	ds_read_b128 v[220:223], v177 offset:56320
	global_load_lds_dwordx4 v[24:25], off
	v_lshl_add_u64 v[24:25], v[242:243], 0, s[42:43]
	s_mov_b32 m0, s33
	s_nop 0
	global_load_lds_dwordx4 v[24:25], off
	s_barrier
	s_waitcnt lgkmcnt(0)
	s_waitcnt lgkmcnt(0)
	v_mfma_f32_16x16x32_bf16 v[24:27], v[120:123], v[20:23], v[128:131]
	v_mfma_f32_16x16x32_bf16 v[160:163], v[204:207], v[44:47], v[24:27]
	v_mfma_f32_16x16x32_bf16 v[24:27], v[208:211], v[20:23], v[132:135]
	v_mfma_f32_16x16x32_bf16 v[144:147], v[212:215], v[44:47], v[24:27]
	v_mfma_f32_16x16x32_bf16 v[24:27], v[120:123], v[52:55], v[136:139]
	v_mfma_f32_16x16x32_bf16 v[100:103], v[204:207], v[76:79], v[24:27]
	v_mfma_f32_16x16x32_bf16 v[24:27], v[208:211], v[52:55], v[140:143]
	v_mfma_f32_16x16x32_bf16 v[88:91], v[212:215], v[76:79], v[24:27]
	v_mfma_f32_16x16x32_bf16 v[24:27], v[120:123], v[96:99], v[148:151]
	v_mfma_f32_16x16x32_bf16 v[60:63], v[204:207], v[104:107], v[24:27]
	v_mfma_f32_16x16x32_bf16 v[24:27], v[208:211], v[96:99], v[156:159]
	v_mfma_f32_16x16x32_bf16 v[56:59], v[212:215], v[104:107], v[24:27]
	v_mfma_f32_16x16x32_bf16 v[24:27], v[120:123], v[216:219], v[170:173]
	v_mfma_f32_16x16x32_bf16 v[12:15], v[208:211], v[216:219], v[12:15]
	v_mfma_f32_16x16x32_bf16 v[28:31], v[204:207], v[220:223], v[24:27]
	v_mfma_f32_16x16x32_bf16 v[24:27], v[212:215], v[220:223], v[12:15]
	s_barrier
	s_add_i32 s42, s44, s16
	s_nop 2
	v_lshl_add_u64 v[12:13], v[240:241], 0, s[52:53]
	s_mov_b32 m0, s42
	s_nop 0
	global_load_lds_dwordx4 v[12:13], off
	v_lshl_add_u64 v[12:13], v[240:241], 0, s[54:55]
	s_add_i32 m0, s42, 0x2000
	s_nop 0
	global_load_lds_dwordx4 v[12:13], off
	s_waitcnt vmcnt(6)
	s_barrier
	v_mfma_f32_16x16x32_bf16 v[12:15], v[224:227], v[20:23], v[180:183]
	v_mfma_f32_16x16x32_bf16 v[128:131], v[228:231], v[44:47], v[12:15]
	v_mfma_f32_16x16x32_bf16 v[12:15], v[232:235], v[20:23], v[184:187]
	v_mfma_f32_16x16x32_bf16 v[120:123], v[236:239], v[44:47], v[12:15]
	v_mfma_f32_16x16x32_bf16 v[12:15], v[224:227], v[52:55], v[188:191]
	v_mfma_f32_16x16x32_bf16 v[84:87], v[228:231], v[76:79], v[12:15]
	v_mfma_f32_16x16x32_bf16 v[12:15], v[232:235], v[52:55], v[108:111]
	v_mfma_f32_16x16x32_bf16 v[76:79], v[236:239], v[76:79], v[12:15]
	v_mfma_f32_16x16x32_bf16 v[12:15], v[224:227], v[96:99], v[192:195]
	v_mfma_f32_16x16x32_bf16 v[52:55], v[228:231], v[104:107], v[12:15]
	v_mfma_f32_16x16x32_bf16 v[12:15], v[232:235], v[96:99], v[196:199]
	v_mfma_f32_16x16x32_bf16 v[44:47], v[236:239], v[104:107], v[12:15]
	v_mfma_f32_16x16x32_bf16 v[12:15], v[224:227], v[216:219], v[200:203]
	v_mfma_f32_16x16x32_bf16 v[20:23], v[228:231], v[220:223], v[12:15]
	v_mfma_f32_16x16x32_bf16 v[12:15], v[232:235], v[216:219], v[92:95]
	v_mfma_f32_16x16x32_bf16 v[12:15], v[236:239], v[220:223], v[12:15]
	s_nop 0
	v_mov_b32_e32 v92, v176
	s_mov_b32 s43, s15
	s_mov_b32 s42, s30
	s_barrier
	s_cmp_lg_u32 s43, 0
	s_cbranch_scc1 .LBB0_426
	v_and_b32_e32 v93, 15, v92
	s_lshl_b32 s43, s42, 6
	v_and_b32_e32 v92, 48, v92
	v_and_or_b32 v170, s43, 64, v92
	v_lshlrev_b32_e32 v92, 2, v170
	v_lshl_or_b32 v168, v93, 9, v92
	global_load_dwordx4 v[132:135], v168, s[24:25] offset:48
	global_load_dwordx4 v[136:139], v168, s[24:25] offset:32
	global_load_dwordx4 v[140:143], v168, s[24:25] offset:16
	global_load_dwordx4 v[148:151], v168, s[24:25]
	s_lshl_b32 s41, s41, 8
	s_lshl_b32 s42, s42, 5
	s_add_i32 s42, s42, s41
	v_lshl_add_u64 v[172:173], s[24:25], 0, v[168:169]
	s_movk_i32 s41, 0x2000
	v_add_co_u32_e32 v92, vcc, s41, v172
	v_lshlrev_b32_e32 v179, 10, v93
	v_lshl_add_u64 v[104:105], v[172:173], 0, s[26:27]
	v_addc_co_u32_e32 v93, vcc, 0, v173, vcc
	global_load_dwordx4 v[108:111], v[92:93], off
	s_nop 0
	global_load_dwordx4 v[92:95], v[104:105], off offset:48
	global_load_dwordx4 v[96:99], v[104:105], off offset:32
	s_nop 0
	global_load_dwordx4 v[104:107], v[104:105], off offset:16
	v_mov_b32_e32 v156, v152
	v_mov_b32_e32 v157, v160
	v_mov_b32_e32 v159, v162
	v_mov_b32_e32 v180, v126
	v_mov_b32_e32 v181, v146
	s_ashr_i32 s41, s42, 6
	v_mov_b32_e32 v171, v169
	s_addk_i32 s42, 0x80
	s_ashr_i32 s42, s42, 6
	s_movk_i32 s43, 0x4000
	s_waitcnt vmcnt(0)
	v_pk_mul_f32 v[180:181], v[180:181], v[132:133]
	v_pk_mul_f32 v[156:157], v[156:157], v[148:149]
	s_nop 0
	v_add_f32_e32 v158, v156, v157
	v_mov_b32_e32 v156, v153
	v_mov_b32_e32 v157, v161
	v_pk_mul_f32 v[156:157], v[156:157], v[150:151]
	s_nop 0
	v_add_f32_e32 v156, v156, v157
	v_cvt_pk_bf16_f32 v156, v158, v156
	v_mov_b32_e32 v158, v154
	v_pk_mul_f32 v[158:159], v[158:159], v[140:141]
	s_nop 0
	v_add_f32_e32 v157, v158, v159
	v_mov_b32_e32 v158, v155
	v_mov_b32_e32 v159, v163
	v_pk_mul_f32 v[158:159], v[158:159], v[142:143]
	s_nop 0
	v_add_f32_e32 v158, v158, v159
	v_cvt_pk_bf16_f32 v157, v157, v158
	v_mov_b32_e32 v158, v124
	v_mov_b32_e32 v159, v144
	v_pk_mul_f32 v[158:159], v[158:159], v[136:137]
	s_nop 0
	v_add_f32_e32 v168, v158, v159
	v_mov_b32_e32 v158, v125
	v_mov_b32_e32 v159, v145
	v_pk_mul_f32 v[158:159], v[158:159], v[138:139]
	s_nop 0
	v_add_f32_e32 v158, v158, v159
	v_add_f32_e32 v159, v180, v181
	v_mov_b32_e32 v180, v127
	v_mov_b32_e32 v181, v147
	v_pk_mul_f32 v[180:181], v[180:181], v[134:135]
	v_cvt_pk_bf16_f32 v158, v168, v158
	s_nop 0
	v_add_f32_e32 v168, v180, v181
	v_mov_b32_e32 v180, v160
	v_mov_b32_e32 v181, v152
	v_mov_b32_e32 v152, v161
	v_pk_mul_f32 v[180:181], v[180:181], v[148:149]
	v_pk_mul_f32 v[152:153], v[152:153], v[150:151]
	v_sub_f32_e32 v160, v180, v181
	v_sub_f32_e32 v152, v152, v153
	v_cvt_pk_bf16_f32 v159, v159, v168
	v_cvt_pk_bf16_f32 v152, v160, v152
	v_mov_b32_e32 v160, v162
	v_mov_b32_e32 v161, v154
	v_mov_b32_e32 v154, v163
	v_pk_mul_f32 v[160:161], v[160:161], v[140:141]
	v_pk_mul_f32 v[154:155], v[154:155], v[142:143]
	v_sub_f32_e32 v153, v160, v161
	v_sub_f32_e32 v154, v154, v155
	v_mov_b32_e32 v155, v124
	v_mov_b32_e32 v124, v145
	v_cvt_pk_bf16_f32 v153, v153, v154
	v_mov_b32_e32 v154, v144
	v_pk_mul_f32 v[124:125], v[124:125], v[138:139]
	v_pk_mul_f32 v[154:155], v[154:155], v[136:137]
	v_sub_f32_e32 v124, v124, v125
	v_sub_f32_e32 v144, v154, v155
	v_cvt_pk_bf16_f32 v154, v144, v124
	v_mov_b32_e32 v124, v146
	v_mov_b32_e32 v125, v126
	v_pk_mul_f32 v[124:125], v[124:125], v[132:133]
	v_mov_b32_e32 v126, v147
	v_sub_f32_e32 v144, v124, v125
	v_pk_mul_f32 v[124:125], v[126:127], v[134:135]
	v_mov_b32_e32 v127, v130
	v_sub_f32_e32 v124, v124, v125
	v_cvt_pk_bf16_f32 v155, v144, v124
	v_add_u32_e32 v124, s41, v179
	v_ashrrev_i32_e32 v125, 31, v124
	v_lshlrev_b64 v[124:125], 8, v[124:125]
	v_lshl_add_u64 v[124:125], s[22:23], 0, v[124:125]
	v_lshl_add_u64 v[124:125], v[124:125], 0, v[170:171]
	global_store_dwordx4 v[124:125], v[156:159], off
	global_store_dwordx4 v[124:125], v[152:155], off offset:128
	v_mov_b32_e32 v124, v116
	v_mov_b32_e32 v125, v128
	v_pk_mul_f32 v[124:125], v[124:125], v[148:149]
	v_mov_b32_e32 v145, v122
	v_add_f32_e32 v126, v124, v125
	v_mov_b32_e32 v124, v117
	v_mov_b32_e32 v125, v129
	v_pk_mul_f32 v[124:125], v[124:125], v[150:151]
	s_nop 0
	v_add_f32_e32 v124, v124, v125
	v_cvt_pk_bf16_f32 v124, v126, v124
	v_mov_b32_e32 v126, v118
	v_pk_mul_f32 v[126:127], v[126:127], v[140:141]
	s_nop 0
	v_add_f32_e32 v125, v126, v127
	v_mov_b32_e32 v126, v119
	v_mov_b32_e32 v127, v131
	v_pk_mul_f32 v[126:127], v[126:127], v[142:143]
	s_nop 0
	v_add_f32_e32 v126, v126, v127
	v_cvt_pk_bf16_f32 v125, v125, v126
	v_mov_b32_e32 v126, v112
	v_mov_b32_e32 v127, v120
	v_pk_mul_f32 v[126:127], v[126:127], v[136:137]
	s_nop 0
	v_add_f32_e32 v144, v126, v127
	v_mov_b32_e32 v126, v113
	v_mov_b32_e32 v127, v121
	v_pk_mul_f32 v[126:127], v[126:127], v[138:139]
	s_nop 0
	v_add_f32_e32 v126, v126, v127
	v_cvt_pk_bf16_f32 v126, v144, v126
	v_mov_b32_e32 v144, v114
	v_pk_mul_f32 v[144:145], v[144:145], v[132:133]
	s_nop 0
	v_add_f32_e32 v127, v144, v145
	v_mov_b32_e32 v144, v115
	v_mov_b32_e32 v145, v123
	v_pk_mul_f32 v[144:145], v[144:145], v[134:135]
	s_nop 0
	v_add_f32_e32 v144, v144, v145
	v_cvt_pk_bf16_f32 v127, v127, v144
	v_mov_b32_e32 v144, v128
	v_mov_b32_e32 v145, v116
	v_mov_b32_e32 v116, v129
	v_pk_mul_f32 v[144:145], v[144:145], v[148:149]
	v_pk_mul_f32 v[116:117], v[116:117], v[150:151]
	v_sub_f32_e32 v128, v144, v145
	v_sub_f32_e32 v116, v116, v117
	v_cvt_pk_bf16_f32 v116, v128, v116
	v_mov_b32_e32 v128, v130
	v_mov_b32_e32 v129, v118
	v_mov_b32_e32 v118, v131
	v_pk_mul_f32 v[128:129], v[128:129], v[140:141]
	v_pk_mul_f32 v[118:119], v[118:119], v[142:143]
	v_sub_f32_e32 v117, v128, v129
	v_sub_f32_e32 v118, v118, v119
	v_cvt_pk_bf16_f32 v117, v117, v118
	v_mov_b32_e32 v118, v120
	v_mov_b32_e32 v119, v112
	v_mov_b32_e32 v112, v121
	v_pk_mul_f32 v[118:119], v[118:119], v[136:137]
	v_pk_mul_f32 v[112:113], v[112:113], v[138:139]
	v_sub_f32_e32 v118, v118, v119
	v_sub_f32_e32 v112, v112, v113
	v_cvt_pk_bf16_f32 v118, v118, v112
	v_mov_b32_e32 v112, v122
	v_mov_b32_e32 v113, v114
	v_pk_mul_f32 v[112:113], v[112:113], v[132:133]
	v_mov_b32_e32 v114, v123
	v_sub_f32_e32 v119, v112, v113
	v_pk_mul_f32 v[112:113], v[114:115], v[134:135]
	v_mov_b32_e32 v115, v102
	v_sub_f32_e32 v112, v112, v113
	v_cvt_pk_bf16_f32 v119, v119, v112
	v_add_u32_e32 v112, s42, v179
	v_ashrrev_i32_e32 v113, 31, v112
	v_lshlrev_b64 v[112:113], 8, v[112:113]
	v_lshl_add_u64 v[112:113], s[22:23], 0, v[112:113]
	v_lshl_add_u64 v[112:113], v[112:113], 0, v[170:171]
	global_store_dwordx4 v[112:113], v[124:127], off
	global_store_dwordx4 v[112:113], v[116:119], off offset:128
	v_mov_b32_e32 v112, v80
	v_mov_b32_e32 v113, v100
	v_pk_mul_f32 v[112:113], v[112:113], v[108:109]
	v_mov_b32_e32 v117, v90
	v_add_f32_e32 v114, v112, v113
	v_mov_b32_e32 v112, v81
	v_mov_b32_e32 v113, v101
	v_pk_mul_f32 v[112:113], v[112:113], v[110:111]
	v_or_b32_e32 v118, 0x4000, v179
	v_add_f32_e32 v112, v112, v113
	v_cvt_pk_bf16_f32 v112, v114, v112
	v_mov_b32_e32 v114, v82
	v_pk_mul_f32 v[114:115], v[114:115], v[104:105]
	s_nop 0
	v_add_f32_e32 v113, v114, v115
	v_mov_b32_e32 v114, v83
	v_mov_b32_e32 v115, v103
	v_pk_mul_f32 v[114:115], v[114:115], v[106:107]
	s_nop 0
	v_add_f32_e32 v114, v114, v115
	v_cvt_pk_bf16_f32 v113, v113, v114
	v_mov_b32_e32 v114, v72
	v_mov_b32_e32 v115, v88
	v_pk_mul_f32 v[114:115], v[114:115], v[96:97]
	s_nop 0
	v_add_f32_e32 v116, v114, v115
	v_mov_b32_e32 v114, v73
	v_mov_b32_e32 v115, v89
	v_pk_mul_f32 v[114:115], v[114:115], v[98:99]
	s_nop 0
	v_add_f32_e32 v114, v114, v115
	v_cvt_pk_bf16_f32 v114, v116, v114
	v_mov_b32_e32 v116, v74
	v_pk_mul_f32 v[116:117], v[116:117], v[92:93]
	s_nop 0
	v_add_f32_e32 v115, v116, v117
	v_mov_b32_e32 v116, v75
	v_mov_b32_e32 v117, v91
	v_pk_mul_f32 v[116:117], v[116:117], v[94:95]
	s_nop 0
	v_add_f32_e32 v116, v116, v117
	v_cvt_pk_bf16_f32 v115, v115, v116
	v_mov_b32_e32 v116, v100
	v_mov_b32_e32 v117, v80
	v_mov_b32_e32 v80, v101
	v_pk_mul_f32 v[116:117], v[116:117], v[108:109]
	v_pk_mul_f32 v[80:81], v[80:81], v[110:111]
	v_sub_f32_e32 v100, v116, v117
	v_sub_f32_e32 v80, v80, v81
	v_cvt_pk_bf16_f32 v80, v100, v80
	v_mov_b32_e32 v100, v102
	v_mov_b32_e32 v101, v82
	v_mov_b32_e32 v82, v103
	v_pk_mul_f32 v[100:101], v[100:101], v[104:105]
	v_pk_mul_f32 v[82:83], v[82:83], v[106:107]
	v_sub_f32_e32 v81, v100, v101
	v_sub_f32_e32 v82, v82, v83
	v_cvt_pk_bf16_f32 v81, v81, v82
	v_mov_b32_e32 v82, v88
	v_mov_b32_e32 v83, v72
	v_mov_b32_e32 v72, v89
	v_pk_mul_f32 v[82:83], v[82:83], v[96:97]
	v_pk_mul_f32 v[72:73], v[72:73], v[98:99]
	v_sub_f32_e32 v82, v82, v83
	v_sub_f32_e32 v72, v72, v73
	v_cvt_pk_bf16_f32 v82, v82, v72
	v_mov_b32_e32 v72, v90
	v_mov_b32_e32 v73, v74
	v_pk_mul_f32 v[72:73], v[72:73], v[92:93]
	v_mov_b32_e32 v74, v91
	v_sub_f32_e32 v83, v72, v73
	v_pk_mul_f32 v[72:73], v[74:75], v[94:95]
	v_mov_b32_e32 v75, v86
	v_sub_f32_e32 v72, v72, v73
	v_cvt_pk_bf16_f32 v83, v83, v72
	v_add_u32_e32 v72, s41, v118
	v_ashrrev_i32_e32 v73, 31, v72
	v_lshlrev_b64 v[72:73], 8, v[72:73]
	v_lshl_add_u64 v[72:73], s[22:23], 0, v[72:73]
	v_lshl_add_u64 v[72:73], v[72:73], 0, v[170:171]
	global_store_dwordx4 v[72:73], v[112:115], off
	global_store_dwordx4 v[72:73], v[80:83], off offset:128
	v_mov_b32_e32 v72, v68
	v_mov_b32_e32 v73, v84
	v_pk_mul_f32 v[72:73], v[72:73], v[108:109]
	v_mov_b32_e32 v81, v78
	v_add_f32_e32 v74, v72, v73
	v_mov_b32_e32 v72, v69
	v_mov_b32_e32 v73, v85
	v_pk_mul_f32 v[72:73], v[72:73], v[110:111]
	v_mov_b32_e32 v101, v58
	v_add_f32_e32 v72, v72, v73
	v_cvt_pk_bf16_f32 v72, v74, v72
	v_mov_b32_e32 v74, v70
	v_pk_mul_f32 v[74:75], v[74:75], v[104:105]
	v_or_b32_e32 v102, 0x8000, v179
	v_add_f32_e32 v73, v74, v75
	v_mov_b32_e32 v74, v71
	v_mov_b32_e32 v75, v87
	v_pk_mul_f32 v[74:75], v[74:75], v[106:107]
	s_nop 0
	v_add_f32_e32 v74, v74, v75
	v_cvt_pk_bf16_f32 v73, v73, v74
	v_mov_b32_e32 v74, v64
	v_mov_b32_e32 v75, v76
	v_pk_mul_f32 v[74:75], v[74:75], v[96:97]
	s_nop 0
	v_add_f32_e32 v80, v74, v75
	v_mov_b32_e32 v74, v65
	v_mov_b32_e32 v75, v77
	v_pk_mul_f32 v[74:75], v[74:75], v[98:99]
	s_nop 0
	v_add_f32_e32 v74, v74, v75
	v_cvt_pk_bf16_f32 v74, v80, v74
	v_mov_b32_e32 v80, v66
	v_pk_mul_f32 v[80:81], v[80:81], v[92:93]
	s_nop 0
	v_add_f32_e32 v75, v80, v81
	v_mov_b32_e32 v80, v67
	v_mov_b32_e32 v81, v79
	v_pk_mul_f32 v[80:81], v[80:81], v[94:95]
	s_nop 0
	v_add_f32_e32 v80, v80, v81
	v_cvt_pk_bf16_f32 v75, v75, v80
	v_mov_b32_e32 v80, v84
	v_mov_b32_e32 v81, v68
	v_mov_b32_e32 v68, v85
	v_pk_mul_f32 v[80:81], v[80:81], v[108:109]
	v_pk_mul_f32 v[68:69], v[68:69], v[110:111]
	v_sub_f32_e32 v80, v80, v81
	v_sub_f32_e32 v68, v68, v69
	v_cvt_pk_bf16_f32 v68, v80, v68
	v_mov_b32_e32 v80, v86
	v_mov_b32_e32 v81, v70
	v_mov_b32_e32 v70, v87
	v_pk_mul_f32 v[80:81], v[80:81], v[104:105]
	v_pk_mul_f32 v[70:71], v[70:71], v[106:107]
	v_sub_f32_e32 v69, v80, v81
	v_sub_f32_e32 v70, v70, v71
	v_cvt_pk_bf16_f32 v69, v69, v70
	v_mov_b32_e32 v70, v76
	v_mov_b32_e32 v71, v64
	v_mov_b32_e32 v64, v77
	v_pk_mul_f32 v[70:71], v[70:71], v[96:97]
	v_pk_mul_f32 v[64:65], v[64:65], v[98:99]
	v_sub_f32_e32 v70, v70, v71
	v_sub_f32_e32 v64, v64, v65
	v_cvt_pk_bf16_f32 v70, v70, v64
	v_mov_b32_e32 v64, v78
	v_mov_b32_e32 v65, v66
	v_pk_mul_f32 v[64:65], v[64:65], v[92:93]
	v_mov_b32_e32 v66, v79
	v_sub_f32_e32 v71, v64, v65
	v_pk_mul_f32 v[64:65], v[66:67], v[94:95]
	v_add_co_u32_e32 v66, vcc, s43, v172
	v_sub_f32_e32 v64, v64, v65
	v_cvt_pk_bf16_f32 v71, v71, v64
	v_add_u32_e32 v64, s42, v118
	v_ashrrev_i32_e32 v65, 31, v64
	v_lshlrev_b64 v[64:65], 8, v[64:65]
	v_lshl_add_u64 v[64:65], s[22:23], 0, v[64:65]
	v_lshl_add_u64 v[64:65], v[64:65], 0, v[170:171]
	global_store_dwordx4 v[64:65], v[72:75], off
	global_store_dwordx4 v[64:65], v[68:71], off offset:128
	v_addc_co_u32_e32 v67, vcc, 0, v173, vcc
	v_lshl_add_u64 v[64:65], v[172:173], 0, s[6:7]
	global_load_dwordx4 v[80:83], v[66:67], off
	global_load_dwordx4 v[84:87], v[64:65], off offset:48
	global_load_dwordx4 v[88:91], v[64:65], off offset:32
	global_load_dwordx4 v[92:95], v[64:65], off offset:16
	s_movk_i32 s43, 0x6000
	v_add_co_u32_e32 v64, vcc, s43, v172
	v_lshl_add_u64 v[72:73], v[172:173], 0, s[34:35]
	s_nop 0
	v_addc_co_u32_e32 v65, vcc, 0, v173, vcc
	global_load_dwordx4 v[76:79], v[64:65], off
	s_nop 0
	global_load_dwordx4 v[64:67], v[72:73], off offset:48
	global_load_dwordx4 v[68:71], v[72:73], off offset:32
	s_nop 0
	global_load_dwordx4 v[72:75], v[72:73], off offset:16
	v_mov_b32_e32 v96, v48
	v_mov_b32_e32 v97, v60
	v_mov_b32_e32 v99, v62
	s_waitcnt vmcnt(0)
	v_pk_mul_f32 v[96:97], v[96:97], v[80:81]
	s_nop 0
	v_add_f32_e32 v98, v96, v97
	v_mov_b32_e32 v96, v49
	v_mov_b32_e32 v97, v61
	v_pk_mul_f32 v[96:97], v[96:97], v[82:83]
	s_nop 0
	v_add_f32_e32 v96, v96, v97
	v_cvt_pk_bf16_f32 v96, v98, v96
	v_mov_b32_e32 v98, v50
	v_pk_mul_f32 v[98:99], v[98:99], v[92:93]
	s_nop 0
	v_add_f32_e32 v97, v98, v99
	v_mov_b32_e32 v98, v51
	v_mov_b32_e32 v99, v63
	v_pk_mul_f32 v[98:99], v[98:99], v[94:95]
	s_nop 0
	v_add_f32_e32 v98, v98, v99
	v_cvt_pk_bf16_f32 v97, v97, v98
	v_mov_b32_e32 v98, v40
	v_mov_b32_e32 v99, v56
	v_pk_mul_f32 v[98:99], v[98:99], v[88:89]
	s_nop 0
	v_add_f32_e32 v100, v98, v99
	v_mov_b32_e32 v98, v41
	v_mov_b32_e32 v99, v57
	v_pk_mul_f32 v[98:99], v[98:99], v[90:91]
	s_nop 0
	v_add_f32_e32 v98, v98, v99
	v_cvt_pk_bf16_f32 v98, v100, v98
	v_mov_b32_e32 v100, v42
	v_pk_mul_f32 v[100:101], v[100:101], v[84:85]
	s_nop 0
	v_add_f32_e32 v99, v100, v101
	v_mov_b32_e32 v100, v43
	v_mov_b32_e32 v101, v59
	v_pk_mul_f32 v[100:101], v[100:101], v[86:87]
	s_nop 0
	v_add_f32_e32 v100, v100, v101
	v_cvt_pk_bf16_f32 v99, v99, v100
	v_mov_b32_e32 v100, v60
	v_mov_b32_e32 v101, v48
	v_mov_b32_e32 v48, v61
	v_pk_mul_f32 v[100:101], v[100:101], v[80:81]
	v_pk_mul_f32 v[48:49], v[48:49], v[82:83]
	v_sub_f32_e32 v60, v100, v101
	v_sub_f32_e32 v48, v48, v49
	v_cvt_pk_bf16_f32 v48, v60, v48
	v_mov_b32_e32 v60, v62
	v_mov_b32_e32 v61, v50
	v_mov_b32_e32 v50, v63
	v_pk_mul_f32 v[60:61], v[60:61], v[92:93]
	v_pk_mul_f32 v[50:51], v[50:51], v[94:95]
	v_sub_f32_e32 v49, v60, v61
	v_sub_f32_e32 v50, v50, v51
	v_cvt_pk_bf16_f32 v49, v49, v50
	v_mov_b32_e32 v50, v56
	v_mov_b32_e32 v51, v40
	v_mov_b32_e32 v40, v57
	v_pk_mul_f32 v[50:51], v[50:51], v[88:89]
	v_pk_mul_f32 v[40:41], v[40:41], v[90:91]
	v_sub_f32_e32 v50, v50, v51
	v_sub_f32_e32 v40, v40, v41
	v_cvt_pk_bf16_f32 v50, v50, v40
	v_mov_b32_e32 v40, v58
	v_mov_b32_e32 v41, v42
	v_pk_mul_f32 v[40:41], v[40:41], v[84:85]
	v_mov_b32_e32 v42, v59
	v_sub_f32_e32 v51, v40, v41
	v_pk_mul_f32 v[40:41], v[42:43], v[86:87]
	v_mov_b32_e32 v43, v54
	v_sub_f32_e32 v40, v40, v41
	v_cvt_pk_bf16_f32 v51, v51, v40
	v_add_u32_e32 v40, s41, v102
	v_ashrrev_i32_e32 v41, 31, v40
	v_lshlrev_b64 v[40:41], 8, v[40:41]
	v_lshl_add_u64 v[40:41], s[22:23], 0, v[40:41]
	v_lshl_add_u64 v[40:41], v[40:41], 0, v[170:171]
	global_store_dwordx4 v[40:41], v[96:99], off
	global_store_dwordx4 v[40:41], v[48:51], off offset:128
	v_mov_b32_e32 v40, v36
	v_mov_b32_e32 v41, v52
	v_pk_mul_f32 v[40:41], v[40:41], v[80:81]
	v_mov_b32_e32 v49, v46
	v_add_f32_e32 v42, v40, v41
	v_mov_b32_e32 v40, v37
	v_mov_b32_e32 v41, v53
	v_pk_mul_f32 v[40:41], v[40:41], v[82:83]
	s_nop 0
	v_add_f32_e32 v40, v40, v41
	v_cvt_pk_bf16_f32 v40, v42, v40
	v_mov_b32_e32 v42, v38
	v_pk_mul_f32 v[42:43], v[42:43], v[92:93]
	s_nop 0
	v_add_f32_e32 v41, v42, v43
	v_mov_b32_e32 v42, v39
	v_mov_b32_e32 v43, v55
	v_pk_mul_f32 v[42:43], v[42:43], v[94:95]
	s_nop 0
	v_add_f32_e32 v42, v42, v43
	v_cvt_pk_bf16_f32 v41, v41, v42
	v_mov_b32_e32 v42, v32
	v_mov_b32_e32 v43, v44
	v_pk_mul_f32 v[42:43], v[42:43], v[88:89]
	s_nop 0
	v_add_f32_e32 v48, v42, v43
	v_mov_b32_e32 v42, v33
	v_mov_b32_e32 v43, v45
	v_pk_mul_f32 v[42:43], v[42:43], v[90:91]
	s_nop 0
	v_add_f32_e32 v42, v42, v43
	v_cvt_pk_bf16_f32 v42, v48, v42
	v_mov_b32_e32 v48, v34
	v_pk_mul_f32 v[48:49], v[48:49], v[84:85]
	s_nop 0
	v_add_f32_e32 v43, v48, v49
	v_mov_b32_e32 v48, v35
	v_mov_b32_e32 v49, v47
	v_pk_mul_f32 v[48:49], v[48:49], v[86:87]
	s_nop 0
	v_add_f32_e32 v48, v48, v49
	v_cvt_pk_bf16_f32 v43, v43, v48
	v_mov_b32_e32 v48, v52
	v_mov_b32_e32 v49, v36
	v_mov_b32_e32 v36, v53
	v_pk_mul_f32 v[48:49], v[48:49], v[80:81]
	v_pk_mul_f32 v[36:37], v[36:37], v[82:83]
	v_sub_f32_e32 v48, v48, v49
	v_sub_f32_e32 v36, v36, v37
	v_cvt_pk_bf16_f32 v36, v48, v36
	v_mov_b32_e32 v48, v54
	v_mov_b32_e32 v49, v38
	v_mov_b32_e32 v38, v55
	v_pk_mul_f32 v[48:49], v[48:49], v[92:93]
	v_pk_mul_f32 v[38:39], v[38:39], v[94:95]
	v_sub_f32_e32 v37, v48, v49
	v_sub_f32_e32 v38, v38, v39
	v_cvt_pk_bf16_f32 v37, v37, v38
	v_mov_b32_e32 v38, v44
	v_mov_b32_e32 v39, v32
	v_mov_b32_e32 v32, v45
	v_pk_mul_f32 v[38:39], v[38:39], v[88:89]
	v_pk_mul_f32 v[32:33], v[32:33], v[90:91]
	v_sub_f32_e32 v38, v38, v39
	v_sub_f32_e32 v32, v32, v33
	v_cvt_pk_bf16_f32 v38, v38, v32
	v_mov_b32_e32 v32, v46
	v_mov_b32_e32 v33, v34
	v_pk_mul_f32 v[32:33], v[32:33], v[84:85]
	v_mov_b32_e32 v34, v47
	v_sub_f32_e32 v39, v32, v33
	v_pk_mul_f32 v[32:33], v[34:35], v[86:87]
	v_mov_b32_e32 v35, v30
	v_sub_f32_e32 v32, v32, v33
	v_cvt_pk_bf16_f32 v39, v39, v32
	v_add_u32_e32 v32, s42, v102
	v_ashrrev_i32_e32 v33, 31, v32
	v_lshlrev_b64 v[32:33], 8, v[32:33]
	v_lshl_add_u64 v[32:33], s[22:23], 0, v[32:33]
	v_lshl_add_u64 v[32:33], v[32:33], 0, v[170:171]
	global_store_dwordx4 v[32:33], v[40:43], off
	global_store_dwordx4 v[32:33], v[36:39], off offset:128
	v_mov_b32_e32 v32, v16
	v_mov_b32_e32 v33, v28
	v_pk_mul_f32 v[32:33], v[32:33], v[76:77]
	v_mov_b32_e32 v37, v26
	v_add_f32_e32 v34, v32, v33
	v_mov_b32_e32 v32, v17
	v_mov_b32_e32 v33, v29
	v_pk_mul_f32 v[32:33], v[32:33], v[78:79]
	v_or_b32_e32 v38, 0xc000, v179
	v_add_f32_e32 v32, v32, v33
	v_cvt_pk_bf16_f32 v32, v34, v32
	v_mov_b32_e32 v34, v18
	v_pk_mul_f32 v[34:35], v[34:35], v[72:73]
	s_nop 0
	v_add_f32_e32 v33, v34, v35
	v_mov_b32_e32 v34, v19
	v_mov_b32_e32 v35, v31
	v_pk_mul_f32 v[34:35], v[34:35], v[74:75]
	s_nop 0
	v_add_f32_e32 v34, v34, v35
	v_cvt_pk_bf16_f32 v33, v33, v34
	v_mov_b32_e32 v34, v8
	v_mov_b32_e32 v35, v24
	v_pk_mul_f32 v[34:35], v[34:35], v[68:69]
	s_nop 0
	v_add_f32_e32 v36, v34, v35
	v_mov_b32_e32 v34, v9
	v_mov_b32_e32 v35, v25
	v_pk_mul_f32 v[34:35], v[34:35], v[70:71]
	s_nop 0
	v_add_f32_e32 v34, v34, v35
	v_cvt_pk_bf16_f32 v34, v36, v34
	v_mov_b32_e32 v36, v10
	v_pk_mul_f32 v[36:37], v[36:37], v[64:65]
	s_nop 0
	v_add_f32_e32 v35, v36, v37
	v_mov_b32_e32 v36, v11
	v_mov_b32_e32 v37, v27
	v_pk_mul_f32 v[36:37], v[36:37], v[66:67]
	s_nop 0
	v_add_f32_e32 v36, v36, v37
	v_cvt_pk_bf16_f32 v35, v35, v36
	v_mov_b32_e32 v36, v28
	v_mov_b32_e32 v37, v16
	v_mov_b32_e32 v16, v29
	v_pk_mul_f32 v[36:37], v[36:37], v[76:77]
	v_pk_mul_f32 v[16:17], v[16:17], v[78:79]
	v_sub_f32_e32 v28, v36, v37
	v_sub_f32_e32 v16, v16, v17
	v_cvt_pk_bf16_f32 v16, v28, v16
	v_mov_b32_e32 v28, v30
	v_mov_b32_e32 v29, v18
	v_mov_b32_e32 v18, v31
	v_pk_mul_f32 v[28:29], v[28:29], v[72:73]
	v_pk_mul_f32 v[18:19], v[18:19], v[74:75]
	v_sub_f32_e32 v17, v28, v29
	v_sub_f32_e32 v18, v18, v19
	v_cvt_pk_bf16_f32 v17, v17, v18
	v_mov_b32_e32 v18, v24
	v_mov_b32_e32 v19, v8
	v_mov_b32_e32 v8, v25
	v_pk_mul_f32 v[18:19], v[18:19], v[68:69]
	v_pk_mul_f32 v[8:9], v[8:9], v[70:71]
	v_sub_f32_e32 v18, v18, v19
	v_sub_f32_e32 v8, v8, v9
	v_cvt_pk_bf16_f32 v18, v18, v8
	v_mov_b32_e32 v8, v26
	v_mov_b32_e32 v9, v10
	v_pk_mul_f32 v[8:9], v[8:9], v[64:65]
	v_mov_b32_e32 v10, v27
	v_sub_f32_e32 v19, v8, v9
	v_pk_mul_f32 v[8:9], v[10:11], v[66:67]
	v_mov_b32_e32 v11, v22
	v_sub_f32_e32 v8, v8, v9
	v_cvt_pk_bf16_f32 v19, v19, v8
	v_add_u32_e32 v8, s41, v38
	v_ashrrev_i32_e32 v9, 31, v8
	v_lshlrev_b64 v[8:9], 8, v[8:9]
	v_lshl_add_u64 v[8:9], s[22:23], 0, v[8:9]
	v_lshl_add_u64 v[8:9], v[8:9], 0, v[170:171]
	global_store_dwordx4 v[8:9], v[32:35], off
	global_store_dwordx4 v[8:9], v[16:19], off offset:128
	v_mov_b32_e32 v8, v4
	v_mov_b32_e32 v9, v20
	v_pk_mul_f32 v[8:9], v[8:9], v[76:77]
	v_mov_b32_e32 v17, v14
	v_add_f32_e32 v10, v8, v9
	v_mov_b32_e32 v8, v5
	v_mov_b32_e32 v9, v21
	v_pk_mul_f32 v[8:9], v[8:9], v[78:79]
	s_nop 0
	v_add_f32_e32 v8, v8, v9
	v_cvt_pk_bf16_f32 v8, v10, v8
	v_mov_b32_e32 v10, v6
	v_pk_mul_f32 v[10:11], v[10:11], v[72:73]
	s_nop 0
	v_add_f32_e32 v9, v10, v11
	v_mov_b32_e32 v10, v7
	v_mov_b32_e32 v11, v23
	v_pk_mul_f32 v[10:11], v[10:11], v[74:75]
	s_nop 0
	v_add_f32_e32 v10, v10, v11
	v_cvt_pk_bf16_f32 v9, v9, v10
	v_mov_b32_e32 v10, v0
	v_mov_b32_e32 v11, v12
	v_pk_mul_f32 v[10:11], v[10:11], v[68:69]
	s_nop 0
	v_add_f32_e32 v16, v10, v11
	v_mov_b32_e32 v10, v1
	v_mov_b32_e32 v11, v13
	v_pk_mul_f32 v[10:11], v[10:11], v[70:71]
	s_nop 0
	v_add_f32_e32 v10, v10, v11
	v_cvt_pk_bf16_f32 v10, v16, v10
	v_mov_b32_e32 v16, v2
	v_pk_mul_f32 v[16:17], v[16:17], v[64:65]
	s_nop 0
	v_add_f32_e32 v11, v16, v17
	v_mov_b32_e32 v16, v3
	v_mov_b32_e32 v17, v15
	v_pk_mul_f32 v[16:17], v[16:17], v[66:67]
	s_nop 0
	v_add_f32_e32 v16, v16, v17
	v_cvt_pk_bf16_f32 v11, v11, v16
	v_mov_b32_e32 v16, v20
	v_mov_b32_e32 v17, v4
	v_mov_b32_e32 v4, v21
	v_pk_mul_f32 v[16:17], v[16:17], v[76:77]
	v_pk_mul_f32 v[4:5], v[4:5], v[78:79]
	v_sub_f32_e32 v16, v16, v17
	v_sub_f32_e32 v4, v4, v5
	v_cvt_pk_bf16_f32 v4, v16, v4
	v_mov_b32_e32 v16, v22
	v_mov_b32_e32 v17, v6
	v_mov_b32_e32 v6, v23
	v_pk_mul_f32 v[16:17], v[16:17], v[72:73]
	v_pk_mul_f32 v[6:7], v[6:7], v[74:75]
	v_sub_f32_e32 v5, v16, v17
	v_sub_f32_e32 v6, v6, v7
	v_cvt_pk_bf16_f32 v5, v5, v6
	v_mov_b32_e32 v6, v12
	v_mov_b32_e32 v7, v0
	v_mov_b32_e32 v0, v13
	v_pk_mul_f32 v[6:7], v[6:7], v[68:69]
	v_pk_mul_f32 v[0:1], v[0:1], v[70:71]
	v_sub_f32_e32 v6, v6, v7
	v_sub_f32_e32 v0, v0, v1
	v_cvt_pk_bf16_f32 v6, v6, v0
	v_mov_b32_e32 v0, v14
	v_mov_b32_e32 v1, v2
	v_pk_mul_f32 v[0:1], v[0:1], v[64:65]
	v_mov_b32_e32 v2, v15
	v_sub_f32_e32 v7, v0, v1
	v_pk_mul_f32 v[0:1], v[2:3], v[66:67]
	s_nop 0
	v_sub_f32_e32 v0, v0, v1
	v_cvt_pk_bf16_f32 v7, v7, v0
	v_add_u32_e32 v0, s42, v38
	v_ashrrev_i32_e32 v1, 31, v0
	v_lshlrev_b64 v[0:1], 8, v[0:1]
	v_lshl_add_u64 v[0:1], s[22:23], 0, v[0:1]
	v_lshl_add_u64 v[0:1], v[0:1], 0, v[170:171]
	global_store_dwordx4 v[0:1], v[8:11], off
	global_store_dwordx4 v[0:1], v[4:7], off offset:128

.LBB0_450:
	s_add_u32 s34, s46, s22
	s_addc_u32 s35, s47, s23
	s_mov_b32 m0, s42
	s_add_u32 s98, s34, s24
	s_addc_u32 s99, s35, s25
	global_load_lds_dwordx4 v203, s[98:99]
	s_mov_b32 m0, s43
	s_add_i32 s4, s41, s50
	global_load_lds_dwordx4 v204, s[98:99]
	s_mov_b32 m0, s48
	s_nop 0
	global_load_lds_dwordx4 v205, s[98:99]
	s_add_u32 s58, s1, s22
	s_addc_u32 s59, s45, s23
	s_mov_b32 m0, s4
	s_mov_b32 s51, s49
	s_add_u32 s100, s58, s26
	s_addc_u32 s101, s59, s27
	global_load_lds_dwordx4 v206, s[100:101]
	s_add_i32 m0, s4, 0x2000
	s_mov_b32 s49, s68
	global_load_lds_dwordx4 v207, s[100:101]
	ds_read_b128 v[64:67], v208 offset:49152
	ds_read_b128 v[68:71], v208 offset:61440
	ds_read_b128 v[222:225], v209 offset:49152
	ds_read_b128 v[226:229], v209 offset:61440
	ds_read_b128 v[230:233], v210 offset:49152
	ds_read_b128 v[234:237], v210 offset:61440
	s_add_i32 s57, 0, 0x12000
	s_waitcnt lgkmcnt(4)
	v_mfma_f32_32x32x16_bf16 v[80:95], v[64:67], v[140:143], 0
	v_exp_f32_e32 v200, v144
	v_add_f32_e32 v144, 0, v186
	v_add_f32_e32 v144, v189, v144
	v_mfma_f32_32x32x16_bf16 v[64:79], v[68:71], v[140:143], 0
	v_add_f32_e32 v144, v187, v144
	v_add_f32_e32 v144, v190, v144
	v_add_f32_e32 v144, v188, v144
	ds_read_b128 v[214:217], v211 offset:49152
	ds_read_b128 v[218:221], v211 offset:61440
	s_waitcnt lgkmcnt(4)
	v_mfma_f32_32x32x16_bf16 v[80:95], v[222:225], v[136:139], v[80:95]
	v_add_f32_e32 v144, v191, v144
	v_add_f32_e32 v144, v184, v144
	v_add_f32_e32 v144, v185, v144
	v_mfma_f32_32x32x16_bf16 v[64:79], v[226:229], v[136:139], v[64:79]
	v_add_f32_e32 v144, v180, v144
	v_add_f32_e32 v144, v182, v144
	v_add_f32_e32 v144, v181, v144
	ds_read_b128 v[222:225], v208 offset:49280
	ds_read_b128 v[226:229], v208 offset:61568
	s_waitcnt lgkmcnt(4)
	v_mfma_f32_32x32x16_bf16 v[80:95], v[230:233], v[132:135], v[80:95]
	v_add_f32_e32 v144, v183, v144
	v_add_f32_e32 v144, v176, v144
	v_add_f32_e32 v144, v178, v144
	v_mfma_f32_32x32x16_bf16 v[64:79], v[234:237], v[132:135], v[64:79]
	v_exp_f32_e32 v162, v162
	v_add_f32_e32 v144, v177, v144
	v_exp_f32_e32 v163, v163
	v_add_f32_e32 v144, v179, v144
	ds_read_b128 v[230:233], v209 offset:49280
	ds_read_b128 v[234:237], v209 offset:61568
	s_waitcnt lgkmcnt(4)
	v_mfma_f32_32x32x16_bf16 v[80:95], v[214:217], v[128:131], v[80:95]
	v_exp_f32_e32 v201, v145
	v_exp_f32_e32 v148, v164
	v_exp_f32_e32 v164, v165
	v_mfma_f32_32x32x16_bf16 v[64:79], v[218:221], v[128:131], v[64:79]
	v_exp_f32_e32 v165, v158
	v_add_f32_e32 v144, v148, v144
	v_add_f32_e32 v144, v164, v144
	ds_read_b128 v[214:217], v210 offset:49280
	ds_read_b128 v[218:221], v210 offset:61568
	s_waitcnt lgkmcnt(4)
	v_mfma_f32_32x32x16_bf16 v[80:95], v[222:225], v[124:127], v[80:95]
	v_add_f32_e32 v144, v162, v144
	v_add_f32_e32 v144, v163, v144
	v_add_f32_e32 v144, v165, v144
	v_mfma_f32_32x32x16_bf16 v[64:79], v[226:229], v[124:127], v[64:79]
	v_exp_f32_e32 v175, v159
	s_nop 0
	v_add_f32_e32 v144, v175, v144
	ds_read_b128 v[222:225], v211 offset:49280
	ds_read_b128 v[226:229], v211 offset:61568
	s_waitcnt lgkmcnt(4)
	v_mfma_f32_32x32x16_bf16 v[80:95], v[230:233], v[120:123], v[80:95]
	v_exp_f32_e32 v192, v154
	v_exp_f32_e32 v193, v155
	v_exp_f32_e32 v194, v146
	v_mfma_f32_32x32x16_bf16 v[64:79], v[234:237], v[120:123], v[64:79]
	v_exp_f32_e32 v195, v147
	v_add_f32_e32 v144, v192, v144
	v_add_f32_e32 v144, v193, v144
	v_add_f32_e32 v144, v194, v144
	ds_read_b128 v[230:233], v208 offset:49408
	ds_read_b128 v[234:237], v208 offset:61696
	s_waitcnt lgkmcnt(4)
	v_mfma_f32_32x32x16_bf16 v[80:95], v[214:217], v[116:119], v[80:95]
	v_exp_f32_e32 v196, v160
	v_exp_f32_e32 v197, v161
	v_exp_f32_e32 v198, v156
	v_mfma_f32_32x32x16_bf16 v[64:79], v[218:221], v[116:119], v[64:79]
	v_exp_f32_e32 v199, v157
	v_add_f32_e32 v144, v195, v144
	v_add_f32_e32 v144, v196, v144
	ds_read_b128 v[214:217], v209 offset:49408
	ds_read_b128 v[218:221], v209 offset:61696
	s_waitcnt lgkmcnt(4)
	v_mfma_f32_32x32x16_bf16 v[80:95], v[222:225], v[112:115], v[80:95]
	v_add_f32_e32 v144, v197, v144
	v_add_f32_e32 v144, v198, v144
	v_add_f32_e32 v144, v199, v144
	v_mfma_f32_32x32x16_bf16 v[64:79], v[226:229], v[112:115], v[64:79]
	v_add_f32_e32 v144, v200, v144
	v_add_f32_e32 v173, v201, v144
	v_mov_b32_e32 v174, v173
	ds_read_b128 v[222:225], v210 offset:49408
	ds_read_b128 v[226:229], v210 offset:61696
	s_waitcnt lgkmcnt(4)
	v_mfma_f32_32x32x16_bf16 v[80:95], v[230:233], v[108:111], v[80:95]
	v_cvt_pk_bf16_f32 v144, v186, v189
	v_cvt_pk_bf16_f32 v145, v187, v190
	v_cvt_pk_bf16_f32 v146, v188, v191
	v_mfma_f32_32x32x16_bf16 v[64:79], v[234:237], v[108:111], v[64:79]
	s_nop 1
	v_permlane32_swap_b32_e32 v173, v174
	v_cvt_pk_bf16_f32 v147, v184, v185
	v_permlane32_swap_b32_e32 v144, v146
	ds_read_b128 v[230:233], v211 offset:49408
	ds_read_b128 v[234:237], v211 offset:61696
	s_waitcnt lgkmcnt(4)
	v_mfma_f32_32x32x16_bf16 v[80:95], v[214:217], v[104:107], v[80:95]
	v_cvt_pk_bf16_f32 v154, v180, v182
	v_cvt_pk_bf16_f32 v155, v181, v183
	v_cvt_pk_bf16_f32 v156, v176, v178
	v_mfma_f32_32x32x16_bf16 v[64:79], v[218:221], v[104:107], v[64:79]
	v_cvt_pk_bf16_f32 v157, v177, v179
	v_cvt_pk_bf16_f32 v158, v148, v164
	v_cvt_pk_bf16_f32 v159, v162, v163
	s_waitcnt lgkmcnt(2)
	v_mfma_f32_32x32x16_bf16 v[80:95], v[222:225], v[100:103], v[80:95]
	v_cvt_pk_bf16_f32 v160, v165, v175
	v_cvt_pk_bf16_f32 v161, v192, v193
	v_cvt_pk_bf16_f32 v162, v194, v195
	v_mfma_f32_32x32x16_bf16 v[64:79], v[226:229], v[100:103], v[64:79]
	v_cvt_pk_bf16_f32 v163, v196, v197
	v_cvt_pk_bf16_f32 v164, v198, v199
	v_cvt_pk_bf16_f32 v165, v200, v201
	s_waitcnt lgkmcnt(0)
	v_mfma_f32_32x32x16_bf16 v[80:95], v[230:233], v[96:99], v[80:95]
	v_permlane32_swap_b32_e32 v145, v147
	v_permlane32_swap_b32_e32 v154, v156
	v_permlane32_swap_b32_e32 v155, v157
	v_mfma_f32_32x32x16_bf16 v[64:79], v[234:237], v[96:99], v[64:79]
	v_permlane32_swap_b32_e32 v158, v160
	v_permlane32_swap_b32_e32 v159, v161
	v_permlane32_swap_b32_e32 v162, v164
	v_permlane32_swap_b32_e32 v163, v165
	s_cmp_lg_u32 0, -1
	s_cselect_b32 s4, 0, 0
	s_add_i32 s44, s68, s4
	v_add_u32_e32 v148, s44, v212
	ds_read_b64_tr_b16 v[176:177], v148 offset:0
	ds_read_b64_tr_b16 v[178:179], v148 offset:0x800
	ds_read_b64_tr_b16 v[180:181], v148 offset:0x1000
	ds_read_b64_tr_b16 v[182:183], v148 offset:0x1800
	ds_read_b64_tr_b16 v[184:185], v148 offset:0x2000
	ds_read_b64_tr_b16 v[186:187], v148 offset:0x2800
	ds_read_b64_tr_b16 v[188:189], v148 offset:0x3000
	ds_read_b64_tr_b16 v[190:191], v148 offset:0x3800
	s_waitcnt lgkmcnt(0)
	s_nop 0
	v_mfma_f32_32x32x16_bf16 v[0:15], v[144:147], v[176:179], v[0:15]
	ds_read_b64_tr_b16 v[176:177], v148 offset:0x200
	ds_read_b64_tr_b16 v[178:179], v148 offset:0xa00
	v_mfma_f32_32x32x16_bf16 v[0:15], v[154:157], v[180:183], v[0:15]
	ds_read_b64_tr_b16 v[180:181], v148 offset:0x1200
	ds_read_b64_tr_b16 v[182:183], v148 offset:0x1a00
	v_mfma_f32_32x32x16_bf16 v[0:15], v[158:161], v[184:187], v[0:15]
	ds_read_b64_tr_b16 v[184:185], v148 offset:0x2200
	ds_read_b64_tr_b16 v[186:187], v148 offset:0x2a00
	v_mfma_f32_32x32x16_bf16 v[0:15], v[162:165], v[188:191], v[0:15]
	ds_read_b64_tr_b16 v[188:189], v148 offset:0x3200
	ds_read_b64_tr_b16 v[190:191], v148 offset:0x3a00
	s_waitcnt lgkmcnt(0)
	v_mfma_f32_32x32x16_bf16 v[48:63], v[144:147], v[176:179], v[48:63]
	ds_read_b64_tr_b16 v[176:177], v148 offset:0x400
	ds_read_b64_tr_b16 v[178:179], v148 offset:0xc00
	v_mfma_f32_32x32x16_bf16 v[48:63], v[154:157], v[180:183], v[48:63]
	ds_read_b64_tr_b16 v[180:181], v148 offset:0x1400
	ds_read_b64_tr_b16 v[182:183], v148 offset:0x1c00
	v_mfma_f32_32x32x16_bf16 v[48:63], v[158:161], v[184:187], v[48:63]
	ds_read_b64_tr_b16 v[184:185], v148 offset:0x2400
	ds_read_b64_tr_b16 v[186:187], v148 offset:0x2c00
	v_mfma_f32_32x32x16_bf16 v[48:63], v[162:165], v[188:191], v[48:63]
	ds_read_b64_tr_b16 v[188:189], v148 offset:0x3400
	ds_read_b64_tr_b16 v[190:191], v148 offset:0x3c00
	s_waitcnt lgkmcnt(0)
	v_mfma_f32_32x32x16_bf16 v[32:47], v[144:147], v[176:179], v[32:47]
	ds_read_b64_tr_b16 v[176:177], v148 offset:0x600
	ds_read_b64_tr_b16 v[178:179], v148 offset:0xe00
	v_mfma_f32_32x32x16_bf16 v[32:47], v[154:157], v[180:183], v[32:47]
	ds_read_b64_tr_b16 v[180:181], v148 offset:0x1600
	ds_read_b64_tr_b16 v[182:183], v148 offset:0x1e00
	v_mfma_f32_32x32x16_bf16 v[32:47], v[158:161], v[184:187], v[32:47]
	ds_read_b64_tr_b16 v[184:185], v148 offset:0x2600
	ds_read_b64_tr_b16 v[186:187], v148 offset:0x2e00
	v_mfma_f32_32x32x16_bf16 v[32:47], v[162:165], v[188:191], v[32:47]
	ds_read_b64_tr_b16 v[188:189], v148 offset:0x3600
	ds_read_b64_tr_b16 v[190:191], v148 offset:0x3e00
	s_waitcnt lgkmcnt(0)
	v_mfma_f32_32x32x16_bf16 v[16:31], v[144:147], v[176:179], v[16:31]
	v_max_f32_e32 v144, v81, v81
	v_max_f32_e32 v145, v80, v80
	v_max_f32_e32 v144, v145, v144
	v_max3_f32 v144, v144, v82, v83
	v_max3_f32 v144, v144, v84, v85
	v_max3_f32 v144, v144, v86, v87
	v_max3_f32 v144, v144, v88, v89
	v_max3_f32 v144, v144, v90, v91
	v_max3_f32 v144, v144, v92, v93
	v_mfma_f32_32x32x16_bf16 v[16:31], v[154:157], v[180:183], v[16:31]
	v_max3_f32 v144, v144, v94, v95
	v_max3_f32 v144, v144, v64, v65
	v_max3_f32 v144, v144, v66, v67
	v_max3_f32 v144, v144, v68, v69
	v_max3_f32 v144, v144, v70, v71
	v_max3_f32 v144, v144, v72, v73
	v_max3_f32 v144, v144, v74, v75
	v_max3_f32 v144, v144, v76, v77
	v_mfma_f32_32x32x16_bf16 v[16:31], v[158:161], v[184:187], v[16:31]
	v_max3_f32 v144, v144, v78, v79
	v_mov_b32_e32 v145, v144
	s_nop 1
	v_permlane32_swap_b32_e32 v144, v145
	v_max_f32_e32 v145, v145, v145
	v_max_f32_e32 v144, v144, v144
	v_max_f32_e32 v144, v144, v145
	v_sub_f32_e32 v145, v144, v172
	v_cmp_ge_f32_e32 vcc, s37, v145
	v_max_f32_e32 v145, v172, v172
	v_max_f32_e32 v144, v145, v144
	v_mfma_f32_32x32x16_bf16 v[16:31], v[162:165], v[188:191], v[16:31]
	v_sub_f32_e32 v145, v172, v144
	v_mul_f32_e32 v145, 0x3dd53b94, v145
	v_exp_f32_e32 v145, v145
	s_cmp_eq_u64 vcc, exec
	s_cselect_b64 s[4:5], -1, 0
	s_waitcnt vmcnt(0)
	v_cndmask_b32_e64 v175, v145, 1.0, s[4:5]
	v_cmp_gt_f32_e32 vcc, 1.0, v175
	s_waitcnt vmcnt(0)
	s_barrier
	s_cbranch_vccz .LBB0_454
	s_and_saveexec_b64 s[60:61], s[2:3]
	ds_write_b32 v153, v175 offset:128
	s_or_b64 exec, exec, s[60:61]
	s_waitcnt lgkmcnt(0)
	v_add_u32_e32 v145, v151, v152
	ds_read_b128 v[154:157], v145 offset:224
	ds_read_b128 v[158:161], v145 offset:192
	ds_read_b128 v[162:165], v145 offset:160
	ds_read_b128 v[176:179], v145 offset:128
	s_waitcnt lgkmcnt(3)
	v_pk_mul_f32 v[12:13], v[12:13], v[154:155]
	s_waitcnt lgkmcnt(2)
	v_pk_mul_f32 v[8:9], v[8:9], v[158:159]
	s_waitcnt lgkmcnt(1)
	v_pk_mul_f32 v[4:5], v[4:5], v[162:163]
	v_pk_mul_f32 v[14:15], v[14:15], v[156:157]
	v_pk_mul_f32 v[10:11], v[10:11], v[160:161]
	v_pk_mul_f32 v[6:7], v[6:7], v[164:165]
	s_waitcnt lgkmcnt(0)
	v_pk_mul_f32 v[2:3], v[2:3], v[178:179]
	v_pk_mul_f32 v[0:1], v[0:1], v[176:177]
	v_pk_mul_f32 v[60:61], v[60:61], v[154:155]
	v_pk_mul_f32 v[56:57], v[56:57], v[158:159]
	v_pk_mul_f32 v[52:53], v[52:53], v[162:163]
	v_pk_mul_f32 v[62:63], v[62:63], v[156:157]
	v_pk_mul_f32 v[58:59], v[58:59], v[160:161]
	v_pk_mul_f32 v[54:55], v[54:55], v[164:165]
	v_pk_mul_f32 v[50:51], v[50:51], v[178:179]
	v_pk_mul_f32 v[48:49], v[48:49], v[176:177]
	v_pk_mul_f32 v[44:45], v[44:45], v[154:155]
	v_pk_mul_f32 v[40:41], v[40:41], v[158:159]
	v_pk_mul_f32 v[36:37], v[36:37], v[162:163]
	v_pk_mul_f32 v[46:47], v[46:47], v[156:157]
	v_pk_mul_f32 v[42:43], v[42:43], v[160:161]
	v_pk_mul_f32 v[38:39], v[38:39], v[164:165]
	v_pk_mul_f32 v[34:35], v[34:35], v[178:179]
	v_pk_mul_f32 v[32:33], v[32:33], v[176:177]
	v_pk_mul_f32 v[28:29], v[28:29], v[154:155]
	v_pk_mul_f32 v[24:25], v[24:25], v[158:159]
	v_pk_mul_f32 v[20:21], v[20:21], v[162:163]
	v_pk_mul_f32 v[30:31], v[30:31], v[156:157]
	v_pk_mul_f32 v[26:27], v[26:27], v[160:161]
	v_pk_mul_f32 v[22:23], v[22:23], v[164:165]
	v_pk_mul_f32 v[18:19], v[18:19], v[178:179]
	v_pk_mul_f32 v[16:17], v[16:17], v[176:177]
.LBB0_454:
	v_cndmask_b32_e64 v154, v144, v172, s[4:5]
	v_mul_f32_e32 v176, 0xbdd53b94, v154
	v_fmamk_f32 v187, v66, 0x3dd53b94, v176
	v_fmamk_f32 v185, v64, 0x3dd53b94, v176
	v_fmamk_f32 v186, v65, 0x3dd53b94, v176
	v_fmamk_f32 v188, v67, 0x3dd53b94, v176
	s_cmp_lg_u32 0, -1
	s_cselect_b32 s4, 0, 0
	s_add_i32 s5, s4, s40
	s_add_i32 m0, s5, 0x12000
	v_fmamk_f32 v178, v69, 0x3dd53b94, v176
	s_add_u32 s98, s34, s52
	s_addc_u32 s99, s35, s53
	global_load_lds_dwordx4 v203, s[98:99]
	s_add_i32 m0, s5, 0x14000
	v_fmamk_f32 v179, v70, 0x3dd53b94, v176
	global_load_lds_dwordx4 v204, s[98:99]
	s_add_i32 m0, s5, 0x16000
	v_fmamk_f32 v189, v68, 0x3dd53b94, v176
	global_load_lds_dwordx4 v205, s[98:99]
	v_fmamk_f32 v180, v71, 0x3dd53b94, v176
	s_add_i32 s5, s41, s49
	s_mov_b32 m0, s5
	v_fmamk_f32 v80, v80, 0x3dd53b94, v176
	s_add_u32 s100, s58, s54
	s_addc_u32 s101, s59, s55
	global_load_lds_dwordx4 v206, s[100:101]
	s_add_i32 m0, s5, 0x2000
	v_exp_f32_e32 v144, v80
	global_load_lds_dwordx4 v207, s[100:101]
	v_fmamk_f32 v81, v81, 0x3dd53b94, v176
	v_fmamk_f32 v82, v82, 0x3dd53b94, v176
	v_fmamk_f32 v83, v83, 0x3dd53b94, v176
	v_fmamk_f32 v84, v84, 0x3dd53b94, v176
	v_fmamk_f32 v85, v85, 0x3dd53b94, v176
	v_fmamk_f32 v86, v86, 0x3dd53b94, v176
	v_fmamk_f32 v87, v87, 0x3dd53b94, v176
	v_fmamk_f32 v88, v88, 0x3dd53b94, v176
	v_fmamk_f32 v89, v89, 0x3dd53b94, v176
	v_fmamk_f32 v90, v90, 0x3dd53b94, v176
	v_fmamk_f32 v91, v91, 0x3dd53b94, v176
	v_fmamk_f32 v92, v92, 0x3dd53b94, v176
	v_fmamk_f32 v93, v93, 0x3dd53b94, v176
	v_fmamk_f32 v94, v94, 0x3dd53b94, v176
	v_fmamk_f32 v95, v95, 0x3dd53b94, v176
	v_fmamk_f32 v181, v72, 0x3dd53b94, v176
	v_fmamk_f32 v182, v73, 0x3dd53b94, v176
	v_fmamk_f32 v183, v74, 0x3dd53b94, v176
	v_fmamk_f32 v184, v75, 0x3dd53b94, v176
	v_fmamk_f32 v177, v76, 0x3dd53b94, v176
	v_exp_f32_e32 v172, v81
	v_exp_f32_e32 v145, v82
	v_exp_f32_e32 v165, v83
	v_exp_f32_e32 v146, v84
	v_exp_f32_e32 v164, v85
	v_exp_f32_e32 v147, v86
	v_exp_f32_e32 v163, v87
	v_exp_f32_e32 v160, v88
	v_exp_f32_e32 v162, v89
	v_exp_f32_e32 v159, v90
	v_exp_f32_e32 v161, v91
	v_exp_f32_e32 v156, v92
	v_exp_f32_e32 v158, v93
	v_exp_f32_e32 v155, v94
	v_exp_f32_e32 v157, v95
	v_fmamk_f32 v190, v77, 0x3dd53b94, v176
	v_fmamk_f32 v191, v78, 0x3dd53b94, v176
	v_fmac_f32_e32 v176, 0x3dd53b94, v79
	ds_read_b128 v[64:67], v208 offset:24576
	ds_read_b128 v[68:71], v208 offset:36864
	ds_read_b128 v[222:225], v209 offset:24576
	ds_read_b128 v[226:229], v209 offset:36864
	ds_read_b128 v[230:233], v210 offset:24576
	ds_read_b128 v[234:237], v210 offset:36864
	s_waitcnt lgkmcnt(4)
	v_mfma_f32_32x32x16_bf16 v[80:95], v[64:67], v[140:143], 0
	v_exp_f32_e32 v178, v178
	v_exp_f32_e32 v179, v179
	v_exp_f32_e32 v180, v180
	v_mfma_f32_32x32x16_bf16 v[64:79], v[68:71], v[140:143], 0
	v_exp_f32_e32 v181, v181
	v_exp_f32_e32 v182, v182
	v_exp_f32_e32 v183, v183
	ds_read_b128 v[214:217], v211 offset:24576
	ds_read_b128 v[218:221], v211 offset:36864
	s_waitcnt lgkmcnt(4)
	v_mfma_f32_32x32x16_bf16 v[80:95], v[222:225], v[136:139], v[80:95]
	v_exp_f32_e32 v184, v184
	v_exp_f32_e32 v190, v190
	v_exp_f32_e32 v191, v191
	v_mfma_f32_32x32x16_bf16 v[64:79], v[226:229], v[136:139], v[64:79]
	v_exp_f32_e32 v148, v185
	v_exp_f32_e32 v185, v186
	v_exp_f32_e32 v186, v187
	ds_read_b128 v[222:225], v208 offset:24704
	ds_read_b128 v[226:229], v208 offset:36992
	s_waitcnt lgkmcnt(4)
	v_mfma_f32_32x32x16_bf16 v[80:95], v[230:233], v[132:135], v[80:95]
	v_exp_f32_e32 v187, v188
	v_exp_f32_e32 v188, v189
	v_exp_f32_e32 v189, v177
	v_mfma_f32_32x32x16_bf16 v[64:79], v[234:237], v[132:135], v[64:79]
	v_exp_f32_e32 v194, v176
	v_add_f32_e32 v176, 0, v144
	v_add_f32_e32 v176, v172, v176
	ds_read_b128 v[230:233], v209 offset:24704
	ds_read_b128 v[234:237], v209 offset:36992
	s_waitcnt lgkmcnt(4)
	v_mfma_f32_32x32x16_bf16 v[80:95], v[214:217], v[128:131], v[80:95]
	v_add_f32_e32 v176, v145, v176
	v_add_f32_e32 v176, v165, v176
	v_add_f32_e32 v176, v146, v176
	v_mfma_f32_32x32x16_bf16 v[64:79], v[218:221], v[128:131], v[64:79]
	v_add_f32_e32 v176, v164, v176
	v_add_f32_e32 v176, v147, v176
	v_add_f32_e32 v176, v163, v176
	v_add_f32_e32 v176, v160, v176
	ds_read_b128 v[214:217], v210 offset:24704
	ds_read_b128 v[218:221], v210 offset:36992
	s_waitcnt lgkmcnt(4)
	v_mfma_f32_32x32x16_bf16 v[80:95], v[222:225], v[124:127], v[80:95]
	v_add_f32_e32 v176, v162, v176
	v_add_f32_e32 v176, v159, v176
	v_add_f32_e32 v176, v161, v176
	v_mfma_f32_32x32x16_bf16 v[64:79], v[226:229], v[124:127], v[64:79]
	v_add_f32_e32 v176, v156, v176
	v_add_f32_e32 v176, v158, v176
	v_add_f32_e32 v176, v155, v176
	ds_read_b128 v[222:225], v211 offset:24704
	ds_read_b128 v[226:229], v211 offset:36992
	s_waitcnt lgkmcnt(4)
	v_mfma_f32_32x32x16_bf16 v[80:95], v[230:233], v[120:123], v[80:95]
	v_add_f32_e32 v176, v157, v176
	v_add_f32_e32 v176, v148, v176
	v_add_f32_e32 v176, v185, v176
	v_mfma_f32_32x32x16_bf16 v[64:79], v[234:237], v[120:123], v[64:79]
	v_add_f32_e32 v176, v186, v176
	v_add_f32_e32 v176, v187, v176
	v_add_f32_e32 v176, v188, v176
	ds_read_b128 v[230:233], v208 offset:24832
	ds_read_b128 v[234:237], v208 offset:37120
	s_waitcnt lgkmcnt(4)
	v_mfma_f32_32x32x16_bf16 v[80:95], v[214:217], v[116:119], v[80:95]
	v_add_f32_e32 v176, v178, v176
	v_add_f32_e32 v176, v179, v176
	v_add_f32_e32 v176, v180, v176
	v_mfma_f32_32x32x16_bf16 v[64:79], v[218:221], v[116:119], v[64:79]
	v_add_f32_e32 v176, v181, v176
	v_add_f32_e32 v176, v182, v176
	v_add_f32_e32 v176, v183, v176
	ds_read_b128 v[214:217], v209 offset:24832
	ds_read_b128 v[218:221], v209 offset:37120
	s_waitcnt lgkmcnt(4)
	v_mfma_f32_32x32x16_bf16 v[80:95], v[222:225], v[112:115], v[80:95]
	v_add_f32_e32 v176, v184, v176
	v_add_f32_e32 v176, v189, v176
	v_add_f32_e32 v176, v190, v176
	v_mfma_f32_32x32x16_bf16 v[64:79], v[226:229], v[112:115], v[64:79]
	v_add_f32_e32 v176, v191, v176
	v_add_f32_e32 v192, v194, v176
	v_mov_b32_e32 v193, v192
	v_cvt_pk_bf16_f32 v144, v144, v172
	ds_read_b128 v[222:225], v210 offset:24832
	ds_read_b128 v[226:229], v210 offset:37120
	s_waitcnt lgkmcnt(4)
	v_mfma_f32_32x32x16_bf16 v[80:95], v[230:233], v[108:111], v[80:95]
	v_cvt_pk_bf16_f32 v145, v145, v165
	v_cvt_pk_bf16_f32 v146, v146, v164
	s_nop 1
	v_mfma_f32_32x32x16_bf16 v[64:79], v[234:237], v[108:111], v[64:79]
	v_permlane32_swap_b32_e32 v192, v193
	v_cvt_pk_bf16_f32 v147, v147, v163
	v_permlane32_swap_b32_e32 v144, v146
	ds_read_b128 v[230:233], v211 offset:24832
	ds_read_b128 v[234:237], v211 offset:37120
	s_waitcnt lgkmcnt(4)
	v_mfma_f32_32x32x16_bf16 v[80:95], v[214:217], v[104:107], v[80:95]
	v_cvt_pk_bf16_f32 v160, v160, v162
	v_cvt_pk_bf16_f32 v161, v159, v161
	v_cvt_pk_bf16_f32 v162, v156, v158
	v_mfma_f32_32x32x16_bf16 v[64:79], v[218:221], v[104:107], v[64:79]
	v_cvt_pk_bf16_f32 v163, v155, v157
	v_cvt_pk_bf16_f32 v156, v148, v185
	v_cvt_pk_bf16_f32 v157, v186, v187
	s_waitcnt lgkmcnt(2)
	v_mfma_f32_32x32x16_bf16 v[80:95], v[222:225], v[100:103], v[80:95]
	v_cvt_pk_bf16_f32 v158, v188, v178
	v_cvt_pk_bf16_f32 v159, v179, v180
	v_cvt_pk_bf16_f32 v176, v181, v182
	v_mfma_f32_32x32x16_bf16 v[64:79], v[226:229], v[100:103], v[64:79]
	v_cvt_pk_bf16_f32 v177, v183, v184
	v_cvt_pk_bf16_f32 v178, v189, v190
	v_cvt_pk_bf16_f32 v179, v191, v194
	s_waitcnt lgkmcnt(0)
	v_mfma_f32_32x32x16_bf16 v[80:95], v[230:233], v[96:99], v[80:95]
	v_permlane32_swap_b32_e32 v145, v147
	v_permlane32_swap_b32_e32 v160, v162
	v_permlane32_swap_b32_e32 v161, v163
	v_mfma_f32_32x32x16_bf16 v[64:79], v[234:237], v[96:99], v[64:79]
	v_permlane32_swap_b32_e32 v156, v158
	v_permlane32_swap_b32_e32 v157, v159
	v_permlane32_swap_b32_e32 v176, v178
	v_permlane32_swap_b32_e32 v177, v179
	s_add_i32 s4, s51, s4
	v_add_u32_e32 v148, s4, v212
	ds_read_b64_tr_b16 v[180:181], v148 offset:0
	ds_read_b64_tr_b16 v[182:183], v148 offset:0x800
	ds_read_b64_tr_b16 v[184:185], v148 offset:0x1000
	ds_read_b64_tr_b16 v[186:187], v148 offset:0x1800
	ds_read_b64_tr_b16 v[188:189], v148 offset:0x2000
	ds_read_b64_tr_b16 v[190:191], v148 offset:0x2800
	ds_read_b64_tr_b16 v[194:195], v148 offset:0x3000
	ds_read_b64_tr_b16 v[196:197], v148 offset:0x3800
	s_waitcnt lgkmcnt(0)
	s_nop 0
	v_mfma_f32_32x32x16_bf16 v[0:15], v[144:147], v[180:183], v[0:15]
	ds_read_b64_tr_b16 v[180:181], v148 offset:0x200
	ds_read_b64_tr_b16 v[182:183], v148 offset:0xa00
	v_mfma_f32_32x32x16_bf16 v[0:15], v[160:163], v[184:187], v[0:15]
	ds_read_b64_tr_b16 v[184:185], v148 offset:0x1200
	ds_read_b64_tr_b16 v[186:187], v148 offset:0x1a00
	v_mfma_f32_32x32x16_bf16 v[0:15], v[156:159], v[188:191], v[0:15]
	ds_read_b64_tr_b16 v[188:189], v148 offset:0x2200
	ds_read_b64_tr_b16 v[190:191], v148 offset:0x2a00
	v_mfma_f32_32x32x16_bf16 v[0:15], v[176:179], v[194:197], v[0:15]
	ds_read_b64_tr_b16 v[194:195], v148 offset:0x3200
	ds_read_b64_tr_b16 v[196:197], v148 offset:0x3a00
	s_waitcnt lgkmcnt(0)
	v_mfma_f32_32x32x16_bf16 v[48:63], v[144:147], v[180:183], v[48:63]
	ds_read_b64_tr_b16 v[180:181], v148 offset:0x400
	ds_read_b64_tr_b16 v[182:183], v148 offset:0xc00
	v_mfma_f32_32x32x16_bf16 v[48:63], v[160:163], v[184:187], v[48:63]
	ds_read_b64_tr_b16 v[184:185], v148 offset:0x1400
	ds_read_b64_tr_b16 v[186:187], v148 offset:0x1c00
	v_mfma_f32_32x32x16_bf16 v[48:63], v[156:159], v[188:191], v[48:63]
	ds_read_b64_tr_b16 v[188:189], v148 offset:0x2400
	ds_read_b64_tr_b16 v[190:191], v148 offset:0x2c00
	v_mfma_f32_32x32x16_bf16 v[48:63], v[176:179], v[194:197], v[48:63]
	ds_read_b64_tr_b16 v[194:195], v148 offset:0x3400
	ds_read_b64_tr_b16 v[196:197], v148 offset:0x3c00
	s_waitcnt lgkmcnt(0)
	v_mfma_f32_32x32x16_bf16 v[32:47], v[144:147], v[180:183], v[32:47]
	ds_read_b64_tr_b16 v[180:181], v148 offset:0x600
	ds_read_b64_tr_b16 v[182:183], v148 offset:0xe00
	v_mfma_f32_32x32x16_bf16 v[32:47], v[160:163], v[184:187], v[32:47]
	ds_read_b64_tr_b16 v[184:185], v148 offset:0x1600
	ds_read_b64_tr_b16 v[186:187], v148 offset:0x1e00
	v_mfma_f32_32x32x16_bf16 v[32:47], v[156:159], v[188:191], v[32:47]
	ds_read_b64_tr_b16 v[188:189], v148 offset:0x2600
	ds_read_b64_tr_b16 v[190:191], v148 offset:0x2e00
	v_mfma_f32_32x32x16_bf16 v[32:47], v[176:179], v[194:197], v[32:47]
	ds_read_b64_tr_b16 v[194:195], v148 offset:0x3600
	ds_read_b64_tr_b16 v[196:197], v148 offset:0x3e00
	s_waitcnt lgkmcnt(0)
	v_mfma_f32_32x32x16_bf16 v[16:31], v[144:147], v[180:183], v[16:31]
	v_max_f32_e32 v144, v81, v81
	v_max_f32_e32 v145, v80, v80
	v_max_f32_e32 v144, v145, v144
	v_max3_f32 v144, v144, v82, v83
	v_max3_f32 v144, v144, v84, v85
	v_max3_f32 v144, v144, v86, v87
	v_max3_f32 v144, v144, v88, v89
	v_max3_f32 v144, v144, v90, v91
	v_max3_f32 v144, v144, v92, v93
	v_mfma_f32_32x32x16_bf16 v[16:31], v[160:163], v[184:187], v[16:31]
	v_max3_f32 v144, v144, v94, v95
	v_max3_f32 v144, v144, v64, v65
	v_max3_f32 v144, v144, v66, v67
	v_max3_f32 v144, v144, v68, v69
	v_max3_f32 v144, v144, v70, v71
	v_max3_f32 v144, v144, v72, v73
	v_max3_f32 v144, v144, v74, v75
	v_max3_f32 v144, v144, v76, v77
	v_mfma_f32_32x32x16_bf16 v[16:31], v[156:159], v[188:191], v[16:31]
	v_max3_f32 v144, v144, v78, v79
	v_mov_b32_e32 v145, v144
	s_nop 1
	v_permlane32_swap_b32_e32 v144, v145
	v_max_f32_e32 v145, v145, v145
	v_max_f32_e32 v144, v144, v144
	v_max_f32_e32 v144, v144, v145
	v_sub_f32_e32 v145, v144, v154
	v_cmp_ge_f32_e32 vcc, s37, v145
	v_max_f32_e32 v145, v154, v154
	v_max_f32_e32 v144, v145, v144
	v_mfma_f32_32x32x16_bf16 v[16:31], v[176:179], v[194:197], v[16:31]
	v_sub_f32_e32 v145, v154, v144
	v_mul_f32_e32 v145, 0x3dd53b94, v145
	v_exp_f32_e32 v145, v145
	s_cmp_eq_u64 vcc, exec
	s_cselect_b64 s[4:5], -1, 0
	s_waitcnt vmcnt(0)
	v_cndmask_b32_e64 v148, v145, 1.0, s[4:5]
	v_cmp_gt_f32_e32 vcc, 1.0, v148
	s_waitcnt vmcnt(0)
	s_barrier
	s_cbranch_vccz .LBB0_458
	s_and_saveexec_b64 s[34:35], s[2:3]
	ds_write_b32 v153, v148 offset:128
	s_or_b64 exec, exec, s[34:35]
	s_waitcnt lgkmcnt(0)
	v_add_u32_e32 v145, v151, v152
	ds_read_b128 v[156:159], v145 offset:224
	ds_read_b128 v[160:163], v145 offset:192
	ds_read_b128 v[176:179], v145 offset:160
	ds_read_b128 v[180:183], v145 offset:128
	s_waitcnt lgkmcnt(3)
	v_pk_mul_f32 v[12:13], v[12:13], v[156:157]
	s_waitcnt lgkmcnt(2)
	v_pk_mul_f32 v[8:9], v[8:9], v[160:161]
	s_waitcnt lgkmcnt(1)
	v_pk_mul_f32 v[4:5], v[4:5], v[176:177]
	v_pk_mul_f32 v[14:15], v[14:15], v[158:159]
	v_pk_mul_f32 v[10:11], v[10:11], v[162:163]
	v_pk_mul_f32 v[6:7], v[6:7], v[178:179]
	s_waitcnt lgkmcnt(0)
	v_pk_mul_f32 v[2:3], v[2:3], v[182:183]
	v_pk_mul_f32 v[0:1], v[0:1], v[180:181]
	v_pk_mul_f32 v[60:61], v[60:61], v[156:157]
	v_pk_mul_f32 v[56:57], v[56:57], v[160:161]
	v_pk_mul_f32 v[52:53], v[52:53], v[176:177]
	v_pk_mul_f32 v[62:63], v[62:63], v[158:159]
	v_pk_mul_f32 v[58:59], v[58:59], v[162:163]
	v_pk_mul_f32 v[54:55], v[54:55], v[178:179]
	v_pk_mul_f32 v[50:51], v[50:51], v[182:183]
	v_pk_mul_f32 v[48:49], v[48:49], v[180:181]
	v_pk_mul_f32 v[44:45], v[44:45], v[156:157]
	v_pk_mul_f32 v[40:41], v[40:41], v[160:161]
	v_pk_mul_f32 v[36:37], v[36:37], v[176:177]
	v_pk_mul_f32 v[46:47], v[46:47], v[158:159]
	v_pk_mul_f32 v[42:43], v[42:43], v[162:163]
	v_pk_mul_f32 v[38:39], v[38:39], v[178:179]
	v_pk_mul_f32 v[34:35], v[34:35], v[182:183]
	v_pk_mul_f32 v[32:33], v[32:33], v[180:181]
	v_pk_mul_f32 v[28:29], v[28:29], v[156:157]
	v_pk_mul_f32 v[24:25], v[24:25], v[160:161]
	v_pk_mul_f32 v[20:21], v[20:21], v[176:177]
	v_pk_mul_f32 v[30:31], v[30:31], v[158:159]
	v_pk_mul_f32 v[26:27], v[26:27], v[162:163]
	v_pk_mul_f32 v[22:23], v[22:23], v[178:179]
	v_pk_mul_f32 v[18:19], v[18:19], v[182:183]
	v_pk_mul_f32 v[16:17], v[16:17], v[180:181]

.LBB0_495:
	s_add_u32 s50, s2, s56
	ds_read_b128 v[0:3], v70
	ds_read_b128 v[4:7], v70 offset:1024
	ds_read_b128 v[8:11], v70 offset:2048
	ds_read_b128 v[12:15], v70 offset:3072
	s_addc_u32 s51, s3, s57
	s_and_b64 s[48:49], s[60:61], exec
	s_cselect_b32 s57, s51, s59
	s_cselect_b32 s56, s50, s58
	s_add_u32 s50, s14, s62
	s_addc_u32 s51, s15, s63
	s_and_b64 s[48:49], s[60:61], exec
	s_cselect_b32 s5, s51, s5
	s_cselect_b32 s4, s50, s4
	v_lshl_add_u64 v[48:49], s[58:59], 0, v[66:67]
	s_mov_b32 m0, s37
	v_lshl_add_u64 v[50:51], v[48:49], 0, s[52:53]
	ds_read_b128 v[16:19], v71
	ds_read_b128 v[20:23], v71 offset:1024
	ds_read_b128 v[24:27], v71 offset:2048
	ds_read_b128 v[28:31], v71 offset:3072
	ds_read_b128 v[32:35], v71 offset:4096
	ds_read_b128 v[36:39], v71 offset:5120
	ds_read_b128 v[40:43], v71 offset:6144
	ds_read_b128 v[44:47], v71 offset:7168
	global_load_lds_dwordx4 v[50:51], off
	v_lshl_add_u64 v[48:49], v[48:49], 0, s[54:55]
	s_mov_b32 m0, s38
	s_nop 0
	global_load_lds_dwordx4 v[48:49], off
	s_waitcnt lgkmcnt(8)
	s_barrier
	s_waitcnt lgkmcnt(0)
	s_waitcnt lgkmcnt(0)
	v_mfma_f32_16x16x32_bf16 v[52:55], v[8:11], v[16:19], 0
	v_mfma_f32_16x16x32_bf16 v[56:59], v[12:15], v[20:23], v[52:55]
	v_mfma_f32_16x16x32_bf16 v[52:55], v[0:3], v[24:27], 0
	v_mfma_f32_16x16x32_bf16 v[60:63], v[4:7], v[28:31], v[52:55]
	v_mfma_f32_16x16x32_bf16 v[52:55], v[8:11], v[24:27], 0
	v_mfma_f32_16x16x32_bf16 v[48:51], v[0:3], v[16:19], 0
	v_mfma_f32_16x16x32_bf16 v[76:79], v[12:15], v[28:31], v[52:55]
	v_mfma_f32_16x16x32_bf16 v[52:55], v[0:3], v[32:35], 0
	v_mfma_f32_16x16x32_bf16 v[0:3], v[0:3], v[40:43], 0
	v_mfma_f32_16x16x32_bf16 v[48:51], v[4:7], v[20:23], v[48:51]
	v_mfma_f32_16x16x32_bf16 v[80:83], v[4:7], v[36:39], v[52:55]
	v_mfma_f32_16x16x32_bf16 v[0:3], v[4:7], v[44:47], v[0:3]
	v_mfma_f32_16x16x32_bf16 v[4:7], v[8:11], v[40:43], 0
	v_mfma_f32_16x16x32_bf16 v[52:55], v[8:11], v[32:35], 0
	v_mfma_f32_16x16x32_bf16 v[8:11], v[12:15], v[44:47], v[4:7]
	v_mfma_f32_16x16x32_bf16 v[84:87], v[12:15], v[36:39], v[52:55]
	s_barrier
	s_mov_b32 m0, s39
	v_lshl_add_u64 v[144:145], s[4:5], 0, v[64:65]
	s_nop 0
	ds_read_b128 v[4:7], v72
	ds_read_b128 v[12:15], v72 offset:1024
	ds_read_b128 v[52:55], v72 offset:2048
	ds_read_b128 v[88:91], v72 offset:3072
	global_load_lds_dwordx4 v[144:145], off
	v_lshl_add_u64 v[92:93], v[144:145], 0, s[6:7]
	s_mov_b32 m0, s40
	s_nop 0
	global_load_lds_dwordx4 v[92:93], off
	s_barrier
	s_waitcnt lgkmcnt(0)
	s_waitcnt lgkmcnt(0)
	v_mfma_f32_16x16x32_bf16 v[92:95], v[4:7], v[16:19], 0
	v_mfma_f32_16x16x32_bf16 v[16:19], v[52:55], v[16:19], 0
	v_mfma_f32_16x16x32_bf16 v[96:99], v[88:91], v[20:23], v[16:19]
	v_mfma_f32_16x16x32_bf16 v[16:19], v[4:7], v[24:27], 0
	v_mfma_f32_16x16x32_bf16 v[100:103], v[12:15], v[28:31], v[16:19]
	v_mfma_f32_16x16x32_bf16 v[16:19], v[52:55], v[24:27], 0
	v_mfma_f32_16x16x32_bf16 v[24:27], v[88:91], v[28:31], v[16:19]
	v_mfma_f32_16x16x32_bf16 v[16:19], v[4:7], v[32:35], 0
	v_mfma_f32_16x16x32_bf16 v[4:7], v[4:7], v[40:43], 0
	v_mfma_f32_16x16x32_bf16 v[92:95], v[12:15], v[20:23], v[92:95]
	v_mfma_f32_16x16x32_bf16 v[28:31], v[12:15], v[36:39], v[16:19]
	v_mfma_f32_16x16x32_bf16 v[16:19], v[52:55], v[32:35], 0
	v_mfma_f32_16x16x32_bf16 v[12:15], v[12:15], v[44:47], v[4:7]
	v_mfma_f32_16x16x32_bf16 v[4:7], v[52:55], v[40:43], 0
	v_mfma_f32_16x16x32_bf16 v[104:107], v[88:91], v[36:39], v[16:19]
	v_mfma_f32_16x16x32_bf16 v[88:91], v[88:91], v[44:47], v[4:7]
	s_mov_b32 m0, s17
	v_lshl_add_u64 v[146:147], s[56:57], 0, v[66:67]
	s_barrier
	global_load_lds_dwordx4 v[146:147], off
	s_nop 0
	v_lshl_add_u64 v[4:5], v[146:147], 0, s[6:7]
	s_mov_b32 m0, s20
	s_nop 0
	global_load_lds_dwordx4 v[4:5], off
	s_barrier
	s_waitcnt lgkmcnt(0)
	s_barrier
	s_mov_b32 m0, s41
	v_lshl_add_u64 v[4:5], v[144:145], 0, s[22:23]
	global_load_lds_dwordx4 v[4:5], off
	v_lshl_add_u64 v[4:5], v[144:145], 0, s[24:25]
	s_mov_b32 m0, s42
	s_nop 0
	global_load_lds_dwordx4 v[4:5], off
	s_waitcnt vmcnt(6)
	s_barrier
	s_barrier
	ds_read_b128 v[4:7], v73
	ds_read_b128 v[40:43], v73 offset:1024
	ds_read_b128 v[44:47], v73 offset:2048
	ds_read_b128 v[108:111], v73 offset:3072
	s_mov_b32 m0, s21
	v_lshl_add_u64 v[16:17], v[146:147], 0, s[22:23]
	ds_read_b128 v[112:115], v71 offset:32768
	ds_read_b128 v[116:119], v71 offset:33792
	ds_read_b128 v[120:123], v71 offset:34816
	ds_read_b128 v[124:127], v71 offset:35840
	ds_read_b128 v[128:131], v71 offset:36864
	ds_read_b128 v[132:135], v71 offset:37888
	ds_read_b128 v[136:139], v71 offset:38912
	ds_read_b128 v[140:143], v71 offset:39936
	global_load_lds_dwordx4 v[16:17], off
	v_lshl_add_u64 v[16:17], v[146:147], 0, s[24:25]
	s_mov_b32 m0, s28
	s_nop 0
	global_load_lds_dwordx4 v[16:17], off
	s_waitcnt lgkmcnt(8)
	s_barrier
	s_waitcnt lgkmcnt(0)
	s_waitcnt lgkmcnt(0)
	v_mfma_f32_16x16x32_bf16 v[16:19], v[4:7], v[112:115], v[48:51]
	v_mfma_f32_16x16x32_bf16 v[52:55], v[40:43], v[116:119], v[16:19]
	v_mfma_f32_16x16x32_bf16 v[16:19], v[44:47], v[112:115], v[56:59]
	v_mfma_f32_16x16x32_bf16 v[48:51], v[108:111], v[116:119], v[16:19]
	v_mfma_f32_16x16x32_bf16 v[16:19], v[4:7], v[120:123], v[60:63]
	v_mfma_f32_16x16x32_bf16 v[36:39], v[40:43], v[124:127], v[16:19]
	v_mfma_f32_16x16x32_bf16 v[16:19], v[44:47], v[120:123], v[76:79]
	v_mfma_f32_16x16x32_bf16 v[32:35], v[108:111], v[124:127], v[16:19]
	v_mfma_f32_16x16x32_bf16 v[16:19], v[4:7], v[128:131], v[80:83]
	v_mfma_f32_16x16x32_bf16 v[0:3], v[4:7], v[136:139], v[0:3]
	v_mfma_f32_16x16x32_bf16 v[20:23], v[40:43], v[132:135], v[16:19]
	v_mfma_f32_16x16x32_bf16 v[16:19], v[44:47], v[128:131], v[84:87]
	v_mfma_f32_16x16x32_bf16 v[4:7], v[40:43], v[140:143], v[0:3]
	v_mfma_f32_16x16x32_bf16 v[0:3], v[44:47], v[136:139], v[8:11]
	v_mfma_f32_16x16x32_bf16 v[16:19], v[108:111], v[132:135], v[16:19]
	v_mfma_f32_16x16x32_bf16 v[0:3], v[108:111], v[140:143], v[0:3]
	s_barrier
	s_mov_b32 m0, s43
	v_lshl_add_u64 v[40:41], v[144:145], 0, s[26:27]
	ds_read_b128 v[8:11], v74
	ds_read_b128 v[76:79], v74 offset:1024
	ds_read_b128 v[80:83], v74 offset:2048
	ds_read_b128 v[84:87], v74 offset:3072
	global_load_lds_dwordx4 v[40:41], off
	v_lshl_add_u64 v[40:41], v[144:145], 0, s[34:35]
	s_mov_b32 m0, s44
	s_nop 0
	global_load_lds_dwordx4 v[40:41], off
	s_barrier
	s_waitcnt lgkmcnt(0)
	s_waitcnt lgkmcnt(0)
	v_mfma_f32_16x16x32_bf16 v[40:43], v[8:11], v[112:115], v[92:95]
	v_mfma_f32_16x16x32_bf16 v[60:63], v[76:79], v[116:119], v[40:43]
	v_mfma_f32_16x16x32_bf16 v[40:43], v[80:83], v[112:115], v[96:99]
	v_mfma_f32_16x16x32_bf16 v[56:59], v[84:87], v[116:119], v[40:43]
	v_mfma_f32_16x16x32_bf16 v[40:43], v[8:11], v[120:123], v[100:103]
	v_mfma_f32_16x16x32_bf16 v[24:27], v[80:83], v[120:123], v[24:27]
	v_mfma_f32_16x16x32_bf16 v[44:47], v[76:79], v[124:127], v[40:43]
	v_mfma_f32_16x16x32_bf16 v[40:43], v[84:87], v[124:127], v[24:27]
	v_mfma_f32_16x16x32_bf16 v[24:27], v[8:11], v[128:131], v[28:31]
	v_mfma_f32_16x16x32_bf16 v[8:11], v[8:11], v[136:139], v[12:15]
	v_mfma_f32_16x16x32_bf16 v[28:31], v[76:79], v[132:135], v[24:27]
	v_mfma_f32_16x16x32_bf16 v[24:27], v[80:83], v[128:131], v[104:107]
	v_mfma_f32_16x16x32_bf16 v[12:15], v[76:79], v[140:143], v[8:11]
	v_mfma_f32_16x16x32_bf16 v[8:11], v[80:83], v[136:139], v[88:91]
	v_mfma_f32_16x16x32_bf16 v[24:27], v[84:87], v[132:135], v[24:27]
	v_mfma_f32_16x16x32_bf16 v[8:11], v[84:87], v[140:143], v[8:11]
	s_mov_b32 m0, s31
	v_lshl_add_u64 v[76:77], v[146:147], 0, s[26:27]
	s_barrier
	global_load_lds_dwordx4 v[76:77], off
	v_lshl_add_u64 v[76:77], v[146:147], 0, s[34:35]
	s_mov_b32 m0, s33
	s_nop 0
	global_load_lds_dwordx4 v[76:77], off
	s_barrier
	s_waitcnt lgkmcnt(0)
	s_barrier
	s_mov_b32 m0, s45
	v_lshl_add_u64 v[76:77], v[144:145], 0, s[52:53]
	global_load_lds_dwordx4 v[76:77], off
	v_lshl_add_u64 v[76:77], v[144:145], 0, s[54:55]
	s_mov_b32 m0, s46
	s_nop 0
	global_load_lds_dwordx4 v[76:77], off
	s_waitcnt vmcnt(6)
	s_barrier
	v_mov_b32_e32 v68, v166
	s_mov_b32 s49, s16
	s_mov_b32 s48, s30
	s_barrier
	s_cmp_lg_u32 s49, 0
	s_cbranch_scc1 .LBB0_497
	s_ashr_i32 s49, s47, 2
	s_lshl_b32 s50, s47, 8
	s_lshl_b32 s47, s47, 11
	v_lshrrev_b32_e32 v75, 1, v68
	s_and_b32 s47, s47, 0x1000
	v_lshlrev_b32_e32 v68, 6, v68
	s_and_b32 s50, s50, 0x100
	s_lshl_b32 s48, s48, 5
	v_and_b32_e32 v68, 0x3c0, v68
	s_add_i32 s47, s47, s49
	s_add_i32 s48, s48, s50
	v_add_u32_e32 v78, s47, v68
	v_and_or_b32 v76, v75, 24, s48
	v_ashrrev_i32_e32 v79, 31, v78
	v_ashrrev_i32_e32 v77, 31, v76
	v_lshlrev_b64 v[80:81], 12, v[78:79]
	v_lshl_add_u64 v[80:81], s[10:11], 0, v[80:81]
	v_lshlrev_b64 v[76:77], 1, v[76:77]
	v_lshl_add_u64 v[80:81], v[80:81], 0, v[76:77]
	v_cvt_pk_bf16_f32 v52, v52, v53
	v_cvt_pk_bf16_f32 v53, v54, v55
	v_cvt_pk_bf16_f32 v54, v48, v49
	v_cvt_pk_bf16_f32 v55, v50, v51
	global_store_dwordx4 v[80:81], v[52:55], off
	v_cvt_pk_bf16_f32 v48, v60, v61
	v_cvt_pk_bf16_f32 v49, v62, v63
	v_add_u32_e32 v68, 0x400, v78
	v_cvt_pk_bf16_f32 v50, v56, v57
	v_cvt_pk_bf16_f32 v51, v58, v59
	global_store_dwordx4 v[80:81], v[48:51], off offset:256
	v_cvt_pk_bf16_f32 v36, v36, v37
	v_cvt_pk_bf16_f32 v37, v38, v39
	v_cvt_pk_bf16_f32 v38, v32, v33
	v_cvt_pk_bf16_f32 v39, v34, v35
	s_nop 1
	v_lshlrev_b64 v[48:49], 12, v[68:69]
	v_lshl_add_u64 v[48:49], s[10:11], 0, v[48:49]
	v_lshl_add_u64 v[48:49], v[48:49], 0, v[76:77]
	global_store_dwordx4 v[48:49], v[36:39], off
	v_cvt_pk_bf16_f32 v32, v44, v45
	v_cvt_pk_bf16_f32 v33, v46, v47
	v_add_u32_e32 v68, 0x800, v78
	v_cvt_pk_bf16_f32 v34, v40, v41
	v_cvt_pk_bf16_f32 v35, v42, v43
	global_store_dwordx4 v[48:49], v[32:35], off offset:256
	v_cvt_pk_bf16_f32 v20, v20, v21
	v_cvt_pk_bf16_f32 v21, v22, v23
	v_cvt_pk_bf16_f32 v22, v16, v17
	v_cvt_pk_bf16_f32 v23, v18, v19
	s_nop 1
	v_lshlrev_b64 v[32:33], 12, v[68:69]
	v_lshl_add_u64 v[32:33], s[10:11], 0, v[32:33]
	v_lshl_add_u64 v[32:33], v[32:33], 0, v[76:77]
	global_store_dwordx4 v[32:33], v[20:23], off
	v_cvt_pk_bf16_f32 v16, v28, v29
	v_cvt_pk_bf16_f32 v17, v30, v31
	v_add_u32_e32 v68, 0xc00, v78
	v_cvt_pk_bf16_f32 v18, v24, v25
	v_cvt_pk_bf16_f32 v19, v26, v27
	global_store_dwordx4 v[32:33], v[16:19], off offset:256
	v_cvt_pk_bf16_f32 v4, v4, v5
	v_cvt_pk_bf16_f32 v5, v6, v7
	v_cvt_pk_bf16_f32 v6, v0, v1
	v_cvt_pk_bf16_f32 v7, v2, v3
	s_nop 1
	v_lshlrev_b64 v[16:17], 12, v[68:69]
	v_lshl_add_u64 v[16:17], s[10:11], 0, v[16:17]
	v_lshl_add_u64 v[16:17], v[16:17], 0, v[76:77]
	global_store_dwordx4 v[16:17], v[4:7], off
	v_cvt_pk_bf16_f32 v0, v12, v13
	v_cvt_pk_bf16_f32 v1, v14, v15
	v_cvt_pk_bf16_f32 v2, v8, v9
	v_cvt_pk_bf16_f32 v3, v10, v11
	global_store_dwordx4 v[16:17], v[0:3], off offset:256

.LBB0_513:
	ds_read_b128 v[140:143], v137
	ds_read_b128 v[144:147], v137 offset:1024
	ds_read_b128 v[148:151], v137 offset:2048
	ds_read_b128 v[152:155], v137 offset:3072
	s_add_u32 s44, s60, 0xfffe0080
	s_addc_u32 s45, s61, -1
	s_cmp_eq_u32 s43, 4
	s_cselect_b32 s45, s53, s45
	s_cselect_b32 s44, s52, s44
	s_cselect_b32 s47, s55, s42
	s_cselect_b32 s46, s54, s18
	s_mov_b32 m0, s37
	v_lshl_add_u64 v[134:135], s[60:61], 0, v[132:133]
	ds_read_b128 v[156:159], v138
	ds_read_b128 v[160:163], v138 offset:1024
	ds_read_b128 v[168:171], v138 offset:2048
	ds_read_b128 v[172:175], v138 offset:3072
	ds_read_b128 v[176:179], v138 offset:4096
	ds_read_b128 v[180:183], v138 offset:5120
	ds_read_b128 v[184:187], v138 offset:6144
	ds_read_b128 v[188:191], v138 offset:7168
	global_load_lds_dwordx4 v[134:135], off
	v_lshl_add_u64 v[134:135], v[134:135], 0, s[2:3]
	s_mov_b32 m0, s38
	s_nop 0
	global_load_lds_dwordx4 v[134:135], off
	s_waitcnt lgkmcnt(8)
	s_barrier
	s_waitcnt lgkmcnt(0)
	s_waitcnt lgkmcnt(0)
	v_mfma_f32_16x16x32_bf16 v[124:127], v[140:143], v[156:159], v[124:127]
	v_mfma_f32_16x16x32_bf16 v[120:123], v[148:151], v[156:159], v[120:123]
	v_mfma_f32_16x16x32_bf16 v[108:111], v[140:143], v[168:171], v[108:111]
	v_mfma_f32_16x16x32_bf16 v[104:107], v[148:151], v[168:171], v[104:107]
	v_mfma_f32_16x16x32_bf16 v[92:95], v[140:143], v[176:179], v[92:95]
	v_mfma_f32_16x16x32_bf16 v[88:91], v[148:151], v[176:179], v[88:91]
	v_mfma_f32_16x16x32_bf16 v[76:79], v[140:143], v[184:187], v[76:79]
	v_mfma_f32_16x16x32_bf16 v[72:75], v[148:151], v[184:187], v[72:75]
	v_mfma_f32_16x16x32_bf16 v[124:127], v[144:147], v[160:163], v[124:127]
	v_mfma_f32_16x16x32_bf16 v[120:123], v[152:155], v[160:163], v[120:123]
	v_mfma_f32_16x16x32_bf16 v[108:111], v[144:147], v[172:175], v[108:111]
	v_mfma_f32_16x16x32_bf16 v[104:107], v[152:155], v[172:175], v[104:107]
	v_mfma_f32_16x16x32_bf16 v[92:95], v[144:147], v[180:183], v[92:95]
	v_mfma_f32_16x16x32_bf16 v[88:91], v[152:155], v[180:183], v[88:91]
	v_mfma_f32_16x16x32_bf16 v[76:79], v[144:147], v[188:191], v[76:79]
	v_mfma_f32_16x16x32_bf16 v[72:75], v[152:155], v[188:191], v[72:75]
	s_barrier
	s_mov_b32 m0, s39
	v_lshl_add_u64 v[134:135], s[46:47], 0, v[128:129]
	ds_read_b128 v[192:195], v139
	ds_read_b128 v[196:199], v139 offset:1024
	ds_read_b128 v[200:203], v139 offset:2048
	ds_read_b128 v[204:207], v139 offset:3072
	global_load_lds_dwordx4 v[134:135], off
	v_lshl_add_u64 v[164:165], v[134:135], 0, s[2:3]
	s_mov_b32 m0, s40
	s_nop 0
	global_load_lds_dwordx4 v[164:165], off
	s_barrier
	s_waitcnt lgkmcnt(0)
	s_waitcnt lgkmcnt(0)
	v_mfma_f32_16x16x32_bf16 v[116:119], v[192:195], v[156:159], v[116:119]
	v_mfma_f32_16x16x32_bf16 v[112:115], v[200:203], v[156:159], v[112:115]
	v_mfma_f32_16x16x32_bf16 v[100:103], v[192:195], v[168:171], v[100:103]
	v_mfma_f32_16x16x32_bf16 v[96:99], v[200:203], v[168:171], v[96:99]
	v_mfma_f32_16x16x32_bf16 v[84:87], v[192:195], v[176:179], v[84:87]
	v_mfma_f32_16x16x32_bf16 v[80:83], v[200:203], v[176:179], v[80:83]
	v_mfma_f32_16x16x32_bf16 v[68:71], v[192:195], v[184:187], v[68:71]
	v_mfma_f32_16x16x32_bf16 v[64:67], v[200:203], v[184:187], v[64:67]
	v_mfma_f32_16x16x32_bf16 v[116:119], v[196:199], v[160:163], v[116:119]
	v_mfma_f32_16x16x32_bf16 v[112:115], v[204:207], v[160:163], v[112:115]
	v_mfma_f32_16x16x32_bf16 v[100:103], v[196:199], v[172:175], v[100:103]
	v_mfma_f32_16x16x32_bf16 v[96:99], v[204:207], v[172:175], v[96:99]
	v_mfma_f32_16x16x32_bf16 v[84:87], v[196:199], v[180:183], v[84:87]
	v_mfma_f32_16x16x32_bf16 v[80:83], v[204:207], v[180:183], v[80:83]
	v_mfma_f32_16x16x32_bf16 v[68:71], v[196:199], v[188:191], v[68:71]
	v_mfma_f32_16x16x32_bf16 v[64:67], v[204:207], v[188:191], v[64:67]
	s_mov_b32 m0, s20
	v_lshl_add_u64 v[164:165], s[44:45], 0, v[130:131]
	s_barrier
	ds_read_b128 v[156:159], v138 offset:16384
	ds_read_b128 v[160:163], v138 offset:17408
	ds_read_b128 v[168:171], v138 offset:18432
	ds_read_b128 v[172:175], v138 offset:19456
	ds_read_b128 v[176:179], v138 offset:20480
	ds_read_b128 v[180:183], v138 offset:21504
	ds_read_b128 v[184:187], v138 offset:22528
	ds_read_b128 v[188:191], v138 offset:23552
	global_load_lds_dwordx4 v[164:165], off
	v_lshl_add_u64 v[208:209], v[164:165], 0, s[2:3]
	s_mov_b32 m0, s21
	s_nop 0
	global_load_lds_dwordx4 v[208:209], off
	s_barrier
	s_waitcnt lgkmcnt(0)
	s_waitcnt lgkmcnt(0)
	v_mfma_f32_16x16x32_bf16 v[60:63], v[140:143], v[156:159], v[60:63]
	v_mfma_f32_16x16x32_bf16 v[56:59], v[148:151], v[156:159], v[56:59]
	v_mfma_f32_16x16x32_bf16 v[48:51], v[140:143], v[168:171], v[48:51]
	v_mfma_f32_16x16x32_bf16 v[40:43], v[148:151], v[168:171], v[40:43]
	v_mfma_f32_16x16x32_bf16 v[32:35], v[140:143], v[176:179], v[32:35]
	v_mfma_f32_16x16x32_bf16 v[24:27], v[148:151], v[176:179], v[24:27]
	v_mfma_f32_16x16x32_bf16 v[16:19], v[140:143], v[184:187], v[16:19]
	v_mfma_f32_16x16x32_bf16 v[8:11], v[148:151], v[184:187], v[8:11]
	v_mfma_f32_16x16x32_bf16 v[60:63], v[144:147], v[160:163], v[60:63]
	v_mfma_f32_16x16x32_bf16 v[56:59], v[152:155], v[160:163], v[56:59]
	v_mfma_f32_16x16x32_bf16 v[48:51], v[144:147], v[172:175], v[48:51]
	v_mfma_f32_16x16x32_bf16 v[40:43], v[152:155], v[172:175], v[40:43]
	v_mfma_f32_16x16x32_bf16 v[32:35], v[144:147], v[180:183], v[32:35]
	v_mfma_f32_16x16x32_bf16 v[24:27], v[152:155], v[180:183], v[24:27]
	v_mfma_f32_16x16x32_bf16 v[16:19], v[144:147], v[188:191], v[16:19]
	v_mfma_f32_16x16x32_bf16 v[8:11], v[152:155], v[188:191], v[8:11]
	s_barrier
	s_add_i32 s44, s36, s17
	v_lshl_add_u64 v[140:141], v[134:135], 0, s[4:5]
	s_mov_b32 m0, s44
	s_nop 0
	global_load_lds_dwordx4 v[140:141], off
	v_lshl_add_u64 v[140:141], v[134:135], 0, s[6:7]
	s_add_i32 m0, s44, 0x2000
	s_nop 0
	global_load_lds_dwordx4 v[140:141], off
	s_waitcnt vmcnt(6)
	s_barrier
	v_mfma_f32_16x16x32_bf16 v[52:55], v[192:195], v[156:159], v[52:55]
	v_mfma_f32_16x16x32_bf16 v[44:47], v[200:203], v[156:159], v[44:47]
	v_mfma_f32_16x16x32_bf16 v[36:39], v[192:195], v[168:171], v[36:39]
	v_mfma_f32_16x16x32_bf16 v[28:31], v[200:203], v[168:171], v[28:31]
	v_mfma_f32_16x16x32_bf16 v[20:23], v[192:195], v[176:179], v[20:23]
	v_mfma_f32_16x16x32_bf16 v[12:15], v[200:203], v[176:179], v[12:15]
	v_mfma_f32_16x16x32_bf16 v[4:7], v[192:195], v[184:187], v[4:7]
	v_mfma_f32_16x16x32_bf16 v[0:3], v[200:203], v[184:187], v[0:3]
	v_mfma_f32_16x16x32_bf16 v[52:55], v[196:199], v[160:163], v[52:55]
	v_mfma_f32_16x16x32_bf16 v[44:47], v[204:207], v[160:163], v[44:47]
	v_mfma_f32_16x16x32_bf16 v[36:39], v[196:199], v[172:175], v[36:39]
	v_mfma_f32_16x16x32_bf16 v[28:31], v[204:207], v[172:175], v[28:31]
	v_mfma_f32_16x16x32_bf16 v[20:23], v[196:199], v[180:183], v[20:23]
	v_mfma_f32_16x16x32_bf16 v[12:15], v[204:207], v[180:183], v[12:15]
	v_mfma_f32_16x16x32_bf16 v[4:7], v[196:199], v[188:191], v[4:7]
	v_mfma_f32_16x16x32_bf16 v[0:3], v[204:207], v[188:191], v[0:3]
	s_add_i32 s44, 0, 0x18000
	v_add_u32_e32 v152, s44, v136
	s_barrier
	ds_read_b128 v[140:143], v152
	ds_read_b128 v[144:147], v152 offset:1024
	ds_read_b128 v[148:151], v152 offset:2048
	ds_read_b128 v[152:155], v152 offset:3072
	s_mov_b32 m0, s28
	v_lshl_add_u64 v[192:193], v[164:165], 0, s[4:5]
	ds_read_b128 v[156:159], v138 offset:32768
	ds_read_b128 v[160:163], v138 offset:33792
	ds_read_b128 v[168:171], v138 offset:34816
	ds_read_b128 v[172:175], v138 offset:35840
	ds_read_b128 v[176:179], v138 offset:36864
	ds_read_b128 v[180:183], v138 offset:37888
	ds_read_b128 v[184:187], v138 offset:38912
	ds_read_b128 v[188:191], v138 offset:39936
	global_load_lds_dwordx4 v[192:193], off
	v_lshl_add_u64 v[192:193], v[164:165], 0, s[6:7]
	s_mov_b32 m0, s29
	s_nop 0
	global_load_lds_dwordx4 v[192:193], off
	s_waitcnt lgkmcnt(8)
	s_barrier
	s_waitcnt lgkmcnt(0)
	s_waitcnt lgkmcnt(0)
	v_mfma_f32_16x16x32_bf16 v[124:127], v[140:143], v[156:159], v[124:127]
	v_mfma_f32_16x16x32_bf16 v[120:123], v[148:151], v[156:159], v[120:123]
	v_mfma_f32_16x16x32_bf16 v[108:111], v[140:143], v[168:171], v[108:111]
	v_mfma_f32_16x16x32_bf16 v[104:107], v[148:151], v[168:171], v[104:107]
	v_mfma_f32_16x16x32_bf16 v[92:95], v[140:143], v[176:179], v[92:95]
	v_mfma_f32_16x16x32_bf16 v[88:91], v[148:151], v[176:179], v[88:91]
	v_mfma_f32_16x16x32_bf16 v[76:79], v[140:143], v[184:187], v[76:79]
	v_mfma_f32_16x16x32_bf16 v[72:75], v[148:151], v[184:187], v[72:75]
	v_mfma_f32_16x16x32_bf16 v[124:127], v[144:147], v[160:163], v[124:127]
	v_mfma_f32_16x16x32_bf16 v[120:123], v[152:155], v[160:163], v[120:123]
	v_mfma_f32_16x16x32_bf16 v[108:111], v[144:147], v[172:175], v[108:111]
	v_mfma_f32_16x16x32_bf16 v[104:107], v[152:155], v[172:175], v[104:107]
	v_mfma_f32_16x16x32_bf16 v[92:95], v[144:147], v[180:183], v[92:95]
	v_mfma_f32_16x16x32_bf16 v[88:91], v[152:155], v[180:183], v[88:91]
	v_mfma_f32_16x16x32_bf16 v[76:79], v[144:147], v[188:191], v[76:79]
	v_mfma_f32_16x16x32_bf16 v[72:75], v[152:155], v[188:191], v[72:75]
	s_barrier
	s_add_i32 s45, 0, 0x1c000
	s_add_i32 s44, s44, s17
	v_add_u32_e32 v167, s45, v136
	v_lshl_add_u64 v[208:209], v[134:135], 0, s[22:23]
	s_mov_b32 m0, s44
	ds_read_b128 v[192:195], v167
	ds_read_b128 v[196:199], v167 offset:1024
	ds_read_b128 v[200:203], v167 offset:2048
	ds_read_b128 v[204:207], v167 offset:3072
	global_load_lds_dwordx4 v[208:209], off
	v_lshl_add_u64 v[208:209], v[134:135], 0, s[24:25]
	s_add_i32 m0, s44, 0x2000
	s_nop 0
	global_load_lds_dwordx4 v[208:209], off
	s_barrier
	s_waitcnt lgkmcnt(0)
	s_waitcnt lgkmcnt(0)
	v_mfma_f32_16x16x32_bf16 v[116:119], v[192:195], v[156:159], v[116:119]
	v_mfma_f32_16x16x32_bf16 v[112:115], v[200:203], v[156:159], v[112:115]
	v_mfma_f32_16x16x32_bf16 v[100:103], v[192:195], v[168:171], v[100:103]
	v_mfma_f32_16x16x32_bf16 v[96:99], v[200:203], v[168:171], v[96:99]
	v_mfma_f32_16x16x32_bf16 v[84:87], v[192:195], v[176:179], v[84:87]
	v_mfma_f32_16x16x32_bf16 v[80:83], v[200:203], v[176:179], v[80:83]
	v_mfma_f32_16x16x32_bf16 v[68:71], v[192:195], v[184:187], v[68:71]
	v_mfma_f32_16x16x32_bf16 v[64:67], v[200:203], v[184:187], v[64:67]
	v_mfma_f32_16x16x32_bf16 v[116:119], v[196:199], v[160:163], v[116:119]
	v_mfma_f32_16x16x32_bf16 v[112:115], v[204:207], v[160:163], v[112:115]
	v_mfma_f32_16x16x32_bf16 v[100:103], v[196:199], v[172:175], v[100:103]
	v_mfma_f32_16x16x32_bf16 v[96:99], v[204:207], v[172:175], v[96:99]
	v_mfma_f32_16x16x32_bf16 v[84:87], v[196:199], v[180:183], v[84:87]
	v_mfma_f32_16x16x32_bf16 v[80:83], v[204:207], v[180:183], v[80:83]
	v_mfma_f32_16x16x32_bf16 v[68:71], v[196:199], v[188:191], v[68:71]
	v_mfma_f32_16x16x32_bf16 v[64:67], v[204:207], v[188:191], v[64:67]
	s_mov_b32 m0, s31
	v_lshl_add_u64 v[208:209], v[164:165], 0, s[22:23]
	s_barrier
	ds_read_b128 v[156:159], v138 offset:49152
	ds_read_b128 v[160:163], v138 offset:50176
	ds_read_b128 v[168:171], v138 offset:51200
	ds_read_b128 v[172:175], v138 offset:52224
	ds_read_b128 v[176:179], v138 offset:53248
	ds_read_b128 v[180:183], v138 offset:54272
	ds_read_b128 v[184:187], v138 offset:55296
	ds_read_b128 v[188:191], v138 offset:56320
	global_load_lds_dwordx4 v[208:209], off
	v_lshl_add_u64 v[164:165], v[164:165], 0, s[24:25]
	s_mov_b32 m0, s33
	s_nop 0
	global_load_lds_dwordx4 v[164:165], off
	s_barrier
	s_waitcnt lgkmcnt(0)
	s_waitcnt lgkmcnt(0)
	v_mfma_f32_16x16x32_bf16 v[60:63], v[140:143], v[156:159], v[60:63]
	v_mfma_f32_16x16x32_bf16 v[56:59], v[148:151], v[156:159], v[56:59]
	v_mfma_f32_16x16x32_bf16 v[48:51], v[140:143], v[168:171], v[48:51]
	v_mfma_f32_16x16x32_bf16 v[40:43], v[148:151], v[168:171], v[40:43]
	v_mfma_f32_16x16x32_bf16 v[32:35], v[140:143], v[176:179], v[32:35]
	v_mfma_f32_16x16x32_bf16 v[24:27], v[148:151], v[176:179], v[24:27]
	v_mfma_f32_16x16x32_bf16 v[16:19], v[140:143], v[184:187], v[16:19]
	v_mfma_f32_16x16x32_bf16 v[8:11], v[148:151], v[184:187], v[8:11]
	v_mfma_f32_16x16x32_bf16 v[60:63], v[144:147], v[160:163], v[60:63]
	v_mfma_f32_16x16x32_bf16 v[56:59], v[152:155], v[160:163], v[56:59]
	v_mfma_f32_16x16x32_bf16 v[48:51], v[144:147], v[172:175], v[48:51]
	v_mfma_f32_16x16x32_bf16 v[40:43], v[152:155], v[172:175], v[40:43]
	v_mfma_f32_16x16x32_bf16 v[32:35], v[144:147], v[180:183], v[32:35]
	v_mfma_f32_16x16x32_bf16 v[24:27], v[152:155], v[180:183], v[24:27]
	v_mfma_f32_16x16x32_bf16 v[16:19], v[144:147], v[188:191], v[16:19]
	v_mfma_f32_16x16x32_bf16 v[8:11], v[152:155], v[188:191], v[8:11]
	s_barrier
	s_add_i32 s44, s45, s17
	v_lshl_add_u64 v[140:141], v[134:135], 0, s[26:27]
	s_mov_b32 m0, s44
	v_lshl_add_u64 v[134:135], v[134:135], 0, s[34:35]
	global_load_lds_dwordx4 v[140:141], off
	s_add_i32 m0, s44, 0x2000
	s_nop 0
	global_load_lds_dwordx4 v[134:135], off
	s_waitcnt vmcnt(6)
	s_barrier
	v_mfma_f32_16x16x32_bf16 v[52:55], v[192:195], v[156:159], v[52:55]
	v_mfma_f32_16x16x32_bf16 v[44:47], v[200:203], v[156:159], v[44:47]
	v_mfma_f32_16x16x32_bf16 v[36:39], v[192:195], v[168:171], v[36:39]
	v_mfma_f32_16x16x32_bf16 v[28:31], v[200:203], v[168:171], v[28:31]
	v_mfma_f32_16x16x32_bf16 v[20:23], v[192:195], v[176:179], v[20:23]
	v_mfma_f32_16x16x32_bf16 v[12:15], v[200:203], v[176:179], v[12:15]
	v_mfma_f32_16x16x32_bf16 v[4:7], v[192:195], v[184:187], v[4:7]
	v_mfma_f32_16x16x32_bf16 v[0:3], v[200:203], v[184:187], v[0:3]
	v_mfma_f32_16x16x32_bf16 v[52:55], v[196:199], v[160:163], v[52:55]
	v_mfma_f32_16x16x32_bf16 v[44:47], v[204:207], v[160:163], v[44:47]
	v_mfma_f32_16x16x32_bf16 v[36:39], v[196:199], v[172:175], v[36:39]
	v_mfma_f32_16x16x32_bf16 v[28:31], v[204:207], v[172:175], v[28:31]
	v_mfma_f32_16x16x32_bf16 v[20:23], v[196:199], v[180:183], v[20:23]
	v_mfma_f32_16x16x32_bf16 v[12:15], v[204:207], v[180:183], v[12:15]
	v_mfma_f32_16x16x32_bf16 v[4:7], v[196:199], v[188:191], v[4:7]
	v_mfma_f32_16x16x32_bf16 v[0:3], v[204:207], v[188:191], v[0:3]
	s_add_i32 s43, s43, 2
	s_add_u32 s60, s60, 0x100
	s_addc_u32 s61, s61, 0
	s_add_u32 s18, s18, 0x100
	s_addc_u32 s42, s42, 0
	s_cmp_gt_u32 s43, 5
	s_barrier
	s_cbranch_scc0 .LBB0_513
	s_bfe_u32 s18, s58, 0x10007
	s_add_i32 s18, s58, s18
	s_sext_i32_i8 s18, s18
	s_lshr_b32 s18, s18, 1
	s_bfe_i64 s[42:43], s[18:19], 0x100000
	s_lshl_b64 s[42:43], s[42:43], 20
	s_add_u32 s42, s10, s42
	v_mov_b32_e32 v140, v166
	s_addc_u32 s43, s11, s43
	s_lshl_b32 s46, s58, 8
	s_lshl_b32 s18, s18, 9
	s_sub_i32 s18, s46, s18
	v_lshrrev_b32_e32 v134, 1, v140
	v_and_or_b32 v134, v134, 24, s18
	s_lshl_b32 s18, s56, 8
	s_addk_i32 s18, 0x2000
	s_mov_b32 s44, s16
	s_mov_b32 s45, s30
	v_and_or_b32 v140, v140, 15, s18
	v_pk_add_f32 v[126:127], v[126:127], 0 op_sel_hi:[1,0]
	v_lshl_add_u32 v134, s45, 5, v134
	v_lshl_add_u32 v140, s44, 6, v140
	v_ashrrev_i32_e32 v135, 31, v134
	v_ashrrev_i32_e32 v141, 31, v140
	v_lshl_add_u64 v[142:143], v[134:135], 1, s[42:43]
	v_lshlrev_b64 v[134:135], 12, v[140:141]
	v_lshl_add_u64 v[134:135], v[142:143], 0, v[134:135]
	v_pk_add_f32 v[124:125], v[124:125], 0 op_sel_hi:[1,0]
	v_pk_add_f32 v[144:145], v[122:123], 0 op_sel_hi:[1,0]
	v_pk_add_f32 v[122:123], v[120:121], 0 op_sel_hi:[1,0]
	v_cvt_pk_bf16_f32 v120, v124, v125
	v_cvt_pk_bf16_f32 v121, v126, v127
	v_pk_add_f32 v[116:117], v[116:117], 0 op_sel_hi:[1,0]
	v_cvt_pk_bf16_f32 v122, v122, v123
	v_cvt_pk_bf16_f32 v123, v144, v145
	global_store_dwordx4 v[134:135], v[120:123], off
	v_pk_add_f32 v[118:119], v[118:119], 0 op_sel_hi:[1,0]
	v_pk_add_f32 v[110:111], v[110:111], 0 op_sel_hi:[1,0]
	v_pk_add_f32 v[120:121], v[114:115], 0 op_sel_hi:[1,0]
	v_pk_add_f32 v[114:115], v[112:113], 0 op_sel_hi:[1,0]
	v_cvt_pk_bf16_f32 v112, v116, v117
	v_cvt_pk_bf16_f32 v113, v118, v119
	v_pk_add_f32 v[108:109], v[108:109], 0 op_sel_hi:[1,0]
	v_cvt_pk_bf16_f32 v114, v114, v115
	v_cvt_pk_bf16_f32 v115, v120, v121
	global_store_dwordx4 v[134:135], v[112:115], off offset:256
	v_pk_add_f32 v[100:101], v[100:101], 0 op_sel_hi:[1,0]
	v_pk_add_f32 v[102:103], v[102:103], 0 op_sel_hi:[1,0]
	v_or_b32_e32 v112, 16, v140
	v_ashrrev_i32_e32 v113, 31, v112
	v_lshlrev_b64 v[112:113], 12, v[112:113]
	v_lshl_add_u64 v[112:113], v[142:143], 0, v[112:113]
	v_pk_add_f32 v[114:115], v[106:107], 0 op_sel_hi:[1,0]
	v_pk_add_f32 v[106:107], v[104:105], 0 op_sel_hi:[1,0]
	v_cvt_pk_bf16_f32 v104, v108, v109
	v_cvt_pk_bf16_f32 v105, v110, v111
	v_pk_add_f32 v[94:95], v[94:95], 0 op_sel_hi:[1,0]
	v_cvt_pk_bf16_f32 v106, v106, v107
	v_cvt_pk_bf16_f32 v107, v114, v115
	global_store_dwordx4 v[112:113], v[104:107], off
	v_pk_add_f32 v[92:93], v[92:93], 0 op_sel_hi:[1,0]
	v_pk_add_f32 v[84:85], v[84:85], 0 op_sel_hi:[1,0]
	v_pk_add_f32 v[104:105], v[98:99], 0 op_sel_hi:[1,0]
	v_pk_add_f32 v[98:99], v[96:97], 0 op_sel_hi:[1,0]
	v_cvt_pk_bf16_f32 v96, v100, v101
	v_cvt_pk_bf16_f32 v97, v102, v103
	v_pk_add_f32 v[86:87], v[86:87], 0 op_sel_hi:[1,0]
	v_cvt_pk_bf16_f32 v98, v98, v99
	v_cvt_pk_bf16_f32 v99, v104, v105
	global_store_dwordx4 v[112:113], v[96:99], off offset:256
	v_pk_add_f32 v[78:79], v[78:79], 0 op_sel_hi:[1,0]
	v_pk_add_f32 v[76:77], v[76:77], 0 op_sel_hi:[1,0]
	v_or_b32_e32 v96, 32, v140
	v_ashrrev_i32_e32 v97, 31, v96
	v_lshlrev_b64 v[96:97], 12, v[96:97]
	v_lshl_add_u64 v[96:97], v[142:143], 0, v[96:97]
	v_pk_add_f32 v[98:99], v[90:91], 0 op_sel_hi:[1,0]
	v_pk_add_f32 v[90:91], v[88:89], 0 op_sel_hi:[1,0]
	v_cvt_pk_bf16_f32 v88, v92, v93
	v_cvt_pk_bf16_f32 v89, v94, v95
	v_pk_add_f32 v[70:71], v[70:71], 0 op_sel_hi:[1,0]
	v_cvt_pk_bf16_f32 v90, v90, v91
	v_cvt_pk_bf16_f32 v91, v98, v99
	global_store_dwordx4 v[96:97], v[88:91], off
	v_pk_add_f32 v[68:69], v[68:69], 0 op_sel_hi:[1,0]
	v_pk_add_f32 v[60:61], v[60:61], 0 op_sel_hi:[1,0]
	v_pk_add_f32 v[88:89], v[82:83], 0 op_sel_hi:[1,0]
	v_pk_add_f32 v[82:83], v[80:81], 0 op_sel_hi:[1,0]
	v_cvt_pk_bf16_f32 v80, v84, v85
	v_cvt_pk_bf16_f32 v81, v86, v87
	s_mov_b32 s18, 0x80000
	v_cvt_pk_bf16_f32 v82, v82, v83
	v_cvt_pk_bf16_f32 v83, v88, v89
	global_store_dwordx4 v[96:97], v[80:83], off offset:256
	v_pk_add_f32 v[62:63], v[62:63], 0 op_sel_hi:[1,0]
	s_mov_b64 s[42:43], 0x80000
	v_or_b32_e32 v80, 48, v140
	v_ashrrev_i32_e32 v81, 31, v80
	v_lshlrev_b64 v[80:81], 12, v[80:81]
	v_lshl_add_u64 v[80:81], v[142:143], 0, v[80:81]
	v_pk_add_f32 v[82:83], v[74:75], 0 op_sel_hi:[1,0]
	v_pk_add_f32 v[74:75], v[72:73], 0 op_sel_hi:[1,0]
	v_cvt_pk_bf16_f32 v72, v76, v77
	v_cvt_pk_bf16_f32 v73, v78, v79
	v_pk_add_f32 v[54:55], v[54:55], 0 op_sel_hi:[1,0]
	v_cvt_pk_bf16_f32 v74, v74, v75
	v_cvt_pk_bf16_f32 v75, v82, v83
	global_store_dwordx4 v[80:81], v[72:75], off
	v_pk_add_f32 v[52:53], v[52:53], 0 op_sel_hi:[1,0]
	v_pk_add_f32 v[48:49], v[48:49], 0 op_sel_hi:[1,0]
	v_pk_add_f32 v[72:73], v[66:67], 0 op_sel_hi:[1,0]
	v_pk_add_f32 v[66:67], v[64:65], 0 op_sel_hi:[1,0]
	v_cvt_pk_bf16_f32 v64, v68, v69
	v_cvt_pk_bf16_f32 v65, v70, v71
	v_pk_add_f32 v[38:39], v[38:39], 0 op_sel_hi:[1,0]
	v_cvt_pk_bf16_f32 v66, v66, v67
	v_cvt_pk_bf16_f32 v67, v72, v73
	global_store_dwordx4 v[80:81], v[64:67], off offset:256
	v_pk_add_f32 v[36:37], v[36:37], 0 op_sel_hi:[1,0]
	v_pk_add_f32 v[32:33], v[32:33], 0 op_sel_hi:[1,0]
	v_pk_add_f32 v[66:67], v[58:59], 0 op_sel_hi:[1,0]
	v_pk_add_f32 v[58:59], v[56:57], 0 op_sel_hi:[1,0]
	v_cvt_pk_bf16_f32 v56, v60, v61
	v_add_co_u32_e32 v60, vcc, s18, v134
	v_cvt_pk_bf16_f32 v57, v62, v63
	v_cvt_pk_bf16_f32 v58, v58, v59
	v_cvt_pk_bf16_f32 v59, v66, v67
	v_lshl_add_u64 v[64:65], v[134:135], 0, s[42:43]
	s_nop 0
	v_addc_co_u32_e32 v61, vcc, 0, v135, vcc
	global_store_dwordx4 v[60:61], v[56:59], off
	s_mov_b32 s18, 0x90000
	s_mov_b64 s[42:43], 0x90000
	v_pk_add_f32 v[56:57], v[46:47], 0 op_sel_hi:[1,0]
	v_pk_add_f32 v[46:47], v[44:45], 0 op_sel_hi:[1,0]
	v_cvt_pk_bf16_f32 v44, v52, v53
	v_cvt_pk_bf16_f32 v45, v54, v55
	v_pk_add_f32 v[22:23], v[22:23], 0 op_sel_hi:[1,0]
	v_cvt_pk_bf16_f32 v46, v46, v47
	v_cvt_pk_bf16_f32 v47, v56, v57
	global_store_dwordx4 v[64:65], v[44:47], off offset:256
	v_pk_add_f32 v[20:21], v[20:21], 0 op_sel_hi:[1,0]
	v_pk_add_f32 v[16:17], v[16:17], 0 op_sel_hi:[1,0]
	v_pk_add_f32 v[46:47], v[50:51], 0 op_sel_hi:[1,0]
	v_pk_add_f32 v[50:51], v[42:43], 0 op_sel_hi:[1,0]
	v_pk_add_f32 v[42:43], v[40:41], 0 op_sel_hi:[1,0]
	v_cvt_pk_bf16_f32 v40, v48, v49
	v_cvt_pk_bf16_f32 v41, v46, v47
	v_add_co_u32_e32 v46, vcc, s18, v134
	v_cvt_pk_bf16_f32 v42, v42, v43
	v_cvt_pk_bf16_f32 v43, v50, v51
	v_lshl_add_u64 v[44:45], v[134:135], 0, s[42:43]
	s_nop 0
	v_addc_co_u32_e32 v47, vcc, 0, v135, vcc
	global_store_dwordx4 v[46:47], v[40:43], off
	s_mov_b32 s18, 0xa0000
	s_mov_b64 s[42:43], 0xa0000
	v_pk_add_f32 v[40:41], v[30:31], 0 op_sel_hi:[1,0]
	v_pk_add_f32 v[30:31], v[28:29], 0 op_sel_hi:[1,0]
	v_cvt_pk_bf16_f32 v28, v36, v37
	v_cvt_pk_bf16_f32 v29, v38, v39
	v_pk_add_f32 v[6:7], v[6:7], 0 op_sel_hi:[1,0]
	v_cvt_pk_bf16_f32 v30, v30, v31
	v_cvt_pk_bf16_f32 v31, v40, v41
	global_store_dwordx4 v[44:45], v[28:31], off offset:256
	v_pk_add_f32 v[4:5], v[4:5], 0 op_sel_hi:[1,0]
	s_mov_b64 s[60:61], -1
	v_pk_add_f32 v[30:31], v[34:35], 0 op_sel_hi:[1,0]
	v_pk_add_f32 v[34:35], v[26:27], 0 op_sel_hi:[1,0]
	v_pk_add_f32 v[26:27], v[24:25], 0 op_sel_hi:[1,0]
	v_cvt_pk_bf16_f32 v24, v32, v33
	v_cvt_pk_bf16_f32 v25, v30, v31
	v_add_co_u32_e32 v30, vcc, s18, v134
	v_cvt_pk_bf16_f32 v26, v26, v27
	v_cvt_pk_bf16_f32 v27, v34, v35
	v_lshl_add_u64 v[28:29], v[134:135], 0, s[42:43]
	s_nop 0
	v_addc_co_u32_e32 v31, vcc, 0, v135, vcc
	global_store_dwordx4 v[30:31], v[24:27], off
	s_mov_b32 s18, 0xb0000
	s_mov_b64 s[42:43], 0xb0000
	v_pk_add_f32 v[24:25], v[14:15], 0 op_sel_hi:[1,0]
	v_pk_add_f32 v[14:15], v[12:13], 0 op_sel_hi:[1,0]
	v_cvt_pk_bf16_f32 v12, v20, v21
	v_cvt_pk_bf16_f32 v13, v22, v23
	s_nop 0
	v_cvt_pk_bf16_f32 v14, v14, v15
	v_cvt_pk_bf16_f32 v15, v24, v25
	global_store_dwordx4 v[28:29], v[12:15], off offset:256
	s_nop 1
	v_pk_add_f32 v[14:15], v[18:19], 0 op_sel_hi:[1,0]
	v_pk_add_f32 v[18:19], v[10:11], 0 op_sel_hi:[1,0]
	v_pk_add_f32 v[10:11], v[8:9], 0 op_sel_hi:[1,0]
	v_cvt_pk_bf16_f32 v8, v16, v17
	v_cvt_pk_bf16_f32 v9, v14, v15
	v_add_co_u32_e32 v14, vcc, s18, v134
	v_lshl_add_u64 v[12:13], v[134:135], 0, s[42:43]
	s_nop 0
	v_addc_co_u32_e32 v15, vcc, 0, v135, vcc
	v_cvt_pk_bf16_f32 v10, v10, v11
	v_cvt_pk_bf16_f32 v11, v18, v19
	global_store_dwordx4 v[14:15], v[8:11], off
	s_mov_b32 s18, s41
	s_nop 0
	v_pk_add_f32 v[8:9], v[2:3], 0 op_sel_hi:[1,0]
	v_pk_add_f32 v[2:3], v[0:1], 0 op_sel_hi:[1,0]
	v_cvt_pk_bf16_f32 v0, v4, v5
	v_cvt_pk_bf16_f32 v1, v6, v7
	s_nop 0
	v_cvt_pk_bf16_f32 v2, v2, v3
	v_cvt_pk_bf16_f32 v3, v8, v9
	global_store_dwordx4 v[12:13], v[0:3], off offset:256
	s_lshl_b32 s18, s18, 2
	s_or_b32 s18, s18, s0
	s_cmp_gt_i32 s18, 3
	s_cbranch_scc1 .LBB0_509
	s_ashr_i32 s42, s18, 31
	s_lshr_b32 s42, s42, 29
	s_add_i32 s42, s18, s42
	s_ashr_i32 s43, s42, 3
	s_and_b32 s42, s42, -8
	s_sub_i32 s18, s18, s42
	s_add_i32 s18, s18, s43
	s_ashr_i32 s42, s18, 31
	s_lshr_b32 s42, s42, 27
	s_add_i32 s42, s18, s42
	s_ashr_i32 s42, s42, 5
	s_lshl_b32 s44, s42, 3
	s_sub_i32 s43, 1, s44
	s_lshl_b32 s42, s42, 5
	s_min_u32 s45, s43, 8
	s_sub_i32 s18, s18, s42
	s_sext_i32_i8 s42, s18
	v_cvt_f32_ubyte0_e32 v1, s45
	v_cvt_f32_i32_e32 v0, s42
	v_rcp_iflag_f32_e32 v2, v1
	s_ashr_i32 s42, s42, 30
	s_or_b32 s46, s42, 1
	s_mov_b64 s[60:61], 0
	v_mul_f32_e32 v2, v0, v2
	v_trunc_f32_e32 v2, v2
	v_fma_f32 v0, -v2, v1, v0
	v_cvt_i32_f32_e32 v2, v2
	v_cmp_ge_f32_e64 s[42:43], |v0|, v1
	s_and_b64 s[42:43], s[42:43], exec
	s_cselect_b32 s42, s46, 0
	v_readfirstlane_b32 s43, v2
	s_add_i32 s42, s43, s42
	s_sext_i32_i8 s58, s42
	s_mul_i32 s42, s42, s45
	s_sub_i32 s18, s18, s42
	s_sext_i32_i8 s18, s18
	s_add_i32 s56, s44, s18
	s_branch .LBB0_509

.LBB0_560:
	s_add_i32 s0, s0, 2
	v_add_u32_e32 v1, s28, v203
	s_add_u32 s4, s64, s34
	ds_read_b128 v[132:135], v1
	ds_read_b128 v[136:139], v1 offset:1024
	ds_read_b128 v[140:143], v1 offset:2048
	ds_read_b128 v[144:147], v1 offset:3072
	s_addc_u32 s5, s65, s35
	s_add_u32 s4, s4, 0x100
	s_addc_u32 s5, s5, 0
	s_add_u32 s8, s39, s34
	s_addc_u32 vcc_lo, s40, s35
	s_cmp_eq_u32 s88, s34
	s_cselect_b32 s5, s57, s5
	s_cselect_b32 s4, s56, s4
	s_cselect_b32 vcc_hi, s59, vcc_lo
	s_cselect_b32 vcc_lo, s58, s8
	v_lshl_add_u64 v[2:3], v[198:199], 0, s[34:35]
	v_lshl_add_u64 v[180:181], v[2:3], 0, s[74:75]
	s_add_i32 m0, s43, 0xc000
	ds_read_b128 v[148:151], v204
	ds_read_b128 v[152:155], v204 offset:1024
	ds_read_b128 v[156:159], v204 offset:2048
	ds_read_b128 v[160:163], v204 offset:3072
	ds_read_b128 v[164:167], v204 offset:4096
	ds_read_b128 v[168:171], v204 offset:5120
	ds_read_b128 v[172:175], v204 offset:6144
	ds_read_b128 v[176:179], v204 offset:7168
	global_load_lds_dwordx4 v[180:181], off
	v_lshl_add_u64 v[2:3], v[2:3], 0, s[76:77]
	s_add_i32 m0, s43, 0xe000
	s_nop 0
	global_load_lds_dwordx4 v[2:3], off
	s_waitcnt lgkmcnt(8)
	s_barrier
	s_waitcnt lgkmcnt(0)
	s_waitcnt lgkmcnt(0)
	v_mfma_f32_16x16x32_bf16 v[128:131], v[132:135], v[148:151], v[128:131]
	v_mfma_f32_16x16x32_bf16 v[124:127], v[140:143], v[148:151], v[124:127]
	v_mfma_f32_16x16x32_bf16 v[112:115], v[132:135], v[156:159], v[112:115]
	v_mfma_f32_16x16x32_bf16 v[108:111], v[140:143], v[156:159], v[108:111]
	v_mfma_f32_16x16x32_bf16 v[96:99], v[132:135], v[164:167], v[96:99]
	v_mfma_f32_16x16x32_bf16 v[92:95], v[140:143], v[164:167], v[92:95]
	v_mfma_f32_16x16x32_bf16 v[80:83], v[132:135], v[172:175], v[80:83]
	v_mfma_f32_16x16x32_bf16 v[76:79], v[140:143], v[172:175], v[76:79]
	v_mfma_f32_16x16x32_bf16 v[128:131], v[136:139], v[152:155], v[128:131]
	v_mfma_f32_16x16x32_bf16 v[124:127], v[144:147], v[152:155], v[124:127]
	v_mfma_f32_16x16x32_bf16 v[112:115], v[136:139], v[160:163], v[112:115]
	v_mfma_f32_16x16x32_bf16 v[108:111], v[144:147], v[160:163], v[108:111]
	v_mfma_f32_16x16x32_bf16 v[96:99], v[136:139], v[168:171], v[96:99]
	v_mfma_f32_16x16x32_bf16 v[92:95], v[144:147], v[168:171], v[92:95]
	v_mfma_f32_16x16x32_bf16 v[80:83], v[136:139], v[176:179], v[80:83]
	v_mfma_f32_16x16x32_bf16 v[76:79], v[144:147], v[176:179], v[76:79]
	s_barrier
	s_add_i32 s8, s28, s42
	v_add_u32_e32 v1, s29, v203
	v_lshl_add_u64 v[200:201], vcc, 0, v[194:195]
	s_mov_b32 m0, s8
	ds_read_b128 v[180:183], v1
	ds_read_b128 v[184:187], v1 offset:1024
	ds_read_b128 v[188:191], v1 offset:2048
	ds_read_b128 v[206:209], v1 offset:3072
	global_load_lds_dwordx4 v[200:201], off
	v_lshl_add_u64 v[2:3], v[200:201], 0, s[10:11]
	s_add_i32 m0, s8, 0x2000
	s_nop 0
	global_load_lds_dwordx4 v[2:3], off
	s_barrier
	s_waitcnt lgkmcnt(0)
	s_waitcnt lgkmcnt(0)
	v_mfma_f32_16x16x32_bf16 v[120:123], v[180:183], v[148:151], v[120:123]
	v_mfma_f32_16x16x32_bf16 v[116:119], v[188:191], v[148:151], v[116:119]
	v_mfma_f32_16x16x32_bf16 v[104:107], v[180:183], v[156:159], v[104:107]
	v_mfma_f32_16x16x32_bf16 v[100:103], v[188:191], v[156:159], v[100:103]
	v_mfma_f32_16x16x32_bf16 v[88:91], v[180:183], v[164:167], v[88:91]
	v_mfma_f32_16x16x32_bf16 v[84:87], v[188:191], v[164:167], v[84:87]
	v_mfma_f32_16x16x32_bf16 v[72:75], v[180:183], v[172:175], v[72:75]
	v_mfma_f32_16x16x32_bf16 v[68:71], v[188:191], v[172:175], v[68:71]
	v_mfma_f32_16x16x32_bf16 v[120:123], v[184:187], v[152:155], v[120:123]
	v_mfma_f32_16x16x32_bf16 v[116:119], v[206:209], v[152:155], v[116:119]
	v_mfma_f32_16x16x32_bf16 v[104:107], v[184:187], v[160:163], v[104:107]
	v_mfma_f32_16x16x32_bf16 v[100:103], v[206:209], v[160:163], v[100:103]
	v_mfma_f32_16x16x32_bf16 v[88:91], v[184:187], v[168:171], v[88:91]
	v_mfma_f32_16x16x32_bf16 v[84:87], v[206:209], v[168:171], v[84:87]
	v_mfma_f32_16x16x32_bf16 v[72:75], v[184:187], v[176:179], v[72:75]
	v_mfma_f32_16x16x32_bf16 v[68:71], v[206:209], v[176:179], v[68:71]
	s_mov_b32 m0, s43
	v_lshl_add_u64 v[210:211], s[4:5], 0, v[192:193]
	s_barrier
	ds_read_b128 v[148:151], v204 offset:16384
	ds_read_b128 v[152:155], v204 offset:17408
	ds_read_b128 v[156:159], v204 offset:18432
	ds_read_b128 v[160:163], v204 offset:19456
	ds_read_b128 v[164:167], v204 offset:20480
	ds_read_b128 v[168:171], v204 offset:21504
	ds_read_b128 v[172:175], v204 offset:22528
	ds_read_b128 v[176:179], v204 offset:23552
	global_load_lds_dwordx4 v[210:211], off
	v_lshl_add_u64 v[2:3], v[210:211], 0, s[10:11]
	s_mov_b32 m0, s44
	s_nop 0
	global_load_lds_dwordx4 v[2:3], off
	s_barrier
	s_waitcnt lgkmcnt(0)
	s_waitcnt lgkmcnt(0)
	v_mfma_f32_16x16x32_bf16 v[64:67], v[132:135], v[148:151], v[64:67]
	v_mfma_f32_16x16x32_bf16 v[60:63], v[140:143], v[148:151], v[60:63]
	v_mfma_f32_16x16x32_bf16 v[48:51], v[132:135], v[156:159], v[48:51]
	v_mfma_f32_16x16x32_bf16 v[44:47], v[140:143], v[156:159], v[44:47]
	v_mfma_f32_16x16x32_bf16 v[32:35], v[132:135], v[164:167], v[32:35]
	v_mfma_f32_16x16x32_bf16 v[28:31], v[140:143], v[164:167], v[28:31]
	v_mfma_f32_16x16x32_bf16 v[16:19], v[132:135], v[172:175], v[16:19]
	v_mfma_f32_16x16x32_bf16 v[12:15], v[140:143], v[172:175], v[12:15]
	v_mfma_f32_16x16x32_bf16 v[64:67], v[136:139], v[152:155], v[64:67]
	v_mfma_f32_16x16x32_bf16 v[60:63], v[144:147], v[152:155], v[60:63]
	v_mfma_f32_16x16x32_bf16 v[48:51], v[136:139], v[160:163], v[48:51]
	v_mfma_f32_16x16x32_bf16 v[44:47], v[144:147], v[160:163], v[44:47]
	v_mfma_f32_16x16x32_bf16 v[32:35], v[136:139], v[168:171], v[32:35]
	v_mfma_f32_16x16x32_bf16 v[28:31], v[144:147], v[168:171], v[28:31]
	v_mfma_f32_16x16x32_bf16 v[16:19], v[136:139], v[176:179], v[16:19]
	v_mfma_f32_16x16x32_bf16 v[12:15], v[144:147], v[176:179], v[12:15]
	s_barrier
	s_add_i32 s4, s29, s42
	v_lshl_add_u64 v[2:3], v[200:201], 0, s[18:19]
	s_mov_b32 m0, s4
	s_nop 0
	global_load_lds_dwordx4 v[2:3], off
	v_lshl_add_u64 v[2:3], v[200:201], 0, s[22:23]
	s_add_i32 m0, s4, 0x2000
	s_nop 0
	global_load_lds_dwordx4 v[2:3], off
	s_waitcnt vmcnt(6)
	s_barrier
	v_mfma_f32_16x16x32_bf16 v[56:59], v[180:183], v[148:151], v[56:59]
	v_mfma_f32_16x16x32_bf16 v[52:55], v[188:191], v[148:151], v[52:55]
	v_mfma_f32_16x16x32_bf16 v[40:43], v[180:183], v[156:159], v[40:43]
	v_mfma_f32_16x16x32_bf16 v[36:39], v[188:191], v[156:159], v[36:39]
	v_mfma_f32_16x16x32_bf16 v[24:27], v[180:183], v[164:167], v[24:27]
	v_mfma_f32_16x16x32_bf16 v[20:23], v[188:191], v[164:167], v[20:23]
	v_mfma_f32_16x16x32_bf16 v[8:11], v[180:183], v[172:175], v[8:11]
	v_mfma_f32_16x16x32_bf16 v[2:5], v[188:191], v[172:175], v[4:7]
	v_mfma_f32_16x16x32_bf16 v[56:59], v[184:187], v[152:155], v[56:59]
	v_mfma_f32_16x16x32_bf16 v[52:55], v[206:209], v[152:155], v[52:55]
	v_mfma_f32_16x16x32_bf16 v[40:43], v[184:187], v[160:163], v[40:43]
	v_mfma_f32_16x16x32_bf16 v[36:39], v[206:209], v[160:163], v[36:39]
	v_mfma_f32_16x16x32_bf16 v[24:27], v[184:187], v[168:171], v[24:27]
	v_mfma_f32_16x16x32_bf16 v[20:23], v[206:209], v[168:171], v[20:23]
	v_mfma_f32_16x16x32_bf16 v[8:11], v[184:187], v[176:179], v[8:11]
	v_mfma_f32_16x16x32_bf16 v[2:5], v[206:209], v[176:179], v[2:5]
	s_add_i32 s4, 0, 0x18000
	v_add_u32_e32 v1, s4, v203
	s_barrier
	ds_read_b128 v[132:135], v1
	ds_read_b128 v[136:139], v1 offset:1024
	ds_read_b128 v[140:143], v1 offset:2048
	ds_read_b128 v[144:147], v1 offset:3072
	s_mov_b32 m0, s45
	v_lshl_add_u64 v[6:7], v[210:211], 0, s[18:19]
	ds_read_b128 v[148:151], v204 offset:32768
	ds_read_b128 v[152:155], v204 offset:33792
	ds_read_b128 v[156:159], v204 offset:34816
	ds_read_b128 v[160:163], v204 offset:35840
	ds_read_b128 v[164:167], v204 offset:36864
	ds_read_b128 v[168:171], v204 offset:37888
	ds_read_b128 v[172:175], v204 offset:38912
	ds_read_b128 v[176:179], v204 offset:39936
	global_load_lds_dwordx4 v[6:7], off
	v_lshl_add_u64 v[6:7], v[210:211], 0, s[22:23]
	s_mov_b32 m0, s46
	s_nop 0
	global_load_lds_dwordx4 v[6:7], off
	s_waitcnt lgkmcnt(8)
	s_barrier
	s_waitcnt lgkmcnt(0)
	s_waitcnt lgkmcnt(0)
	v_mfma_f32_16x16x32_bf16 v[128:131], v[132:135], v[148:151], v[128:131]
	v_mfma_f32_16x16x32_bf16 v[124:127], v[140:143], v[148:151], v[124:127]
	v_mfma_f32_16x16x32_bf16 v[112:115], v[132:135], v[156:159], v[112:115]
	v_mfma_f32_16x16x32_bf16 v[108:111], v[140:143], v[156:159], v[108:111]
	v_mfma_f32_16x16x32_bf16 v[96:99], v[132:135], v[164:167], v[96:99]
	v_mfma_f32_16x16x32_bf16 v[92:95], v[140:143], v[164:167], v[92:95]
	v_mfma_f32_16x16x32_bf16 v[80:83], v[132:135], v[172:175], v[80:83]
	v_mfma_f32_16x16x32_bf16 v[76:79], v[140:143], v[172:175], v[76:79]
	v_mfma_f32_16x16x32_bf16 v[128:131], v[136:139], v[152:155], v[128:131]
	v_mfma_f32_16x16x32_bf16 v[124:127], v[144:147], v[152:155], v[124:127]
	v_mfma_f32_16x16x32_bf16 v[112:115], v[136:139], v[160:163], v[112:115]
	v_mfma_f32_16x16x32_bf16 v[108:111], v[144:147], v[160:163], v[108:111]
	v_mfma_f32_16x16x32_bf16 v[96:99], v[136:139], v[168:171], v[96:99]
	v_mfma_f32_16x16x32_bf16 v[92:95], v[144:147], v[168:171], v[92:95]
	v_mfma_f32_16x16x32_bf16 v[80:83], v[136:139], v[176:179], v[80:83]
	v_mfma_f32_16x16x32_bf16 v[76:79], v[144:147], v[176:179], v[76:79]
	s_barrier
	s_add_i32 s5, 0, 0x1c000
	s_add_i32 s4, s4, s42
	v_add_u32_e32 v1, s5, v203
	v_lshl_add_u64 v[6:7], v[200:201], 0, s[70:71]
	s_mov_b32 m0, s4
	ds_read_b128 v[180:183], v1
	ds_read_b128 v[184:187], v1 offset:1024
	ds_read_b128 v[188:191], v1 offset:2048
	ds_read_b128 v[206:209], v1 offset:3072
	global_load_lds_dwordx4 v[6:7], off
	v_lshl_add_u64 v[6:7], v[200:201], 0, s[72:73]
	s_add_i32 m0, s4, 0x2000
	s_nop 0
	global_load_lds_dwordx4 v[6:7], off
	s_barrier
	s_waitcnt lgkmcnt(0)
	s_waitcnt lgkmcnt(0)
	v_mfma_f32_16x16x32_bf16 v[120:123], v[180:183], v[148:151], v[120:123]
	v_mfma_f32_16x16x32_bf16 v[116:119], v[188:191], v[148:151], v[116:119]
	v_mfma_f32_16x16x32_bf16 v[104:107], v[180:183], v[156:159], v[104:107]
	v_mfma_f32_16x16x32_bf16 v[100:103], v[188:191], v[156:159], v[100:103]
	v_mfma_f32_16x16x32_bf16 v[88:91], v[180:183], v[164:167], v[88:91]
	v_mfma_f32_16x16x32_bf16 v[84:87], v[188:191], v[164:167], v[84:87]
	v_mfma_f32_16x16x32_bf16 v[72:75], v[180:183], v[172:175], v[72:75]
	v_mfma_f32_16x16x32_bf16 v[68:71], v[188:191], v[172:175], v[68:71]
	v_mfma_f32_16x16x32_bf16 v[120:123], v[184:187], v[152:155], v[120:123]
	v_mfma_f32_16x16x32_bf16 v[116:119], v[206:209], v[152:155], v[116:119]
	v_mfma_f32_16x16x32_bf16 v[104:107], v[184:187], v[160:163], v[104:107]
	v_mfma_f32_16x16x32_bf16 v[100:103], v[206:209], v[160:163], v[100:103]
	v_mfma_f32_16x16x32_bf16 v[88:91], v[184:187], v[168:171], v[88:91]
	v_mfma_f32_16x16x32_bf16 v[84:87], v[206:209], v[168:171], v[84:87]
	v_mfma_f32_16x16x32_bf16 v[72:75], v[184:187], v[176:179], v[72:75]
	v_mfma_f32_16x16x32_bf16 v[68:71], v[206:209], v[176:179], v[68:71]
	s_mov_b32 m0, s16
	v_lshl_add_u64 v[6:7], v[210:211], 0, s[70:71]
	s_barrier
	ds_read_b128 v[148:151], v204 offset:49152
	ds_read_b128 v[152:155], v204 offset:50176
	ds_read_b128 v[156:159], v204 offset:51200
	ds_read_b128 v[160:163], v204 offset:52224
	ds_read_b128 v[164:167], v204 offset:53248
	ds_read_b128 v[168:171], v204 offset:54272
	ds_read_b128 v[172:175], v204 offset:55296
	ds_read_b128 v[176:179], v204 offset:56320
	global_load_lds_dwordx4 v[6:7], off
	v_lshl_add_u64 v[6:7], v[210:211], 0, s[72:73]
	s_mov_b32 m0, s17
	s_nop 0
	global_load_lds_dwordx4 v[6:7], off
	s_barrier
	s_waitcnt lgkmcnt(0)
	s_waitcnt lgkmcnt(0)
	v_mfma_f32_16x16x32_bf16 v[64:67], v[132:135], v[148:151], v[64:67]
	v_mfma_f32_16x16x32_bf16 v[60:63], v[140:143], v[148:151], v[60:63]
	v_mfma_f32_16x16x32_bf16 v[48:51], v[132:135], v[156:159], v[48:51]
	v_mfma_f32_16x16x32_bf16 v[44:47], v[140:143], v[156:159], v[44:47]
	v_mfma_f32_16x16x32_bf16 v[32:35], v[132:135], v[164:167], v[32:35]
	v_mfma_f32_16x16x32_bf16 v[28:31], v[140:143], v[164:167], v[28:31]
	v_mfma_f32_16x16x32_bf16 v[16:19], v[132:135], v[172:175], v[16:19]
	v_mfma_f32_16x16x32_bf16 v[12:15], v[140:143], v[172:175], v[12:15]
	v_mfma_f32_16x16x32_bf16 v[64:67], v[136:139], v[152:155], v[64:67]
	v_mfma_f32_16x16x32_bf16 v[60:63], v[144:147], v[152:155], v[60:63]
	v_mfma_f32_16x16x32_bf16 v[48:51], v[136:139], v[160:163], v[48:51]
	v_mfma_f32_16x16x32_bf16 v[44:47], v[144:147], v[160:163], v[44:47]
	v_mfma_f32_16x16x32_bf16 v[32:35], v[136:139], v[168:171], v[32:35]
	v_mfma_f32_16x16x32_bf16 v[28:31], v[144:147], v[168:171], v[28:31]
	v_mfma_f32_16x16x32_bf16 v[16:19], v[136:139], v[176:179], v[16:19]
	v_mfma_f32_16x16x32_bf16 v[12:15], v[144:147], v[176:179], v[12:15]
	s_barrier
	s_add_i32 s4, s5, s42
	v_lshl_add_u64 v[6:7], v[200:201], 0, s[74:75]
	s_mov_b32 m0, s4
	s_nop 0
	global_load_lds_dwordx4 v[6:7], off
	v_lshl_add_u64 v[6:7], v[200:201], 0, s[76:77]
	s_add_i32 m0, s4, 0x2000
	s_nop 0
	global_load_lds_dwordx4 v[6:7], off
	s_waitcnt vmcnt(6)
	s_barrier
	v_mfma_f32_16x16x32_bf16 v[56:59], v[180:183], v[148:151], v[56:59]
	v_mfma_f32_16x16x32_bf16 v[52:55], v[188:191], v[148:151], v[52:55]
	v_mfma_f32_16x16x32_bf16 v[40:43], v[180:183], v[156:159], v[40:43]
	v_mfma_f32_16x16x32_bf16 v[36:39], v[188:191], v[156:159], v[36:39]
	v_mfma_f32_16x16x32_bf16 v[24:27], v[180:183], v[164:167], v[24:27]
	v_mfma_f32_16x16x32_bf16 v[20:23], v[188:191], v[164:167], v[20:23]
	v_mfma_f32_16x16x32_bf16 v[6:9], v[180:183], v[172:175], v[8:11]
	v_mfma_f32_16x16x32_bf16 v[2:5], v[188:191], v[172:175], v[2:5]
	v_mfma_f32_16x16x32_bf16 v[56:59], v[184:187], v[152:155], v[56:59]
	v_mfma_f32_16x16x32_bf16 v[52:55], v[206:209], v[152:155], v[52:55]
	v_mfma_f32_16x16x32_bf16 v[40:43], v[184:187], v[160:163], v[40:43]
	v_mfma_f32_16x16x32_bf16 v[36:39], v[206:209], v[160:163], v[36:39]
	v_mfma_f32_16x16x32_bf16 v[24:27], v[184:187], v[168:171], v[24:27]
	v_mfma_f32_16x16x32_bf16 v[20:23], v[206:209], v[168:171], v[20:23]
	v_mfma_f32_16x16x32_bf16 v[8:11], v[184:187], v[176:179], v[6:9]
	v_mfma_f32_16x16x32_bf16 v[4:7], v[206:209], v[176:179], v[2:5]
	s_add_u32 s34, s34, 0x100
	s_addc_u32 s35, s35, 0
	s_cmp_ge_u32 s0, s1
	s_barrier
	s_cbranch_scc1 .LBB0_563

.LBB0_627:
	ds_read_b128 v[128:131], v212
	ds_read_b128 v[132:135], v212 offset:1024
	ds_read_b128 v[136:139], v212 offset:2048
	ds_read_b128 v[140:143], v212 offset:3072
	s_add_i32 s49, s48, 2
	s_add_u32 s50, s64, 0xfff80080
	s_addc_u32 s51, s65, -1
	s_cmp_eq_u32 s27, s48
	s_cselect_b32 s51, s61, s51
	s_cselect_b32 s50, s60, s50
	s_cselect_b32 s67, s5, s47
	s_cselect_b32 s66, s4, s35
	v_lshl_add_u64 v[176:177], s[64:65], 0, v[198:199]
	s_add_i32 m0, s29, 0xc000
	ds_read_b128 v[144:147], v213
	ds_read_b128 v[148:151], v213 offset:1024
	ds_read_b128 v[152:155], v213 offset:2048
	ds_read_b128 v[156:159], v213 offset:3072
	ds_read_b128 v[160:163], v213 offset:4096
	ds_read_b128 v[164:167], v213 offset:5120
	ds_read_b128 v[168:171], v213 offset:6144
	ds_read_b128 v[172:175], v213 offset:7168
	global_load_lds_dwordx4 v[176:177], off
	v_lshl_add_u64 v[176:177], v[176:177], 0, s[18:19]
	s_add_i32 m0, s29, 0xe000
	s_nop 0
	global_load_lds_dwordx4 v[176:177], off
	s_waitcnt lgkmcnt(8)
	s_barrier
	s_waitcnt lgkmcnt(0)
	s_waitcnt lgkmcnt(0)
	v_mfma_f32_16x16x32_bf16 v[124:127], v[128:131], v[144:147], v[124:127]
	v_mfma_f32_16x16x32_bf16 v[120:123], v[136:139], v[144:147], v[120:123]
	v_mfma_f32_16x16x32_bf16 v[116:119], v[128:131], v[152:155], v[116:119]
	v_mfma_f32_16x16x32_bf16 v[112:115], v[136:139], v[152:155], v[112:115]
	v_mfma_f32_16x16x32_bf16 v[104:107], v[128:131], v[160:163], v[104:107]
	v_mfma_f32_16x16x32_bf16 v[96:99], v[136:139], v[160:163], v[96:99]
	v_mfma_f32_16x16x32_bf16 v[88:91], v[128:131], v[168:171], v[88:91]
	v_mfma_f32_16x16x32_bf16 v[80:83], v[136:139], v[168:171], v[80:83]
	v_mfma_f32_16x16x32_bf16 v[124:127], v[132:135], v[148:151], v[124:127]
	v_mfma_f32_16x16x32_bf16 v[120:123], v[140:143], v[148:151], v[120:123]
	v_mfma_f32_16x16x32_bf16 v[116:119], v[132:135], v[156:159], v[116:119]
	v_mfma_f32_16x16x32_bf16 v[112:115], v[140:143], v[156:159], v[112:115]
	v_mfma_f32_16x16x32_bf16 v[104:107], v[132:135], v[164:167], v[104:107]
	v_mfma_f32_16x16x32_bf16 v[96:99], v[140:143], v[164:167], v[96:99]
	v_mfma_f32_16x16x32_bf16 v[88:91], v[132:135], v[172:175], v[88:91]
	v_mfma_f32_16x16x32_bf16 v[80:83], v[140:143], v[172:175], v[80:83]
	s_barrier
	s_add_i32 s48, s44, s28
	v_lshl_add_u64 v[200:201], s[66:67], 0, v[194:195]
	s_mov_b32 m0, s48
	ds_read_b128 v[176:179], v214
	ds_read_b128 v[180:183], v214 offset:1024
	ds_read_b128 v[184:187], v214 offset:2048
	ds_read_b128 v[188:191], v214 offset:3072
	global_load_lds_dwordx4 v[200:201], off
	v_lshl_add_u64 v[202:203], v[200:201], 0, s[18:19]
	s_add_i32 m0, s48, 0x2000
	s_nop 0
	global_load_lds_dwordx4 v[202:203], off
	s_barrier
	s_waitcnt lgkmcnt(0)
	s_waitcnt lgkmcnt(0)
	v_mfma_f32_16x16x32_bf16 v[108:111], v[176:179], v[144:147], v[108:111]
	v_mfma_f32_16x16x32_bf16 v[100:103], v[184:187], v[144:147], v[100:103]
	v_mfma_f32_16x16x32_bf16 v[92:95], v[176:179], v[152:155], v[92:95]
	v_mfma_f32_16x16x32_bf16 v[84:87], v[184:187], v[152:155], v[84:87]
	v_mfma_f32_16x16x32_bf16 v[76:79], v[176:179], v[160:163], v[76:79]
	v_mfma_f32_16x16x32_bf16 v[72:75], v[184:187], v[160:163], v[72:75]
	v_mfma_f32_16x16x32_bf16 v[68:71], v[176:179], v[168:171], v[68:71]
	v_mfma_f32_16x16x32_bf16 v[64:67], v[184:187], v[168:171], v[64:67]
	v_mfma_f32_16x16x32_bf16 v[108:111], v[180:183], v[148:151], v[108:111]
	v_mfma_f32_16x16x32_bf16 v[100:103], v[188:191], v[148:151], v[100:103]
	v_mfma_f32_16x16x32_bf16 v[92:95], v[180:183], v[156:159], v[92:95]
	v_mfma_f32_16x16x32_bf16 v[84:87], v[188:191], v[156:159], v[84:87]
	v_mfma_f32_16x16x32_bf16 v[76:79], v[180:183], v[164:167], v[76:79]
	v_mfma_f32_16x16x32_bf16 v[72:75], v[188:191], v[164:167], v[72:75]
	v_mfma_f32_16x16x32_bf16 v[68:71], v[180:183], v[172:175], v[68:71]
	v_mfma_f32_16x16x32_bf16 v[64:67], v[188:191], v[172:175], v[64:67]
	s_mov_b32 m0, s29
	v_lshl_add_u64 v[202:203], s[50:51], 0, v[192:193]
	s_barrier
	ds_read_b128 v[144:147], v213 offset:16384
	ds_read_b128 v[148:151], v213 offset:17408
	ds_read_b128 v[152:155], v213 offset:18432
	ds_read_b128 v[156:159], v213 offset:19456
	ds_read_b128 v[160:163], v213 offset:20480
	ds_read_b128 v[164:167], v213 offset:21504
	ds_read_b128 v[168:171], v213 offset:22528
	ds_read_b128 v[172:175], v213 offset:23552
	global_load_lds_dwordx4 v[202:203], off
	v_lshl_add_u64 v[204:205], v[202:203], 0, s[18:19]
	s_mov_b32 m0, s30
	s_nop 0
	global_load_lds_dwordx4 v[204:205], off
	s_barrier
	s_waitcnt lgkmcnt(0)
	s_waitcnt lgkmcnt(0)
	v_mfma_f32_16x16x32_bf16 v[60:63], v[128:131], v[144:147], v[60:63]
	v_mfma_f32_16x16x32_bf16 v[56:59], v[136:139], v[144:147], v[56:59]
	v_mfma_f32_16x16x32_bf16 v[52:55], v[128:131], v[152:155], v[52:55]
	v_mfma_f32_16x16x32_bf16 v[48:51], v[136:139], v[152:155], v[48:51]
	v_mfma_f32_16x16x32_bf16 v[40:43], v[128:131], v[160:163], v[40:43]
	v_mfma_f32_16x16x32_bf16 v[32:35], v[136:139], v[160:163], v[32:35]
	v_mfma_f32_16x16x32_bf16 v[24:27], v[128:131], v[168:171], v[24:27]
	v_mfma_f32_16x16x32_bf16 v[16:19], v[136:139], v[168:171], v[16:19]
	v_mfma_f32_16x16x32_bf16 v[60:63], v[132:135], v[148:151], v[60:63]
	v_mfma_f32_16x16x32_bf16 v[56:59], v[140:143], v[148:151], v[56:59]
	v_mfma_f32_16x16x32_bf16 v[52:55], v[132:135], v[156:159], v[52:55]
	v_mfma_f32_16x16x32_bf16 v[48:51], v[140:143], v[156:159], v[48:51]
	v_mfma_f32_16x16x32_bf16 v[40:43], v[132:135], v[164:167], v[40:43]
	v_mfma_f32_16x16x32_bf16 v[32:35], v[140:143], v[164:167], v[32:35]
	v_mfma_f32_16x16x32_bf16 v[24:27], v[132:135], v[172:175], v[24:27]
	v_mfma_f32_16x16x32_bf16 v[16:19], v[140:143], v[172:175], v[16:19]
	s_barrier
	s_add_i32 s48, s45, s28
	v_lshl_add_u64 v[128:129], v[200:201], 0, s[22:23]
	s_mov_b32 m0, s48
	s_nop 0
	global_load_lds_dwordx4 v[128:129], off
	v_lshl_add_u64 v[128:129], v[200:201], 0, s[24:25]
	s_add_i32 m0, s48, 0x2000
	s_nop 0
	global_load_lds_dwordx4 v[128:129], off
	s_waitcnt vmcnt(6)
	s_barrier
	v_mfma_f32_16x16x32_bf16 v[44:47], v[176:179], v[144:147], v[44:47]
	v_mfma_f32_16x16x32_bf16 v[36:39], v[184:187], v[144:147], v[36:39]
	v_mfma_f32_16x16x32_bf16 v[28:31], v[176:179], v[152:155], v[28:31]
	v_mfma_f32_16x16x32_bf16 v[20:23], v[184:187], v[152:155], v[20:23]
	v_mfma_f32_16x16x32_bf16 v[12:15], v[176:179], v[160:163], v[12:15]
	v_mfma_f32_16x16x32_bf16 v[8:11], v[184:187], v[160:163], v[8:11]
	v_mfma_f32_16x16x32_bf16 v[4:7], v[176:179], v[168:171], v[4:7]
	v_mfma_f32_16x16x32_bf16 v[0:3], v[184:187], v[168:171], v[0:3]
	v_mfma_f32_16x16x32_bf16 v[44:47], v[180:183], v[148:151], v[44:47]
	v_mfma_f32_16x16x32_bf16 v[36:39], v[188:191], v[148:151], v[36:39]
	v_mfma_f32_16x16x32_bf16 v[28:31], v[180:183], v[156:159], v[28:31]
	v_mfma_f32_16x16x32_bf16 v[20:23], v[188:191], v[156:159], v[20:23]
	v_mfma_f32_16x16x32_bf16 v[12:15], v[180:183], v[164:167], v[12:15]
	v_mfma_f32_16x16x32_bf16 v[8:11], v[188:191], v[164:167], v[8:11]
	v_mfma_f32_16x16x32_bf16 v[4:7], v[180:183], v[172:175], v[4:7]
	v_mfma_f32_16x16x32_bf16 v[0:3], v[188:191], v[172:175], v[0:3]
	s_add_i32 s48, 0, 0x18000
	v_add_u32_e32 v140, s48, v211
	s_barrier
	ds_read_b128 v[128:131], v140
	ds_read_b128 v[132:135], v140 offset:1024
	ds_read_b128 v[136:139], v140 offset:2048
	ds_read_b128 v[140:143], v140 offset:3072
	s_mov_b32 m0, s33
	v_lshl_add_u64 v[176:177], v[202:203], 0, s[22:23]
	ds_read_b128 v[144:147], v213 offset:32768
	ds_read_b128 v[148:151], v213 offset:33792
	ds_read_b128 v[152:155], v213 offset:34816
	ds_read_b128 v[156:159], v213 offset:35840
	ds_read_b128 v[160:163], v213 offset:36864
	ds_read_b128 v[164:167], v213 offset:37888
	ds_read_b128 v[168:171], v213 offset:38912
	ds_read_b128 v[172:175], v213 offset:39936
	global_load_lds_dwordx4 v[176:177], off
	v_lshl_add_u64 v[176:177], v[202:203], 0, s[24:25]
	s_mov_b32 m0, s36
	s_nop 0
	global_load_lds_dwordx4 v[176:177], off
	s_waitcnt lgkmcnt(8)
	s_barrier
	s_waitcnt lgkmcnt(0)
	s_waitcnt lgkmcnt(0)
	v_mfma_f32_16x16x32_bf16 v[124:127], v[128:131], v[144:147], v[124:127]
	v_mfma_f32_16x16x32_bf16 v[120:123], v[136:139], v[144:147], v[120:123]
	v_mfma_f32_16x16x32_bf16 v[116:119], v[128:131], v[152:155], v[116:119]
	v_mfma_f32_16x16x32_bf16 v[112:115], v[136:139], v[152:155], v[112:115]
	v_mfma_f32_16x16x32_bf16 v[104:107], v[128:131], v[160:163], v[104:107]
	v_mfma_f32_16x16x32_bf16 v[96:99], v[136:139], v[160:163], v[96:99]
	v_mfma_f32_16x16x32_bf16 v[88:91], v[128:131], v[168:171], v[88:91]
	v_mfma_f32_16x16x32_bf16 v[80:83], v[136:139], v[168:171], v[80:83]
	v_mfma_f32_16x16x32_bf16 v[124:127], v[132:135], v[148:151], v[124:127]
	v_mfma_f32_16x16x32_bf16 v[120:123], v[140:143], v[148:151], v[120:123]
	v_mfma_f32_16x16x32_bf16 v[116:119], v[132:135], v[156:159], v[116:119]
	v_mfma_f32_16x16x32_bf16 v[112:115], v[140:143], v[156:159], v[112:115]
	v_mfma_f32_16x16x32_bf16 v[104:107], v[132:135], v[164:167], v[104:107]
	v_mfma_f32_16x16x32_bf16 v[96:99], v[140:143], v[164:167], v[96:99]
	v_mfma_f32_16x16x32_bf16 v[88:91], v[132:135], v[172:175], v[88:91]
	v_mfma_f32_16x16x32_bf16 v[80:83], v[140:143], v[172:175], v[80:83]
	s_barrier
	s_add_i32 s50, 0, 0x1c000
	s_add_i32 s48, s48, s28
	v_add_u32_e32 v188, s50, v211
	v_lshl_add_u64 v[204:205], v[200:201], 0, s[52:53]
	s_mov_b32 m0, s48
	ds_read_b128 v[176:179], v188
	ds_read_b128 v[180:183], v188 offset:1024
	ds_read_b128 v[184:187], v188 offset:2048
	ds_read_b128 v[188:191], v188 offset:3072
	global_load_lds_dwordx4 v[204:205], off
	v_lshl_add_u64 v[204:205], v[200:201], 0, s[54:55]
	s_add_i32 m0, s48, 0x2000
	s_nop 0
	global_load_lds_dwordx4 v[204:205], off
	s_barrier
	s_waitcnt lgkmcnt(0)
	s_waitcnt lgkmcnt(0)
	v_mfma_f32_16x16x32_bf16 v[108:111], v[176:179], v[144:147], v[108:111]
	v_mfma_f32_16x16x32_bf16 v[100:103], v[184:187], v[144:147], v[100:103]
	v_mfma_f32_16x16x32_bf16 v[92:95], v[176:179], v[152:155], v[92:95]
	v_mfma_f32_16x16x32_bf16 v[84:87], v[184:187], v[152:155], v[84:87]
	v_mfma_f32_16x16x32_bf16 v[76:79], v[176:179], v[160:163], v[76:79]
	v_mfma_f32_16x16x32_bf16 v[72:75], v[184:187], v[160:163], v[72:75]
	v_mfma_f32_16x16x32_bf16 v[68:71], v[176:179], v[168:171], v[68:71]
	v_mfma_f32_16x16x32_bf16 v[64:67], v[184:187], v[168:171], v[64:67]
	v_mfma_f32_16x16x32_bf16 v[108:111], v[180:183], v[148:151], v[108:111]
	v_mfma_f32_16x16x32_bf16 v[100:103], v[188:191], v[148:151], v[100:103]
	v_mfma_f32_16x16x32_bf16 v[92:95], v[180:183], v[156:159], v[92:95]
	v_mfma_f32_16x16x32_bf16 v[84:87], v[188:191], v[156:159], v[84:87]
	v_mfma_f32_16x16x32_bf16 v[76:79], v[180:183], v[164:167], v[76:79]
	v_mfma_f32_16x16x32_bf16 v[72:75], v[188:191], v[164:167], v[72:75]
	v_mfma_f32_16x16x32_bf16 v[68:71], v[180:183], v[172:175], v[68:71]
	v_mfma_f32_16x16x32_bf16 v[64:67], v[188:191], v[172:175], v[64:67]
	s_mov_b32 m0, s42
	v_lshl_add_u64 v[204:205], v[202:203], 0, s[52:53]
	s_barrier
	ds_read_b128 v[144:147], v213 offset:49152
	ds_read_b128 v[148:151], v213 offset:50176
	ds_read_b128 v[152:155], v213 offset:51200
	ds_read_b128 v[156:159], v213 offset:52224
	ds_read_b128 v[160:163], v213 offset:53248
	ds_read_b128 v[164:167], v213 offset:54272
	ds_read_b128 v[168:171], v213 offset:55296
	ds_read_b128 v[172:175], v213 offset:56320
	global_load_lds_dwordx4 v[204:205], off
	v_lshl_add_u64 v[202:203], v[202:203], 0, s[54:55]
	s_mov_b32 m0, s43
	s_nop 0
	global_load_lds_dwordx4 v[202:203], off
	s_barrier
	s_waitcnt lgkmcnt(0)
	s_waitcnt lgkmcnt(0)
	v_mfma_f32_16x16x32_bf16 v[60:63], v[128:131], v[144:147], v[60:63]
	v_mfma_f32_16x16x32_bf16 v[56:59], v[136:139], v[144:147], v[56:59]
	v_mfma_f32_16x16x32_bf16 v[52:55], v[128:131], v[152:155], v[52:55]
	v_mfma_f32_16x16x32_bf16 v[48:51], v[136:139], v[152:155], v[48:51]
	v_mfma_f32_16x16x32_bf16 v[40:43], v[128:131], v[160:163], v[40:43]
	v_mfma_f32_16x16x32_bf16 v[32:35], v[136:139], v[160:163], v[32:35]
	v_mfma_f32_16x16x32_bf16 v[24:27], v[128:131], v[168:171], v[24:27]
	v_mfma_f32_16x16x32_bf16 v[16:19], v[136:139], v[168:171], v[16:19]
	v_mfma_f32_16x16x32_bf16 v[60:63], v[132:135], v[148:151], v[60:63]
	v_mfma_f32_16x16x32_bf16 v[56:59], v[140:143], v[148:151], v[56:59]
	v_mfma_f32_16x16x32_bf16 v[52:55], v[132:135], v[156:159], v[52:55]
	v_mfma_f32_16x16x32_bf16 v[48:51], v[140:143], v[156:159], v[48:51]
	v_mfma_f32_16x16x32_bf16 v[40:43], v[132:135], v[164:167], v[40:43]
	v_mfma_f32_16x16x32_bf16 v[32:35], v[140:143], v[164:167], v[32:35]
	v_mfma_f32_16x16x32_bf16 v[24:27], v[132:135], v[172:175], v[24:27]
	v_mfma_f32_16x16x32_bf16 v[16:19], v[140:143], v[172:175], v[16:19]
	s_barrier
	s_add_i32 s48, s50, s28
	v_lshl_add_u64 v[128:129], v[200:201], 0, s[56:57]
	s_mov_b32 m0, s48
	s_nop 0
	global_load_lds_dwordx4 v[128:129], off
	v_lshl_add_u64 v[128:129], v[200:201], 0, s[58:59]
	s_add_i32 m0, s48, 0x2000
	s_nop 0
	global_load_lds_dwordx4 v[128:129], off
	s_waitcnt vmcnt(6)
	s_barrier
	v_mfma_f32_16x16x32_bf16 v[44:47], v[176:179], v[144:147], v[44:47]
	v_mfma_f32_16x16x32_bf16 v[36:39], v[184:187], v[144:147], v[36:39]
	v_mfma_f32_16x16x32_bf16 v[28:31], v[176:179], v[152:155], v[28:31]
	v_mfma_f32_16x16x32_bf16 v[20:23], v[184:187], v[152:155], v[20:23]
	v_mfma_f32_16x16x32_bf16 v[12:15], v[176:179], v[160:163], v[12:15]
	v_mfma_f32_16x16x32_bf16 v[8:11], v[184:187], v[160:163], v[8:11]
	v_mfma_f32_16x16x32_bf16 v[4:7], v[176:179], v[168:171], v[4:7]
	v_mfma_f32_16x16x32_bf16 v[0:3], v[184:187], v[168:171], v[0:3]
	v_mfma_f32_16x16x32_bf16 v[44:47], v[180:183], v[148:151], v[44:47]
	v_mfma_f32_16x16x32_bf16 v[36:39], v[188:191], v[148:151], v[36:39]
	v_mfma_f32_16x16x32_bf16 v[28:31], v[180:183], v[156:159], v[28:31]
	v_mfma_f32_16x16x32_bf16 v[20:23], v[188:191], v[156:159], v[20:23]
	v_mfma_f32_16x16x32_bf16 v[12:15], v[180:183], v[164:167], v[12:15]
	v_mfma_f32_16x16x32_bf16 v[8:11], v[188:191], v[164:167], v[8:11]
	v_mfma_f32_16x16x32_bf16 v[4:7], v[180:183], v[172:175], v[4:7]
	v_mfma_f32_16x16x32_bf16 v[0:3], v[188:191], v[172:175], v[0:3]
	s_add_u32 s64, s64, 0x100
	s_addc_u32 s65, s65, 0
	s_add_u32 s35, s35, 0x100
	s_addc_u32 s47, s47, 0
	s_cmp_ge_u32 s49, s10
	s_mov_b32 s48, s49
	s_barrier
	s_cbranch_scc0 .LBB0_627
	v_mov_b32_e32 v128, v210
	s_mov_b32 s47, s41
	v_and_b32_e32 v215, 15, v128
	v_bfe_u32 v196, v128, 4, 2
	s_mov_b32 s10, s21
	s_mov_b64 s[64:65], -1
	s_and_b64 vcc, exec, s[62:63]
	s_cbranch_vccz .LBB0_630
	s_sub_i32 s27, s34, 32
	s_cmp_lt_i32 s34, 32
	v_readlane_b32 s64, v245, 34
	s_movk_i32 s35, 0x3000
	s_cselect_b32 s48, s34, s27
	v_readlane_b32 s65, v245, 35
	v_readlane_b32 s68, v245, 38
	v_readlane_b32 s69, v245, 39
	s_mov_b32 s49, 0x1d5b3600
	s_cselect_b32 s35, s35, 0x6000
	s_cselect_b32 s27, s65, s69
	s_cselect_b32 s62, s64, s68
	s_cselect_b32 s63, s49, 0x1f5b3600
	s_ashr_i32 s49, s48, 31
	s_lshl_b64 s[50:51], s[6:7], 2
	s_add_u32 s62, s62, s50
	s_addc_u32 s27, s27, s51
	s_add_u32 s63, s13, s63
	s_addc_u32 s64, s14, 0
	s_lshl_b32 s50, s31, 8
	s_lshl_b32 s51, s47, 5
	s_add_i32 s51, s51, s50
	s_cmp_gt_i32 s34, 15
	s_cselect_b32 s35, s35, 0
	v_lshl_or_b32 v144, v196, 3, s51
	s_lshl_b32 s35, s35, 2
	s_add_u32 s50, s37, s35
	v_ashrrev_i32_e32 v145, 31, v144
	s_addc_u32 s51, s38, 0
	v_lshlrev_b64 v[146:147], 2, v[144:145]
	v_lshl_add_u64 v[132:133], s[50:51], 0, v[146:147]
	s_lshl_b64 s[50:51], s[48:49], 21
	s_add_u32 s50, s62, s50
	s_addc_u32 s51, s27, s51
	s_lshl_b64 s[48:49], s[48:49], 20
	v_lshl_or_b32 v202, s10, 6, v215
	s_add_u32 s48, s63, s48
	s_addc_u32 s49, s64, s49
	v_ashrrev_i32_e32 v203, 31, v202
	v_lshl_add_u64 v[204:205], s[50:51], 0, v[146:147]
	v_lshl_add_u64 v[200:201], v[144:145], 1, s[48:49]
	v_lshlrev_b64 v[144:145], 13, v[202:203]
	v_lshl_add_u64 v[144:145], v[204:205], 0, v[144:145]
	global_load_dwordx4 v[136:139], v[132:133], off offset:16
	global_load_dwordx4 v[140:143], v[132:133], off
	global_load_dwordx4 v[128:131], v[132:133], off offset:528
	s_nop 0
	global_load_dwordx4 v[132:135], v[132:133], off offset:512
	s_nop 0
	global_load_dwordx4 v[216:219], v[144:145], off offset:16
	global_load_dwordx4 v[220:223], v[144:145], off
	global_load_dwordx4 v[224:227], v[144:145], off offset:528
	global_load_dwordx4 v[228:231], v[144:145], off offset:512
	v_or_b32_e32 v232, 16, v202
	v_ashrrev_i32_e32 v233, 31, v232
	v_lshlrev_b64 v[144:145], 13, v[232:233]
	v_lshl_add_u64 v[144:145], v[204:205], 0, v[144:145]
	v_or_b32_e32 v208, 32, v202
	global_load_dwordx4 v[184:187], v[144:145], off offset:16
	global_load_dwordx4 v[188:191], v[144:145], off
	global_load_dwordx4 v[172:175], v[144:145], off offset:528
	global_load_dwordx4 v[180:183], v[144:145], off offset:512
	v_ashrrev_i32_e32 v209, 31, v208
	v_lshlrev_b64 v[144:145], 13, v[208:209]
	v_lshl_add_u64 v[144:145], v[204:205], 0, v[144:145]
	v_or_b32_e32 v206, 48, v202
	global_load_dwordx4 v[168:171], v[144:145], off offset:16
	global_load_dwordx4 v[176:179], v[144:145], off
	global_load_dwordx4 v[156:159], v[144:145], off offset:528
	global_load_dwordx4 v[164:167], v[144:145], off offset:512
	v_ashrrev_i32_e32 v207, 31, v206
	v_lshlrev_b64 v[144:145], 13, v[206:207]
	v_lshl_add_u64 v[148:149], v[204:205], 0, v[144:145]
	global_load_dwordx4 v[152:155], v[148:149], off offset:16
	global_load_dwordx4 v[160:163], v[148:149], off
	global_load_dwordx4 v[144:147], v[148:149], off offset:528
	s_nop 0
	global_load_dwordx4 v[148:151], v[148:149], off offset:512
	v_lshlrev_b64 v[234:235], 12, v[202:203]
	v_lshl_add_u64 v[234:235], v[200:201], 0, v[234:235]
	v_readlane_b32 s66, v245, 36
	v_readlane_b32 s67, v245, 37
	v_readlane_b32 s70, v245, 40
	v_readlane_b32 s71, v245, 41
	v_readlane_b32 s72, v245, 42
	v_readlane_b32 s73, v245, 43
	v_readlane_b32 s74, v245, 44
	v_readlane_b32 s75, v245, 45
	v_readlane_b32 s76, v245, 46
	v_readlane_b32 s77, v245, 47
	v_readlane_b32 s78, v245, 48
	v_readlane_b32 s79, v245, 49
	s_mov_b64 s[64:65], 0
	s_waitcnt vmcnt(0)
	v_pk_fma_f32 v[236:237], v[122:123], v[138:139], v[218:219]
	v_pk_fma_f32 v[222:223], v[126:127], v[142:143], v[222:223]
	v_pk_fma_f32 v[220:221], v[124:125], v[140:141], v[220:221]
	v_pk_fma_f32 v[218:219], v[120:121], v[136:137], v[216:217]
	v_cvt_pk_bf16_f32 v216, v220, v221
	v_cvt_pk_bf16_f32 v217, v222, v223
	v_pk_fma_f32 v[220:221], v[102:103], v[130:131], v[226:227]
	v_cvt_pk_bf16_f32 v218, v218, v219
	v_cvt_pk_bf16_f32 v219, v236, v237
	global_store_dwordx4 v[234:235], v[216:219], off
	v_pk_fma_f32 v[222:223], v[100:101], v[128:129], v[224:225]
	v_pk_fma_f32 v[190:191], v[118:119], v[142:143], v[190:191]
	v_pk_fma_f32 v[216:217], v[108:109], v[132:133], v[228:229]
	v_pk_fma_f32 v[218:219], v[110:111], v[134:135], v[230:231]
	v_cvt_pk_bf16_f32 v216, v216, v217
	v_pk_fma_f32 v[188:189], v[116:117], v[140:141], v[188:189]
	v_cvt_pk_bf16_f32 v217, v218, v219
	v_cvt_pk_bf16_f32 v218, v222, v223
	v_cvt_pk_bf16_f32 v219, v220, v221
	global_store_dwordx4 v[234:235], v[216:219], off offset:256
	v_pk_fma_f32 v[182:183], v[94:95], v[134:135], v[182:183]
	v_pk_fma_f32 v[180:181], v[92:93], v[132:133], v[180:181]
	v_lshlrev_b64 v[216:217], 12, v[232:233]
	v_lshl_add_u64 v[216:217], v[200:201], 0, v[216:217]
	v_pk_fma_f32 v[218:219], v[114:115], v[138:139], v[186:187]
	v_pk_fma_f32 v[186:187], v[112:113], v[136:137], v[184:185]
	v_cvt_pk_bf16_f32 v184, v188, v189
	v_cvt_pk_bf16_f32 v185, v190, v191
	v_pk_fma_f32 v[176:177], v[104:105], v[140:141], v[176:177]
	v_cvt_pk_bf16_f32 v186, v186, v187
	v_cvt_pk_bf16_f32 v187, v218, v219
	global_store_dwordx4 v[216:217], v[184:187], off
	v_pk_fma_f32 v[166:167], v[78:79], v[134:135], v[166:167]
	v_pk_fma_f32 v[164:165], v[76:77], v[132:133], v[164:165]
	v_pk_fma_f32 v[184:185], v[86:87], v[130:131], v[174:175]
	v_pk_fma_f32 v[174:175], v[84:85], v[128:129], v[172:173]
	v_cvt_pk_bf16_f32 v172, v180, v181
	v_cvt_pk_bf16_f32 v173, v182, v183
	v_pk_fma_f32 v[160:161], v[88:89], v[140:141], v[160:161]
	v_cvt_pk_bf16_f32 v174, v174, v175
	v_cvt_pk_bf16_f32 v175, v184, v185
	global_store_dwordx4 v[216:217], v[172:175], off offset:256
	v_add_u32_e32 v224, 0x80, v202
	v_pk_fma_f32 v[150:151], v[70:71], v[134:135], v[150:151]
	v_lshlrev_b64 v[172:173], 12, v[208:209]
	v_lshl_add_u64 v[172:173], v[200:201], 0, v[172:173]
	v_pk_fma_f32 v[174:175], v[106:107], v[142:143], v[178:179]
	v_pk_fma_f32 v[178:179], v[98:99], v[138:139], v[170:171]
	v_pk_fma_f32 v[170:171], v[96:97], v[136:137], v[168:169]
	v_cvt_pk_bf16_f32 v168, v176, v177
	v_cvt_pk_bf16_f32 v169, v174, v175
	v_pk_fma_f32 v[148:149], v[68:69], v[132:133], v[148:149]
	v_cvt_pk_bf16_f32 v170, v170, v171
	v_cvt_pk_bf16_f32 v171, v178, v179
	global_store_dwordx4 v[172:173], v[168:171], off
	v_ashrrev_i32_e32 v225, 31, v224
	v_add_u32_e32 v226, 0x90, v202
	v_pk_fma_f32 v[168:169], v[74:75], v[130:131], v[158:159]
	v_pk_fma_f32 v[158:159], v[72:73], v[128:129], v[156:157]
	v_cvt_pk_bf16_f32 v156, v164, v165
	v_cvt_pk_bf16_f32 v157, v166, v167
	v_ashrrev_i32_e32 v227, 31, v226
	v_cvt_pk_bf16_f32 v158, v158, v159
	v_cvt_pk_bf16_f32 v159, v168, v169
	global_store_dwordx4 v[172:173], v[156:159], off offset:256
	v_add_u32_e32 v228, 0xa0, v202
	v_ashrrev_i32_e32 v229, 31, v228
	v_lshlrev_b64 v[156:157], 12, v[206:207]
	v_lshl_add_u64 v[156:157], v[200:201], 0, v[156:157]
	v_pk_fma_f32 v[158:159], v[90:91], v[142:143], v[162:163]
	v_pk_fma_f32 v[162:163], v[82:83], v[138:139], v[154:155]
	v_pk_fma_f32 v[154:155], v[80:81], v[136:137], v[152:153]
	v_cvt_pk_bf16_f32 v152, v160, v161
	v_cvt_pk_bf16_f32 v153, v158, v159
	v_lshlrev_b64 v[160:161], 13, v[226:227]
	v_cvt_pk_bf16_f32 v154, v154, v155
	v_cvt_pk_bf16_f32 v155, v162, v163
	global_store_dwordx4 v[156:157], v[152:155], off
	v_lshl_add_u64 v[172:173], v[204:205], 0, v[160:161]
	v_lshlrev_b64 v[176:177], 13, v[228:229]
	v_pk_fma_f32 v[152:153], v[66:67], v[130:131], v[146:147]
	v_pk_fma_f32 v[146:147], v[64:65], v[128:129], v[144:145]
	v_cvt_pk_bf16_f32 v144, v148, v149
	v_cvt_pk_bf16_f32 v145, v150, v151
	v_lshl_add_u64 v[188:189], v[204:205], 0, v[176:177]
	v_cvt_pk_bf16_f32 v146, v146, v147
	v_cvt_pk_bf16_f32 v147, v152, v153
	global_store_dwordx4 v[156:157], v[144:147], off offset:256
	v_add_u32_e32 v230, 0xb0, v202
	v_ashrrev_i32_e32 v231, 31, v230
	v_lshlrev_b64 v[144:145], 13, v[224:225]
	v_lshl_add_u64 v[156:157], v[204:205], 0, v[144:145]
	global_load_dwordx4 v[144:147], v[156:157], off offset:16
	global_load_dwordx4 v[148:151], v[156:157], off
	global_load_dwordx4 v[152:155], v[156:157], off offset:528
	s_nop 0
	global_load_dwordx4 v[156:159], v[156:157], off offset:512
	s_nop 0
	global_load_dwordx4 v[160:163], v[172:173], off offset:16
	global_load_dwordx4 v[164:167], v[172:173], off
	global_load_dwordx4 v[168:171], v[172:173], off offset:528
	s_nop 0
	global_load_dwordx4 v[172:175], v[172:173], off offset:512
	s_nop 0
	global_load_dwordx4 v[176:179], v[188:189], off offset:16
	global_load_dwordx4 v[180:183], v[188:189], off
	global_load_dwordx4 v[184:187], v[188:189], off offset:528
	s_nop 0
	global_load_dwordx4 v[188:191], v[188:189], off offset:512
	v_lshlrev_b64 v[202:203], 13, v[230:231]
	v_lshl_add_u64 v[220:221], v[204:205], 0, v[202:203]
	global_load_dwordx4 v[202:205], v[220:221], off offset:16
	global_load_dwordx4 v[206:209], v[220:221], off
	global_load_dwordx4 v[216:219], v[220:221], off offset:528
	s_nop 0
	global_load_dwordx4 v[220:223], v[220:221], off offset:512
	v_lshlrev_b64 v[224:225], 12, v[224:225]
	v_lshl_add_u64 v[224:225], v[200:201], 0, v[224:225]
	s_waitcnt vmcnt(0)
	v_pk_fma_f32 v[232:233], v[58:59], v[138:139], v[146:147]
	v_pk_fma_f32 v[150:151], v[62:63], v[142:143], v[150:151]
	v_pk_fma_f32 v[148:149], v[60:61], v[140:141], v[148:149]
	v_pk_fma_f32 v[146:147], v[56:57], v[136:137], v[144:145]
	v_cvt_pk_bf16_f32 v144, v148, v149
	v_cvt_pk_bf16_f32 v145, v150, v151
	v_pk_fma_f32 v[148:149], v[38:39], v[130:131], v[154:155]
	v_cvt_pk_bf16_f32 v146, v146, v147
	v_cvt_pk_bf16_f32 v147, v232, v233
	global_store_dwordx4 v[224:225], v[144:147], off
	v_pk_fma_f32 v[150:151], v[36:37], v[128:129], v[152:153]
	v_pk_fma_f32 v[152:153], v[48:49], v[136:137], v[160:161]
	v_pk_fma_f32 v[144:145], v[44:45], v[132:133], v[156:157]
	v_pk_fma_f32 v[146:147], v[46:47], v[134:135], v[158:159]
	v_cvt_pk_bf16_f32 v144, v144, v145
	s_nop 0
	v_cvt_pk_bf16_f32 v145, v146, v147
	v_cvt_pk_bf16_f32 v146, v150, v151
	v_cvt_pk_bf16_f32 v147, v148, v149
	global_store_dwordx4 v[224:225], v[144:147], off offset:256
	v_pk_fma_f32 v[150:151], v[50:51], v[138:139], v[162:163]
	s_nop 0
	v_lshlrev_b64 v[144:145], 12, v[226:227]
	v_lshl_add_u64 v[148:149], v[200:201], 0, v[144:145]
	v_pk_fma_f32 v[144:145], v[52:53], v[140:141], v[164:165]
	v_pk_fma_f32 v[146:147], v[54:55], v[142:143], v[166:167]
	v_cvt_pk_bf16_f32 v144, v144, v145
	s_nop 0
	v_cvt_pk_bf16_f32 v145, v146, v147
	v_cvt_pk_bf16_f32 v146, v152, v153
	v_cvt_pk_bf16_f32 v147, v150, v151
	global_store_dwordx4 v[148:149], v[144:147], off
	v_pk_fma_f32 v[150:151], v[22:23], v[130:131], v[170:171]
	v_pk_fma_f32 v[152:153], v[20:21], v[128:129], v[168:169]
	v_pk_fma_f32 v[144:145], v[28:29], v[132:133], v[172:173]
	v_pk_fma_f32 v[146:147], v[30:31], v[134:135], v[174:175]
	v_cvt_pk_bf16_f32 v144, v144, v145
	s_nop 0
	v_cvt_pk_bf16_f32 v145, v146, v147
	v_cvt_pk_bf16_f32 v146, v152, v153
	v_cvt_pk_bf16_f32 v147, v150, v151
	global_store_dwordx4 v[148:149], v[144:147], off offset:256
	v_pk_fma_f32 v[150:151], v[34:35], v[138:139], v[178:179]
	v_pk_fma_f32 v[152:153], v[32:33], v[136:137], v[176:177]
	v_lshlrev_b64 v[144:145], 12, v[228:229]
	v_lshl_add_u64 v[148:149], v[200:201], 0, v[144:145]
	v_pk_fma_f32 v[144:145], v[40:41], v[140:141], v[180:181]
	v_pk_fma_f32 v[146:147], v[42:43], v[142:143], v[182:183]
	v_cvt_pk_bf16_f32 v144, v144, v145
	v_pk_fma_f32 v[142:143], v[26:27], v[142:143], v[208:209]
	v_cvt_pk_bf16_f32 v145, v146, v147
	v_cvt_pk_bf16_f32 v146, v152, v153
	v_cvt_pk_bf16_f32 v147, v150, v151
	global_store_dwordx4 v[148:149], v[144:147], off
	v_pk_fma_f32 v[150:151], v[10:11], v[130:131], v[186:187]
	v_pk_fma_f32 v[152:153], v[8:9], v[128:129], v[184:185]
	v_pk_fma_f32 v[144:145], v[12:13], v[132:133], v[188:189]
	v_pk_fma_f32 v[146:147], v[14:15], v[134:135], v[190:191]
	v_cvt_pk_bf16_f32 v144, v144, v145
	v_pk_fma_f32 v[140:141], v[24:25], v[140:141], v[206:207]
	v_cvt_pk_bf16_f32 v145, v146, v147
	v_cvt_pk_bf16_f32 v146, v152, v153
	v_cvt_pk_bf16_f32 v147, v150, v151
	global_store_dwordx4 v[148:149], v[144:147], off offset:256
	v_pk_fma_f32 v[134:135], v[6:7], v[134:135], v[222:223]
	v_pk_fma_f32 v[132:133], v[4:5], v[132:133], v[220:221]
	v_lshlrev_b64 v[144:145], 12, v[230:231]
	v_lshl_add_u64 v[144:145], v[200:201], 0, v[144:145]
	v_pk_fma_f32 v[146:147], v[18:19], v[138:139], v[204:205]
	v_pk_fma_f32 v[138:139], v[16:17], v[136:137], v[202:203]
	v_cvt_pk_bf16_f32 v136, v140, v141
	v_cvt_pk_bf16_f32 v137, v142, v143
	s_nop 0
	v_cvt_pk_bf16_f32 v138, v138, v139
	v_cvt_pk_bf16_f32 v139, v146, v147
	global_store_dwordx4 v[144:145], v[136:139], off
	s_nop 1
	v_pk_fma_f32 v[136:137], v[2:3], v[130:131], v[218:219]
	v_pk_fma_f32 v[130:131], v[0:1], v[128:129], v[216:217]
	v_cvt_pk_bf16_f32 v128, v132, v133
	v_cvt_pk_bf16_f32 v129, v134, v135
	s_nop 0
	v_cvt_pk_bf16_f32 v130, v130, v131
	v_cvt_pk_bf16_f32 v131, v136, v137
	global_store_dwordx4 v[144:145], v[128:131], off offset:256

.LBB0_705:
	ds_read_b128 v[142:145], v138
	ds_read_b128 v[146:149], v138 offset:1024
	ds_read_b128 v[150:153], v138 offset:2048
	ds_read_b128 v[154:157], v138 offset:3072
	s_add_u32 s48, s54, 0xfff80080
	s_addc_u32 s49, s55, -1
	s_cmp_eq_u32 s47, 28
	s_cselect_b32 s49, s25, s49
	s_cselect_b32 s48, s24, s48
	s_cselect_b32 s51, s27, s46
	s_cselect_b32 s50, s26, s45
	v_lshl_add_u64 v[134:135], s[54:55], 0, v[132:133]
	s_add_i32 m0, s31, 0xc000
	ds_read_b128 v[158:161], v139
	ds_read_b128 v[162:165], v139 offset:1024
	ds_read_b128 v[166:169], v139 offset:2048
	ds_read_b128 v[170:173], v139 offset:3072
	ds_read_b128 v[174:177], v139 offset:4096
	ds_read_b128 v[178:181], v139 offset:5120
	ds_read_b128 v[182:185], v139 offset:6144
	ds_read_b128 v[186:189], v139 offset:7168
	global_load_lds_dwordx4 v[134:135], off
	v_lshl_add_u64 v[134:135], v[134:135], 0, s[4:5]
	s_add_i32 m0, s31, 0xe000
	s_nop 0
	global_load_lds_dwordx4 v[134:135], off
	s_waitcnt lgkmcnt(8)
	s_barrier
	s_waitcnt lgkmcnt(0)
	s_waitcnt lgkmcnt(0)
	v_mfma_f32_16x16x32_bf16 v[124:127], v[142:145], v[158:161], v[124:127]
	v_mfma_f32_16x16x32_bf16 v[120:123], v[150:153], v[158:161], v[120:123]
	v_mfma_f32_16x16x32_bf16 v[108:111], v[142:145], v[166:169], v[108:111]
	v_mfma_f32_16x16x32_bf16 v[104:107], v[150:153], v[166:169], v[104:107]
	v_mfma_f32_16x16x32_bf16 v[92:95], v[142:145], v[174:177], v[92:95]
	v_mfma_f32_16x16x32_bf16 v[88:91], v[150:153], v[174:177], v[88:91]
	v_mfma_f32_16x16x32_bf16 v[76:79], v[142:145], v[182:185], v[76:79]
	v_mfma_f32_16x16x32_bf16 v[72:75], v[150:153], v[182:185], v[72:75]
	v_mfma_f32_16x16x32_bf16 v[124:127], v[146:149], v[162:165], v[124:127]
	v_mfma_f32_16x16x32_bf16 v[120:123], v[154:157], v[162:165], v[120:123]
	v_mfma_f32_16x16x32_bf16 v[108:111], v[146:149], v[170:173], v[108:111]
	v_mfma_f32_16x16x32_bf16 v[104:107], v[154:157], v[170:173], v[104:107]
	v_mfma_f32_16x16x32_bf16 v[92:95], v[146:149], v[178:181], v[92:95]
	v_mfma_f32_16x16x32_bf16 v[88:91], v[154:157], v[178:181], v[88:91]
	v_mfma_f32_16x16x32_bf16 v[76:79], v[146:149], v[186:189], v[76:79]
	v_mfma_f32_16x16x32_bf16 v[72:75], v[154:157], v[186:189], v[72:75]
	s_barrier
	v_lshl_add_u64 v[134:135], s[50:51], 0, v[128:129]
	s_add_i32 s50, s42, s30
	s_mov_b32 m0, s50
	ds_read_b128 v[190:193], v140
	ds_read_b128 v[194:197], v140 offset:1024
	ds_read_b128 v[198:201], v140 offset:2048
	ds_read_b128 v[202:205], v140 offset:3072
	global_load_lds_dwordx4 v[134:135], off
	v_lshl_add_u64 v[206:207], v[134:135], 0, s[4:5]
	s_add_i32 m0, s50, 0x2000
	s_nop 0
	global_load_lds_dwordx4 v[206:207], off
	s_barrier
	s_waitcnt lgkmcnt(0)
	s_waitcnt lgkmcnt(0)
	v_mfma_f32_16x16x32_bf16 v[116:119], v[190:193], v[158:161], v[116:119]
	v_mfma_f32_16x16x32_bf16 v[112:115], v[198:201], v[158:161], v[112:115]
	v_mfma_f32_16x16x32_bf16 v[100:103], v[190:193], v[166:169], v[100:103]
	v_mfma_f32_16x16x32_bf16 v[96:99], v[198:201], v[166:169], v[96:99]
	v_mfma_f32_16x16x32_bf16 v[84:87], v[190:193], v[174:177], v[84:87]
	v_mfma_f32_16x16x32_bf16 v[80:83], v[198:201], v[174:177], v[80:83]
	v_mfma_f32_16x16x32_bf16 v[68:71], v[190:193], v[182:185], v[68:71]
	v_mfma_f32_16x16x32_bf16 v[64:67], v[198:201], v[182:185], v[64:67]
	v_mfma_f32_16x16x32_bf16 v[116:119], v[194:197], v[162:165], v[116:119]
	v_mfma_f32_16x16x32_bf16 v[112:115], v[202:205], v[162:165], v[112:115]
	v_mfma_f32_16x16x32_bf16 v[100:103], v[194:197], v[170:173], v[100:103]
	v_mfma_f32_16x16x32_bf16 v[96:99], v[202:205], v[170:173], v[96:99]
	v_mfma_f32_16x16x32_bf16 v[84:87], v[194:197], v[178:181], v[84:87]
	v_mfma_f32_16x16x32_bf16 v[80:83], v[202:205], v[178:181], v[80:83]
	v_mfma_f32_16x16x32_bf16 v[68:71], v[194:197], v[186:189], v[68:71]
	v_mfma_f32_16x16x32_bf16 v[64:67], v[202:205], v[186:189], v[64:67]
	s_mov_b32 m0, s31
	v_lshl_add_u64 v[206:207], s[48:49], 0, v[130:131]
	s_barrier
	ds_read_b128 v[158:161], v139 offset:16384
	ds_read_b128 v[162:165], v139 offset:17408
	ds_read_b128 v[166:169], v139 offset:18432
	ds_read_b128 v[170:173], v139 offset:19456
	ds_read_b128 v[174:177], v139 offset:20480
	ds_read_b128 v[178:181], v139 offset:21504
	ds_read_b128 v[182:185], v139 offset:22528
	ds_read_b128 v[186:189], v139 offset:23552
	global_load_lds_dwordx4 v[206:207], off
	v_lshl_add_u64 v[208:209], v[206:207], 0, s[4:5]
	s_mov_b32 m0, s33
	s_nop 0
	global_load_lds_dwordx4 v[208:209], off
	s_barrier
	s_waitcnt lgkmcnt(0)
	s_waitcnt lgkmcnt(0)
	v_mfma_f32_16x16x32_bf16 v[60:63], v[142:145], v[158:161], v[60:63]
	v_mfma_f32_16x16x32_bf16 v[56:59], v[150:153], v[158:161], v[56:59]
	v_mfma_f32_16x16x32_bf16 v[44:47], v[142:145], v[166:169], v[44:47]
	v_mfma_f32_16x16x32_bf16 v[40:43], v[150:153], v[166:169], v[40:43]
	v_mfma_f32_16x16x32_bf16 v[28:31], v[142:145], v[174:177], v[28:31]
	v_mfma_f32_16x16x32_bf16 v[24:27], v[150:153], v[174:177], v[24:27]
	v_mfma_f32_16x16x32_bf16 v[12:15], v[142:145], v[182:185], v[12:15]
	v_mfma_f32_16x16x32_bf16 v[8:11], v[150:153], v[182:185], v[8:11]
	v_mfma_f32_16x16x32_bf16 v[60:63], v[146:149], v[162:165], v[60:63]
	v_mfma_f32_16x16x32_bf16 v[56:59], v[154:157], v[162:165], v[56:59]
	v_mfma_f32_16x16x32_bf16 v[44:47], v[146:149], v[170:173], v[44:47]
	v_mfma_f32_16x16x32_bf16 v[40:43], v[154:157], v[170:173], v[40:43]
	v_mfma_f32_16x16x32_bf16 v[28:31], v[146:149], v[178:181], v[28:31]
	v_mfma_f32_16x16x32_bf16 v[24:27], v[154:157], v[178:181], v[24:27]
	v_mfma_f32_16x16x32_bf16 v[12:15], v[146:149], v[186:189], v[12:15]
	v_mfma_f32_16x16x32_bf16 v[8:11], v[154:157], v[186:189], v[8:11]
	s_barrier
	s_add_i32 s48, s43, s30
	v_lshl_add_u64 v[142:143], v[134:135], 0, s[6:7]
	s_mov_b32 m0, s48
	s_nop 0
	global_load_lds_dwordx4 v[142:143], off
	v_lshl_add_u64 v[142:143], v[134:135], 0, s[8:9]
	s_add_i32 m0, s48, 0x2000
	s_nop 0
	global_load_lds_dwordx4 v[142:143], off
	s_waitcnt vmcnt(6)
	s_barrier
	v_mfma_f32_16x16x32_bf16 v[52:55], v[190:193], v[158:161], v[52:55]
	v_mfma_f32_16x16x32_bf16 v[48:51], v[198:201], v[158:161], v[48:51]
	v_mfma_f32_16x16x32_bf16 v[36:39], v[190:193], v[166:169], v[36:39]
	v_mfma_f32_16x16x32_bf16 v[32:35], v[198:201], v[166:169], v[32:35]
	v_mfma_f32_16x16x32_bf16 v[20:23], v[190:193], v[174:177], v[20:23]
	v_mfma_f32_16x16x32_bf16 v[16:19], v[198:201], v[174:177], v[16:19]
	v_mfma_f32_16x16x32_bf16 v[4:7], v[190:193], v[182:185], v[4:7]
	v_mfma_f32_16x16x32_bf16 v[0:3], v[198:201], v[182:185], v[0:3]
	v_mfma_f32_16x16x32_bf16 v[52:55], v[194:197], v[162:165], v[52:55]
	v_mfma_f32_16x16x32_bf16 v[48:51], v[202:205], v[162:165], v[48:51]
	v_mfma_f32_16x16x32_bf16 v[36:39], v[194:197], v[170:173], v[36:39]
	v_mfma_f32_16x16x32_bf16 v[32:35], v[202:205], v[170:173], v[32:35]
	v_mfma_f32_16x16x32_bf16 v[20:23], v[194:197], v[178:181], v[20:23]
	v_mfma_f32_16x16x32_bf16 v[16:19], v[202:205], v[178:181], v[16:19]
	v_mfma_f32_16x16x32_bf16 v[4:7], v[194:197], v[186:189], v[4:7]
	v_mfma_f32_16x16x32_bf16 v[0:3], v[202:205], v[186:189], v[0:3]
	s_add_i32 s48, 0, 0x18000
	v_add_u32_e32 v141, s48, v137
	s_barrier
	ds_read_b128 v[142:145], v141
	ds_read_b128 v[146:149], v141 offset:1024
	ds_read_b128 v[150:153], v141 offset:2048
	ds_read_b128 v[154:157], v141 offset:3072
	s_mov_b32 m0, s35
	v_lshl_add_u64 v[190:191], v[206:207], 0, s[6:7]
	ds_read_b128 v[158:161], v139 offset:32768
	ds_read_b128 v[162:165], v139 offset:33792
	ds_read_b128 v[166:169], v139 offset:34816
	ds_read_b128 v[170:173], v139 offset:35840
	ds_read_b128 v[174:177], v139 offset:36864
	ds_read_b128 v[178:181], v139 offset:37888
	ds_read_b128 v[182:185], v139 offset:38912
	ds_read_b128 v[186:189], v139 offset:39936
	global_load_lds_dwordx4 v[190:191], off
	v_lshl_add_u64 v[190:191], v[206:207], 0, s[8:9]
	s_mov_b32 m0, s36
	s_nop 0
	global_load_lds_dwordx4 v[190:191], off
	s_waitcnt lgkmcnt(8)
	s_barrier
	s_waitcnt lgkmcnt(0)
	s_waitcnt lgkmcnt(0)
	v_mfma_f32_16x16x32_bf16 v[124:127], v[142:145], v[158:161], v[124:127]
	v_mfma_f32_16x16x32_bf16 v[120:123], v[150:153], v[158:161], v[120:123]
	v_mfma_f32_16x16x32_bf16 v[108:111], v[142:145], v[166:169], v[108:111]
	v_mfma_f32_16x16x32_bf16 v[104:107], v[150:153], v[166:169], v[104:107]
	v_mfma_f32_16x16x32_bf16 v[92:95], v[142:145], v[174:177], v[92:95]
	v_mfma_f32_16x16x32_bf16 v[88:91], v[150:153], v[174:177], v[88:91]
	v_mfma_f32_16x16x32_bf16 v[76:79], v[142:145], v[182:185], v[76:79]
	v_mfma_f32_16x16x32_bf16 v[72:75], v[150:153], v[182:185], v[72:75]
	v_mfma_f32_16x16x32_bf16 v[124:127], v[146:149], v[162:165], v[124:127]
	v_mfma_f32_16x16x32_bf16 v[120:123], v[154:157], v[162:165], v[120:123]
	v_mfma_f32_16x16x32_bf16 v[108:111], v[146:149], v[170:173], v[108:111]
	v_mfma_f32_16x16x32_bf16 v[104:107], v[154:157], v[170:173], v[104:107]
	v_mfma_f32_16x16x32_bf16 v[92:95], v[146:149], v[178:181], v[92:95]
	v_mfma_f32_16x16x32_bf16 v[88:91], v[154:157], v[178:181], v[88:91]
	v_mfma_f32_16x16x32_bf16 v[76:79], v[146:149], v[186:189], v[76:79]
	v_mfma_f32_16x16x32_bf16 v[72:75], v[154:157], v[186:189], v[72:75]
	s_barrier
	s_add_i32 s49, 0, 0x1c000
	s_add_i32 s48, s48, s30
	v_add_u32_e32 v141, s49, v137
	v_lshl_add_u64 v[208:209], v[134:135], 0, s[16:17]
	s_mov_b32 m0, s48
	ds_read_b128 v[190:193], v141
	ds_read_b128 v[194:197], v141 offset:1024
	ds_read_b128 v[198:201], v141 offset:2048
	ds_read_b128 v[202:205], v141 offset:3072
	global_load_lds_dwordx4 v[208:209], off
	v_lshl_add_u64 v[208:209], v[134:135], 0, s[18:19]
	s_add_i32 m0, s48, 0x2000
	s_nop 0
	global_load_lds_dwordx4 v[208:209], off
	s_barrier
	s_waitcnt lgkmcnt(0)
	s_waitcnt lgkmcnt(0)
	v_mfma_f32_16x16x32_bf16 v[116:119], v[190:193], v[158:161], v[116:119]
	v_mfma_f32_16x16x32_bf16 v[112:115], v[198:201], v[158:161], v[112:115]
	v_mfma_f32_16x16x32_bf16 v[100:103], v[190:193], v[166:169], v[100:103]
	v_mfma_f32_16x16x32_bf16 v[96:99], v[198:201], v[166:169], v[96:99]
	v_mfma_f32_16x16x32_bf16 v[84:87], v[190:193], v[174:177], v[84:87]
	v_mfma_f32_16x16x32_bf16 v[80:83], v[198:201], v[174:177], v[80:83]
	v_mfma_f32_16x16x32_bf16 v[68:71], v[190:193], v[182:185], v[68:71]
	v_mfma_f32_16x16x32_bf16 v[64:67], v[198:201], v[182:185], v[64:67]
	v_mfma_f32_16x16x32_bf16 v[116:119], v[194:197], v[162:165], v[116:119]
	v_mfma_f32_16x16x32_bf16 v[112:115], v[202:205], v[162:165], v[112:115]
	v_mfma_f32_16x16x32_bf16 v[100:103], v[194:197], v[170:173], v[100:103]
	v_mfma_f32_16x16x32_bf16 v[96:99], v[202:205], v[170:173], v[96:99]
	v_mfma_f32_16x16x32_bf16 v[84:87], v[194:197], v[178:181], v[84:87]
	v_mfma_f32_16x16x32_bf16 v[80:83], v[202:205], v[178:181], v[80:83]
	v_mfma_f32_16x16x32_bf16 v[68:71], v[194:197], v[186:189], v[68:71]
	v_mfma_f32_16x16x32_bf16 v[64:67], v[202:205], v[186:189], v[64:67]
	s_mov_b32 m0, s37
	v_lshl_add_u64 v[208:209], v[206:207], 0, s[16:17]
	s_barrier
	ds_read_b128 v[158:161], v139 offset:49152
	ds_read_b128 v[162:165], v139 offset:50176
	ds_read_b128 v[166:169], v139 offset:51200
	ds_read_b128 v[170:173], v139 offset:52224
	ds_read_b128 v[174:177], v139 offset:53248
	ds_read_b128 v[178:181], v139 offset:54272
	ds_read_b128 v[182:185], v139 offset:55296
	ds_read_b128 v[186:189], v139 offset:56320
	global_load_lds_dwordx4 v[208:209], off
	v_lshl_add_u64 v[206:207], v[206:207], 0, s[18:19]
	s_mov_b32 m0, s38
	s_nop 0
	global_load_lds_dwordx4 v[206:207], off
	s_barrier
	s_waitcnt lgkmcnt(0)
	s_waitcnt lgkmcnt(0)
	v_mfma_f32_16x16x32_bf16 v[60:63], v[142:145], v[158:161], v[60:63]
	v_mfma_f32_16x16x32_bf16 v[56:59], v[150:153], v[158:161], v[56:59]
	v_mfma_f32_16x16x32_bf16 v[44:47], v[142:145], v[166:169], v[44:47]
	v_mfma_f32_16x16x32_bf16 v[40:43], v[150:153], v[166:169], v[40:43]
	v_mfma_f32_16x16x32_bf16 v[28:31], v[142:145], v[174:177], v[28:31]
	v_mfma_f32_16x16x32_bf16 v[24:27], v[150:153], v[174:177], v[24:27]
	v_mfma_f32_16x16x32_bf16 v[12:15], v[142:145], v[182:185], v[12:15]
	v_mfma_f32_16x16x32_bf16 v[8:11], v[150:153], v[182:185], v[8:11]
	v_mfma_f32_16x16x32_bf16 v[60:63], v[146:149], v[162:165], v[60:63]
	v_mfma_f32_16x16x32_bf16 v[56:59], v[154:157], v[162:165], v[56:59]
	v_mfma_f32_16x16x32_bf16 v[44:47], v[146:149], v[170:173], v[44:47]
	v_mfma_f32_16x16x32_bf16 v[40:43], v[154:157], v[170:173], v[40:43]
	v_mfma_f32_16x16x32_bf16 v[28:31], v[146:149], v[178:181], v[28:31]
	v_mfma_f32_16x16x32_bf16 v[24:27], v[154:157], v[178:181], v[24:27]
	v_mfma_f32_16x16x32_bf16 v[12:15], v[146:149], v[186:189], v[12:15]
	v_mfma_f32_16x16x32_bf16 v[8:11], v[154:157], v[186:189], v[8:11]
	s_barrier
	s_add_i32 s48, s49, s30
	v_lshl_add_u64 v[142:143], v[134:135], 0, s[20:21]
	s_mov_b32 m0, s48
	v_lshl_add_u64 v[134:135], v[134:135], 0, s[22:23]
	global_load_lds_dwordx4 v[142:143], off
	s_add_i32 m0, s48, 0x2000
	s_nop 0
	global_load_lds_dwordx4 v[134:135], off
	s_waitcnt vmcnt(6)
	s_barrier
	v_mfma_f32_16x16x32_bf16 v[52:55], v[190:193], v[158:161], v[52:55]
	v_mfma_f32_16x16x32_bf16 v[48:51], v[198:201], v[158:161], v[48:51]
	v_mfma_f32_16x16x32_bf16 v[36:39], v[190:193], v[166:169], v[36:39]
	v_mfma_f32_16x16x32_bf16 v[32:35], v[198:201], v[166:169], v[32:35]
	v_mfma_f32_16x16x32_bf16 v[20:23], v[190:193], v[174:177], v[20:23]
	v_mfma_f32_16x16x32_bf16 v[16:19], v[198:201], v[174:177], v[16:19]
	v_mfma_f32_16x16x32_bf16 v[4:7], v[190:193], v[182:185], v[4:7]
	v_mfma_f32_16x16x32_bf16 v[0:3], v[198:201], v[182:185], v[0:3]
	v_mfma_f32_16x16x32_bf16 v[52:55], v[194:197], v[162:165], v[52:55]
	v_mfma_f32_16x16x32_bf16 v[48:51], v[202:205], v[162:165], v[48:51]
	v_mfma_f32_16x16x32_bf16 v[36:39], v[194:197], v[170:173], v[36:39]
	v_mfma_f32_16x16x32_bf16 v[32:35], v[202:205], v[170:173], v[32:35]
	v_mfma_f32_16x16x32_bf16 v[20:23], v[194:197], v[178:181], v[20:23]
	v_mfma_f32_16x16x32_bf16 v[16:19], v[202:205], v[178:181], v[16:19]
	v_mfma_f32_16x16x32_bf16 v[4:7], v[194:197], v[186:189], v[4:7]
	v_mfma_f32_16x16x32_bf16 v[0:3], v[202:205], v[186:189], v[0:3]
	s_add_i32 s47, s47, 2
	s_add_u32 s54, s54, 0x100
	s_addc_u32 s55, s55, 0
	s_add_u32 s45, s45, 0x100
	s_addc_u32 s46, s46, 0
	s_cmp_gt_u32 s47, 29
	s_barrier
	s_cbranch_scc0 .LBB0_705
	v_mov_b32_e32 v134, v136
	s_mov_b32 s45, s29
	s_mov_b32 s46, s39
	s_lshl_b32 s34, s34, 8
	s_lshl_b32 s45, s45, 6
	s_add_i32 s45, s45, s34
	v_lshrrev_b32_e32 v135, 1, v134
	v_and_or_b32 v141, v134, 15, s45
	v_mul_f32_e32 v134, 0xbfb8aa3b, v124
	v_exp_f32_e32 v144, v134
	v_mul_f32_e32 v134, 0xbfb8aa3b, v120
	v_exp_f32_e32 v145, v134
	s_lshl_b32 s47, s52, 7
	v_add_f32_e32 v144, 1.0, v144
	v_rcp_f32_e32 v146, v144
	v_add_f32_e32 v144, 1.0, v145
	v_rcp_f32_e32 v147, v144
	s_lshl_b32 s46, s46, 5
	v_mul_f32_e32 v124, v124, v146
	v_mul_f32_e32 v116, v124, v116
	v_mul_f32_e32 v124, 0xbfb8aa3b, v125
	v_exp_f32_e32 v124, v124
	v_mul_f32_e32 v146, 0xbfb8aa3b, v121
	v_exp_f32_e32 v146, v146
	v_mul_f32_e32 v120, v120, v147
	v_mul_f32_e32 v120, v120, v112
	v_add_f32_e32 v112, 1.0, v124
	v_rcp_f32_e32 v112, v112
	v_add_f32_e32 v124, 1.0, v146
	v_mul_f32_e32 v146, 0xbfb8aa3b, v126
	v_rcp_f32_e32 v124, v124
	v_exp_f32_e32 v146, v146
	v_mul_f32_e32 v112, v125, v112
	v_mul_f32_e32 v117, v112, v117
	v_mul_f32_e32 v112, v121, v124
	v_add_f32_e32 v121, 1.0, v146
	v_rcp_f32_e32 v121, v121
	v_mul_f32_e32 v124, 0xbfb8aa3b, v122
	v_exp_f32_e32 v124, v124
	v_mul_f32_e32 v125, v112, v113
	v_mul_f32_e32 v112, v126, v121
	v_mul_f32_e32 v113, 0xbfb8aa3b, v127
	v_mul_f32_e32 v121, v112, v118
	v_exp_f32_e32 v113, v113
	v_mul_f32_e32 v118, 0xbfb8aa3b, v123
	v_exp_f32_e32 v118, v118
	v_add_f32_e32 v112, 1.0, v124
	v_rcp_f32_e32 v112, v112
	v_add_f32_e32 v113, 1.0, v113
	v_rcp_f32_e32 v113, v113
	v_add_f32_e32 v118, 1.0, v118
	v_rcp_f32_e32 v118, v118
	s_add_i32 s46, s46, s47
	v_mul_f32_e32 v112, v122, v112
	v_and_or_b32 v142, v135, 24, s46
	v_mul_f32_e32 v122, v112, v114
	v_mul_f32_e32 v112, v127, v113
	v_ashrrev_i32_e32 v143, 31, v142
	v_mov_b64_e32 v[134:135], s[10:11]
	v_mul_f32_e32 v124, v112, v119
	v_mul_f32_e32 v112, v123, v118
	v_mad_i64_i32 v[144:145], s[46:47], v141, s44, v[134:135]
	v_mul_f32_e32 v123, v112, v115
	v_lshlrev_b64 v[112:113], 1, v[142:143]
	v_lshl_add_u64 v[118:119], v[144:145], 0, v[112:113]
	v_cvt_pk_bf16_f32 v114, v116, v117
	v_cvt_pk_bf16_f32 v115, v121, v124
	v_cvt_pk_bf16_f32 v116, v120, v125
	v_cvt_pk_bf16_f32 v117, v122, v123
	global_store_dwordx4 v[118:119], v[114:117], off
	s_mov_b32 s34, s40
	s_mov_b64 s[54:55], -1
	v_mul_f32_e32 v114, 0xbfb8aa3b, v108
	v_exp_f32_e32 v114, v114
	v_mul_f32_e32 v115, 0xbfb8aa3b, v104
	v_exp_f32_e32 v115, v115
	v_or_b32_e32 v116, 16, v141
	v_add_f32_e32 v114, 1.0, v114
	v_rcp_f32_e32 v117, v114
	v_add_f32_e32 v114, 1.0, v115
	v_rcp_f32_e32 v118, v114
	v_mad_i64_i32 v[114:115], s[46:47], v116, s44, v[134:135]
	v_mul_f32_e32 v108, v108, v117
	v_mul_f32_e32 v108, v108, v100
	v_mul_f32_e32 v100, v104, v118
	v_mul_f32_e32 v104, 0xbfb8aa3b, v109
	v_exp_f32_e32 v104, v104
	v_mul_f32_e32 v116, 0xbfb8aa3b, v105
	v_mul_f32_e32 v117, v100, v96
	v_exp_f32_e32 v116, v116
	v_add_f32_e32 v96, 1.0, v104
	v_rcp_f32_e32 v96, v96
	v_mul_f32_e32 v104, 0xbfb8aa3b, v110
	v_exp_f32_e32 v104, v104
	v_add_f32_e32 v100, 1.0, v116
	v_mul_f32_e32 v96, v109, v96
	v_rcp_f32_e32 v100, v100
	v_mul_f32_e32 v96, v96, v101
	v_add_f32_e32 v101, 1.0, v104
	v_rcp_f32_e32 v101, v101
	v_mul_f32_e32 v100, v105, v100
	v_mul_f32_e32 v104, 0xbfb8aa3b, v106
	v_mul_f32_e32 v105, v100, v97
	v_mul_f32_e32 v97, v110, v101
	v_exp_f32_e32 v104, v104
	v_mul_f32_e32 v97, v97, v102
	v_mul_f32_e32 v101, 0xbfb8aa3b, v111
	v_mul_f32_e32 v102, 0xbfb8aa3b, v107
	v_exp_f32_e32 v101, v101
	v_exp_f32_e32 v102, v102
	v_add_f32_e32 v100, 1.0, v104
	v_rcp_f32_e32 v100, v100
	v_add_f32_e32 v101, 1.0, v101
	v_add_f32_e32 v102, 1.0, v102
	v_rcp_f32_e32 v101, v101
	v_rcp_f32_e32 v102, v102
	v_mul_f32_e32 v100, v106, v100
	v_mul_f32_e32 v104, v100, v98
	v_mul_f32_e32 v98, v111, v101
	v_mul_f32_e32 v100, v107, v102
	v_mul_f32_e32 v98, v98, v103
	v_mul_f32_e32 v99, v100, v99
	v_lshl_add_u64 v[100:101], v[114:115], 0, v[112:113]
	v_cvt_pk_bf16_f32 v96, v108, v96
	v_cvt_pk_bf16_f32 v97, v97, v98
	v_cvt_pk_bf16_f32 v98, v117, v105
	v_cvt_pk_bf16_f32 v99, v104, v99
	global_store_dwordx4 v[100:101], v[96:99], off
	s_nop 1
	v_mul_f32_e32 v96, 0xbfb8aa3b, v92
	v_exp_f32_e32 v96, v96
	v_mul_f32_e32 v97, 0xbfb8aa3b, v88
	v_exp_f32_e32 v97, v97
	v_or_b32_e32 v98, 32, v141
	v_add_f32_e32 v96, 1.0, v96
	v_rcp_f32_e32 v99, v96
	v_add_f32_e32 v96, 1.0, v97
	v_rcp_f32_e32 v100, v96
	v_mad_i64_i32 v[96:97], s[46:47], v98, s44, v[134:135]
	v_mul_f32_e32 v92, v92, v99
	v_mul_f32_e32 v92, v92, v84
	v_mul_f32_e32 v84, v88, v100
	v_mul_f32_e32 v88, 0xbfb8aa3b, v93
	v_exp_f32_e32 v88, v88
	v_mul_f32_e32 v98, 0xbfb8aa3b, v89
	v_mul_f32_e32 v99, v84, v80
	v_exp_f32_e32 v98, v98
	v_add_f32_e32 v80, 1.0, v88
	v_rcp_f32_e32 v80, v80
	v_mul_f32_e32 v88, 0xbfb8aa3b, v94
	v_exp_f32_e32 v88, v88
	v_add_f32_e32 v84, 1.0, v98
	v_mul_f32_e32 v80, v93, v80
	v_rcp_f32_e32 v84, v84
	v_mul_f32_e32 v80, v80, v85
	v_add_f32_e32 v85, 1.0, v88
	v_rcp_f32_e32 v85, v85
	v_mul_f32_e32 v84, v89, v84
	v_mul_f32_e32 v88, 0xbfb8aa3b, v90
	v_mul_f32_e32 v89, v84, v81
	v_mul_f32_e32 v81, v94, v85
	v_exp_f32_e32 v88, v88
	v_mul_f32_e32 v81, v81, v86
	v_mul_f32_e32 v85, 0xbfb8aa3b, v95
	v_mul_f32_e32 v86, 0xbfb8aa3b, v91
	v_exp_f32_e32 v85, v85
	v_exp_f32_e32 v86, v86
	v_add_f32_e32 v84, 1.0, v88
	v_rcp_f32_e32 v84, v84
	v_add_f32_e32 v85, 1.0, v85
	v_add_f32_e32 v86, 1.0, v86
	v_rcp_f32_e32 v85, v85
	v_rcp_f32_e32 v86, v86
	v_mul_f32_e32 v84, v90, v84
	v_mul_f32_e32 v88, v84, v82
	v_mul_f32_e32 v82, v95, v85
	v_mul_f32_e32 v84, v91, v86
	v_mul_f32_e32 v82, v82, v87
	v_mul_f32_e32 v83, v84, v83
	v_lshl_add_u64 v[84:85], v[96:97], 0, v[112:113]
	v_cvt_pk_bf16_f32 v80, v92, v80
	v_cvt_pk_bf16_f32 v81, v81, v82
	v_cvt_pk_bf16_f32 v82, v99, v89
	v_cvt_pk_bf16_f32 v83, v88, v83
	global_store_dwordx4 v[84:85], v[80:83], off
	s_nop 1
	v_mul_f32_e32 v80, 0xbfb8aa3b, v76
	v_exp_f32_e32 v80, v80
	v_mul_f32_e32 v81, 0xbfb8aa3b, v72
	v_exp_f32_e32 v81, v81
	v_or_b32_e32 v82, 48, v141
	v_add_f32_e32 v80, 1.0, v80
	v_rcp_f32_e32 v83, v80
	v_add_f32_e32 v80, 1.0, v81
	v_rcp_f32_e32 v84, v80
	v_mad_i64_i32 v[80:81], s[46:47], v82, s44, v[134:135]
	v_mul_f32_e32 v76, v76, v83
	v_mul_f32_e32 v76, v76, v68
	v_mul_f32_e32 v68, v72, v84
	v_mul_f32_e32 v72, 0xbfb8aa3b, v77
	v_exp_f32_e32 v72, v72
	v_mul_f32_e32 v82, 0xbfb8aa3b, v73
	v_mul_f32_e32 v83, v68, v64
	v_exp_f32_e32 v82, v82
	v_add_f32_e32 v64, 1.0, v72
	v_rcp_f32_e32 v64, v64
	v_mul_f32_e32 v72, 0xbfb8aa3b, v78
	v_exp_f32_e32 v72, v72
	v_add_f32_e32 v68, 1.0, v82
	v_mul_f32_e32 v64, v77, v64
	v_rcp_f32_e32 v68, v68
	v_mul_f32_e32 v64, v64, v69
	v_add_f32_e32 v69, 1.0, v72
	v_rcp_f32_e32 v69, v69
	v_mul_f32_e32 v68, v73, v68
	v_mul_f32_e32 v72, 0xbfb8aa3b, v74
	v_mul_f32_e32 v73, v68, v65
	v_mul_f32_e32 v65, v78, v69
	v_exp_f32_e32 v72, v72
	v_mul_f32_e32 v65, v65, v70
	v_mul_f32_e32 v69, 0xbfb8aa3b, v79
	v_mul_f32_e32 v70, 0xbfb8aa3b, v75
	v_exp_f32_e32 v69, v69
	v_exp_f32_e32 v70, v70
	v_add_f32_e32 v68, 1.0, v72
	v_rcp_f32_e32 v68, v68
	v_add_f32_e32 v69, 1.0, v69
	v_add_f32_e32 v70, 1.0, v70
	v_rcp_f32_e32 v69, v69
	v_rcp_f32_e32 v70, v70
	v_mul_f32_e32 v68, v74, v68
	v_mul_f32_e32 v72, v68, v66
	v_mul_f32_e32 v66, v79, v69
	v_mul_f32_e32 v68, v75, v70
	v_mul_f32_e32 v66, v66, v71
	v_mul_f32_e32 v67, v68, v67
	v_lshl_add_u64 v[68:69], v[80:81], 0, v[112:113]
	v_cvt_pk_bf16_f32 v64, v76, v64
	v_cvt_pk_bf16_f32 v65, v65, v66
	v_cvt_pk_bf16_f32 v66, v83, v73
	v_cvt_pk_bf16_f32 v67, v72, v67
	global_store_dwordx4 v[68:69], v[64:67], off
	s_nop 1
	v_mul_f32_e32 v64, 0xbfb8aa3b, v60
	v_exp_f32_e32 v64, v64
	v_mul_f32_e32 v65, 0xbfb8aa3b, v56
	v_exp_f32_e32 v65, v65
	v_add_u32_e32 v66, 0x80, v141
	v_add_f32_e32 v64, 1.0, v64
	v_rcp_f32_e32 v67, v64
	v_add_f32_e32 v64, 1.0, v65
	v_rcp_f32_e32 v68, v64
	v_mad_i64_i32 v[64:65], s[46:47], v66, s44, v[134:135]
	v_mul_f32_e32 v60, v60, v67
	v_mul_f32_e32 v60, v60, v52
	v_mul_f32_e32 v52, v56, v68
	v_mul_f32_e32 v56, 0xbfb8aa3b, v61
	v_exp_f32_e32 v56, v56
	v_mul_f32_e32 v66, 0xbfb8aa3b, v57
	v_mul_f32_e32 v67, v52, v48
	v_exp_f32_e32 v66, v66
	v_add_f32_e32 v48, 1.0, v56
	v_rcp_f32_e32 v48, v48
	v_mul_f32_e32 v56, 0xbfb8aa3b, v62
	v_exp_f32_e32 v56, v56
	v_add_f32_e32 v52, 1.0, v66
	v_mul_f32_e32 v48, v61, v48
	v_rcp_f32_e32 v52, v52
	v_mul_f32_e32 v48, v48, v53
	v_add_f32_e32 v53, 1.0, v56
	v_rcp_f32_e32 v53, v53
	v_mul_f32_e32 v52, v57, v52
	v_mul_f32_e32 v56, 0xbfb8aa3b, v58
	v_mul_f32_e32 v57, v52, v49
	v_mul_f32_e32 v49, v62, v53
	v_exp_f32_e32 v56, v56
	v_mul_f32_e32 v49, v49, v54
	v_mul_f32_e32 v53, 0xbfb8aa3b, v63
	v_mul_f32_e32 v54, 0xbfb8aa3b, v59
	v_exp_f32_e32 v53, v53
	v_exp_f32_e32 v54, v54
	v_add_f32_e32 v52, 1.0, v56
	v_rcp_f32_e32 v52, v52
	v_add_f32_e32 v53, 1.0, v53
	v_add_f32_e32 v54, 1.0, v54
	v_rcp_f32_e32 v53, v53
	v_rcp_f32_e32 v54, v54
	v_mul_f32_e32 v52, v58, v52
	v_mul_f32_e32 v56, v52, v50
	v_mul_f32_e32 v50, v63, v53
	v_mul_f32_e32 v52, v59, v54
	v_mul_f32_e32 v50, v50, v55
	v_mul_f32_e32 v51, v52, v51
	v_lshl_add_u64 v[52:53], v[64:65], 0, v[112:113]
	v_cvt_pk_bf16_f32 v48, v60, v48
	v_cvt_pk_bf16_f32 v49, v49, v50
	v_cvt_pk_bf16_f32 v50, v67, v57
	v_cvt_pk_bf16_f32 v51, v56, v51
	global_store_dwordx4 v[52:53], v[48:51], off
	s_nop 1
	v_mul_f32_e32 v48, 0xbfb8aa3b, v44
	v_exp_f32_e32 v48, v48
	v_mul_f32_e32 v49, 0xbfb8aa3b, v40
	v_exp_f32_e32 v49, v49
	v_add_u32_e32 v50, 0x90, v141
	v_add_f32_e32 v48, 1.0, v48
	v_rcp_f32_e32 v51, v48
	v_add_f32_e32 v48, 1.0, v49
	v_rcp_f32_e32 v52, v48
	v_mad_i64_i32 v[48:49], s[46:47], v50, s44, v[134:135]
	v_mul_f32_e32 v44, v44, v51
	v_mul_f32_e32 v44, v44, v36
	v_mul_f32_e32 v36, v40, v52
	v_mul_f32_e32 v40, 0xbfb8aa3b, v45
	v_exp_f32_e32 v40, v40
	v_mul_f32_e32 v50, 0xbfb8aa3b, v41
	v_mul_f32_e32 v51, v36, v32
	v_exp_f32_e32 v50, v50
	v_add_f32_e32 v32, 1.0, v40
	v_rcp_f32_e32 v32, v32
	v_mul_f32_e32 v40, 0xbfb8aa3b, v46
	v_exp_f32_e32 v40, v40
	v_add_f32_e32 v36, 1.0, v50
	v_mul_f32_e32 v32, v45, v32
	v_rcp_f32_e32 v36, v36
	v_mul_f32_e32 v32, v32, v37
	v_add_f32_e32 v37, 1.0, v40
	v_rcp_f32_e32 v37, v37
	v_mul_f32_e32 v36, v41, v36
	v_mul_f32_e32 v40, 0xbfb8aa3b, v42
	v_mul_f32_e32 v41, v36, v33
	v_mul_f32_e32 v33, v46, v37
	v_exp_f32_e32 v40, v40
	v_mul_f32_e32 v33, v33, v38
	v_mul_f32_e32 v37, 0xbfb8aa3b, v47
	v_mul_f32_e32 v38, 0xbfb8aa3b, v43
	v_exp_f32_e32 v37, v37
	v_exp_f32_e32 v38, v38
	v_add_f32_e32 v36, 1.0, v40
	v_rcp_f32_e32 v36, v36
	v_add_f32_e32 v37, 1.0, v37
	v_add_f32_e32 v38, 1.0, v38
	v_rcp_f32_e32 v37, v37
	v_rcp_f32_e32 v38, v38
	v_mul_f32_e32 v36, v42, v36
	v_mul_f32_e32 v40, v36, v34
	v_mul_f32_e32 v34, v47, v37
	v_mul_f32_e32 v36, v43, v38
	v_mul_f32_e32 v34, v34, v39
	v_mul_f32_e32 v35, v36, v35
	v_lshl_add_u64 v[36:37], v[48:49], 0, v[112:113]
	v_cvt_pk_bf16_f32 v32, v44, v32
	v_cvt_pk_bf16_f32 v33, v33, v34
	v_cvt_pk_bf16_f32 v34, v51, v41
	v_cvt_pk_bf16_f32 v35, v40, v35
	global_store_dwordx4 v[36:37], v[32:35], off
	s_nop 1
	v_mul_f32_e32 v32, 0xbfb8aa3b, v28
	v_exp_f32_e32 v32, v32
	v_mul_f32_e32 v33, 0xbfb8aa3b, v24
	v_exp_f32_e32 v33, v33
	v_add_u32_e32 v34, 0xa0, v141
	v_add_f32_e32 v32, 1.0, v32
	v_rcp_f32_e32 v35, v32
	v_add_f32_e32 v32, 1.0, v33
	v_rcp_f32_e32 v36, v32
	v_mad_i64_i32 v[32:33], s[46:47], v34, s44, v[134:135]
	v_mul_f32_e32 v28, v28, v35
	v_mul_f32_e32 v28, v28, v20
	v_mul_f32_e32 v20, v24, v36
	v_mul_f32_e32 v24, 0xbfb8aa3b, v29
	v_exp_f32_e32 v24, v24
	v_mul_f32_e32 v34, 0xbfb8aa3b, v25
	v_mul_f32_e32 v35, v20, v16
	v_exp_f32_e32 v34, v34
	v_add_f32_e32 v16, 1.0, v24
	v_rcp_f32_e32 v16, v16
	v_mul_f32_e32 v24, 0xbfb8aa3b, v30
	v_exp_f32_e32 v24, v24
	v_add_f32_e32 v20, 1.0, v34
	v_mul_f32_e32 v16, v29, v16
	v_rcp_f32_e32 v20, v20
	v_mul_f32_e32 v16, v16, v21
	v_add_f32_e32 v21, 1.0, v24
	v_rcp_f32_e32 v21, v21
	v_mul_f32_e32 v20, v25, v20
	v_mul_f32_e32 v24, 0xbfb8aa3b, v26
	v_mul_f32_e32 v25, v20, v17
	v_mul_f32_e32 v17, v30, v21
	v_exp_f32_e32 v24, v24
	v_mul_f32_e32 v17, v17, v22
	v_mul_f32_e32 v21, 0xbfb8aa3b, v31
	v_mul_f32_e32 v22, 0xbfb8aa3b, v27
	v_exp_f32_e32 v21, v21
	v_exp_f32_e32 v22, v22
	v_add_f32_e32 v20, 1.0, v24
	v_rcp_f32_e32 v20, v20
	v_add_f32_e32 v21, 1.0, v21
	v_add_f32_e32 v22, 1.0, v22
	v_rcp_f32_e32 v21, v21
	v_rcp_f32_e32 v22, v22
	v_mul_f32_e32 v20, v26, v20
	v_mul_f32_e32 v24, v20, v18
	v_mul_f32_e32 v18, v31, v21
	v_mul_f32_e32 v20, v27, v22
	v_mul_f32_e32 v18, v18, v23
	v_mul_f32_e32 v19, v20, v19
	v_lshl_add_u64 v[20:21], v[32:33], 0, v[112:113]
	v_cvt_pk_bf16_f32 v16, v28, v16
	v_cvt_pk_bf16_f32 v17, v17, v18
	v_cvt_pk_bf16_f32 v18, v35, v25
	v_cvt_pk_bf16_f32 v19, v24, v19
	global_store_dwordx4 v[20:21], v[16:19], off
	s_nop 1
	v_mul_f32_e32 v16, 0xbfb8aa3b, v12
	v_exp_f32_e32 v16, v16
	v_mul_f32_e32 v17, 0xbfb8aa3b, v8
	v_exp_f32_e32 v17, v17
	v_add_u32_e32 v18, 0xb0, v141
	v_add_f32_e32 v16, 1.0, v16
	v_rcp_f32_e32 v19, v16
	v_add_f32_e32 v16, 1.0, v17
	v_rcp_f32_e32 v20, v16
	v_mad_i64_i32 v[16:17], s[46:47], v18, s44, v[134:135]
	v_mul_f32_e32 v12, v12, v19
	v_mul_f32_e32 v12, v12, v4
	v_mul_f32_e32 v4, v8, v20
	v_mul_f32_e32 v8, 0xbfb8aa3b, v13
	v_exp_f32_e32 v8, v8
	v_mul_f32_e32 v18, 0xbfb8aa3b, v9
	v_mul_f32_e32 v19, v4, v0
	v_exp_f32_e32 v18, v18
	v_add_f32_e32 v0, 1.0, v8
	v_rcp_f32_e32 v0, v0
	v_mul_f32_e32 v8, 0xbfb8aa3b, v14
	v_exp_f32_e32 v8, v8
	v_add_f32_e32 v4, 1.0, v18
	v_mul_f32_e32 v0, v13, v0
	v_rcp_f32_e32 v4, v4
	v_mul_f32_e32 v0, v0, v5
	v_add_f32_e32 v5, 1.0, v8
	v_rcp_f32_e32 v5, v5
	v_mul_f32_e32 v4, v9, v4
	v_mul_f32_e32 v8, 0xbfb8aa3b, v10
	v_mul_f32_e32 v9, v4, v1
	v_mul_f32_e32 v1, v14, v5
	v_exp_f32_e32 v8, v8
	v_mul_f32_e32 v1, v1, v6
	v_mul_f32_e32 v5, 0xbfb8aa3b, v15
	v_mul_f32_e32 v6, 0xbfb8aa3b, v11
	v_exp_f32_e32 v5, v5
	v_exp_f32_e32 v6, v6
	v_add_f32_e32 v4, 1.0, v8
	v_rcp_f32_e32 v4, v4
	v_add_f32_e32 v5, 1.0, v5
	v_add_f32_e32 v6, 1.0, v6
	v_rcp_f32_e32 v5, v5
	v_rcp_f32_e32 v6, v6
	v_mul_f32_e32 v4, v10, v4
	v_mul_f32_e32 v8, v4, v2
	v_mul_f32_e32 v2, v15, v5
	v_mul_f32_e32 v4, v11, v6
	v_mul_f32_e32 v2, v2, v7
	v_mul_f32_e32 v3, v4, v3
	v_lshl_add_u64 v[4:5], v[16:17], 0, v[112:113]
	v_cvt_pk_bf16_f32 v0, v12, v0
	v_cvt_pk_bf16_f32 v1, v1, v2
	v_cvt_pk_bf16_f32 v2, v19, v9
	v_cvt_pk_bf16_f32 v3, v8, v3
	global_store_dwordx4 v[4:5], v[0:3], off
	s_mul_i32 s45, s34, s0
	s_add_i32 s45, s45, s1
	s_cmpk_gt_i32 s45, 0x5d7
	s_cbranch_scc1 .LBB0_701
	s_ashr_i32 s34, s45, 31
	s_lshr_b32 s34, s34, 29
	s_add_i32 s34, s45, s34
	s_ashr_i32 s46, s34, 3
	s_and_b32 s34, s34, -8
	s_sub_i32 s34, s45, s34
	s_cmp_lt_i32 s34, 0
	s_cselect_b32 s45, s41, 0xbb
	s_mul_i32 s34, s45, s34
	s_add_i32 s34, s34, s46
	s_mul_hi_i32 s45, s34, 0x2e8ba2e9
	s_lshr_b32 s46, s45, 31
	s_ashr_i32 s45, s45, 6
	s_add_i32 s45, s45, s46
	s_lshl_b32 s48, s45, 3
	s_sub_i32 s46, 34, s48
	s_min_u32 s49, s46, 8
	s_mulk_i32 s45, 0x160
	s_sub_i32 s34, s34, s45
	v_cvt_f32_ubyte0_e32 v1, s49
	v_cvt_f32_i32_e32 v0, s34
	v_rcp_iflag_f32_e32 v2, v1
	s_ashr_i32 s45, s34, 30
	s_or_b32 s45, s45, 1
	s_mov_b64 s[54:55], 0
	v_mul_f32_e32 v2, v0, v2
	v_trunc_f32_e32 v2, v2
	v_fma_f32 v0, -v2, v1, v0
	v_cvt_i32_f32_e32 v2, v2
	v_cmp_ge_f32_e64 s[46:47], |v0|, v1
	s_and_b64 s[46:47], s[46:47], exec
	s_cselect_b32 s45, s45, 0
	v_readfirstlane_b32 s46, v2
	s_add_i32 s45, s46, s45
	s_sext_i32_i16 s52, s45
	s_mul_i32 s45, s45, s49
	s_sub_i32 s34, s34, s45
	s_sext_i32_i16 s34, s34
	s_add_i32 s34, s48, s34
	s_branch .LBB0_701

.LBB0_752:
	ds_read_b128 v[128:131], v224
	ds_read_b128 v[132:135], v224 offset:1024
	ds_read_b128 v[136:139], v224 offset:2048
	ds_read_b128 v[140:143], v224 offset:3072
	s_add_i32 s60, s23, 2
	s_add_u32 s61, s34, 0xffea0080
	s_addc_u32 s63, s35, -1
	s_cmp_eq_u32 s1, s23
	s_cselect_b32 s65, s57, s63
	s_cselect_b32 s64, s56, s61
	s_cselect_b32 s67, s5, s21
	s_cselect_b32 s66, s4, s6
	v_lshl_add_u64 v[184:185], s[34:35], 0, v[150:151]
	s_add_i32 m0, s38, 0xc000
	ds_read_b128 v[152:155], v225
	ds_read_b128 v[156:159], v225 offset:1024
	ds_read_b128 v[160:163], v225 offset:2048
	ds_read_b128 v[164:167], v225 offset:3072
	ds_read_b128 v[168:171], v225 offset:4096
	ds_read_b128 v[172:175], v225 offset:5120
	ds_read_b128 v[176:179], v225 offset:6144
	ds_read_b128 v[180:183], v225 offset:7168
	global_load_lds_dwordx4 v[184:185], off
	v_lshl_add_u64 v[184:185], v[184:185], 0, s[10:11]
	s_add_i32 m0, s38, 0xe000
	s_nop 0
	global_load_lds_dwordx4 v[184:185], off
	s_waitcnt lgkmcnt(8)
	s_barrier
	s_waitcnt lgkmcnt(0)
	s_waitcnt lgkmcnt(0)
	v_mfma_f32_16x16x32_bf16 v[124:127], v[128:131], v[152:155], v[124:127]
	v_mfma_f32_16x16x32_bf16 v[120:123], v[136:139], v[152:155], v[120:123]
	v_mfma_f32_16x16x32_bf16 v[116:119], v[128:131], v[160:163], v[116:119]
	v_mfma_f32_16x16x32_bf16 v[112:115], v[136:139], v[160:163], v[112:115]
	v_mfma_f32_16x16x32_bf16 v[104:107], v[128:131], v[168:171], v[104:107]
	v_mfma_f32_16x16x32_bf16 v[96:99], v[136:139], v[168:171], v[96:99]
	v_mfma_f32_16x16x32_bf16 v[88:91], v[128:131], v[176:179], v[88:91]
	v_mfma_f32_16x16x32_bf16 v[80:83], v[136:139], v[176:179], v[80:83]
	v_mfma_f32_16x16x32_bf16 v[124:127], v[132:135], v[156:159], v[124:127]
	v_mfma_f32_16x16x32_bf16 v[120:123], v[140:143], v[156:159], v[120:123]
	v_mfma_f32_16x16x32_bf16 v[116:119], v[132:135], v[164:167], v[116:119]
	v_mfma_f32_16x16x32_bf16 v[112:115], v[140:143], v[164:167], v[112:115]
	v_mfma_f32_16x16x32_bf16 v[104:107], v[132:135], v[172:175], v[104:107]
	v_mfma_f32_16x16x32_bf16 v[96:99], v[140:143], v[172:175], v[96:99]
	v_mfma_f32_16x16x32_bf16 v[88:91], v[132:135], v[180:183], v[88:91]
	v_mfma_f32_16x16x32_bf16 v[80:83], v[140:143], v[180:183], v[80:83]
	s_barrier
	s_add_i32 s23, s50, s37
	v_lshl_add_u64 v[200:201], s[66:67], 0, v[146:147]
	s_mov_b32 m0, s23
	ds_read_b128 v[184:187], v226
	ds_read_b128 v[188:191], v226 offset:1024
	ds_read_b128 v[192:195], v226 offset:2048
	ds_read_b128 v[196:199], v226 offset:3072
	global_load_lds_dwordx4 v[200:201], off
	v_lshl_add_u64 v[202:203], v[200:201], 0, s[10:11]
	s_add_i32 m0, s23, 0x2000
	s_nop 0
	global_load_lds_dwordx4 v[202:203], off
	s_barrier
	s_waitcnt lgkmcnt(0)
	s_waitcnt lgkmcnt(0)
	v_mfma_f32_16x16x32_bf16 v[108:111], v[184:187], v[152:155], v[108:111]
	v_mfma_f32_16x16x32_bf16 v[100:103], v[192:195], v[152:155], v[100:103]
	v_mfma_f32_16x16x32_bf16 v[92:95], v[184:187], v[160:163], v[92:95]
	v_mfma_f32_16x16x32_bf16 v[84:87], v[192:195], v[160:163], v[84:87]
	v_mfma_f32_16x16x32_bf16 v[76:79], v[184:187], v[168:171], v[76:79]
	v_mfma_f32_16x16x32_bf16 v[72:75], v[192:195], v[168:171], v[72:75]
	v_mfma_f32_16x16x32_bf16 v[68:71], v[184:187], v[176:179], v[68:71]
	v_mfma_f32_16x16x32_bf16 v[64:67], v[192:195], v[176:179], v[64:67]
	v_mfma_f32_16x16x32_bf16 v[108:111], v[188:191], v[156:159], v[108:111]
	v_mfma_f32_16x16x32_bf16 v[100:103], v[196:199], v[156:159], v[100:103]
	v_mfma_f32_16x16x32_bf16 v[92:95], v[188:191], v[164:167], v[92:95]
	v_mfma_f32_16x16x32_bf16 v[84:87], v[196:199], v[164:167], v[84:87]
	v_mfma_f32_16x16x32_bf16 v[76:79], v[188:191], v[172:175], v[76:79]
	v_mfma_f32_16x16x32_bf16 v[72:75], v[196:199], v[172:175], v[72:75]
	v_mfma_f32_16x16x32_bf16 v[68:71], v[188:191], v[180:183], v[68:71]
	v_mfma_f32_16x16x32_bf16 v[64:67], v[196:199], v[180:183], v[64:67]
	s_mov_b32 m0, s38
	v_lshl_add_u64 v[202:203], s[64:65], 0, v[144:145]
	s_barrier
	ds_read_b128 v[152:155], v225 offset:16384
	ds_read_b128 v[156:159], v225 offset:17408
	ds_read_b128 v[160:163], v225 offset:18432
	ds_read_b128 v[164:167], v225 offset:19456
	ds_read_b128 v[168:171], v225 offset:20480
	ds_read_b128 v[172:175], v225 offset:21504
	ds_read_b128 v[176:179], v225 offset:22528
	ds_read_b128 v[180:183], v225 offset:23552
	global_load_lds_dwordx4 v[202:203], off
	v_lshl_add_u64 v[204:205], v[202:203], 0, s[10:11]
	s_mov_b32 m0, s39
	s_nop 0
	global_load_lds_dwordx4 v[204:205], off
	s_barrier
	s_waitcnt lgkmcnt(0)
	s_waitcnt lgkmcnt(0)
	v_mfma_f32_16x16x32_bf16 v[60:63], v[128:131], v[152:155], v[60:63]
	v_mfma_f32_16x16x32_bf16 v[56:59], v[136:139], v[152:155], v[56:59]
	v_mfma_f32_16x16x32_bf16 v[52:55], v[128:131], v[160:163], v[52:55]
	v_mfma_f32_16x16x32_bf16 v[48:51], v[136:139], v[160:163], v[48:51]
	v_mfma_f32_16x16x32_bf16 v[40:43], v[128:131], v[168:171], v[40:43]
	v_mfma_f32_16x16x32_bf16 v[32:35], v[136:139], v[168:171], v[32:35]
	v_mfma_f32_16x16x32_bf16 v[24:27], v[128:131], v[176:179], v[24:27]
	v_mfma_f32_16x16x32_bf16 v[16:19], v[136:139], v[176:179], v[16:19]
	v_mfma_f32_16x16x32_bf16 v[60:63], v[132:135], v[156:159], v[60:63]
	v_mfma_f32_16x16x32_bf16 v[56:59], v[140:143], v[156:159], v[56:59]
	v_mfma_f32_16x16x32_bf16 v[52:55], v[132:135], v[164:167], v[52:55]
	v_mfma_f32_16x16x32_bf16 v[48:51], v[140:143], v[164:167], v[48:51]
	v_mfma_f32_16x16x32_bf16 v[40:43], v[132:135], v[172:175], v[40:43]
	v_mfma_f32_16x16x32_bf16 v[32:35], v[140:143], v[172:175], v[32:35]
	v_mfma_f32_16x16x32_bf16 v[24:27], v[132:135], v[180:183], v[24:27]
	v_mfma_f32_16x16x32_bf16 v[16:19], v[140:143], v[180:183], v[16:19]
	s_barrier
	s_add_i32 s23, s51, s37
	v_lshl_add_u64 v[128:129], v[200:201], 0, s[16:17]
	s_mov_b32 m0, s23
	s_nop 0
	global_load_lds_dwordx4 v[128:129], off
	v_lshl_add_u64 v[128:129], v[200:201], 0, s[18:19]
	s_add_i32 m0, s23, 0x2000
	s_nop 0
	global_load_lds_dwordx4 v[128:129], off
	s_waitcnt vmcnt(6)
	s_barrier
	v_mfma_f32_16x16x32_bf16 v[44:47], v[184:187], v[152:155], v[44:47]
	v_mfma_f32_16x16x32_bf16 v[36:39], v[192:195], v[152:155], v[36:39]
	v_mfma_f32_16x16x32_bf16 v[28:31], v[184:187], v[160:163], v[28:31]
	v_mfma_f32_16x16x32_bf16 v[20:23], v[192:195], v[160:163], v[20:23]
	v_mfma_f32_16x16x32_bf16 v[12:15], v[184:187], v[168:171], v[12:15]
	v_mfma_f32_16x16x32_bf16 v[8:11], v[192:195], v[168:171], v[8:11]
	v_mfma_f32_16x16x32_bf16 v[4:7], v[184:187], v[176:179], v[4:7]
	v_mfma_f32_16x16x32_bf16 v[0:3], v[192:195], v[176:179], v[0:3]
	v_mfma_f32_16x16x32_bf16 v[44:47], v[188:191], v[156:159], v[44:47]
	v_mfma_f32_16x16x32_bf16 v[36:39], v[196:199], v[156:159], v[36:39]
	v_mfma_f32_16x16x32_bf16 v[28:31], v[188:191], v[164:167], v[28:31]
	v_mfma_f32_16x16x32_bf16 v[20:23], v[196:199], v[164:167], v[20:23]
	v_mfma_f32_16x16x32_bf16 v[12:15], v[188:191], v[172:175], v[12:15]
	v_mfma_f32_16x16x32_bf16 v[8:11], v[196:199], v[172:175], v[8:11]
	v_mfma_f32_16x16x32_bf16 v[4:7], v[188:191], v[180:183], v[4:7]
	v_mfma_f32_16x16x32_bf16 v[0:3], v[196:199], v[180:183], v[0:3]
	s_add_i32 s23, 0, 0x18000
	v_add_u32_e32 v140, s23, v223
	s_barrier
	ds_read_b128 v[128:131], v140
	ds_read_b128 v[132:135], v140 offset:1024
	ds_read_b128 v[136:139], v140 offset:2048
	ds_read_b128 v[140:143], v140 offset:3072
	s_mov_b32 m0, s40
	v_lshl_add_u64 v[184:185], v[202:203], 0, s[16:17]
	ds_read_b128 v[152:155], v225 offset:32768
	ds_read_b128 v[156:159], v225 offset:33792
	ds_read_b128 v[160:163], v225 offset:34816
	ds_read_b128 v[164:167], v225 offset:35840
	ds_read_b128 v[168:171], v225 offset:36864
	ds_read_b128 v[172:175], v225 offset:37888
	ds_read_b128 v[176:179], v225 offset:38912
	ds_read_b128 v[180:183], v225 offset:39936
	global_load_lds_dwordx4 v[184:185], off
	v_lshl_add_u64 v[184:185], v[202:203], 0, s[18:19]
	s_mov_b32 m0, s41
	s_nop 0
	global_load_lds_dwordx4 v[184:185], off
	s_waitcnt lgkmcnt(8)
	s_barrier
	s_waitcnt lgkmcnt(0)
	s_waitcnt lgkmcnt(0)
	v_mfma_f32_16x16x32_bf16 v[124:127], v[128:131], v[152:155], v[124:127]
	v_mfma_f32_16x16x32_bf16 v[120:123], v[136:139], v[152:155], v[120:123]
	v_mfma_f32_16x16x32_bf16 v[116:119], v[128:131], v[160:163], v[116:119]
	v_mfma_f32_16x16x32_bf16 v[112:115], v[136:139], v[160:163], v[112:115]
	v_mfma_f32_16x16x32_bf16 v[104:107], v[128:131], v[168:171], v[104:107]
	v_mfma_f32_16x16x32_bf16 v[96:99], v[136:139], v[168:171], v[96:99]
	v_mfma_f32_16x16x32_bf16 v[88:91], v[128:131], v[176:179], v[88:91]
	v_mfma_f32_16x16x32_bf16 v[80:83], v[136:139], v[176:179], v[80:83]
	v_mfma_f32_16x16x32_bf16 v[124:127], v[132:135], v[156:159], v[124:127]
	v_mfma_f32_16x16x32_bf16 v[120:123], v[140:143], v[156:159], v[120:123]
	v_mfma_f32_16x16x32_bf16 v[116:119], v[132:135], v[164:167], v[116:119]
	v_mfma_f32_16x16x32_bf16 v[112:115], v[140:143], v[164:167], v[112:115]
	v_mfma_f32_16x16x32_bf16 v[104:107], v[132:135], v[172:175], v[104:107]
	v_mfma_f32_16x16x32_bf16 v[96:99], v[140:143], v[172:175], v[96:99]
	v_mfma_f32_16x16x32_bf16 v[88:91], v[132:135], v[180:183], v[88:91]
	v_mfma_f32_16x16x32_bf16 v[80:83], v[140:143], v[180:183], v[80:83]
	s_barrier
	s_add_i32 s61, 0, 0x1c000
	s_add_i32 s23, s23, s37
	v_add_u32_e32 v148, s61, v223
	v_lshl_add_u64 v[204:205], v[200:201], 0, s[24:25]
	s_mov_b32 m0, s23
	ds_read_b128 v[184:187], v148
	ds_read_b128 v[188:191], v148 offset:1024
	ds_read_b128 v[192:195], v148 offset:2048
	ds_read_b128 v[196:199], v148 offset:3072
	global_load_lds_dwordx4 v[204:205], off
	v_lshl_add_u64 v[204:205], v[200:201], 0, s[26:27]
	s_add_i32 m0, s23, 0x2000
	s_nop 0
	global_load_lds_dwordx4 v[204:205], off
	s_barrier
	s_waitcnt lgkmcnt(0)
	s_waitcnt lgkmcnt(0)
	v_mfma_f32_16x16x32_bf16 v[108:111], v[184:187], v[152:155], v[108:111]
	v_mfma_f32_16x16x32_bf16 v[100:103], v[192:195], v[152:155], v[100:103]
	v_mfma_f32_16x16x32_bf16 v[92:95], v[184:187], v[160:163], v[92:95]
	v_mfma_f32_16x16x32_bf16 v[84:87], v[192:195], v[160:163], v[84:87]
	v_mfma_f32_16x16x32_bf16 v[76:79], v[184:187], v[168:171], v[76:79]
	v_mfma_f32_16x16x32_bf16 v[72:75], v[192:195], v[168:171], v[72:75]
	v_mfma_f32_16x16x32_bf16 v[68:71], v[184:187], v[176:179], v[68:71]
	v_mfma_f32_16x16x32_bf16 v[64:67], v[192:195], v[176:179], v[64:67]
	v_mfma_f32_16x16x32_bf16 v[108:111], v[188:191], v[156:159], v[108:111]
	v_mfma_f32_16x16x32_bf16 v[100:103], v[196:199], v[156:159], v[100:103]
	v_mfma_f32_16x16x32_bf16 v[92:95], v[188:191], v[164:167], v[92:95]
	v_mfma_f32_16x16x32_bf16 v[84:87], v[196:199], v[164:167], v[84:87]
	v_mfma_f32_16x16x32_bf16 v[76:79], v[188:191], v[172:175], v[76:79]
	v_mfma_f32_16x16x32_bf16 v[72:75], v[196:199], v[172:175], v[72:75]
	v_mfma_f32_16x16x32_bf16 v[68:71], v[188:191], v[180:183], v[68:71]
	v_mfma_f32_16x16x32_bf16 v[64:67], v[196:199], v[180:183], v[64:67]
	s_mov_b32 m0, s47
	v_lshl_add_u64 v[204:205], v[202:203], 0, s[24:25]
	s_barrier
	ds_read_b128 v[152:155], v225 offset:49152
	ds_read_b128 v[156:159], v225 offset:50176
	ds_read_b128 v[160:163], v225 offset:51200
	ds_read_b128 v[164:167], v225 offset:52224
	ds_read_b128 v[168:171], v225 offset:53248
	ds_read_b128 v[172:175], v225 offset:54272
	ds_read_b128 v[176:179], v225 offset:55296
	ds_read_b128 v[180:183], v225 offset:56320
	global_load_lds_dwordx4 v[204:205], off
	v_lshl_add_u64 v[202:203], v[202:203], 0, s[26:27]
	s_mov_b32 m0, s48
	s_nop 0
	global_load_lds_dwordx4 v[202:203], off
	s_barrier
	s_waitcnt lgkmcnt(0)
	s_waitcnt lgkmcnt(0)
	v_mfma_f32_16x16x32_bf16 v[60:63], v[128:131], v[152:155], v[60:63]
	v_mfma_f32_16x16x32_bf16 v[56:59], v[136:139], v[152:155], v[56:59]
	v_mfma_f32_16x16x32_bf16 v[52:55], v[128:131], v[160:163], v[52:55]
	v_mfma_f32_16x16x32_bf16 v[48:51], v[136:139], v[160:163], v[48:51]
	v_mfma_f32_16x16x32_bf16 v[40:43], v[128:131], v[168:171], v[40:43]
	v_mfma_f32_16x16x32_bf16 v[32:35], v[136:139], v[168:171], v[32:35]
	v_mfma_f32_16x16x32_bf16 v[24:27], v[128:131], v[176:179], v[24:27]
	v_mfma_f32_16x16x32_bf16 v[16:19], v[136:139], v[176:179], v[16:19]
	v_mfma_f32_16x16x32_bf16 v[60:63], v[132:135], v[156:159], v[60:63]
	v_mfma_f32_16x16x32_bf16 v[56:59], v[140:143], v[156:159], v[56:59]
	v_mfma_f32_16x16x32_bf16 v[52:55], v[132:135], v[164:167], v[52:55]
	v_mfma_f32_16x16x32_bf16 v[48:51], v[140:143], v[164:167], v[48:51]
	v_mfma_f32_16x16x32_bf16 v[40:43], v[132:135], v[172:175], v[40:43]
	v_mfma_f32_16x16x32_bf16 v[32:35], v[140:143], v[172:175], v[32:35]
	v_mfma_f32_16x16x32_bf16 v[24:27], v[132:135], v[180:183], v[24:27]
	v_mfma_f32_16x16x32_bf16 v[16:19], v[140:143], v[180:183], v[16:19]
	s_barrier
	s_add_i32 s23, s61, s37
	v_lshl_add_u64 v[128:129], v[200:201], 0, s[52:53]
	s_mov_b32 m0, s23
	s_nop 0
	global_load_lds_dwordx4 v[128:129], off
	v_lshl_add_u64 v[128:129], v[200:201], 0, s[54:55]
	s_add_i32 m0, s23, 0x2000
	s_nop 0
	global_load_lds_dwordx4 v[128:129], off
	s_waitcnt vmcnt(6)
	s_barrier
	v_mfma_f32_16x16x32_bf16 v[44:47], v[184:187], v[152:155], v[44:47]
	v_mfma_f32_16x16x32_bf16 v[36:39], v[192:195], v[152:155], v[36:39]
	v_mfma_f32_16x16x32_bf16 v[28:31], v[184:187], v[160:163], v[28:31]
	v_mfma_f32_16x16x32_bf16 v[20:23], v[192:195], v[160:163], v[20:23]
	v_mfma_f32_16x16x32_bf16 v[12:15], v[184:187], v[168:171], v[12:15]
	v_mfma_f32_16x16x32_bf16 v[8:11], v[192:195], v[168:171], v[8:11]
	v_mfma_f32_16x16x32_bf16 v[4:7], v[184:187], v[176:179], v[4:7]
	v_mfma_f32_16x16x32_bf16 v[0:3], v[192:195], v[176:179], v[0:3]
	v_mfma_f32_16x16x32_bf16 v[44:47], v[188:191], v[156:159], v[44:47]
	v_mfma_f32_16x16x32_bf16 v[36:39], v[196:199], v[156:159], v[36:39]
	v_mfma_f32_16x16x32_bf16 v[28:31], v[188:191], v[164:167], v[28:31]
	v_mfma_f32_16x16x32_bf16 v[20:23], v[196:199], v[164:167], v[20:23]
	v_mfma_f32_16x16x32_bf16 v[12:15], v[188:191], v[172:175], v[12:15]
	v_mfma_f32_16x16x32_bf16 v[8:11], v[196:199], v[172:175], v[8:11]
	v_mfma_f32_16x16x32_bf16 v[4:7], v[188:191], v[180:183], v[4:7]
	v_mfma_f32_16x16x32_bf16 v[0:3], v[196:199], v[180:183], v[0:3]
	s_add_u32 s34, s34, 0x100
	s_addc_u32 s35, s35, 0
	s_add_u32 s6, s6, 0x100
	s_addc_u32 s21, s21, 0
	s_cmp_ge_u32 s60, s0
	s_mov_b32 s23, s60
	s_barrier
	s_cbranch_scc0 .LBB0_752
	v_mov_b32_e32 v128, v222
	s_mov_b32 s0, s36
	s_mov_b32 s1, s46
	s_lshl_b32 s34, s1, 5
	v_and_b32_e32 v227, 15, v128
	v_bfe_u32 v148, v128, 4, 2
	s_mov_b64 s[60:61], -1
	s_and_b64 vcc, exec, s[58:59]
	s_cbranch_vccz .LBB0_755
	s_sub_i32 s1, s22, 32
	s_cmp_lt_i32 s22, 32
	s_movk_i32 s6, 0x3000
	s_cselect_b32 s58, s22, s1
	s_mov_b32 s1, 0x1d5b3600
	s_cselect_b32 s6, s6, 0x6000
	s_cselect_b32 s1, s1, 0x1f5b3600
	s_ashr_i32 s59, s58, 31
	s_add_u32 s1, s15, s1
	s_addc_u32 s21, s28, 0
	s_lshl_b32 s23, s49, 8
	s_add_i32 s23, s34, s23
	s_cmp_gt_i32 s22, 15
	s_cselect_b32 s6, s6, 0
	s_lshl_b32 s6, s6, 2
	s_add_u32 s60, s42, s6
	s_addc_u32 s61, s43, 0
	s_lshl_b64 s[58:59], s[58:59], 20
	v_lshl_or_b32 v154, v148, 3, s23
	v_lshl_or_b32 v152, s0, 6, v227
	s_add_u32 s58, s1, s58
	v_ashrrev_i32_e32 v155, 31, v154
	s_addc_u32 s59, s21, s59
	v_ashrrev_i32_e32 v153, 31, v152
	v_lshl_add_u64 v[132:133], v[154:155], 2, s[60:61]
	v_lshl_add_u64 v[154:155], v[154:155], 1, s[58:59]
	v_lshlrev_b64 v[156:157], 12, v[152:153]
	v_lshl_add_u64 v[156:157], v[154:155], 0, v[156:157]
	global_load_dwordx4 v[136:139], v[132:133], off offset:16
	global_load_dwordx4 v[140:143], v[132:133], off
	global_load_dwordx4 v[128:131], v[132:133], off offset:528
	s_nop 0
	global_load_dwordx4 v[132:135], v[132:133], off offset:512
	v_or_b32_e32 v168, 48, v152
	global_load_dwordx4 v[158:161], v[156:157], off
	v_ashrrev_i32_e32 v169, 31, v168
	v_lshlrev_b64 v[168:169], 12, v[168:169]
	v_lshl_add_u64 v[168:169], v[154:155], 0, v[168:169]
	global_load_dwordx4 v[218:221], v[168:169], off
	s_mov_b64 s[60:61], 0
	global_load_dwordx4 v[228:231], v[168:169], off offset:256
	s_waitcnt vmcnt(0)
	v_lshlrev_b32_e32 v170, 16, v158
	v_and_b32_e32 v171, 0xffff0000, v158
	v_lshlrev_b32_e32 v176, 16, v159
	v_and_b32_e32 v177, 0xffff0000, v159
	v_lshlrev_b32_e32 v162, 16, v160
	v_and_b32_e32 v163, 0xffff0000, v160
	v_lshlrev_b32_e32 v166, 16, v161
	v_and_b32_e32 v167, 0xffff0000, v161
	global_load_dwordx4 v[158:161], v[156:157], off offset:256
	v_pk_fma_f32 v[162:163], v[120:121], v[136:137], v[162:163]
	v_lshlrev_b32_e32 v216, 16, v221
	v_and_b32_e32 v217, 0xffff0000, v221
	v_pk_fma_f32 v[176:177], v[126:127], v[142:143], v[176:177]
	v_pk_fma_f32 v[170:171], v[124:125], v[140:141], v[170:171]
	v_pk_fma_f32 v[166:167], v[122:123], v[138:139], v[166:167]
	v_lshlrev_b32_e32 v214, 16, v218
	v_and_b32_e32 v215, 0xffff0000, v218
	v_lshlrev_b32_e32 v218, 16, v219
	v_and_b32_e32 v219, 0xffff0000, v219
	v_lshlrev_b32_e32 v232, 16, v228
	v_and_b32_e32 v233, 0xffff0000, v228
	v_lshlrev_b32_e32 v234, 16, v229
	v_and_b32_e32 v235, 0xffff0000, v229
	v_and_b32_e32 v221, 0xffff0000, v230
	v_lshlrev_b32_e32 v236, 16, v231
	v_and_b32_e32 v237, 0xffff0000, v231
	s_waitcnt vmcnt(0)
	v_lshlrev_b32_e32 v174, 16, v158
	v_and_b32_e32 v175, 0xffff0000, v158
	v_lshlrev_b32_e32 v164, 16, v160
	v_and_b32_e32 v165, 0xffff0000, v160
	v_or_b32_e32 v158, 16, v152
	v_or_b32_e32 v160, 32, v152
	v_lshlrev_b32_e32 v178, 16, v159
	v_and_b32_e32 v179, 0xffff0000, v159
	v_lshlrev_b32_e32 v172, 16, v161
	v_and_b32_e32 v173, 0xffff0000, v161
	v_ashrrev_i32_e32 v159, 31, v158
	v_ashrrev_i32_e32 v161, 31, v160
	v_lshlrev_b64 v[158:159], 12, v[158:159]
	v_lshlrev_b64 v[160:161], 12, v[160:161]
	v_lshl_add_u64 v[158:159], v[154:155], 0, v[158:159]
	v_lshl_add_u64 v[160:161], v[154:155], 0, v[160:161]
	global_load_dwordx4 v[184:187], v[158:159], off
	global_load_dwordx4 v[194:197], v[158:159], off offset:256
	global_load_dwordx4 v[200:203], v[160:161], off
	global_load_dwordx4 v[210:213], v[160:161], off offset:256
	v_cvt_pk_bf16_f32 v228, v170, v171
	v_cvt_pk_bf16_f32 v229, v176, v177
	v_pk_fma_f32 v[164:165], v[100:101], v[128:129], v[164:165]
	v_pk_fma_f32 v[170:171], v[102:103], v[130:131], v[172:173]
	s_waitcnt vmcnt(0)
	v_lshlrev_b32_e32 v182, 16, v184
	v_and_b32_e32 v183, 0xffff0000, v184
	v_lshlrev_b32_e32 v188, 16, v185
	v_and_b32_e32 v189, 0xffff0000, v185
	v_lshlrev_b32_e32 v180, 16, v186
	v_and_b32_e32 v181, 0xffff0000, v186
	v_lshlrev_b32_e32 v184, 16, v187
	v_and_b32_e32 v185, 0xffff0000, v187
	v_lshlrev_b32_e32 v186, 16, v196
	v_and_b32_e32 v187, 0xffff0000, v196
	v_lshlrev_b32_e32 v192, 16, v197
	v_and_b32_e32 v193, 0xffff0000, v197
	v_lshlrev_b32_e32 v198, 16, v200
	v_and_b32_e32 v199, 0xffff0000, v200
	v_lshlrev_b32_e32 v204, 16, v201
	v_and_b32_e32 v205, 0xffff0000, v201
	v_lshlrev_b32_e32 v196, 16, v202
	v_and_b32_e32 v197, 0xffff0000, v202
	v_lshlrev_b32_e32 v200, 16, v203
	v_and_b32_e32 v201, 0xffff0000, v203
	v_lshlrev_b32_e32 v202, 16, v212
	v_and_b32_e32 v203, 0xffff0000, v212
	v_lshlrev_b32_e32 v208, 16, v213
	v_and_b32_e32 v209, 0xffff0000, v213
	v_lshlrev_b32_e32 v212, 16, v220
	v_and_b32_e32 v213, 0xffff0000, v220
	v_lshlrev_b32_e32 v220, 16, v230
	v_cvt_pk_bf16_f32 v230, v162, v163
	v_pk_fma_f32 v[162:163], v[108:109], v[132:133], v[174:175]
	v_cvt_pk_bf16_f32 v231, v166, v167
	global_store_dwordx4 v[156:157], v[228:231], off
	v_pk_fma_f32 v[166:167], v[110:111], v[134:135], v[178:179]
	v_cvt_pk_bf16_f32 v162, v162, v163
	v_lshlrev_b32_e32 v190, 16, v194
	v_cvt_pk_bf16_f32 v163, v166, v167
	v_cvt_pk_bf16_f32 v164, v164, v165
	v_cvt_pk_bf16_f32 v165, v170, v171
	global_store_dwordx4 v[156:157], v[162:165], off offset:256
	v_and_b32_e32 v191, 0xffff0000, v194
	v_lshlrev_b32_e32 v194, 16, v195
	v_pk_fma_f32 v[162:163], v[116:117], v[140:141], v[182:183]
	v_and_b32_e32 v195, 0xffff0000, v195
	v_pk_fma_f32 v[156:157], v[118:119], v[142:143], v[188:189]
	v_pk_fma_f32 v[164:165], v[112:113], v[136:137], v[180:181]
	v_cvt_pk_bf16_f32 v162, v162, v163
	v_cvt_pk_bf16_f32 v163, v156, v157
	v_pk_fma_f32 v[166:167], v[114:115], v[138:139], v[184:185]
	v_cvt_pk_bf16_f32 v164, v164, v165
	v_pk_fma_f32 v[156:157], v[94:95], v[134:135], v[194:195]
	v_cvt_pk_bf16_f32 v165, v166, v167
	global_store_dwordx4 v[158:159], v[162:165], off
	v_lshlrev_b32_e32 v206, 16, v210
	v_and_b32_e32 v207, 0xffff0000, v210
	v_pk_fma_f32 v[162:163], v[92:93], v[132:133], v[190:191]
	v_pk_fma_f32 v[164:165], v[84:85], v[128:129], v[186:187]
	v_cvt_pk_bf16_f32 v162, v162, v163
	v_cvt_pk_bf16_f32 v163, v156, v157
	v_pk_fma_f32 v[156:157], v[104:105], v[140:141], v[198:199]
	v_pk_fma_f32 v[166:167], v[86:87], v[130:131], v[192:193]
	v_cvt_pk_bf16_f32 v164, v164, v165
	v_lshlrev_b32_e32 v210, 16, v211
	v_cvt_pk_bf16_f32 v165, v166, v167
	global_store_dwordx4 v[158:159], v[162:165], off offset:256
	v_pk_fma_f32 v[158:159], v[106:107], v[142:143], v[204:205]
	v_cvt_pk_bf16_f32 v156, v156, v157
	v_and_b32_e32 v211, 0xffff0000, v211
	v_cvt_pk_bf16_f32 v157, v158, v159
	v_pk_fma_f32 v[162:163], v[98:99], v[138:139], v[200:201]
	v_pk_fma_f32 v[164:165], v[96:97], v[136:137], v[196:197]
	s_nop 0
	v_cvt_pk_bf16_f32 v158, v164, v165
	v_cvt_pk_bf16_f32 v159, v162, v163
	global_store_dwordx4 v[160:161], v[156:159], off
	v_pk_fma_f32 v[162:163], v[74:75], v[130:131], v[208:209]
	v_pk_fma_f32 v[164:165], v[72:73], v[128:129], v[202:203]
	v_pk_fma_f32 v[156:157], v[76:77], v[132:133], v[206:207]
	v_pk_fma_f32 v[158:159], v[78:79], v[134:135], v[210:211]
	v_cvt_pk_bf16_f32 v156, v156, v157
	s_nop 0
	v_cvt_pk_bf16_f32 v157, v158, v159
	v_cvt_pk_bf16_f32 v158, v164, v165
	v_cvt_pk_bf16_f32 v159, v162, v163
	global_store_dwordx4 v[160:161], v[156:159], off offset:256
	v_pk_fma_f32 v[160:161], v[82:83], v[138:139], v[216:217]
	v_pk_fma_f32 v[162:163], v[80:81], v[136:137], v[212:213]
	v_pk_fma_f32 v[156:157], v[88:89], v[140:141], v[214:215]
	v_pk_fma_f32 v[158:159], v[90:91], v[142:143], v[218:219]
	v_cvt_pk_bf16_f32 v156, v156, v157
	s_nop 0
	v_cvt_pk_bf16_f32 v157, v158, v159
	v_cvt_pk_bf16_f32 v158, v162, v163
	v_cvt_pk_bf16_f32 v159, v160, v161
	global_store_dwordx4 v[168:169], v[156:159], off
	v_pk_fma_f32 v[160:161], v[66:67], v[130:131], v[236:237]
	v_pk_fma_f32 v[162:163], v[64:65], v[128:129], v[220:221]
	v_pk_fma_f32 v[156:157], v[68:69], v[132:133], v[232:233]
	v_pk_fma_f32 v[158:159], v[70:71], v[134:135], v[234:235]
	v_cvt_pk_bf16_f32 v156, v156, v157
	s_nop 0
	v_cvt_pk_bf16_f32 v157, v158, v159
	v_cvt_pk_bf16_f32 v158, v162, v163
	v_cvt_pk_bf16_f32 v159, v160, v161
	global_store_dwordx4 v[168:169], v[156:159], off offset:256
	s_nop 1
	v_add_u32_e32 v156, 0x80, v152
	v_ashrrev_i32_e32 v157, 31, v156
	v_lshlrev_b64 v[156:157], 12, v[156:157]
	v_lshl_add_u64 v[156:157], v[154:155], 0, v[156:157]
	global_load_dwordx4 v[158:161], v[156:157], off
	s_waitcnt vmcnt(0)
	v_lshlrev_b32_e32 v164, 16, v158
	v_and_b32_e32 v165, 0xffff0000, v158
	v_lshlrev_b32_e32 v170, 16, v159
	v_and_b32_e32 v171, 0xffff0000, v159
	v_lshlrev_b32_e32 v162, 16, v160
	v_and_b32_e32 v163, 0xffff0000, v160
	v_lshlrev_b32_e32 v166, 16, v161
	v_and_b32_e32 v167, 0xffff0000, v161
	global_load_dwordx4 v[158:161], v[156:157], off offset:256
	v_pk_fma_f32 v[170:171], v[62:63], v[142:143], v[170:171]
	v_pk_fma_f32 v[164:165], v[60:61], v[140:141], v[164:165]
	v_pk_fma_f32 v[230:231], v[56:57], v[136:137], v[162:163]
	v_pk_fma_f32 v[166:167], v[58:59], v[138:139], v[166:167]
	s_waitcnt vmcnt(0)
	v_lshlrev_b32_e32 v172, 16, v158
	v_and_b32_e32 v173, 0xffff0000, v158
	v_lshlrev_b32_e32 v168, 16, v160
	v_and_b32_e32 v169, 0xffff0000, v160
	v_add_u32_e32 v158, 0x90, v152
	v_add_u32_e32 v160, 0xa0, v152
	v_add_u32_e32 v152, 0xb0, v152
	v_lshlrev_b32_e32 v176, 16, v159
	v_and_b32_e32 v177, 0xffff0000, v159
	v_ashrrev_i32_e32 v159, 31, v158
	v_ashrrev_i32_e32 v153, 31, v152
	v_lshlrev_b64 v[158:159], 12, v[158:159]
	v_lshlrev_b64 v[152:153], 12, v[152:153]
	v_lshl_add_u64 v[158:159], v[154:155], 0, v[158:159]
	v_lshl_add_u64 v[152:153], v[154:155], 0, v[152:153]
	global_load_dwordx4 v[182:185], v[158:159], off
	global_load_dwordx4 v[214:217], v[152:153], off
	v_lshlrev_b32_e32 v174, 16, v161
	v_and_b32_e32 v175, 0xffff0000, v161
	v_ashrrev_i32_e32 v161, 31, v160
	v_lshlrev_b64 v[160:161], 12, v[160:161]
	global_load_dwordx4 v[192:195], v[158:159], off offset:256
	v_lshl_add_u64 v[160:161], v[154:155], 0, v[160:161]
	global_load_dwordx4 v[198:201], v[160:161], off
	global_load_dwordx4 v[208:211], v[160:161], off offset:256
	v_pk_fma_f32 v[168:169], v[36:37], v[128:129], v[168:169]
	s_waitcnt vmcnt(0)
	v_lshlrev_b32_e32 v180, 16, v182
	v_lshlrev_b32_e32 v154, 16, v216
	v_and_b32_e32 v155, 0xffff0000, v216
	v_lshlrev_b32_e32 v212, 16, v217
	v_and_b32_e32 v213, 0xffff0000, v217
	global_load_dwordx4 v[216:219], v[152:153], off offset:256
	v_cvt_pk_bf16_f32 v162, v164, v165
	v_cvt_pk_bf16_f32 v163, v170, v171
	v_cvt_pk_bf16_f32 v164, v230, v231
	v_cvt_pk_bf16_f32 v165, v166, v167
	global_store_dwordx4 v[156:157], v[162:165], off
	v_and_b32_e32 v181, 0xffff0000, v182
	v_lshlrev_b32_e32 v186, 16, v183
	v_pk_fma_f32 v[162:163], v[44:45], v[132:133], v[172:173]
	v_pk_fma_f32 v[164:165], v[46:47], v[134:135], v[176:177]
	v_cvt_pk_bf16_f32 v162, v162, v163
	v_and_b32_e32 v187, 0xffff0000, v183
	v_cvt_pk_bf16_f32 v163, v164, v165
	v_lshlrev_b32_e32 v178, 16, v184
	v_and_b32_e32 v179, 0xffff0000, v184
	v_pk_fma_f32 v[166:167], v[38:39], v[130:131], v[174:175]
	v_cvt_pk_bf16_f32 v164, v168, v169
	v_lshlrev_b32_e32 v182, 16, v185
	v_cvt_pk_bf16_f32 v165, v166, v167
	global_store_dwordx4 v[156:157], v[162:165], off offset:256
	v_and_b32_e32 v183, 0xffff0000, v185
	v_lshlrev_b32_e32 v188, 16, v192
	v_pk_fma_f32 v[162:163], v[52:53], v[140:141], v[180:181]
	v_and_b32_e32 v189, 0xffff0000, v192
	v_lshlrev_b32_e32 v192, 16, v193
	v_and_b32_e32 v193, 0xffff0000, v193
	v_pk_fma_f32 v[156:157], v[54:55], v[142:143], v[186:187]
	v_pk_fma_f32 v[164:165], v[48:49], v[136:137], v[178:179]
	v_cvt_pk_bf16_f32 v162, v162, v163
	v_cvt_pk_bf16_f32 v163, v156, v157
	v_lshlrev_b32_e32 v184, 16, v194
	v_and_b32_e32 v185, 0xffff0000, v194
	v_lshlrev_b32_e32 v196, 16, v198
	v_and_b32_e32 v197, 0xffff0000, v198
	v_pk_fma_f32 v[166:167], v[50:51], v[138:139], v[182:183]
	v_cvt_pk_bf16_f32 v164, v164, v165
	v_pk_fma_f32 v[156:157], v[30:31], v[134:135], v[192:193]
	v_cvt_pk_bf16_f32 v165, v166, v167
	global_store_dwordx4 v[158:159], v[162:165], off
	v_lshlrev_b32_e32 v190, 16, v195
	v_and_b32_e32 v191, 0xffff0000, v195
	v_pk_fma_f32 v[162:163], v[28:29], v[132:133], v[188:189]
	v_lshlrev_b32_e32 v202, 16, v199
	v_and_b32_e32 v203, 0xffff0000, v199
	v_pk_fma_f32 v[164:165], v[20:21], v[128:129], v[184:185]
	v_cvt_pk_bf16_f32 v162, v162, v163
	v_cvt_pk_bf16_f32 v163, v156, v157
	v_pk_fma_f32 v[156:157], v[40:41], v[140:141], v[196:197]
	v_lshlrev_b32_e32 v194, 16, v200
	v_and_b32_e32 v195, 0xffff0000, v200
	v_lshlrev_b32_e32 v198, 16, v201
	v_and_b32_e32 v199, 0xffff0000, v201
	v_lshlrev_b32_e32 v204, 16, v208
	v_and_b32_e32 v205, 0xffff0000, v208
	v_pk_fma_f32 v[166:167], v[22:23], v[130:131], v[190:191]
	v_cvt_pk_bf16_f32 v164, v164, v165
	v_lshlrev_b32_e32 v208, 16, v209
	v_cvt_pk_bf16_f32 v165, v166, v167
	global_store_dwordx4 v[158:159], v[162:165], off offset:256
	v_pk_fma_f32 v[158:159], v[42:43], v[142:143], v[202:203]
	v_cvt_pk_bf16_f32 v156, v156, v157
	v_and_b32_e32 v209, 0xffff0000, v209
	v_cvt_pk_bf16_f32 v157, v158, v159
	v_pk_fma_f32 v[162:163], v[34:35], v[138:139], v[198:199]
	v_pk_fma_f32 v[164:165], v[32:33], v[136:137], v[194:195]
	v_lshlrev_b32_e32 v200, 16, v210
	v_cvt_pk_bf16_f32 v158, v164, v165
	v_cvt_pk_bf16_f32 v159, v162, v163
	global_store_dwordx4 v[160:161], v[156:159], off
	v_and_b32_e32 v201, 0xffff0000, v210
	v_lshlrev_b32_e32 v206, 16, v211
	v_pk_fma_f32 v[156:157], v[12:13], v[132:133], v[204:205]
	v_and_b32_e32 v207, 0xffff0000, v211
	v_lshlrev_b32_e32 v210, 16, v214
	v_and_b32_e32 v211, 0xffff0000, v214
	v_lshlrev_b32_e32 v214, 16, v215
	v_and_b32_e32 v215, 0xffff0000, v215
	v_pk_fma_f32 v[158:159], v[14:15], v[134:135], v[208:209]
	v_cvt_pk_bf16_f32 v156, v156, v157
	v_pk_fma_f32 v[162:163], v[10:11], v[130:131], v[206:207]
	v_cvt_pk_bf16_f32 v157, v158, v159
	s_waitcnt vmcnt(0)
	v_lshlrev_b32_e32 v228, 16, v218
	v_and_b32_e32 v229, 0xffff0000, v218
	v_lshlrev_b32_e32 v218, 16, v219
	v_and_b32_e32 v219, 0xffff0000, v219
	v_pk_fma_f32 v[164:165], v[8:9], v[128:129], v[200:201]
	v_pk_fma_f32 v[142:143], v[26:27], v[142:143], v[214:215]
	v_cvt_pk_bf16_f32 v158, v164, v165
	v_cvt_pk_bf16_f32 v159, v162, v163
	global_store_dwordx4 v[160:161], v[156:159], off offset:256
	v_pk_fma_f32 v[140:141], v[24:25], v[140:141], v[210:211]
	v_lshlrev_b32_e32 v220, 16, v216
	v_pk_fma_f32 v[156:157], v[18:19], v[138:139], v[212:213]
	v_pk_fma_f32 v[138:139], v[16:17], v[136:137], v[154:155]
	v_cvt_pk_bf16_f32 v136, v140, v141
	v_cvt_pk_bf16_f32 v137, v142, v143
	v_and_b32_e32 v221, 0xffff0000, v216
	v_lshlrev_b32_e32 v216, 16, v217
	v_and_b32_e32 v217, 0xffff0000, v217
	v_cvt_pk_bf16_f32 v138, v138, v139
	v_cvt_pk_bf16_f32 v139, v156, v157
	global_store_dwordx4 v[152:153], v[136:139], off
	v_pk_fma_f32 v[134:135], v[6:7], v[134:135], v[216:217]
	v_pk_fma_f32 v[132:133], v[4:5], v[132:133], v[220:221]
	v_pk_fma_f32 v[136:137], v[2:3], v[130:131], v[218:219]
	v_pk_fma_f32 v[130:131], v[0:1], v[128:129], v[228:229]
	v_cvt_pk_bf16_f32 v128, v132, v133
	v_cvt_pk_bf16_f32 v129, v134, v135
	s_nop 0
	v_cvt_pk_bf16_f32 v130, v130, v131
	v_cvt_pk_bf16_f32 v131, v136, v137
	global_store_dwordx4 v[152:153], v[128:131], off offset:256

.LBB0_784:
	s_mov_b64 s[4:5], 0
	s_load_dword s12, s[90:91], 0xd8
	v_mbcnt_lo_u32_b32 v0, -1, 0
	v_mbcnt_hi_u32_b32 v77, -1, v0
	v_or_b32_e32 v76, s94, v77
	s_mov_b32 s0, s88
	s_add_u32 s8, s86, s4
	s_waitcnt lgkmcnt(0)
	s_mov_b32 s1, s12
	v_mov_b32_e32 v78, v76
	s_mov_b32 s13, s12
	s_addc_u32 s9, s87, s5
	s_abs_i32 s22, s13
	v_cvt_f32_u32_e32 v2, s22
	v_lshlrev_b32_e32 v0, 2, v78
	v_and_b32_e32 v84, 60, v0
	s_sub_i32 s2, 0, s22
	v_rcp_iflag_f32_e32 v0, v2
	s_mov_b32 s14, s88
	s_add_i32 s15, s14, s13
	v_mul_f32_e32 v0, 0x4f7ffffe, v0
	v_cvt_u32_f32_e32 v0, v0
	s_abs_i32 s1, s15
	s_ashr_i32 s0, s15, 31
	v_ashrrev_i32_e32 v80, 3, v78
	v_readfirstlane_b32 s23, v0
	s_mul_i32 s2, s2, s23
	s_mul_hi_u32 s2, s23, s2
	s_add_i32 s23, s23, s2
	s_mul_hi_u32 s2, s1, s23
	s_mul_i32 s2, s2, s22
	s_sub_i32 s1, s1, s2
	s_sub_i32 s2, s1, s22
	s_cmp_ge_u32 s1, s22
	s_cselect_b32 s1, s2, s1
	s_sub_i32 s2, s1, s22
	s_cmp_ge_u32 s1, s22
	s_cselect_b32 s1, s2, s1
	s_xor_b32 s1, s1, s0
	v_lshlrev_b32_e32 v2, 3, v78
	s_sub_i32 s24, s1, s0
	v_ashrrev_i32_e32 v79, 4, v78
	v_mov_b32_e32 v1, 0
	v_lshl_add_u32 v81, v84, 2, 0
	v_and_b32_e32 v82, 56, v2
	s_cmpk_lt_i32 s24, 0x480
	v_lshl_add_u32 v83, v80, 2, 0
	s_load_dword s59, s[90:91], 0xd8
	v_mbcnt_lo_u32_b32 v100, -1, 0
	v_mbcnt_hi_u32_b32 v100, -1, v100
	s_lshr_b32 s69, s94, 6
	s_lshl_b32 s82, s69, 10
	s_lshl_b32 s83, s69, 1
	s_lshr_b32 s98, s69, 2
	v_lshrrev_b32_e32 v101, 5, v100
	v_and_b32_e32 v113, 31, v100
	s_add_i32 s70, s83, 0
	v_add_u32_e32 v102, s70, v101
	s_add_i32 s70, s98, 0
	v_xor_b32_e32 v106, s70, v113
	v_lshlrev_b32_e32 v106, 4, v106
	s_add_i32 s70, s83, 16
	v_add_u32_e32 v103, s70, v101
	s_add_i32 s70, s98, 2
	v_xor_b32_e32 v107, s70, v113
	v_lshlrev_b32_e32 v107, 4, v107
	s_add_i32 s70, s83, 32
	v_add_u32_e32 v104, s70, v101
	s_add_i32 s70, s98, 4
	v_xor_b32_e32 v108, s70, v113
	v_lshlrev_b32_e32 v108, 4, v108
	s_add_i32 s70, s83, 48
	v_add_u32_e32 v105, s70, v101
	s_add_i32 s70, s98, 6
	v_xor_b32_e32 v109, s70, v113
	v_lshlrev_b32_e32 v109, 4, v109
	s_lshr_b32 s70, s94, 3
	v_lshrrev_b32_e32 v112, 3, v100
	v_add_u32_e32 v112, s70, v112
	v_and_b32_e32 v101, 7, v100
	v_lshlrev_b32_e32 v111, 4, v101
	v_lshrrev_b32_e32 v113, 2, v112
	v_xor_b32_e32 v113, v113, v101
	v_lshlrev_b32_e32 v113, 4, v113
	v_lshl_add_u32 v110, v101, 12, v113
	v_and_b32_e32 v113, 3, v112
	v_lshl_add_u32 v110, v113, 2, v110
	s_waitcnt lgkmcnt(0)
	s_mov_b32 s61, s88
	s_mov_b32 s60, s88
	s_mov_b32 s58, -2

.Lwp1_doissue:
	s_cmp_lt_u32 s60, 7520
	s_cbranch_scc0 .Lwp1_noissue
	s_add_u32 s99, s58, 2
	s_and_b32 s99, s99, 3
	s_cmp_lt_u32 s60, 2272
	s_cbranch_scc0 .Lwp1_isel_m_1
	v_readlane_b32 s62, v245, 0
	v_readlane_b32 s63, v245, 1
	s_sub_u32 s65, s60, 0
	s_mov_b32 s64, 0x8d00
	s_mul_hi_u32 s66, s65, 0x39b0ad2
	s_mul_i32 s69, s66, 71
	s_sub_u32 s67, s65, s69
	s_add_u32 s62, s62, 0x4680000
	s_addc_u32 s63, s63, 0
	s_cmp_eq_u32 s67, 70
	s_cselect_b32 s68, 1, 0
	s_branch .Lwp1_isel_done_m
.Lwp1_isel_m_1:
	s_cmp_lt_u32 s60, 2400
	s_cbranch_scc0 .Lwp1_isel_m_2
	v_readlane_b32 s62, v245, 16
	v_readlane_b32 s63, v245, 17
	s_sub_u32 s65, s60, 2272
	s_mov_b32 s64, 0x2000
	s_lshr_b32 s66, s65, 4
	s_mul_i32 s69, s66, 16
	s_sub_u32 s67, s65, s69
	s_add_u32 s62, s62, 0x400000
	s_addc_u32 s63, s63, 0
	s_mov_b32 s68, 0
	s_branch .Lwp1_isel_done_m
.Lwp1_isel_m_2:
	s_cmp_lt_u32 s60, 2656
	s_cbranch_scc0 .Lwp1_isel_m_3
	v_readlane_b32 s62, v245, 18
	v_readlane_b32 s63, v245, 19
	s_sub_u32 s65, s60, 2400
	s_mov_b32 s64, 0x2000
	s_lshr_b32 s66, s65, 4
	s_mul_i32 s69, s66, 16
	s_sub_u32 s67, s65, s69
	s_add_u32 s62, s62, 0x800000
	s_addc_u32 s63, s63, 0
	s_mov_b32 s68, 0
	s_branch .Lwp1_isel_done_m
.Lwp1_isel_m_3:
	s_cmp_lt_u32 s60, 2784
	s_cbranch_scc0 .Lwp1_isel_m_4
	v_readlane_b32 s62, v245, 22
	v_readlane_b32 s63, v245, 23
	s_sub_u32 s65, s60, 2656
	s_mov_b32 s64, 0x2000
	s_lshr_b32 s66, s65, 4
	s_mul_i32 s69, s66, 16
	s_sub_u32 s67, s65, s69
	s_add_u32 s62, s62, 0x400000
	s_addc_u32 s63, s63, 0
	s_mov_b32 s68, 0
	s_branch .Lwp1_isel_done_m
.Lwp1_isel_m_4:
	s_cmp_lt_u32 s60, 3296
	s_cbranch_scc0 .Lwp1_isel_m_5
	v_readlane_b32 s62, v245, 24
	v_readlane_b32 s63, v245, 25
	s_sub_u32 s65, s60, 2784
	s_mov_b32 s64, 0x2000
	s_lshr_b32 s66, s65, 4
	s_mul_i32 s69, s66, 16
	s_sub_u32 s67, s65, s69
	s_add_u32 s62, s62, 0x1000000
	s_addc_u32 s63, s63, 0
	s_mov_b32 s68, 0
	s_branch .Lwp1_isel_done_m
.Lwp1_isel_m_5:
	s_cmp_lt_u32 s60, 4704
	s_cbranch_scc0 .Lwp1_isel_m_6
	v_readlane_b32 s62, v245, 26
	v_readlane_b32 s63, v245, 27
	s_sub_u32 s65, s60, 3296
	s_mov_b32 s64, 0x5800
	s_mul_hi_u32 s66, s65, 0x5d1745e
	s_mul_i32 s69, s66, 44
	s_sub_u32 s67, s65, s69
	s_add_u32 s62, s62, 0x2c00000
	s_addc_u32 s63, s63, 0
	s_mov_b32 s68, 0
	s_branch .Lwp1_isel_done_m
.Lwp1_isel_m_6:
	s_cmp_lt_u32 s60, 6112
	s_cbranch_scc0 .Lwp1_isel_m_7
	v_readlane_b32 s62, v245, 28
	v_readlane_b32 s63, v245, 29
	s_sub_u32 s65, s60, 4704
	s_mov_b32 s64, 0x5800
	s_mul_hi_u32 s66, s65, 0x5d1745e
	s_mul_i32 s69, s66, 44
	s_sub_u32 s67, s65, s69
	s_add_u32 s62, s62, 0x2c00000
	s_addc_u32 s63, s63, 0
	s_mov_b32 s68, 0
	s_branch .Lwp1_isel_done_m
.Lwp1_isel_m_7:
	v_readlane_b32 s62, v245, 30
	v_readlane_b32 s63, v245, 31
	s_sub_u32 s65, s60, 6112
	s_mov_b32 s64, 0x2000
	s_lshr_b32 s66, s65, 4
	s_mul_i32 s69, s66, 16
	s_sub_u32 s67, s65, s69
	s_add_u32 s62, s62, 0x2c00000
	s_addc_u32 s63, s63, 0
	s_mov_b32 s68, 0

.LBB0_866:
.LBB0_905:
	v_lshl_add_u32 v4, s14, 9, v78
	s_movk_i32 s0, 0x2400
	v_cmp_gt_i32_e32 vcc, s0, v4
	s_waitcnt vmcnt(0)
	s_barrier
	s_and_saveexec_b64 s[2:3], vcc
	s_cbranch_execz .LBB0_910
	v_readlane_b32 s16, v245, 0
	v_readlane_b32 s18, v245, 2
	v_readlane_b32 s19, v245, 3
	s_lshl_b64 s[0:1], s[4:5], 2
	s_mov_b64 s[10:11], s[18:19]
	s_add_u32 s10, s10, s0
	s_addc_u32 s11, s11, s1
	s_lshl_b32 s16, s13, 9
	s_add_u32 s0, s86, s4
	v_readlane_b32 s17, v245, 1
	v_ashrrev_i32_e32 v5, 31, v4
	s_addc_u32 s1, s87, s5
	v_readlane_b32 s20, v245, 4
	v_readlane_b32 s21, v245, 5
	v_lshl_add_u64 v[0:1], v[4:5], 2, s[0:1]
	s_mov_b64 s[0:1], 0x219b3600
	s_ashr_i32 s17, s16, 31
	v_lshl_add_u64 v[0:1], v[0:1], 0, s[0:1]
	s_lshl_b64 s[18:19], s[16:17], 2
	s_mov_b64 s[20:21], 0
	s_movk_i32 s0, 0x1800
	v_mov_b32_e32 v3, 0
	s_movk_i32 s1, 0x23ff
	v_mov_b32_e32 v2, v4
	v_readlane_b32 s22, v245, 6
	v_readlane_b32 s23, v245, 7
	v_readlane_b32 s24, v245, 8
	v_readlane_b32 s25, v245, 9
	v_readlane_b32 s26, v245, 10
	v_readlane_b32 s27, v245, 11
	v_readlane_b32 s28, v245, 12
	v_readlane_b32 s29, v245, 13
	v_readlane_b32 s30, v245, 14
	v_readlane_b32 s31, v245, 15
	s_branch .LBB0_908

.LBB0_956:
	ds_read_b128 v[128:131], v154
	ds_read_b128 v[132:135], v154 offset:1024
	ds_read_b128 v[136:139], v154 offset:2048
	ds_read_b128 v[140:143], v154 offset:3072
	s_add_u32 s44, s40, 0xfff80080
	s_addc_u32 s45, s41, -1
	s_cmp_eq_u32 s43, 28
	s_cselect_b32 s45, s29, s45
	s_cselect_b32 s44, s28, s44
	s_cselect_b32 s47, s35, s42
	s_cselect_b32 s46, s34, s2
	v_lshl_add_u64 v[150:151], s[40:41], 0, v[148:149]
	s_add_i32 m0, s37, 0xc000
	ds_read_b128 v[158:161], v155
	ds_read_b128 v[162:165], v155 offset:1024
	ds_read_b128 v[166:169], v155 offset:2048
	ds_read_b128 v[170:173], v155 offset:3072
	ds_read_b128 v[174:177], v155 offset:4096
	ds_read_b128 v[178:181], v155 offset:5120
	ds_read_b128 v[182:185], v155 offset:6144
	ds_read_b128 v[186:189], v155 offset:7168
	global_load_lds_dwordx4 v[150:151], off
	v_lshl_add_u64 v[150:151], v[150:151], 0, s[6:7]
	s_add_i32 m0, s37, 0xe000
	s_nop 0
	global_load_lds_dwordx4 v[150:151], off
	s_waitcnt lgkmcnt(8)
	s_barrier
	s_waitcnt lgkmcnt(0)
	s_waitcnt lgkmcnt(0)
	v_mfma_f32_16x16x32_bf16 v[124:127], v[128:131], v[158:161], v[124:127]
	v_mfma_f32_16x16x32_bf16 v[120:123], v[136:139], v[158:161], v[120:123]
	v_mfma_f32_16x16x32_bf16 v[116:119], v[128:131], v[166:169], v[116:119]
	v_mfma_f32_16x16x32_bf16 v[112:115], v[136:139], v[166:169], v[112:115]
	v_mfma_f32_16x16x32_bf16 v[108:111], v[128:131], v[174:177], v[108:111]
	v_mfma_f32_16x16x32_bf16 v[100:103], v[136:139], v[174:177], v[100:103]
	v_mfma_f32_16x16x32_bf16 v[92:95], v[128:131], v[182:185], v[92:95]
	v_mfma_f32_16x16x32_bf16 v[80:83], v[136:139], v[182:185], v[80:83]
	v_mfma_f32_16x16x32_bf16 v[124:127], v[132:135], v[162:165], v[124:127]
	v_mfma_f32_16x16x32_bf16 v[120:123], v[140:143], v[162:165], v[120:123]
	v_mfma_f32_16x16x32_bf16 v[116:119], v[132:135], v[170:173], v[116:119]
	v_mfma_f32_16x16x32_bf16 v[112:115], v[140:143], v[170:173], v[112:115]
	v_mfma_f32_16x16x32_bf16 v[108:111], v[132:135], v[178:181], v[108:111]
	v_mfma_f32_16x16x32_bf16 v[100:103], v[140:143], v[178:181], v[100:103]
	v_mfma_f32_16x16x32_bf16 v[92:95], v[132:135], v[186:189], v[92:95]
	v_mfma_f32_16x16x32_bf16 v[80:83], v[140:143], v[186:189], v[80:83]
	s_barrier
	v_lshl_add_u64 v[150:151], s[46:47], 0, v[146:147]
	s_add_i32 s46, s54, s33
	s_mov_b32 m0, s46
	ds_read_b128 v[190:193], v156
	ds_read_b128 v[194:197], v156 offset:1024
	ds_read_b128 v[198:201], v156 offset:2048
	ds_read_b128 v[202:205], v156 offset:3072
	global_load_lds_dwordx4 v[150:151], off
	v_lshl_add_u64 v[206:207], v[150:151], 0, s[6:7]
	s_add_i32 m0, s46, 0x2000
	s_nop 0
	global_load_lds_dwordx4 v[206:207], off
	s_barrier
	s_waitcnt lgkmcnt(0)
	s_waitcnt lgkmcnt(0)
	v_mfma_f32_16x16x32_bf16 v[104:107], v[190:193], v[158:161], v[104:107]
	v_mfma_f32_16x16x32_bf16 v[96:99], v[198:201], v[158:161], v[96:99]
	v_mfma_f32_16x16x32_bf16 v[88:91], v[190:193], v[166:169], v[88:91]
	v_mfma_f32_16x16x32_bf16 v[84:87], v[198:201], v[166:169], v[84:87]
	v_mfma_f32_16x16x32_bf16 v[76:79], v[190:193], v[174:177], v[76:79]
	v_mfma_f32_16x16x32_bf16 v[72:75], v[198:201], v[174:177], v[72:75]
	v_mfma_f32_16x16x32_bf16 v[68:71], v[190:193], v[182:185], v[68:71]
	v_mfma_f32_16x16x32_bf16 v[64:67], v[198:201], v[182:185], v[64:67]
	v_mfma_f32_16x16x32_bf16 v[104:107], v[194:197], v[162:165], v[104:107]
	v_mfma_f32_16x16x32_bf16 v[96:99], v[202:205], v[162:165], v[96:99]
	v_mfma_f32_16x16x32_bf16 v[88:91], v[194:197], v[170:173], v[88:91]
	v_mfma_f32_16x16x32_bf16 v[84:87], v[202:205], v[170:173], v[84:87]
	v_mfma_f32_16x16x32_bf16 v[76:79], v[194:197], v[178:181], v[76:79]
	v_mfma_f32_16x16x32_bf16 v[72:75], v[202:205], v[178:181], v[72:75]
	v_mfma_f32_16x16x32_bf16 v[68:71], v[194:197], v[186:189], v[68:71]
	v_mfma_f32_16x16x32_bf16 v[64:67], v[202:205], v[186:189], v[64:67]
	s_mov_b32 m0, s37
	v_lshl_add_u64 v[206:207], s[44:45], 0, v[144:145]
	s_barrier
	ds_read_b128 v[158:161], v155 offset:16384
	ds_read_b128 v[162:165], v155 offset:17408
	ds_read_b128 v[166:169], v155 offset:18432
	ds_read_b128 v[170:173], v155 offset:19456
	ds_read_b128 v[174:177], v155 offset:20480
	ds_read_b128 v[178:181], v155 offset:21504
	ds_read_b128 v[182:185], v155 offset:22528
	ds_read_b128 v[186:189], v155 offset:23552
	global_load_lds_dwordx4 v[206:207], off
	v_lshl_add_u64 v[208:209], v[206:207], 0, s[6:7]
	s_mov_b32 m0, s39
	s_nop 0
	global_load_lds_dwordx4 v[208:209], off
	s_barrier
	s_waitcnt lgkmcnt(0)
	s_waitcnt lgkmcnt(0)
	v_mfma_f32_16x16x32_bf16 v[60:63], v[128:131], v[158:161], v[60:63]
	v_mfma_f32_16x16x32_bf16 v[56:59], v[136:139], v[158:161], v[56:59]
	v_mfma_f32_16x16x32_bf16 v[48:51], v[128:131], v[166:169], v[48:51]
	v_mfma_f32_16x16x32_bf16 v[40:43], v[136:139], v[166:169], v[40:43]
	v_mfma_f32_16x16x32_bf16 v[32:35], v[128:131], v[174:177], v[32:35]
	v_mfma_f32_16x16x32_bf16 v[24:27], v[136:139], v[174:177], v[24:27]
	v_mfma_f32_16x16x32_bf16 v[16:19], v[128:131], v[182:185], v[16:19]
	v_mfma_f32_16x16x32_bf16 v[8:11], v[136:139], v[182:185], v[8:11]
	v_mfma_f32_16x16x32_bf16 v[60:63], v[132:135], v[162:165], v[60:63]
	v_mfma_f32_16x16x32_bf16 v[56:59], v[140:143], v[162:165], v[56:59]
	v_mfma_f32_16x16x32_bf16 v[48:51], v[132:135], v[170:173], v[48:51]
	v_mfma_f32_16x16x32_bf16 v[40:43], v[140:143], v[170:173], v[40:43]
	v_mfma_f32_16x16x32_bf16 v[32:35], v[132:135], v[178:181], v[32:35]
	v_mfma_f32_16x16x32_bf16 v[24:27], v[140:143], v[178:181], v[24:27]
	v_mfma_f32_16x16x32_bf16 v[16:19], v[132:135], v[186:189], v[16:19]
	v_mfma_f32_16x16x32_bf16 v[8:11], v[140:143], v[186:189], v[8:11]
	s_barrier
	s_add_i32 s44, s55, s33
	v_lshl_add_u64 v[128:129], v[150:151], 0, s[8:9]
	s_mov_b32 m0, s44
	s_nop 0
	global_load_lds_dwordx4 v[128:129], off
	v_lshl_add_u64 v[128:129], v[150:151], 0, s[10:11]
	s_add_i32 m0, s44, 0x2000
	s_nop 0
	global_load_lds_dwordx4 v[128:129], off
	s_waitcnt vmcnt(6)
	s_barrier
	v_mfma_f32_16x16x32_bf16 v[52:55], v[190:193], v[158:161], v[52:55]
	v_mfma_f32_16x16x32_bf16 v[44:47], v[198:201], v[158:161], v[44:47]
	v_mfma_f32_16x16x32_bf16 v[36:39], v[190:193], v[166:169], v[36:39]
	v_mfma_f32_16x16x32_bf16 v[28:31], v[198:201], v[166:169], v[28:31]
	v_mfma_f32_16x16x32_bf16 v[20:23], v[190:193], v[174:177], v[20:23]
	v_mfma_f32_16x16x32_bf16 v[12:15], v[198:201], v[174:177], v[12:15]
	v_mfma_f32_16x16x32_bf16 v[4:7], v[190:193], v[182:185], v[4:7]
	v_mfma_f32_16x16x32_bf16 v[0:3], v[198:201], v[182:185], v[0:3]
	v_mfma_f32_16x16x32_bf16 v[52:55], v[194:197], v[162:165], v[52:55]
	v_mfma_f32_16x16x32_bf16 v[44:47], v[202:205], v[162:165], v[44:47]
	v_mfma_f32_16x16x32_bf16 v[36:39], v[194:197], v[170:173], v[36:39]
	v_mfma_f32_16x16x32_bf16 v[28:31], v[202:205], v[170:173], v[28:31]
	v_mfma_f32_16x16x32_bf16 v[20:23], v[194:197], v[178:181], v[20:23]
	v_mfma_f32_16x16x32_bf16 v[12:15], v[202:205], v[178:181], v[12:15]
	v_mfma_f32_16x16x32_bf16 v[4:7], v[194:197], v[186:189], v[4:7]
	v_mfma_f32_16x16x32_bf16 v[0:3], v[202:205], v[186:189], v[0:3]
	s_add_i32 s44, 0, 0x18000
	v_add_u32_e32 v140, s44, v153
	s_barrier
	ds_read_b128 v[128:131], v140
	ds_read_b128 v[132:135], v140 offset:1024
	ds_read_b128 v[136:139], v140 offset:2048
	ds_read_b128 v[140:143], v140 offset:3072
	s_mov_b32 m0, s48
	v_lshl_add_u64 v[190:191], v[206:207], 0, s[8:9]
	ds_read_b128 v[158:161], v155 offset:32768
	ds_read_b128 v[162:165], v155 offset:33792
	ds_read_b128 v[166:169], v155 offset:34816
	ds_read_b128 v[170:173], v155 offset:35840
	ds_read_b128 v[174:177], v155 offset:36864
	ds_read_b128 v[178:181], v155 offset:37888
	ds_read_b128 v[182:185], v155 offset:38912
	ds_read_b128 v[186:189], v155 offset:39936
	global_load_lds_dwordx4 v[190:191], off
	v_lshl_add_u64 v[190:191], v[206:207], 0, s[10:11]
	s_mov_b32 m0, s49
	s_nop 0
	global_load_lds_dwordx4 v[190:191], off
	s_waitcnt lgkmcnt(8)
	s_barrier
	s_waitcnt lgkmcnt(0)
	s_waitcnt lgkmcnt(0)
	v_mfma_f32_16x16x32_bf16 v[124:127], v[128:131], v[158:161], v[124:127]
	v_mfma_f32_16x16x32_bf16 v[120:123], v[136:139], v[158:161], v[120:123]
	v_mfma_f32_16x16x32_bf16 v[116:119], v[128:131], v[166:169], v[116:119]
	v_mfma_f32_16x16x32_bf16 v[112:115], v[136:139], v[166:169], v[112:115]
	v_mfma_f32_16x16x32_bf16 v[108:111], v[128:131], v[174:177], v[108:111]
	v_mfma_f32_16x16x32_bf16 v[100:103], v[136:139], v[174:177], v[100:103]
	v_mfma_f32_16x16x32_bf16 v[92:95], v[128:131], v[182:185], v[92:95]
	v_mfma_f32_16x16x32_bf16 v[80:83], v[136:139], v[182:185], v[80:83]
	v_mfma_f32_16x16x32_bf16 v[124:127], v[132:135], v[162:165], v[124:127]
	v_mfma_f32_16x16x32_bf16 v[120:123], v[140:143], v[162:165], v[120:123]
	v_mfma_f32_16x16x32_bf16 v[116:119], v[132:135], v[170:173], v[116:119]
	v_mfma_f32_16x16x32_bf16 v[112:115], v[140:143], v[170:173], v[112:115]
	v_mfma_f32_16x16x32_bf16 v[108:111], v[132:135], v[178:181], v[108:111]
	v_mfma_f32_16x16x32_bf16 v[100:103], v[140:143], v[178:181], v[100:103]
	v_mfma_f32_16x16x32_bf16 v[92:95], v[132:135], v[186:189], v[92:95]
	v_mfma_f32_16x16x32_bf16 v[80:83], v[140:143], v[186:189], v[80:83]
	s_barrier
	s_add_i32 s45, 0, 0x1c000
	s_add_i32 s44, s44, s33
	v_add_u32_e32 v157, s45, v153
	v_lshl_add_u64 v[208:209], v[150:151], 0, s[20:21]
	s_mov_b32 m0, s44
	ds_read_b128 v[190:193], v157
	ds_read_b128 v[194:197], v157 offset:1024
	ds_read_b128 v[198:201], v157 offset:2048
	ds_read_b128 v[202:205], v157 offset:3072
	global_load_lds_dwordx4 v[208:209], off
	v_lshl_add_u64 v[208:209], v[150:151], 0, s[22:23]
	s_add_i32 m0, s44, 0x2000
	s_nop 0
	global_load_lds_dwordx4 v[208:209], off
	s_barrier
	s_waitcnt lgkmcnt(0)
	s_waitcnt lgkmcnt(0)
	v_mfma_f32_16x16x32_bf16 v[104:107], v[190:193], v[158:161], v[104:107]
	v_mfma_f32_16x16x32_bf16 v[96:99], v[198:201], v[158:161], v[96:99]
	v_mfma_f32_16x16x32_bf16 v[88:91], v[190:193], v[166:169], v[88:91]
	v_mfma_f32_16x16x32_bf16 v[84:87], v[198:201], v[166:169], v[84:87]
	v_mfma_f32_16x16x32_bf16 v[76:79], v[190:193], v[174:177], v[76:79]
	v_mfma_f32_16x16x32_bf16 v[72:75], v[198:201], v[174:177], v[72:75]
	v_mfma_f32_16x16x32_bf16 v[68:71], v[190:193], v[182:185], v[68:71]
	v_mfma_f32_16x16x32_bf16 v[64:67], v[198:201], v[182:185], v[64:67]
	v_mfma_f32_16x16x32_bf16 v[104:107], v[194:197], v[162:165], v[104:107]
	v_mfma_f32_16x16x32_bf16 v[96:99], v[202:205], v[162:165], v[96:99]
	v_mfma_f32_16x16x32_bf16 v[88:91], v[194:197], v[170:173], v[88:91]
	v_mfma_f32_16x16x32_bf16 v[84:87], v[202:205], v[170:173], v[84:87]
	v_mfma_f32_16x16x32_bf16 v[76:79], v[194:197], v[178:181], v[76:79]
	v_mfma_f32_16x16x32_bf16 v[72:75], v[202:205], v[178:181], v[72:75]
	v_mfma_f32_16x16x32_bf16 v[68:71], v[194:197], v[186:189], v[68:71]
	v_mfma_f32_16x16x32_bf16 v[64:67], v[202:205], v[186:189], v[64:67]
	s_mov_b32 m0, s50
	v_lshl_add_u64 v[208:209], v[206:207], 0, s[20:21]
	s_barrier
	ds_read_b128 v[158:161], v155 offset:49152
	ds_read_b128 v[162:165], v155 offset:50176
	ds_read_b128 v[166:169], v155 offset:51200
	ds_read_b128 v[170:173], v155 offset:52224
	ds_read_b128 v[174:177], v155 offset:53248
	ds_read_b128 v[178:181], v155 offset:54272
	ds_read_b128 v[182:185], v155 offset:55296
	ds_read_b128 v[186:189], v155 offset:56320
	global_load_lds_dwordx4 v[208:209], off
	v_lshl_add_u64 v[206:207], v[206:207], 0, s[22:23]
	s_mov_b32 m0, s51
	s_nop 0
	global_load_lds_dwordx4 v[206:207], off
	s_barrier
	s_waitcnt lgkmcnt(0)
	s_waitcnt lgkmcnt(0)
	v_mfma_f32_16x16x32_bf16 v[60:63], v[128:131], v[158:161], v[60:63]
	v_mfma_f32_16x16x32_bf16 v[56:59], v[136:139], v[158:161], v[56:59]
	v_mfma_f32_16x16x32_bf16 v[48:51], v[128:131], v[166:169], v[48:51]
	v_mfma_f32_16x16x32_bf16 v[40:43], v[136:139], v[166:169], v[40:43]
	v_mfma_f32_16x16x32_bf16 v[32:35], v[128:131], v[174:177], v[32:35]
	v_mfma_f32_16x16x32_bf16 v[24:27], v[136:139], v[174:177], v[24:27]
	v_mfma_f32_16x16x32_bf16 v[16:19], v[128:131], v[182:185], v[16:19]
	v_mfma_f32_16x16x32_bf16 v[8:11], v[136:139], v[182:185], v[8:11]
	v_mfma_f32_16x16x32_bf16 v[60:63], v[132:135], v[162:165], v[60:63]
	v_mfma_f32_16x16x32_bf16 v[56:59], v[140:143], v[162:165], v[56:59]
	v_mfma_f32_16x16x32_bf16 v[48:51], v[132:135], v[170:173], v[48:51]
	v_mfma_f32_16x16x32_bf16 v[40:43], v[140:143], v[170:173], v[40:43]
	v_mfma_f32_16x16x32_bf16 v[32:35], v[132:135], v[178:181], v[32:35]
	v_mfma_f32_16x16x32_bf16 v[24:27], v[140:143], v[178:181], v[24:27]
	v_mfma_f32_16x16x32_bf16 v[16:19], v[132:135], v[186:189], v[16:19]
	v_mfma_f32_16x16x32_bf16 v[8:11], v[140:143], v[186:189], v[8:11]
	s_barrier
	s_add_i32 s44, s45, s33
	v_lshl_add_u64 v[128:129], v[150:151], 0, s[24:25]
	s_mov_b32 m0, s44
	s_nop 0
	global_load_lds_dwordx4 v[128:129], off
	v_lshl_add_u64 v[128:129], v[150:151], 0, s[26:27]
	s_add_i32 m0, s44, 0x2000
	s_nop 0
	global_load_lds_dwordx4 v[128:129], off
	s_waitcnt vmcnt(6)
	s_barrier
	v_mfma_f32_16x16x32_bf16 v[52:55], v[190:193], v[158:161], v[52:55]
	v_mfma_f32_16x16x32_bf16 v[44:47], v[198:201], v[158:161], v[44:47]
	v_mfma_f32_16x16x32_bf16 v[36:39], v[190:193], v[166:169], v[36:39]
	v_mfma_f32_16x16x32_bf16 v[28:31], v[198:201], v[166:169], v[28:31]
	v_mfma_f32_16x16x32_bf16 v[20:23], v[190:193], v[174:177], v[20:23]
	v_mfma_f32_16x16x32_bf16 v[12:15], v[198:201], v[174:177], v[12:15]
	v_mfma_f32_16x16x32_bf16 v[4:7], v[190:193], v[182:185], v[4:7]
	v_mfma_f32_16x16x32_bf16 v[0:3], v[198:201], v[182:185], v[0:3]
	v_mfma_f32_16x16x32_bf16 v[52:55], v[194:197], v[162:165], v[52:55]
	v_mfma_f32_16x16x32_bf16 v[44:47], v[202:205], v[162:165], v[44:47]
	v_mfma_f32_16x16x32_bf16 v[36:39], v[194:197], v[170:173], v[36:39]
	v_mfma_f32_16x16x32_bf16 v[28:31], v[202:205], v[170:173], v[28:31]
	v_mfma_f32_16x16x32_bf16 v[20:23], v[194:197], v[178:181], v[20:23]
	v_mfma_f32_16x16x32_bf16 v[12:15], v[202:205], v[178:181], v[12:15]
	v_mfma_f32_16x16x32_bf16 v[4:7], v[194:197], v[186:189], v[4:7]
	v_mfma_f32_16x16x32_bf16 v[0:3], v[202:205], v[186:189], v[0:3]
	s_add_i32 s43, s43, 2
	s_add_u32 s40, s40, 0x100
	s_addc_u32 s41, s41, 0
	s_add_u32 s2, s2, 0x100
	s_addc_u32 s42, s42, 0
	s_cmp_gt_u32 s43, 29
	s_barrier
	s_cbranch_scc0 .LBB0_956
	v_mov_b32_e32 v157, v152
	s_mov_b32 s2, s52
	s_mov_b32 s40, s31
	s_lshl_b32 s38, s38, 8
	s_lshl_b32 s2, s2, 5
	s_add_i32 s2, s2, s38
	v_lshrrev_b32_e32 v128, 1, v157
	v_and_or_b32 v150, v128, 24, s2
	v_ashrrev_i32_e32 v151, 31, v150
	v_lshl_add_u64 v[128:129], v[150:151], 2, s[18:19]
	global_load_dwordx4 v[140:143], v[128:129], off
	global_load_dwordx4 v[136:139], v[128:129], off offset:16
	global_load_dwordx4 v[132:135], v[128:129], off offset:512
	s_nop 0
	global_load_dwordx4 v[128:131], v[128:129], off offset:528
	s_lshl_b32 s2, s36, 8
	v_and_or_b32 v157, v157, 15, s2
	v_lshl_add_u32 v157, s40, 6, v157
	v_lshl_add_u64 v[150:151], v[150:151], 1, s[16:17]
	v_mad_i64_i32 v[158:159], s[40:41], v157, s56, v[150:151]
	v_or_b32_e32 v160, 16, v157
	v_mad_i64_i32 v[160:161], s[40:41], v160, s56, v[150:151]
	v_or_b32_e32 v162, 32, v157
	v_mad_i64_i32 v[162:163], s[40:41], v162, s56, v[150:151]
	v_or_b32_e32 v164, 48, v157
	v_mad_i64_i32 v[164:165], s[40:41], v164, s56, v[150:151]
	s_mov_b32 s2, s57
	s_waitcnt vmcnt(0)
	v_pk_add_f32 v[126:127], v[126:127], v[142:143]
	v_pk_add_f32 v[124:125], v[124:125], v[140:141]
	v_pk_add_f32 v[168:169], v[68:69], v[132:133]
	v_cvt_pk_bf16_f32 v68, v124, v125
	v_cvt_pk_bf16_f32 v69, v126, v127
	v_pk_add_f32 v[122:123], v[122:123], v[138:139]
	v_pk_add_f32 v[120:121], v[120:121], v[136:137]
	v_pk_add_f32 v[106:107], v[106:107], v[134:135]
	v_pk_add_f32 v[104:105], v[104:105], v[132:133]
	v_pk_add_f32 v[166:167], v[70:71], v[134:135]
	v_cvt_pk_bf16_f32 v70, v120, v121
	v_cvt_pk_bf16_f32 v71, v122, v123
	global_store_dwordx4 v[158:159], v[68:71], off
	v_pk_add_f32 v[98:99], v[98:99], v[130:131]
	v_pk_add_f32 v[96:97], v[96:97], v[128:129]
	v_cvt_pk_bf16_f32 v68, v104, v105
	v_cvt_pk_bf16_f32 v69, v106, v107
	v_pk_add_f32 v[118:119], v[118:119], v[142:143]
	v_pk_add_f32 v[116:117], v[116:117], v[140:141]
	v_cvt_pk_bf16_f32 v70, v96, v97
	v_cvt_pk_bf16_f32 v71, v98, v99
	global_store_dwordx4 v[158:159], v[68:71], off offset:256
	v_pk_add_f32 v[114:115], v[114:115], v[138:139]
	v_pk_add_f32 v[112:113], v[112:113], v[136:137]
	v_cvt_pk_bf16_f32 v68, v116, v117
	v_cvt_pk_bf16_f32 v69, v118, v119
	v_pk_add_f32 v[90:91], v[90:91], v[134:135]
	v_pk_add_f32 v[88:89], v[88:89], v[132:133]
	v_cvt_pk_bf16_f32 v70, v112, v113
	v_cvt_pk_bf16_f32 v71, v114, v115
	global_store_dwordx4 v[160:161], v[68:71], off
	v_pk_add_f32 v[86:87], v[86:87], v[130:131]
	v_pk_add_f32 v[84:85], v[84:85], v[128:129]
	v_cvt_pk_bf16_f32 v68, v88, v89
	v_cvt_pk_bf16_f32 v69, v90, v91
	v_pk_add_f32 v[110:111], v[110:111], v[142:143]
	v_pk_add_f32 v[108:109], v[108:109], v[140:141]
	v_cvt_pk_bf16_f32 v70, v84, v85
	v_cvt_pk_bf16_f32 v71, v86, v87
	global_store_dwordx4 v[160:161], v[68:71], off offset:256
	v_pk_add_f32 v[102:103], v[102:103], v[138:139]
	v_pk_add_f32 v[100:101], v[100:101], v[136:137]
	v_cvt_pk_bf16_f32 v68, v108, v109
	v_cvt_pk_bf16_f32 v69, v110, v111
	v_pk_add_f32 v[78:79], v[78:79], v[134:135]
	v_pk_add_f32 v[76:77], v[76:77], v[132:133]
	v_cvt_pk_bf16_f32 v70, v100, v101
	v_cvt_pk_bf16_f32 v71, v102, v103
	global_store_dwordx4 v[162:163], v[68:71], off
	v_pk_add_f32 v[74:75], v[74:75], v[130:131]
	v_pk_add_f32 v[72:73], v[72:73], v[128:129]
	v_cvt_pk_bf16_f32 v68, v76, v77
	v_cvt_pk_bf16_f32 v69, v78, v79
	v_pk_add_f32 v[94:95], v[94:95], v[142:143]
	v_pk_add_f32 v[92:93], v[92:93], v[140:141]
	v_cvt_pk_bf16_f32 v70, v72, v73
	v_cvt_pk_bf16_f32 v71, v74, v75
	global_store_dwordx4 v[162:163], v[68:71], off offset:256
	v_pk_add_f32 v[82:83], v[82:83], v[138:139]
	v_pk_add_f32 v[80:81], v[80:81], v[136:137]
	v_cvt_pk_bf16_f32 v68, v92, v93
	v_cvt_pk_bf16_f32 v69, v94, v95
	v_pk_add_f32 v[62:63], v[62:63], v[142:143]
	v_cvt_pk_bf16_f32 v70, v80, v81
	v_cvt_pk_bf16_f32 v71, v82, v83
	global_store_dwordx4 v[164:165], v[68:71], off
	v_pk_add_f32 v[60:61], v[60:61], v[140:141]
	v_pk_add_f32 v[52:53], v[52:53], v[132:133]
	v_pk_add_f32 v[68:69], v[66:67], v[130:131]
	v_pk_add_f32 v[66:67], v[64:65], v[128:129]
	v_cvt_pk_bf16_f32 v64, v168, v169
	v_cvt_pk_bf16_f32 v65, v166, v167
	v_pk_add_f32 v[54:55], v[54:55], v[134:135]
	v_cvt_pk_bf16_f32 v66, v66, v67
	v_cvt_pk_bf16_f32 v67, v68, v69
	global_store_dwordx4 v[164:165], v[64:67], off offset:256
	v_pk_add_f32 v[48:49], v[48:49], v[140:141]
	v_pk_add_f32 v[36:37], v[36:37], v[132:133]
	v_add_u32_e32 v64, 0x80, v157
	v_mad_i64_i32 v[64:65], s[40:41], v64, s56, v[150:151]
	v_pk_add_f32 v[66:67], v[58:59], v[138:139]
	v_pk_add_f32 v[58:59], v[56:57], v[136:137]
	v_cvt_pk_bf16_f32 v56, v60, v61
	v_cvt_pk_bf16_f32 v57, v62, v63
	v_pk_add_f32 v[38:39], v[38:39], v[134:135]
	v_cvt_pk_bf16_f32 v58, v58, v59
	v_cvt_pk_bf16_f32 v59, v66, v67
	global_store_dwordx4 v[64:65], v[56:59], off
	v_pk_add_f32 v[32:33], v[32:33], v[140:141]
	v_pk_add_f32 v[20:21], v[20:21], v[132:133]
	v_pk_add_f32 v[56:57], v[46:47], v[130:131]
	v_pk_add_f32 v[46:47], v[44:45], v[128:129]
	v_cvt_pk_bf16_f32 v44, v52, v53
	v_cvt_pk_bf16_f32 v45, v54, v55
	v_pk_add_f32 v[22:23], v[22:23], v[134:135]
	v_cvt_pk_bf16_f32 v46, v46, v47
	v_cvt_pk_bf16_f32 v47, v56, v57
	global_store_dwordx4 v[64:65], v[44:47], off offset:256
	v_pk_add_f32 v[16:17], v[16:17], v[140:141]
	v_pk_add_f32 v[6:7], v[6:7], v[134:135]
	v_add_u32_e32 v44, 0x90, v157
	v_mad_i64_i32 v[44:45], s[40:41], v44, s56, v[150:151]
	v_pk_add_f32 v[46:47], v[50:51], v[142:143]
	v_pk_add_f32 v[50:51], v[42:43], v[138:139]
	v_pk_add_f32 v[42:43], v[40:41], v[136:137]
	v_cvt_pk_bf16_f32 v40, v48, v49
	v_cvt_pk_bf16_f32 v41, v46, v47
	v_pk_add_f32 v[4:5], v[4:5], v[132:133]
	v_cvt_pk_bf16_f32 v42, v42, v43
	v_cvt_pk_bf16_f32 v43, v50, v51
	global_store_dwordx4 v[44:45], v[40:43], off
	s_nop 1
	v_pk_add_f32 v[40:41], v[30:31], v[130:131]
	v_pk_add_f32 v[30:31], v[28:29], v[128:129]
	v_cvt_pk_bf16_f32 v28, v36, v37
	v_cvt_pk_bf16_f32 v29, v38, v39
	s_nop 0
	v_cvt_pk_bf16_f32 v30, v30, v31
	v_cvt_pk_bf16_f32 v31, v40, v41
	global_store_dwordx4 v[44:45], v[28:31], off offset:256
	s_nop 1
	v_add_u32_e32 v28, 0xa0, v157
	v_mad_i64_i32 v[28:29], s[40:41], v28, s56, v[150:151]
	v_pk_add_f32 v[30:31], v[34:35], v[142:143]
	v_pk_add_f32 v[34:35], v[26:27], v[138:139]
	v_pk_add_f32 v[26:27], v[24:25], v[136:137]
	v_cvt_pk_bf16_f32 v24, v32, v33
	v_cvt_pk_bf16_f32 v25, v30, v31
	s_nop 0
	v_cvt_pk_bf16_f32 v26, v26, v27
	v_cvt_pk_bf16_f32 v27, v34, v35
	global_store_dwordx4 v[28:29], v[24:27], off
	s_nop 1
	v_pk_add_f32 v[24:25], v[14:15], v[130:131]
	v_pk_add_f32 v[14:15], v[12:13], v[128:129]
	v_cvt_pk_bf16_f32 v12, v20, v21
	v_cvt_pk_bf16_f32 v13, v22, v23
	s_nop 0
	v_cvt_pk_bf16_f32 v14, v14, v15
	v_cvt_pk_bf16_f32 v15, v24, v25
	global_store_dwordx4 v[28:29], v[12:15], off offset:256
	s_nop 1
	v_add_u32_e32 v12, 0xb0, v157
	v_mad_i64_i32 v[12:13], s[40:41], v12, s56, v[150:151]
	v_pk_add_f32 v[14:15], v[18:19], v[142:143]
	v_pk_add_f32 v[18:19], v[10:11], v[138:139]
	v_pk_add_f32 v[10:11], v[8:9], v[136:137]
	v_cvt_pk_bf16_f32 v8, v16, v17
	v_cvt_pk_bf16_f32 v9, v14, v15
	s_mov_b64 s[40:41], -1
	v_cvt_pk_bf16_f32 v10, v10, v11
	v_cvt_pk_bf16_f32 v11, v18, v19
	global_store_dwordx4 v[12:13], v[8:11], off
	s_nop 1
	v_pk_add_f32 v[8:9], v[2:3], v[130:131]
	v_pk_add_f32 v[2:3], v[0:1], v[128:129]
	v_cvt_pk_bf16_f32 v0, v4, v5
	v_cvt_pk_bf16_f32 v1, v6, v7
	s_nop 0
	v_cvt_pk_bf16_f32 v2, v2, v3
	v_cvt_pk_bf16_f32 v3, v8, v9
	global_store_dwordx4 v[12:13], v[0:3], off offset:256
	s_mul_i32 s2, s2, s0
	s_add_i32 s2, s2, s1
	s_cmpk_gt_i32 s2, 0x47f
	s_cbranch_scc0 .LBB0_961
	s_andn2_b64 vcc, exec, s[40:41]
	s_cbranch_vccnz .LBB0_962

.LBB0_987:
	ds_read_b128 v[142:145], v138
	ds_read_b128 v[146:149], v138 offset:1024
	ds_read_b128 v[150:153], v138 offset:2048
	ds_read_b128 v[154:157], v138 offset:3072
	s_add_u32 s53, s44, 0xffdc0080
	s_addc_u32 s64, s45, -1
	s_cmp_eq_u32 s52, 4
	s_cselect_b32 s65, s41, s64
	s_cselect_b32 s64, s40, s53
	s_cselect_b32 s67, s43, s47
	s_cselect_b32 s66, s42, s46
	v_lshl_add_u64 v[134:135], s[44:45], 0, v[132:133]
	s_add_i32 m0, s49, 0xc000
	ds_read_b128 v[158:161], v139
	ds_read_b128 v[162:165], v139 offset:1024
	ds_read_b128 v[166:169], v139 offset:2048
	ds_read_b128 v[170:173], v139 offset:3072
	ds_read_b128 v[174:177], v139 offset:4096
	ds_read_b128 v[178:181], v139 offset:5120
	ds_read_b128 v[182:185], v139 offset:6144
	ds_read_b128 v[186:189], v139 offset:7168
	global_load_lds_dwordx4 v[134:135], off
	v_lshl_add_u64 v[134:135], v[134:135], 0, s[10:11]
	s_add_i32 m0, s49, 0xe000
	s_nop 0
	global_load_lds_dwordx4 v[134:135], off
	s_waitcnt lgkmcnt(8)
	s_barrier
	s_waitcnt lgkmcnt(0)
	s_waitcnt lgkmcnt(0)
	v_mfma_f32_16x16x32_bf16 v[124:127], v[142:145], v[158:161], v[124:127]
	v_mfma_f32_16x16x32_bf16 v[120:123], v[150:153], v[158:161], v[120:123]
	v_mfma_f32_16x16x32_bf16 v[112:115], v[142:145], v[166:169], v[112:115]
	v_mfma_f32_16x16x32_bf16 v[104:107], v[150:153], v[166:169], v[104:107]
	v_mfma_f32_16x16x32_bf16 v[96:99], v[142:145], v[174:177], v[96:99]
	v_mfma_f32_16x16x32_bf16 v[88:91], v[150:153], v[174:177], v[88:91]
	v_mfma_f32_16x16x32_bf16 v[80:83], v[142:145], v[182:185], v[80:83]
	v_mfma_f32_16x16x32_bf16 v[72:75], v[150:153], v[182:185], v[72:75]
	v_mfma_f32_16x16x32_bf16 v[124:127], v[146:149], v[162:165], v[124:127]
	v_mfma_f32_16x16x32_bf16 v[120:123], v[154:157], v[162:165], v[120:123]
	v_mfma_f32_16x16x32_bf16 v[112:115], v[146:149], v[170:173], v[112:115]
	v_mfma_f32_16x16x32_bf16 v[104:107], v[154:157], v[170:173], v[104:107]
	v_mfma_f32_16x16x32_bf16 v[96:99], v[146:149], v[178:181], v[96:99]
	v_mfma_f32_16x16x32_bf16 v[88:91], v[154:157], v[178:181], v[88:91]
	v_mfma_f32_16x16x32_bf16 v[80:83], v[146:149], v[186:189], v[80:83]
	v_mfma_f32_16x16x32_bf16 v[72:75], v[154:157], v[186:189], v[72:75]
	s_barrier
	s_add_i32 s53, s59, s48
	v_lshl_add_u64 v[134:135], s[66:67], 0, v[128:129]
	s_mov_b32 m0, s53
	ds_read_b128 v[190:193], v140
	ds_read_b128 v[194:197], v140 offset:1024
	ds_read_b128 v[198:201], v140 offset:2048
	ds_read_b128 v[202:205], v140 offset:3072
	global_load_lds_dwordx4 v[134:135], off
	v_lshl_add_u64 v[206:207], v[134:135], 0, s[8:9]
	s_add_i32 m0, s53, 0x2000
	s_nop 0
	global_load_lds_dwordx4 v[206:207], off
	s_barrier
	s_waitcnt lgkmcnt(0)
	s_waitcnt lgkmcnt(0)
	v_mfma_f32_16x16x32_bf16 v[116:119], v[190:193], v[158:161], v[116:119]
	v_mfma_f32_16x16x32_bf16 v[108:111], v[198:201], v[158:161], v[108:111]
	v_mfma_f32_16x16x32_bf16 v[100:103], v[190:193], v[166:169], v[100:103]
	v_mfma_f32_16x16x32_bf16 v[92:95], v[198:201], v[166:169], v[92:95]
	v_mfma_f32_16x16x32_bf16 v[84:87], v[190:193], v[174:177], v[84:87]
	v_mfma_f32_16x16x32_bf16 v[76:79], v[198:201], v[174:177], v[76:79]
	v_mfma_f32_16x16x32_bf16 v[68:71], v[190:193], v[182:185], v[68:71]
	v_mfma_f32_16x16x32_bf16 v[64:67], v[198:201], v[182:185], v[64:67]
	v_mfma_f32_16x16x32_bf16 v[116:119], v[194:197], v[162:165], v[116:119]
	v_mfma_f32_16x16x32_bf16 v[108:111], v[202:205], v[162:165], v[108:111]
	v_mfma_f32_16x16x32_bf16 v[100:103], v[194:197], v[170:173], v[100:103]
	v_mfma_f32_16x16x32_bf16 v[92:95], v[202:205], v[170:173], v[92:95]
	v_mfma_f32_16x16x32_bf16 v[84:87], v[194:197], v[178:181], v[84:87]
	v_mfma_f32_16x16x32_bf16 v[76:79], v[202:205], v[178:181], v[76:79]
	v_mfma_f32_16x16x32_bf16 v[68:71], v[194:197], v[186:189], v[68:71]
	v_mfma_f32_16x16x32_bf16 v[64:67], v[202:205], v[186:189], v[64:67]
	s_mov_b32 m0, s49
	v_lshl_add_u64 v[206:207], s[64:65], 0, v[130:131]
	s_barrier
	ds_read_b128 v[158:161], v139 offset:16384
	ds_read_b128 v[162:165], v139 offset:17408
	ds_read_b128 v[166:169], v139 offset:18432
	ds_read_b128 v[170:173], v139 offset:19456
	ds_read_b128 v[174:177], v139 offset:20480
	ds_read_b128 v[178:181], v139 offset:21504
	ds_read_b128 v[182:185], v139 offset:22528
	ds_read_b128 v[186:189], v139 offset:23552
	global_load_lds_dwordx4 v[206:207], off
	v_lshl_add_u64 v[208:209], v[206:207], 0, s[10:11]
	s_mov_b32 m0, s50
	s_nop 0
	global_load_lds_dwordx4 v[208:209], off
	s_barrier
	s_waitcnt lgkmcnt(0)
	s_waitcnt lgkmcnt(0)
	v_mfma_f32_16x16x32_bf16 v[60:63], v[142:145], v[158:161], v[60:63]
	v_mfma_f32_16x16x32_bf16 v[56:59], v[150:153], v[158:161], v[56:59]
	v_mfma_f32_16x16x32_bf16 v[48:51], v[142:145], v[166:169], v[48:51]
	v_mfma_f32_16x16x32_bf16 v[40:43], v[150:153], v[166:169], v[40:43]
	v_mfma_f32_16x16x32_bf16 v[32:35], v[142:145], v[174:177], v[32:35]
	v_mfma_f32_16x16x32_bf16 v[24:27], v[150:153], v[174:177], v[24:27]
	v_mfma_f32_16x16x32_bf16 v[16:19], v[142:145], v[182:185], v[16:19]
	v_mfma_f32_16x16x32_bf16 v[8:11], v[150:153], v[182:185], v[8:11]
	v_mfma_f32_16x16x32_bf16 v[60:63], v[146:149], v[162:165], v[60:63]
	v_mfma_f32_16x16x32_bf16 v[56:59], v[154:157], v[162:165], v[56:59]
	v_mfma_f32_16x16x32_bf16 v[48:51], v[146:149], v[170:173], v[48:51]
	v_mfma_f32_16x16x32_bf16 v[40:43], v[154:157], v[170:173], v[40:43]
	v_mfma_f32_16x16x32_bf16 v[32:35], v[146:149], v[178:181], v[32:35]
	v_mfma_f32_16x16x32_bf16 v[24:27], v[154:157], v[178:181], v[24:27]
	v_mfma_f32_16x16x32_bf16 v[16:19], v[146:149], v[186:189], v[16:19]
	v_mfma_f32_16x16x32_bf16 v[8:11], v[154:157], v[186:189], v[8:11]
	s_barrier
	s_add_i32 s53, s60, s48
	v_lshl_add_u64 v[142:143], v[134:135], 0, s[16:17]
	s_mov_b32 m0, s53
	s_nop 0
	global_load_lds_dwordx4 v[142:143], off
	v_lshl_add_u64 v[142:143], v[134:135], 0, s[18:19]
	s_add_i32 m0, s53, 0x2000
	s_nop 0
	global_load_lds_dwordx4 v[142:143], off
	s_waitcnt vmcnt(6)
	s_barrier
	v_mfma_f32_16x16x32_bf16 v[52:55], v[190:193], v[158:161], v[52:55]
	v_mfma_f32_16x16x32_bf16 v[44:47], v[198:201], v[158:161], v[44:47]
	v_mfma_f32_16x16x32_bf16 v[36:39], v[190:193], v[166:169], v[36:39]
	v_mfma_f32_16x16x32_bf16 v[28:31], v[198:201], v[166:169], v[28:31]
	v_mfma_f32_16x16x32_bf16 v[20:23], v[190:193], v[174:177], v[20:23]
	v_mfma_f32_16x16x32_bf16 v[12:15], v[198:201], v[174:177], v[12:15]
	v_mfma_f32_16x16x32_bf16 v[4:7], v[190:193], v[182:185], v[4:7]
	v_mfma_f32_16x16x32_bf16 v[0:3], v[198:201], v[182:185], v[0:3]
	v_mfma_f32_16x16x32_bf16 v[52:55], v[194:197], v[162:165], v[52:55]
	v_mfma_f32_16x16x32_bf16 v[44:47], v[202:205], v[162:165], v[44:47]
	v_mfma_f32_16x16x32_bf16 v[36:39], v[194:197], v[170:173], v[36:39]
	v_mfma_f32_16x16x32_bf16 v[28:31], v[202:205], v[170:173], v[28:31]
	v_mfma_f32_16x16x32_bf16 v[20:23], v[194:197], v[178:181], v[20:23]
	v_mfma_f32_16x16x32_bf16 v[12:15], v[202:205], v[178:181], v[12:15]
	v_mfma_f32_16x16x32_bf16 v[4:7], v[194:197], v[186:189], v[4:7]
	v_mfma_f32_16x16x32_bf16 v[0:3], v[202:205], v[186:189], v[0:3]
	s_add_i32 s53, 0, 0x18000
	v_add_u32_e32 v141, s53, v137
	s_barrier
	ds_read_b128 v[142:145], v141
	ds_read_b128 v[146:149], v141 offset:1024
	ds_read_b128 v[150:153], v141 offset:2048
	ds_read_b128 v[154:157], v141 offset:3072
	s_mov_b32 m0, s51
	v_lshl_add_u64 v[190:191], v[206:207], 0, s[20:21]
	ds_read_b128 v[158:161], v139 offset:32768
	ds_read_b128 v[162:165], v139 offset:33792
	ds_read_b128 v[166:169], v139 offset:34816
	ds_read_b128 v[170:173], v139 offset:35840
	ds_read_b128 v[174:177], v139 offset:36864
	ds_read_b128 v[178:181], v139 offset:37888
	ds_read_b128 v[182:185], v139 offset:38912
	ds_read_b128 v[186:189], v139 offset:39936
	global_load_lds_dwordx4 v[190:191], off
	v_lshl_add_u64 v[190:191], v[206:207], 0, s[22:23]
	s_mov_b32 m0, s54
	s_nop 0
	global_load_lds_dwordx4 v[190:191], off
	s_waitcnt lgkmcnt(8)
	s_barrier
	s_waitcnt lgkmcnt(0)
	s_waitcnt lgkmcnt(0)
	v_mfma_f32_16x16x32_bf16 v[124:127], v[142:145], v[158:161], v[124:127]
	v_mfma_f32_16x16x32_bf16 v[120:123], v[150:153], v[158:161], v[120:123]
	v_mfma_f32_16x16x32_bf16 v[112:115], v[142:145], v[166:169], v[112:115]
	v_mfma_f32_16x16x32_bf16 v[104:107], v[150:153], v[166:169], v[104:107]
	v_mfma_f32_16x16x32_bf16 v[96:99], v[142:145], v[174:177], v[96:99]
	v_mfma_f32_16x16x32_bf16 v[88:91], v[150:153], v[174:177], v[88:91]
	v_mfma_f32_16x16x32_bf16 v[80:83], v[142:145], v[182:185], v[80:83]
	v_mfma_f32_16x16x32_bf16 v[72:75], v[150:153], v[182:185], v[72:75]
	v_mfma_f32_16x16x32_bf16 v[124:127], v[146:149], v[162:165], v[124:127]
	v_mfma_f32_16x16x32_bf16 v[120:123], v[154:157], v[162:165], v[120:123]
	v_mfma_f32_16x16x32_bf16 v[112:115], v[146:149], v[170:173], v[112:115]
	v_mfma_f32_16x16x32_bf16 v[104:107], v[154:157], v[170:173], v[104:107]
	v_mfma_f32_16x16x32_bf16 v[96:99], v[146:149], v[178:181], v[96:99]
	v_mfma_f32_16x16x32_bf16 v[88:91], v[154:157], v[178:181], v[88:91]
	v_mfma_f32_16x16x32_bf16 v[80:83], v[146:149], v[186:189], v[80:83]
	v_mfma_f32_16x16x32_bf16 v[72:75], v[154:157], v[186:189], v[72:75]
	s_barrier
	s_add_i32 s64, 0, 0x1c000
	s_add_i32 s53, s53, s48
	v_add_u32_e32 v141, s64, v137
	v_lshl_add_u64 v[208:209], v[134:135], 0, s[26:27]
	s_mov_b32 m0, s53
	ds_read_b128 v[190:193], v141
	ds_read_b128 v[194:197], v141 offset:1024
	ds_read_b128 v[198:201], v141 offset:2048
	ds_read_b128 v[202:205], v141 offset:3072
	global_load_lds_dwordx4 v[208:209], off
	v_lshl_add_u64 v[208:209], v[134:135], 0, s[28:29]
	s_add_i32 m0, s53, 0x2000
	s_nop 0
	global_load_lds_dwordx4 v[208:209], off
	s_barrier
	s_waitcnt lgkmcnt(0)
	s_waitcnt lgkmcnt(0)
	v_mfma_f32_16x16x32_bf16 v[116:119], v[190:193], v[158:161], v[116:119]
	v_mfma_f32_16x16x32_bf16 v[108:111], v[198:201], v[158:161], v[108:111]
	v_mfma_f32_16x16x32_bf16 v[100:103], v[190:193], v[166:169], v[100:103]
	v_mfma_f32_16x16x32_bf16 v[92:95], v[198:201], v[166:169], v[92:95]
	v_mfma_f32_16x16x32_bf16 v[84:87], v[190:193], v[174:177], v[84:87]
	v_mfma_f32_16x16x32_bf16 v[76:79], v[198:201], v[174:177], v[76:79]
	v_mfma_f32_16x16x32_bf16 v[68:71], v[190:193], v[182:185], v[68:71]
	v_mfma_f32_16x16x32_bf16 v[64:67], v[198:201], v[182:185], v[64:67]
	v_mfma_f32_16x16x32_bf16 v[116:119], v[194:197], v[162:165], v[116:119]
	v_mfma_f32_16x16x32_bf16 v[108:111], v[202:205], v[162:165], v[108:111]
	v_mfma_f32_16x16x32_bf16 v[100:103], v[194:197], v[170:173], v[100:103]
	v_mfma_f32_16x16x32_bf16 v[92:95], v[202:205], v[170:173], v[92:95]
	v_mfma_f32_16x16x32_bf16 v[84:87], v[194:197], v[178:181], v[84:87]
	v_mfma_f32_16x16x32_bf16 v[76:79], v[202:205], v[178:181], v[76:79]
	v_mfma_f32_16x16x32_bf16 v[68:71], v[194:197], v[186:189], v[68:71]
	v_mfma_f32_16x16x32_bf16 v[64:67], v[202:205], v[186:189], v[64:67]
	s_mov_b32 m0, s55
	v_lshl_add_u64 v[208:209], v[206:207], 0, s[26:27]
	s_barrier
	ds_read_b128 v[158:161], v139 offset:49152
	ds_read_b128 v[162:165], v139 offset:50176
	ds_read_b128 v[166:169], v139 offset:51200
	ds_read_b128 v[170:173], v139 offset:52224
	ds_read_b128 v[174:177], v139 offset:53248
	ds_read_b128 v[178:181], v139 offset:54272
	ds_read_b128 v[182:185], v139 offset:55296
	ds_read_b128 v[186:189], v139 offset:56320
	global_load_lds_dwordx4 v[208:209], off
	v_lshl_add_u64 v[206:207], v[206:207], 0, s[34:35]
	s_mov_b32 m0, s56
	s_nop 0
	global_load_lds_dwordx4 v[206:207], off
	s_barrier
	s_waitcnt lgkmcnt(0)
	s_waitcnt lgkmcnt(0)
	v_mfma_f32_16x16x32_bf16 v[60:63], v[142:145], v[158:161], v[60:63]
	v_mfma_f32_16x16x32_bf16 v[56:59], v[150:153], v[158:161], v[56:59]
	v_mfma_f32_16x16x32_bf16 v[48:51], v[142:145], v[166:169], v[48:51]
	v_mfma_f32_16x16x32_bf16 v[40:43], v[150:153], v[166:169], v[40:43]
	v_mfma_f32_16x16x32_bf16 v[32:35], v[142:145], v[174:177], v[32:35]
	v_mfma_f32_16x16x32_bf16 v[24:27], v[150:153], v[174:177], v[24:27]
	v_mfma_f32_16x16x32_bf16 v[16:19], v[142:145], v[182:185], v[16:19]
	v_mfma_f32_16x16x32_bf16 v[8:11], v[150:153], v[182:185], v[8:11]
	v_mfma_f32_16x16x32_bf16 v[60:63], v[146:149], v[162:165], v[60:63]
	v_mfma_f32_16x16x32_bf16 v[56:59], v[154:157], v[162:165], v[56:59]
	v_mfma_f32_16x16x32_bf16 v[48:51], v[146:149], v[170:173], v[48:51]
	v_mfma_f32_16x16x32_bf16 v[40:43], v[154:157], v[170:173], v[40:43]
	v_mfma_f32_16x16x32_bf16 v[32:35], v[146:149], v[178:181], v[32:35]
	v_mfma_f32_16x16x32_bf16 v[24:27], v[154:157], v[178:181], v[24:27]
	v_mfma_f32_16x16x32_bf16 v[16:19], v[146:149], v[186:189], v[16:19]
	v_mfma_f32_16x16x32_bf16 v[8:11], v[154:157], v[186:189], v[8:11]
	s_barrier
	s_add_i32 s53, s64, s48
	v_lshl_add_u64 v[142:143], v[134:135], 0, s[36:37]
	s_mov_b32 m0, s53
	v_lshl_add_u64 v[134:135], v[134:135], 0, s[38:39]
	global_load_lds_dwordx4 v[142:143], off
	s_add_i32 m0, s53, 0x2000
	s_nop 0
	global_load_lds_dwordx4 v[134:135], off
	s_waitcnt vmcnt(6)
	s_barrier
	v_mfma_f32_16x16x32_bf16 v[52:55], v[190:193], v[158:161], v[52:55]
	v_mfma_f32_16x16x32_bf16 v[44:47], v[198:201], v[158:161], v[44:47]
	v_mfma_f32_16x16x32_bf16 v[36:39], v[190:193], v[166:169], v[36:39]
	v_mfma_f32_16x16x32_bf16 v[28:31], v[198:201], v[166:169], v[28:31]
	v_mfma_f32_16x16x32_bf16 v[20:23], v[190:193], v[174:177], v[20:23]
	v_mfma_f32_16x16x32_bf16 v[12:15], v[198:201], v[174:177], v[12:15]
	v_mfma_f32_16x16x32_bf16 v[4:7], v[190:193], v[182:185], v[4:7]
	v_mfma_f32_16x16x32_bf16 v[0:3], v[198:201], v[182:185], v[0:3]
	v_mfma_f32_16x16x32_bf16 v[52:55], v[194:197], v[162:165], v[52:55]
	v_mfma_f32_16x16x32_bf16 v[44:47], v[202:205], v[162:165], v[44:47]
	v_mfma_f32_16x16x32_bf16 v[36:39], v[194:197], v[170:173], v[36:39]
	v_mfma_f32_16x16x32_bf16 v[28:31], v[202:205], v[170:173], v[28:31]
	v_mfma_f32_16x16x32_bf16 v[20:23], v[194:197], v[178:181], v[20:23]
	v_mfma_f32_16x16x32_bf16 v[12:15], v[202:205], v[178:181], v[12:15]
	v_mfma_f32_16x16x32_bf16 v[4:7], v[194:197], v[186:189], v[4:7]
	v_mfma_f32_16x16x32_bf16 v[0:3], v[202:205], v[186:189], v[0:3]
	s_add_i32 s52, s52, 2
	s_add_u32 s44, s44, 0x100
	s_addc_u32 s45, s45, 0
	s_add_u32 s46, s46, 0x100
	s_addc_u32 s47, s47, 0
	s_cmp_gt_u32 s52, 5
	s_barrier
	s_cbranch_scc0 .LBB0_987
	v_mov_b32_e32 v141, v136
	s_mov_b32 s44, s33
	s_mov_b32 s45, s57
	s_lshl_b32 s46, s63, 8
	s_lshl_b32 s45, s45, 5
	s_add_i32 s45, s45, s46
	v_lshrrev_b32_e32 v134, 1, v141
	v_and_or_b32 v134, v134, 24, s45
	s_lshl_b32 s45, s62, 8
	v_ashrrev_i32_e32 v135, 31, v134
	v_and_or_b32 v141, v141, 15, s45
	v_lshl_add_u32 v141, s44, 6, v141
	v_lshl_add_u64 v[134:135], v[134:135], 1, s[24:25]
	v_mad_i64_i32 v[142:143], s[44:45], v141, s61, v[134:135]
	v_pk_add_f32 v[126:127], v[126:127], 0 op_sel_hi:[1,0]
	v_pk_add_f32 v[124:125], v[124:125], 0 op_sel_hi:[1,0]
	v_pk_add_f32 v[144:145], v[122:123], 0 op_sel_hi:[1,0]
	v_pk_add_f32 v[122:123], v[120:121], 0 op_sel_hi:[1,0]
	v_cvt_pk_bf16_f32 v120, v124, v125
	v_cvt_pk_bf16_f32 v121, v126, v127
	v_pk_add_f32 v[116:117], v[116:117], 0 op_sel_hi:[1,0]
	v_cvt_pk_bf16_f32 v122, v122, v123
	v_cvt_pk_bf16_f32 v123, v144, v145
	global_store_dwordx4 v[142:143], v[120:123], off
	v_pk_add_f32 v[118:119], v[118:119], 0 op_sel_hi:[1,0]
	v_pk_add_f32 v[112:113], v[112:113], 0 op_sel_hi:[1,0]
	v_pk_add_f32 v[120:121], v[110:111], 0 op_sel_hi:[1,0]
	v_pk_add_f32 v[110:111], v[108:109], 0 op_sel_hi:[1,0]
	v_cvt_pk_bf16_f32 v108, v116, v117
	v_cvt_pk_bf16_f32 v109, v118, v119
	v_pk_add_f32 v[100:101], v[100:101], 0 op_sel_hi:[1,0]
	v_cvt_pk_bf16_f32 v110, v110, v111
	v_cvt_pk_bf16_f32 v111, v120, v121
	global_store_dwordx4 v[142:143], v[108:111], off offset:256
	v_pk_add_f32 v[102:103], v[102:103], 0 op_sel_hi:[1,0]
	v_pk_add_f32 v[96:97], v[96:97], 0 op_sel_hi:[1,0]
	v_or_b32_e32 v108, 16, v141
	v_mad_i64_i32 v[108:109], s[44:45], v108, s61, v[134:135]
	v_pk_add_f32 v[110:111], v[114:115], 0 op_sel_hi:[1,0]
	v_pk_add_f32 v[114:115], v[106:107], 0 op_sel_hi:[1,0]
	v_pk_add_f32 v[106:107], v[104:105], 0 op_sel_hi:[1,0]
	v_cvt_pk_bf16_f32 v104, v112, v113
	v_cvt_pk_bf16_f32 v105, v110, v111
	v_pk_add_f32 v[84:85], v[84:85], 0 op_sel_hi:[1,0]
	v_cvt_pk_bf16_f32 v106, v106, v107
	v_cvt_pk_bf16_f32 v107, v114, v115
	global_store_dwordx4 v[108:109], v[104:107], off
	v_pk_add_f32 v[86:87], v[86:87], 0 op_sel_hi:[1,0]
	v_pk_add_f32 v[80:81], v[80:81], 0 op_sel_hi:[1,0]
	v_pk_add_f32 v[104:105], v[94:95], 0 op_sel_hi:[1,0]
	v_pk_add_f32 v[94:95], v[92:93], 0 op_sel_hi:[1,0]
	v_cvt_pk_bf16_f32 v92, v100, v101
	v_cvt_pk_bf16_f32 v93, v102, v103
	v_pk_add_f32 v[68:69], v[68:69], 0 op_sel_hi:[1,0]
	v_cvt_pk_bf16_f32 v94, v94, v95
	v_cvt_pk_bf16_f32 v95, v104, v105
	global_store_dwordx4 v[108:109], v[92:95], off offset:256
	v_pk_add_f32 v[70:71], v[70:71], 0 op_sel_hi:[1,0]
	v_pk_add_f32 v[62:63], v[62:63], 0 op_sel_hi:[1,0]
	v_or_b32_e32 v92, 32, v141
	v_mad_i64_i32 v[92:93], s[44:45], v92, s61, v[134:135]
	v_pk_add_f32 v[94:95], v[98:99], 0 op_sel_hi:[1,0]
	v_pk_add_f32 v[98:99], v[90:91], 0 op_sel_hi:[1,0]
	v_pk_add_f32 v[90:91], v[88:89], 0 op_sel_hi:[1,0]
	v_cvt_pk_bf16_f32 v88, v96, v97
	v_cvt_pk_bf16_f32 v89, v94, v95
	v_pk_add_f32 v[60:61], v[60:61], 0 op_sel_hi:[1,0]
	v_cvt_pk_bf16_f32 v90, v90, v91
	v_cvt_pk_bf16_f32 v91, v98, v99
	global_store_dwordx4 v[92:93], v[88:91], off
	v_pk_add_f32 v[52:53], v[52:53], 0 op_sel_hi:[1,0]
	v_pk_add_f32 v[54:55], v[54:55], 0 op_sel_hi:[1,0]
	v_pk_add_f32 v[88:89], v[78:79], 0 op_sel_hi:[1,0]
	v_pk_add_f32 v[78:79], v[76:77], 0 op_sel_hi:[1,0]
	v_cvt_pk_bf16_f32 v76, v84, v85
	v_cvt_pk_bf16_f32 v77, v86, v87
	v_pk_add_f32 v[48:49], v[48:49], 0 op_sel_hi:[1,0]
	v_cvt_pk_bf16_f32 v78, v78, v79
	v_cvt_pk_bf16_f32 v79, v88, v89
	global_store_dwordx4 v[92:93], v[76:79], off offset:256
	v_pk_add_f32 v[36:37], v[36:37], 0 op_sel_hi:[1,0]
	v_pk_add_f32 v[38:39], v[38:39], 0 op_sel_hi:[1,0]
	v_or_b32_e32 v76, 48, v141
	v_mad_i64_i32 v[76:77], s[44:45], v76, s61, v[134:135]
	v_pk_add_f32 v[78:79], v[82:83], 0 op_sel_hi:[1,0]
	v_pk_add_f32 v[82:83], v[74:75], 0 op_sel_hi:[1,0]
	v_pk_add_f32 v[74:75], v[72:73], 0 op_sel_hi:[1,0]
	v_cvt_pk_bf16_f32 v72, v80, v81
	v_cvt_pk_bf16_f32 v73, v78, v79
	v_pk_add_f32 v[32:33], v[32:33], 0 op_sel_hi:[1,0]
	v_cvt_pk_bf16_f32 v74, v74, v75
	v_cvt_pk_bf16_f32 v75, v82, v83
	global_store_dwordx4 v[76:77], v[72:75], off
	v_pk_add_f32 v[20:21], v[20:21], 0 op_sel_hi:[1,0]
	v_pk_add_f32 v[22:23], v[22:23], 0 op_sel_hi:[1,0]
	v_pk_add_f32 v[72:73], v[66:67], 0 op_sel_hi:[1,0]
	v_pk_add_f32 v[66:67], v[64:65], 0 op_sel_hi:[1,0]
	v_cvt_pk_bf16_f32 v64, v68, v69
	v_cvt_pk_bf16_f32 v65, v70, v71
	v_pk_add_f32 v[16:17], v[16:17], 0 op_sel_hi:[1,0]
	v_cvt_pk_bf16_f32 v66, v66, v67
	v_cvt_pk_bf16_f32 v67, v72, v73
	global_store_dwordx4 v[76:77], v[64:67], off offset:256
	v_pk_add_f32 v[6:7], v[6:7], 0 op_sel_hi:[1,0]
	v_pk_add_f32 v[4:5], v[4:5], 0 op_sel_hi:[1,0]
	v_add_u32_e32 v64, 0x80, v141
	v_mad_i64_i32 v[64:65], s[44:45], v64, s61, v[134:135]
	v_pk_add_f32 v[66:67], v[58:59], 0 op_sel_hi:[1,0]
	v_pk_add_f32 v[58:59], v[56:57], 0 op_sel_hi:[1,0]
	v_cvt_pk_bf16_f32 v56, v60, v61
	v_cvt_pk_bf16_f32 v57, v62, v63
	s_nop 0
	v_cvt_pk_bf16_f32 v58, v58, v59
	v_cvt_pk_bf16_f32 v59, v66, v67
	global_store_dwordx4 v[64:65], v[56:59], off
	s_nop 1
	v_pk_add_f32 v[56:57], v[46:47], 0 op_sel_hi:[1,0]
	v_pk_add_f32 v[46:47], v[44:45], 0 op_sel_hi:[1,0]
	v_cvt_pk_bf16_f32 v44, v52, v53
	v_cvt_pk_bf16_f32 v45, v54, v55
	s_nop 0
	v_cvt_pk_bf16_f32 v46, v46, v47
	v_cvt_pk_bf16_f32 v47, v56, v57
	global_store_dwordx4 v[64:65], v[44:47], off offset:256
	s_nop 1
	v_add_u32_e32 v44, 0x90, v141
	v_mad_i64_i32 v[44:45], s[44:45], v44, s61, v[134:135]
	v_pk_add_f32 v[46:47], v[50:51], 0 op_sel_hi:[1,0]
	v_pk_add_f32 v[50:51], v[42:43], 0 op_sel_hi:[1,0]
	v_pk_add_f32 v[42:43], v[40:41], 0 op_sel_hi:[1,0]
	v_cvt_pk_bf16_f32 v40, v48, v49
	v_cvt_pk_bf16_f32 v41, v46, v47
	s_nop 0
	v_cvt_pk_bf16_f32 v42, v42, v43
	v_cvt_pk_bf16_f32 v43, v50, v51
	global_store_dwordx4 v[44:45], v[40:43], off
	s_nop 1
	v_pk_add_f32 v[40:41], v[30:31], 0 op_sel_hi:[1,0]
	v_pk_add_f32 v[30:31], v[28:29], 0 op_sel_hi:[1,0]
	v_cvt_pk_bf16_f32 v28, v36, v37
	v_cvt_pk_bf16_f32 v29, v38, v39
	s_nop 0
	v_cvt_pk_bf16_f32 v30, v30, v31
	v_cvt_pk_bf16_f32 v31, v40, v41
	global_store_dwordx4 v[44:45], v[28:31], off offset:256
	s_nop 1
	v_add_u32_e32 v28, 0xa0, v141
	v_mad_i64_i32 v[28:29], s[44:45], v28, s61, v[134:135]
	v_pk_add_f32 v[30:31], v[34:35], 0 op_sel_hi:[1,0]
	v_pk_add_f32 v[34:35], v[26:27], 0 op_sel_hi:[1,0]
	v_pk_add_f32 v[26:27], v[24:25], 0 op_sel_hi:[1,0]
	v_cvt_pk_bf16_f32 v24, v32, v33
	v_cvt_pk_bf16_f32 v25, v30, v31
	s_nop 0
	v_cvt_pk_bf16_f32 v26, v26, v27
	v_cvt_pk_bf16_f32 v27, v34, v35
	global_store_dwordx4 v[28:29], v[24:27], off
	s_nop 1
	v_pk_add_f32 v[24:25], v[14:15], 0 op_sel_hi:[1,0]
	v_pk_add_f32 v[14:15], v[12:13], 0 op_sel_hi:[1,0]
	v_cvt_pk_bf16_f32 v12, v20, v21
	v_cvt_pk_bf16_f32 v13, v22, v23
	s_nop 0
	v_cvt_pk_bf16_f32 v14, v14, v15
	v_cvt_pk_bf16_f32 v15, v24, v25
	global_store_dwordx4 v[28:29], v[12:15], off offset:256
	s_nop 1
	v_add_u32_e32 v12, 0xb0, v141
	v_mad_i64_i32 v[12:13], s[44:45], v12, s61, v[134:135]
	v_pk_add_f32 v[14:15], v[18:19], 0 op_sel_hi:[1,0]
	v_pk_add_f32 v[18:19], v[10:11], 0 op_sel_hi:[1,0]
	v_pk_add_f32 v[10:11], v[8:9], 0 op_sel_hi:[1,0]
	v_cvt_pk_bf16_f32 v8, v16, v17
	v_cvt_pk_bf16_f32 v9, v14, v15
	s_mov_b32 s44, s58
	v_cvt_pk_bf16_f32 v10, v10, v11
	v_cvt_pk_bf16_f32 v11, v18, v19
	global_store_dwordx4 v[12:13], v[8:11], off
	s_nop 1
	v_pk_add_f32 v[8:9], v[2:3], 0 op_sel_hi:[1,0]
	v_pk_add_f32 v[2:3], v[0:1], 0 op_sel_hi:[1,0]
	v_cvt_pk_bf16_f32 v0, v4, v5
	v_cvt_pk_bf16_f32 v1, v6, v7
	s_nop 0
	v_cvt_pk_bf16_f32 v2, v2, v3
	v_cvt_pk_bf16_f32 v3, v8, v9
	global_store_dwordx4 v[12:13], v[0:3], off offset:256
	s_mul_i32 s46, s44, s13
	s_add_i32 s46, s46, s14
	s_cmpk_gt_i32 s46, 0xbf
	s_mov_b64 s[44:45], -1
	s_cbranch_scc1 .LBB0_983
	s_ashr_i32 s44, s46, 31
	s_lshr_b32 s44, s44, 29
	s_add_i32 s44, s46, s44
	s_ashr_i32 s45, s44, 3
	s_and_b32 s44, s44, -8
	s_sub_i32 s44, s46, s44
	s_cmp_lt_i32 s44, 0
	s_cselect_b32 s46, 25, 24
	s_mul_i32 s44, s46, s44
	s_add_i32 s44, s44, s45
	s_mul_hi_i32 s45, s44, 0x2aaaaaab
	s_lshr_b32 s46, s45, 31
	s_ashr_i32 s45, s45, 3
	s_add_i32 s45, s45, s46
	s_lshl_b32 s46, s45, 3
	s_mul_i32 s45, s45, 48
	s_sub_i32 s44, s44, s45
	s_bfe_i32 s45, s44, 0x80000
	s_bfe_u32 s45, s45, 0x3000c
	s_add_i32 s45, s44, s45
	s_bfe_i32 s47, s45, 0x80000
	s_and_b32 s45, s45, 0xf8
	s_sub_i32 s44, s44, s45
	s_sext_i32_i16 s47, s47
	s_sext_i32_i8 s44, s44
	s_add_i32 s62, s46, s44
	s_ashr_i32 s63, s47, 3
	s_mov_b64 s[44:45], 0
	s_branch .LBB0_983

.LBB0_1001:
	s_add_u32 s56, s44, s70
	s_addc_u32 s57, s45, 0
	s_add_u32 s71, s56, 0x100
	s_addc_u32 s72, s57, 0
	v_cndmask_b32_e64 v132, 0, 1, s[54:55]
	s_and_b64 s[54:55], s[52:53], exec
	s_cselect_b32 s54, s40, s71
	s_cselect_b32 s55, s41, s72
	s_add_u32 s70, s46, s70
	s_addc_u32 s71, s47, 0
	ds_read_b128 v[140:143], v135
	ds_read_b128 v[144:147], v135 offset:1024
	ds_read_b128 v[148:151], v135 offset:2048
	ds_read_b128 v[152:155], v135 offset:3072
	s_add_u32 s70, s70, 0x100
	s_addc_u32 s71, s71, 0
	s_and_b64 s[52:53], s[52:53], exec
	s_cselect_b32 s52, s42, s70
	s_cselect_b32 s53, s43, s71
	s_add_i32 s73, 0, 0x1c000
	s_add_i32 s75, 0, 0x18000
	s_add_i32 s71, s73, s51
	s_add_i32 s79, s66, s51
	s_add_i32 s77, s67, s51
	s_add_i32 s74, s75, s51
	s_add_i32 s70, s71, 0x2000
	s_add_i32 m0, s58, 0xc000
	s_add_i32 s80, s58, 0xe000
	s_add_i32 s78, s79, 0x2000
	s_add_i32 s76, s77, 0x2000
	s_add_i32 s72, s74, 0x2000
	v_cmp_ne_u32_e32 vcc, 1, v132
	v_lshl_add_u64 v[132:133], s[56:57], 0, v[130:131]
	s_mov_b64 s[56:57], 0x240080
	v_lshl_add_u64 v[188:189], v[132:133], 0, s[56:57]
	s_mov_b64 s[56:57], 0x360080
	ds_read_b128 v[156:159], v137
	ds_read_b128 v[160:163], v137 offset:1024
	ds_read_b128 v[164:167], v137 offset:2048
	ds_read_b128 v[168:171], v137 offset:3072
	ds_read_b128 v[172:175], v137 offset:4096
	ds_read_b128 v[176:179], v137 offset:5120
	ds_read_b128 v[180:183], v137 offset:6144
	ds_read_b128 v[184:187], v137 offset:7168
	global_load_lds_dwordx4 v[188:189], off
	v_lshl_add_u64 v[132:133], v[132:133], 0, s[56:57]
	s_mov_b32 m0, s80
	s_nop 0
	global_load_lds_dwordx4 v[132:133], off
	s_waitcnt lgkmcnt(8)
	s_barrier
	s_waitcnt lgkmcnt(0)
	s_waitcnt lgkmcnt(0)
	v_mfma_f32_16x16x32_bf16 v[124:127], v[140:143], v[156:159], v[124:127]
	v_mfma_f32_16x16x32_bf16 v[120:123], v[148:151], v[156:159], v[120:123]
	v_mfma_f32_16x16x32_bf16 v[112:115], v[140:143], v[164:167], v[112:115]
	v_mfma_f32_16x16x32_bf16 v[104:107], v[148:151], v[164:167], v[104:107]
	v_mfma_f32_16x16x32_bf16 v[96:99], v[140:143], v[172:175], v[96:99]
	v_mfma_f32_16x16x32_bf16 v[88:91], v[148:151], v[172:175], v[88:91]
	v_mfma_f32_16x16x32_bf16 v[80:83], v[140:143], v[180:183], v[80:83]
	v_mfma_f32_16x16x32_bf16 v[72:75], v[148:151], v[180:183], v[72:75]
	v_mfma_f32_16x16x32_bf16 v[124:127], v[144:147], v[160:163], v[124:127]
	v_mfma_f32_16x16x32_bf16 v[120:123], v[152:155], v[160:163], v[120:123]
	v_mfma_f32_16x16x32_bf16 v[112:115], v[144:147], v[168:171], v[112:115]
	v_mfma_f32_16x16x32_bf16 v[104:107], v[152:155], v[168:171], v[104:107]
	v_mfma_f32_16x16x32_bf16 v[96:99], v[144:147], v[176:179], v[96:99]
	v_mfma_f32_16x16x32_bf16 v[88:91], v[152:155], v[176:179], v[88:91]
	v_mfma_f32_16x16x32_bf16 v[80:83], v[144:147], v[184:187], v[80:83]
	v_mfma_f32_16x16x32_bf16 v[72:75], v[152:155], v[184:187], v[72:75]
	s_barrier
	s_mov_b32 m0, s79
	v_lshl_add_u64 v[132:133], s[52:53], 0, v[128:129]
	ds_read_b128 v[188:191], v138
	ds_read_b128 v[192:195], v138 offset:1024
	ds_read_b128 v[196:199], v138 offset:2048
	ds_read_b128 v[200:203], v138 offset:3072
	global_load_lds_dwordx4 v[132:133], off
	v_lshl_add_u64 v[204:205], v[132:133], 0, s[8:9]
	s_mov_b32 m0, s78
	s_nop 0
	global_load_lds_dwordx4 v[204:205], off
	s_barrier
	s_waitcnt lgkmcnt(0)
	s_waitcnt lgkmcnt(0)
	v_mfma_f32_16x16x32_bf16 v[116:119], v[188:191], v[156:159], v[116:119]
	v_mfma_f32_16x16x32_bf16 v[108:111], v[196:199], v[156:159], v[108:111]
	v_mfma_f32_16x16x32_bf16 v[100:103], v[188:191], v[164:167], v[100:103]
	v_mfma_f32_16x16x32_bf16 v[92:95], v[196:199], v[164:167], v[92:95]
	v_mfma_f32_16x16x32_bf16 v[84:87], v[188:191], v[172:175], v[84:87]
	v_mfma_f32_16x16x32_bf16 v[76:79], v[196:199], v[172:175], v[76:79]
	v_mfma_f32_16x16x32_bf16 v[68:71], v[188:191], v[180:183], v[68:71]
	v_mfma_f32_16x16x32_bf16 v[64:67], v[196:199], v[180:183], v[64:67]
	v_mfma_f32_16x16x32_bf16 v[116:119], v[192:195], v[160:163], v[116:119]
	v_mfma_f32_16x16x32_bf16 v[108:111], v[200:203], v[160:163], v[108:111]
	v_mfma_f32_16x16x32_bf16 v[100:103], v[192:195], v[168:171], v[100:103]
	v_mfma_f32_16x16x32_bf16 v[92:95], v[200:203], v[168:171], v[92:95]
	v_mfma_f32_16x16x32_bf16 v[84:87], v[192:195], v[176:179], v[84:87]
	v_mfma_f32_16x16x32_bf16 v[76:79], v[200:203], v[176:179], v[76:79]
	v_mfma_f32_16x16x32_bf16 v[68:71], v[192:195], v[184:187], v[68:71]
	v_mfma_f32_16x16x32_bf16 v[64:67], v[200:203], v[184:187], v[64:67]
	s_mov_b32 m0, s58
	v_lshl_add_u64 v[204:205], s[54:55], 0, v[130:131]
	s_barrier
	ds_read_b128 v[156:159], v137 offset:16384
	ds_read_b128 v[160:163], v137 offset:17408
	ds_read_b128 v[164:167], v137 offset:18432
	ds_read_b128 v[168:171], v137 offset:19456
	ds_read_b128 v[172:175], v137 offset:20480
	ds_read_b128 v[176:179], v137 offset:21504
	ds_read_b128 v[180:183], v137 offset:22528
	ds_read_b128 v[184:187], v137 offset:23552
	global_load_lds_dwordx4 v[204:205], off
	v_lshl_add_u64 v[206:207], v[204:205], 0, s[10:11]
	s_mov_b32 m0, s59
	s_nop 0
	global_load_lds_dwordx4 v[206:207], off
	s_barrier
	s_waitcnt lgkmcnt(0)
	s_waitcnt lgkmcnt(0)
	v_mfma_f32_16x16x32_bf16 v[60:63], v[140:143], v[156:159], v[60:63]
	v_mfma_f32_16x16x32_bf16 v[56:59], v[148:151], v[156:159], v[56:59]
	v_mfma_f32_16x16x32_bf16 v[48:51], v[140:143], v[164:167], v[48:51]
	v_mfma_f32_16x16x32_bf16 v[40:43], v[148:151], v[164:167], v[40:43]
	v_mfma_f32_16x16x32_bf16 v[32:35], v[140:143], v[172:175], v[32:35]
	v_mfma_f32_16x16x32_bf16 v[24:27], v[148:151], v[172:175], v[24:27]
	v_mfma_f32_16x16x32_bf16 v[16:19], v[140:143], v[180:183], v[16:19]
	v_mfma_f32_16x16x32_bf16 v[8:11], v[148:151], v[180:183], v[8:11]
	v_mfma_f32_16x16x32_bf16 v[60:63], v[144:147], v[160:163], v[60:63]
	v_mfma_f32_16x16x32_bf16 v[56:59], v[152:155], v[160:163], v[56:59]
	v_mfma_f32_16x16x32_bf16 v[48:51], v[144:147], v[168:171], v[48:51]
	v_mfma_f32_16x16x32_bf16 v[40:43], v[152:155], v[168:171], v[40:43]
	v_mfma_f32_16x16x32_bf16 v[32:35], v[144:147], v[176:179], v[32:35]
	v_mfma_f32_16x16x32_bf16 v[24:27], v[152:155], v[176:179], v[24:27]
	v_mfma_f32_16x16x32_bf16 v[16:19], v[144:147], v[184:187], v[16:19]
	v_mfma_f32_16x16x32_bf16 v[8:11], v[152:155], v[184:187], v[8:11]
	s_barrier
	s_mov_b32 m0, s77
	v_lshl_add_u64 v[140:141], v[132:133], 0, s[16:17]
	global_load_lds_dwordx4 v[140:141], off
	v_lshl_add_u64 v[140:141], v[132:133], 0, s[18:19]
	s_mov_b32 m0, s76
	s_nop 0
	global_load_lds_dwordx4 v[140:141], off
	s_waitcnt vmcnt(6)
	s_barrier
	v_mfma_f32_16x16x32_bf16 v[52:55], v[188:191], v[156:159], v[52:55]
	v_mfma_f32_16x16x32_bf16 v[44:47], v[196:199], v[156:159], v[44:47]
	v_mfma_f32_16x16x32_bf16 v[36:39], v[188:191], v[164:167], v[36:39]
	v_mfma_f32_16x16x32_bf16 v[28:31], v[196:199], v[164:167], v[28:31]
	v_mfma_f32_16x16x32_bf16 v[20:23], v[188:191], v[172:175], v[20:23]
	v_mfma_f32_16x16x32_bf16 v[12:15], v[196:199], v[172:175], v[12:15]
	v_mfma_f32_16x16x32_bf16 v[4:7], v[188:191], v[180:183], v[4:7]
	v_mfma_f32_16x16x32_bf16 v[0:3], v[196:199], v[180:183], v[0:3]
	v_mfma_f32_16x16x32_bf16 v[52:55], v[192:195], v[160:163], v[52:55]
	v_mfma_f32_16x16x32_bf16 v[44:47], v[200:203], v[160:163], v[44:47]
	v_mfma_f32_16x16x32_bf16 v[36:39], v[192:195], v[168:171], v[36:39]
	v_mfma_f32_16x16x32_bf16 v[28:31], v[200:203], v[168:171], v[28:31]
	v_mfma_f32_16x16x32_bf16 v[20:23], v[192:195], v[176:179], v[20:23]
	v_mfma_f32_16x16x32_bf16 v[12:15], v[200:203], v[176:179], v[12:15]
	v_mfma_f32_16x16x32_bf16 v[4:7], v[192:195], v[184:187], v[4:7]
	v_mfma_f32_16x16x32_bf16 v[0:3], v[200:203], v[184:187], v[0:3]
	v_add_u32_e32 v139, s75, v134
	s_barrier
	ds_read_b128 v[140:143], v139
	ds_read_b128 v[144:147], v139 offset:1024
	ds_read_b128 v[148:151], v139 offset:2048
	ds_read_b128 v[152:155], v139 offset:3072
	s_mov_b32 m0, s60
	v_lshl_add_u64 v[188:189], v[204:205], 0, s[20:21]
	ds_read_b128 v[156:159], v137 offset:32768
	ds_read_b128 v[160:163], v137 offset:33792
	ds_read_b128 v[164:167], v137 offset:34816
	ds_read_b128 v[168:171], v137 offset:35840
	ds_read_b128 v[172:175], v137 offset:36864
	ds_read_b128 v[176:179], v137 offset:37888
	ds_read_b128 v[180:183], v137 offset:38912
	ds_read_b128 v[184:187], v137 offset:39936
	global_load_lds_dwordx4 v[188:189], off
	v_lshl_add_u64 v[188:189], v[204:205], 0, s[22:23]
	s_mov_b32 m0, s61
	s_nop 0
	global_load_lds_dwordx4 v[188:189], off
	s_waitcnt lgkmcnt(8)
	s_barrier
	s_waitcnt lgkmcnt(0)
	s_waitcnt lgkmcnt(0)
	v_mfma_f32_16x16x32_bf16 v[124:127], v[140:143], v[156:159], v[124:127]
	v_mfma_f32_16x16x32_bf16 v[120:123], v[148:151], v[156:159], v[120:123]
	v_mfma_f32_16x16x32_bf16 v[112:115], v[140:143], v[164:167], v[112:115]
	v_mfma_f32_16x16x32_bf16 v[104:107], v[148:151], v[164:167], v[104:107]
	v_mfma_f32_16x16x32_bf16 v[96:99], v[140:143], v[172:175], v[96:99]
	v_mfma_f32_16x16x32_bf16 v[88:91], v[148:151], v[172:175], v[88:91]
	v_mfma_f32_16x16x32_bf16 v[80:83], v[140:143], v[180:183], v[80:83]
	v_mfma_f32_16x16x32_bf16 v[72:75], v[148:151], v[180:183], v[72:75]
	v_mfma_f32_16x16x32_bf16 v[124:127], v[144:147], v[160:163], v[124:127]
	v_mfma_f32_16x16x32_bf16 v[120:123], v[152:155], v[160:163], v[120:123]
	v_mfma_f32_16x16x32_bf16 v[112:115], v[144:147], v[168:171], v[112:115]
	v_mfma_f32_16x16x32_bf16 v[104:107], v[152:155], v[168:171], v[104:107]
	v_mfma_f32_16x16x32_bf16 v[96:99], v[144:147], v[176:179], v[96:99]
	v_mfma_f32_16x16x32_bf16 v[88:91], v[152:155], v[176:179], v[88:91]
	v_mfma_f32_16x16x32_bf16 v[80:83], v[144:147], v[184:187], v[80:83]
	v_mfma_f32_16x16x32_bf16 v[72:75], v[152:155], v[184:187], v[72:75]
	s_barrier
	s_mov_b32 m0, s74
	v_add_u32_e32 v139, s73, v134
	v_lshl_add_u64 v[206:207], v[132:133], 0, s[26:27]
	ds_read_b128 v[188:191], v139
	ds_read_b128 v[192:195], v139 offset:1024
	ds_read_b128 v[196:199], v139 offset:2048
	ds_read_b128 v[200:203], v139 offset:3072
	global_load_lds_dwordx4 v[206:207], off
	v_lshl_add_u64 v[206:207], v[132:133], 0, s[28:29]
	s_mov_b32 m0, s72
	s_nop 0
	global_load_lds_dwordx4 v[206:207], off
	s_barrier
	s_waitcnt lgkmcnt(0)
	s_waitcnt lgkmcnt(0)
	v_mfma_f32_16x16x32_bf16 v[116:119], v[188:191], v[156:159], v[116:119]
	v_mfma_f32_16x16x32_bf16 v[108:111], v[196:199], v[156:159], v[108:111]
	v_mfma_f32_16x16x32_bf16 v[100:103], v[188:191], v[164:167], v[100:103]
	v_mfma_f32_16x16x32_bf16 v[92:95], v[196:199], v[164:167], v[92:95]
	v_mfma_f32_16x16x32_bf16 v[84:87], v[188:191], v[172:175], v[84:87]
	v_mfma_f32_16x16x32_bf16 v[76:79], v[196:199], v[172:175], v[76:79]
	v_mfma_f32_16x16x32_bf16 v[68:71], v[188:191], v[180:183], v[68:71]
	v_mfma_f32_16x16x32_bf16 v[64:67], v[196:199], v[180:183], v[64:67]
	v_mfma_f32_16x16x32_bf16 v[116:119], v[192:195], v[160:163], v[116:119]
	v_mfma_f32_16x16x32_bf16 v[108:111], v[200:203], v[160:163], v[108:111]
	v_mfma_f32_16x16x32_bf16 v[100:103], v[192:195], v[168:171], v[100:103]
	v_mfma_f32_16x16x32_bf16 v[92:95], v[200:203], v[168:171], v[92:95]
	v_mfma_f32_16x16x32_bf16 v[84:87], v[192:195], v[176:179], v[84:87]
	v_mfma_f32_16x16x32_bf16 v[76:79], v[200:203], v[176:179], v[76:79]
	v_mfma_f32_16x16x32_bf16 v[68:71], v[192:195], v[184:187], v[68:71]
	v_mfma_f32_16x16x32_bf16 v[64:67], v[200:203], v[184:187], v[64:67]
	s_mov_b32 m0, s64
	v_lshl_add_u64 v[206:207], v[204:205], 0, s[26:27]
	s_barrier
	ds_read_b128 v[156:159], v137 offset:49152
	ds_read_b128 v[160:163], v137 offset:50176
	ds_read_b128 v[164:167], v137 offset:51200
	ds_read_b128 v[168:171], v137 offset:52224
	ds_read_b128 v[172:175], v137 offset:53248
	ds_read_b128 v[176:179], v137 offset:54272
	ds_read_b128 v[180:183], v137 offset:55296
	ds_read_b128 v[184:187], v137 offset:56320
	global_load_lds_dwordx4 v[206:207], off
	v_lshl_add_u64 v[204:205], v[204:205], 0, s[34:35]
	s_mov_b32 m0, s65
	s_nop 0
	global_load_lds_dwordx4 v[204:205], off
	s_barrier
	s_waitcnt lgkmcnt(0)
	s_waitcnt lgkmcnt(0)
	v_mfma_f32_16x16x32_bf16 v[60:63], v[140:143], v[156:159], v[60:63]
	v_mfma_f32_16x16x32_bf16 v[56:59], v[148:151], v[156:159], v[56:59]
	v_mfma_f32_16x16x32_bf16 v[48:51], v[140:143], v[164:167], v[48:51]
	v_mfma_f32_16x16x32_bf16 v[40:43], v[148:151], v[164:167], v[40:43]
	v_mfma_f32_16x16x32_bf16 v[32:35], v[140:143], v[172:175], v[32:35]
	v_mfma_f32_16x16x32_bf16 v[24:27], v[148:151], v[172:175], v[24:27]
	v_mfma_f32_16x16x32_bf16 v[16:19], v[140:143], v[180:183], v[16:19]
	v_mfma_f32_16x16x32_bf16 v[8:11], v[148:151], v[180:183], v[8:11]
	v_mfma_f32_16x16x32_bf16 v[60:63], v[144:147], v[160:163], v[60:63]
	v_mfma_f32_16x16x32_bf16 v[56:59], v[152:155], v[160:163], v[56:59]
	v_mfma_f32_16x16x32_bf16 v[48:51], v[144:147], v[168:171], v[48:51]
	v_mfma_f32_16x16x32_bf16 v[40:43], v[152:155], v[168:171], v[40:43]
	v_mfma_f32_16x16x32_bf16 v[32:35], v[144:147], v[176:179], v[32:35]
	v_mfma_f32_16x16x32_bf16 v[24:27], v[152:155], v[176:179], v[24:27]
	v_mfma_f32_16x16x32_bf16 v[16:19], v[144:147], v[184:187], v[16:19]
	v_mfma_f32_16x16x32_bf16 v[8:11], v[152:155], v[184:187], v[8:11]
	s_barrier
	s_mov_b32 m0, s71
	v_lshl_add_u64 v[140:141], v[132:133], 0, s[36:37]
	global_load_lds_dwordx4 v[140:141], off
	v_lshl_add_u64 v[132:133], v[132:133], 0, s[38:39]
	s_mov_b32 m0, s70
	s_nop 0
	global_load_lds_dwordx4 v[132:133], off
	s_waitcnt vmcnt(6)
	s_barrier
	v_mfma_f32_16x16x32_bf16 v[52:55], v[188:191], v[156:159], v[52:55]
	v_mfma_f32_16x16x32_bf16 v[44:47], v[196:199], v[156:159], v[44:47]
	v_mfma_f32_16x16x32_bf16 v[36:39], v[188:191], v[164:167], v[36:39]
	v_mfma_f32_16x16x32_bf16 v[28:31], v[196:199], v[164:167], v[28:31]
	v_mfma_f32_16x16x32_bf16 v[20:23], v[188:191], v[172:175], v[20:23]
	v_mfma_f32_16x16x32_bf16 v[12:15], v[196:199], v[172:175], v[12:15]
	v_mfma_f32_16x16x32_bf16 v[4:7], v[188:191], v[180:183], v[4:7]
	v_mfma_f32_16x16x32_bf16 v[0:3], v[196:199], v[180:183], v[0:3]
	v_mfma_f32_16x16x32_bf16 v[52:55], v[192:195], v[160:163], v[52:55]
	v_mfma_f32_16x16x32_bf16 v[44:47], v[200:203], v[160:163], v[44:47]
	v_mfma_f32_16x16x32_bf16 v[36:39], v[192:195], v[168:171], v[36:39]
	v_mfma_f32_16x16x32_bf16 v[28:31], v[200:203], v[168:171], v[28:31]
	v_mfma_f32_16x16x32_bf16 v[20:23], v[192:195], v[176:179], v[20:23]
	v_mfma_f32_16x16x32_bf16 v[12:15], v[200:203], v[176:179], v[12:15]
	v_mfma_f32_16x16x32_bf16 v[4:7], v[192:195], v[184:187], v[4:7]
	v_mfma_f32_16x16x32_bf16 v[0:3], v[200:203], v[184:187], v[0:3]
	s_movk_i32 s70, 0x100
	s_mov_b64 s[54:55], 0
	s_mov_b64 s[52:53], -1
	s_barrier
	s_cbranch_vccz .LBB0_1001
	v_mov_b32_e32 v139, v136
	s_mov_b32 s44, s50
	s_mov_b32 s45, s63
	s_lshl_b32 s46, s69, 8
	s_lshl_b32 s45, s45, 5
	s_add_i32 s45, s45, s46
	v_lshrrev_b32_e32 v132, 1, v139
	v_and_or_b32 v132, v132, 24, s45
	s_lshl_b32 s45, s68, 8
	v_and_or_b32 v139, v139, 15, s45
	v_lshl_add_u32 v140, s44, 6, v139
	v_ashrrev_i32_e32 v133, 31, v132
	v_ashrrev_i32_e32 v141, 31, v140
	v_lshl_add_u64 v[142:143], v[132:133], 1, s[24:25]
	v_lshlrev_b64 v[132:133], 12, v[140:141]
	v_lshl_add_u64 v[132:133], v[142:143], 0, v[132:133]
	v_pk_add_f32 v[126:127], v[126:127], 0 op_sel_hi:[1,0]
	v_pk_add_f32 v[124:125], v[124:125], 0 op_sel_hi:[1,0]
	v_pk_add_f32 v[144:145], v[122:123], 0 op_sel_hi:[1,0]
	v_pk_add_f32 v[122:123], v[120:121], 0 op_sel_hi:[1,0]
	v_cvt_pk_bf16_f32 v120, v124, v125
	v_cvt_pk_bf16_f32 v121, v126, v127
	v_pk_add_f32 v[116:117], v[116:117], 0 op_sel_hi:[1,0]
	v_cvt_pk_bf16_f32 v122, v122, v123
	v_cvt_pk_bf16_f32 v123, v144, v145
	global_store_dwordx4 v[132:133], v[120:123], off
	v_pk_add_f32 v[118:119], v[118:119], 0 op_sel_hi:[1,0]
	v_pk_add_f32 v[112:113], v[112:113], 0 op_sel_hi:[1,0]
	v_pk_add_f32 v[120:121], v[110:111], 0 op_sel_hi:[1,0]
	v_pk_add_f32 v[110:111], v[108:109], 0 op_sel_hi:[1,0]
	v_cvt_pk_bf16_f32 v108, v116, v117
	v_cvt_pk_bf16_f32 v109, v118, v119
	v_pk_add_f32 v[100:101], v[100:101], 0 op_sel_hi:[1,0]
	v_cvt_pk_bf16_f32 v110, v110, v111
	v_cvt_pk_bf16_f32 v111, v120, v121
	global_store_dwordx4 v[132:133], v[108:111], off offset:256
	v_pk_add_f32 v[102:103], v[102:103], 0 op_sel_hi:[1,0]
	v_pk_add_f32 v[96:97], v[96:97], 0 op_sel_hi:[1,0]
	v_or_b32_e32 v108, 16, v140
	v_ashrrev_i32_e32 v109, 31, v108
	v_lshlrev_b64 v[108:109], 12, v[108:109]
	v_lshl_add_u64 v[108:109], v[142:143], 0, v[108:109]
	v_pk_add_f32 v[110:111], v[114:115], 0 op_sel_hi:[1,0]
	v_pk_add_f32 v[114:115], v[106:107], 0 op_sel_hi:[1,0]
	v_pk_add_f32 v[106:107], v[104:105], 0 op_sel_hi:[1,0]
	v_cvt_pk_bf16_f32 v104, v112, v113
	v_cvt_pk_bf16_f32 v105, v110, v111
	v_pk_add_f32 v[84:85], v[84:85], 0 op_sel_hi:[1,0]
	v_cvt_pk_bf16_f32 v106, v106, v107
	v_cvt_pk_bf16_f32 v107, v114, v115
	global_store_dwordx4 v[108:109], v[104:107], off
	v_pk_add_f32 v[86:87], v[86:87], 0 op_sel_hi:[1,0]
	v_pk_add_f32 v[80:81], v[80:81], 0 op_sel_hi:[1,0]
	v_pk_add_f32 v[104:105], v[94:95], 0 op_sel_hi:[1,0]
	v_pk_add_f32 v[94:95], v[92:93], 0 op_sel_hi:[1,0]
	v_cvt_pk_bf16_f32 v92, v100, v101
	v_cvt_pk_bf16_f32 v93, v102, v103
	v_pk_add_f32 v[70:71], v[70:71], 0 op_sel_hi:[1,0]
	v_cvt_pk_bf16_f32 v94, v94, v95
	v_cvt_pk_bf16_f32 v95, v104, v105
	global_store_dwordx4 v[108:109], v[92:95], off offset:256
	v_pk_add_f32 v[68:69], v[68:69], 0 op_sel_hi:[1,0]
	s_mov_b64 s[44:45], 0x80000
	v_or_b32_e32 v92, 32, v140
	v_ashrrev_i32_e32 v93, 31, v92
	v_lshlrev_b64 v[92:93], 12, v[92:93]
	v_lshl_add_u64 v[92:93], v[142:143], 0, v[92:93]
	v_pk_add_f32 v[94:95], v[98:99], 0 op_sel_hi:[1,0]
	v_pk_add_f32 v[98:99], v[90:91], 0 op_sel_hi:[1,0]
	v_pk_add_f32 v[90:91], v[88:89], 0 op_sel_hi:[1,0]
	v_cvt_pk_bf16_f32 v88, v96, v97
	v_cvt_pk_bf16_f32 v89, v94, v95
	v_pk_add_f32 v[60:61], v[60:61], 0 op_sel_hi:[1,0]
	v_cvt_pk_bf16_f32 v90, v90, v91
	v_cvt_pk_bf16_f32 v91, v98, v99
	global_store_dwordx4 v[92:93], v[88:91], off
	v_pk_add_f32 v[62:63], v[62:63], 0 op_sel_hi:[1,0]
	v_pk_add_f32 v[54:55], v[54:55], 0 op_sel_hi:[1,0]
	v_pk_add_f32 v[88:89], v[78:79], 0 op_sel_hi:[1,0]
	v_pk_add_f32 v[78:79], v[76:77], 0 op_sel_hi:[1,0]
	v_cvt_pk_bf16_f32 v76, v84, v85
	v_cvt_pk_bf16_f32 v77, v86, v87
	v_pk_add_f32 v[52:53], v[52:53], 0 op_sel_hi:[1,0]
	v_cvt_pk_bf16_f32 v78, v78, v79
	v_cvt_pk_bf16_f32 v79, v88, v89
	global_store_dwordx4 v[92:93], v[76:79], off offset:256
	v_pk_add_f32 v[48:49], v[48:49], 0 op_sel_hi:[1,0]
	v_pk_add_f32 v[38:39], v[38:39], 0 op_sel_hi:[1,0]
	v_or_b32_e32 v76, 48, v140
	v_ashrrev_i32_e32 v77, 31, v76
	v_lshlrev_b64 v[76:77], 12, v[76:77]
	v_lshl_add_u64 v[76:77], v[142:143], 0, v[76:77]
	v_pk_add_f32 v[78:79], v[82:83], 0 op_sel_hi:[1,0]
	v_pk_add_f32 v[82:83], v[74:75], 0 op_sel_hi:[1,0]
	v_pk_add_f32 v[74:75], v[72:73], 0 op_sel_hi:[1,0]
	v_cvt_pk_bf16_f32 v72, v80, v81
	v_cvt_pk_bf16_f32 v73, v78, v79
	v_pk_add_f32 v[36:37], v[36:37], 0 op_sel_hi:[1,0]
	v_cvt_pk_bf16_f32 v74, v74, v75
	v_cvt_pk_bf16_f32 v75, v82, v83
	global_store_dwordx4 v[76:77], v[72:75], off
	v_pk_add_f32 v[32:33], v[32:33], 0 op_sel_hi:[1,0]
	v_pk_add_f32 v[22:23], v[22:23], 0 op_sel_hi:[1,0]
	v_pk_add_f32 v[72:73], v[66:67], 0 op_sel_hi:[1,0]
	v_pk_add_f32 v[66:67], v[64:65], 0 op_sel_hi:[1,0]
	v_cvt_pk_bf16_f32 v64, v68, v69
	v_cvt_pk_bf16_f32 v65, v70, v71
	v_pk_add_f32 v[20:21], v[20:21], 0 op_sel_hi:[1,0]
	v_cvt_pk_bf16_f32 v66, v66, v67
	v_cvt_pk_bf16_f32 v67, v72, v73
	global_store_dwordx4 v[76:77], v[64:67], off offset:256
	v_pk_add_f32 v[16:17], v[16:17], 0 op_sel_hi:[1,0]
	v_pk_add_f32 v[6:7], v[6:7], 0 op_sel_hi:[1,0]
	v_lshl_add_u64 v[64:65], v[132:133], 0, s[44:45]
	s_mov_b32 s44, 0x80000
	v_pk_add_f32 v[66:67], v[58:59], 0 op_sel_hi:[1,0]
	v_pk_add_f32 v[58:59], v[56:57], 0 op_sel_hi:[1,0]
	v_cvt_pk_bf16_f32 v56, v60, v61
	v_add_co_u32_e32 v60, vcc, s44, v132
	v_cvt_pk_bf16_f32 v57, v62, v63
	v_cvt_pk_bf16_f32 v58, v58, v59
	v_cvt_pk_bf16_f32 v59, v66, v67
	s_mov_b64 s[44:45], 0x90000
	s_nop 0
	v_addc_co_u32_e32 v61, vcc, 0, v133, vcc
	global_store_dwordx4 v[60:61], v[56:59], off
	v_pk_add_f32 v[4:5], v[4:5], 0 op_sel_hi:[1,0]
	s_nop 0
	v_pk_add_f32 v[56:57], v[46:47], 0 op_sel_hi:[1,0]
	v_pk_add_f32 v[46:47], v[44:45], 0 op_sel_hi:[1,0]
	v_cvt_pk_bf16_f32 v44, v52, v53
	v_cvt_pk_bf16_f32 v45, v54, v55
	s_nop 0
	v_cvt_pk_bf16_f32 v46, v46, v47
	v_cvt_pk_bf16_f32 v47, v56, v57
	global_store_dwordx4 v[64:65], v[44:47], off offset:256
	s_nop 1
	v_lshl_add_u64 v[44:45], v[132:133], 0, s[44:45]
	v_pk_add_f32 v[46:47], v[50:51], 0 op_sel_hi:[1,0]
	s_mov_b32 s44, 0x90000
	v_pk_add_f32 v[50:51], v[42:43], 0 op_sel_hi:[1,0]
	v_pk_add_f32 v[42:43], v[40:41], 0 op_sel_hi:[1,0]
	v_cvt_pk_bf16_f32 v40, v48, v49
	v_cvt_pk_bf16_f32 v41, v46, v47
	v_add_co_u32_e32 v46, vcc, s44, v132
	v_cvt_pk_bf16_f32 v42, v42, v43
	v_cvt_pk_bf16_f32 v43, v50, v51
	s_mov_b64 s[44:45], 0xa0000
	s_nop 0
	v_addc_co_u32_e32 v47, vcc, 0, v133, vcc
	global_store_dwordx4 v[46:47], v[40:43], off
	s_nop 1
	v_pk_add_f32 v[40:41], v[30:31], 0 op_sel_hi:[1,0]
	v_pk_add_f32 v[30:31], v[28:29], 0 op_sel_hi:[1,0]
	v_cvt_pk_bf16_f32 v28, v36, v37
	v_cvt_pk_bf16_f32 v29, v38, v39
	s_nop 0
	v_cvt_pk_bf16_f32 v30, v30, v31
	v_cvt_pk_bf16_f32 v31, v40, v41
	global_store_dwordx4 v[44:45], v[28:31], off offset:256
	s_nop 1
	v_lshl_add_u64 v[28:29], v[132:133], 0, s[44:45]
	v_pk_add_f32 v[30:31], v[34:35], 0 op_sel_hi:[1,0]
	s_mov_b32 s44, 0xa0000
	v_pk_add_f32 v[34:35], v[26:27], 0 op_sel_hi:[1,0]
	v_pk_add_f32 v[26:27], v[24:25], 0 op_sel_hi:[1,0]
	v_cvt_pk_bf16_f32 v24, v32, v33
	v_cvt_pk_bf16_f32 v25, v30, v31
	v_add_co_u32_e32 v30, vcc, s44, v132
	v_cvt_pk_bf16_f32 v26, v26, v27
	v_cvt_pk_bf16_f32 v27, v34, v35
	s_mov_b64 s[44:45], 0xb0000
	s_nop 0
	v_addc_co_u32_e32 v31, vcc, 0, v133, vcc
	global_store_dwordx4 v[30:31], v[24:27], off
	s_nop 1
	v_pk_add_f32 v[24:25], v[14:15], 0 op_sel_hi:[1,0]
	v_pk_add_f32 v[14:15], v[12:13], 0 op_sel_hi:[1,0]
	v_cvt_pk_bf16_f32 v12, v20, v21
	v_cvt_pk_bf16_f32 v13, v22, v23
	s_nop 0
	v_cvt_pk_bf16_f32 v14, v14, v15
	v_cvt_pk_bf16_f32 v15, v24, v25
	global_store_dwordx4 v[28:29], v[12:15], off offset:256
	s_nop 1
	v_lshl_add_u64 v[12:13], v[132:133], 0, s[44:45]
	v_pk_add_f32 v[14:15], v[18:19], 0 op_sel_hi:[1,0]
	s_mov_b32 s44, 0xb0000
	v_pk_add_f32 v[18:19], v[10:11], 0 op_sel_hi:[1,0]
	v_pk_add_f32 v[10:11], v[8:9], 0 op_sel_hi:[1,0]
	v_cvt_pk_bf16_f32 v8, v16, v17
	v_cvt_pk_bf16_f32 v9, v14, v15
	v_add_co_u32_e32 v14, vcc, s44, v132
	v_cvt_pk_bf16_f32 v10, v10, v11
	v_cvt_pk_bf16_f32 v11, v18, v19
	s_mov_b32 s44, s62
	s_nop 0
	v_addc_co_u32_e32 v15, vcc, 0, v133, vcc
	global_store_dwordx4 v[14:15], v[8:11], off
	s_nop 1
	v_pk_add_f32 v[8:9], v[2:3], 0 op_sel_hi:[1,0]
	v_pk_add_f32 v[2:3], v[0:1], 0 op_sel_hi:[1,0]
	v_cvt_pk_bf16_f32 v0, v4, v5
	v_cvt_pk_bf16_f32 v1, v6, v7
	s_nop 0
	v_cvt_pk_bf16_f32 v2, v2, v3
	v_cvt_pk_bf16_f32 v3, v8, v9
	global_store_dwordx4 v[12:13], v[0:3], off offset:256
	s_mul_i32 s46, s44, s13
	s_add_i32 s46, s46, s15
	s_cmpk_gt_i32 s46, 0x10f
	s_mov_b64 s[44:45], -1
	s_cbranch_scc1 .LBB0_997
	s_ashr_i32 s44, s46, 31
	s_lshr_b32 s44, s44, 29
	s_add_i32 s44, s46, s44
	s_ashr_i32 s45, s44, 3
	s_and_b32 s44, s44, -8
	s_sub_i32 s44, s46, s44
	s_cmp_lt_i32 s44, 0
	s_cselect_b32 s46, 35, 34
	s_mul_i32 s44, s46, s44
	s_add_i32 s44, s44, s45
	s_ashr_i32 s45, s44, 31
	s_lshr_b32 s45, s45, 26
	s_add_i32 s45, s44, s45
	s_ashr_i32 s46, s45, 6
	s_lshl_b32 s46, s46, 3
	s_sub_i32 s47, 34, s46
	s_min_u32 s47, s47, 8
	s_andn2_b32 s45, s45, 63
	s_sub_i32 s52, s44, s45
	v_cvt_f32_ubyte0_e32 v1, s47
	v_cvt_f32_i32_e32 v0, s52
	v_rcp_iflag_f32_e32 v2, v1
	s_ashr_i32 s44, s52, 30
	s_or_b32 s53, s44, 1
	v_mul_f32_e32 v2, v0, v2
	v_trunc_f32_e32 v2, v2
	v_fma_f32 v0, -v2, v1, v0
	v_cvt_i32_f32_e32 v2, v2
	v_cmp_ge_f32_e64 s[44:45], |v0|, v1
	s_and_b64 s[44:45], s[44:45], exec
	s_cselect_b32 s44, s53, 0
	v_readfirstlane_b32 s45, v2
	s_add_i32 s44, s45, s44
	s_sext_i32_i8 s69, s44
	s_mul_i32 s44, s44, s47
	s_sub_i32 s44, s52, s44
	s_sext_i32_i8 s44, s44
	s_add_i32 s68, s46, s44
	s_mov_b64 s[44:45], 0
	s_branch .LBB0_997

.LBB0_1022:
	ds_read_b128 v[142:145], v138
	ds_read_b128 v[146:149], v138 offset:1024
	ds_read_b128 v[150:153], v138 offset:2048
	ds_read_b128 v[154:157], v138 offset:3072
	s_add_u32 s55, s46, 0xfffe0080
	s_addc_u32 s65, s47, -1
	s_cmp_eq_u32 s54, 4
	s_cselect_b32 s67, s45, s65
	s_cselect_b32 s66, s44, s55
	s_cselect_b32 s69, s43, s53
	s_cselect_b32 s68, s42, s52
	v_lshl_add_u64 v[190:191], s[46:47], 0, v[134:135]
	s_add_i32 m0, s33, 0xc000
	ds_read_b128 v[158:161], v139
	ds_read_b128 v[162:165], v139 offset:1024
	ds_read_b128 v[166:169], v139 offset:2048
	ds_read_b128 v[170:173], v139 offset:3072
	ds_read_b128 v[174:177], v139 offset:4096
	ds_read_b128 v[178:181], v139 offset:5120
	ds_read_b128 v[182:185], v139 offset:6144
	ds_read_b128 v[186:189], v139 offset:7168
	global_load_lds_dwordx4 v[190:191], off
	v_lshl_add_u64 v[190:191], v[190:191], 0, s[16:17]
	s_add_i32 m0, s33, 0xe000
	s_nop 0
	global_load_lds_dwordx4 v[190:191], off
	s_waitcnt lgkmcnt(8)
	s_barrier
	s_waitcnt lgkmcnt(0)
	s_waitcnt lgkmcnt(0)
	v_mfma_f32_16x16x32_bf16 v[124:127], v[142:145], v[158:161], v[124:127]
	v_mfma_f32_16x16x32_bf16 v[120:123], v[150:153], v[158:161], v[120:123]
	v_mfma_f32_16x16x32_bf16 v[112:115], v[142:145], v[166:169], v[112:115]
	v_mfma_f32_16x16x32_bf16 v[104:107], v[150:153], v[166:169], v[104:107]
	v_mfma_f32_16x16x32_bf16 v[96:99], v[142:145], v[174:177], v[96:99]
	v_mfma_f32_16x16x32_bf16 v[88:91], v[150:153], v[174:177], v[88:91]
	v_mfma_f32_16x16x32_bf16 v[80:83], v[142:145], v[182:185], v[80:83]
	v_mfma_f32_16x16x32_bf16 v[72:75], v[150:153], v[182:185], v[72:75]
	v_mfma_f32_16x16x32_bf16 v[124:127], v[146:149], v[162:165], v[124:127]
	v_mfma_f32_16x16x32_bf16 v[120:123], v[154:157], v[162:165], v[120:123]
	v_mfma_f32_16x16x32_bf16 v[112:115], v[146:149], v[170:173], v[112:115]
	v_mfma_f32_16x16x32_bf16 v[104:107], v[154:157], v[170:173], v[104:107]
	v_mfma_f32_16x16x32_bf16 v[96:99], v[146:149], v[178:181], v[96:99]
	v_mfma_f32_16x16x32_bf16 v[88:91], v[154:157], v[178:181], v[88:91]
	v_mfma_f32_16x16x32_bf16 v[80:83], v[146:149], v[186:189], v[80:83]
	v_mfma_f32_16x16x32_bf16 v[72:75], v[154:157], v[186:189], v[72:75]
	s_barrier
	s_add_i32 s55, s61, s31
	v_lshl_add_u64 v[206:207], s[68:69], 0, v[128:129]
	s_mov_b32 m0, s55
	ds_read_b128 v[190:193], v140
	ds_read_b128 v[194:197], v140 offset:1024
	ds_read_b128 v[198:201], v140 offset:2048
	ds_read_b128 v[202:205], v140 offset:3072
	global_load_lds_dwordx4 v[206:207], off
	v_lshl_add_u64 v[208:209], v[206:207], 0, s[10:11]
	s_add_i32 m0, s55, 0x2000
	s_nop 0
	global_load_lds_dwordx4 v[208:209], off
	s_barrier
	s_waitcnt lgkmcnt(0)
	s_waitcnt lgkmcnt(0)
	v_mfma_f32_16x16x32_bf16 v[116:119], v[190:193], v[158:161], v[116:119]
	v_mfma_f32_16x16x32_bf16 v[108:111], v[198:201], v[158:161], v[108:111]
	v_mfma_f32_16x16x32_bf16 v[100:103], v[190:193], v[166:169], v[100:103]
	v_mfma_f32_16x16x32_bf16 v[92:95], v[198:201], v[166:169], v[92:95]
	v_mfma_f32_16x16x32_bf16 v[84:87], v[190:193], v[174:177], v[84:87]
	v_mfma_f32_16x16x32_bf16 v[76:79], v[198:201], v[174:177], v[76:79]
	v_mfma_f32_16x16x32_bf16 v[68:71], v[190:193], v[182:185], v[68:71]
	v_mfma_f32_16x16x32_bf16 v[64:67], v[198:201], v[182:185], v[64:67]
	v_mfma_f32_16x16x32_bf16 v[116:119], v[194:197], v[162:165], v[116:119]
	v_mfma_f32_16x16x32_bf16 v[108:111], v[202:205], v[162:165], v[108:111]
	v_mfma_f32_16x16x32_bf16 v[100:103], v[194:197], v[170:173], v[100:103]
	v_mfma_f32_16x16x32_bf16 v[92:95], v[202:205], v[170:173], v[92:95]
	v_mfma_f32_16x16x32_bf16 v[84:87], v[194:197], v[178:181], v[84:87]
	v_mfma_f32_16x16x32_bf16 v[76:79], v[202:205], v[178:181], v[76:79]
	v_mfma_f32_16x16x32_bf16 v[68:71], v[194:197], v[186:189], v[68:71]
	v_mfma_f32_16x16x32_bf16 v[64:67], v[202:205], v[186:189], v[64:67]
	s_mov_b32 m0, s33
	v_lshl_add_u64 v[208:209], s[66:67], 0, v[130:131]
	s_barrier
	ds_read_b128 v[158:161], v139 offset:16384
	ds_read_b128 v[162:165], v139 offset:17408
	ds_read_b128 v[166:169], v139 offset:18432
	ds_read_b128 v[170:173], v139 offset:19456
	ds_read_b128 v[174:177], v139 offset:20480
	ds_read_b128 v[178:181], v139 offset:21504
	ds_read_b128 v[182:185], v139 offset:22528
	ds_read_b128 v[186:189], v139 offset:23552
	global_load_lds_dwordx4 v[208:209], off
	v_lshl_add_u64 v[210:211], v[208:209], 0, s[16:17]
	s_mov_b32 m0, s48
	s_nop 0
	global_load_lds_dwordx4 v[210:211], off
	s_barrier
	s_waitcnt lgkmcnt(0)
	s_waitcnt lgkmcnt(0)
	v_mfma_f32_16x16x32_bf16 v[60:63], v[142:145], v[158:161], v[60:63]
	v_mfma_f32_16x16x32_bf16 v[56:59], v[150:153], v[158:161], v[56:59]
	v_mfma_f32_16x16x32_bf16 v[52:55], v[142:145], v[166:169], v[52:55]
	v_mfma_f32_16x16x32_bf16 v[44:47], v[150:153], v[166:169], v[44:47]
	v_mfma_f32_16x16x32_bf16 v[36:39], v[142:145], v[174:177], v[36:39]
	v_mfma_f32_16x16x32_bf16 v[28:31], v[150:153], v[174:177], v[28:31]
	v_mfma_f32_16x16x32_bf16 v[20:23], v[142:145], v[182:185], v[20:23]
	v_mfma_f32_16x16x32_bf16 v[12:15], v[150:153], v[182:185], v[12:15]
	v_mfma_f32_16x16x32_bf16 v[60:63], v[146:149], v[162:165], v[60:63]
	v_mfma_f32_16x16x32_bf16 v[56:59], v[154:157], v[162:165], v[56:59]
	v_mfma_f32_16x16x32_bf16 v[52:55], v[146:149], v[170:173], v[52:55]
	v_mfma_f32_16x16x32_bf16 v[44:47], v[154:157], v[170:173], v[44:47]
	v_mfma_f32_16x16x32_bf16 v[36:39], v[146:149], v[178:181], v[36:39]
	v_mfma_f32_16x16x32_bf16 v[28:31], v[154:157], v[178:181], v[28:31]
	v_mfma_f32_16x16x32_bf16 v[20:23], v[146:149], v[186:189], v[20:23]
	v_mfma_f32_16x16x32_bf16 v[12:15], v[154:157], v[186:189], v[12:15]
	s_barrier
	s_add_i32 s55, s62, s31
	v_lshl_add_u64 v[142:143], v[206:207], 0, s[18:19]
	s_mov_b32 m0, s55
	s_nop 0
	global_load_lds_dwordx4 v[142:143], off
	v_lshl_add_u64 v[142:143], v[206:207], 0, s[20:21]
	s_add_i32 m0, s55, 0x2000
	s_nop 0
	global_load_lds_dwordx4 v[142:143], off
	s_waitcnt vmcnt(6)
	s_barrier
	v_mfma_f32_16x16x32_bf16 v[48:51], v[190:193], v[158:161], v[48:51]
	v_mfma_f32_16x16x32_bf16 v[40:43], v[198:201], v[158:161], v[40:43]
	v_mfma_f32_16x16x32_bf16 v[32:35], v[190:193], v[166:169], v[32:35]
	v_mfma_f32_16x16x32_bf16 v[24:27], v[198:201], v[166:169], v[24:27]
	v_mfma_f32_16x16x32_bf16 v[16:19], v[190:193], v[174:177], v[16:19]
	v_mfma_f32_16x16x32_bf16 v[8:11], v[198:201], v[174:177], v[8:11]
	v_mfma_f32_16x16x32_bf16 v[4:7], v[190:193], v[182:185], v[4:7]
	v_mfma_f32_16x16x32_bf16 v[0:3], v[198:201], v[182:185], v[0:3]
	v_mfma_f32_16x16x32_bf16 v[48:51], v[194:197], v[162:165], v[48:51]
	v_mfma_f32_16x16x32_bf16 v[40:43], v[202:205], v[162:165], v[40:43]
	v_mfma_f32_16x16x32_bf16 v[32:35], v[194:197], v[170:173], v[32:35]
	v_mfma_f32_16x16x32_bf16 v[24:27], v[202:205], v[170:173], v[24:27]
	v_mfma_f32_16x16x32_bf16 v[16:19], v[194:197], v[178:181], v[16:19]
	v_mfma_f32_16x16x32_bf16 v[8:11], v[202:205], v[178:181], v[8:11]
	v_mfma_f32_16x16x32_bf16 v[4:7], v[194:197], v[186:189], v[4:7]
	v_mfma_f32_16x16x32_bf16 v[0:3], v[202:205], v[186:189], v[0:3]
	s_add_i32 s55, 0, 0x18000
	v_add_u32_e32 v132, s55, v137
	s_barrier
	ds_read_b128 v[142:145], v132
	ds_read_b128 v[146:149], v132 offset:1024
	ds_read_b128 v[150:153], v132 offset:2048
	ds_read_b128 v[154:157], v132 offset:3072
	s_mov_b32 m0, s49
	v_lshl_add_u64 v[190:191], v[208:209], 0, s[22:23]
	ds_read_b128 v[158:161], v139 offset:32768
	ds_read_b128 v[162:165], v139 offset:33792
	ds_read_b128 v[166:169], v139 offset:34816
	ds_read_b128 v[170:173], v139 offset:35840
	ds_read_b128 v[174:177], v139 offset:36864
	ds_read_b128 v[178:181], v139 offset:37888
	ds_read_b128 v[182:185], v139 offset:38912
	ds_read_b128 v[186:189], v139 offset:39936
	global_load_lds_dwordx4 v[190:191], off
	v_lshl_add_u64 v[190:191], v[208:209], 0, s[24:25]
	s_mov_b32 m0, s50
	s_nop 0
	global_load_lds_dwordx4 v[190:191], off
	s_waitcnt lgkmcnt(8)
	s_barrier
	s_waitcnt lgkmcnt(0)
	s_waitcnt lgkmcnt(0)
	v_mfma_f32_16x16x32_bf16 v[124:127], v[142:145], v[158:161], v[124:127]
	v_mfma_f32_16x16x32_bf16 v[120:123], v[150:153], v[158:161], v[120:123]
	v_mfma_f32_16x16x32_bf16 v[112:115], v[142:145], v[166:169], v[112:115]
	v_mfma_f32_16x16x32_bf16 v[104:107], v[150:153], v[166:169], v[104:107]
	v_mfma_f32_16x16x32_bf16 v[96:99], v[142:145], v[174:177], v[96:99]
	v_mfma_f32_16x16x32_bf16 v[88:91], v[150:153], v[174:177], v[88:91]
	v_mfma_f32_16x16x32_bf16 v[80:83], v[142:145], v[182:185], v[80:83]
	v_mfma_f32_16x16x32_bf16 v[72:75], v[150:153], v[182:185], v[72:75]
	v_mfma_f32_16x16x32_bf16 v[124:127], v[146:149], v[162:165], v[124:127]
	v_mfma_f32_16x16x32_bf16 v[120:123], v[154:157], v[162:165], v[120:123]
	v_mfma_f32_16x16x32_bf16 v[112:115], v[146:149], v[170:173], v[112:115]
	v_mfma_f32_16x16x32_bf16 v[104:107], v[154:157], v[170:173], v[104:107]
	v_mfma_f32_16x16x32_bf16 v[96:99], v[146:149], v[178:181], v[96:99]
	v_mfma_f32_16x16x32_bf16 v[88:91], v[154:157], v[178:181], v[88:91]
	v_mfma_f32_16x16x32_bf16 v[80:83], v[146:149], v[186:189], v[80:83]
	v_mfma_f32_16x16x32_bf16 v[72:75], v[154:157], v[186:189], v[72:75]
	s_barrier
	s_add_i32 s65, 0, 0x1c000
	s_add_i32 s55, s55, s31
	v_add_u32_e32 v132, s65, v137
	v_lshl_add_u64 v[210:211], v[206:207], 0, s[26:27]
	s_mov_b32 m0, s55
	ds_read_b128 v[190:193], v132
	ds_read_b128 v[194:197], v132 offset:1024
	ds_read_b128 v[198:201], v132 offset:2048
	ds_read_b128 v[202:205], v132 offset:3072
	global_load_lds_dwordx4 v[210:211], off
	v_lshl_add_u64 v[210:211], v[206:207], 0, s[28:29]
	s_add_i32 m0, s55, 0x2000
	s_nop 0
	global_load_lds_dwordx4 v[210:211], off
	s_barrier
	s_waitcnt lgkmcnt(0)
	s_waitcnt lgkmcnt(0)
	v_mfma_f32_16x16x32_bf16 v[116:119], v[190:193], v[158:161], v[116:119]
	v_mfma_f32_16x16x32_bf16 v[108:111], v[198:201], v[158:161], v[108:111]
	v_mfma_f32_16x16x32_bf16 v[100:103], v[190:193], v[166:169], v[100:103]
	v_mfma_f32_16x16x32_bf16 v[92:95], v[198:201], v[166:169], v[92:95]
	v_mfma_f32_16x16x32_bf16 v[84:87], v[190:193], v[174:177], v[84:87]
	v_mfma_f32_16x16x32_bf16 v[76:79], v[198:201], v[174:177], v[76:79]
	v_mfma_f32_16x16x32_bf16 v[68:71], v[190:193], v[182:185], v[68:71]
	v_mfma_f32_16x16x32_bf16 v[64:67], v[198:201], v[182:185], v[64:67]
	v_mfma_f32_16x16x32_bf16 v[116:119], v[194:197], v[162:165], v[116:119]
	v_mfma_f32_16x16x32_bf16 v[108:111], v[202:205], v[162:165], v[108:111]
	v_mfma_f32_16x16x32_bf16 v[100:103], v[194:197], v[170:173], v[100:103]
	v_mfma_f32_16x16x32_bf16 v[92:95], v[202:205], v[170:173], v[92:95]
	v_mfma_f32_16x16x32_bf16 v[84:87], v[194:197], v[178:181], v[84:87]
	v_mfma_f32_16x16x32_bf16 v[76:79], v[202:205], v[178:181], v[76:79]
	v_mfma_f32_16x16x32_bf16 v[68:71], v[194:197], v[186:189], v[68:71]
	v_mfma_f32_16x16x32_bf16 v[64:67], v[202:205], v[186:189], v[64:67]
	s_mov_b32 m0, s56
	v_lshl_add_u64 v[210:211], v[208:209], 0, s[26:27]
	s_barrier
	ds_read_b128 v[158:161], v139 offset:49152
	ds_read_b128 v[162:165], v139 offset:50176
	ds_read_b128 v[166:169], v139 offset:51200
	ds_read_b128 v[170:173], v139 offset:52224
	ds_read_b128 v[174:177], v139 offset:53248
	ds_read_b128 v[178:181], v139 offset:54272
	ds_read_b128 v[182:185], v139 offset:55296
	ds_read_b128 v[186:189], v139 offset:56320
	global_load_lds_dwordx4 v[210:211], off
	v_lshl_add_u64 v[208:209], v[208:209], 0, s[34:35]
	s_mov_b32 m0, s57
	s_nop 0
	global_load_lds_dwordx4 v[208:209], off
	s_barrier
	s_waitcnt lgkmcnt(0)
	s_waitcnt lgkmcnt(0)
	v_mfma_f32_16x16x32_bf16 v[60:63], v[142:145], v[158:161], v[60:63]
	v_mfma_f32_16x16x32_bf16 v[56:59], v[150:153], v[158:161], v[56:59]
	v_mfma_f32_16x16x32_bf16 v[52:55], v[142:145], v[166:169], v[52:55]
	v_mfma_f32_16x16x32_bf16 v[44:47], v[150:153], v[166:169], v[44:47]
	v_mfma_f32_16x16x32_bf16 v[36:39], v[142:145], v[174:177], v[36:39]
	v_mfma_f32_16x16x32_bf16 v[28:31], v[150:153], v[174:177], v[28:31]
	v_mfma_f32_16x16x32_bf16 v[20:23], v[142:145], v[182:185], v[20:23]
	v_mfma_f32_16x16x32_bf16 v[12:15], v[150:153], v[182:185], v[12:15]
	v_mfma_f32_16x16x32_bf16 v[60:63], v[146:149], v[162:165], v[60:63]
	v_mfma_f32_16x16x32_bf16 v[56:59], v[154:157], v[162:165], v[56:59]
	v_mfma_f32_16x16x32_bf16 v[52:55], v[146:149], v[170:173], v[52:55]
	v_mfma_f32_16x16x32_bf16 v[44:47], v[154:157], v[170:173], v[44:47]
	v_mfma_f32_16x16x32_bf16 v[36:39], v[146:149], v[178:181], v[36:39]
	v_mfma_f32_16x16x32_bf16 v[28:31], v[154:157], v[178:181], v[28:31]
	v_mfma_f32_16x16x32_bf16 v[20:23], v[146:149], v[186:189], v[20:23]
	v_mfma_f32_16x16x32_bf16 v[12:15], v[154:157], v[186:189], v[12:15]
	s_barrier
	s_add_i32 s55, s65, s31
	v_lshl_add_u64 v[142:143], v[206:207], 0, s[36:37]
	s_mov_b32 m0, s55
	s_nop 0
	global_load_lds_dwordx4 v[142:143], off
	v_lshl_add_u64 v[142:143], v[206:207], 0, s[38:39]
	s_add_i32 m0, s55, 0x2000
	s_nop 0
	global_load_lds_dwordx4 v[142:143], off
	s_waitcnt vmcnt(6)
	s_barrier
	v_mfma_f32_16x16x32_bf16 v[48:51], v[190:193], v[158:161], v[48:51]
	v_mfma_f32_16x16x32_bf16 v[40:43], v[198:201], v[158:161], v[40:43]
	v_mfma_f32_16x16x32_bf16 v[32:35], v[190:193], v[166:169], v[32:35]
	v_mfma_f32_16x16x32_bf16 v[24:27], v[198:201], v[166:169], v[24:27]
	v_mfma_f32_16x16x32_bf16 v[16:19], v[190:193], v[174:177], v[16:19]
	v_mfma_f32_16x16x32_bf16 v[8:11], v[198:201], v[174:177], v[8:11]
	v_mfma_f32_16x16x32_bf16 v[4:7], v[190:193], v[182:185], v[4:7]
	v_mfma_f32_16x16x32_bf16 v[0:3], v[198:201], v[182:185], v[0:3]
	v_mfma_f32_16x16x32_bf16 v[48:51], v[194:197], v[162:165], v[48:51]
	v_mfma_f32_16x16x32_bf16 v[40:43], v[202:205], v[162:165], v[40:43]
	v_mfma_f32_16x16x32_bf16 v[32:35], v[194:197], v[170:173], v[32:35]
	v_mfma_f32_16x16x32_bf16 v[24:27], v[202:205], v[170:173], v[24:27]
	v_mfma_f32_16x16x32_bf16 v[16:19], v[194:197], v[178:181], v[16:19]
	v_mfma_f32_16x16x32_bf16 v[8:11], v[202:205], v[178:181], v[8:11]
	v_mfma_f32_16x16x32_bf16 v[4:7], v[194:197], v[186:189], v[4:7]
	v_mfma_f32_16x16x32_bf16 v[0:3], v[202:205], v[186:189], v[0:3]
	s_add_i32 s54, s54, 2
	s_add_u32 s46, s46, 0x100
	s_addc_u32 s47, s47, 0
	s_add_u32 s52, s52, 0x100
	s_addc_u32 s53, s53, 0
	s_cmp_gt_u32 s54, 5
	s_barrier
	s_cbranch_scc0 .LBB0_1022
	s_lshl_b32 s52, s64, 5
	s_and_b32 s52, s52, 0xfffffe00
	s_lshl_b32 s53, s63, 7
	v_mov_b32_e32 v132, v136
	s_mov_b32 s46, s58
	s_mov_b32 s47, s30
	s_add_i32 s52, s52, s53
	v_cvt_pk_bf16_f32 v124, v124, v125
	v_cvt_pk_bf16_f32 v125, v126, v127
	v_cvt_pk_bf16_f32 v126, v120, v121
	v_cvt_pk_bf16_f32 v127, v122, v123
	s_nop 0
	v_and_or_b32 v141, v132, 15, s52
	v_lshl_add_u32 v142, s47, 6, v141
	s_lshl_b32 s47, s64, 9
	s_and_b32 s47, s47, 0x1e00
	s_add_u32 s52, s59, s47
	s_addc_u32 s53, s60, 0
	s_lshl_b32 s46, s46, 5
	s_ashr_i32 s47, s46, 31
	s_lshl_b64 s[46:47], s[46:47], 1
	s_add_u32 s46, s52, s46
	s_addc_u32 s47, s53, s47
	v_and_b32_e32 v132, 48, v132
	v_ashrrev_i32_e32 v143, 31, v142
	v_lshl_add_u64 v[144:145], s[46:47], 0, v[132:133]
	v_lshlrev_b64 v[146:147], 14, v[142:143]
	v_lshl_add_u64 v[148:149], v[144:145], 0, v[146:147]
	global_store_dwordx4 v[148:149], v[124:127], off
	v_cvt_pk_bf16_f32 v116, v116, v117
	v_cvt_pk_bf16_f32 v117, v118, v119
	v_cvt_pk_bf16_f32 v118, v108, v109
	v_or_b32_e32 v108, 16, v142
	v_ashrrev_i32_e32 v109, 31, v108
	v_cvt_pk_bf16_f32 v119, v110, v111
	global_store_dwordx4 v[148:149], v[116:119], off offset:256
	s_mov_b32 s46, s51
	s_nop 0
	v_lshlrev_b64 v[116:117], 14, v[108:109]
	v_lshl_add_u64 v[118:119], v[144:145], 0, v[116:117]
	v_cvt_pk_bf16_f32 v108, v112, v113
	v_cvt_pk_bf16_f32 v109, v114, v115
	v_cvt_pk_bf16_f32 v110, v104, v105
	v_cvt_pk_bf16_f32 v111, v106, v107
	global_store_dwordx4 v[118:119], v[108:111], off
	v_cvt_pk_bf16_f32 v100, v100, v101
	v_cvt_pk_bf16_f32 v101, v102, v103
	v_cvt_pk_bf16_f32 v102, v92, v93
	v_or_b32_e32 v92, 32, v142
	v_ashrrev_i32_e32 v93, 31, v92
	v_cvt_pk_bf16_f32 v103, v94, v95
	global_store_dwordx4 v[118:119], v[100:103], off offset:256
	s_nop 1
	v_lshlrev_b64 v[100:101], 14, v[92:93]
	v_lshl_add_u64 v[102:103], v[144:145], 0, v[100:101]
	v_cvt_pk_bf16_f32 v92, v96, v97
	v_cvt_pk_bf16_f32 v93, v98, v99
	v_cvt_pk_bf16_f32 v94, v88, v89
	v_cvt_pk_bf16_f32 v95, v90, v91
	global_store_dwordx4 v[102:103], v[92:95], off
	v_cvt_pk_bf16_f32 v84, v84, v85
	v_cvt_pk_bf16_f32 v85, v86, v87
	v_cvt_pk_bf16_f32 v86, v76, v77
	v_or_b32_e32 v76, 48, v142
	v_ashrrev_i32_e32 v77, 31, v76
	v_cvt_pk_bf16_f32 v87, v78, v79
	global_store_dwordx4 v[102:103], v[84:87], off offset:256
	s_nop 1
	v_lshlrev_b64 v[84:85], 14, v[76:77]
	v_lshl_add_u64 v[86:87], v[144:145], 0, v[84:85]
	v_cvt_pk_bf16_f32 v76, v80, v81
	v_cvt_pk_bf16_f32 v77, v82, v83
	v_cvt_pk_bf16_f32 v78, v72, v73
	v_cvt_pk_bf16_f32 v79, v74, v75
	global_store_dwordx4 v[86:87], v[76:79], off
	v_cvt_pk_bf16_f32 v68, v68, v69
	v_cvt_pk_bf16_f32 v69, v70, v71
	v_cvt_pk_bf16_f32 v70, v64, v65
	v_lshl_add_u64 v[64:65], v[144:145], 0, s[40:41]
	v_cvt_pk_bf16_f32 v71, v66, v67
	v_lshl_add_u64 v[66:67], v[64:65], 0, v[146:147]
	global_store_dwordx4 v[86:87], v[68:71], off offset:256
	v_cvt_pk_bf16_f32 v60, v60, v61
	v_cvt_pk_bf16_f32 v61, v62, v63
	v_cvt_pk_bf16_f32 v62, v56, v57
	v_cvt_pk_bf16_f32 v63, v58, v59
	global_store_dwordx4 v[66:67], v[60:63], off
	v_cvt_pk_bf16_f32 v48, v48, v49
	v_cvt_pk_bf16_f32 v49, v50, v51
	v_cvt_pk_bf16_f32 v50, v40, v41
	v_cvt_pk_bf16_f32 v51, v42, v43
	global_store_dwordx4 v[66:67], v[48:51], off offset:256
	v_cvt_pk_bf16_f32 v40, v52, v53
	v_cvt_pk_bf16_f32 v41, v54, v55
	v_cvt_pk_bf16_f32 v42, v44, v45
	v_cvt_pk_bf16_f32 v43, v46, v47
	s_nop 1
	v_lshl_add_u64 v[48:49], v[64:65], 0, v[116:117]
	global_store_dwordx4 v[48:49], v[40:43], off
	v_cvt_pk_bf16_f32 v32, v32, v33
	v_cvt_pk_bf16_f32 v33, v34, v35
	v_cvt_pk_bf16_f32 v34, v24, v25
	v_cvt_pk_bf16_f32 v35, v26, v27
	global_store_dwordx4 v[48:49], v[32:35], off offset:256
	v_cvt_pk_bf16_f32 v24, v36, v37
	v_cvt_pk_bf16_f32 v25, v38, v39
	v_cvt_pk_bf16_f32 v26, v28, v29
	v_cvt_pk_bf16_f32 v27, v30, v31
	s_nop 1
	v_lshl_add_u64 v[32:33], v[64:65], 0, v[100:101]
	global_store_dwordx4 v[32:33], v[24:27], off
	v_cvt_pk_bf16_f32 v16, v16, v17
	v_cvt_pk_bf16_f32 v17, v18, v19
	v_cvt_pk_bf16_f32 v18, v8, v9
	v_cvt_pk_bf16_f32 v19, v10, v11
	global_store_dwordx4 v[32:33], v[16:19], off offset:256
	v_cvt_pk_bf16_f32 v8, v20, v21
	v_cvt_pk_bf16_f32 v9, v22, v23
	v_cvt_pk_bf16_f32 v10, v12, v13
	v_cvt_pk_bf16_f32 v11, v14, v15
	s_nop 1
	v_lshl_add_u64 v[16:17], v[64:65], 0, v[84:85]
	global_store_dwordx4 v[16:17], v[8:11], off
	v_cvt_pk_bf16_f32 v4, v4, v5
	v_cvt_pk_bf16_f32 v5, v6, v7
	v_cvt_pk_bf16_f32 v6, v0, v1
	v_cvt_pk_bf16_f32 v7, v2, v3
	global_store_dwordx4 v[16:17], v[4:7], off offset:256
	s_mul_i32 s53, s46, s13
	s_add_i32 s53, s53, s0
	s_cmpk_gt_i32 s53, 0x7f
	s_mov_b64 s[46:47], -1
	s_cbranch_scc1 .LBB0_1012
	s_ashr_i32 s46, s53, 31
	s_lshr_b32 s46, s46, 29
	s_add_i32 s52, s53, s46
	s_and_b32 s46, s52, -8
	s_sub_i32 s53, s53, s46
	s_cmp_gt_i32 s53, -1
	s_mov_b64 s[46:47], -1
	s_cbranch_scc0 .LBB0_1026
	s_lshl_b32 s54, s53, 4
	s_mov_b64 s[46:47], 0

.LBB0_1072:
	s_add_u32 s65, s2, s42
	ds_read_b128 v[0:3], v157
	ds_read_b128 v[4:7], v157 offset:1024
	ds_read_b128 v[8:11], v157 offset:2048
	ds_read_b128 v[12:15], v157 offset:3072
	s_addc_u32 s66, s3, s43
	s_and_b64 s[42:43], s[46:47], exec
	s_cselect_b32 s43, s66, s45
	s_cselect_b32 s42, s65, s44
	s_add_u32 s48, s1, s48
	s_addc_u32 s49, s14, s49
	s_and_b64 s[46:47], s[46:47], exec
	s_cselect_b32 s5, s49, s5
	s_cselect_b32 s4, s48, s4
	v_lshl_add_u64 v[48:49], s[44:45], 0, v[150:151]
	s_mov_b32 m0, s60
	v_lshl_add_u64 v[50:51], v[48:49], 0, s[34:35]
	ds_read_b128 v[16:19], v158
	ds_read_b128 v[20:23], v158 offset:1024
	ds_read_b128 v[24:27], v158 offset:2048
	ds_read_b128 v[28:31], v158 offset:3072
	ds_read_b128 v[32:35], v158 offset:4096
	ds_read_b128 v[36:39], v158 offset:5120
	ds_read_b128 v[40:43], v158 offset:6144
	ds_read_b128 v[44:47], v158 offset:7168
	global_load_lds_dwordx4 v[50:51], off
	v_lshl_add_u64 v[48:49], v[48:49], 0, s[36:37]
	s_mov_b32 m0, s61
	s_nop 0
	global_load_lds_dwordx4 v[48:49], off
	s_waitcnt lgkmcnt(8)
	s_barrier
	s_waitcnt lgkmcnt(0)
	s_waitcnt lgkmcnt(0)
	v_mfma_f32_16x16x32_bf16 v[48:51], v[0:3], v[16:19], 0
	v_mfma_f32_16x16x32_bf16 v[52:55], v[8:11], v[16:19], 0
	v_mfma_f32_16x16x32_bf16 v[56:59], v[0:3], v[24:27], 0
	v_mfma_f32_16x16x32_bf16 v[60:63], v[8:11], v[24:27], 0
	v_mfma_f32_16x16x32_bf16 v[64:67], v[0:3], v[32:35], 0
	v_mfma_f32_16x16x32_bf16 v[68:71], v[8:11], v[32:35], 0
	v_mfma_f32_16x16x32_bf16 v[72:75], v[0:3], v[40:43], 0
	v_mfma_f32_16x16x32_bf16 v[76:79], v[8:11], v[40:43], 0
	v_mfma_f32_16x16x32_bf16 v[48:51], v[4:7], v[20:23], v[48:51]
	v_mfma_f32_16x16x32_bf16 v[52:55], v[12:15], v[20:23], v[52:55]
	v_mfma_f32_16x16x32_bf16 v[56:59], v[4:7], v[28:31], v[56:59]
	v_mfma_f32_16x16x32_bf16 v[60:63], v[12:15], v[28:31], v[60:63]
	v_mfma_f32_16x16x32_bf16 v[64:67], v[4:7], v[36:39], v[64:67]
	v_mfma_f32_16x16x32_bf16 v[68:71], v[12:15], v[36:39], v[68:71]
	v_mfma_f32_16x16x32_bf16 v[72:75], v[4:7], v[44:47], v[72:75]
	v_mfma_f32_16x16x32_bf16 v[80:83], v[12:15], v[44:47], v[76:79]
	s_barrier
	s_mov_b32 m0, s63
	v_lshl_add_u64 v[154:155], s[4:5], 0, v[148:149]
	ds_read_b128 v[76:79], v159
	ds_read_b128 v[84:87], v159 offset:1024
	ds_read_b128 v[88:91], v159 offset:2048
	ds_read_b128 v[92:95], v159 offset:3072
	global_load_lds_dwordx4 v[154:155], off
	v_lshl_add_u64 v[96:97], v[154:155], 0, s[6:7]
	s_add_i32 m0, s63, 0x2000
	s_nop 0
	global_load_lds_dwordx4 v[96:97], off
	s_barrier
	s_waitcnt lgkmcnt(0)
	s_waitcnt lgkmcnt(0)
	v_mfma_f32_16x16x32_bf16 v[96:99], v[76:79], v[16:19], 0
	v_mfma_f32_16x16x32_bf16 v[16:19], v[88:91], v[16:19], 0
	v_mfma_f32_16x16x32_bf16 v[96:99], v[84:87], v[20:23], v[96:99]
	v_mfma_f32_16x16x32_bf16 v[16:19], v[92:95], v[20:23], v[16:19]
	v_mfma_f32_16x16x32_bf16 v[20:23], v[76:79], v[24:27], 0
	v_mfma_f32_16x16x32_bf16 v[100:103], v[84:87], v[28:31], v[20:23]
	v_mfma_f32_16x16x32_bf16 v[20:23], v[88:91], v[24:27], 0
	v_mfma_f32_16x16x32_bf16 v[24:27], v[92:95], v[28:31], v[20:23]
	v_mfma_f32_16x16x32_bf16 v[20:23], v[76:79], v[32:35], 0
	v_mfma_f32_16x16x32_bf16 v[28:31], v[84:87], v[36:39], v[20:23]
	v_mfma_f32_16x16x32_bf16 v[20:23], v[88:91], v[32:35], 0
	v_mfma_f32_16x16x32_bf16 v[32:35], v[92:95], v[36:39], v[20:23]
	v_mfma_f32_16x16x32_bf16 v[20:23], v[76:79], v[40:43], 0
	v_mfma_f32_16x16x32_bf16 v[108:111], v[84:87], v[44:47], v[20:23]
	v_mfma_f32_16x16x32_bf16 v[20:23], v[88:91], v[40:43], 0
	v_mfma_f32_16x16x32_bf16 v[40:43], v[92:95], v[44:47], v[20:23]
	s_mov_b32 m0, s31
	v_lshl_add_u64 v[242:243], s[42:43], 0, v[150:151]
	s_barrier
	s_nop 2
	ds_read_b128 v[20:23], v158 offset:16384
	ds_read_b128 v[36:39], v158 offset:17408
	ds_read_b128 v[44:47], v158 offset:18432
	ds_read_b128 v[104:107], v158 offset:19456
	ds_read_b128 v[112:115], v158 offset:20480
	ds_read_b128 v[116:119], v158 offset:21504
	ds_read_b128 v[120:123], v158 offset:22528
	ds_read_b128 v[124:127], v158 offset:23552
	global_load_lds_dwordx4 v[242:243], off
	v_lshl_add_u64 v[128:129], v[242:243], 0, s[6:7]
	s_mov_b32 m0, s33
	s_nop 0
	global_load_lds_dwordx4 v[128:129], off
	s_barrier
	s_waitcnt lgkmcnt(0)
	s_waitcnt lgkmcnt(0)
	v_mfma_f32_16x16x32_bf16 v[132:135], v[8:11], v[20:23], 0
	v_mfma_f32_16x16x32_bf16 v[136:139], v[12:15], v[36:39], v[132:135]
	v_mfma_f32_16x16x32_bf16 v[132:135], v[0:3], v[44:47], 0
	v_mfma_f32_16x16x32_bf16 v[140:143], v[4:7], v[104:107], v[132:135]
	v_mfma_f32_16x16x32_bf16 v[132:135], v[8:11], v[44:47], 0
	v_mfma_f32_16x16x32_bf16 v[128:131], v[0:3], v[20:23], 0
	v_mfma_f32_16x16x32_bf16 v[160:163], v[12:15], v[104:107], v[132:135]
	v_mfma_f32_16x16x32_bf16 v[132:135], v[0:3], v[112:115], 0
	v_mfma_f32_16x16x32_bf16 v[0:3], v[0:3], v[120:123], 0
	v_mfma_f32_16x16x32_bf16 v[172:175], v[4:7], v[124:127], v[0:3]
	v_mfma_f32_16x16x32_bf16 v[0:3], v[8:11], v[120:123], 0
	v_mfma_f32_16x16x32_bf16 v[128:131], v[4:7], v[36:39], v[128:131]
	v_mfma_f32_16x16x32_bf16 v[164:167], v[4:7], v[116:119], v[132:135]
	v_mfma_f32_16x16x32_bf16 v[132:135], v[8:11], v[112:115], 0
	v_mfma_f32_16x16x32_bf16 v[8:11], v[12:15], v[124:127], v[0:3]
	v_mfma_f32_16x16x32_bf16 v[168:171], v[12:15], v[116:119], v[132:135]
	s_barrier
	s_add_i32 s44, s62, s30
	v_lshl_add_u64 v[0:1], v[154:155], 0, s[10:11]
	s_mov_b32 m0, s44
	s_nop 0
	global_load_lds_dwordx4 v[0:1], off
	v_lshl_add_u64 v[0:1], v[154:155], 0, s[16:17]
	s_add_i32 m0, s44, 0x2000
	s_nop 0
	global_load_lds_dwordx4 v[0:1], off
	s_waitcnt vmcnt(6)
	s_barrier
	v_mfma_f32_16x16x32_bf16 v[0:3], v[76:79], v[20:23], 0
	v_mfma_f32_16x16x32_bf16 v[176:179], v[84:87], v[36:39], v[0:3]
	v_mfma_f32_16x16x32_bf16 v[0:3], v[88:91], v[20:23], 0
	v_mfma_f32_16x16x32_bf16 v[182:185], v[92:95], v[36:39], v[0:3]
	v_mfma_f32_16x16x32_bf16 v[0:3], v[76:79], v[44:47], 0
	v_mfma_f32_16x16x32_bf16 v[186:189], v[84:87], v[104:107], v[0:3]
	v_mfma_f32_16x16x32_bf16 v[0:3], v[88:91], v[44:47], 0
	v_mfma_f32_16x16x32_bf16 v[190:193], v[92:95], v[104:107], v[0:3]
	v_mfma_f32_16x16x32_bf16 v[0:3], v[76:79], v[112:115], 0
	v_mfma_f32_16x16x32_bf16 v[194:197], v[84:87], v[116:119], v[0:3]
	v_mfma_f32_16x16x32_bf16 v[0:3], v[88:91], v[112:115], 0
	v_mfma_f32_16x16x32_bf16 v[112:115], v[92:95], v[116:119], v[0:3]
	v_mfma_f32_16x16x32_bf16 v[0:3], v[76:79], v[120:123], 0
	v_mfma_f32_16x16x32_bf16 v[116:119], v[84:87], v[124:127], v[0:3]
	v_mfma_f32_16x16x32_bf16 v[0:3], v[88:91], v[120:123], 0
	v_mfma_f32_16x16x32_bf16 v[198:201], v[92:95], v[124:127], v[0:3]
	s_add_i32 s44, 0, 0x18000
	s_nop 4
	v_add_u32_e32 v0, s44, v156
	s_barrier
	ds_read_b128 v[120:123], v0
	ds_read_b128 v[202:205], v0 offset:1024
	ds_read_b128 v[206:209], v0 offset:2048
	ds_read_b128 v[210:213], v0 offset:3072
	s_mov_b32 m0, s50
	v_lshl_add_u64 v[12:13], v[242:243], 0, s[10:11]
	ds_read_b128 v[0:3], v158 offset:32768
	ds_read_b128 v[4:7], v158 offset:33792
	ds_read_b128 v[36:39], v158 offset:34816
	ds_read_b128 v[88:91], v158 offset:35840
	ds_read_b128 v[92:95], v158 offset:36864
	ds_read_b128 v[144:147], v158 offset:37888
	ds_read_b128 v[214:217], v158 offset:38912
	ds_read_b128 v[218:221], v158 offset:39936
	global_load_lds_dwordx4 v[12:13], off
	v_lshl_add_u64 v[12:13], v[242:243], 0, s[16:17]
	s_mov_b32 m0, s51
	s_nop 0
	global_load_lds_dwordx4 v[12:13], off
	s_waitcnt lgkmcnt(8)
	s_barrier
	s_waitcnt lgkmcnt(0)
	s_waitcnt lgkmcnt(0)
	v_mfma_f32_16x16x32_bf16 v[12:15], v[120:123], v[0:3], v[48:51]
	v_mfma_f32_16x16x32_bf16 v[132:135], v[202:205], v[4:7], v[12:15]
	v_mfma_f32_16x16x32_bf16 v[12:15], v[206:209], v[0:3], v[52:55]
	v_mfma_f32_16x16x32_bf16 v[124:127], v[210:213], v[4:7], v[12:15]
	v_mfma_f32_16x16x32_bf16 v[12:15], v[120:123], v[36:39], v[56:59]
	v_mfma_f32_16x16x32_bf16 v[84:87], v[202:205], v[88:91], v[12:15]
	v_mfma_f32_16x16x32_bf16 v[12:15], v[206:209], v[36:39], v[60:63]
	v_mfma_f32_16x16x32_bf16 v[76:79], v[210:213], v[88:91], v[12:15]
	v_mfma_f32_16x16x32_bf16 v[12:15], v[120:123], v[92:95], v[64:67]
	v_mfma_f32_16x16x32_bf16 v[52:55], v[202:205], v[144:147], v[12:15]
	v_mfma_f32_16x16x32_bf16 v[12:15], v[206:209], v[92:95], v[68:71]
	v_mfma_f32_16x16x32_bf16 v[44:47], v[210:213], v[144:147], v[12:15]
	v_mfma_f32_16x16x32_bf16 v[12:15], v[120:123], v[214:217], v[72:75]
	v_mfma_f32_16x16x32_bf16 v[20:23], v[202:205], v[218:221], v[12:15]
	v_mfma_f32_16x16x32_bf16 v[12:15], v[206:209], v[214:217], v[80:83]
	v_mfma_f32_16x16x32_bf16 v[12:15], v[210:213], v[218:221], v[12:15]
	s_barrier
	s_add_i32 s45, 0, 0x1c000
	v_add_u32_e32 v48, s45, v156
	s_add_i32 s44, s44, s30
	ds_read_b128 v[222:225], v48
	ds_read_b128 v[226:229], v48 offset:1024
	ds_read_b128 v[230:233], v48 offset:2048
	ds_read_b128 v[234:237], v48 offset:3072
	v_lshl_add_u64 v[48:49], v[154:155], 0, s[22:23]
	s_mov_b32 m0, s44
	s_nop 0
	global_load_lds_dwordx4 v[48:49], off
	v_lshl_add_u64 v[48:49], v[154:155], 0, s[24:25]
	s_add_i32 m0, s44, 0x2000
	s_nop 0
	global_load_lds_dwordx4 v[48:49], off
	s_barrier
	s_waitcnt lgkmcnt(0)
	s_waitcnt lgkmcnt(0)
	v_mfma_f32_16x16x32_bf16 v[48:51], v[222:225], v[0:3], v[96:99]
	v_mfma_f32_16x16x32_bf16 v[0:3], v[230:233], v[0:3], v[16:19]
	v_mfma_f32_16x16x32_bf16 v[96:99], v[234:237], v[4:7], v[0:3]
	v_mfma_f32_16x16x32_bf16 v[0:3], v[222:225], v[36:39], v[100:103]
	v_mfma_f32_16x16x32_bf16 v[68:71], v[226:229], v[88:91], v[0:3]
	v_mfma_f32_16x16x32_bf16 v[0:3], v[230:233], v[36:39], v[24:27]
	v_mfma_f32_16x16x32_bf16 v[64:67], v[234:237], v[88:91], v[0:3]
	v_mfma_f32_16x16x32_bf16 v[0:3], v[222:225], v[92:95], v[28:31]
	v_mfma_f32_16x16x32_bf16 v[36:39], v[226:229], v[144:147], v[0:3]
	v_mfma_f32_16x16x32_bf16 v[0:3], v[230:233], v[92:95], v[32:35]
	v_mfma_f32_16x16x32_bf16 v[32:35], v[234:237], v[144:147], v[0:3]
	v_mfma_f32_16x16x32_bf16 v[0:3], v[222:225], v[214:217], v[108:111]
	v_mfma_f32_16x16x32_bf16 v[104:107], v[226:229], v[4:7], v[48:51]
	v_mfma_f32_16x16x32_bf16 v[4:7], v[226:229], v[218:221], v[0:3]
	v_mfma_f32_16x16x32_bf16 v[0:3], v[230:233], v[214:217], v[40:43]
	v_mfma_f32_16x16x32_bf16 v[0:3], v[234:237], v[218:221], v[0:3]
	s_mov_b32 m0, s56
	v_lshl_add_u64 v[24:25], v[242:243], 0, s[38:39]
	s_barrier
	ds_read_b128 v[16:19], v158 offset:49152
	ds_read_b128 v[40:43], v158 offset:50176
	ds_read_b128 v[48:51], v158 offset:51200
	ds_read_b128 v[72:75], v158 offset:52224
	ds_read_b128 v[108:111], v158 offset:53248
	ds_read_b128 v[214:217], v158 offset:54272
	ds_read_b128 v[218:221], v158 offset:55296
	ds_read_b128 v[238:241], v158 offset:56320
	global_load_lds_dwordx4 v[24:25], off
	v_lshl_add_u64 v[24:25], v[242:243], 0, s[40:41]
	s_mov_b32 m0, s57
	s_nop 0
	global_load_lds_dwordx4 v[24:25], off
	s_barrier
	s_waitcnt lgkmcnt(0)
	s_waitcnt lgkmcnt(0)
	v_mfma_f32_16x16x32_bf16 v[24:27], v[120:123], v[16:19], v[128:131]
	v_mfma_f32_16x16x32_bf16 v[100:103], v[202:205], v[40:43], v[24:27]
	v_mfma_f32_16x16x32_bf16 v[24:27], v[206:209], v[16:19], v[136:139]
	v_mfma_f32_16x16x32_bf16 v[144:147], v[210:213], v[40:43], v[24:27]
	v_mfma_f32_16x16x32_bf16 v[24:27], v[120:123], v[48:51], v[140:143]
	v_mfma_f32_16x16x32_bf16 v[92:95], v[202:205], v[72:75], v[24:27]
	v_mfma_f32_16x16x32_bf16 v[24:27], v[206:209], v[48:51], v[160:163]
	v_mfma_f32_16x16x32_bf16 v[88:91], v[210:213], v[72:75], v[24:27]
	v_mfma_f32_16x16x32_bf16 v[24:27], v[120:123], v[108:111], v[164:167]
	v_mfma_f32_16x16x32_bf16 v[60:63], v[202:205], v[214:217], v[24:27]
	v_mfma_f32_16x16x32_bf16 v[24:27], v[206:209], v[108:111], v[168:171]
	v_mfma_f32_16x16x32_bf16 v[56:59], v[210:213], v[214:217], v[24:27]
	v_mfma_f32_16x16x32_bf16 v[24:27], v[120:123], v[218:221], v[172:175]
	v_mfma_f32_16x16x32_bf16 v[8:11], v[206:209], v[218:221], v[8:11]
	v_mfma_f32_16x16x32_bf16 v[28:31], v[202:205], v[238:241], v[24:27]
	v_mfma_f32_16x16x32_bf16 v[24:27], v[210:213], v[238:241], v[8:11]
	s_barrier
	s_add_i32 s44, s45, s30
	s_nop 2
	v_lshl_add_u64 v[8:9], v[154:155], 0, s[26:27]
	s_mov_b32 m0, s44
	s_nop 0
	global_load_lds_dwordx4 v[8:9], off
	v_lshl_add_u64 v[8:9], v[154:155], 0, s[28:29]
	s_add_i32 m0, s44, 0x2000
	s_nop 0
	global_load_lds_dwordx4 v[8:9], off
	s_waitcnt vmcnt(6)
	s_barrier
	v_mfma_f32_16x16x32_bf16 v[8:11], v[222:225], v[16:19], v[176:179]
	v_mfma_f32_16x16x32_bf16 v[128:131], v[226:229], v[40:43], v[8:11]
	v_mfma_f32_16x16x32_bf16 v[8:11], v[230:233], v[16:19], v[182:185]
	v_mfma_f32_16x16x32_bf16 v[120:123], v[234:237], v[40:43], v[8:11]
	v_mfma_f32_16x16x32_bf16 v[8:11], v[222:225], v[48:51], v[186:189]
	v_mfma_f32_16x16x32_bf16 v[80:83], v[226:229], v[72:75], v[8:11]
	v_mfma_f32_16x16x32_bf16 v[8:11], v[230:233], v[48:51], v[190:193]
	v_mfma_f32_16x16x32_bf16 v[72:75], v[234:237], v[72:75], v[8:11]
	v_mfma_f32_16x16x32_bf16 v[8:11], v[222:225], v[108:111], v[194:197]
	v_mfma_f32_16x16x32_bf16 v[48:51], v[226:229], v[214:217], v[8:11]
	v_mfma_f32_16x16x32_bf16 v[8:11], v[230:233], v[108:111], v[112:115]
	v_mfma_f32_16x16x32_bf16 v[40:43], v[234:237], v[214:217], v[8:11]
	v_mfma_f32_16x16x32_bf16 v[8:11], v[222:225], v[218:221], v[116:119]
	v_mfma_f32_16x16x32_bf16 v[16:19], v[226:229], v[238:241], v[8:11]
	v_mfma_f32_16x16x32_bf16 v[8:11], v[230:233], v[218:221], v[198:201]
	v_mfma_f32_16x16x32_bf16 v[8:11], v[234:237], v[238:241], v[8:11]
	v_mov_b32_e32 v108, v180
	s_mov_b32 s45, s15
	s_mov_b32 s44, s58
	s_barrier
	s_cmp_lg_u32 s45, 0
	s_cbranch_scc1 .LBB0_1074
	v_and_b32_e32 v109, 15, v108
	s_lshl_b32 s45, s44, 6
	v_and_b32_e32 v108, 48, v108
	v_and_or_b32 v154, s45, 64, v108
	v_lshlrev_b32_e32 v108, 2, v154
	v_lshl_or_b32 v152, v109, 9, v108
	global_load_dwordx4 v[160:163], v152, s[20:21]
	global_load_dwordx4 v[164:167], v152, s[20:21] offset:16
	global_load_dwordx4 v[140:143], v152, s[20:21] offset:32
	global_load_dwordx4 v[136:139], v152, s[20:21] offset:48
	v_mov_b32_e32 v176, v124
	v_mov_b32_e32 v177, v144
	v_mov_b32_e32 v179, v145
	v_mov_b32_e32 v190, v144
	v_mov_b32_e32 v191, v124
	v_mov_b32_e32 v124, v145
	v_lshl_add_u64 v[144:145], s[20:21], 0, v[152:153]
	v_mov_b32_e32 v169, v100
	v_mov_b32_e32 v186, v100
	v_add_co_u32_e32 v100, vcc, s53, v144
	v_mov_b32_e32 v168, v132
	v_mov_b32_e32 v171, v101
	v_mov_b32_e32 v187, v132
	v_mov_b32_e32 v132, v101
	v_lshl_add_u64 v[112:113], v[144:145], 0, s[22:23]
	v_addc_co_u32_e32 v101, vcc, 0, v145, vcc
	v_mov_b32_e32 v172, v134
	v_mov_b32_e32 v173, v102
	v_mov_b32_e32 v175, v103
	v_mov_b32_e32 v183, v146
	v_mov_b32_e32 v188, v102
	v_mov_b32_e32 v189, v134
	v_mov_b32_e32 v134, v103
	v_mov_b32_e32 v192, v146
	v_lshlrev_b32_e32 v146, 10, v109
	global_load_dwordx4 v[116:119], v[100:101], off
	s_nop 0
	global_load_dwordx4 v[100:103], v[112:113], off offset:48
	global_load_dwordx4 v[108:111], v[112:113], off offset:32
	s_nop 0
	global_load_dwordx4 v[112:115], v[112:113], off offset:16
	v_mov_b32_e32 v170, v133
	v_mov_b32_e32 v174, v135
	v_mov_b32_e32 v178, v125
	v_mov_b32_e32 v182, v126
	v_mov_b32_e32 v184, v127
	v_mov_b32_e32 v185, v147
	v_mov_b32_e32 v193, v126
	s_lshl_b32 s45, s64, 8
	s_lshl_b32 s44, s44, 5
	s_add_i32 s44, s44, s45
	s_ashr_i32 s45, s44, 6
	s_addk_i32 s44, 0x80
	s_ashr_i32 s44, s44, 6
	s_waitcnt vmcnt(0)
	v_pk_mul_f32 v[168:169], v[168:169], v[160:161]
	v_pk_mul_f32 v[170:171], v[170:171], v[162:163]
	v_pk_mul_f32 v[174:175], v[174:175], v[166:167]
	v_pk_mul_f32 v[176:177], v[176:177], v[140:141]
	v_pk_mul_f32 v[178:179], v[178:179], v[142:143]
	v_pk_mul_f32 v[124:125], v[124:125], v[142:143]
	v_pk_mul_f32 v[172:173], v[172:173], v[164:165]
	v_pk_mul_f32 v[182:183], v[182:183], v[136:137]
	v_pk_mul_f32 v[184:185], v[184:185], v[138:139]
	v_pk_mul_f32 v[186:187], v[186:187], v[160:161]
	v_pk_mul_f32 v[132:133], v[132:133], v[162:163]
	v_pk_mul_f32 v[188:189], v[188:189], v[164:165]
	v_pk_mul_f32 v[134:135], v[134:135], v[166:167]
	v_pk_mul_f32 v[190:191], v[190:191], v[140:141]
	v_add_f32_e32 v126, v168, v169
	v_add_f32_e32 v152, v170, v171
	v_add_f32_e32 v168, v174, v175
	v_add_f32_e32 v169, v176, v177
	v_add_f32_e32 v170, v178, v179
	v_sub_f32_e32 v124, v124, v125
	v_add_f32_e32 v155, v172, v173
	v_add_f32_e32 v171, v182, v183
	v_add_f32_e32 v172, v184, v185
	v_sub_f32_e32 v173, v186, v187
	v_sub_f32_e32 v174, v132, v133
	v_sub_f32_e32 v175, v188, v189
	v_sub_f32_e32 v176, v134, v135
	v_sub_f32_e32 v177, v190, v191
	v_cvt_pk_bf16_f32 v132, v126, v152
	v_cvt_pk_bf16_f32 v133, v155, v168
	v_cvt_pk_bf16_f32 v134, v169, v170
	v_cvt_pk_bf16_f32 v135, v171, v172
	v_cvt_pk_bf16_f32 v168, v173, v174
	v_cvt_pk_bf16_f32 v169, v175, v176
	v_cvt_pk_bf16_f32 v170, v177, v124
	v_pk_mul_f32 v[124:125], v[192:193], v[136:137]
	v_mov_b32_e32 v126, v147
	v_sub_f32_e32 v152, v124, v125
	v_pk_mul_f32 v[124:125], v[126:127], v[138:139]
	v_mov_b32_e32 v155, v153
	v_sub_f32_e32 v124, v124, v125
	v_cvt_pk_bf16_f32 v171, v152, v124
	v_add_u32_e32 v124, s45, v146
	v_ashrrev_i32_e32 v125, 31, v124
	v_lshlrev_b64 v[124:125], 8, v[124:125]
	v_lshl_add_u64 v[124:125], s[18:19], 0, v[124:125]
	v_lshl_add_u64 v[124:125], v[124:125], 0, v[154:155]
	global_store_dwordx4 v[124:125], v[132:135], off
	global_store_dwordx4 v[124:125], v[168:171], off offset:128
	v_mov_b32_e32 v124, v104
	v_mov_b32_e32 v125, v128
	v_pk_mul_f32 v[124:125], v[124:125], v[160:161]
	v_mov_b32_e32 v127, v130
	v_add_f32_e32 v126, v124, v125
	v_mov_b32_e32 v124, v105
	v_mov_b32_e32 v125, v129
	v_pk_mul_f32 v[124:125], v[124:125], v[162:163]
	v_mov_b32_e32 v133, v122
	v_add_f32_e32 v124, v124, v125
	v_cvt_pk_bf16_f32 v124, v126, v124
	v_mov_b32_e32 v126, v106
	v_pk_mul_f32 v[126:127], v[126:127], v[164:165]
	s_nop 0
	v_add_f32_e32 v125, v126, v127
	v_mov_b32_e32 v126, v107
	v_mov_b32_e32 v127, v131
	v_pk_mul_f32 v[126:127], v[126:127], v[166:167]
	s_nop 0
	v_add_f32_e32 v126, v126, v127
	v_cvt_pk_bf16_f32 v125, v125, v126
	v_mov_b32_e32 v126, v96
	v_mov_b32_e32 v127, v120
	v_pk_mul_f32 v[126:127], v[126:127], v[140:141]
	s_nop 0
	v_add_f32_e32 v132, v126, v127
	v_mov_b32_e32 v126, v97
	v_mov_b32_e32 v127, v121
	v_pk_mul_f32 v[126:127], v[126:127], v[142:143]
	s_nop 0
	v_add_f32_e32 v126, v126, v127
	v_cvt_pk_bf16_f32 v126, v132, v126
	v_mov_b32_e32 v132, v98
	v_pk_mul_f32 v[132:133], v[132:133], v[136:137]
	s_nop 0
	v_add_f32_e32 v127, v132, v133
	v_mov_b32_e32 v132, v99
	v_mov_b32_e32 v133, v123
	v_pk_mul_f32 v[132:133], v[132:133], v[138:139]
	s_nop 0
	v_add_f32_e32 v132, v132, v133
	v_cvt_pk_bf16_f32 v127, v127, v132
	v_mov_b32_e32 v132, v128
	v_mov_b32_e32 v133, v104
	v_mov_b32_e32 v104, v129
	v_pk_mul_f32 v[132:133], v[132:133], v[160:161]
	v_pk_mul_f32 v[104:105], v[104:105], v[162:163]
	v_sub_f32_e32 v128, v132, v133
	v_sub_f32_e32 v104, v104, v105
	v_cvt_pk_bf16_f32 v104, v128, v104
	v_mov_b32_e32 v128, v130
	v_mov_b32_e32 v129, v106
	v_mov_b32_e32 v106, v131
	v_pk_mul_f32 v[128:129], v[128:129], v[164:165]
	v_pk_mul_f32 v[106:107], v[106:107], v[166:167]
	v_sub_f32_e32 v105, v128, v129
	v_sub_f32_e32 v106, v106, v107
	v_cvt_pk_bf16_f32 v105, v105, v106
	v_mov_b32_e32 v106, v120
	v_mov_b32_e32 v107, v96
	v_mov_b32_e32 v96, v121
	v_pk_mul_f32 v[106:107], v[106:107], v[140:141]
	v_pk_mul_f32 v[96:97], v[96:97], v[142:143]
	v_sub_f32_e32 v106, v106, v107
	v_sub_f32_e32 v96, v96, v97
	v_cvt_pk_bf16_f32 v106, v106, v96
	v_mov_b32_e32 v96, v122
	v_mov_b32_e32 v97, v98
	v_pk_mul_f32 v[96:97], v[96:97], v[136:137]
	v_mov_b32_e32 v98, v123
	v_sub_f32_e32 v107, v96, v97
	v_pk_mul_f32 v[96:97], v[98:99], v[138:139]
	v_mov_b32_e32 v99, v94
	v_sub_f32_e32 v96, v96, v97
	v_cvt_pk_bf16_f32 v107, v107, v96
	v_add_u32_e32 v96, s44, v146
	v_ashrrev_i32_e32 v97, 31, v96
	v_lshlrev_b64 v[96:97], 8, v[96:97]
	v_lshl_add_u64 v[96:97], s[18:19], 0, v[96:97]
	v_lshl_add_u64 v[96:97], v[96:97], 0, v[154:155]
	global_store_dwordx4 v[96:97], v[124:127], off
	global_store_dwordx4 v[96:97], v[104:107], off offset:128
	v_mov_b32_e32 v96, v84
	v_mov_b32_e32 v97, v92
	v_pk_mul_f32 v[96:97], v[96:97], v[116:117]
	v_mov_b32_e32 v105, v90
	v_add_f32_e32 v98, v96, v97
	v_mov_b32_e32 v96, v85
	v_mov_b32_e32 v97, v93
	v_pk_mul_f32 v[96:97], v[96:97], v[118:119]
	v_or_b32_e32 v106, 0x4000, v146
	v_add_f32_e32 v96, v96, v97
	v_cvt_pk_bf16_f32 v96, v98, v96
	v_mov_b32_e32 v98, v86
	v_pk_mul_f32 v[98:99], v[98:99], v[112:113]
	s_nop 0
	v_add_f32_e32 v97, v98, v99
	v_mov_b32_e32 v98, v87
	v_mov_b32_e32 v99, v95
	v_pk_mul_f32 v[98:99], v[98:99], v[114:115]
	s_nop 0
	v_add_f32_e32 v98, v98, v99
	v_cvt_pk_bf16_f32 v97, v97, v98
	v_mov_b32_e32 v98, v76
	v_mov_b32_e32 v99, v88
	v_pk_mul_f32 v[98:99], v[98:99], v[108:109]
	s_nop 0
	v_add_f32_e32 v104, v98, v99
	v_mov_b32_e32 v98, v77
	v_mov_b32_e32 v99, v89
	v_pk_mul_f32 v[98:99], v[98:99], v[110:111]
	s_nop 0
	v_add_f32_e32 v98, v98, v99
	v_cvt_pk_bf16_f32 v98, v104, v98
	v_mov_b32_e32 v104, v78
	v_pk_mul_f32 v[104:105], v[104:105], v[100:101]
	s_nop 0
	v_add_f32_e32 v99, v104, v105
	v_mov_b32_e32 v104, v79
	v_mov_b32_e32 v105, v91
	v_pk_mul_f32 v[104:105], v[104:105], v[102:103]
	s_nop 0
	v_add_f32_e32 v104, v104, v105
	v_cvt_pk_bf16_f32 v99, v99, v104
	v_mov_b32_e32 v104, v92
	v_mov_b32_e32 v105, v84
	v_mov_b32_e32 v84, v93
	v_pk_mul_f32 v[104:105], v[104:105], v[116:117]
	v_pk_mul_f32 v[84:85], v[84:85], v[118:119]
	v_sub_f32_e32 v92, v104, v105
	v_sub_f32_e32 v84, v84, v85
	v_cvt_pk_bf16_f32 v84, v92, v84
	v_mov_b32_e32 v92, v94
	v_mov_b32_e32 v93, v86
	v_mov_b32_e32 v86, v95
	v_pk_mul_f32 v[92:93], v[92:93], v[112:113]
	v_pk_mul_f32 v[86:87], v[86:87], v[114:115]
	v_sub_f32_e32 v85, v92, v93
	v_sub_f32_e32 v86, v86, v87
	v_cvt_pk_bf16_f32 v85, v85, v86
	v_mov_b32_e32 v86, v88
	v_mov_b32_e32 v87, v76
	v_mov_b32_e32 v76, v89
	v_pk_mul_f32 v[86:87], v[86:87], v[108:109]
	v_pk_mul_f32 v[76:77], v[76:77], v[110:111]
	v_sub_f32_e32 v86, v86, v87
	v_sub_f32_e32 v76, v76, v77
	v_cvt_pk_bf16_f32 v86, v86, v76
	v_mov_b32_e32 v76, v90
	v_mov_b32_e32 v77, v78
	v_pk_mul_f32 v[76:77], v[76:77], v[100:101]
	v_mov_b32_e32 v78, v91
	v_sub_f32_e32 v87, v76, v77
	v_pk_mul_f32 v[76:77], v[78:79], v[102:103]
	v_mov_b32_e32 v79, v82
	v_sub_f32_e32 v76, v76, v77
	v_cvt_pk_bf16_f32 v87, v87, v76
	v_add_u32_e32 v76, s45, v106
	v_ashrrev_i32_e32 v77, 31, v76
	v_lshlrev_b64 v[76:77], 8, v[76:77]
	v_lshl_add_u64 v[76:77], s[18:19], 0, v[76:77]
	v_lshl_add_u64 v[76:77], v[76:77], 0, v[154:155]
	global_store_dwordx4 v[76:77], v[96:99], off
	global_store_dwordx4 v[76:77], v[84:87], off offset:128
	v_mov_b32_e32 v76, v68
	v_mov_b32_e32 v77, v80
	v_pk_mul_f32 v[76:77], v[76:77], v[116:117]
	v_mov_b32_e32 v85, v74
	v_add_f32_e32 v78, v76, v77
	v_mov_b32_e32 v76, v69
	v_mov_b32_e32 v77, v81
	v_pk_mul_f32 v[76:77], v[76:77], v[118:119]
	v_mov_b32_e32 v96, v52
	v_add_f32_e32 v76, v76, v77
	v_cvt_pk_bf16_f32 v76, v78, v76
	v_mov_b32_e32 v78, v70
	v_pk_mul_f32 v[78:79], v[78:79], v[112:113]
	v_mov_b32_e32 v97, v60
	v_add_f32_e32 v77, v78, v79
	v_mov_b32_e32 v78, v71
	v_mov_b32_e32 v79, v83
	v_pk_mul_f32 v[78:79], v[78:79], v[114:115]
	v_mov_b32_e32 v99, v62
	v_add_f32_e32 v78, v78, v79
	v_cvt_pk_bf16_f32 v77, v77, v78
	v_mov_b32_e32 v78, v64
	v_mov_b32_e32 v79, v72
	v_pk_mul_f32 v[78:79], v[78:79], v[108:109]
	s_nop 0
	v_add_f32_e32 v84, v78, v79
	v_mov_b32_e32 v78, v65
	v_mov_b32_e32 v79, v73
	v_pk_mul_f32 v[78:79], v[78:79], v[110:111]
	s_nop 0
	v_add_f32_e32 v78, v78, v79
	v_cvt_pk_bf16_f32 v78, v84, v78
	v_mov_b32_e32 v84, v66
	v_pk_mul_f32 v[84:85], v[84:85], v[100:101]
	s_nop 0
	v_add_f32_e32 v79, v84, v85
	v_mov_b32_e32 v84, v67
	v_mov_b32_e32 v85, v75
	v_pk_mul_f32 v[84:85], v[84:85], v[102:103]
	s_nop 0
	v_add_f32_e32 v84, v84, v85
	v_cvt_pk_bf16_f32 v79, v79, v84
	v_mov_b32_e32 v84, v80
	v_mov_b32_e32 v85, v68
	v_mov_b32_e32 v68, v81
	v_pk_mul_f32 v[84:85], v[84:85], v[116:117]
	v_pk_mul_f32 v[68:69], v[68:69], v[118:119]
	v_sub_f32_e32 v80, v84, v85
	v_sub_f32_e32 v68, v68, v69
	v_cvt_pk_bf16_f32 v68, v80, v68
	v_mov_b32_e32 v80, v82
	v_mov_b32_e32 v81, v70
	v_mov_b32_e32 v70, v83
	v_pk_mul_f32 v[80:81], v[80:81], v[112:113]
	v_pk_mul_f32 v[70:71], v[70:71], v[114:115]
	v_sub_f32_e32 v69, v80, v81
	v_sub_f32_e32 v70, v70, v71
	v_cvt_pk_bf16_f32 v69, v69, v70
	v_mov_b32_e32 v70, v72
	v_mov_b32_e32 v71, v64
	v_mov_b32_e32 v64, v73
	v_pk_mul_f32 v[70:71], v[70:71], v[108:109]
	v_pk_mul_f32 v[64:65], v[64:65], v[110:111]
	v_sub_f32_e32 v70, v70, v71
	v_sub_f32_e32 v64, v64, v65
	v_cvt_pk_bf16_f32 v70, v70, v64
	v_mov_b32_e32 v64, v74
	v_mov_b32_e32 v65, v66
	v_pk_mul_f32 v[64:65], v[64:65], v[100:101]
	v_mov_b32_e32 v66, v75
	v_sub_f32_e32 v71, v64, v65
	v_pk_mul_f32 v[64:65], v[66:67], v[102:103]
	v_lshl_add_u64 v[72:73], v[144:145], 0, s[24:25]
	v_sub_f32_e32 v64, v64, v65
	v_cvt_pk_bf16_f32 v71, v71, v64
	v_add_u32_e32 v64, s44, v106
	v_ashrrev_i32_e32 v65, 31, v64
	v_lshlrev_b64 v[64:65], 8, v[64:65]
	v_lshl_add_u64 v[64:65], s[18:19], 0, v[64:65]
	v_lshl_add_u64 v[64:65], v[64:65], 0, v[154:155]
	global_store_dwordx4 v[64:65], v[76:79], off
	global_store_dwordx4 v[64:65], v[68:71], off offset:128
	v_add_co_u32_e32 v64, vcc, s54, v144
	v_mov_b32_e32 v101, v58
	s_nop 0
	v_addc_co_u32_e32 v65, vcc, 0, v145, vcc
	global_load_dwordx4 v[80:83], v[64:65], off
	v_lshl_add_u64 v[64:65], v[144:145], 0, s[6:7]
	global_load_dwordx4 v[84:87], v[64:65], off offset:16
	global_load_dwordx4 v[88:91], v[64:65], off offset:32
	global_load_dwordx4 v[92:95], v[64:65], off offset:48
	v_add_co_u32_e32 v64, vcc, s55, v144
	v_or_b32_e32 v102, 0x8000, v146
	s_nop 0
	v_addc_co_u32_e32 v65, vcc, 0, v145, vcc
	global_load_dwordx4 v[76:79], v[64:65], off
	s_nop 0
	global_load_dwordx4 v[64:67], v[72:73], off offset:48
	global_load_dwordx4 v[68:71], v[72:73], off offset:32
	s_nop 0
	global_load_dwordx4 v[72:75], v[72:73], off offset:16
	s_waitcnt vmcnt(0)
	v_pk_mul_f32 v[96:97], v[96:97], v[80:81]
	s_nop 0
	v_add_f32_e32 v98, v96, v97
	v_mov_b32_e32 v96, v53
	v_mov_b32_e32 v97, v61
	v_pk_mul_f32 v[96:97], v[96:97], v[82:83]
	s_nop 0
	v_add_f32_e32 v96, v96, v97
	v_cvt_pk_bf16_f32 v96, v98, v96
	v_mov_b32_e32 v98, v54
	v_pk_mul_f32 v[98:99], v[98:99], v[84:85]
	s_nop 0
	v_add_f32_e32 v97, v98, v99
	v_mov_b32_e32 v98, v55
	v_mov_b32_e32 v99, v63
	v_pk_mul_f32 v[98:99], v[98:99], v[86:87]
	s_nop 0
	v_add_f32_e32 v98, v98, v99
	v_cvt_pk_bf16_f32 v97, v97, v98
	v_mov_b32_e32 v98, v44
	v_mov_b32_e32 v99, v56
	v_pk_mul_f32 v[98:99], v[98:99], v[88:89]
	s_nop 0
	v_add_f32_e32 v100, v98, v99
	v_mov_b32_e32 v98, v45
	v_mov_b32_e32 v99, v57
	v_pk_mul_f32 v[98:99], v[98:99], v[90:91]
	s_nop 0
	v_add_f32_e32 v98, v98, v99
	v_cvt_pk_bf16_f32 v98, v100, v98
	v_mov_b32_e32 v100, v46
	v_pk_mul_f32 v[100:101], v[100:101], v[92:93]
	s_nop 0
	v_add_f32_e32 v99, v100, v101
	v_mov_b32_e32 v100, v47
	v_mov_b32_e32 v101, v59
	v_pk_mul_f32 v[100:101], v[100:101], v[94:95]
	s_nop 0
	v_add_f32_e32 v100, v100, v101
	v_cvt_pk_bf16_f32 v99, v99, v100
	v_mov_b32_e32 v100, v60
	v_mov_b32_e32 v101, v52
	v_mov_b32_e32 v52, v61
	v_pk_mul_f32 v[100:101], v[100:101], v[80:81]
	v_pk_mul_f32 v[52:53], v[52:53], v[82:83]
	v_sub_f32_e32 v60, v100, v101
	v_sub_f32_e32 v52, v52, v53
	v_cvt_pk_bf16_f32 v52, v60, v52
	v_mov_b32_e32 v60, v62
	v_mov_b32_e32 v61, v54
	v_mov_b32_e32 v54, v63
	v_pk_mul_f32 v[60:61], v[60:61], v[84:85]
	v_pk_mul_f32 v[54:55], v[54:55], v[86:87]
	v_sub_f32_e32 v53, v60, v61
	v_sub_f32_e32 v54, v54, v55
	v_cvt_pk_bf16_f32 v53, v53, v54
	v_mov_b32_e32 v54, v56
	v_mov_b32_e32 v55, v44
	v_mov_b32_e32 v44, v57
	v_pk_mul_f32 v[54:55], v[54:55], v[88:89]
	v_pk_mul_f32 v[44:45], v[44:45], v[90:91]
	v_sub_f32_e32 v54, v54, v55
	v_sub_f32_e32 v44, v44, v45
	v_cvt_pk_bf16_f32 v54, v54, v44
	v_mov_b32_e32 v44, v58
	v_mov_b32_e32 v45, v46
	v_pk_mul_f32 v[44:45], v[44:45], v[92:93]
	v_mov_b32_e32 v46, v59
	v_sub_f32_e32 v55, v44, v45
	v_pk_mul_f32 v[44:45], v[46:47], v[94:95]
	v_mov_b32_e32 v47, v50
	v_sub_f32_e32 v44, v44, v45
	v_cvt_pk_bf16_f32 v55, v55, v44
	v_add_u32_e32 v44, s45, v102
	v_ashrrev_i32_e32 v45, 31, v44
	v_lshlrev_b64 v[44:45], 8, v[44:45]
	v_lshl_add_u64 v[44:45], s[18:19], 0, v[44:45]
	v_lshl_add_u64 v[44:45], v[44:45], 0, v[154:155]
	global_store_dwordx4 v[44:45], v[96:99], off
	global_store_dwordx4 v[44:45], v[52:55], off offset:128
	v_mov_b32_e32 v44, v36
	v_mov_b32_e32 v45, v48
	v_pk_mul_f32 v[44:45], v[44:45], v[80:81]
	v_mov_b32_e32 v53, v42
	v_add_f32_e32 v46, v44, v45
	v_mov_b32_e32 v44, v37
	v_mov_b32_e32 v45, v49
	v_pk_mul_f32 v[44:45], v[44:45], v[82:83]
	s_nop 0
	v_add_f32_e32 v44, v44, v45
	v_cvt_pk_bf16_f32 v44, v46, v44
	v_mov_b32_e32 v46, v38
	v_pk_mul_f32 v[46:47], v[46:47], v[84:85]
	s_nop 0
	v_add_f32_e32 v45, v46, v47
	v_mov_b32_e32 v46, v39
	v_mov_b32_e32 v47, v51
	v_pk_mul_f32 v[46:47], v[46:47], v[86:87]
	s_nop 0
	v_add_f32_e32 v46, v46, v47
	v_cvt_pk_bf16_f32 v45, v45, v46
	v_mov_b32_e32 v46, v32
	v_mov_b32_e32 v47, v40
	v_pk_mul_f32 v[46:47], v[46:47], v[88:89]
	s_nop 0
	v_add_f32_e32 v52, v46, v47
	v_mov_b32_e32 v46, v33
	v_mov_b32_e32 v47, v41
	v_pk_mul_f32 v[46:47], v[46:47], v[90:91]
	s_nop 0
	v_add_f32_e32 v46, v46, v47
	v_cvt_pk_bf16_f32 v46, v52, v46
	v_mov_b32_e32 v52, v34
	v_pk_mul_f32 v[52:53], v[52:53], v[92:93]
	s_nop 0
	v_add_f32_e32 v47, v52, v53
	v_mov_b32_e32 v52, v35
	v_mov_b32_e32 v53, v43
	v_pk_mul_f32 v[52:53], v[52:53], v[94:95]
	s_nop 0
	v_add_f32_e32 v52, v52, v53
	v_cvt_pk_bf16_f32 v47, v47, v52
	v_mov_b32_e32 v52, v48
	v_mov_b32_e32 v53, v36
	v_mov_b32_e32 v36, v49
	v_pk_mul_f32 v[52:53], v[52:53], v[80:81]
	v_pk_mul_f32 v[36:37], v[36:37], v[82:83]
	v_sub_f32_e32 v48, v52, v53
	v_sub_f32_e32 v36, v36, v37
	v_cvt_pk_bf16_f32 v36, v48, v36
	v_mov_b32_e32 v48, v50
	v_mov_b32_e32 v49, v38
	v_mov_b32_e32 v38, v51
	v_pk_mul_f32 v[48:49], v[48:49], v[84:85]
	v_pk_mul_f32 v[38:39], v[38:39], v[86:87]
	v_sub_f32_e32 v37, v48, v49
	v_sub_f32_e32 v38, v38, v39
	v_cvt_pk_bf16_f32 v37, v37, v38
	v_mov_b32_e32 v38, v40
	v_mov_b32_e32 v39, v32
	v_mov_b32_e32 v32, v41
	v_pk_mul_f32 v[38:39], v[38:39], v[88:89]
	v_pk_mul_f32 v[32:33], v[32:33], v[90:91]
	v_sub_f32_e32 v38, v38, v39
	v_sub_f32_e32 v32, v32, v33
	v_cvt_pk_bf16_f32 v38, v38, v32
	v_mov_b32_e32 v32, v42
	v_mov_b32_e32 v33, v34
	v_pk_mul_f32 v[32:33], v[32:33], v[92:93]
	v_mov_b32_e32 v34, v43
	v_sub_f32_e32 v39, v32, v33
	v_pk_mul_f32 v[32:33], v[34:35], v[94:95]
	v_mov_b32_e32 v35, v30
	v_sub_f32_e32 v32, v32, v33
	v_cvt_pk_bf16_f32 v39, v39, v32
	v_add_u32_e32 v32, s44, v102
	v_ashrrev_i32_e32 v33, 31, v32
	v_lshlrev_b64 v[32:33], 8, v[32:33]
	v_lshl_add_u64 v[32:33], s[18:19], 0, v[32:33]
	v_lshl_add_u64 v[32:33], v[32:33], 0, v[154:155]
	global_store_dwordx4 v[32:33], v[44:47], off
	global_store_dwordx4 v[32:33], v[36:39], off offset:128
	v_mov_b32_e32 v32, v20
	v_mov_b32_e32 v33, v28
	v_pk_mul_f32 v[32:33], v[32:33], v[76:77]
	v_mov_b32_e32 v37, v26
	v_add_f32_e32 v34, v32, v33
	v_mov_b32_e32 v32, v21
	v_mov_b32_e32 v33, v29
	v_pk_mul_f32 v[32:33], v[32:33], v[78:79]
	v_or_b32_e32 v38, 0xc000, v146
	v_add_f32_e32 v32, v32, v33
	v_cvt_pk_bf16_f32 v32, v34, v32
	v_mov_b32_e32 v34, v22
	v_pk_mul_f32 v[34:35], v[34:35], v[72:73]
	s_nop 0
	v_add_f32_e32 v33, v34, v35
	v_mov_b32_e32 v34, v23
	v_mov_b32_e32 v35, v31
	v_pk_mul_f32 v[34:35], v[34:35], v[74:75]
	s_nop 0
	v_add_f32_e32 v34, v34, v35
	v_cvt_pk_bf16_f32 v33, v33, v34
	v_mov_b32_e32 v34, v12
	v_mov_b32_e32 v35, v24
	v_pk_mul_f32 v[34:35], v[34:35], v[68:69]
	s_nop 0
	v_add_f32_e32 v36, v34, v35
	v_mov_b32_e32 v34, v13
	v_mov_b32_e32 v35, v25
	v_pk_mul_f32 v[34:35], v[34:35], v[70:71]
	s_nop 0
	v_add_f32_e32 v34, v34, v35
	v_cvt_pk_bf16_f32 v34, v36, v34
	v_mov_b32_e32 v36, v14
	v_pk_mul_f32 v[36:37], v[36:37], v[64:65]
	s_nop 0
	v_add_f32_e32 v35, v36, v37
	v_mov_b32_e32 v36, v15
	v_mov_b32_e32 v37, v27
	v_pk_mul_f32 v[36:37], v[36:37], v[66:67]
	s_nop 0
	v_add_f32_e32 v36, v36, v37
	v_cvt_pk_bf16_f32 v35, v35, v36
	v_mov_b32_e32 v36, v28
	v_mov_b32_e32 v37, v20
	v_mov_b32_e32 v20, v29
	v_pk_mul_f32 v[36:37], v[36:37], v[76:77]
	v_pk_mul_f32 v[20:21], v[20:21], v[78:79]
	v_sub_f32_e32 v28, v36, v37
	v_sub_f32_e32 v20, v20, v21
	v_cvt_pk_bf16_f32 v20, v28, v20
	v_mov_b32_e32 v28, v30
	v_mov_b32_e32 v29, v22
	v_mov_b32_e32 v22, v31
	v_pk_mul_f32 v[28:29], v[28:29], v[72:73]
	v_pk_mul_f32 v[22:23], v[22:23], v[74:75]
	v_sub_f32_e32 v21, v28, v29
	v_sub_f32_e32 v22, v22, v23
	v_cvt_pk_bf16_f32 v21, v21, v22
	v_mov_b32_e32 v22, v24
	v_mov_b32_e32 v23, v12
	v_mov_b32_e32 v12, v25
	v_pk_mul_f32 v[22:23], v[22:23], v[68:69]
	v_pk_mul_f32 v[12:13], v[12:13], v[70:71]
	v_sub_f32_e32 v22, v22, v23
	v_sub_f32_e32 v12, v12, v13
	v_cvt_pk_bf16_f32 v22, v22, v12
	v_mov_b32_e32 v12, v26
	v_mov_b32_e32 v13, v14
	v_pk_mul_f32 v[12:13], v[12:13], v[64:65]
	v_mov_b32_e32 v14, v27
	v_sub_f32_e32 v23, v12, v13
	v_pk_mul_f32 v[12:13], v[14:15], v[66:67]
	v_mov_b32_e32 v15, v18
	v_sub_f32_e32 v12, v12, v13
	v_cvt_pk_bf16_f32 v23, v23, v12
	v_add_u32_e32 v12, s45, v38
	v_ashrrev_i32_e32 v13, 31, v12
	v_lshlrev_b64 v[12:13], 8, v[12:13]
	v_lshl_add_u64 v[12:13], s[18:19], 0, v[12:13]
	v_lshl_add_u64 v[12:13], v[12:13], 0, v[154:155]
	global_store_dwordx4 v[12:13], v[32:35], off
	global_store_dwordx4 v[12:13], v[20:23], off offset:128
	v_mov_b32_e32 v12, v4
	v_mov_b32_e32 v13, v16
	v_pk_mul_f32 v[12:13], v[12:13], v[76:77]
	v_mov_b32_e32 v21, v10
	v_add_f32_e32 v14, v12, v13
	v_mov_b32_e32 v12, v5
	v_mov_b32_e32 v13, v17
	v_pk_mul_f32 v[12:13], v[12:13], v[78:79]
	s_nop 0
	v_add_f32_e32 v12, v12, v13
	v_cvt_pk_bf16_f32 v12, v14, v12
	v_mov_b32_e32 v14, v6
	v_pk_mul_f32 v[14:15], v[14:15], v[72:73]
	s_nop 0
	v_add_f32_e32 v13, v14, v15
	v_mov_b32_e32 v14, v7
	v_mov_b32_e32 v15, v19
	v_pk_mul_f32 v[14:15], v[14:15], v[74:75]
	s_nop 0
	v_add_f32_e32 v14, v14, v15
	v_cvt_pk_bf16_f32 v13, v13, v14
	v_mov_b32_e32 v14, v0
	v_mov_b32_e32 v15, v8
	v_pk_mul_f32 v[14:15], v[14:15], v[68:69]
	s_nop 0
	v_add_f32_e32 v20, v14, v15
	v_mov_b32_e32 v14, v1
	v_mov_b32_e32 v15, v9
	v_pk_mul_f32 v[14:15], v[14:15], v[70:71]
	s_nop 0
	v_add_f32_e32 v14, v14, v15
	v_cvt_pk_bf16_f32 v14, v20, v14
	v_mov_b32_e32 v20, v2
	v_pk_mul_f32 v[20:21], v[20:21], v[64:65]
	s_nop 0
	v_add_f32_e32 v15, v20, v21
	v_mov_b32_e32 v20, v3
	v_mov_b32_e32 v21, v11
	v_pk_mul_f32 v[20:21], v[20:21], v[66:67]
	s_nop 0
	v_add_f32_e32 v20, v20, v21
	v_cvt_pk_bf16_f32 v15, v15, v20
	v_mov_b32_e32 v20, v16
	v_mov_b32_e32 v21, v4
	v_mov_b32_e32 v4, v17
	v_pk_mul_f32 v[20:21], v[20:21], v[76:77]
	v_pk_mul_f32 v[4:5], v[4:5], v[78:79]
	v_sub_f32_e32 v16, v20, v21
	v_sub_f32_e32 v4, v4, v5
	v_cvt_pk_bf16_f32 v4, v16, v4
	v_mov_b32_e32 v16, v18
	v_mov_b32_e32 v17, v6
	v_mov_b32_e32 v6, v19
	v_pk_mul_f32 v[16:17], v[16:17], v[72:73]
	v_pk_mul_f32 v[6:7], v[6:7], v[74:75]
	v_sub_f32_e32 v5, v16, v17
	v_sub_f32_e32 v6, v6, v7
	v_cvt_pk_bf16_f32 v5, v5, v6
	v_mov_b32_e32 v6, v8
	v_mov_b32_e32 v7, v0
	v_mov_b32_e32 v0, v9
	v_pk_mul_f32 v[6:7], v[6:7], v[68:69]
	v_pk_mul_f32 v[0:1], v[0:1], v[70:71]
	v_sub_f32_e32 v6, v6, v7
	v_sub_f32_e32 v0, v0, v1
	v_cvt_pk_bf16_f32 v6, v6, v0
	v_mov_b32_e32 v0, v10
	v_mov_b32_e32 v1, v2
	v_pk_mul_f32 v[0:1], v[0:1], v[64:65]
	v_mov_b32_e32 v2, v11
	v_sub_f32_e32 v7, v0, v1
	v_pk_mul_f32 v[0:1], v[2:3], v[66:67]
	s_nop 0
	v_sub_f32_e32 v0, v0, v1
	v_cvt_pk_bf16_f32 v7, v7, v0
	v_add_u32_e32 v0, s44, v38
	v_ashrrev_i32_e32 v1, 31, v0
	v_lshlrev_b64 v[0:1], 8, v[0:1]
	v_lshl_add_u64 v[0:1], s[18:19], 0, v[0:1]
	v_lshl_add_u64 v[0:1], v[0:1], 0, v[154:155]
	global_store_dwordx4 v[0:1], v[12:15], off
	global_store_dwordx4 v[0:1], v[4:7], off offset:128

.LBB0_1098:
	s_add_u32 s34, s43, s16
	s_addc_u32 s35, s44, s17
	s_mov_b32 m0, s76
	s_add_u32 s98, s34, s20
	s_addc_u32 s99, s35, s21
	global_load_lds_dwordx4 v240, s[98:99]
	s_mov_b32 m0, s77
	s_nop 0
	global_load_lds_dwordx4 v241, s[98:99]
	s_mov_b32 m0, s45
	s_nop 0
	global_load_lds_dwordx4 v242, s[98:99]
	s_add_i32 s4, s1, s47
	s_add_u32 s38, s41, s16
	s_addc_u32 s39, s42, s17
	s_mov_b32 m0, s4
	s_mov_b32 s48, s46
	s_add_u32 s100, s38, s22
	s_addc_u32 s101, s39, s23
	global_load_lds_dwordx4 v243, s[100:101]
	s_add_i32 m0, s4, 0x2000
	s_mov_b32 s46, s36
	global_load_lds_dwordx4 v244, s[100:101]
	ds_read_b128 v[64:67], v246 offset:49152
	ds_read_b128 v[68:71], v246 offset:61440
	ds_read_b128 v[232:235], v247 offset:49152
	ds_read_b128 v[236:239], v247 offset:61440
	ds_read_b128 v[200:203], v248 offset:49152
	ds_read_b128 v[204:207], v248 offset:61440
	s_add_i32 s49, 0, 0x12000
	s_waitcnt lgkmcnt(4)
	v_mfma_f32_32x32x16_bf16 v[80:95], v[64:67], v[140:143], 0
	v_exp_f32_e32 v160, v160
	v_exp_f32_e32 v161, v161
	v_exp_f32_e32 v164, v164
	v_mfma_f32_32x32x16_bf16 v[64:79], v[68:71], v[140:143], 0
	v_exp_f32_e32 v165, v165
	v_exp_f32_e32 v175, v157
	v_exp_f32_e32 v144, v162
	ds_read_b128 v[216:219], v249 offset:49152
	ds_read_b128 v[220:223], v249 offset:61440
	s_waitcnt lgkmcnt(4)
	v_mfma_f32_32x32x16_bf16 v[80:95], v[232:235], v[136:139], v[80:95]
	v_exp_f32_e32 v162, v163
	v_exp_f32_e32 v163, v156
	v_exp_f32_e32 v214, v150
	v_mfma_f32_32x32x16_bf16 v[64:79], v[236:239], v[136:139], v[64:79]
	v_add_f32_e32 v150, 0, v185
	v_add_f32_e32 v150, v189, v150
	v_add_f32_e32 v150, v186, v150
	ds_read_b128 v[232:235], v246 offset:49280
	ds_read_b128 v[236:239], v246 offset:61568
	s_waitcnt lgkmcnt(4)
	v_mfma_f32_32x32x16_bf16 v[80:95], v[200:203], v[132:135], v[80:95]
	v_add_f32_e32 v150, v190, v150
	v_add_f32_e32 v150, v187, v150
	v_add_f32_e32 v150, v191, v150
	v_mfma_f32_32x32x16_bf16 v[64:79], v[204:207], v[132:135], v[64:79]
	v_add_f32_e32 v150, v184, v150
	v_add_f32_e32 v150, v188, v150
	v_add_f32_e32 v150, v178, v150
	ds_read_b128 v[200:203], v247 offset:49280
	ds_read_b128 v[204:207], v247 offset:61568
	s_waitcnt lgkmcnt(4)
	v_mfma_f32_32x32x16_bf16 v[80:95], v[216:219], v[128:131], v[80:95]
	v_add_f32_e32 v150, v182, v150
	v_add_f32_e32 v150, v179, v150
	v_add_f32_e32 v150, v183, v150
	v_mfma_f32_32x32x16_bf16 v[64:79], v[220:223], v[128:131], v[64:79]
	v_add_f32_e32 v150, v176, v150
	v_add_f32_e32 v150, v180, v150
	v_add_f32_e32 v150, v177, v150
	v_add_f32_e32 v150, v181, v150
	ds_read_b128 v[216:219], v248 offset:49280
	ds_read_b128 v[220:223], v248 offset:61568
	s_waitcnt lgkmcnt(4)
	v_mfma_f32_32x32x16_bf16 v[80:95], v[232:235], v[124:127], v[80:95]
	v_add_f32_e32 v150, v144, v150
	v_add_f32_e32 v150, v162, v150
	v_exp_f32_e32 v212, v152
	v_mfma_f32_32x32x16_bf16 v[64:79], v[236:239], v[124:127], v[64:79]
	v_add_f32_e32 v150, v160, v150
	v_exp_f32_e32 v213, v153
	v_add_f32_e32 v150, v161, v150
	ds_read_b128 v[232:235], v249 offset:49280
	ds_read_b128 v[236:239], v249 offset:61568
	s_waitcnt lgkmcnt(4)
	v_mfma_f32_32x32x16_bf16 v[80:95], v[200:203], v[120:123], v[80:95]
	v_add_f32_e32 v150, v163, v150
	v_exp_f32_e32 v215, v151
	v_add_f32_e32 v150, v175, v150
	v_mfma_f32_32x32x16_bf16 v[64:79], v[204:207], v[120:123], v[64:79]
	v_add_f32_e32 v150, v212, v150
	v_add_f32_e32 v150, v213, v150
	v_exp_f32_e32 v228, v158
	ds_read_b128 v[200:203], v246 offset:49408
	ds_read_b128 v[204:207], v246 offset:61696
	s_waitcnt lgkmcnt(4)
	v_mfma_f32_32x32x16_bf16 v[80:95], v[216:219], v[116:119], v[80:95]
	v_add_f32_e32 v150, v214, v150
	v_exp_f32_e32 v229, v159
	v_add_f32_e32 v150, v215, v150
	v_mfma_f32_32x32x16_bf16 v[64:79], v[220:223], v[116:119], v[64:79]
	v_exp_f32_e32 v230, v154
	v_add_f32_e32 v150, v164, v150
	v_exp_f32_e32 v231, v155
	ds_read_b128 v[216:219], v247 offset:49408
	ds_read_b128 v[220:223], v247 offset:61696
	s_waitcnt lgkmcnt(4)
	v_mfma_f32_32x32x16_bf16 v[80:95], v[232:235], v[112:115], v[80:95]
	v_add_f32_e32 v150, v165, v150
	v_add_f32_e32 v150, v228, v150
	v_add_f32_e32 v150, v229, v150
	v_mfma_f32_32x32x16_bf16 v[64:79], v[236:239], v[112:115], v[64:79]
	v_add_f32_e32 v150, v230, v150
	v_add_f32_e32 v173, v231, v150
	v_mov_b32_e32 v174, v173
	s_nop 1
	ds_read_b128 v[232:235], v248 offset:49408
	ds_read_b128 v[236:239], v248 offset:61696
	s_waitcnt lgkmcnt(4)
	v_mfma_f32_32x32x16_bf16 v[80:95], v[200:203], v[108:111], v[80:95]
	v_permlane32_swap_b32_e32 v173, v174
	v_cvt_pk_bf16_f32 v150, v185, v189
	v_cvt_pk_bf16_f32 v151, v186, v190
	v_mfma_f32_32x32x16_bf16 v[64:79], v[204:207], v[108:111], v[64:79]
	v_cvt_pk_bf16_f32 v152, v187, v191
	v_cvt_pk_bf16_f32 v153, v184, v188
	v_cvt_pk_bf16_f32 v154, v178, v182
	ds_read_b128 v[200:203], v249 offset:49408
	ds_read_b128 v[204:207], v249 offset:61696
	s_waitcnt lgkmcnt(4)
	v_mfma_f32_32x32x16_bf16 v[80:95], v[216:219], v[104:107], v[80:95]
	v_cvt_pk_bf16_f32 v155, v179, v183
	v_cvt_pk_bf16_f32 v156, v176, v180
	v_cvt_pk_bf16_f32 v157, v177, v181
	v_mfma_f32_32x32x16_bf16 v[64:79], v[220:223], v[104:107], v[64:79]
	v_cvt_pk_bf16_f32 v158, v144, v162
	v_cvt_pk_bf16_f32 v159, v160, v161
	v_cvt_pk_bf16_f32 v160, v163, v175
	s_waitcnt lgkmcnt(2)
	v_mfma_f32_32x32x16_bf16 v[80:95], v[232:235], v[100:103], v[80:95]
	v_cvt_pk_bf16_f32 v161, v212, v213
	v_cvt_pk_bf16_f32 v162, v214, v215
	v_cvt_pk_bf16_f32 v163, v164, v165
	v_mfma_f32_32x32x16_bf16 v[64:79], v[236:239], v[100:103], v[64:79]
	v_cvt_pk_bf16_f32 v164, v228, v229
	v_cvt_pk_bf16_f32 v165, v230, v231
	v_permlane32_swap_b32_e32 v150, v152
	s_waitcnt lgkmcnt(0)
	v_mfma_f32_32x32x16_bf16 v[80:95], v[200:203], v[96:99], v[80:95]
	v_permlane32_swap_b32_e32 v151, v153
	v_permlane32_swap_b32_e32 v154, v156
	v_permlane32_swap_b32_e32 v155, v157
	v_mfma_f32_32x32x16_bf16 v[64:79], v[204:207], v[96:99], v[64:79]
	v_permlane32_swap_b32_e32 v158, v160
	v_permlane32_swap_b32_e32 v159, v161
	v_permlane32_swap_b32_e32 v162, v164
	v_permlane32_swap_b32_e32 v163, v165
	s_cmp_lg_u32 0, -1
	s_cselect_b32 s4, 0, 0
	s_add_i32 s40, s36, s4
	v_add_u32_e32 v144, s40, v250
	ds_read_b64_tr_b16 v[176:177], v144 offset:0
	ds_read_b64_tr_b16 v[178:179], v144 offset:0x800
	ds_read_b64_tr_b16 v[180:181], v144 offset:0x1000
	ds_read_b64_tr_b16 v[182:183], v144 offset:0x1800
	ds_read_b64_tr_b16 v[184:185], v144 offset:0x2000
	ds_read_b64_tr_b16 v[186:187], v144 offset:0x2800
	ds_read_b64_tr_b16 v[188:189], v144 offset:0x3000
	ds_read_b64_tr_b16 v[190:191], v144 offset:0x3800
	s_waitcnt lgkmcnt(0)
	s_nop 0
	v_mfma_f32_32x32x16_bf16 v[0:15], v[150:153], v[176:179], v[0:15]
	ds_read_b64_tr_b16 v[176:177], v144 offset:0x200
	ds_read_b64_tr_b16 v[178:179], v144 offset:0xa00
	v_mfma_f32_32x32x16_bf16 v[0:15], v[154:157], v[180:183], v[0:15]
	ds_read_b64_tr_b16 v[180:181], v144 offset:0x1200
	ds_read_b64_tr_b16 v[182:183], v144 offset:0x1a00
	v_mfma_f32_32x32x16_bf16 v[0:15], v[158:161], v[184:187], v[0:15]
	ds_read_b64_tr_b16 v[184:185], v144 offset:0x2200
	ds_read_b64_tr_b16 v[186:187], v144 offset:0x2a00
	ds_read_b64_tr_b16 v[192:193], v144 offset:0x3200
	ds_read_b64_tr_b16 v[194:195], v144 offset:0x3a00
	s_waitcnt lgkmcnt(0)
	v_mfma_f32_32x32x16_bf16 v[0:15], v[162:165], v[188:191], v[0:15]
	v_mfma_f32_32x32x16_bf16 v[48:63], v[150:153], v[176:179], v[48:63]
	ds_read_b64_tr_b16 v[176:177], v144 offset:0x400
	ds_read_b64_tr_b16 v[178:179], v144 offset:0xc00
	v_mfma_f32_32x32x16_bf16 v[48:63], v[154:157], v[180:183], v[48:63]
	ds_read_b64_tr_b16 v[180:181], v144 offset:0x1400
	ds_read_b64_tr_b16 v[182:183], v144 offset:0x1c00
	v_mfma_f32_32x32x16_bf16 v[48:63], v[158:161], v[184:187], v[48:63]
	ds_read_b64_tr_b16 v[184:185], v144 offset:0x2400
	ds_read_b64_tr_b16 v[186:187], v144 offset:0x2c00
	ds_read_b64_tr_b16 v[188:189], v144 offset:0x3400
	ds_read_b64_tr_b16 v[190:191], v144 offset:0x3c00
	s_waitcnt lgkmcnt(0)
	v_mfma_f32_32x32x16_bf16 v[48:63], v[162:165], v[192:195], v[48:63]
	v_mfma_f32_32x32x16_bf16 v[32:47], v[150:153], v[176:179], v[32:47]
	ds_read_b64_tr_b16 v[176:177], v144 offset:0x600
	ds_read_b64_tr_b16 v[178:179], v144 offset:0xe00
	v_mfma_f32_32x32x16_bf16 v[32:47], v[154:157], v[180:183], v[32:47]
	ds_read_b64_tr_b16 v[180:181], v144 offset:0x1600
	ds_read_b64_tr_b16 v[182:183], v144 offset:0x1e00
	v_mfma_f32_32x32x16_bf16 v[32:47], v[158:161], v[184:187], v[32:47]
	ds_read_b64_tr_b16 v[184:185], v144 offset:0x2600
	ds_read_b64_tr_b16 v[186:187], v144 offset:0x2e00
	ds_read_b64_tr_b16 v[192:193], v144 offset:0x3600
	ds_read_b64_tr_b16 v[194:195], v144 offset:0x3e00
	s_waitcnt lgkmcnt(0)
	v_mfma_f32_32x32x16_bf16 v[32:47], v[162:165], v[188:191], v[32:47]
	v_mfma_f32_32x32x16_bf16 v[16:31], v[150:153], v[176:179], v[16:31]
	v_max_f32_e32 v144, v81, v81
	v_max_f32_e32 v175, v80, v80
	v_max_f32_e32 v144, v175, v144
	v_max3_f32 v144, v144, v82, v83
	v_max3_f32 v144, v144, v84, v85
	v_max3_f32 v144, v144, v86, v87
	v_max3_f32 v144, v144, v88, v89
	v_max3_f32 v144, v144, v90, v91
	v_mfma_f32_32x32x16_bf16 v[16:31], v[154:157], v[180:183], v[16:31]
	v_max3_f32 v144, v144, v92, v93
	v_max3_f32 v144, v144, v94, v95
	v_max3_f32 v144, v144, v64, v65
	v_max3_f32 v144, v144, v66, v67
	v_max3_f32 v144, v144, v68, v69
	v_max3_f32 v144, v144, v70, v71
	v_max3_f32 v144, v144, v72, v73
	v_max3_f32 v144, v144, v74, v75
	v_mfma_f32_32x32x16_bf16 v[16:31], v[158:161], v[184:187], v[16:31]
	v_max3_f32 v144, v144, v76, v77
	v_max3_f32 v144, v144, v78, v79
	v_mov_b32_e32 v150, v144
	s_nop 1
	v_permlane32_swap_b32_e32 v144, v150
	v_max_f32_e32 v150, v150, v150
	v_max_f32_e32 v144, v144, v144
	v_max_f32_e32 v144, v144, v150
	v_max_f32_e32 v151, v172, v172
	v_sub_f32_e32 v150, v144, v172
	v_max_f32_e32 v144, v151, v144
	v_mfma_f32_32x32x16_bf16 v[16:31], v[162:165], v[192:195], v[16:31]
	v_sub_f32_e32 v151, v172, v144
	v_mul_f32_e32 v151, 0x3dd53b94, v151
	v_exp_f32_e32 v151, v151
	v_cmp_ge_f32_e32 vcc, s63, v150
	s_cmp_eq_u64 vcc, exec
	s_cselect_b64 s[4:5], -1, 0
	s_waitcnt vmcnt(0)
	v_cndmask_b32_e64 v175, v151, 1.0, s[4:5]
	v_cmp_gt_f32_e32 vcc, 1.0, v175
	s_waitcnt vmcnt(0)
	s_barrier
	s_cbranch_vccz .LBB0_1102
	s_and_saveexec_b64 s[36:37], s[2:3]
	ds_write_b32 v149, v175 offset:128
	s_or_b64 exec, exec, s[36:37]
	s_waitcnt lgkmcnt(0)
	v_add_u32_e32 v162, v147, v148
	ds_read_b128 v[150:153], v162 offset:224
	ds_read_b128 v[154:157], v162 offset:192
	ds_read_b128 v[158:161], v162 offset:160
	ds_read_b128 v[162:165], v162 offset:128
	s_waitcnt lgkmcnt(3)
	v_pk_mul_f32 v[12:13], v[12:13], v[150:151]
	s_waitcnt lgkmcnt(2)
	v_pk_mul_f32 v[8:9], v[8:9], v[154:155]
	s_waitcnt lgkmcnt(1)
	v_pk_mul_f32 v[4:5], v[4:5], v[158:159]
	v_pk_mul_f32 v[14:15], v[14:15], v[152:153]
	v_pk_mul_f32 v[10:11], v[10:11], v[156:157]
	v_pk_mul_f32 v[6:7], v[6:7], v[160:161]
	s_waitcnt lgkmcnt(0)
	v_pk_mul_f32 v[2:3], v[2:3], v[164:165]
	v_pk_mul_f32 v[0:1], v[0:1], v[162:163]
	v_pk_mul_f32 v[60:61], v[60:61], v[150:151]
	v_pk_mul_f32 v[56:57], v[56:57], v[154:155]
	v_pk_mul_f32 v[52:53], v[52:53], v[158:159]
	v_pk_mul_f32 v[62:63], v[62:63], v[152:153]
	v_pk_mul_f32 v[58:59], v[58:59], v[156:157]
	v_pk_mul_f32 v[54:55], v[54:55], v[160:161]
	v_pk_mul_f32 v[50:51], v[50:51], v[164:165]
	v_pk_mul_f32 v[48:49], v[48:49], v[162:163]
	v_pk_mul_f32 v[44:45], v[44:45], v[150:151]
	v_pk_mul_f32 v[40:41], v[40:41], v[154:155]
	v_pk_mul_f32 v[36:37], v[36:37], v[158:159]
	v_pk_mul_f32 v[46:47], v[46:47], v[152:153]
	v_pk_mul_f32 v[42:43], v[42:43], v[156:157]
	v_pk_mul_f32 v[38:39], v[38:39], v[160:161]
	v_pk_mul_f32 v[34:35], v[34:35], v[164:165]
	v_pk_mul_f32 v[32:33], v[32:33], v[162:163]
	v_pk_mul_f32 v[28:29], v[28:29], v[150:151]
	v_pk_mul_f32 v[24:25], v[24:25], v[154:155]
	v_pk_mul_f32 v[20:21], v[20:21], v[158:159]
	v_pk_mul_f32 v[30:31], v[30:31], v[152:153]
	v_pk_mul_f32 v[26:27], v[26:27], v[156:157]
	v_pk_mul_f32 v[22:23], v[22:23], v[160:161]
	v_pk_mul_f32 v[18:19], v[18:19], v[164:165]
	v_pk_mul_f32 v[16:17], v[16:17], v[162:163]
.LBB0_1102:
	v_cndmask_b32_e64 v150, v144, v172, s[4:5]
	v_mul_f32_e32 v176, 0xbdd53b94, v150
	v_fmamk_f32 v187, v66, 0x3dd53b94, v176
	v_fmamk_f32 v185, v64, 0x3dd53b94, v176
	v_fmamk_f32 v186, v65, 0x3dd53b94, v176
	v_fmamk_f32 v188, v67, 0x3dd53b94, v176
	s_cmp_lg_u32 0, -1
	s_cselect_b32 s4, 0, 0
	s_add_i32 s5, s4, s0
	s_add_i32 m0, s5, 0x12000
	v_fmamk_f32 v178, v69, 0x3dd53b94, v176
	s_add_u32 s98, s34, s24
	s_addc_u32 s99, s35, s25
	global_load_lds_dwordx4 v240, s[98:99]
	s_add_i32 m0, s5, 0x14000
	v_fmamk_f32 v179, v70, 0x3dd53b94, v176
	global_load_lds_dwordx4 v241, s[98:99]
	s_add_i32 m0, s5, 0x16000
	v_fmamk_f32 v189, v68, 0x3dd53b94, v176
	global_load_lds_dwordx4 v242, s[98:99]
	v_fmamk_f32 v180, v71, 0x3dd53b94, v176
	s_add_i32 s5, s1, s46
	s_mov_b32 m0, s5
	v_fmamk_f32 v94, v94, 0x3dd53b94, v176
	s_add_u32 s100, s38, s26
	s_addc_u32 s101, s39, s27
	global_load_lds_dwordx4 v243, s[100:101]
	s_add_i32 m0, s5, 0x2000
	v_exp_f32_e32 v151, v94
	global_load_lds_dwordx4 v244, s[100:101]
	v_fmamk_f32 v80, v80, 0x3dd53b94, v176
	v_fmamk_f32 v81, v81, 0x3dd53b94, v176
	v_fmamk_f32 v82, v82, 0x3dd53b94, v176
	v_fmamk_f32 v83, v83, 0x3dd53b94, v176
	v_fmamk_f32 v84, v84, 0x3dd53b94, v176
	v_fmamk_f32 v85, v85, 0x3dd53b94, v176
	v_fmamk_f32 v86, v86, 0x3dd53b94, v176
	v_fmamk_f32 v87, v87, 0x3dd53b94, v176
	v_fmamk_f32 v88, v88, 0x3dd53b94, v176
	v_fmamk_f32 v89, v89, 0x3dd53b94, v176
	v_fmamk_f32 v90, v90, 0x3dd53b94, v176
	v_fmamk_f32 v91, v91, 0x3dd53b94, v176
	v_fmamk_f32 v92, v92, 0x3dd53b94, v176
	v_fmamk_f32 v93, v93, 0x3dd53b94, v176
	v_fmamk_f32 v95, v95, 0x3dd53b94, v176
	v_fmamk_f32 v181, v72, 0x3dd53b94, v176
	v_fmamk_f32 v182, v73, 0x3dd53b94, v176
	v_fmamk_f32 v183, v74, 0x3dd53b94, v176
	v_fmamk_f32 v184, v75, 0x3dd53b94, v176
	v_fmamk_f32 v177, v76, 0x3dd53b94, v176
	v_exp_f32_e32 v164, v80
	v_exp_f32_e32 v172, v81
	v_exp_f32_e32 v162, v82
	v_exp_f32_e32 v165, v83
	v_exp_f32_e32 v161, v84
	v_exp_f32_e32 v163, v85
	v_exp_f32_e32 v159, v86
	v_exp_f32_e32 v160, v87
	v_exp_f32_e32 v156, v88
	v_exp_f32_e32 v158, v89
	v_exp_f32_e32 v155, v90
	v_exp_f32_e32 v157, v91
	v_exp_f32_e32 v152, v92
	v_exp_f32_e32 v154, v93
	v_exp_f32_e32 v153, v95
	v_fmamk_f32 v190, v77, 0x3dd53b94, v176
	v_fmamk_f32 v191, v78, 0x3dd53b94, v176
	v_fmac_f32_e32 v176, 0x3dd53b94, v79
	ds_read_b128 v[64:67], v246 offset:24576
	ds_read_b128 v[68:71], v246 offset:36864
	ds_read_b128 v[232:235], v247 offset:24576
	ds_read_b128 v[236:239], v247 offset:36864
	ds_read_b128 v[200:203], v248 offset:24576
	ds_read_b128 v[204:207], v248 offset:36864
	s_waitcnt lgkmcnt(4)
	v_mfma_f32_32x32x16_bf16 v[80:95], v[64:67], v[140:143], 0
	v_exp_f32_e32 v180, v180
	v_exp_f32_e32 v181, v181
	v_exp_f32_e32 v182, v182
	v_mfma_f32_32x32x16_bf16 v[64:79], v[68:71], v[140:143], 0
	v_exp_f32_e32 v183, v183
	v_exp_f32_e32 v184, v184
	v_exp_f32_e32 v190, v190
	ds_read_b128 v[216:219], v249 offset:24576
	ds_read_b128 v[220:223], v249 offset:36864
	s_waitcnt lgkmcnt(4)
	v_mfma_f32_32x32x16_bf16 v[80:95], v[232:235], v[136:139], v[80:95]
	v_exp_f32_e32 v191, v191
	v_exp_f32_e32 v144, v185
	v_exp_f32_e32 v185, v186
	v_mfma_f32_32x32x16_bf16 v[64:79], v[236:239], v[136:139], v[64:79]
	v_exp_f32_e32 v186, v187
	v_exp_f32_e32 v187, v188
	v_exp_f32_e32 v188, v189
	ds_read_b128 v[232:235], v246 offset:24704
	ds_read_b128 v[236:239], v246 offset:36992
	s_waitcnt lgkmcnt(4)
	v_mfma_f32_32x32x16_bf16 v[80:95], v[200:203], v[132:135], v[80:95]
	v_exp_f32_e32 v189, v178
	v_exp_f32_e32 v214, v176
	v_add_f32_e32 v176, 0, v164
	v_mfma_f32_32x32x16_bf16 v[64:79], v[204:207], v[132:135], v[64:79]
	v_add_f32_e32 v176, v172, v176
	v_add_f32_e32 v176, v162, v176
	v_add_f32_e32 v176, v165, v176
	ds_read_b128 v[200:203], v247 offset:24704
	ds_read_b128 v[204:207], v247 offset:36992
	s_waitcnt lgkmcnt(4)
	v_mfma_f32_32x32x16_bf16 v[80:95], v[216:219], v[128:131], v[80:95]
	v_add_f32_e32 v176, v161, v176
	v_add_f32_e32 v176, v163, v176
	v_add_f32_e32 v176, v159, v176
	v_mfma_f32_32x32x16_bf16 v[64:79], v[220:223], v[128:131], v[64:79]
	v_add_f32_e32 v176, v160, v176
	v_add_f32_e32 v176, v156, v176
	v_add_f32_e32 v176, v158, v176
	v_add_f32_e32 v176, v155, v176
	ds_read_b128 v[216:219], v248 offset:24704
	ds_read_b128 v[220:223], v248 offset:36992
	s_waitcnt lgkmcnt(4)
	v_mfma_f32_32x32x16_bf16 v[80:95], v[232:235], v[124:127], v[80:95]
	v_add_f32_e32 v176, v157, v176
	v_add_f32_e32 v176, v152, v176
	v_add_f32_e32 v176, v154, v176
	v_mfma_f32_32x32x16_bf16 v[64:79], v[236:239], v[124:127], v[64:79]
	v_add_f32_e32 v176, v151, v176
	v_add_f32_e32 v176, v153, v176
	v_add_f32_e32 v176, v144, v176
	ds_read_b128 v[232:235], v249 offset:24704
	ds_read_b128 v[236:239], v249 offset:36992
	s_waitcnt lgkmcnt(4)
	v_mfma_f32_32x32x16_bf16 v[80:95], v[200:203], v[120:123], v[80:95]
	v_add_f32_e32 v176, v185, v176
	v_exp_f32_e32 v212, v179
	v_add_f32_e32 v176, v186, v176
	v_mfma_f32_32x32x16_bf16 v[64:79], v[204:207], v[120:123], v[64:79]
	v_add_f32_e32 v176, v187, v176
	v_add_f32_e32 v176, v188, v176
	v_add_f32_e32 v176, v189, v176
	ds_read_b128 v[200:203], v246 offset:24832
	ds_read_b128 v[204:207], v246 offset:37120
	s_waitcnt lgkmcnt(4)
	v_mfma_f32_32x32x16_bf16 v[80:95], v[216:219], v[116:119], v[80:95]
	v_add_f32_e32 v176, v212, v176
	v_add_f32_e32 v176, v180, v176
	v_exp_f32_e32 v213, v177
	v_mfma_f32_32x32x16_bf16 v[64:79], v[220:223], v[116:119], v[64:79]
	v_add_f32_e32 v176, v181, v176
	v_add_f32_e32 v176, v182, v176
	v_add_f32_e32 v176, v183, v176
	ds_read_b128 v[216:219], v247 offset:24832
	ds_read_b128 v[220:223], v247 offset:37120
	s_waitcnt lgkmcnt(4)
	v_mfma_f32_32x32x16_bf16 v[80:95], v[232:235], v[112:115], v[80:95]
	v_add_f32_e32 v176, v184, v176
	v_add_f32_e32 v176, v213, v176
	v_add_f32_e32 v176, v190, v176
	v_mfma_f32_32x32x16_bf16 v[64:79], v[236:239], v[112:115], v[64:79]
	v_add_f32_e32 v176, v191, v176
	v_add_f32_e32 v192, v214, v176
	v_mov_b32_e32 v193, v192
	s_nop 1
	ds_read_b128 v[232:235], v248 offset:24832
	ds_read_b128 v[236:239], v248 offset:37120
	s_waitcnt lgkmcnt(4)
	v_mfma_f32_32x32x16_bf16 v[80:95], v[200:203], v[108:111], v[80:95]
	v_permlane32_swap_b32_e32 v192, v193
	v_cvt_pk_bf16_f32 v176, v164, v172
	v_cvt_pk_bf16_f32 v177, v162, v165
	v_mfma_f32_32x32x16_bf16 v[64:79], v[204:207], v[108:111], v[64:79]
	v_cvt_pk_bf16_f32 v178, v161, v163
	v_cvt_pk_bf16_f32 v179, v159, v160
	v_cvt_pk_bf16_f32 v156, v156, v158
	ds_read_b128 v[200:203], v249 offset:24832
	ds_read_b128 v[204:207], v249 offset:37120
	s_waitcnt lgkmcnt(4)
	v_mfma_f32_32x32x16_bf16 v[80:95], v[216:219], v[104:107], v[80:95]
	v_cvt_pk_bf16_f32 v157, v155, v157
	v_cvt_pk_bf16_f32 v158, v152, v154
	v_cvt_pk_bf16_f32 v159, v151, v153
	v_mfma_f32_32x32x16_bf16 v[64:79], v[220:223], v[104:107], v[64:79]
	v_cvt_pk_bf16_f32 v152, v144, v185
	v_cvt_pk_bf16_f32 v153, v186, v187
	v_cvt_pk_bf16_f32 v154, v188, v189
	s_waitcnt lgkmcnt(2)
	v_mfma_f32_32x32x16_bf16 v[80:95], v[232:235], v[100:103], v[80:95]
	v_cvt_pk_bf16_f32 v155, v212, v180
	v_cvt_pk_bf16_f32 v160, v181, v182
	v_cvt_pk_bf16_f32 v161, v183, v184
	v_mfma_f32_32x32x16_bf16 v[64:79], v[236:239], v[100:103], v[64:79]
	v_cvt_pk_bf16_f32 v162, v213, v190
	v_cvt_pk_bf16_f32 v163, v191, v214
	v_permlane32_swap_b32_e32 v176, v178
	s_waitcnt lgkmcnt(0)
	v_mfma_f32_32x32x16_bf16 v[80:95], v[200:203], v[96:99], v[80:95]
	v_permlane32_swap_b32_e32 v177, v179
	v_permlane32_swap_b32_e32 v156, v158
	v_permlane32_swap_b32_e32 v157, v159
	v_mfma_f32_32x32x16_bf16 v[64:79], v[204:207], v[96:99], v[64:79]
	v_permlane32_swap_b32_e32 v152, v154
	v_permlane32_swap_b32_e32 v153, v155
	v_permlane32_swap_b32_e32 v160, v162
	v_permlane32_swap_b32_e32 v161, v163
	s_add_i32 s4, s48, s4
	v_add_u32_e32 v144, s4, v250
	ds_read_b64_tr_b16 v[180:181], v144 offset:0
	ds_read_b64_tr_b16 v[182:183], v144 offset:0x800
	ds_read_b64_tr_b16 v[184:185], v144 offset:0x1000
	ds_read_b64_tr_b16 v[186:187], v144 offset:0x1800
	ds_read_b64_tr_b16 v[188:189], v144 offset:0x2000
	ds_read_b64_tr_b16 v[190:191], v144 offset:0x2800
	ds_read_b64_tr_b16 v[194:195], v144 offset:0x3000
	ds_read_b64_tr_b16 v[196:197], v144 offset:0x3800
	s_waitcnt lgkmcnt(0)
	s_nop 0
	v_mfma_f32_32x32x16_bf16 v[0:15], v[176:179], v[180:183], v[0:15]
	ds_read_b64_tr_b16 v[180:181], v144 offset:0x200
	ds_read_b64_tr_b16 v[182:183], v144 offset:0xa00
	v_mfma_f32_32x32x16_bf16 v[0:15], v[156:159], v[184:187], v[0:15]
	ds_read_b64_tr_b16 v[184:185], v144 offset:0x1200
	ds_read_b64_tr_b16 v[186:187], v144 offset:0x1a00
	v_mfma_f32_32x32x16_bf16 v[0:15], v[152:155], v[188:191], v[0:15]
	ds_read_b64_tr_b16 v[188:189], v144 offset:0x2200
	ds_read_b64_tr_b16 v[190:191], v144 offset:0x2a00
	ds_read_b64_tr_b16 v[198:199], v144 offset:0x3200
	ds_read_b64_tr_b16 v[200:201], v144 offset:0x3a00
	s_waitcnt lgkmcnt(0)
	v_mfma_f32_32x32x16_bf16 v[0:15], v[160:163], v[194:197], v[0:15]
	v_mfma_f32_32x32x16_bf16 v[48:63], v[176:179], v[180:183], v[48:63]
	ds_read_b64_tr_b16 v[180:181], v144 offset:0x400
	ds_read_b64_tr_b16 v[182:183], v144 offset:0xc00
	v_mfma_f32_32x32x16_bf16 v[48:63], v[156:159], v[184:187], v[48:63]
	ds_read_b64_tr_b16 v[184:185], v144 offset:0x1400
	ds_read_b64_tr_b16 v[186:187], v144 offset:0x1c00
	v_mfma_f32_32x32x16_bf16 v[48:63], v[152:155], v[188:191], v[48:63]
	ds_read_b64_tr_b16 v[188:189], v144 offset:0x2400
	ds_read_b64_tr_b16 v[190:191], v144 offset:0x2c00
	ds_read_b64_tr_b16 v[194:195], v144 offset:0x3400
	ds_read_b64_tr_b16 v[196:197], v144 offset:0x3c00
	s_waitcnt lgkmcnt(0)
	v_mfma_f32_32x32x16_bf16 v[48:63], v[160:163], v[198:201], v[48:63]
	v_mfma_f32_32x32x16_bf16 v[32:47], v[176:179], v[180:183], v[32:47]
	ds_read_b64_tr_b16 v[180:181], v144 offset:0x600
	ds_read_b64_tr_b16 v[182:183], v144 offset:0xe00
	v_mfma_f32_32x32x16_bf16 v[32:47], v[156:159], v[184:187], v[32:47]
	ds_read_b64_tr_b16 v[184:185], v144 offset:0x1600
	ds_read_b64_tr_b16 v[186:187], v144 offset:0x1e00
	v_mfma_f32_32x32x16_bf16 v[32:47], v[152:155], v[188:191], v[32:47]
	ds_read_b64_tr_b16 v[188:189], v144 offset:0x2600
	ds_read_b64_tr_b16 v[190:191], v144 offset:0x2e00
	ds_read_b64_tr_b16 v[198:199], v144 offset:0x3600
	ds_read_b64_tr_b16 v[200:201], v144 offset:0x3e00
	s_waitcnt lgkmcnt(0)
	v_mfma_f32_32x32x16_bf16 v[32:47], v[160:163], v[194:197], v[32:47]
	v_mfma_f32_32x32x16_bf16 v[16:31], v[176:179], v[180:183], v[16:31]
	v_max_f32_e32 v144, v81, v81
	v_max_f32_e32 v151, v80, v80
	v_max_f32_e32 v144, v151, v144
	v_max3_f32 v144, v144, v82, v83
	v_max3_f32 v144, v144, v84, v85
	v_max3_f32 v144, v144, v86, v87
	v_max3_f32 v144, v144, v88, v89
	v_max3_f32 v144, v144, v90, v91
	v_mfma_f32_32x32x16_bf16 v[16:31], v[156:159], v[184:187], v[16:31]
	v_max3_f32 v144, v144, v92, v93
	v_max3_f32 v144, v144, v94, v95
	v_max3_f32 v144, v144, v64, v65
	v_max3_f32 v144, v144, v66, v67
	v_max3_f32 v144, v144, v68, v69
	v_max3_f32 v144, v144, v70, v71
	v_max3_f32 v144, v144, v72, v73
	v_max3_f32 v144, v144, v74, v75
	v_mfma_f32_32x32x16_bf16 v[16:31], v[152:155], v[188:191], v[16:31]
	v_max3_f32 v144, v144, v76, v77
	v_max3_f32 v144, v144, v78, v79
	v_mov_b32_e32 v151, v144
	s_nop 1
	v_permlane32_swap_b32_e32 v144, v151
	v_max_f32_e32 v151, v151, v151
	v_max_f32_e32 v144, v144, v144
	v_max_f32_e32 v144, v144, v151
	v_max_f32_e32 v151, v150, v150
	v_max_f32_e32 v151, v151, v144
	v_sub_f32_e32 v152, v144, v150
	v_mfma_f32_32x32x16_bf16 v[16:31], v[160:163], v[198:201], v[16:31]
	v_sub_f32_e32 v144, v150, v151
	v_mul_f32_e32 v144, 0x3dd53b94, v144
	v_exp_f32_e32 v144, v144
	v_cmp_ge_f32_e32 vcc, s63, v152
	s_cmp_eq_u64 vcc, exec
	s_cselect_b64 s[4:5], -1, 0
	s_waitcnt vmcnt(0)
	v_cndmask_b32_e64 v144, v144, 1.0, s[4:5]
	v_cmp_gt_f32_e32 vcc, 1.0, v144
	s_waitcnt vmcnt(0)
	s_barrier
	s_cbranch_vccz .LBB0_1106
	s_and_saveexec_b64 s[34:35], s[2:3]
	ds_write_b32 v149, v144 offset:128
	s_or_b64 exec, exec, s[34:35]
	s_waitcnt lgkmcnt(0)
	v_add_u32_e32 v164, v147, v148
	ds_read_b128 v[152:155], v164 offset:224
	ds_read_b128 v[156:159], v164 offset:192
	ds_read_b128 v[160:163], v164 offset:160
	ds_read_b128 v[176:179], v164 offset:128
	s_waitcnt lgkmcnt(3)
	v_pk_mul_f32 v[12:13], v[12:13], v[152:153]
	s_waitcnt lgkmcnt(2)
	v_pk_mul_f32 v[8:9], v[8:9], v[156:157]
	s_waitcnt lgkmcnt(1)
	v_pk_mul_f32 v[4:5], v[4:5], v[160:161]
	v_pk_mul_f32 v[14:15], v[14:15], v[154:155]
	v_pk_mul_f32 v[10:11], v[10:11], v[158:159]
	v_pk_mul_f32 v[6:7], v[6:7], v[162:163]
	s_waitcnt lgkmcnt(0)
	v_pk_mul_f32 v[2:3], v[2:3], v[178:179]
	v_pk_mul_f32 v[0:1], v[0:1], v[176:177]
	v_pk_mul_f32 v[60:61], v[60:61], v[152:153]
	v_pk_mul_f32 v[56:57], v[56:57], v[156:157]
	v_pk_mul_f32 v[52:53], v[52:53], v[160:161]
	v_pk_mul_f32 v[62:63], v[62:63], v[154:155]
	v_pk_mul_f32 v[58:59], v[58:59], v[158:159]
	v_pk_mul_f32 v[54:55], v[54:55], v[162:163]
	v_pk_mul_f32 v[50:51], v[50:51], v[178:179]
	v_pk_mul_f32 v[48:49], v[48:49], v[176:177]
	v_pk_mul_f32 v[44:45], v[44:45], v[152:153]
	v_pk_mul_f32 v[40:41], v[40:41], v[156:157]
	v_pk_mul_f32 v[36:37], v[36:37], v[160:161]
	v_pk_mul_f32 v[46:47], v[46:47], v[154:155]
	v_pk_mul_f32 v[42:43], v[42:43], v[158:159]
	v_pk_mul_f32 v[38:39], v[38:39], v[162:163]
	v_pk_mul_f32 v[34:35], v[34:35], v[178:179]
	v_pk_mul_f32 v[32:33], v[32:33], v[176:177]
	v_pk_mul_f32 v[28:29], v[28:29], v[152:153]
	v_pk_mul_f32 v[24:25], v[24:25], v[156:157]
	v_pk_mul_f32 v[20:21], v[20:21], v[160:161]
	v_pk_mul_f32 v[30:31], v[30:31], v[154:155]
	v_pk_mul_f32 v[26:27], v[26:27], v[158:159]
	v_pk_mul_f32 v[22:23], v[22:23], v[162:163]
	v_pk_mul_f32 v[18:19], v[18:19], v[178:179]
	v_pk_mul_f32 v[16:17], v[16:17], v[176:177]

.LBB0_1126:
	s_add_u32 s57, s2, s28
	ds_read_b128 v[0:3], v70
	ds_read_b128 v[4:7], v70 offset:1024
	ds_read_b128 v[8:11], v70 offset:2048
	ds_read_b128 v[12:15], v70 offset:3072
	s_addc_u32 s58, s3, s29
	s_and_b64 s[28:29], s[36:37], exec
	s_cselect_b32 s29, s58, s35
	s_cselect_b32 s28, s57, s34
	s_add_u32 s38, s1, s38
	s_addc_u32 s39, s14, s39
	s_and_b64 s[36:37], s[36:37], exec
	s_cselect_b32 s5, s39, s5
	s_cselect_b32 s4, s38, s4
	v_lshl_add_u64 v[48:49], s[34:35], 0, v[66:67]
	s_mov_b32 m0, s46
	v_lshl_add_u64 v[50:51], v[48:49], 0, s[24:25]
	ds_read_b128 v[16:19], v71
	ds_read_b128 v[20:23], v71 offset:1024
	ds_read_b128 v[24:27], v71 offset:2048
	ds_read_b128 v[28:31], v71 offset:3072
	ds_read_b128 v[32:35], v71 offset:4096
	ds_read_b128 v[36:39], v71 offset:5120
	ds_read_b128 v[40:43], v71 offset:6144
	ds_read_b128 v[44:47], v71 offset:7168
	global_load_lds_dwordx4 v[50:51], off
	v_lshl_add_u64 v[48:49], v[48:49], 0, s[26:27]
	s_mov_b32 m0, s47
	s_nop 0
	global_load_lds_dwordx4 v[48:49], off
	s_waitcnt lgkmcnt(8)
	s_barrier
	s_waitcnt lgkmcnt(0)
	s_waitcnt lgkmcnt(0)
	v_mfma_f32_16x16x32_bf16 v[52:55], v[8:11], v[16:19], 0
	v_mfma_f32_16x16x32_bf16 v[56:59], v[12:15], v[20:23], v[52:55]
	v_mfma_f32_16x16x32_bf16 v[52:55], v[0:3], v[24:27], 0
	v_mfma_f32_16x16x32_bf16 v[60:63], v[4:7], v[28:31], v[52:55]
	v_mfma_f32_16x16x32_bf16 v[52:55], v[8:11], v[24:27], 0
	v_mfma_f32_16x16x32_bf16 v[48:51], v[0:3], v[16:19], 0
	v_mfma_f32_16x16x32_bf16 v[76:79], v[12:15], v[28:31], v[52:55]
	v_mfma_f32_16x16x32_bf16 v[52:55], v[0:3], v[32:35], 0
	v_mfma_f32_16x16x32_bf16 v[0:3], v[0:3], v[40:43], 0
	v_mfma_f32_16x16x32_bf16 v[48:51], v[4:7], v[20:23], v[48:51]
	v_mfma_f32_16x16x32_bf16 v[80:83], v[4:7], v[36:39], v[52:55]
	v_mfma_f32_16x16x32_bf16 v[0:3], v[4:7], v[44:47], v[0:3]
	v_mfma_f32_16x16x32_bf16 v[4:7], v[8:11], v[40:43], 0
	v_mfma_f32_16x16x32_bf16 v[52:55], v[8:11], v[32:35], 0
	v_mfma_f32_16x16x32_bf16 v[8:11], v[12:15], v[44:47], v[4:7]
	v_mfma_f32_16x16x32_bf16 v[84:87], v[12:15], v[36:39], v[52:55]
	s_barrier
	s_mov_b32 m0, s48
	v_lshl_add_u64 v[144:145], s[4:5], 0, v[64:65]
	s_nop 0
	ds_read_b128 v[4:7], v72
	ds_read_b128 v[12:15], v72 offset:1024
	ds_read_b128 v[52:55], v72 offset:2048
	ds_read_b128 v[88:91], v72 offset:3072
	global_load_lds_dwordx4 v[144:145], off
	v_lshl_add_u64 v[92:93], v[144:145], 0, s[16:17]
	s_mov_b32 m0, s49
	s_nop 0
	global_load_lds_dwordx4 v[92:93], off
	s_barrier
	s_waitcnt lgkmcnt(0)
	s_waitcnt lgkmcnt(0)
	v_mfma_f32_16x16x32_bf16 v[92:95], v[4:7], v[16:19], 0
	v_mfma_f32_16x16x32_bf16 v[16:19], v[52:55], v[16:19], 0
	v_mfma_f32_16x16x32_bf16 v[96:99], v[88:91], v[20:23], v[16:19]
	v_mfma_f32_16x16x32_bf16 v[16:19], v[4:7], v[24:27], 0
	v_mfma_f32_16x16x32_bf16 v[100:103], v[12:15], v[28:31], v[16:19]
	v_mfma_f32_16x16x32_bf16 v[16:19], v[52:55], v[24:27], 0
	v_mfma_f32_16x16x32_bf16 v[24:27], v[88:91], v[28:31], v[16:19]
	v_mfma_f32_16x16x32_bf16 v[16:19], v[4:7], v[32:35], 0
	v_mfma_f32_16x16x32_bf16 v[4:7], v[4:7], v[40:43], 0
	v_mfma_f32_16x16x32_bf16 v[92:95], v[12:15], v[20:23], v[92:95]
	v_mfma_f32_16x16x32_bf16 v[28:31], v[12:15], v[36:39], v[16:19]
	v_mfma_f32_16x16x32_bf16 v[16:19], v[52:55], v[32:35], 0
	v_mfma_f32_16x16x32_bf16 v[12:15], v[12:15], v[44:47], v[4:7]
	v_mfma_f32_16x16x32_bf16 v[4:7], v[52:55], v[40:43], 0
	v_mfma_f32_16x16x32_bf16 v[104:107], v[88:91], v[36:39], v[16:19]
	v_mfma_f32_16x16x32_bf16 v[88:91], v[88:91], v[44:47], v[4:7]
	s_mov_b32 m0, s30
	v_lshl_add_u64 v[146:147], s[28:29], 0, v[66:67]
	s_barrier
	global_load_lds_dwordx4 v[146:147], off
	s_nop 0
	v_lshl_add_u64 v[4:5], v[146:147], 0, s[16:17]
	s_mov_b32 m0, s31
	s_nop 0
	global_load_lds_dwordx4 v[4:5], off
	s_barrier
	s_waitcnt lgkmcnt(0)
	s_barrier
	s_mov_b32 m0, s50
	v_lshl_add_u64 v[4:5], v[144:145], 0, s[10:11]
	global_load_lds_dwordx4 v[4:5], off
	v_lshl_add_u64 v[4:5], v[144:145], 0, s[18:19]
	s_mov_b32 m0, s51
	s_nop 0
	global_load_lds_dwordx4 v[4:5], off
	s_waitcnt vmcnt(6)
	s_barrier
	s_barrier
	ds_read_b128 v[4:7], v73
	ds_read_b128 v[40:43], v73 offset:1024
	ds_read_b128 v[44:47], v73 offset:2048
	ds_read_b128 v[108:111], v73 offset:3072
	s_mov_b32 m0, s33
	v_lshl_add_u64 v[16:17], v[146:147], 0, s[10:11]
	ds_read_b128 v[112:115], v71 offset:32768
	ds_read_b128 v[116:119], v71 offset:33792
	ds_read_b128 v[120:123], v71 offset:34816
	ds_read_b128 v[124:127], v71 offset:35840
	ds_read_b128 v[128:131], v71 offset:36864
	ds_read_b128 v[132:135], v71 offset:37888
	ds_read_b128 v[136:139], v71 offset:38912
	ds_read_b128 v[140:143], v71 offset:39936
	global_load_lds_dwordx4 v[16:17], off
	v_lshl_add_u64 v[16:17], v[146:147], 0, s[18:19]
	s_mov_b32 m0, s40
	s_nop 0
	global_load_lds_dwordx4 v[16:17], off
	s_waitcnt lgkmcnt(8)
	s_barrier
	s_waitcnt lgkmcnt(0)
	s_waitcnt lgkmcnt(0)
	v_mfma_f32_16x16x32_bf16 v[16:19], v[4:7], v[112:115], v[48:51]
	v_mfma_f32_16x16x32_bf16 v[52:55], v[40:43], v[116:119], v[16:19]
	v_mfma_f32_16x16x32_bf16 v[16:19], v[44:47], v[112:115], v[56:59]
	v_mfma_f32_16x16x32_bf16 v[48:51], v[108:111], v[116:119], v[16:19]
	v_mfma_f32_16x16x32_bf16 v[16:19], v[4:7], v[120:123], v[60:63]
	v_mfma_f32_16x16x32_bf16 v[36:39], v[40:43], v[124:127], v[16:19]
	v_mfma_f32_16x16x32_bf16 v[16:19], v[44:47], v[120:123], v[76:79]
	v_mfma_f32_16x16x32_bf16 v[32:35], v[108:111], v[124:127], v[16:19]
	v_mfma_f32_16x16x32_bf16 v[16:19], v[4:7], v[128:131], v[80:83]
	v_mfma_f32_16x16x32_bf16 v[0:3], v[4:7], v[136:139], v[0:3]
	v_mfma_f32_16x16x32_bf16 v[20:23], v[40:43], v[132:135], v[16:19]
	v_mfma_f32_16x16x32_bf16 v[16:19], v[44:47], v[128:131], v[84:87]
	v_mfma_f32_16x16x32_bf16 v[4:7], v[40:43], v[140:143], v[0:3]
	v_mfma_f32_16x16x32_bf16 v[0:3], v[44:47], v[136:139], v[8:11]
	v_mfma_f32_16x16x32_bf16 v[16:19], v[108:111], v[132:135], v[16:19]
	v_mfma_f32_16x16x32_bf16 v[0:3], v[108:111], v[140:143], v[0:3]
	s_barrier
	s_mov_b32 m0, s52
	v_lshl_add_u64 v[40:41], v[144:145], 0, s[20:21]
	ds_read_b128 v[8:11], v74
	ds_read_b128 v[76:79], v74 offset:1024
	ds_read_b128 v[80:83], v74 offset:2048
	ds_read_b128 v[84:87], v74 offset:3072
	global_load_lds_dwordx4 v[40:41], off
	v_lshl_add_u64 v[40:41], v[144:145], 0, s[22:23]
	s_mov_b32 m0, s53
	s_nop 0
	global_load_lds_dwordx4 v[40:41], off
	s_barrier
	s_waitcnt lgkmcnt(0)
	s_waitcnt lgkmcnt(0)
	v_mfma_f32_16x16x32_bf16 v[40:43], v[8:11], v[112:115], v[92:95]
	v_mfma_f32_16x16x32_bf16 v[60:63], v[76:79], v[116:119], v[40:43]
	v_mfma_f32_16x16x32_bf16 v[40:43], v[80:83], v[112:115], v[96:99]
	v_mfma_f32_16x16x32_bf16 v[56:59], v[84:87], v[116:119], v[40:43]
	v_mfma_f32_16x16x32_bf16 v[40:43], v[8:11], v[120:123], v[100:103]
	v_mfma_f32_16x16x32_bf16 v[24:27], v[80:83], v[120:123], v[24:27]
	v_mfma_f32_16x16x32_bf16 v[44:47], v[76:79], v[124:127], v[40:43]
	v_mfma_f32_16x16x32_bf16 v[40:43], v[84:87], v[124:127], v[24:27]
	v_mfma_f32_16x16x32_bf16 v[24:27], v[8:11], v[128:131], v[28:31]
	v_mfma_f32_16x16x32_bf16 v[8:11], v[8:11], v[136:139], v[12:15]
	v_mfma_f32_16x16x32_bf16 v[28:31], v[76:79], v[132:135], v[24:27]
	v_mfma_f32_16x16x32_bf16 v[24:27], v[80:83], v[128:131], v[104:107]
	v_mfma_f32_16x16x32_bf16 v[12:15], v[76:79], v[140:143], v[8:11]
	v_mfma_f32_16x16x32_bf16 v[8:11], v[80:83], v[136:139], v[88:91]
	v_mfma_f32_16x16x32_bf16 v[24:27], v[84:87], v[132:135], v[24:27]
	v_mfma_f32_16x16x32_bf16 v[8:11], v[84:87], v[140:143], v[8:11]
	s_mov_b32 m0, s42
	v_lshl_add_u64 v[76:77], v[146:147], 0, s[20:21]
	s_barrier
	global_load_lds_dwordx4 v[76:77], off
	v_lshl_add_u64 v[76:77], v[146:147], 0, s[22:23]
	s_mov_b32 m0, s43
	s_nop 0
	global_load_lds_dwordx4 v[76:77], off
	s_barrier
	s_waitcnt lgkmcnt(0)
	s_barrier
	s_mov_b32 m0, s54
	v_lshl_add_u64 v[76:77], v[144:145], 0, s[24:25]
	global_load_lds_dwordx4 v[76:77], off
	v_lshl_add_u64 v[76:77], v[144:145], 0, s[26:27]
	s_mov_b32 m0, s55
	s_nop 0
	global_load_lds_dwordx4 v[76:77], off
	s_waitcnt vmcnt(6)
	s_barrier
	v_mov_b32_e32 v68, v166
	s_mov_b32 s34, s44
	s_mov_b32 s35, s15
	s_barrier
	s_cmp_lg_u32 s35, 0
	s_cbranch_scc1 .LBB0_1128
	s_lshl_b32 s36, s56, 8
	s_and_b32 s36, s36, 0x100
	s_lshl_b32 s34, s34, 5
	s_add_i32 s34, s34, s36
	v_lshrrev_b32_e32 v75, 1, v68
	v_and_or_b32 v76, v75, 24, s34
	s_lshl_b32 s34, s56, 11
	s_ashr_i32 s35, s56, 2
	s_and_b32 s34, s34, 0x1000
	v_lshlrev_b32_e32 v68, 6, v68
	v_and_b32_e32 v68, 0x3c0, v68
	s_add_i32 s34, s34, s35
	v_add_u32_e32 v78, s34, v68
	v_ashrrev_i32_e32 v79, 31, v78
	v_ashrrev_i32_e32 v77, 31, v76
	v_lshlrev_b64 v[80:81], 12, v[78:79]
	v_lshl_add_u64 v[80:81], s[8:9], 0, v[80:81]
	v_lshlrev_b64 v[76:77], 1, v[76:77]
	v_lshl_add_u64 v[80:81], v[80:81], 0, v[76:77]
	v_cvt_pk_bf16_f32 v52, v52, v53
	v_cvt_pk_bf16_f32 v53, v54, v55
	v_cvt_pk_bf16_f32 v54, v48, v49
	v_cvt_pk_bf16_f32 v55, v50, v51
	global_store_dwordx4 v[80:81], v[52:55], off
	v_cvt_pk_bf16_f32 v48, v60, v61
	v_cvt_pk_bf16_f32 v49, v62, v63
	v_add_u32_e32 v68, 0x400, v78
	v_cvt_pk_bf16_f32 v50, v56, v57
	v_cvt_pk_bf16_f32 v51, v58, v59
	global_store_dwordx4 v[80:81], v[48:51], off offset:256
	v_cvt_pk_bf16_f32 v36, v36, v37
	v_cvt_pk_bf16_f32 v37, v38, v39
	v_cvt_pk_bf16_f32 v38, v32, v33
	v_cvt_pk_bf16_f32 v39, v34, v35
	s_nop 1
	v_lshlrev_b64 v[48:49], 12, v[68:69]
	v_lshl_add_u64 v[48:49], s[8:9], 0, v[48:49]
	v_lshl_add_u64 v[48:49], v[48:49], 0, v[76:77]
	global_store_dwordx4 v[48:49], v[36:39], off
	v_cvt_pk_bf16_f32 v32, v44, v45
	v_cvt_pk_bf16_f32 v33, v46, v47
	v_add_u32_e32 v68, 0x800, v78
	v_cvt_pk_bf16_f32 v34, v40, v41
	v_cvt_pk_bf16_f32 v35, v42, v43
	global_store_dwordx4 v[48:49], v[32:35], off offset:256
	v_cvt_pk_bf16_f32 v20, v20, v21
	v_cvt_pk_bf16_f32 v21, v22, v23
	v_cvt_pk_bf16_f32 v22, v16, v17
	v_cvt_pk_bf16_f32 v23, v18, v19
	s_nop 1
	v_lshlrev_b64 v[32:33], 12, v[68:69]
	v_lshl_add_u64 v[32:33], s[8:9], 0, v[32:33]
	v_lshl_add_u64 v[32:33], v[32:33], 0, v[76:77]
	global_store_dwordx4 v[32:33], v[20:23], off
	v_cvt_pk_bf16_f32 v16, v28, v29
	v_cvt_pk_bf16_f32 v17, v30, v31
	v_add_u32_e32 v68, 0xc00, v78
	v_cvt_pk_bf16_f32 v18, v24, v25
	v_cvt_pk_bf16_f32 v19, v26, v27
	global_store_dwordx4 v[32:33], v[16:19], off offset:256
	v_cvt_pk_bf16_f32 v4, v4, v5
	v_cvt_pk_bf16_f32 v5, v6, v7
	v_cvt_pk_bf16_f32 v6, v0, v1
	v_cvt_pk_bf16_f32 v7, v2, v3
	s_nop 1
	v_lshlrev_b64 v[16:17], 12, v[68:69]
	v_lshl_add_u64 v[16:17], s[8:9], 0, v[16:17]
	v_lshl_add_u64 v[16:17], v[16:17], 0, v[76:77]
	global_store_dwordx4 v[16:17], v[4:7], off
	v_cvt_pk_bf16_f32 v0, v12, v13
	v_cvt_pk_bf16_f32 v1, v14, v15
	v_cvt_pk_bf16_f32 v2, v8, v9
	v_cvt_pk_bf16_f32 v3, v10, v11
	global_store_dwordx4 v[16:17], v[0:3], off offset:256

.LBB0_1162:
	s_add_i32 s2, s68, 2
	v_add_u32_e32 v1, s60, v199
	s_add_u32 s3, s44, s34
	ds_read_b128 v[132:135], v1
	ds_read_b128 v[136:139], v1 offset:1024
	ds_read_b128 v[140:143], v1 offset:2048
	ds_read_b128 v[144:147], v1 offset:3072
	s_addc_u32 s28, s45, s35
	s_add_u32 s3, s3, 0x100
	s_addc_u32 s28, s28, 0
	s_add_u32 s69, s66, s34
	s_addc_u32 s72, s67, s35
	s_cmpk_eq_i32 s34, 0xf00
	s_cselect_b32 s71, s41, s28
	s_cselect_b32 s70, s40, s3
	s_cselect_b32 s73, s43, s72
	s_cselect_b32 s72, s42, s69
	v_lshl_add_u64 v[2:3], v[194:195], 0, s[34:35]
	v_lshl_add_u64 v[180:181], v[2:3], 0, s[24:25]
	s_add_i32 m0, s48, 0xc000
	ds_read_b128 v[148:151], v200
	ds_read_b128 v[152:155], v200 offset:1024
	ds_read_b128 v[156:159], v200 offset:2048
	ds_read_b128 v[160:163], v200 offset:3072
	ds_read_b128 v[164:167], v200 offset:4096
	ds_read_b128 v[168:171], v200 offset:5120
	ds_read_b128 v[172:175], v200 offset:6144
	ds_read_b128 v[176:179], v200 offset:7168
	global_load_lds_dwordx4 v[180:181], off
	v_lshl_add_u64 v[2:3], v[2:3], 0, s[26:27]
	s_add_i32 m0, s48, 0xe000
	s_nop 0
	global_load_lds_dwordx4 v[2:3], off
	s_waitcnt lgkmcnt(8)
	s_barrier
	s_waitcnt lgkmcnt(0)
	s_waitcnt lgkmcnt(0)
	v_mfma_f32_16x16x32_bf16 v[128:131], v[132:135], v[148:151], v[128:131]
	v_mfma_f32_16x16x32_bf16 v[124:127], v[140:143], v[148:151], v[124:127]
	v_mfma_f32_16x16x32_bf16 v[112:115], v[132:135], v[156:159], v[112:115]
	v_mfma_f32_16x16x32_bf16 v[108:111], v[140:143], v[156:159], v[108:111]
	v_mfma_f32_16x16x32_bf16 v[96:99], v[132:135], v[164:167], v[96:99]
	v_mfma_f32_16x16x32_bf16 v[92:95], v[140:143], v[164:167], v[92:95]
	v_mfma_f32_16x16x32_bf16 v[80:83], v[132:135], v[172:175], v[80:83]
	v_mfma_f32_16x16x32_bf16 v[76:79], v[140:143], v[172:175], v[76:79]
	v_mfma_f32_16x16x32_bf16 v[128:131], v[136:139], v[152:155], v[128:131]
	v_mfma_f32_16x16x32_bf16 v[124:127], v[144:147], v[152:155], v[124:127]
	v_mfma_f32_16x16x32_bf16 v[112:115], v[136:139], v[160:163], v[112:115]
	v_mfma_f32_16x16x32_bf16 v[108:111], v[144:147], v[160:163], v[108:111]
	v_mfma_f32_16x16x32_bf16 v[96:99], v[136:139], v[168:171], v[96:99]
	v_mfma_f32_16x16x32_bf16 v[92:95], v[144:147], v[168:171], v[92:95]
	v_mfma_f32_16x16x32_bf16 v[80:83], v[136:139], v[176:179], v[80:83]
	v_mfma_f32_16x16x32_bf16 v[76:79], v[144:147], v[176:179], v[76:79]
	s_barrier
	s_add_i32 s3, s60, s47
	v_add_u32_e32 v1, s61, v199
	v_lshl_add_u64 v[196:197], s[72:73], 0, v[188:189]
	s_mov_b32 m0, s3
	ds_read_b128 v[180:183], v1
	ds_read_b128 v[184:187], v1 offset:1024
	ds_read_b128 v[202:205], v1 offset:2048
	ds_read_b128 v[206:209], v1 offset:3072
	global_load_lds_dwordx4 v[196:197], off
	v_lshl_add_u64 v[2:3], v[196:197], 0, s[6:7]
	s_add_i32 m0, s3, 0x2000
	s_nop 0
	global_load_lds_dwordx4 v[2:3], off
	s_barrier
	s_waitcnt lgkmcnt(0)
	s_waitcnt lgkmcnt(0)
	v_mfma_f32_16x16x32_bf16 v[120:123], v[180:183], v[148:151], v[120:123]
	v_mfma_f32_16x16x32_bf16 v[116:119], v[202:205], v[148:151], v[116:119]
	v_mfma_f32_16x16x32_bf16 v[104:107], v[180:183], v[156:159], v[104:107]
	v_mfma_f32_16x16x32_bf16 v[100:103], v[202:205], v[156:159], v[100:103]
	v_mfma_f32_16x16x32_bf16 v[88:91], v[180:183], v[164:167], v[88:91]
	v_mfma_f32_16x16x32_bf16 v[84:87], v[202:205], v[164:167], v[84:87]
	v_mfma_f32_16x16x32_bf16 v[72:75], v[180:183], v[172:175], v[72:75]
	v_mfma_f32_16x16x32_bf16 v[68:71], v[202:205], v[172:175], v[68:71]
	v_mfma_f32_16x16x32_bf16 v[120:123], v[184:187], v[152:155], v[120:123]
	v_mfma_f32_16x16x32_bf16 v[116:119], v[206:209], v[152:155], v[116:119]
	v_mfma_f32_16x16x32_bf16 v[104:107], v[184:187], v[160:163], v[104:107]
	v_mfma_f32_16x16x32_bf16 v[100:103], v[206:209], v[160:163], v[100:103]
	v_mfma_f32_16x16x32_bf16 v[88:91], v[184:187], v[168:171], v[88:91]
	v_mfma_f32_16x16x32_bf16 v[84:87], v[206:209], v[168:171], v[84:87]
	v_mfma_f32_16x16x32_bf16 v[72:75], v[184:187], v[176:179], v[72:75]
	v_mfma_f32_16x16x32_bf16 v[68:71], v[206:209], v[176:179], v[68:71]
	s_mov_b32 m0, s48
	v_lshl_add_u64 v[210:211], s[70:71], 0, v[190:191]
	s_barrier
	ds_read_b128 v[148:151], v200 offset:16384
	ds_read_b128 v[152:155], v200 offset:17408
	ds_read_b128 v[156:159], v200 offset:18432
	ds_read_b128 v[160:163], v200 offset:19456
	ds_read_b128 v[164:167], v200 offset:20480
	ds_read_b128 v[168:171], v200 offset:21504
	ds_read_b128 v[172:175], v200 offset:22528
	ds_read_b128 v[176:179], v200 offset:23552
	global_load_lds_dwordx4 v[210:211], off
	v_lshl_add_u64 v[2:3], v[210:211], 0, s[6:7]
	s_mov_b32 m0, s49
	s_nop 0
	global_load_lds_dwordx4 v[2:3], off
	s_barrier
	s_waitcnt lgkmcnt(0)
	s_waitcnt lgkmcnt(0)
	v_mfma_f32_16x16x32_bf16 v[64:67], v[132:135], v[148:151], v[64:67]
	v_mfma_f32_16x16x32_bf16 v[60:63], v[140:143], v[148:151], v[60:63]
	v_mfma_f32_16x16x32_bf16 v[48:51], v[132:135], v[156:159], v[48:51]
	v_mfma_f32_16x16x32_bf16 v[44:47], v[140:143], v[156:159], v[44:47]
	v_mfma_f32_16x16x32_bf16 v[32:35], v[132:135], v[164:167], v[32:35]
	v_mfma_f32_16x16x32_bf16 v[28:31], v[140:143], v[164:167], v[28:31]
	v_mfma_f32_16x16x32_bf16 v[16:19], v[132:135], v[172:175], v[16:19]
	v_mfma_f32_16x16x32_bf16 v[12:15], v[140:143], v[172:175], v[12:15]
	v_mfma_f32_16x16x32_bf16 v[64:67], v[136:139], v[152:155], v[64:67]
	v_mfma_f32_16x16x32_bf16 v[60:63], v[144:147], v[152:155], v[60:63]
	v_mfma_f32_16x16x32_bf16 v[48:51], v[136:139], v[160:163], v[48:51]
	v_mfma_f32_16x16x32_bf16 v[44:47], v[144:147], v[160:163], v[44:47]
	v_mfma_f32_16x16x32_bf16 v[32:35], v[136:139], v[168:171], v[32:35]
	v_mfma_f32_16x16x32_bf16 v[28:31], v[144:147], v[168:171], v[28:31]
	v_mfma_f32_16x16x32_bf16 v[16:19], v[136:139], v[176:179], v[16:19]
	v_mfma_f32_16x16x32_bf16 v[12:15], v[144:147], v[176:179], v[12:15]
	s_barrier
	s_add_i32 s3, s61, s47
	v_lshl_add_u64 v[2:3], v[196:197], 0, s[8:9]
	s_mov_b32 m0, s3
	s_nop 0
	global_load_lds_dwordx4 v[2:3], off
	v_lshl_add_u64 v[2:3], v[196:197], 0, s[10:11]
	s_add_i32 m0, s3, 0x2000
	s_nop 0
	global_load_lds_dwordx4 v[2:3], off
	s_waitcnt vmcnt(6)
	s_barrier
	v_mfma_f32_16x16x32_bf16 v[56:59], v[180:183], v[148:151], v[56:59]
	v_mfma_f32_16x16x32_bf16 v[52:55], v[202:205], v[148:151], v[52:55]
	v_mfma_f32_16x16x32_bf16 v[40:43], v[180:183], v[156:159], v[40:43]
	v_mfma_f32_16x16x32_bf16 v[36:39], v[202:205], v[156:159], v[36:39]
	v_mfma_f32_16x16x32_bf16 v[24:27], v[180:183], v[164:167], v[24:27]
	v_mfma_f32_16x16x32_bf16 v[20:23], v[202:205], v[164:167], v[20:23]
	v_mfma_f32_16x16x32_bf16 v[8:11], v[180:183], v[172:175], v[8:11]
	v_mfma_f32_16x16x32_bf16 v[2:5], v[202:205], v[172:175], v[4:7]
	v_mfma_f32_16x16x32_bf16 v[56:59], v[184:187], v[152:155], v[56:59]
	v_mfma_f32_16x16x32_bf16 v[52:55], v[206:209], v[152:155], v[52:55]
	v_mfma_f32_16x16x32_bf16 v[40:43], v[184:187], v[160:163], v[40:43]
	v_mfma_f32_16x16x32_bf16 v[36:39], v[206:209], v[160:163], v[36:39]
	v_mfma_f32_16x16x32_bf16 v[24:27], v[184:187], v[168:171], v[24:27]
	v_mfma_f32_16x16x32_bf16 v[20:23], v[206:209], v[168:171], v[20:23]
	v_mfma_f32_16x16x32_bf16 v[8:11], v[184:187], v[176:179], v[8:11]
	v_mfma_f32_16x16x32_bf16 v[2:5], v[206:209], v[176:179], v[2:5]
	s_add_i32 s3, 0, 0x18000
	v_add_u32_e32 v1, s3, v199
	s_barrier
	ds_read_b128 v[132:135], v1
	ds_read_b128 v[136:139], v1 offset:1024
	ds_read_b128 v[140:143], v1 offset:2048
	ds_read_b128 v[144:147], v1 offset:3072
	s_mov_b32 m0, s50
	v_lshl_add_u64 v[6:7], v[210:211], 0, s[8:9]
	ds_read_b128 v[148:151], v200 offset:32768
	ds_read_b128 v[152:155], v200 offset:33792
	ds_read_b128 v[156:159], v200 offset:34816
	ds_read_b128 v[160:163], v200 offset:35840
	ds_read_b128 v[164:167], v200 offset:36864
	ds_read_b128 v[168:171], v200 offset:37888
	ds_read_b128 v[172:175], v200 offset:38912
	ds_read_b128 v[176:179], v200 offset:39936
	global_load_lds_dwordx4 v[6:7], off
	v_lshl_add_u64 v[6:7], v[210:211], 0, s[10:11]
	s_mov_b32 m0, s51
	s_nop 0
	global_load_lds_dwordx4 v[6:7], off
	s_waitcnt lgkmcnt(8)
	s_barrier
	s_waitcnt lgkmcnt(0)
	s_waitcnt lgkmcnt(0)
	v_mfma_f32_16x16x32_bf16 v[128:131], v[132:135], v[148:151], v[128:131]
	v_mfma_f32_16x16x32_bf16 v[124:127], v[140:143], v[148:151], v[124:127]
	v_mfma_f32_16x16x32_bf16 v[112:115], v[132:135], v[156:159], v[112:115]
	v_mfma_f32_16x16x32_bf16 v[108:111], v[140:143], v[156:159], v[108:111]
	v_mfma_f32_16x16x32_bf16 v[96:99], v[132:135], v[164:167], v[96:99]
	v_mfma_f32_16x16x32_bf16 v[92:95], v[140:143], v[164:167], v[92:95]
	v_mfma_f32_16x16x32_bf16 v[80:83], v[132:135], v[172:175], v[80:83]
	v_mfma_f32_16x16x32_bf16 v[76:79], v[140:143], v[172:175], v[76:79]
	v_mfma_f32_16x16x32_bf16 v[128:131], v[136:139], v[152:155], v[128:131]
	v_mfma_f32_16x16x32_bf16 v[124:127], v[144:147], v[152:155], v[124:127]
	v_mfma_f32_16x16x32_bf16 v[112:115], v[136:139], v[160:163], v[112:115]
	v_mfma_f32_16x16x32_bf16 v[108:111], v[144:147], v[160:163], v[108:111]
	v_mfma_f32_16x16x32_bf16 v[96:99], v[136:139], v[168:171], v[96:99]
	v_mfma_f32_16x16x32_bf16 v[92:95], v[144:147], v[168:171], v[92:95]
	v_mfma_f32_16x16x32_bf16 v[80:83], v[136:139], v[176:179], v[80:83]
	v_mfma_f32_16x16x32_bf16 v[76:79], v[144:147], v[176:179], v[76:79]
	s_barrier
	s_add_i32 s28, 0, 0x1c000
	s_add_i32 s3, s3, s47
	v_add_u32_e32 v1, s28, v199
	v_lshl_add_u64 v[6:7], v[196:197], 0, s[20:21]
	s_mov_b32 m0, s3
	ds_read_b128 v[180:183], v1
	ds_read_b128 v[184:187], v1 offset:1024
	ds_read_b128 v[202:205], v1 offset:2048
	ds_read_b128 v[206:209], v1 offset:3072
	global_load_lds_dwordx4 v[6:7], off
	v_lshl_add_u64 v[6:7], v[196:197], 0, s[22:23]
	s_add_i32 m0, s3, 0x2000
	s_nop 0
	global_load_lds_dwordx4 v[6:7], off
	s_barrier
	s_waitcnt lgkmcnt(0)
	s_waitcnt lgkmcnt(0)
	v_mfma_f32_16x16x32_bf16 v[120:123], v[180:183], v[148:151], v[120:123]
	v_mfma_f32_16x16x32_bf16 v[116:119], v[202:205], v[148:151], v[116:119]
	v_mfma_f32_16x16x32_bf16 v[104:107], v[180:183], v[156:159], v[104:107]
	v_mfma_f32_16x16x32_bf16 v[100:103], v[202:205], v[156:159], v[100:103]
	v_mfma_f32_16x16x32_bf16 v[88:91], v[180:183], v[164:167], v[88:91]
	v_mfma_f32_16x16x32_bf16 v[84:87], v[202:205], v[164:167], v[84:87]
	v_mfma_f32_16x16x32_bf16 v[72:75], v[180:183], v[172:175], v[72:75]
	v_mfma_f32_16x16x32_bf16 v[68:71], v[202:205], v[172:175], v[68:71]
	v_mfma_f32_16x16x32_bf16 v[120:123], v[184:187], v[152:155], v[120:123]
	v_mfma_f32_16x16x32_bf16 v[116:119], v[206:209], v[152:155], v[116:119]
	v_mfma_f32_16x16x32_bf16 v[104:107], v[184:187], v[160:163], v[104:107]
	v_mfma_f32_16x16x32_bf16 v[100:103], v[206:209], v[160:163], v[100:103]
	v_mfma_f32_16x16x32_bf16 v[88:91], v[184:187], v[168:171], v[88:91]
	v_mfma_f32_16x16x32_bf16 v[84:87], v[206:209], v[168:171], v[84:87]
	v_mfma_f32_16x16x32_bf16 v[72:75], v[184:187], v[176:179], v[72:75]
	v_mfma_f32_16x16x32_bf16 v[68:71], v[206:209], v[176:179], v[68:71]
	s_mov_b32 m0, s53
	v_lshl_add_u64 v[6:7], v[210:211], 0, s[20:21]
	s_barrier
	ds_read_b128 v[148:151], v200 offset:49152
	ds_read_b128 v[152:155], v200 offset:50176
	ds_read_b128 v[156:159], v200 offset:51200
	ds_read_b128 v[160:163], v200 offset:52224
	ds_read_b128 v[164:167], v200 offset:53248
	ds_read_b128 v[168:171], v200 offset:54272
	ds_read_b128 v[172:175], v200 offset:55296
	ds_read_b128 v[176:179], v200 offset:56320
	global_load_lds_dwordx4 v[6:7], off
	v_lshl_add_u64 v[6:7], v[210:211], 0, s[22:23]
	s_mov_b32 m0, s54
	s_nop 0
	global_load_lds_dwordx4 v[6:7], off
	s_barrier
	s_waitcnt lgkmcnt(0)
	s_waitcnt lgkmcnt(0)
	v_mfma_f32_16x16x32_bf16 v[64:67], v[132:135], v[148:151], v[64:67]
	v_mfma_f32_16x16x32_bf16 v[60:63], v[140:143], v[148:151], v[60:63]
	v_mfma_f32_16x16x32_bf16 v[48:51], v[132:135], v[156:159], v[48:51]
	v_mfma_f32_16x16x32_bf16 v[44:47], v[140:143], v[156:159], v[44:47]
	v_mfma_f32_16x16x32_bf16 v[32:35], v[132:135], v[164:167], v[32:35]
	v_mfma_f32_16x16x32_bf16 v[28:31], v[140:143], v[164:167], v[28:31]
	v_mfma_f32_16x16x32_bf16 v[16:19], v[132:135], v[172:175], v[16:19]
	v_mfma_f32_16x16x32_bf16 v[12:15], v[140:143], v[172:175], v[12:15]
	v_mfma_f32_16x16x32_bf16 v[64:67], v[136:139], v[152:155], v[64:67]
	v_mfma_f32_16x16x32_bf16 v[60:63], v[144:147], v[152:155], v[60:63]
	v_mfma_f32_16x16x32_bf16 v[48:51], v[136:139], v[160:163], v[48:51]
	v_mfma_f32_16x16x32_bf16 v[44:47], v[144:147], v[160:163], v[44:47]
	v_mfma_f32_16x16x32_bf16 v[32:35], v[136:139], v[168:171], v[32:35]
	v_mfma_f32_16x16x32_bf16 v[28:31], v[144:147], v[168:171], v[28:31]
	v_mfma_f32_16x16x32_bf16 v[16:19], v[136:139], v[176:179], v[16:19]
	v_mfma_f32_16x16x32_bf16 v[12:15], v[144:147], v[176:179], v[12:15]
	s_barrier
	s_add_i32 s3, s28, s47
	v_lshl_add_u64 v[6:7], v[196:197], 0, s[24:25]
	s_mov_b32 m0, s3
	s_nop 0
	global_load_lds_dwordx4 v[6:7], off
	v_lshl_add_u64 v[6:7], v[196:197], 0, s[26:27]
	s_add_i32 m0, s3, 0x2000
	s_nop 0
	global_load_lds_dwordx4 v[6:7], off
	s_waitcnt vmcnt(6)
	s_barrier
	v_mfma_f32_16x16x32_bf16 v[56:59], v[180:183], v[148:151], v[56:59]
	v_mfma_f32_16x16x32_bf16 v[52:55], v[202:205], v[148:151], v[52:55]
	v_mfma_f32_16x16x32_bf16 v[40:43], v[180:183], v[156:159], v[40:43]
	v_mfma_f32_16x16x32_bf16 v[36:39], v[202:205], v[156:159], v[36:39]
	v_mfma_f32_16x16x32_bf16 v[24:27], v[180:183], v[164:167], v[24:27]
	v_mfma_f32_16x16x32_bf16 v[20:23], v[202:205], v[164:167], v[20:23]
	v_mfma_f32_16x16x32_bf16 v[6:9], v[180:183], v[172:175], v[8:11]
	v_mfma_f32_16x16x32_bf16 v[2:5], v[202:205], v[172:175], v[2:5]
	v_mfma_f32_16x16x32_bf16 v[56:59], v[184:187], v[152:155], v[56:59]
	v_mfma_f32_16x16x32_bf16 v[52:55], v[206:209], v[152:155], v[52:55]
	v_mfma_f32_16x16x32_bf16 v[40:43], v[184:187], v[160:163], v[40:43]
	v_mfma_f32_16x16x32_bf16 v[36:39], v[206:209], v[160:163], v[36:39]
	v_mfma_f32_16x16x32_bf16 v[24:27], v[184:187], v[168:171], v[24:27]
	v_mfma_f32_16x16x32_bf16 v[20:23], v[206:209], v[168:171], v[20:23]
	v_mfma_f32_16x16x32_bf16 v[8:11], v[184:187], v[176:179], v[6:9]
	v_mfma_f32_16x16x32_bf16 v[4:7], v[206:209], v[176:179], v[2:5]
	s_add_u32 s34, s34, 0x100
	s_addc_u32 s35, s35, 0
	s_cmp_gt_u32 s68, 29
	s_barrier
	s_cbranch_scc1 .LBB0_1164
	s_mov_b32 s68, s2
	s_and_b32 s2, s68, 0x7fffffee
	s_cmp_lg_u32 s2, 8
	s_cbranch_scc0 .LBB0_1161
	s_branch .LBB0_1162

.LBB0_1197:
	ds_read_b128 v[128:131], v164
	ds_read_b128 v[132:135], v164 offset:1024
	ds_read_b128 v[136:139], v164 offset:2048
	ds_read_b128 v[140:143], v164 offset:3072
	s_add_u32 s36, s28, 0xfff80080
	s_addc_u32 s37, s29, -1
	s_cmp_eq_u32 s35, 28
	s_cselect_b32 s37, s23, s37
	s_cselect_b32 s36, s22, s36
	s_cselect_b32 s55, s25, s34
	s_cselect_b32 s54, s24, s27
	v_lshl_add_u64 v[188:189], s[28:29], 0, v[148:149]
	s_add_i32 m0, s38, 0xc000
	ds_read_b128 v[150:153], v165
	ds_read_b128 v[154:157], v165 offset:1024
	ds_read_b128 v[158:161], v165 offset:2048
	ds_read_b128 v[168:171], v165 offset:3072
	ds_read_b128 v[172:175], v165 offset:4096
	ds_read_b128 v[176:179], v165 offset:5120
	ds_read_b128 v[180:183], v165 offset:6144
	ds_read_b128 v[184:187], v165 offset:7168
	global_load_lds_dwordx4 v[188:189], off
	v_lshl_add_u64 v[188:189], v[188:189], 0, s[4:5]
	s_add_i32 m0, s38, 0xe000
	s_nop 0
	global_load_lds_dwordx4 v[188:189], off
	s_waitcnt lgkmcnt(8)
	s_barrier
	s_waitcnt lgkmcnt(0)
	s_waitcnt lgkmcnt(0)
	v_mfma_f32_16x16x32_bf16 v[124:127], v[128:131], v[150:153], v[124:127]
	v_mfma_f32_16x16x32_bf16 v[120:123], v[136:139], v[150:153], v[120:123]
	v_mfma_f32_16x16x32_bf16 v[112:115], v[128:131], v[158:161], v[112:115]
	v_mfma_f32_16x16x32_bf16 v[104:107], v[136:139], v[158:161], v[104:107]
	v_mfma_f32_16x16x32_bf16 v[96:99], v[128:131], v[172:175], v[96:99]
	v_mfma_f32_16x16x32_bf16 v[88:91], v[136:139], v[172:175], v[88:91]
	v_mfma_f32_16x16x32_bf16 v[80:83], v[128:131], v[180:183], v[80:83]
	v_mfma_f32_16x16x32_bf16 v[72:75], v[136:139], v[180:183], v[72:75]
	v_mfma_f32_16x16x32_bf16 v[124:127], v[132:135], v[154:157], v[124:127]
	v_mfma_f32_16x16x32_bf16 v[120:123], v[140:143], v[154:157], v[120:123]
	v_mfma_f32_16x16x32_bf16 v[112:115], v[132:135], v[168:171], v[112:115]
	v_mfma_f32_16x16x32_bf16 v[104:107], v[140:143], v[168:171], v[104:107]
	v_mfma_f32_16x16x32_bf16 v[96:99], v[132:135], v[176:179], v[96:99]
	v_mfma_f32_16x16x32_bf16 v[88:91], v[140:143], v[176:179], v[88:91]
	v_mfma_f32_16x16x32_bf16 v[80:83], v[132:135], v[184:187], v[80:83]
	v_mfma_f32_16x16x32_bf16 v[72:75], v[140:143], v[184:187], v[72:75]
	s_barrier
	s_add_i32 s53, s50, s33
	v_lshl_add_u64 v[204:205], s[54:55], 0, v[144:145]
	s_mov_b32 m0, s53
	ds_read_b128 v[188:191], v166
	ds_read_b128 v[192:195], v166 offset:1024
	ds_read_b128 v[196:199], v166 offset:2048
	ds_read_b128 v[200:203], v166 offset:3072
	global_load_lds_dwordx4 v[204:205], off
	v_lshl_add_u64 v[206:207], v[204:205], 0, s[4:5]
	s_add_i32 m0, s53, 0x2000
	s_nop 0
	global_load_lds_dwordx4 v[206:207], off
	s_barrier
	s_waitcnt lgkmcnt(0)
	s_waitcnt lgkmcnt(0)
	v_mfma_f32_16x16x32_bf16 v[116:119], v[188:191], v[150:153], v[116:119]
	v_mfma_f32_16x16x32_bf16 v[108:111], v[196:199], v[150:153], v[108:111]
	v_mfma_f32_16x16x32_bf16 v[100:103], v[188:191], v[158:161], v[100:103]
	v_mfma_f32_16x16x32_bf16 v[92:95], v[196:199], v[158:161], v[92:95]
	v_mfma_f32_16x16x32_bf16 v[84:87], v[188:191], v[172:175], v[84:87]
	v_mfma_f32_16x16x32_bf16 v[76:79], v[196:199], v[172:175], v[76:79]
	v_mfma_f32_16x16x32_bf16 v[68:71], v[188:191], v[180:183], v[68:71]
	v_mfma_f32_16x16x32_bf16 v[64:67], v[196:199], v[180:183], v[64:67]
	v_mfma_f32_16x16x32_bf16 v[116:119], v[192:195], v[154:157], v[116:119]
	v_mfma_f32_16x16x32_bf16 v[108:111], v[200:203], v[154:157], v[108:111]
	v_mfma_f32_16x16x32_bf16 v[100:103], v[192:195], v[168:171], v[100:103]
	v_mfma_f32_16x16x32_bf16 v[92:95], v[200:203], v[168:171], v[92:95]
	v_mfma_f32_16x16x32_bf16 v[84:87], v[192:195], v[176:179], v[84:87]
	v_mfma_f32_16x16x32_bf16 v[76:79], v[200:203], v[176:179], v[76:79]
	v_mfma_f32_16x16x32_bf16 v[68:71], v[192:195], v[184:187], v[68:71]
	v_mfma_f32_16x16x32_bf16 v[64:67], v[200:203], v[184:187], v[64:67]
	s_mov_b32 m0, s38
	v_lshl_add_u64 v[206:207], s[36:37], 0, v[146:147]
	s_barrier
	ds_read_b128 v[150:153], v165 offset:16384
	ds_read_b128 v[154:157], v165 offset:17408
	ds_read_b128 v[158:161], v165 offset:18432
	ds_read_b128 v[168:171], v165 offset:19456
	ds_read_b128 v[172:175], v165 offset:20480
	ds_read_b128 v[176:179], v165 offset:21504
	ds_read_b128 v[180:183], v165 offset:22528
	ds_read_b128 v[184:187], v165 offset:23552
	global_load_lds_dwordx4 v[206:207], off
	v_lshl_add_u64 v[208:209], v[206:207], 0, s[4:5]
	s_mov_b32 m0, s39
	s_nop 0
	global_load_lds_dwordx4 v[208:209], off
	s_barrier
	s_waitcnt lgkmcnt(0)
	s_waitcnt lgkmcnt(0)
	v_mfma_f32_16x16x32_bf16 v[60:63], v[128:131], v[150:153], v[60:63]
	v_mfma_f32_16x16x32_bf16 v[56:59], v[136:139], v[150:153], v[56:59]
	v_mfma_f32_16x16x32_bf16 v[48:51], v[128:131], v[158:161], v[48:51]
	v_mfma_f32_16x16x32_bf16 v[40:43], v[136:139], v[158:161], v[40:43]
	v_mfma_f32_16x16x32_bf16 v[32:35], v[128:131], v[172:175], v[32:35]
	v_mfma_f32_16x16x32_bf16 v[24:27], v[136:139], v[172:175], v[24:27]
	v_mfma_f32_16x16x32_bf16 v[16:19], v[128:131], v[180:183], v[16:19]
	v_mfma_f32_16x16x32_bf16 v[8:11], v[136:139], v[180:183], v[8:11]
	v_mfma_f32_16x16x32_bf16 v[60:63], v[132:135], v[154:157], v[60:63]
	v_mfma_f32_16x16x32_bf16 v[56:59], v[140:143], v[154:157], v[56:59]
	v_mfma_f32_16x16x32_bf16 v[48:51], v[132:135], v[168:171], v[48:51]
	v_mfma_f32_16x16x32_bf16 v[40:43], v[140:143], v[168:171], v[40:43]
	v_mfma_f32_16x16x32_bf16 v[32:35], v[132:135], v[176:179], v[32:35]
	v_mfma_f32_16x16x32_bf16 v[24:27], v[140:143], v[176:179], v[24:27]
	v_mfma_f32_16x16x32_bf16 v[16:19], v[132:135], v[184:187], v[16:19]
	v_mfma_f32_16x16x32_bf16 v[8:11], v[140:143], v[184:187], v[8:11]
	s_barrier
	s_add_i32 s36, s51, s33
	v_lshl_add_u64 v[128:129], v[204:205], 0, s[6:7]
	s_mov_b32 m0, s36
	s_nop 0
	global_load_lds_dwordx4 v[128:129], off
	v_lshl_add_u64 v[128:129], v[204:205], 0, s[8:9]
	s_add_i32 m0, s36, 0x2000
	s_nop 0
	global_load_lds_dwordx4 v[128:129], off
	s_waitcnt vmcnt(6)
	s_barrier
	v_mfma_f32_16x16x32_bf16 v[52:55], v[188:191], v[150:153], v[52:55]
	v_mfma_f32_16x16x32_bf16 v[44:47], v[196:199], v[150:153], v[44:47]
	v_mfma_f32_16x16x32_bf16 v[36:39], v[188:191], v[158:161], v[36:39]
	v_mfma_f32_16x16x32_bf16 v[28:31], v[196:199], v[158:161], v[28:31]
	v_mfma_f32_16x16x32_bf16 v[20:23], v[188:191], v[172:175], v[20:23]
	v_mfma_f32_16x16x32_bf16 v[12:15], v[196:199], v[172:175], v[12:15]
	v_mfma_f32_16x16x32_bf16 v[4:7], v[188:191], v[180:183], v[4:7]
	v_mfma_f32_16x16x32_bf16 v[0:3], v[196:199], v[180:183], v[0:3]
	v_mfma_f32_16x16x32_bf16 v[52:55], v[192:195], v[154:157], v[52:55]
	v_mfma_f32_16x16x32_bf16 v[44:47], v[200:203], v[154:157], v[44:47]
	v_mfma_f32_16x16x32_bf16 v[36:39], v[192:195], v[168:171], v[36:39]
	v_mfma_f32_16x16x32_bf16 v[28:31], v[200:203], v[168:171], v[28:31]
	v_mfma_f32_16x16x32_bf16 v[20:23], v[192:195], v[176:179], v[20:23]
	v_mfma_f32_16x16x32_bf16 v[12:15], v[200:203], v[176:179], v[12:15]
	v_mfma_f32_16x16x32_bf16 v[4:7], v[192:195], v[184:187], v[4:7]
	v_mfma_f32_16x16x32_bf16 v[0:3], v[200:203], v[184:187], v[0:3]
	s_add_i32 s36, 0, 0x18000
	v_add_u32_e32 v140, s36, v163
	s_barrier
	ds_read_b128 v[128:131], v140
	ds_read_b128 v[132:135], v140 offset:1024
	ds_read_b128 v[136:139], v140 offset:2048
	ds_read_b128 v[140:143], v140 offset:3072
	s_mov_b32 m0, s40
	v_lshl_add_u64 v[188:189], v[206:207], 0, s[6:7]
	ds_read_b128 v[150:153], v165 offset:32768
	ds_read_b128 v[154:157], v165 offset:33792
	ds_read_b128 v[158:161], v165 offset:34816
	ds_read_b128 v[168:171], v165 offset:35840
	ds_read_b128 v[172:175], v165 offset:36864
	ds_read_b128 v[176:179], v165 offset:37888
	ds_read_b128 v[180:183], v165 offset:38912
	ds_read_b128 v[184:187], v165 offset:39936
	global_load_lds_dwordx4 v[188:189], off
	v_lshl_add_u64 v[188:189], v[206:207], 0, s[8:9]
	s_mov_b32 m0, s41
	s_nop 0
	global_load_lds_dwordx4 v[188:189], off
	s_waitcnt lgkmcnt(8)
	s_barrier
	s_waitcnt lgkmcnt(0)
	s_waitcnt lgkmcnt(0)
	v_mfma_f32_16x16x32_bf16 v[124:127], v[128:131], v[150:153], v[124:127]
	v_mfma_f32_16x16x32_bf16 v[120:123], v[136:139], v[150:153], v[120:123]
	v_mfma_f32_16x16x32_bf16 v[112:115], v[128:131], v[158:161], v[112:115]
	v_mfma_f32_16x16x32_bf16 v[104:107], v[136:139], v[158:161], v[104:107]
	v_mfma_f32_16x16x32_bf16 v[96:99], v[128:131], v[172:175], v[96:99]
	v_mfma_f32_16x16x32_bf16 v[88:91], v[136:139], v[172:175], v[88:91]
	v_mfma_f32_16x16x32_bf16 v[80:83], v[128:131], v[180:183], v[80:83]
	v_mfma_f32_16x16x32_bf16 v[72:75], v[136:139], v[180:183], v[72:75]
	v_mfma_f32_16x16x32_bf16 v[124:127], v[132:135], v[154:157], v[124:127]
	v_mfma_f32_16x16x32_bf16 v[120:123], v[140:143], v[154:157], v[120:123]
	v_mfma_f32_16x16x32_bf16 v[112:115], v[132:135], v[168:171], v[112:115]
	v_mfma_f32_16x16x32_bf16 v[104:107], v[140:143], v[168:171], v[104:107]
	v_mfma_f32_16x16x32_bf16 v[96:99], v[132:135], v[176:179], v[96:99]
	v_mfma_f32_16x16x32_bf16 v[88:91], v[140:143], v[176:179], v[88:91]
	v_mfma_f32_16x16x32_bf16 v[80:83], v[132:135], v[184:187], v[80:83]
	v_mfma_f32_16x16x32_bf16 v[72:75], v[140:143], v[184:187], v[72:75]
	s_barrier
	s_add_i32 s37, 0, 0x1c000
	s_add_i32 s36, s36, s33
	v_add_u32_e32 v167, s37, v163
	v_lshl_add_u64 v[208:209], v[204:205], 0, s[10:11]
	s_mov_b32 m0, s36
	ds_read_b128 v[188:191], v167
	ds_read_b128 v[192:195], v167 offset:1024
	ds_read_b128 v[196:199], v167 offset:2048
	ds_read_b128 v[200:203], v167 offset:3072
	global_load_lds_dwordx4 v[208:209], off
	v_lshl_add_u64 v[208:209], v[204:205], 0, s[16:17]
	s_add_i32 m0, s36, 0x2000
	s_nop 0
	global_load_lds_dwordx4 v[208:209], off
	s_barrier
	s_waitcnt lgkmcnt(0)
	s_waitcnt lgkmcnt(0)
	v_mfma_f32_16x16x32_bf16 v[116:119], v[188:191], v[150:153], v[116:119]
	v_mfma_f32_16x16x32_bf16 v[108:111], v[196:199], v[150:153], v[108:111]
	v_mfma_f32_16x16x32_bf16 v[100:103], v[188:191], v[158:161], v[100:103]
	v_mfma_f32_16x16x32_bf16 v[92:95], v[196:199], v[158:161], v[92:95]
	v_mfma_f32_16x16x32_bf16 v[84:87], v[188:191], v[172:175], v[84:87]
	v_mfma_f32_16x16x32_bf16 v[76:79], v[196:199], v[172:175], v[76:79]
	v_mfma_f32_16x16x32_bf16 v[68:71], v[188:191], v[180:183], v[68:71]
	v_mfma_f32_16x16x32_bf16 v[64:67], v[196:199], v[180:183], v[64:67]
	v_mfma_f32_16x16x32_bf16 v[116:119], v[192:195], v[154:157], v[116:119]
	v_mfma_f32_16x16x32_bf16 v[108:111], v[200:203], v[154:157], v[108:111]
	v_mfma_f32_16x16x32_bf16 v[100:103], v[192:195], v[168:171], v[100:103]
	v_mfma_f32_16x16x32_bf16 v[92:95], v[200:203], v[168:171], v[92:95]
	v_mfma_f32_16x16x32_bf16 v[84:87], v[192:195], v[176:179], v[84:87]
	v_mfma_f32_16x16x32_bf16 v[76:79], v[200:203], v[176:179], v[76:79]
	v_mfma_f32_16x16x32_bf16 v[68:71], v[192:195], v[184:187], v[68:71]
	v_mfma_f32_16x16x32_bf16 v[64:67], v[200:203], v[184:187], v[64:67]
	s_mov_b32 m0, s44
	v_lshl_add_u64 v[208:209], v[206:207], 0, s[10:11]
	s_barrier
	ds_read_b128 v[150:153], v165 offset:49152
	ds_read_b128 v[154:157], v165 offset:50176
	ds_read_b128 v[158:161], v165 offset:51200
	ds_read_b128 v[168:171], v165 offset:52224
	ds_read_b128 v[172:175], v165 offset:53248
	ds_read_b128 v[176:179], v165 offset:54272
	ds_read_b128 v[180:183], v165 offset:55296
	ds_read_b128 v[184:187], v165 offset:56320
	global_load_lds_dwordx4 v[208:209], off
	v_lshl_add_u64 v[206:207], v[206:207], 0, s[16:17]
	s_mov_b32 m0, s45
	s_nop 0
	global_load_lds_dwordx4 v[206:207], off
	s_barrier
	s_waitcnt lgkmcnt(0)
	s_waitcnt lgkmcnt(0)
	v_mfma_f32_16x16x32_bf16 v[60:63], v[128:131], v[150:153], v[60:63]
	v_mfma_f32_16x16x32_bf16 v[56:59], v[136:139], v[150:153], v[56:59]
	v_mfma_f32_16x16x32_bf16 v[48:51], v[128:131], v[158:161], v[48:51]
	v_mfma_f32_16x16x32_bf16 v[40:43], v[136:139], v[158:161], v[40:43]
	v_mfma_f32_16x16x32_bf16 v[32:35], v[128:131], v[172:175], v[32:35]
	v_mfma_f32_16x16x32_bf16 v[24:27], v[136:139], v[172:175], v[24:27]
	v_mfma_f32_16x16x32_bf16 v[16:19], v[128:131], v[180:183], v[16:19]
	v_mfma_f32_16x16x32_bf16 v[8:11], v[136:139], v[180:183], v[8:11]
	v_mfma_f32_16x16x32_bf16 v[60:63], v[132:135], v[154:157], v[60:63]
	v_mfma_f32_16x16x32_bf16 v[56:59], v[140:143], v[154:157], v[56:59]
	v_mfma_f32_16x16x32_bf16 v[48:51], v[132:135], v[168:171], v[48:51]
	v_mfma_f32_16x16x32_bf16 v[40:43], v[140:143], v[168:171], v[40:43]
	v_mfma_f32_16x16x32_bf16 v[32:35], v[132:135], v[176:179], v[32:35]
	v_mfma_f32_16x16x32_bf16 v[24:27], v[140:143], v[176:179], v[24:27]
	v_mfma_f32_16x16x32_bf16 v[16:19], v[132:135], v[184:187], v[16:19]
	v_mfma_f32_16x16x32_bf16 v[8:11], v[140:143], v[184:187], v[8:11]
	s_barrier
	s_add_i32 s36, s37, s33
	v_lshl_add_u64 v[128:129], v[204:205], 0, s[18:19]
	s_mov_b32 m0, s36
	s_nop 0
	global_load_lds_dwordx4 v[128:129], off
	v_lshl_add_u64 v[128:129], v[204:205], 0, s[20:21]
	s_add_i32 m0, s36, 0x2000
	s_nop 0
	global_load_lds_dwordx4 v[128:129], off
	s_waitcnt vmcnt(6)
	s_barrier
	v_mfma_f32_16x16x32_bf16 v[52:55], v[188:191], v[150:153], v[52:55]
	v_mfma_f32_16x16x32_bf16 v[44:47], v[196:199], v[150:153], v[44:47]
	v_mfma_f32_16x16x32_bf16 v[36:39], v[188:191], v[158:161], v[36:39]
	v_mfma_f32_16x16x32_bf16 v[28:31], v[196:199], v[158:161], v[28:31]
	v_mfma_f32_16x16x32_bf16 v[20:23], v[188:191], v[172:175], v[20:23]
	v_mfma_f32_16x16x32_bf16 v[12:15], v[196:199], v[172:175], v[12:15]
	v_mfma_f32_16x16x32_bf16 v[4:7], v[188:191], v[180:183], v[4:7]
	v_mfma_f32_16x16x32_bf16 v[0:3], v[196:199], v[180:183], v[0:3]
	v_mfma_f32_16x16x32_bf16 v[52:55], v[192:195], v[154:157], v[52:55]
	v_mfma_f32_16x16x32_bf16 v[44:47], v[200:203], v[154:157], v[44:47]
	v_mfma_f32_16x16x32_bf16 v[36:39], v[192:195], v[168:171], v[36:39]
	v_mfma_f32_16x16x32_bf16 v[28:31], v[200:203], v[168:171], v[28:31]
	v_mfma_f32_16x16x32_bf16 v[20:23], v[192:195], v[176:179], v[20:23]
	v_mfma_f32_16x16x32_bf16 v[12:15], v[200:203], v[176:179], v[12:15]
	v_mfma_f32_16x16x32_bf16 v[4:7], v[192:195], v[184:187], v[4:7]
	v_mfma_f32_16x16x32_bf16 v[0:3], v[200:203], v[184:187], v[0:3]
	s_add_i32 s35, s35, 2
	s_add_u32 s28, s28, 0x100
	s_addc_u32 s29, s29, 0
	s_add_u32 s27, s27, 0x100
	s_addc_u32 s34, s34, 0
	s_cmp_gt_u32 s35, 29
	s_barrier
	s_cbranch_scc0 .LBB0_1197
	v_mov_b32_e32 v128, v162
	s_mov_b32 s34, s31
	s_mov_b32 s28, s46
	s_cmp_lt_i32 s26, 16
	s_cselect_b32 s29, 0, 0xc000
	s_lshl_b32 s35, s52, 8
	s_lshl_b32 s28, s28, 5
	v_and_b32_e32 v130, 15, v128
	s_ashr_i32 s27, s26, 31
	s_add_i32 s28, s28, s35
	v_lshrrev_b32_e32 v128, 1, v128
	v_and_or_b32 v128, v128, 24, s28
	s_add_u32 s28, s42, s29
	s_addc_u32 s29, s43, 0
	s_lshl_b64 s[26:27], s[26:27], 20
	v_lshl_or_b32 v150, s34, 6, v130
	s_add_u32 s26, s48, s26
	v_ashrrev_i32_e32 v129, 31, v128
	s_addc_u32 s27, s49, s27
	v_ashrrev_i32_e32 v151, 31, v150
	v_lshl_add_u64 v[152:153], v[128:129], 1, s[26:27]
	v_lshlrev_b64 v[130:131], 12, v[150:151]
	v_lshl_add_u64 v[200:201], v[152:153], 0, v[130:131]
	v_or_b32_e32 v130, 16, v150
	v_ashrrev_i32_e32 v131, 31, v130
	v_lshlrev_b64 v[130:131], 12, v[130:131]
	v_lshl_add_u64 v[158:159], v[152:153], 0, v[130:131]
	v_or_b32_e32 v130, 32, v150
	v_ashrrev_i32_e32 v131, 31, v130
	v_lshlrev_b64 v[130:131], 12, v[130:131]
	v_lshl_add_u64 v[156:157], v[152:153], 0, v[130:131]
	v_or_b32_e32 v130, 48, v150
	v_ashrrev_i32_e32 v131, 31, v130
	v_lshlrev_b64 v[130:131], 12, v[130:131]
	global_load_dwordx4 v[168:171], v[200:201], off
	global_load_dwordx4 v[172:175], v[200:201], off offset:256
	v_lshl_add_u64 v[154:155], v[152:153], 0, v[130:131]
	v_lshl_add_u64 v[128:129], v[128:129], 2, s[28:29]
	global_load_dwordx4 v[176:179], v[158:159], off
	global_load_dwordx4 v[180:183], v[158:159], off offset:256
	global_load_dwordx4 v[184:187], v[156:157], off
	global_load_dwordx4 v[188:191], v[156:157], off offset:256
	global_load_dwordx4 v[192:195], v[154:155], off
	global_load_dwordx4 v[196:199], v[154:155], off offset:256
	global_load_dwordx4 v[140:143], v[128:129], off
	global_load_dwordx4 v[136:139], v[128:129], off offset:16
	global_load_dwordx4 v[132:135], v[128:129], off offset:512
	s_nop 0
	global_load_dwordx4 v[128:131], v[128:129], off offset:528
	s_mov_b32 s26, s47
	s_mov_b64 s[28:29], -1
	s_waitcnt vmcnt(0)
	v_lshlrev_b32_e32 v202, 16, v168
	v_and_b32_e32 v203, 0xffff0000, v168
	v_lshlrev_b32_e32 v168, 16, v169
	v_and_b32_e32 v169, 0xffff0000, v169
	v_lshlrev_b32_e32 v204, 16, v170
	v_and_b32_e32 v205, 0xffff0000, v170
	v_lshlrev_b32_e32 v170, 16, v171
	v_and_b32_e32 v171, 0xffff0000, v171
	v_lshlrev_b32_e32 v208, 16, v174
	v_and_b32_e32 v209, 0xffff0000, v174
	v_lshlrev_b32_e32 v174, 16, v175
	v_and_b32_e32 v175, 0xffff0000, v175
	v_pk_fma_f32 v[126:127], v[126:127], v[142:143], v[168:169]
	v_pk_fma_f32 v[124:125], v[124:125], v[140:141], v[202:203]
	v_pk_fma_f32 v[168:169], v[122:123], v[138:139], v[170:171]
	v_pk_fma_f32 v[122:123], v[120:121], v[136:137], v[204:205]
	v_cvt_pk_bf16_f32 v120, v124, v125
	v_cvt_pk_bf16_f32 v121, v126, v127
	v_lshlrev_b32_e32 v206, 16, v172
	v_and_b32_e32 v207, 0xffff0000, v172
	v_lshlrev_b32_e32 v172, 16, v173
	v_and_b32_e32 v173, 0xffff0000, v173
	v_cvt_pk_bf16_f32 v122, v122, v123
	v_cvt_pk_bf16_f32 v123, v168, v169
	global_store_dwordx4 v[200:201], v[120:123], off
	v_lshlrev_b32_e32 v210, 16, v176
	v_and_b32_e32 v211, 0xffff0000, v176
	v_pk_fma_f32 v[120:121], v[110:111], v[130:131], v[174:175]
	v_pk_fma_f32 v[110:111], v[108:109], v[128:129], v[208:209]
	v_lshlrev_b32_e32 v176, 16, v177
	v_and_b32_e32 v177, 0xffff0000, v177
	v_lshlrev_b32_e32 v212, 16, v178
	v_and_b32_e32 v213, 0xffff0000, v178
	v_lshlrev_b32_e32 v178, 16, v179
	v_and_b32_e32 v179, 0xffff0000, v179
	v_pk_fma_f32 v[118:119], v[118:119], v[134:135], v[172:173]
	v_pk_fma_f32 v[116:117], v[116:117], v[132:133], v[206:207]
	v_lshlrev_b32_e32 v216, 16, v182
	v_cvt_pk_bf16_f32 v108, v116, v117
	v_cvt_pk_bf16_f32 v109, v118, v119
	v_cvt_pk_bf16_f32 v110, v110, v111
	v_cvt_pk_bf16_f32 v111, v120, v121
	v_and_b32_e32 v217, 0xffff0000, v182
	v_lshlrev_b32_e32 v182, 16, v183
	v_and_b32_e32 v183, 0xffff0000, v183
	global_store_dwordx4 v[200:201], v[108:111], off offset:256
	v_lshlrev_b32_e32 v214, 16, v180
	v_and_b32_e32 v215, 0xffff0000, v180
	v_pk_fma_f32 v[108:109], v[114:115], v[142:143], v[176:177]
	v_pk_fma_f32 v[110:111], v[112:113], v[140:141], v[210:211]
	v_pk_fma_f32 v[112:113], v[106:107], v[138:139], v[178:179]
	v_pk_fma_f32 v[106:107], v[104:105], v[136:137], v[212:213]
	v_cvt_pk_bf16_f32 v104, v110, v111
	v_cvt_pk_bf16_f32 v105, v108, v109
	v_lshlrev_b32_e32 v180, 16, v181
	v_and_b32_e32 v181, 0xffff0000, v181
	v_cvt_pk_bf16_f32 v106, v106, v107
	v_cvt_pk_bf16_f32 v107, v112, v113
	global_store_dwordx4 v[158:159], v[104:107], off
	v_lshlrev_b32_e32 v218, 16, v184
	v_and_b32_e32 v219, 0xffff0000, v184
	v_pk_fma_f32 v[104:105], v[94:95], v[130:131], v[182:183]
	v_pk_fma_f32 v[94:95], v[92:93], v[128:129], v[216:217]
	v_lshlrev_b32_e32 v184, 16, v185
	v_and_b32_e32 v185, 0xffff0000, v185
	v_lshlrev_b32_e32 v220, 16, v186
	v_and_b32_e32 v221, 0xffff0000, v186
	v_lshlrev_b32_e32 v186, 16, v187
	v_and_b32_e32 v187, 0xffff0000, v187
	v_pk_fma_f32 v[102:103], v[102:103], v[134:135], v[180:181]
	v_pk_fma_f32 v[100:101], v[100:101], v[132:133], v[214:215]
	v_lshlrev_b32_e32 v224, 16, v190
	v_cvt_pk_bf16_f32 v92, v100, v101
	v_cvt_pk_bf16_f32 v93, v102, v103
	v_cvt_pk_bf16_f32 v94, v94, v95
	v_cvt_pk_bf16_f32 v95, v104, v105
	v_and_b32_e32 v225, 0xffff0000, v190
	v_lshlrev_b32_e32 v190, 16, v191
	v_and_b32_e32 v191, 0xffff0000, v191
	global_store_dwordx4 v[158:159], v[92:95], off offset:256
	v_lshlrev_b32_e32 v222, 16, v188
	v_and_b32_e32 v223, 0xffff0000, v188
	v_pk_fma_f32 v[92:93], v[98:99], v[142:143], v[184:185]
	v_pk_fma_f32 v[94:95], v[96:97], v[140:141], v[218:219]
	v_pk_fma_f32 v[96:97], v[90:91], v[138:139], v[186:187]
	v_pk_fma_f32 v[90:91], v[88:89], v[136:137], v[220:221]
	v_cvt_pk_bf16_f32 v88, v94, v95
	v_cvt_pk_bf16_f32 v89, v92, v93
	v_lshlrev_b32_e32 v188, 16, v189
	v_and_b32_e32 v189, 0xffff0000, v189
	v_cvt_pk_bf16_f32 v90, v90, v91
	v_cvt_pk_bf16_f32 v91, v96, v97
	global_store_dwordx4 v[156:157], v[88:91], off
	v_lshlrev_b32_e32 v226, 16, v192
	v_and_b32_e32 v227, 0xffff0000, v192
	v_pk_fma_f32 v[88:89], v[78:79], v[130:131], v[190:191]
	v_pk_fma_f32 v[78:79], v[76:77], v[128:129], v[224:225]
	v_lshlrev_b32_e32 v192, 16, v193
	v_and_b32_e32 v193, 0xffff0000, v193
	v_lshlrev_b32_e32 v228, 16, v194
	v_and_b32_e32 v229, 0xffff0000, v194
	v_lshlrev_b32_e32 v194, 16, v195
	v_and_b32_e32 v195, 0xffff0000, v195
	v_pk_fma_f32 v[86:87], v[86:87], v[134:135], v[188:189]
	v_pk_fma_f32 v[84:85], v[84:85], v[132:133], v[222:223]
	v_lshlrev_b32_e32 v230, 16, v196
	v_cvt_pk_bf16_f32 v76, v84, v85
	v_cvt_pk_bf16_f32 v77, v86, v87
	v_cvt_pk_bf16_f32 v78, v78, v79
	v_cvt_pk_bf16_f32 v79, v88, v89
	v_and_b32_e32 v231, 0xffff0000, v196
	v_lshlrev_b32_e32 v160, 16, v198
	v_and_b32_e32 v161, 0xffff0000, v198
	v_lshlrev_b32_e32 v198, 16, v199
	v_and_b32_e32 v199, 0xffff0000, v199
	global_store_dwordx4 v[156:157], v[76:79], off offset:256
	v_lshlrev_b32_e32 v196, 16, v197
	v_and_b32_e32 v197, 0xffff0000, v197
	v_pk_fma_f32 v[76:77], v[82:83], v[142:143], v[192:193]
	v_pk_fma_f32 v[78:79], v[80:81], v[140:141], v[226:227]
	v_pk_fma_f32 v[80:81], v[74:75], v[138:139], v[194:195]
	v_pk_fma_f32 v[74:75], v[72:73], v[136:137], v[228:229]
	v_cvt_pk_bf16_f32 v72, v78, v79
	v_cvt_pk_bf16_f32 v73, v76, v77
	v_pk_fma_f32 v[68:69], v[68:69], v[132:133], v[230:231]
	v_cvt_pk_bf16_f32 v74, v74, v75
	v_cvt_pk_bf16_f32 v75, v80, v81
	global_store_dwordx4 v[154:155], v[72:75], off
	v_pk_fma_f32 v[70:71], v[70:71], v[134:135], v[196:197]
	s_nop 0
	v_pk_fma_f32 v[72:73], v[66:67], v[130:131], v[198:199]
	v_pk_fma_f32 v[66:67], v[64:65], v[128:129], v[160:161]
	v_cvt_pk_bf16_f32 v64, v68, v69
	v_cvt_pk_bf16_f32 v65, v70, v71
	s_nop 0
	v_cvt_pk_bf16_f32 v66, v66, v67
	v_cvt_pk_bf16_f32 v67, v72, v73
	global_store_dwordx4 v[154:155], v[64:67], off offset:256
	s_nop 1
	v_add_u32_e32 v64, 0x80, v150
	v_ashrrev_i32_e32 v65, 31, v64
	v_lshlrev_b64 v[64:65], 12, v[64:65]
	v_lshl_add_u64 v[100:101], v[152:153], 0, v[64:65]
	v_add_u32_e32 v64, 0x90, v150
	global_load_dwordx4 v[68:71], v[100:101], off
	global_load_dwordx4 v[72:75], v[100:101], off offset:256
	v_ashrrev_i32_e32 v65, 31, v64
	v_lshlrev_b64 v[64:65], 12, v[64:65]
	v_lshl_add_u64 v[102:103], v[152:153], 0, v[64:65]
	v_add_u32_e32 v64, 0xa0, v150
	global_load_dwordx4 v[76:79], v[102:103], off
	global_load_dwordx4 v[80:83], v[102:103], off offset:256
	v_ashrrev_i32_e32 v65, 31, v64
	v_lshlrev_b64 v[64:65], 12, v[64:65]
	v_lshl_add_u64 v[66:67], v[152:153], 0, v[64:65]
	v_add_u32_e32 v64, 0xb0, v150
	global_load_dwordx4 v[84:87], v[66:67], off
	global_load_dwordx4 v[88:91], v[66:67], off offset:256
	v_ashrrev_i32_e32 v65, 31, v64
	v_lshlrev_b64 v[64:65], 12, v[64:65]
	v_lshl_add_u64 v[64:65], v[152:153], 0, v[64:65]
	global_load_dwordx4 v[92:95], v[64:65], off
	global_load_dwordx4 v[96:99], v[64:65], off offset:256
	s_waitcnt vmcnt(0)
	v_lshlrev_b32_e32 v104, 16, v68
	v_and_b32_e32 v105, 0xffff0000, v68
	v_lshlrev_b32_e32 v68, 16, v69
	v_and_b32_e32 v69, 0xffff0000, v69
	v_lshlrev_b32_e32 v106, 16, v70
	v_and_b32_e32 v107, 0xffff0000, v70
	v_lshlrev_b32_e32 v70, 16, v71
	v_and_b32_e32 v71, 0xffff0000, v71
	v_lshlrev_b32_e32 v110, 16, v74
	v_and_b32_e32 v111, 0xffff0000, v74
	v_lshlrev_b32_e32 v74, 16, v75
	v_and_b32_e32 v75, 0xffff0000, v75
	v_pk_fma_f32 v[62:63], v[62:63], v[142:143], v[68:69]
	v_pk_fma_f32 v[60:61], v[60:61], v[140:141], v[104:105]
	v_pk_fma_f32 v[68:69], v[58:59], v[138:139], v[70:71]
	v_pk_fma_f32 v[58:59], v[56:57], v[136:137], v[106:107]
	v_cvt_pk_bf16_f32 v56, v60, v61
	v_cvt_pk_bf16_f32 v57, v62, v63
	v_lshlrev_b32_e32 v108, 16, v72
	v_and_b32_e32 v109, 0xffff0000, v72
	v_lshlrev_b32_e32 v72, 16, v73
	v_and_b32_e32 v73, 0xffff0000, v73
	v_cvt_pk_bf16_f32 v58, v58, v59
	v_cvt_pk_bf16_f32 v59, v68, v69
	global_store_dwordx4 v[100:101], v[56:59], off
	v_lshlrev_b32_e32 v112, 16, v76
	v_and_b32_e32 v113, 0xffff0000, v76
	v_pk_fma_f32 v[56:57], v[46:47], v[130:131], v[74:75]
	v_pk_fma_f32 v[46:47], v[44:45], v[128:129], v[110:111]
	v_lshlrev_b32_e32 v76, 16, v77
	v_and_b32_e32 v77, 0xffff0000, v77
	v_lshlrev_b32_e32 v114, 16, v78
	v_and_b32_e32 v115, 0xffff0000, v78
	v_lshlrev_b32_e32 v78, 16, v79
	v_and_b32_e32 v79, 0xffff0000, v79
	v_pk_fma_f32 v[54:55], v[54:55], v[134:135], v[72:73]
	v_pk_fma_f32 v[52:53], v[52:53], v[132:133], v[108:109]
	v_lshlrev_b32_e32 v118, 16, v82
	v_cvt_pk_bf16_f32 v44, v52, v53
	v_cvt_pk_bf16_f32 v45, v54, v55
	v_cvt_pk_bf16_f32 v46, v46, v47
	v_cvt_pk_bf16_f32 v47, v56, v57
	v_and_b32_e32 v119, 0xffff0000, v82
	v_lshlrev_b32_e32 v82, 16, v83
	v_and_b32_e32 v83, 0xffff0000, v83
	global_store_dwordx4 v[100:101], v[44:47], off offset:256
	v_lshlrev_b32_e32 v116, 16, v80
	v_and_b32_e32 v117, 0xffff0000, v80
	v_pk_fma_f32 v[44:45], v[50:51], v[142:143], v[76:77]
	v_pk_fma_f32 v[46:47], v[48:49], v[140:141], v[112:113]
	v_pk_fma_f32 v[48:49], v[42:43], v[138:139], v[78:79]
	v_pk_fma_f32 v[42:43], v[40:41], v[136:137], v[114:115]
	v_cvt_pk_bf16_f32 v40, v46, v47
	v_cvt_pk_bf16_f32 v41, v44, v45
	v_lshlrev_b32_e32 v80, 16, v81
	v_and_b32_e32 v81, 0xffff0000, v81
	v_cvt_pk_bf16_f32 v42, v42, v43
	v_cvt_pk_bf16_f32 v43, v48, v49
	global_store_dwordx4 v[102:103], v[40:43], off
	v_lshlrev_b32_e32 v120, 16, v84
	v_and_b32_e32 v121, 0xffff0000, v84
	v_pk_fma_f32 v[40:41], v[30:31], v[130:131], v[82:83]
	v_pk_fma_f32 v[30:31], v[28:29], v[128:129], v[118:119]
	v_lshlrev_b32_e32 v84, 16, v85
	v_and_b32_e32 v85, 0xffff0000, v85
	v_lshlrev_b32_e32 v122, 16, v86
	v_and_b32_e32 v123, 0xffff0000, v86
	v_lshlrev_b32_e32 v86, 16, v87
	v_and_b32_e32 v87, 0xffff0000, v87
	v_pk_fma_f32 v[38:39], v[38:39], v[134:135], v[80:81]
	v_pk_fma_f32 v[36:37], v[36:37], v[132:133], v[116:117]
	v_lshlrev_b32_e32 v126, 16, v90
	v_cvt_pk_bf16_f32 v28, v36, v37
	v_cvt_pk_bf16_f32 v29, v38, v39
	v_cvt_pk_bf16_f32 v30, v30, v31
	v_cvt_pk_bf16_f32 v31, v40, v41
	v_and_b32_e32 v127, 0xffff0000, v90
	v_lshlrev_b32_e32 v90, 16, v91
	v_and_b32_e32 v91, 0xffff0000, v91
	global_store_dwordx4 v[102:103], v[28:31], off offset:256
	v_lshlrev_b32_e32 v124, 16, v88
	v_and_b32_e32 v125, 0xffff0000, v88
	v_pk_fma_f32 v[28:29], v[34:35], v[142:143], v[84:85]
	v_pk_fma_f32 v[30:31], v[32:33], v[140:141], v[120:121]
	v_pk_fma_f32 v[32:33], v[26:27], v[138:139], v[86:87]
	v_pk_fma_f32 v[26:27], v[24:25], v[136:137], v[122:123]
	v_cvt_pk_bf16_f32 v24, v30, v31
	v_cvt_pk_bf16_f32 v25, v28, v29
	v_lshlrev_b32_e32 v88, 16, v89
	v_and_b32_e32 v89, 0xffff0000, v89
	v_cvt_pk_bf16_f32 v26, v26, v27
	v_cvt_pk_bf16_f32 v27, v32, v33
	global_store_dwordx4 v[66:67], v[24:27], off
	v_lshlrev_b32_e32 v150, 16, v92
	v_and_b32_e32 v151, 0xffff0000, v92
	v_pk_fma_f32 v[24:25], v[14:15], v[130:131], v[90:91]
	v_pk_fma_f32 v[14:15], v[12:13], v[128:129], v[126:127]
	v_lshlrev_b32_e32 v92, 16, v93
	v_and_b32_e32 v93, 0xffff0000, v93
	v_lshlrev_b32_e32 v152, 16, v94
	v_and_b32_e32 v153, 0xffff0000, v94
	v_lshlrev_b32_e32 v94, 16, v95
	v_and_b32_e32 v95, 0xffff0000, v95
	v_pk_fma_f32 v[22:23], v[22:23], v[134:135], v[88:89]
	v_pk_fma_f32 v[20:21], v[20:21], v[132:133], v[124:125]
	v_lshlrev_b32_e32 v156, 16, v98
	v_cvt_pk_bf16_f32 v12, v20, v21
	v_cvt_pk_bf16_f32 v13, v22, v23
	v_cvt_pk_bf16_f32 v14, v14, v15
	v_cvt_pk_bf16_f32 v15, v24, v25
	v_and_b32_e32 v157, 0xffff0000, v98
	v_lshlrev_b32_e32 v98, 16, v99
	v_and_b32_e32 v99, 0xffff0000, v99
	global_store_dwordx4 v[66:67], v[12:15], off offset:256
	v_lshlrev_b32_e32 v154, 16, v96
	v_and_b32_e32 v155, 0xffff0000, v96
	v_pk_fma_f32 v[12:13], v[18:19], v[142:143], v[92:93]
	v_pk_fma_f32 v[14:15], v[16:17], v[140:141], v[150:151]
	v_pk_fma_f32 v[16:17], v[10:11], v[138:139], v[94:95]
	v_pk_fma_f32 v[10:11], v[8:9], v[136:137], v[152:153]
	v_cvt_pk_bf16_f32 v8, v14, v15
	v_cvt_pk_bf16_f32 v9, v12, v13
	v_lshlrev_b32_e32 v96, 16, v97
	v_and_b32_e32 v97, 0xffff0000, v97
	v_cvt_pk_bf16_f32 v10, v10, v11
	v_cvt_pk_bf16_f32 v11, v16, v17
	global_store_dwordx4 v[64:65], v[8:11], off
	v_pk_fma_f32 v[6:7], v[6:7], v[134:135], v[96:97]
	v_pk_fma_f32 v[4:5], v[4:5], v[132:133], v[154:155]
	v_pk_fma_f32 v[8:9], v[2:3], v[130:131], v[98:99]
	v_pk_fma_f32 v[2:3], v[0:1], v[128:129], v[156:157]
	v_cvt_pk_bf16_f32 v0, v4, v5
	v_cvt_pk_bf16_f32 v1, v6, v7
	s_nop 0
	v_cvt_pk_bf16_f32 v2, v2, v3
	v_cvt_pk_bf16_f32 v3, v8, v9
	global_store_dwordx4 v[64:65], v[0:3], off offset:256
	s_mul_i32 s27, s26, s0
	s_add_i32 s27, s27, s1
	s_cmpk_gt_i32 s27, 0xff
	s_cbranch_scc1 .LBB0_1189
	s_ashr_i32 s26, s27, 31
	s_lshr_b32 s26, s26, 29
	s_add_i32 s28, s27, s26
	s_and_b32 s26, s28, -8
	s_sub_i32 s29, s27, s26
	s_cmp_gt_i32 s29, -1
	s_mov_b64 s[26:27], -1
	s_cbranch_scc0 .LBB0_1201
	s_lshl_b32 s34, s29, 5
	s_mov_b64 s[26:27], 0

.LBB0_1244:
	ds_read_b128 v[142:145], v138
	ds_read_b128 v[146:149], v138 offset:1024
	ds_read_b128 v[150:153], v138 offset:2048
	ds_read_b128 v[154:157], v138 offset:3072
	s_add_u32 s35, s28, 0xfff80080
	s_addc_u32 s52, s29, -1
	s_cmp_eq_u32 s34, 28
	s_cselect_b32 s53, s25, s52
	s_cselect_b32 s52, s24, s35
	s_cselect_b32 s55, s27, s31
	s_cselect_b32 s54, s26, s30
	v_lshl_add_u64 v[134:135], s[28:29], 0, v[132:133]
	s_add_i32 m0, s38, 0xc000
	ds_read_b128 v[158:161], v139
	ds_read_b128 v[162:165], v139 offset:1024
	ds_read_b128 v[166:169], v139 offset:2048
	ds_read_b128 v[170:173], v139 offset:3072
	ds_read_b128 v[174:177], v139 offset:4096
	ds_read_b128 v[178:181], v139 offset:5120
	ds_read_b128 v[182:185], v139 offset:6144
	ds_read_b128 v[186:189], v139 offset:7168
	global_load_lds_dwordx4 v[134:135], off
	v_lshl_add_u64 v[134:135], v[134:135], 0, s[4:5]
	s_add_i32 m0, s38, 0xe000
	s_nop 0
	global_load_lds_dwordx4 v[134:135], off
	s_waitcnt lgkmcnt(8)
	s_barrier
	s_waitcnt lgkmcnt(0)
	s_waitcnt lgkmcnt(0)
	v_mfma_f32_16x16x32_bf16 v[124:127], v[142:145], v[158:161], v[124:127]
	v_mfma_f32_16x16x32_bf16 v[120:123], v[150:153], v[158:161], v[120:123]
	v_mfma_f32_16x16x32_bf16 v[108:111], v[142:145], v[166:169], v[108:111]
	v_mfma_f32_16x16x32_bf16 v[104:107], v[150:153], v[166:169], v[104:107]
	v_mfma_f32_16x16x32_bf16 v[92:95], v[142:145], v[174:177], v[92:95]
	v_mfma_f32_16x16x32_bf16 v[88:91], v[150:153], v[174:177], v[88:91]
	v_mfma_f32_16x16x32_bf16 v[76:79], v[142:145], v[182:185], v[76:79]
	v_mfma_f32_16x16x32_bf16 v[72:75], v[150:153], v[182:185], v[72:75]
	v_mfma_f32_16x16x32_bf16 v[124:127], v[146:149], v[162:165], v[124:127]
	v_mfma_f32_16x16x32_bf16 v[120:123], v[154:157], v[162:165], v[120:123]
	v_mfma_f32_16x16x32_bf16 v[108:111], v[146:149], v[170:173], v[108:111]
	v_mfma_f32_16x16x32_bf16 v[104:107], v[154:157], v[170:173], v[104:107]
	v_mfma_f32_16x16x32_bf16 v[92:95], v[146:149], v[178:181], v[92:95]
	v_mfma_f32_16x16x32_bf16 v[88:91], v[154:157], v[178:181], v[88:91]
	v_mfma_f32_16x16x32_bf16 v[76:79], v[146:149], v[186:189], v[76:79]
	v_mfma_f32_16x16x32_bf16 v[72:75], v[154:157], v[186:189], v[72:75]
	s_barrier
	s_add_i32 s35, s47, s37
	v_lshl_add_u64 v[134:135], s[54:55], 0, v[128:129]
	s_mov_b32 m0, s35
	ds_read_b128 v[190:193], v140
	ds_read_b128 v[194:197], v140 offset:1024
	ds_read_b128 v[198:201], v140 offset:2048
	ds_read_b128 v[202:205], v140 offset:3072
	global_load_lds_dwordx4 v[134:135], off
	v_lshl_add_u64 v[206:207], v[134:135], 0, s[4:5]
	s_add_i32 m0, s35, 0x2000
	s_nop 0
	global_load_lds_dwordx4 v[206:207], off
	s_barrier
	s_waitcnt lgkmcnt(0)
	s_waitcnt lgkmcnt(0)
	v_mfma_f32_16x16x32_bf16 v[116:119], v[190:193], v[158:161], v[116:119]
	v_mfma_f32_16x16x32_bf16 v[112:115], v[198:201], v[158:161], v[112:115]
	v_mfma_f32_16x16x32_bf16 v[100:103], v[190:193], v[166:169], v[100:103]
	v_mfma_f32_16x16x32_bf16 v[96:99], v[198:201], v[166:169], v[96:99]
	v_mfma_f32_16x16x32_bf16 v[84:87], v[190:193], v[174:177], v[84:87]
	v_mfma_f32_16x16x32_bf16 v[80:83], v[198:201], v[174:177], v[80:83]
	v_mfma_f32_16x16x32_bf16 v[68:71], v[190:193], v[182:185], v[68:71]
	v_mfma_f32_16x16x32_bf16 v[64:67], v[198:201], v[182:185], v[64:67]
	v_mfma_f32_16x16x32_bf16 v[116:119], v[194:197], v[162:165], v[116:119]
	v_mfma_f32_16x16x32_bf16 v[112:115], v[202:205], v[162:165], v[112:115]
	v_mfma_f32_16x16x32_bf16 v[100:103], v[194:197], v[170:173], v[100:103]
	v_mfma_f32_16x16x32_bf16 v[96:99], v[202:205], v[170:173], v[96:99]
	v_mfma_f32_16x16x32_bf16 v[84:87], v[194:197], v[178:181], v[84:87]
	v_mfma_f32_16x16x32_bf16 v[80:83], v[202:205], v[178:181], v[80:83]
	v_mfma_f32_16x16x32_bf16 v[68:71], v[194:197], v[186:189], v[68:71]
	v_mfma_f32_16x16x32_bf16 v[64:67], v[202:205], v[186:189], v[64:67]
	s_mov_b32 m0, s38
	v_lshl_add_u64 v[206:207], s[52:53], 0, v[130:131]
	s_barrier
	ds_read_b128 v[158:161], v139 offset:16384
	ds_read_b128 v[162:165], v139 offset:17408
	ds_read_b128 v[166:169], v139 offset:18432
	ds_read_b128 v[170:173], v139 offset:19456
	ds_read_b128 v[174:177], v139 offset:20480
	ds_read_b128 v[178:181], v139 offset:21504
	ds_read_b128 v[182:185], v139 offset:22528
	ds_read_b128 v[186:189], v139 offset:23552
	global_load_lds_dwordx4 v[206:207], off
	v_lshl_add_u64 v[208:209], v[206:207], 0, s[4:5]
	s_mov_b32 m0, s39
	s_nop 0
	global_load_lds_dwordx4 v[208:209], off
	s_barrier
	s_waitcnt lgkmcnt(0)
	s_waitcnt lgkmcnt(0)
	v_mfma_f32_16x16x32_bf16 v[60:63], v[142:145], v[158:161], v[60:63]
	v_mfma_f32_16x16x32_bf16 v[56:59], v[150:153], v[158:161], v[56:59]
	v_mfma_f32_16x16x32_bf16 v[44:47], v[142:145], v[166:169], v[44:47]
	v_mfma_f32_16x16x32_bf16 v[40:43], v[150:153], v[166:169], v[40:43]
	v_mfma_f32_16x16x32_bf16 v[28:31], v[142:145], v[174:177], v[28:31]
	v_mfma_f32_16x16x32_bf16 v[24:27], v[150:153], v[174:177], v[24:27]
	v_mfma_f32_16x16x32_bf16 v[12:15], v[142:145], v[182:185], v[12:15]
	v_mfma_f32_16x16x32_bf16 v[8:11], v[150:153], v[182:185], v[8:11]
	v_mfma_f32_16x16x32_bf16 v[60:63], v[146:149], v[162:165], v[60:63]
	v_mfma_f32_16x16x32_bf16 v[56:59], v[154:157], v[162:165], v[56:59]
	v_mfma_f32_16x16x32_bf16 v[44:47], v[146:149], v[170:173], v[44:47]
	v_mfma_f32_16x16x32_bf16 v[40:43], v[154:157], v[170:173], v[40:43]
	v_mfma_f32_16x16x32_bf16 v[28:31], v[146:149], v[178:181], v[28:31]
	v_mfma_f32_16x16x32_bf16 v[24:27], v[154:157], v[178:181], v[24:27]
	v_mfma_f32_16x16x32_bf16 v[12:15], v[146:149], v[186:189], v[12:15]
	v_mfma_f32_16x16x32_bf16 v[8:11], v[154:157], v[186:189], v[8:11]
	s_barrier
	s_add_i32 s35, s48, s37
	v_lshl_add_u64 v[142:143], v[134:135], 0, s[6:7]
	s_mov_b32 m0, s35
	s_nop 0
	global_load_lds_dwordx4 v[142:143], off
	v_lshl_add_u64 v[142:143], v[134:135], 0, s[8:9]
	s_add_i32 m0, s35, 0x2000
	s_nop 0
	global_load_lds_dwordx4 v[142:143], off
	s_waitcnt vmcnt(6)
	s_barrier
	v_mfma_f32_16x16x32_bf16 v[52:55], v[190:193], v[158:161], v[52:55]
	v_mfma_f32_16x16x32_bf16 v[48:51], v[198:201], v[158:161], v[48:51]
	v_mfma_f32_16x16x32_bf16 v[36:39], v[190:193], v[166:169], v[36:39]
	v_mfma_f32_16x16x32_bf16 v[32:35], v[198:201], v[166:169], v[32:35]
	v_mfma_f32_16x16x32_bf16 v[20:23], v[190:193], v[174:177], v[20:23]
	v_mfma_f32_16x16x32_bf16 v[16:19], v[198:201], v[174:177], v[16:19]
	v_mfma_f32_16x16x32_bf16 v[4:7], v[190:193], v[182:185], v[4:7]
	v_mfma_f32_16x16x32_bf16 v[0:3], v[198:201], v[182:185], v[0:3]
	v_mfma_f32_16x16x32_bf16 v[52:55], v[194:197], v[162:165], v[52:55]
	v_mfma_f32_16x16x32_bf16 v[48:51], v[202:205], v[162:165], v[48:51]
	v_mfma_f32_16x16x32_bf16 v[36:39], v[194:197], v[170:173], v[36:39]
	v_mfma_f32_16x16x32_bf16 v[32:35], v[202:205], v[170:173], v[32:35]
	v_mfma_f32_16x16x32_bf16 v[20:23], v[194:197], v[178:181], v[20:23]
	v_mfma_f32_16x16x32_bf16 v[16:19], v[202:205], v[178:181], v[16:19]
	v_mfma_f32_16x16x32_bf16 v[4:7], v[194:197], v[186:189], v[4:7]
	v_mfma_f32_16x16x32_bf16 v[0:3], v[202:205], v[186:189], v[0:3]
	s_add_i32 s35, 0, 0x18000
	v_add_u32_e32 v141, s35, v137
	s_barrier
	ds_read_b128 v[142:145], v141
	ds_read_b128 v[146:149], v141 offset:1024
	ds_read_b128 v[150:153], v141 offset:2048
	ds_read_b128 v[154:157], v141 offset:3072
	s_mov_b32 m0, s40
	v_lshl_add_u64 v[190:191], v[206:207], 0, s[6:7]
	ds_read_b128 v[158:161], v139 offset:32768
	ds_read_b128 v[162:165], v139 offset:33792
	ds_read_b128 v[166:169], v139 offset:34816
	ds_read_b128 v[170:173], v139 offset:35840
	ds_read_b128 v[174:177], v139 offset:36864
	ds_read_b128 v[178:181], v139 offset:37888
	ds_read_b128 v[182:185], v139 offset:38912
	ds_read_b128 v[186:189], v139 offset:39936
	global_load_lds_dwordx4 v[190:191], off
	v_lshl_add_u64 v[190:191], v[206:207], 0, s[8:9]
	s_mov_b32 m0, s41
	s_nop 0
	global_load_lds_dwordx4 v[190:191], off
	s_waitcnt lgkmcnt(8)
	s_barrier
	s_waitcnt lgkmcnt(0)
	s_waitcnt lgkmcnt(0)
	v_mfma_f32_16x16x32_bf16 v[124:127], v[142:145], v[158:161], v[124:127]
	v_mfma_f32_16x16x32_bf16 v[120:123], v[150:153], v[158:161], v[120:123]
	v_mfma_f32_16x16x32_bf16 v[108:111], v[142:145], v[166:169], v[108:111]
	v_mfma_f32_16x16x32_bf16 v[104:107], v[150:153], v[166:169], v[104:107]
	v_mfma_f32_16x16x32_bf16 v[92:95], v[142:145], v[174:177], v[92:95]
	v_mfma_f32_16x16x32_bf16 v[88:91], v[150:153], v[174:177], v[88:91]
	v_mfma_f32_16x16x32_bf16 v[76:79], v[142:145], v[182:185], v[76:79]
	v_mfma_f32_16x16x32_bf16 v[72:75], v[150:153], v[182:185], v[72:75]
	v_mfma_f32_16x16x32_bf16 v[124:127], v[146:149], v[162:165], v[124:127]
	v_mfma_f32_16x16x32_bf16 v[120:123], v[154:157], v[162:165], v[120:123]
	v_mfma_f32_16x16x32_bf16 v[108:111], v[146:149], v[170:173], v[108:111]
	v_mfma_f32_16x16x32_bf16 v[104:107], v[154:157], v[170:173], v[104:107]
	v_mfma_f32_16x16x32_bf16 v[92:95], v[146:149], v[178:181], v[92:95]
	v_mfma_f32_16x16x32_bf16 v[88:91], v[154:157], v[178:181], v[88:91]
	v_mfma_f32_16x16x32_bf16 v[76:79], v[146:149], v[186:189], v[76:79]
	v_mfma_f32_16x16x32_bf16 v[72:75], v[154:157], v[186:189], v[72:75]
	s_barrier
	s_add_i32 s52, 0, 0x1c000
	s_add_i32 s35, s35, s37
	v_add_u32_e32 v141, s52, v137
	v_lshl_add_u64 v[208:209], v[134:135], 0, s[16:17]
	s_mov_b32 m0, s35
	ds_read_b128 v[190:193], v141
	ds_read_b128 v[194:197], v141 offset:1024
	ds_read_b128 v[198:201], v141 offset:2048
	ds_read_b128 v[202:205], v141 offset:3072
	global_load_lds_dwordx4 v[208:209], off
	v_lshl_add_u64 v[208:209], v[134:135], 0, s[18:19]
	s_add_i32 m0, s35, 0x2000
	s_nop 0
	global_load_lds_dwordx4 v[208:209], off
	s_barrier
	s_waitcnt lgkmcnt(0)
	s_waitcnt lgkmcnt(0)
	v_mfma_f32_16x16x32_bf16 v[116:119], v[190:193], v[158:161], v[116:119]
	v_mfma_f32_16x16x32_bf16 v[112:115], v[198:201], v[158:161], v[112:115]
	v_mfma_f32_16x16x32_bf16 v[100:103], v[190:193], v[166:169], v[100:103]
	v_mfma_f32_16x16x32_bf16 v[96:99], v[198:201], v[166:169], v[96:99]
	v_mfma_f32_16x16x32_bf16 v[84:87], v[190:193], v[174:177], v[84:87]
	v_mfma_f32_16x16x32_bf16 v[80:83], v[198:201], v[174:177], v[80:83]
	v_mfma_f32_16x16x32_bf16 v[68:71], v[190:193], v[182:185], v[68:71]
	v_mfma_f32_16x16x32_bf16 v[64:67], v[198:201], v[182:185], v[64:67]
	v_mfma_f32_16x16x32_bf16 v[116:119], v[194:197], v[162:165], v[116:119]
	v_mfma_f32_16x16x32_bf16 v[112:115], v[202:205], v[162:165], v[112:115]
	v_mfma_f32_16x16x32_bf16 v[100:103], v[194:197], v[170:173], v[100:103]
	v_mfma_f32_16x16x32_bf16 v[96:99], v[202:205], v[170:173], v[96:99]
	v_mfma_f32_16x16x32_bf16 v[84:87], v[194:197], v[178:181], v[84:87]
	v_mfma_f32_16x16x32_bf16 v[80:83], v[202:205], v[178:181], v[80:83]
	v_mfma_f32_16x16x32_bf16 v[68:71], v[194:197], v[186:189], v[68:71]
	v_mfma_f32_16x16x32_bf16 v[64:67], v[202:205], v[186:189], v[64:67]
	s_mov_b32 m0, s42
	v_lshl_add_u64 v[208:209], v[206:207], 0, s[16:17]
	s_barrier
	ds_read_b128 v[158:161], v139 offset:49152
	ds_read_b128 v[162:165], v139 offset:50176
	ds_read_b128 v[166:169], v139 offset:51200
	ds_read_b128 v[170:173], v139 offset:52224
	ds_read_b128 v[174:177], v139 offset:53248
	ds_read_b128 v[178:181], v139 offset:54272
	ds_read_b128 v[182:185], v139 offset:55296
	ds_read_b128 v[186:189], v139 offset:56320
	global_load_lds_dwordx4 v[208:209], off
	v_lshl_add_u64 v[206:207], v[206:207], 0, s[18:19]
	s_mov_b32 m0, s43
	s_nop 0
	global_load_lds_dwordx4 v[206:207], off
	s_barrier
	s_waitcnt lgkmcnt(0)
	s_waitcnt lgkmcnt(0)
	v_mfma_f32_16x16x32_bf16 v[60:63], v[142:145], v[158:161], v[60:63]
	v_mfma_f32_16x16x32_bf16 v[56:59], v[150:153], v[158:161], v[56:59]
	v_mfma_f32_16x16x32_bf16 v[44:47], v[142:145], v[166:169], v[44:47]
	v_mfma_f32_16x16x32_bf16 v[40:43], v[150:153], v[166:169], v[40:43]
	v_mfma_f32_16x16x32_bf16 v[28:31], v[142:145], v[174:177], v[28:31]
	v_mfma_f32_16x16x32_bf16 v[24:27], v[150:153], v[174:177], v[24:27]
	v_mfma_f32_16x16x32_bf16 v[12:15], v[142:145], v[182:185], v[12:15]
	v_mfma_f32_16x16x32_bf16 v[8:11], v[150:153], v[182:185], v[8:11]
	v_mfma_f32_16x16x32_bf16 v[60:63], v[146:149], v[162:165], v[60:63]
	v_mfma_f32_16x16x32_bf16 v[56:59], v[154:157], v[162:165], v[56:59]
	v_mfma_f32_16x16x32_bf16 v[44:47], v[146:149], v[170:173], v[44:47]
	v_mfma_f32_16x16x32_bf16 v[40:43], v[154:157], v[170:173], v[40:43]
	v_mfma_f32_16x16x32_bf16 v[28:31], v[146:149], v[178:181], v[28:31]
	v_mfma_f32_16x16x32_bf16 v[24:27], v[154:157], v[178:181], v[24:27]
	v_mfma_f32_16x16x32_bf16 v[12:15], v[146:149], v[186:189], v[12:15]
	v_mfma_f32_16x16x32_bf16 v[8:11], v[154:157], v[186:189], v[8:11]
	s_barrier
	s_add_i32 s35, s52, s37
	v_lshl_add_u64 v[142:143], v[134:135], 0, s[20:21]
	s_mov_b32 m0, s35
	v_lshl_add_u64 v[134:135], v[134:135], 0, s[22:23]
	global_load_lds_dwordx4 v[142:143], off
	s_add_i32 m0, s35, 0x2000
	s_nop 0
	global_load_lds_dwordx4 v[134:135], off
	s_waitcnt vmcnt(6)
	s_barrier
	v_mfma_f32_16x16x32_bf16 v[52:55], v[190:193], v[158:161], v[52:55]
	v_mfma_f32_16x16x32_bf16 v[48:51], v[198:201], v[158:161], v[48:51]
	v_mfma_f32_16x16x32_bf16 v[36:39], v[190:193], v[166:169], v[36:39]
	v_mfma_f32_16x16x32_bf16 v[32:35], v[198:201], v[166:169], v[32:35]
	v_mfma_f32_16x16x32_bf16 v[20:23], v[190:193], v[174:177], v[20:23]
	v_mfma_f32_16x16x32_bf16 v[16:19], v[198:201], v[174:177], v[16:19]
	v_mfma_f32_16x16x32_bf16 v[4:7], v[190:193], v[182:185], v[4:7]
	v_mfma_f32_16x16x32_bf16 v[0:3], v[198:201], v[182:185], v[0:3]
	v_mfma_f32_16x16x32_bf16 v[52:55], v[194:197], v[162:165], v[52:55]
	v_mfma_f32_16x16x32_bf16 v[48:51], v[202:205], v[162:165], v[48:51]
	v_mfma_f32_16x16x32_bf16 v[36:39], v[194:197], v[170:173], v[36:39]
	v_mfma_f32_16x16x32_bf16 v[32:35], v[202:205], v[170:173], v[32:35]
	v_mfma_f32_16x16x32_bf16 v[20:23], v[194:197], v[178:181], v[20:23]
	v_mfma_f32_16x16x32_bf16 v[16:19], v[202:205], v[178:181], v[16:19]
	v_mfma_f32_16x16x32_bf16 v[4:7], v[194:197], v[186:189], v[4:7]
	v_mfma_f32_16x16x32_bf16 v[0:3], v[202:205], v[186:189], v[0:3]
	s_add_i32 s34, s34, 2
	s_add_u32 s28, s28, 0x100
	s_addc_u32 s29, s29, 0
	s_add_u32 s30, s30, 0x100
	s_addc_u32 s31, s31, 0
	s_cmp_gt_u32 s34, 29
	s_barrier
	s_cbranch_scc0 .LBB0_1244
	v_mov_b32_e32 v134, v136
	s_mov_b32 s28, s44
	s_mov_b32 s29, s36
	s_lshl_b32 s30, s51, 7
	s_lshl_b32 s28, s28, 5
	s_add_i32 s28, s28, s30
	v_lshrrev_b32_e32 v135, 1, v134
	v_and_or_b32 v142, v135, 24, s28
	s_lshl_b32 s28, s50, 8
	s_lshl_b32 s29, s29, 6
	s_add_i32 s29, s29, s28
	v_and_or_b32 v141, v134, 15, s29
	v_mul_f32_e32 v134, 0xbfb8aa3b, v124
	v_exp_f32_e32 v144, v134
	v_mul_f32_e32 v134, 0xbfb8aa3b, v120
	v_exp_f32_e32 v145, v134
	v_ashrrev_i32_e32 v143, 31, v142
	v_add_f32_e32 v144, 1.0, v144
	v_rcp_f32_e32 v146, v144
	v_add_f32_e32 v144, 1.0, v145
	v_rcp_f32_e32 v147, v144
	v_mov_b64_e32 v[134:135], s[10:11]
	v_mul_f32_e32 v124, v124, v146
	v_mul_f32_e32 v116, v124, v116
	v_mul_f32_e32 v124, 0xbfb8aa3b, v125
	v_exp_f32_e32 v124, v124
	v_mul_f32_e32 v146, 0xbfb8aa3b, v121
	v_exp_f32_e32 v146, v146
	v_mul_f32_e32 v120, v120, v147
	v_mul_f32_e32 v120, v120, v112
	v_add_f32_e32 v112, 1.0, v124
	v_rcp_f32_e32 v112, v112
	v_add_f32_e32 v124, 1.0, v146
	v_mul_f32_e32 v146, 0xbfb8aa3b, v126
	v_rcp_f32_e32 v124, v124
	v_exp_f32_e32 v146, v146
	v_mul_f32_e32 v112, v125, v112
	v_mul_f32_e32 v117, v112, v117
	v_mul_f32_e32 v112, v121, v124
	v_add_f32_e32 v121, 1.0, v146
	v_rcp_f32_e32 v121, v121
	v_mul_f32_e32 v124, 0xbfb8aa3b, v122
	v_exp_f32_e32 v124, v124
	v_mul_f32_e32 v125, v112, v113
	v_mul_f32_e32 v112, v126, v121
	v_mul_f32_e32 v113, 0xbfb8aa3b, v127
	v_mul_f32_e32 v121, v112, v118
	v_exp_f32_e32 v113, v113
	v_mul_f32_e32 v118, 0xbfb8aa3b, v123
	v_exp_f32_e32 v118, v118
	v_add_f32_e32 v112, 1.0, v124
	v_rcp_f32_e32 v112, v112
	v_add_f32_e32 v113, 1.0, v113
	v_rcp_f32_e32 v113, v113
	v_add_f32_e32 v118, 1.0, v118
	v_rcp_f32_e32 v118, v118
	v_mul_f32_e32 v112, v122, v112
	v_mul_f32_e32 v122, v112, v114
	v_mul_f32_e32 v112, v127, v113
	v_mul_f32_e32 v124, v112, v119
	v_mul_f32_e32 v112, v123, v118
	v_mad_i64_i32 v[144:145], s[28:29], v141, s49, v[134:135]
	v_mul_f32_e32 v123, v112, v115
	v_lshlrev_b64 v[112:113], 1, v[142:143]
	v_lshl_add_u64 v[118:119], v[144:145], 0, v[112:113]
	v_cvt_pk_bf16_f32 v114, v116, v117
	v_cvt_pk_bf16_f32 v115, v121, v124
	v_cvt_pk_bf16_f32 v116, v120, v125
	v_cvt_pk_bf16_f32 v117, v122, v123
	global_store_dwordx4 v[118:119], v[114:117], off
	s_nop 1
	v_mul_f32_e32 v114, 0xbfb8aa3b, v108
	v_exp_f32_e32 v114, v114
	v_mul_f32_e32 v115, 0xbfb8aa3b, v104
	v_exp_f32_e32 v115, v115
	v_or_b32_e32 v116, 16, v141
	v_add_f32_e32 v114, 1.0, v114
	v_rcp_f32_e32 v117, v114
	v_add_f32_e32 v114, 1.0, v115
	v_rcp_f32_e32 v118, v114
	v_mad_i64_i32 v[114:115], s[28:29], v116, s49, v[134:135]
	v_mul_f32_e32 v108, v108, v117
	v_mul_f32_e32 v108, v108, v100
	v_mul_f32_e32 v100, v104, v118
	v_mul_f32_e32 v104, 0xbfb8aa3b, v109
	v_exp_f32_e32 v104, v104
	v_mul_f32_e32 v116, 0xbfb8aa3b, v105
	v_mul_f32_e32 v117, v100, v96
	v_exp_f32_e32 v116, v116
	v_add_f32_e32 v96, 1.0, v104
	v_rcp_f32_e32 v96, v96
	v_mul_f32_e32 v104, 0xbfb8aa3b, v110
	v_exp_f32_e32 v104, v104
	v_add_f32_e32 v100, 1.0, v116
	v_mul_f32_e32 v96, v109, v96
	v_rcp_f32_e32 v100, v100
	v_mul_f32_e32 v96, v96, v101
	v_add_f32_e32 v101, 1.0, v104
	v_rcp_f32_e32 v101, v101
	v_mul_f32_e32 v100, v105, v100
	v_mul_f32_e32 v104, 0xbfb8aa3b, v106
	v_mul_f32_e32 v105, v100, v97
	v_mul_f32_e32 v97, v110, v101
	v_exp_f32_e32 v104, v104
	v_mul_f32_e32 v97, v97, v102
	v_mul_f32_e32 v101, 0xbfb8aa3b, v111
	v_mul_f32_e32 v102, 0xbfb8aa3b, v107
	v_exp_f32_e32 v101, v101
	v_exp_f32_e32 v102, v102
	v_add_f32_e32 v100, 1.0, v104
	v_rcp_f32_e32 v100, v100
	v_add_f32_e32 v101, 1.0, v101
	v_add_f32_e32 v102, 1.0, v102
	v_rcp_f32_e32 v101, v101
	v_rcp_f32_e32 v102, v102
	v_mul_f32_e32 v100, v106, v100
	v_mul_f32_e32 v104, v100, v98
	v_mul_f32_e32 v98, v111, v101
	v_mul_f32_e32 v100, v107, v102
	v_mul_f32_e32 v98, v98, v103
	v_mul_f32_e32 v99, v100, v99
	v_lshl_add_u64 v[100:101], v[114:115], 0, v[112:113]
	v_cvt_pk_bf16_f32 v96, v108, v96
	v_cvt_pk_bf16_f32 v97, v97, v98
	v_cvt_pk_bf16_f32 v98, v117, v105
	v_cvt_pk_bf16_f32 v99, v104, v99
	global_store_dwordx4 v[100:101], v[96:99], off
	s_nop 1
	v_mul_f32_e32 v96, 0xbfb8aa3b, v92
	v_exp_f32_e32 v96, v96
	v_mul_f32_e32 v97, 0xbfb8aa3b, v88
	v_exp_f32_e32 v97, v97
	v_or_b32_e32 v98, 32, v141
	v_add_f32_e32 v96, 1.0, v96
	v_rcp_f32_e32 v99, v96
	v_add_f32_e32 v96, 1.0, v97
	v_rcp_f32_e32 v100, v96
	v_mad_i64_i32 v[96:97], s[28:29], v98, s49, v[134:135]
	v_mul_f32_e32 v92, v92, v99
	v_mul_f32_e32 v92, v92, v84
	v_mul_f32_e32 v84, v88, v100
	v_mul_f32_e32 v88, 0xbfb8aa3b, v93
	v_exp_f32_e32 v88, v88
	v_mul_f32_e32 v98, 0xbfb8aa3b, v89
	v_mul_f32_e32 v99, v84, v80
	v_exp_f32_e32 v98, v98
	v_add_f32_e32 v80, 1.0, v88
	v_rcp_f32_e32 v80, v80
	v_mul_f32_e32 v88, 0xbfb8aa3b, v94
	v_exp_f32_e32 v88, v88
	v_add_f32_e32 v84, 1.0, v98
	v_mul_f32_e32 v80, v93, v80
	v_rcp_f32_e32 v84, v84
	v_mul_f32_e32 v80, v80, v85
	v_add_f32_e32 v85, 1.0, v88
	v_rcp_f32_e32 v85, v85
	v_mul_f32_e32 v84, v89, v84
	v_mul_f32_e32 v88, 0xbfb8aa3b, v90
	v_mul_f32_e32 v89, v84, v81
	v_mul_f32_e32 v81, v94, v85
	v_exp_f32_e32 v88, v88
	v_mul_f32_e32 v81, v81, v86
	v_mul_f32_e32 v85, 0xbfb8aa3b, v95
	v_mul_f32_e32 v86, 0xbfb8aa3b, v91
	v_exp_f32_e32 v85, v85
	v_exp_f32_e32 v86, v86
	v_add_f32_e32 v84, 1.0, v88
	v_rcp_f32_e32 v84, v84
	v_add_f32_e32 v85, 1.0, v85
	v_add_f32_e32 v86, 1.0, v86
	v_rcp_f32_e32 v85, v85
	v_rcp_f32_e32 v86, v86
	v_mul_f32_e32 v84, v90, v84
	v_mul_f32_e32 v88, v84, v82
	v_mul_f32_e32 v82, v95, v85
	v_mul_f32_e32 v84, v91, v86
	v_mul_f32_e32 v82, v82, v87
	v_mul_f32_e32 v83, v84, v83
	v_lshl_add_u64 v[84:85], v[96:97], 0, v[112:113]
	v_cvt_pk_bf16_f32 v80, v92, v80
	v_cvt_pk_bf16_f32 v81, v81, v82
	v_cvt_pk_bf16_f32 v82, v99, v89
	v_cvt_pk_bf16_f32 v83, v88, v83
	global_store_dwordx4 v[84:85], v[80:83], off
	s_nop 1
	v_mul_f32_e32 v80, 0xbfb8aa3b, v76
	v_exp_f32_e32 v80, v80
	v_mul_f32_e32 v81, 0xbfb8aa3b, v72
	v_exp_f32_e32 v81, v81
	v_or_b32_e32 v82, 48, v141
	v_add_f32_e32 v80, 1.0, v80
	v_rcp_f32_e32 v83, v80
	v_add_f32_e32 v80, 1.0, v81
	v_rcp_f32_e32 v84, v80
	v_mad_i64_i32 v[80:81], s[28:29], v82, s49, v[134:135]
	v_mul_f32_e32 v76, v76, v83
	v_mul_f32_e32 v76, v76, v68
	v_mul_f32_e32 v68, v72, v84
	v_mul_f32_e32 v72, 0xbfb8aa3b, v77
	v_exp_f32_e32 v72, v72
	v_mul_f32_e32 v82, 0xbfb8aa3b, v73
	v_mul_f32_e32 v83, v68, v64
	v_exp_f32_e32 v82, v82
	v_add_f32_e32 v64, 1.0, v72
	v_rcp_f32_e32 v64, v64
	v_mul_f32_e32 v72, 0xbfb8aa3b, v78
	v_exp_f32_e32 v72, v72
	v_add_f32_e32 v68, 1.0, v82
	v_mul_f32_e32 v64, v77, v64
	v_rcp_f32_e32 v68, v68
	v_mul_f32_e32 v64, v64, v69
	v_add_f32_e32 v69, 1.0, v72
	v_rcp_f32_e32 v69, v69
	v_mul_f32_e32 v68, v73, v68
	v_mul_f32_e32 v72, 0xbfb8aa3b, v74
	v_mul_f32_e32 v73, v68, v65
	v_mul_f32_e32 v65, v78, v69
	v_exp_f32_e32 v72, v72
	v_mul_f32_e32 v65, v65, v70
	v_mul_f32_e32 v69, 0xbfb8aa3b, v79
	v_mul_f32_e32 v70, 0xbfb8aa3b, v75
	v_exp_f32_e32 v69, v69
	v_exp_f32_e32 v70, v70
	v_add_f32_e32 v68, 1.0, v72
	v_rcp_f32_e32 v68, v68
	v_add_f32_e32 v69, 1.0, v69
	v_add_f32_e32 v70, 1.0, v70
	v_rcp_f32_e32 v69, v69
	v_rcp_f32_e32 v70, v70
	v_mul_f32_e32 v68, v74, v68
	v_mul_f32_e32 v72, v68, v66
	v_mul_f32_e32 v66, v79, v69
	v_mul_f32_e32 v68, v75, v70
	v_mul_f32_e32 v66, v66, v71
	v_mul_f32_e32 v67, v68, v67
	v_lshl_add_u64 v[68:69], v[80:81], 0, v[112:113]
	v_cvt_pk_bf16_f32 v64, v76, v64
	v_cvt_pk_bf16_f32 v65, v65, v66
	v_cvt_pk_bf16_f32 v66, v83, v73
	v_cvt_pk_bf16_f32 v67, v72, v67
	global_store_dwordx4 v[68:69], v[64:67], off
	s_nop 1
	v_mul_f32_e32 v64, 0xbfb8aa3b, v60
	v_exp_f32_e32 v64, v64
	v_mul_f32_e32 v65, 0xbfb8aa3b, v56
	v_exp_f32_e32 v65, v65
	v_add_u32_e32 v66, 0x80, v141
	v_add_f32_e32 v64, 1.0, v64
	v_rcp_f32_e32 v67, v64
	v_add_f32_e32 v64, 1.0, v65
	v_rcp_f32_e32 v68, v64
	v_mad_i64_i32 v[64:65], s[28:29], v66, s49, v[134:135]
	v_mul_f32_e32 v60, v60, v67
	v_mul_f32_e32 v60, v60, v52
	v_mul_f32_e32 v52, v56, v68
	v_mul_f32_e32 v56, 0xbfb8aa3b, v61
	v_exp_f32_e32 v56, v56
	v_mul_f32_e32 v66, 0xbfb8aa3b, v57
	v_mul_f32_e32 v67, v52, v48
	v_exp_f32_e32 v66, v66
	v_add_f32_e32 v48, 1.0, v56
	v_rcp_f32_e32 v48, v48
	v_mul_f32_e32 v56, 0xbfb8aa3b, v62
	v_exp_f32_e32 v56, v56
	v_add_f32_e32 v52, 1.0, v66
	v_mul_f32_e32 v48, v61, v48
	v_rcp_f32_e32 v52, v52
	v_mul_f32_e32 v48, v48, v53
	v_add_f32_e32 v53, 1.0, v56
	v_rcp_f32_e32 v53, v53
	v_mul_f32_e32 v52, v57, v52
	v_mul_f32_e32 v56, 0xbfb8aa3b, v58
	v_mul_f32_e32 v57, v52, v49
	v_mul_f32_e32 v49, v62, v53
	v_exp_f32_e32 v56, v56
	v_mul_f32_e32 v49, v49, v54
	v_mul_f32_e32 v53, 0xbfb8aa3b, v63
	v_mul_f32_e32 v54, 0xbfb8aa3b, v59
	v_exp_f32_e32 v53, v53
	v_exp_f32_e32 v54, v54
	v_add_f32_e32 v52, 1.0, v56
	v_rcp_f32_e32 v52, v52
	v_add_f32_e32 v53, 1.0, v53
	v_add_f32_e32 v54, 1.0, v54
	v_rcp_f32_e32 v53, v53
	v_rcp_f32_e32 v54, v54
	v_mul_f32_e32 v52, v58, v52
	v_mul_f32_e32 v56, v52, v50
	v_mul_f32_e32 v50, v63, v53
	v_mul_f32_e32 v52, v59, v54
	v_mul_f32_e32 v50, v50, v55
	v_mul_f32_e32 v51, v52, v51
	v_lshl_add_u64 v[52:53], v[64:65], 0, v[112:113]
	v_cvt_pk_bf16_f32 v48, v60, v48
	v_cvt_pk_bf16_f32 v49, v49, v50
	v_cvt_pk_bf16_f32 v50, v67, v57
	v_cvt_pk_bf16_f32 v51, v56, v51
	global_store_dwordx4 v[52:53], v[48:51], off
	s_nop 1
	v_mul_f32_e32 v48, 0xbfb8aa3b, v44
	v_exp_f32_e32 v48, v48
	v_mul_f32_e32 v49, 0xbfb8aa3b, v40
	v_exp_f32_e32 v49, v49
	v_add_u32_e32 v50, 0x90, v141
	v_add_f32_e32 v48, 1.0, v48
	v_rcp_f32_e32 v51, v48
	v_add_f32_e32 v48, 1.0, v49
	v_rcp_f32_e32 v52, v48
	v_mad_i64_i32 v[48:49], s[28:29], v50, s49, v[134:135]
	v_mul_f32_e32 v44, v44, v51
	v_mul_f32_e32 v44, v44, v36
	v_mul_f32_e32 v36, v40, v52
	v_mul_f32_e32 v40, 0xbfb8aa3b, v45
	v_exp_f32_e32 v40, v40
	v_mul_f32_e32 v50, 0xbfb8aa3b, v41
	v_mul_f32_e32 v51, v36, v32
	v_exp_f32_e32 v50, v50
	v_add_f32_e32 v32, 1.0, v40
	v_rcp_f32_e32 v32, v32
	v_mul_f32_e32 v40, 0xbfb8aa3b, v46
	v_exp_f32_e32 v40, v40
	v_add_f32_e32 v36, 1.0, v50
	v_mul_f32_e32 v32, v45, v32
	v_rcp_f32_e32 v36, v36
	v_mul_f32_e32 v32, v32, v37
	v_add_f32_e32 v37, 1.0, v40
	v_rcp_f32_e32 v37, v37
	v_mul_f32_e32 v36, v41, v36
	v_mul_f32_e32 v40, 0xbfb8aa3b, v42
	v_mul_f32_e32 v41, v36, v33
	v_mul_f32_e32 v33, v46, v37
	v_exp_f32_e32 v40, v40
	v_mul_f32_e32 v33, v33, v38
	v_mul_f32_e32 v37, 0xbfb8aa3b, v47
	v_mul_f32_e32 v38, 0xbfb8aa3b, v43
	v_exp_f32_e32 v37, v37
	v_exp_f32_e32 v38, v38
	v_add_f32_e32 v36, 1.0, v40
	v_rcp_f32_e32 v36, v36
	v_add_f32_e32 v37, 1.0, v37
	v_add_f32_e32 v38, 1.0, v38
	v_rcp_f32_e32 v37, v37
	v_rcp_f32_e32 v38, v38
	v_mul_f32_e32 v36, v42, v36
	v_mul_f32_e32 v40, v36, v34
	v_mul_f32_e32 v34, v47, v37
	v_mul_f32_e32 v36, v43, v38
	v_mul_f32_e32 v34, v34, v39
	v_mul_f32_e32 v35, v36, v35
	v_lshl_add_u64 v[36:37], v[48:49], 0, v[112:113]
	v_cvt_pk_bf16_f32 v32, v44, v32
	v_cvt_pk_bf16_f32 v33, v33, v34
	v_cvt_pk_bf16_f32 v34, v51, v41
	v_cvt_pk_bf16_f32 v35, v40, v35
	global_store_dwordx4 v[36:37], v[32:35], off
	s_nop 1
	v_mul_f32_e32 v32, 0xbfb8aa3b, v28
	v_exp_f32_e32 v32, v32
	v_mul_f32_e32 v33, 0xbfb8aa3b, v24
	v_exp_f32_e32 v33, v33
	v_add_u32_e32 v34, 0xa0, v141
	v_add_f32_e32 v32, 1.0, v32
	v_rcp_f32_e32 v35, v32
	v_add_f32_e32 v32, 1.0, v33
	v_rcp_f32_e32 v36, v32
	v_mad_i64_i32 v[32:33], s[28:29], v34, s49, v[134:135]
	v_mul_f32_e32 v28, v28, v35
	v_mul_f32_e32 v28, v28, v20
	v_mul_f32_e32 v20, v24, v36
	v_mul_f32_e32 v24, 0xbfb8aa3b, v29
	v_exp_f32_e32 v24, v24
	v_mul_f32_e32 v34, 0xbfb8aa3b, v25
	v_mul_f32_e32 v35, v20, v16
	v_exp_f32_e32 v34, v34
	v_add_f32_e32 v16, 1.0, v24
	v_rcp_f32_e32 v16, v16
	v_mul_f32_e32 v24, 0xbfb8aa3b, v30
	v_exp_f32_e32 v24, v24
	v_add_f32_e32 v20, 1.0, v34
	v_mul_f32_e32 v16, v29, v16
	v_rcp_f32_e32 v20, v20
	v_mul_f32_e32 v16, v16, v21
	v_add_f32_e32 v21, 1.0, v24
	v_rcp_f32_e32 v21, v21
	v_mul_f32_e32 v20, v25, v20
	v_mul_f32_e32 v24, 0xbfb8aa3b, v26
	v_mul_f32_e32 v25, v20, v17
	v_mul_f32_e32 v17, v30, v21
	v_exp_f32_e32 v24, v24
	v_mul_f32_e32 v17, v17, v22
	v_mul_f32_e32 v21, 0xbfb8aa3b, v31
	v_mul_f32_e32 v22, 0xbfb8aa3b, v27
	v_exp_f32_e32 v21, v21
	v_exp_f32_e32 v22, v22
	v_add_f32_e32 v20, 1.0, v24
	v_rcp_f32_e32 v20, v20
	v_add_f32_e32 v21, 1.0, v21
	v_add_f32_e32 v22, 1.0, v22
	v_rcp_f32_e32 v21, v21
	v_rcp_f32_e32 v22, v22
	v_mul_f32_e32 v20, v26, v20
	v_mul_f32_e32 v24, v20, v18
	v_mul_f32_e32 v18, v31, v21
	v_mul_f32_e32 v20, v27, v22
	v_mul_f32_e32 v18, v18, v23
	v_mul_f32_e32 v19, v20, v19
	v_lshl_add_u64 v[20:21], v[32:33], 0, v[112:113]
	v_cvt_pk_bf16_f32 v16, v28, v16
	v_cvt_pk_bf16_f32 v17, v17, v18
	v_cvt_pk_bf16_f32 v18, v35, v25
	v_cvt_pk_bf16_f32 v19, v24, v19
	global_store_dwordx4 v[20:21], v[16:19], off
	s_nop 1
	v_mul_f32_e32 v16, 0xbfb8aa3b, v12
	v_exp_f32_e32 v16, v16
	v_mul_f32_e32 v17, 0xbfb8aa3b, v8
	v_exp_f32_e32 v17, v17
	v_add_u32_e32 v18, 0xb0, v141
	v_add_f32_e32 v16, 1.0, v16
	v_rcp_f32_e32 v19, v16
	v_add_f32_e32 v16, 1.0, v17
	v_rcp_f32_e32 v20, v16
	v_mad_i64_i32 v[16:17], s[28:29], v18, s49, v[134:135]
	v_mul_f32_e32 v12, v12, v19
	v_mul_f32_e32 v12, v12, v4
	v_mul_f32_e32 v4, v8, v20
	v_mul_f32_e32 v8, 0xbfb8aa3b, v13
	v_exp_f32_e32 v8, v8
	v_mul_f32_e32 v18, 0xbfb8aa3b, v9
	v_mul_f32_e32 v19, v4, v0
	v_exp_f32_e32 v18, v18
	v_add_f32_e32 v0, 1.0, v8
	v_rcp_f32_e32 v0, v0
	v_mul_f32_e32 v8, 0xbfb8aa3b, v14
	v_exp_f32_e32 v8, v8
	v_add_f32_e32 v4, 1.0, v18
	v_mul_f32_e32 v0, v13, v0
	v_rcp_f32_e32 v4, v4
	v_mul_f32_e32 v0, v0, v5
	v_add_f32_e32 v5, 1.0, v8
	v_rcp_f32_e32 v5, v5
	v_mul_f32_e32 v4, v9, v4
	v_mul_f32_e32 v8, 0xbfb8aa3b, v10
	v_mul_f32_e32 v9, v4, v1
	v_mul_f32_e32 v1, v14, v5
	v_exp_f32_e32 v8, v8
	v_mul_f32_e32 v1, v1, v6
	v_mul_f32_e32 v5, 0xbfb8aa3b, v15
	v_mul_f32_e32 v6, 0xbfb8aa3b, v11
	v_exp_f32_e32 v5, v5
	v_exp_f32_e32 v6, v6
	v_add_f32_e32 v4, 1.0, v8
	v_rcp_f32_e32 v4, v4
	v_add_f32_e32 v5, 1.0, v5
	v_add_f32_e32 v6, 1.0, v6
	v_rcp_f32_e32 v5, v5
	v_rcp_f32_e32 v6, v6
	v_mul_f32_e32 v4, v10, v4
	v_mul_f32_e32 v8, v4, v2
	v_mul_f32_e32 v2, v15, v5
	v_mul_f32_e32 v4, v11, v6
	v_mul_f32_e32 v2, v2, v7
	v_mul_f32_e32 v3, v4, v3
	v_lshl_add_u64 v[4:5], v[16:17], 0, v[112:113]
	s_mov_b32 s28, s45
	v_cvt_pk_bf16_f32 v0, v12, v0
	v_cvt_pk_bf16_f32 v1, v1, v2
	v_cvt_pk_bf16_f32 v2, v19, v9
	v_cvt_pk_bf16_f32 v3, v8, v3
	global_store_dwordx4 v[4:5], v[0:3], off
	s_mul_i32 s30, s28, s0
	s_add_i32 s30, s30, s1
	s_cmpk_gt_i32 s30, 0x57f
	s_mov_b64 s[28:29], -1
	s_cbranch_scc1 .LBB0_1240
	s_ashr_i32 s28, s30, 31
	s_lshr_b32 s28, s28, 29
	s_add_i32 s28, s30, s28
	s_ashr_i32 s29, s28, 3
	s_and_b32 s28, s28, -8
	s_sub_i32 s28, s30, s28
	s_cmp_lt_i32 s28, 0
	s_cselect_b32 s30, s46, 0xb0
	s_mul_i32 s28, s30, s28
	s_add_i32 s28, s28, s29
	s_mul_hi_i32 s29, s28, 0x2e8ba2e9
	s_lshr_b32 s30, s29, 31
	s_ashr_i32 s29, s29, 6
	s_add_i32 s29, s29, s30
	s_lshl_b32 s30, s29, 3
	s_mulk_i32 s29, 0x160
	s_sub_i32 s28, s28, s29
	s_bfe_u32 s29, s28, 0x3001c
	s_add_i32 s29, s28, s29
	s_sext_i32_i16 s31, s29
	s_and_b32 s29, s29, 0xfff8
	s_sub_i32 s28, s28, s29
	s_sext_i32_i16 s28, s28
	s_add_i32 s50, s30, s28
	s_ashr_i32 s51, s31, 3
	s_mov_b64 s[28:29], 0
	s_branch .LBB0_1240

.LBB0_1275:
	ds_read_b128 v[128:131], v160
	ds_read_b128 v[132:135], v160 offset:1024
	ds_read_b128 v[136:139], v160 offset:2048
	ds_read_b128 v[140:143], v160 offset:3072
	s_add_u32 s26, s22, 0xffea0080
	s_addc_u32 s27, s23, -1
	s_cmpk_eq_i32 s25, 0x54
	s_cselect_b32 s27, s17, s27
	s_cselect_b32 s26, s16, s26
	s_cselect_b32 s53, s19, s24
	s_cselect_b32 s52, s18, s21
	v_lshl_add_u64 v[188:189], s[22:23], 0, v[148:149]
	s_add_i32 m0, s35, 0xc000
	ds_read_b128 v[150:153], v161
	ds_read_b128 v[154:157], v161 offset:1024
	ds_read_b128 v[164:167], v161 offset:2048
	ds_read_b128 v[168:171], v161 offset:3072
	ds_read_b128 v[172:175], v161 offset:4096
	ds_read_b128 v[176:179], v161 offset:5120
	ds_read_b128 v[180:183], v161 offset:6144
	ds_read_b128 v[184:187], v161 offset:7168
	global_load_lds_dwordx4 v[188:189], off
	v_lshl_add_u64 v[188:189], v[188:189], 0, s[0:1]
	s_add_i32 m0, s35, 0xe000
	s_nop 0
	global_load_lds_dwordx4 v[188:189], off
	s_waitcnt lgkmcnt(8)
	s_barrier
	s_waitcnt lgkmcnt(0)
	s_waitcnt lgkmcnt(0)
	v_mfma_f32_16x16x32_bf16 v[124:127], v[128:131], v[150:153], v[124:127]
	v_mfma_f32_16x16x32_bf16 v[120:123], v[136:139], v[150:153], v[120:123]
	v_mfma_f32_16x16x32_bf16 v[112:115], v[128:131], v[164:167], v[112:115]
	v_mfma_f32_16x16x32_bf16 v[104:107], v[136:139], v[164:167], v[104:107]
	v_mfma_f32_16x16x32_bf16 v[96:99], v[128:131], v[172:175], v[96:99]
	v_mfma_f32_16x16x32_bf16 v[88:91], v[136:139], v[172:175], v[88:91]
	v_mfma_f32_16x16x32_bf16 v[80:83], v[128:131], v[180:183], v[80:83]
	v_mfma_f32_16x16x32_bf16 v[72:75], v[136:139], v[180:183], v[72:75]
	v_mfma_f32_16x16x32_bf16 v[124:127], v[132:135], v[154:157], v[124:127]
	v_mfma_f32_16x16x32_bf16 v[120:123], v[140:143], v[154:157], v[120:123]
	v_mfma_f32_16x16x32_bf16 v[112:115], v[132:135], v[168:171], v[112:115]
	v_mfma_f32_16x16x32_bf16 v[104:107], v[140:143], v[168:171], v[104:107]
	v_mfma_f32_16x16x32_bf16 v[96:99], v[132:135], v[176:179], v[96:99]
	v_mfma_f32_16x16x32_bf16 v[88:91], v[140:143], v[176:179], v[88:91]
	v_mfma_f32_16x16x32_bf16 v[80:83], v[132:135], v[184:187], v[80:83]
	v_mfma_f32_16x16x32_bf16 v[72:75], v[140:143], v[184:187], v[72:75]
	s_barrier
	v_lshl_add_u64 v[204:205], s[52:53], 0, v[144:145]
	s_add_i32 s52, s49, s34
	s_mov_b32 m0, s52
	ds_read_b128 v[188:191], v162
	ds_read_b128 v[192:195], v162 offset:1024
	ds_read_b128 v[196:199], v162 offset:2048
	ds_read_b128 v[200:203], v162 offset:3072
	global_load_lds_dwordx4 v[204:205], off
	v_lshl_add_u64 v[206:207], v[204:205], 0, s[0:1]
	s_add_i32 m0, s52, 0x2000
	s_nop 0
	global_load_lds_dwordx4 v[206:207], off
	s_barrier
	s_waitcnt lgkmcnt(0)
	s_waitcnt lgkmcnt(0)
	v_mfma_f32_16x16x32_bf16 v[116:119], v[188:191], v[150:153], v[116:119]
	v_mfma_f32_16x16x32_bf16 v[108:111], v[196:199], v[150:153], v[108:111]
	v_mfma_f32_16x16x32_bf16 v[100:103], v[188:191], v[164:167], v[100:103]
	v_mfma_f32_16x16x32_bf16 v[92:95], v[196:199], v[164:167], v[92:95]
	v_mfma_f32_16x16x32_bf16 v[84:87], v[188:191], v[172:175], v[84:87]
	v_mfma_f32_16x16x32_bf16 v[76:79], v[196:199], v[172:175], v[76:79]
	v_mfma_f32_16x16x32_bf16 v[68:71], v[188:191], v[180:183], v[68:71]
	v_mfma_f32_16x16x32_bf16 v[64:67], v[196:199], v[180:183], v[64:67]
	v_mfma_f32_16x16x32_bf16 v[116:119], v[192:195], v[154:157], v[116:119]
	v_mfma_f32_16x16x32_bf16 v[108:111], v[200:203], v[154:157], v[108:111]
	v_mfma_f32_16x16x32_bf16 v[100:103], v[192:195], v[168:171], v[100:103]
	v_mfma_f32_16x16x32_bf16 v[92:95], v[200:203], v[168:171], v[92:95]
	v_mfma_f32_16x16x32_bf16 v[84:87], v[192:195], v[176:179], v[84:87]
	v_mfma_f32_16x16x32_bf16 v[76:79], v[200:203], v[176:179], v[76:79]
	v_mfma_f32_16x16x32_bf16 v[68:71], v[192:195], v[184:187], v[68:71]
	v_mfma_f32_16x16x32_bf16 v[64:67], v[200:203], v[184:187], v[64:67]
	s_mov_b32 m0, s35
	v_lshl_add_u64 v[206:207], s[26:27], 0, v[146:147]
	s_barrier
	ds_read_b128 v[150:153], v161 offset:16384
	ds_read_b128 v[154:157], v161 offset:17408
	ds_read_b128 v[164:167], v161 offset:18432
	ds_read_b128 v[168:171], v161 offset:19456
	ds_read_b128 v[172:175], v161 offset:20480
	ds_read_b128 v[176:179], v161 offset:21504
	ds_read_b128 v[180:183], v161 offset:22528
	ds_read_b128 v[184:187], v161 offset:23552
	global_load_lds_dwordx4 v[206:207], off
	v_lshl_add_u64 v[208:209], v[206:207], 0, s[0:1]
	s_mov_b32 m0, s36
	s_nop 0
	global_load_lds_dwordx4 v[208:209], off
	s_barrier
	s_waitcnt lgkmcnt(0)
	s_waitcnt lgkmcnt(0)
	v_mfma_f32_16x16x32_bf16 v[60:63], v[128:131], v[150:153], v[60:63]
	v_mfma_f32_16x16x32_bf16 v[56:59], v[136:139], v[150:153], v[56:59]
	v_mfma_f32_16x16x32_bf16 v[48:51], v[128:131], v[164:167], v[48:51]
	v_mfma_f32_16x16x32_bf16 v[40:43], v[136:139], v[164:167], v[40:43]
	v_mfma_f32_16x16x32_bf16 v[32:35], v[128:131], v[172:175], v[32:35]
	v_mfma_f32_16x16x32_bf16 v[24:27], v[136:139], v[172:175], v[24:27]
	v_mfma_f32_16x16x32_bf16 v[16:19], v[128:131], v[180:183], v[16:19]
	v_mfma_f32_16x16x32_bf16 v[8:11], v[136:139], v[180:183], v[8:11]
	v_mfma_f32_16x16x32_bf16 v[60:63], v[132:135], v[154:157], v[60:63]
	v_mfma_f32_16x16x32_bf16 v[56:59], v[140:143], v[154:157], v[56:59]
	v_mfma_f32_16x16x32_bf16 v[48:51], v[132:135], v[168:171], v[48:51]
	v_mfma_f32_16x16x32_bf16 v[40:43], v[140:143], v[168:171], v[40:43]
	v_mfma_f32_16x16x32_bf16 v[32:35], v[132:135], v[176:179], v[32:35]
	v_mfma_f32_16x16x32_bf16 v[24:27], v[140:143], v[176:179], v[24:27]
	v_mfma_f32_16x16x32_bf16 v[16:19], v[132:135], v[184:187], v[16:19]
	v_mfma_f32_16x16x32_bf16 v[8:11], v[140:143], v[184:187], v[8:11]
	s_barrier
	s_add_i32 s26, s50, s34
	v_lshl_add_u64 v[128:129], v[204:205], 0, s[2:3]
	s_mov_b32 m0, s26
	s_nop 0
	global_load_lds_dwordx4 v[128:129], off
	v_lshl_add_u64 v[128:129], v[204:205], 0, s[4:5]
	s_add_i32 m0, s26, 0x2000
	s_nop 0
	global_load_lds_dwordx4 v[128:129], off
	s_waitcnt vmcnt(6)
	s_barrier
	v_mfma_f32_16x16x32_bf16 v[52:55], v[188:191], v[150:153], v[52:55]
	v_mfma_f32_16x16x32_bf16 v[44:47], v[196:199], v[150:153], v[44:47]
	v_mfma_f32_16x16x32_bf16 v[36:39], v[188:191], v[164:167], v[36:39]
	v_mfma_f32_16x16x32_bf16 v[28:31], v[196:199], v[164:167], v[28:31]
	v_mfma_f32_16x16x32_bf16 v[20:23], v[188:191], v[172:175], v[20:23]
	v_mfma_f32_16x16x32_bf16 v[12:15], v[196:199], v[172:175], v[12:15]
	v_mfma_f32_16x16x32_bf16 v[4:7], v[188:191], v[180:183], v[4:7]
	v_mfma_f32_16x16x32_bf16 v[0:3], v[196:199], v[180:183], v[0:3]
	v_mfma_f32_16x16x32_bf16 v[52:55], v[192:195], v[154:157], v[52:55]
	v_mfma_f32_16x16x32_bf16 v[44:47], v[200:203], v[154:157], v[44:47]
	v_mfma_f32_16x16x32_bf16 v[36:39], v[192:195], v[168:171], v[36:39]
	v_mfma_f32_16x16x32_bf16 v[28:31], v[200:203], v[168:171], v[28:31]
	v_mfma_f32_16x16x32_bf16 v[20:23], v[192:195], v[176:179], v[20:23]
	v_mfma_f32_16x16x32_bf16 v[12:15], v[200:203], v[176:179], v[12:15]
	v_mfma_f32_16x16x32_bf16 v[4:7], v[192:195], v[184:187], v[4:7]
	v_mfma_f32_16x16x32_bf16 v[0:3], v[200:203], v[184:187], v[0:3]
	s_add_i32 s26, 0, 0x18000
	v_add_u32_e32 v140, s26, v159
	s_barrier
	ds_read_b128 v[128:131], v140
	ds_read_b128 v[132:135], v140 offset:1024
	ds_read_b128 v[136:139], v140 offset:2048
	ds_read_b128 v[140:143], v140 offset:3072
	s_mov_b32 m0, s37
	v_lshl_add_u64 v[188:189], v[206:207], 0, s[2:3]
	ds_read_b128 v[150:153], v161 offset:32768
	ds_read_b128 v[154:157], v161 offset:33792
	ds_read_b128 v[164:167], v161 offset:34816
	ds_read_b128 v[168:171], v161 offset:35840
	ds_read_b128 v[172:175], v161 offset:36864
	ds_read_b128 v[176:179], v161 offset:37888
	ds_read_b128 v[180:183], v161 offset:38912
	ds_read_b128 v[184:187], v161 offset:39936
	global_load_lds_dwordx4 v[188:189], off
	v_lshl_add_u64 v[188:189], v[206:207], 0, s[4:5]
	s_mov_b32 m0, s38
	s_nop 0
	global_load_lds_dwordx4 v[188:189], off
	s_waitcnt lgkmcnt(8)
	s_barrier
	s_waitcnt lgkmcnt(0)
	s_waitcnt lgkmcnt(0)
	v_mfma_f32_16x16x32_bf16 v[124:127], v[128:131], v[150:153], v[124:127]
	v_mfma_f32_16x16x32_bf16 v[120:123], v[136:139], v[150:153], v[120:123]
	v_mfma_f32_16x16x32_bf16 v[112:115], v[128:131], v[164:167], v[112:115]
	v_mfma_f32_16x16x32_bf16 v[104:107], v[136:139], v[164:167], v[104:107]
	v_mfma_f32_16x16x32_bf16 v[96:99], v[128:131], v[172:175], v[96:99]
	v_mfma_f32_16x16x32_bf16 v[88:91], v[136:139], v[172:175], v[88:91]
	v_mfma_f32_16x16x32_bf16 v[80:83], v[128:131], v[180:183], v[80:83]
	v_mfma_f32_16x16x32_bf16 v[72:75], v[136:139], v[180:183], v[72:75]
	v_mfma_f32_16x16x32_bf16 v[124:127], v[132:135], v[154:157], v[124:127]
	v_mfma_f32_16x16x32_bf16 v[120:123], v[140:143], v[154:157], v[120:123]
	v_mfma_f32_16x16x32_bf16 v[112:115], v[132:135], v[168:171], v[112:115]
	v_mfma_f32_16x16x32_bf16 v[104:107], v[140:143], v[168:171], v[104:107]
	v_mfma_f32_16x16x32_bf16 v[96:99], v[132:135], v[176:179], v[96:99]
	v_mfma_f32_16x16x32_bf16 v[88:91], v[140:143], v[176:179], v[88:91]
	v_mfma_f32_16x16x32_bf16 v[80:83], v[132:135], v[184:187], v[80:83]
	v_mfma_f32_16x16x32_bf16 v[72:75], v[140:143], v[184:187], v[72:75]
	s_barrier
	s_add_i32 s27, 0, 0x1c000
	s_add_i32 s26, s26, s34
	v_add_u32_e32 v163, s27, v159
	v_lshl_add_u64 v[208:209], v[204:205], 0, s[6:7]
	s_mov_b32 m0, s26
	ds_read_b128 v[188:191], v163
	ds_read_b128 v[192:195], v163 offset:1024
	ds_read_b128 v[196:199], v163 offset:2048
	ds_read_b128 v[200:203], v163 offset:3072
	global_load_lds_dwordx4 v[208:209], off
	v_lshl_add_u64 v[208:209], v[204:205], 0, s[8:9]
	s_add_i32 m0, s26, 0x2000
	s_nop 0
	global_load_lds_dwordx4 v[208:209], off
	s_barrier
	s_waitcnt lgkmcnt(0)
	s_waitcnt lgkmcnt(0)
	v_mfma_f32_16x16x32_bf16 v[116:119], v[188:191], v[150:153], v[116:119]
	v_mfma_f32_16x16x32_bf16 v[108:111], v[196:199], v[150:153], v[108:111]
	v_mfma_f32_16x16x32_bf16 v[100:103], v[188:191], v[164:167], v[100:103]
	v_mfma_f32_16x16x32_bf16 v[92:95], v[196:199], v[164:167], v[92:95]
	v_mfma_f32_16x16x32_bf16 v[84:87], v[188:191], v[172:175], v[84:87]
	v_mfma_f32_16x16x32_bf16 v[76:79], v[196:199], v[172:175], v[76:79]
	v_mfma_f32_16x16x32_bf16 v[68:71], v[188:191], v[180:183], v[68:71]
	v_mfma_f32_16x16x32_bf16 v[64:67], v[196:199], v[180:183], v[64:67]
	v_mfma_f32_16x16x32_bf16 v[116:119], v[192:195], v[154:157], v[116:119]
	v_mfma_f32_16x16x32_bf16 v[108:111], v[200:203], v[154:157], v[108:111]
	v_mfma_f32_16x16x32_bf16 v[100:103], v[192:195], v[168:171], v[100:103]
	v_mfma_f32_16x16x32_bf16 v[92:95], v[200:203], v[168:171], v[92:95]
	v_mfma_f32_16x16x32_bf16 v[84:87], v[192:195], v[176:179], v[84:87]
	v_mfma_f32_16x16x32_bf16 v[76:79], v[200:203], v[176:179], v[76:79]
	v_mfma_f32_16x16x32_bf16 v[68:71], v[192:195], v[184:187], v[68:71]
	v_mfma_f32_16x16x32_bf16 v[64:67], v[200:203], v[184:187], v[64:67]
	s_mov_b32 m0, s43
	v_lshl_add_u64 v[208:209], v[206:207], 0, s[6:7]
	s_barrier
	ds_read_b128 v[150:153], v161 offset:49152
	ds_read_b128 v[154:157], v161 offset:50176
	ds_read_b128 v[164:167], v161 offset:51200
	ds_read_b128 v[168:171], v161 offset:52224
	ds_read_b128 v[172:175], v161 offset:53248
	ds_read_b128 v[176:179], v161 offset:54272
	ds_read_b128 v[180:183], v161 offset:55296
	ds_read_b128 v[184:187], v161 offset:56320
	global_load_lds_dwordx4 v[208:209], off
	v_lshl_add_u64 v[206:207], v[206:207], 0, s[8:9]
	s_mov_b32 m0, s44
	s_nop 0
	global_load_lds_dwordx4 v[206:207], off
	s_barrier
	s_waitcnt lgkmcnt(0)
	s_waitcnt lgkmcnt(0)
	v_mfma_f32_16x16x32_bf16 v[60:63], v[128:131], v[150:153], v[60:63]
	v_mfma_f32_16x16x32_bf16 v[56:59], v[136:139], v[150:153], v[56:59]
	v_mfma_f32_16x16x32_bf16 v[48:51], v[128:131], v[164:167], v[48:51]
	v_mfma_f32_16x16x32_bf16 v[40:43], v[136:139], v[164:167], v[40:43]
	v_mfma_f32_16x16x32_bf16 v[32:35], v[128:131], v[172:175], v[32:35]
	v_mfma_f32_16x16x32_bf16 v[24:27], v[136:139], v[172:175], v[24:27]
	v_mfma_f32_16x16x32_bf16 v[16:19], v[128:131], v[180:183], v[16:19]
	v_mfma_f32_16x16x32_bf16 v[8:11], v[136:139], v[180:183], v[8:11]
	v_mfma_f32_16x16x32_bf16 v[60:63], v[132:135], v[154:157], v[60:63]
	v_mfma_f32_16x16x32_bf16 v[56:59], v[140:143], v[154:157], v[56:59]
	v_mfma_f32_16x16x32_bf16 v[48:51], v[132:135], v[168:171], v[48:51]
	v_mfma_f32_16x16x32_bf16 v[40:43], v[140:143], v[168:171], v[40:43]
	v_mfma_f32_16x16x32_bf16 v[32:35], v[132:135], v[176:179], v[32:35]
	v_mfma_f32_16x16x32_bf16 v[24:27], v[140:143], v[176:179], v[24:27]
	v_mfma_f32_16x16x32_bf16 v[16:19], v[132:135], v[184:187], v[16:19]
	v_mfma_f32_16x16x32_bf16 v[8:11], v[140:143], v[184:187], v[8:11]
	s_barrier
	s_add_i32 s26, s27, s34
	v_lshl_add_u64 v[128:129], v[204:205], 0, s[10:11]
	s_mov_b32 m0, s26
	s_nop 0
	global_load_lds_dwordx4 v[128:129], off
	v_lshl_add_u64 v[128:129], v[204:205], 0, s[14:15]
	s_add_i32 m0, s26, 0x2000
	s_nop 0
	global_load_lds_dwordx4 v[128:129], off
	s_waitcnt vmcnt(6)
	s_barrier
	v_mfma_f32_16x16x32_bf16 v[52:55], v[188:191], v[150:153], v[52:55]
	v_mfma_f32_16x16x32_bf16 v[44:47], v[196:199], v[150:153], v[44:47]
	v_mfma_f32_16x16x32_bf16 v[36:39], v[188:191], v[164:167], v[36:39]
	v_mfma_f32_16x16x32_bf16 v[28:31], v[196:199], v[164:167], v[28:31]
	v_mfma_f32_16x16x32_bf16 v[20:23], v[188:191], v[172:175], v[20:23]
	v_mfma_f32_16x16x32_bf16 v[12:15], v[196:199], v[172:175], v[12:15]
	v_mfma_f32_16x16x32_bf16 v[4:7], v[188:191], v[180:183], v[4:7]
	v_mfma_f32_16x16x32_bf16 v[0:3], v[196:199], v[180:183], v[0:3]
	v_mfma_f32_16x16x32_bf16 v[52:55], v[192:195], v[154:157], v[52:55]
	v_mfma_f32_16x16x32_bf16 v[44:47], v[200:203], v[154:157], v[44:47]
	v_mfma_f32_16x16x32_bf16 v[36:39], v[192:195], v[168:171], v[36:39]
	v_mfma_f32_16x16x32_bf16 v[28:31], v[200:203], v[168:171], v[28:31]
	v_mfma_f32_16x16x32_bf16 v[20:23], v[192:195], v[176:179], v[20:23]
	v_mfma_f32_16x16x32_bf16 v[12:15], v[200:203], v[176:179], v[12:15]
	v_mfma_f32_16x16x32_bf16 v[4:7], v[192:195], v[184:187], v[4:7]
	v_mfma_f32_16x16x32_bf16 v[0:3], v[200:203], v[184:187], v[0:3]
	s_add_i32 s25, s25, 2
	s_add_u32 s22, s22, 0x100
	s_addc_u32 s23, s23, 0
	s_add_u32 s21, s21, 0x100
	s_addc_u32 s24, s24, 0
	s_cmpk_gt_u32 s25, 0x55
	s_barrier
	s_cbranch_scc0 .LBB0_1275
	v_mov_b32_e32 v128, v158
	s_mov_b32 s24, s33
	s_mov_b32 s22, s45
	s_cmp_lt_i32 s20, 16
	s_cselect_b32 s23, 0, 0xc000
	s_lshl_b32 s25, s51, 8
	s_lshl_b32 s22, s22, 5
	v_and_b32_e32 v130, 15, v128
	s_ashr_i32 s21, s20, 31
	s_add_i32 s22, s22, s25
	v_lshrrev_b32_e32 v128, 1, v128
	v_and_or_b32 v128, v128, 24, s22
	s_add_u32 s22, s41, s23
	s_addc_u32 s23, s42, 0
	v_lshl_or_b32 v152, s24, 6, v130
	s_lshl_b64 s[24:25], s[20:21], 20
	s_add_u32 s24, s47, s24
	v_ashrrev_i32_e32 v129, 31, v128
	s_addc_u32 s25, s48, s25
	v_ashrrev_i32_e32 v153, 31, v152
	v_lshl_add_u64 v[154:155], v[128:129], 1, s[24:25]
	v_lshlrev_b64 v[130:131], 12, v[152:153]
	v_or_b32_e32 v196, 16, v152
	v_lshl_add_u64 v[130:131], v[154:155], 0, v[130:131]
	v_ashrrev_i32_e32 v197, 31, v196
	global_load_dwordx4 v[164:167], v[130:131], off
	global_load_dwordx4 v[168:171], v[130:131], off offset:256
	v_lshlrev_b64 v[130:131], 12, v[196:197]
	v_or_b32_e32 v198, 32, v152
	v_lshl_add_u64 v[130:131], v[154:155], 0, v[130:131]
	v_ashrrev_i32_e32 v199, 31, v198
	global_load_dwordx4 v[172:175], v[130:131], off
	global_load_dwordx4 v[176:179], v[130:131], off offset:256
	v_lshlrev_b64 v[130:131], 12, v[198:199]
	v_or_b32_e32 v156, 48, v152
	v_lshl_add_u64 v[130:131], v[154:155], 0, v[130:131]
	v_ashrrev_i32_e32 v157, 31, v156
	global_load_dwordx4 v[180:183], v[130:131], off
	global_load_dwordx4 v[184:187], v[130:131], off offset:256
	v_lshlrev_b64 v[130:131], 12, v[156:157]
	v_lshlrev_b64 v[150:151], 2, v[128:129]
	v_lshl_add_u64 v[130:131], v[154:155], 0, v[130:131]
	v_lshl_add_u64 v[128:129], s[22:23], 0, v[150:151]
	global_load_dwordx4 v[188:191], v[130:131], off
	global_load_dwordx4 v[192:195], v[130:131], off offset:256
	global_load_dwordx4 v[140:143], v[128:129], off
	global_load_dwordx4 v[136:139], v[128:129], off offset:16
	global_load_dwordx4 v[132:135], v[128:129], off offset:512
	s_nop 0
	global_load_dwordx4 v[128:131], v[128:129], off offset:528
	s_lshl_b64 s[20:21], s[20:21], 21
	s_add_u32 s20, s39, s20
	s_addc_u32 s21, s40, s21
	v_lshl_add_u64 v[150:151], s[20:21], 0, v[150:151]
	v_lshlrev_b64 v[232:233], 13, v[152:153]
	v_lshl_add_u64 v[232:233], v[150:151], 0, v[232:233]
	s_mov_b32 s20, s46
	s_mov_b64 s[22:23], -1
	s_waitcnt vmcnt(0)
	v_lshlrev_b32_e32 v200, 16, v164
	v_and_b32_e32 v201, 0xffff0000, v164
	v_lshlrev_b32_e32 v164, 16, v165
	v_and_b32_e32 v165, 0xffff0000, v165
	v_lshlrev_b32_e32 v204, 16, v168
	v_and_b32_e32 v205, 0xffff0000, v168
	v_lshlrev_b32_e32 v168, 16, v169
	v_and_b32_e32 v169, 0xffff0000, v169
	v_lshlrev_b32_e32 v206, 16, v170
	v_and_b32_e32 v207, 0xffff0000, v170
	v_lshlrev_b32_e32 v202, 16, v166
	v_and_b32_e32 v203, 0xffff0000, v166
	v_lshlrev_b32_e32 v166, 16, v167
	v_and_b32_e32 v167, 0xffff0000, v167
	v_lshlrev_b32_e32 v170, 16, v171
	v_and_b32_e32 v171, 0xffff0000, v171
	v_pk_fma_f32 v[126:127], v[126:127], v[142:143], v[164:165]
	v_pk_fma_f32 v[124:125], v[124:125], v[140:141], v[200:201]
	v_pk_fma_f32 v[118:119], v[118:119], v[134:135], v[168:169]
	v_pk_fma_f32 v[116:117], v[116:117], v[132:133], v[204:205]
	v_pk_fma_f32 v[108:109], v[108:109], v[128:129], v[206:207]
	v_lshlrev_b32_e32 v208, 16, v172
	v_and_b32_e32 v209, 0xffff0000, v172
	v_lshlrev_b32_e32 v172, 16, v173
	v_and_b32_e32 v173, 0xffff0000, v173
	v_lshlrev_b32_e32 v212, 16, v176
	v_and_b32_e32 v213, 0xffff0000, v176
	v_lshlrev_b32_e32 v176, 16, v177
	v_and_b32_e32 v177, 0xffff0000, v177
	v_lshlrev_b32_e32 v214, 16, v178
	v_and_b32_e32 v215, 0xffff0000, v178
	v_pk_fma_f32 v[122:123], v[122:123], v[138:139], v[166:167]
	v_pk_fma_f32 v[120:121], v[120:121], v[136:137], v[202:203]
	global_store_dwordx4 v[232:233], v[124:127], off
	global_store_dwordx4 v[232:233], v[120:123], off offset:16
	v_pk_fma_f32 v[110:111], v[110:111], v[130:131], v[170:171]
	global_store_dwordx4 v[232:233], v[116:119], off offset:512
	global_store_dwordx4 v[232:233], v[108:111], off offset:528
	v_lshlrev_b32_e32 v210, 16, v174
	v_and_b32_e32 v211, 0xffff0000, v174
	v_lshlrev_b64 v[108:109], 13, v[196:197]
	v_lshlrev_b32_e32 v174, 16, v175
	v_and_b32_e32 v175, 0xffff0000, v175
	v_lshlrev_b32_e32 v178, 16, v179
	v_and_b32_e32 v179, 0xffff0000, v179
	v_lshl_add_u64 v[116:117], v[150:151], 0, v[108:109]
	v_pk_fma_f32 v[110:111], v[114:115], v[142:143], v[172:173]
	v_pk_fma_f32 v[108:109], v[112:113], v[140:141], v[208:209]
	v_pk_fma_f32 v[102:103], v[102:103], v[134:135], v[176:177]
	v_pk_fma_f32 v[100:101], v[100:101], v[132:133], v[212:213]
	v_pk_fma_f32 v[92:93], v[92:93], v[128:129], v[214:215]
	v_lshlrev_b32_e32 v216, 16, v180
	v_and_b32_e32 v217, 0xffff0000, v180
	v_lshlrev_b32_e32 v180, 16, v181
	v_and_b32_e32 v181, 0xffff0000, v181
	v_lshlrev_b32_e32 v220, 16, v184
	v_and_b32_e32 v221, 0xffff0000, v184
	v_lshlrev_b32_e32 v184, 16, v185
	v_and_b32_e32 v185, 0xffff0000, v185
	v_lshlrev_b32_e32 v222, 16, v186
	v_and_b32_e32 v223, 0xffff0000, v186
	v_pk_fma_f32 v[106:107], v[106:107], v[138:139], v[174:175]
	v_pk_fma_f32 v[104:105], v[104:105], v[136:137], v[210:211]
	global_store_dwordx4 v[116:117], v[108:111], off
	global_store_dwordx4 v[116:117], v[104:107], off offset:16
	v_pk_fma_f32 v[94:95], v[94:95], v[130:131], v[178:179]
	global_store_dwordx4 v[116:117], v[100:103], off offset:512
	global_store_dwordx4 v[116:117], v[92:95], off offset:528
	v_lshlrev_b32_e32 v218, 16, v182
	v_and_b32_e32 v219, 0xffff0000, v182
	v_lshlrev_b64 v[92:93], 13, v[198:199]
	v_lshlrev_b32_e32 v182, 16, v183
	v_and_b32_e32 v183, 0xffff0000, v183
	v_lshlrev_b32_e32 v186, 16, v187
	v_and_b32_e32 v187, 0xffff0000, v187
	v_lshl_add_u64 v[100:101], v[150:151], 0, v[92:93]
	v_pk_fma_f32 v[94:95], v[98:99], v[142:143], v[180:181]
	v_pk_fma_f32 v[92:93], v[96:97], v[140:141], v[216:217]
	v_pk_fma_f32 v[86:87], v[86:87], v[134:135], v[184:185]
	v_pk_fma_f32 v[84:85], v[84:85], v[132:133], v[220:221]
	v_pk_fma_f32 v[76:77], v[76:77], v[128:129], v[222:223]
	v_lshlrev_b32_e32 v224, 16, v188
	v_and_b32_e32 v225, 0xffff0000, v188
	v_lshlrev_b32_e32 v188, 16, v189
	v_and_b32_e32 v189, 0xffff0000, v189
	v_lshlrev_b32_e32 v228, 16, v192
	v_and_b32_e32 v229, 0xffff0000, v192
	v_lshlrev_b32_e32 v192, 16, v193
	v_and_b32_e32 v193, 0xffff0000, v193
	v_lshlrev_b32_e32 v230, 16, v194
	v_and_b32_e32 v231, 0xffff0000, v194
	v_pk_fma_f32 v[90:91], v[90:91], v[138:139], v[182:183]
	v_pk_fma_f32 v[88:89], v[88:89], v[136:137], v[218:219]
	global_store_dwordx4 v[100:101], v[92:95], off
	global_store_dwordx4 v[100:101], v[88:91], off offset:16
	v_pk_fma_f32 v[78:79], v[78:79], v[130:131], v[186:187]
	global_store_dwordx4 v[100:101], v[84:87], off offset:512
	global_store_dwordx4 v[100:101], v[76:79], off offset:528
	v_add_u32_e32 v96, 0x80, v152
	v_lshlrev_b32_e32 v226, 16, v190
	v_lshlrev_b64 v[76:77], 13, v[156:157]
	v_and_b32_e32 v227, 0xffff0000, v190
	v_lshlrev_b32_e32 v190, 16, v191
	v_and_b32_e32 v191, 0xffff0000, v191
	v_lshlrev_b32_e32 v194, 16, v195
	v_and_b32_e32 v195, 0xffff0000, v195
	v_lshl_add_u64 v[84:85], v[150:151], 0, v[76:77]
	v_pk_fma_f32 v[78:79], v[82:83], v[142:143], v[188:189]
	v_pk_fma_f32 v[76:77], v[80:81], v[140:141], v[224:225]
	v_pk_fma_f32 v[70:71], v[70:71], v[134:135], v[192:193]
	v_pk_fma_f32 v[68:69], v[68:69], v[132:133], v[228:229]
	v_pk_fma_f32 v[64:65], v[64:65], v[128:129], v[230:231]
	v_ashrrev_i32_e32 v97, 31, v96
	v_pk_fma_f32 v[74:75], v[74:75], v[138:139], v[190:191]
	v_pk_fma_f32 v[72:73], v[72:73], v[136:137], v[226:227]
	global_store_dwordx4 v[84:85], v[76:79], off
	global_store_dwordx4 v[84:85], v[72:75], off offset:16
	v_pk_fma_f32 v[66:67], v[66:67], v[130:131], v[194:195]
	global_store_dwordx4 v[84:85], v[68:71], off offset:512
	global_store_dwordx4 v[84:85], v[64:67], off offset:528
	v_add_u32_e32 v98, 0x90, v152
	v_ashrrev_i32_e32 v99, 31, v98
	v_lshlrev_b64 v[64:65], 12, v[96:97]
	v_lshl_add_u64 v[68:69], v[154:155], 0, v[64:65]
	global_load_dwordx4 v[64:67], v[68:69], off
	s_nop 0
	global_load_dwordx4 v[68:71], v[68:69], off offset:256
	v_lshlrev_b64 v[72:73], 12, v[98:99]
	v_add_u32_e32 v100, 0xa0, v152
	v_lshl_add_u64 v[80:81], v[154:155], 0, v[72:73]
	v_ashrrev_i32_e32 v101, 31, v100
	global_load_dwordx4 v[72:75], v[80:81], off
	global_load_dwordx4 v[76:79], v[80:81], off offset:256
	v_lshlrev_b64 v[80:81], 12, v[100:101]
	v_add_u32_e32 v102, 0xb0, v152
	v_lshl_add_u64 v[88:89], v[154:155], 0, v[80:81]
	v_ashrrev_i32_e32 v103, 31, v102
	global_load_dwordx4 v[80:83], v[88:89], off
	global_load_dwordx4 v[84:87], v[88:89], off offset:256
	v_lshlrev_b64 v[88:89], 12, v[102:103]
	v_lshl_add_u64 v[92:93], v[154:155], 0, v[88:89]
	global_load_dwordx4 v[88:91], v[92:93], off
	s_nop 0
	global_load_dwordx4 v[92:95], v[92:93], off offset:256
	v_lshlrev_b64 v[96:97], 13, v[96:97]
	v_lshl_add_u64 v[96:97], v[150:151], 0, v[96:97]
	s_waitcnt vmcnt(0)
	v_lshlrev_b32_e32 v104, 16, v64
	v_and_b32_e32 v105, 0xffff0000, v64
	v_lshlrev_b32_e32 v64, 16, v65
	v_and_b32_e32 v65, 0xffff0000, v65
	v_lshlrev_b32_e32 v108, 16, v68
	v_and_b32_e32 v109, 0xffff0000, v68
	v_lshlrev_b32_e32 v68, 16, v69
	v_and_b32_e32 v69, 0xffff0000, v69
	v_lshlrev_b32_e32 v110, 16, v70
	v_and_b32_e32 v111, 0xffff0000, v70
	v_lshlrev_b32_e32 v106, 16, v66
	v_and_b32_e32 v107, 0xffff0000, v66
	v_lshlrev_b32_e32 v66, 16, v67
	v_and_b32_e32 v67, 0xffff0000, v67
	v_lshlrev_b32_e32 v70, 16, v71
	v_and_b32_e32 v71, 0xffff0000, v71
	v_pk_fma_f32 v[62:63], v[62:63], v[142:143], v[64:65]
	v_pk_fma_f32 v[60:61], v[60:61], v[140:141], v[104:105]
	v_pk_fma_f32 v[54:55], v[54:55], v[134:135], v[68:69]
	v_pk_fma_f32 v[52:53], v[52:53], v[132:133], v[108:109]
	v_pk_fma_f32 v[44:45], v[44:45], v[128:129], v[110:111]
	v_lshlrev_b32_e32 v112, 16, v72
	v_and_b32_e32 v113, 0xffff0000, v72
	v_lshlrev_b32_e32 v72, 16, v73
	v_and_b32_e32 v73, 0xffff0000, v73
	v_lshlrev_b32_e32 v116, 16, v76
	v_and_b32_e32 v117, 0xffff0000, v76
	v_lshlrev_b32_e32 v76, 16, v77
	v_and_b32_e32 v77, 0xffff0000, v77
	v_lshlrev_b32_e32 v118, 16, v78
	v_and_b32_e32 v119, 0xffff0000, v78
	v_pk_fma_f32 v[58:59], v[58:59], v[138:139], v[66:67]
	v_pk_fma_f32 v[56:57], v[56:57], v[136:137], v[106:107]
	global_store_dwordx4 v[96:97], v[60:63], off
	global_store_dwordx4 v[96:97], v[56:59], off offset:16
	v_pk_fma_f32 v[46:47], v[46:47], v[130:131], v[70:71]
	global_store_dwordx4 v[96:97], v[52:55], off offset:512
	global_store_dwordx4 v[96:97], v[44:47], off offset:528
	v_lshlrev_b32_e32 v114, 16, v74
	v_and_b32_e32 v115, 0xffff0000, v74
	v_lshlrev_b64 v[44:45], 13, v[98:99]
	v_lshlrev_b32_e32 v74, 16, v75
	v_and_b32_e32 v75, 0xffff0000, v75
	v_lshlrev_b32_e32 v78, 16, v79
	v_and_b32_e32 v79, 0xffff0000, v79
	v_lshl_add_u64 v[52:53], v[150:151], 0, v[44:45]
	v_pk_fma_f32 v[46:47], v[50:51], v[142:143], v[72:73]
	v_pk_fma_f32 v[44:45], v[48:49], v[140:141], v[112:113]
	v_pk_fma_f32 v[38:39], v[38:39], v[134:135], v[76:77]
	v_pk_fma_f32 v[36:37], v[36:37], v[132:133], v[116:117]
	v_pk_fma_f32 v[28:29], v[28:29], v[128:129], v[118:119]
	v_lshlrev_b32_e32 v120, 16, v80
	v_and_b32_e32 v121, 0xffff0000, v80
	v_lshlrev_b32_e32 v80, 16, v81
	v_and_b32_e32 v81, 0xffff0000, v81
	v_lshlrev_b32_e32 v124, 16, v84
	v_and_b32_e32 v125, 0xffff0000, v84
	v_lshlrev_b32_e32 v84, 16, v85
	v_and_b32_e32 v85, 0xffff0000, v85
	v_lshlrev_b32_e32 v126, 16, v86
	v_and_b32_e32 v127, 0xffff0000, v86
	v_pk_fma_f32 v[42:43], v[42:43], v[138:139], v[74:75]
	v_pk_fma_f32 v[40:41], v[40:41], v[136:137], v[114:115]
	global_store_dwordx4 v[52:53], v[44:47], off
	global_store_dwordx4 v[52:53], v[40:43], off offset:16
	v_pk_fma_f32 v[30:31], v[30:31], v[130:131], v[78:79]
	global_store_dwordx4 v[52:53], v[36:39], off offset:512
	global_store_dwordx4 v[52:53], v[28:31], off offset:528
	v_lshlrev_b32_e32 v122, 16, v82
	v_and_b32_e32 v123, 0xffff0000, v82
	v_lshlrev_b64 v[28:29], 13, v[100:101]
	v_lshlrev_b32_e32 v82, 16, v83
	v_and_b32_e32 v83, 0xffff0000, v83
	v_lshlrev_b32_e32 v86, 16, v87
	v_and_b32_e32 v87, 0xffff0000, v87
	v_lshl_add_u64 v[36:37], v[150:151], 0, v[28:29]
	v_pk_fma_f32 v[30:31], v[34:35], v[142:143], v[80:81]
	v_pk_fma_f32 v[28:29], v[32:33], v[140:141], v[120:121]
	v_pk_fma_f32 v[22:23], v[22:23], v[134:135], v[84:85]
	v_pk_fma_f32 v[20:21], v[20:21], v[132:133], v[124:125]
	v_pk_fma_f32 v[12:13], v[12:13], v[128:129], v[126:127]
	v_lshlrev_b32_e32 v152, 16, v88
	v_and_b32_e32 v153, 0xffff0000, v88
	v_lshlrev_b32_e32 v88, 16, v89
	v_and_b32_e32 v89, 0xffff0000, v89
	v_lshlrev_b32_e32 v156, 16, v92
	v_and_b32_e32 v157, 0xffff0000, v92
	v_lshlrev_b32_e32 v92, 16, v93
	v_and_b32_e32 v93, 0xffff0000, v93
	v_pk_fma_f32 v[26:27], v[26:27], v[138:139], v[82:83]
	v_pk_fma_f32 v[24:25], v[24:25], v[136:137], v[122:123]
	global_store_dwordx4 v[36:37], v[28:31], off
	global_store_dwordx4 v[36:37], v[24:27], off offset:16
	v_pk_fma_f32 v[14:15], v[14:15], v[130:131], v[86:87]
	global_store_dwordx4 v[36:37], v[20:23], off offset:512
	global_store_dwordx4 v[36:37], v[12:15], off offset:528
	v_lshlrev_b32_e32 v154, 16, v90
	v_and_b32_e32 v155, 0xffff0000, v90
	v_lshlrev_b64 v[12:13], 13, v[102:103]
	v_lshlrev_b32_e32 v90, 16, v91
	v_and_b32_e32 v91, 0xffff0000, v91
	v_lshlrev_b32_e32 v164, 16, v94
	v_and_b32_e32 v165, 0xffff0000, v94
	v_lshlrev_b32_e32 v94, 16, v95
	v_and_b32_e32 v95, 0xffff0000, v95
	v_lshl_add_u64 v[20:21], v[150:151], 0, v[12:13]
	v_pk_fma_f32 v[14:15], v[18:19], v[142:143], v[88:89]
	v_pk_fma_f32 v[12:13], v[16:17], v[140:141], v[152:153]
	v_pk_fma_f32 v[6:7], v[6:7], v[134:135], v[92:93]
	v_pk_fma_f32 v[4:5], v[4:5], v[132:133], v[156:157]
	v_pk_fma_f32 v[10:11], v[10:11], v[138:139], v[90:91]
	v_pk_fma_f32 v[8:9], v[8:9], v[136:137], v[154:155]
	global_store_dwordx4 v[20:21], v[12:15], off
	global_store_dwordx4 v[20:21], v[8:11], off offset:16
	v_pk_fma_f32 v[2:3], v[2:3], v[130:131], v[94:95]
	v_pk_fma_f32 v[0:1], v[0:1], v[128:129], v[164:165]
	global_store_dwordx4 v[20:21], v[4:7], off offset:512
	global_store_dwordx4 v[20:21], v[0:3], off offset:528
	s_mul_i32 s21, s20, s12
	s_add_i32 s21, s21, s88
	s_cmpk_gt_i32 s21, 0xff
	s_cbranch_scc1 .LBB0_1267
	s_ashr_i32 s20, s21, 31
	s_lshr_b32 s20, s20, 29
	s_add_i32 s22, s21, s20
	s_and_b32 s20, s22, -8
	s_sub_i32 s23, s21, s20
	s_cmp_gt_i32 s23, -1
	s_mov_b64 s[20:21], -1
	s_cbranch_scc0 .LBB0_1279
	s_lshl_b32 s24, s23, 5
	s_mov_b64 s[20:21], 0
